# all flat_load/flat_store/flat_atomic converted to global_* (addresses are always global): s_waitcnt lgkmcnt for LDS/bpermute no longer waits on VMEM
# baseline (speedup 1.0000x reference)
.LBB0_13:
	v_ashrrev_i32_e32 v8, 7, v7
	v_ashrrev_i32_e32 v9, 31, v8
	v_lshl_add_u64 v[8:9], v[8:9], 2, s[6:7]
	global_load_dword v10, v[8:9], off
	v_add_co_u32_e32 v8, vcc, 0xff800000, v4
	v_add_u32_e32 v7, s92, v7
	s_nop 0
	v_addc_co_u32_e32 v9, vcc, -1, v5, vcc
	v_cmp_lt_i32_e32 vcc, s3, v7
	s_or_b64 s[10:11], vcc, s[10:11]
	s_waitcnt vmcnt(0) lgkmcnt(0)
	v_cvt_f32_i32_e32 v10, v10
	v_mul_f32_e32 v10, v6, v10
	v_cvt_f64_f32_e32 v[10:11], v10
	v_mul_f64 v[12:13], v[10:11], s[12:13]
	v_rndne_f64_e32 v[12:13], v[12:13]
	v_fmac_f64_e32 v[10:11], s[14:15], v[12:13]
	v_cvt_f32_f64_e32 v10, v[10:11]
	v_mul_f32_e32 v10, 0.15915494, v10
	v_cos_f32_e32 v11, v10
	v_sin_f32_e32 v10, v10
	global_store_dword v[8:9], v11, off
	global_store_dword v[4:5], v10, off
	v_lshl_add_u64 v[4:5], v[4:5], 0, s[0:1]
	s_andn2_b64 exec, exec, s[10:11]
	s_cbranch_execnz .LBB0_13

.LBB0_16:
	v_ashrrev_i32_e32 v8, 5, v2
	v_ashrrev_i32_e32 v9, 31, v8
	v_lshl_add_u64 v[8:9], v[8:9], 2, s[6:7]
	global_load_dword v3, v[8:9], off
	v_add_co_u32_e32 v8, vcc, 0x200000, v4
	v_add_u32_e32 v2, s92, v2
	s_nop 0
	v_addc_co_u32_e32 v9, vcc, 0, v5, vcc
	v_cmp_lt_i32_e32 vcc, s3, v2
	s_or_b64 s[10:11], vcc, s[10:11]
	s_waitcnt vmcnt(0) lgkmcnt(0)
	v_cvt_f32_i32_e32 v3, v3
	v_mul_f32_e32 v3, v6, v3
	v_cvt_f64_f32_e32 v[10:11], v3
	v_mul_f64 v[12:13], v[10:11], s[12:13]
	v_rndne_f64_e32 v[12:13], v[12:13]
	v_fmac_f64_e32 v[10:11], s[14:15], v[12:13]
	v_cvt_f32_f64_e32 v3, v[10:11]
	v_mul_f32_e32 v3, 0.15915494, v3
	v_cos_f32_e32 v7, v3
	v_sin_f32_e32 v3, v3
	global_store_dword v[4:5], v7, off
	global_store_dword v[8:9], v3, off
	v_lshl_add_u64 v[4:5], v[4:5], 0, s[0:1]
	s_andn2_b64 exec, exec, s[10:11]
	s_cbranch_execnz .LBB0_16

.LBB0_20:
	v_add_co_u32_e32 v18, vcc, 0xfffff000, v42
	global_load_dwordx4 v[2:5], v[42:43], off
	global_load_dwordx4 v[6:9], v[42:43], off offset:1024
	global_load_dwordx4 v[10:13], v[42:43], off offset:2048
	global_load_dwordx4 v[14:17], v[42:43], off offset:3072
	v_addc_co_u32_e32 v19, vcc, -1, v43, vcc
	global_load_dwordx4 v[30:33], v[18:19], off
	v_add_co_u32_e32 v18, vcc, 0xfffff400, v42
	s_waitcnt vmcnt(0) lgkmcnt(0)
	v_mul_f32_e32 v50, v3, v3
	v_addc_co_u32_e32 v19, vcc, -1, v43, vcc
	v_add_co_u32_e32 v20, vcc, 0xfffff800, v42
	global_load_dwordx4 v[26:29], v[18:19], off
	s_nop 0
	v_addc_co_u32_e32 v21, vcc, -1, v43, vcc
	global_load_dwordx4 v[22:25], v[20:21], off
	v_add_co_u32_e32 v18, vcc, 0xfffffc00, v42
	v_mul_f32_e32 v51, v5, v5
	s_nop 0
	v_addc_co_u32_e32 v19, vcc, -1, v43, vcc
	global_load_dwordx4 v[18:21], v[18:19], off
	v_mul_f32_e32 v53, v7, v7
	v_mul_f32_e32 v54, v9, v9
	v_mul_f32_e32 v55, v11, v11
	v_mul_f32_e32 v56, v13, v13
	v_fmac_f32_e32 v50, v2, v2
	v_fmac_f32_e32 v51, v4, v4
	v_fmac_f32_e32 v53, v6, v6
	v_fmac_f32_e32 v54, v8, v8
	v_fmac_f32_e32 v55, v10, v10
	v_fmac_f32_e32 v56, v12, v12
	v_mul_f32_e32 v59, v31, v31
	v_mul_f32_e32 v60, v33, v33
	v_add_f32_e32 v50, v50, v51
	v_add_f32_e32 v51, v53, v54
	v_add_f32_e32 v53, v55, v56
	v_fmac_f32_e32 v59, v30, v30
	v_fmac_f32_e32 v60, v32, v32
	v_add_f32_e32 v56, v59, v60
	v_mul_f32_e32 v57, v15, v15
	v_mul_f32_e32 v58, v17, v17
	v_fmac_f32_e32 v57, v14, v14
	v_fmac_f32_e32 v58, v16, v16
	s_waitcnt vmcnt(0) lgkmcnt(0)
	v_mul_f32_e32 v54, v27, v27
	v_mul_f32_e32 v55, v29, v29
	v_fmac_f32_e32 v54, v26, v26
	v_fmac_f32_e32 v55, v28, v28
	v_mul_f32_e32 v59, v23, v23
	v_mul_f32_e32 v60, v25, v25
	v_add_f32_e32 v54, v54, v55
	v_fmac_f32_e32 v59, v22, v22
	v_fmac_f32_e32 v60, v24, v24
	v_mul_f32_e32 v55, v19, v19
	v_mul_f32_e32 v61, v21, v21
	v_add_f32_e32 v54, v56, v54
	v_add_f32_e32 v56, v59, v60
	v_fmac_f32_e32 v55, v18, v18
	v_fmac_f32_e32 v61, v20, v20
	v_add_f32_e32 v54, v54, v56
	v_add_f32_e32 v55, v55, v61
	v_add_f32_e32 v54, v54, v55
	v_add_f32_e32 v50, v54, v50
	v_add_f32_e32 v50, v50, v51
	v_add_f32_e32 v50, v50, v53
	v_add_f32_e32 v51, v57, v58
	v_add_f32_e32 v50, v50, v51
	ds_bpermute_b32 v51, v44, v50
	s_waitcnt lgkmcnt(0)
	v_add_f32_e32 v50, v50, v51
	ds_bpermute_b32 v51, v45, v50
	s_waitcnt lgkmcnt(0)
	v_add_f32_e32 v50, v50, v51
	ds_bpermute_b32 v51, v46, v50
	s_waitcnt lgkmcnt(0)
	v_add_f32_e32 v50, v50, v51
	ds_bpermute_b32 v51, v47, v50
	s_waitcnt lgkmcnt(0)
	v_add_f32_e32 v50, v50, v51
	ds_bpermute_b32 v51, v48, v50
	s_waitcnt lgkmcnt(0)
	v_add_f32_e32 v50, v50, v51
	ds_bpermute_b32 v51, v49, v50
	s_and_saveexec_b64 s[14:15], s[0:1]
	s_cbranch_execz .LBB0_19
	s_waitcnt lgkmcnt(0)
	v_add_f32_e32 v53, v50, v51
	v_lshl_add_u64 v[50:51], s[26:27], 0, v[38:39]
	global_store_dword v[50:51], v53, off
	s_branch .LBB0_19

.LBB0_27:
	v_mul_hi_i32 v14, v56, s26
	v_lshrrev_b32_e32 v15, 31, v14
	v_ashrrev_i32_e32 v14, 6, v14
	v_add_u32_e32 v14, v14, v15
	v_mul_i32_i24_e32 v15, 0x180, v14
	v_lshlrev_b32_e32 v14, 6, v14
	v_lshlrev_b32_e32 v15, 5, v15
	v_sub_u32_e32 v16, v55, v15
	v_or_b32_e32 v50, v14, v1
	v_mad_i64_i32 v[18:19], s[86:87], v50, s27, v[12:13]
	v_ashrrev_i32_e32 v17, 31, v16
	v_lshl_add_u64 v[16:17], v[16:17], 2, v[18:19]
	v_lshl_add_u64 v[42:43], v[16:17], 0, v[2:3]
	v_add_co_u32_e32 v18, vcc, s28, v42
	s_nop 1
	v_addc_co_u32_e32 v19, vcc, 0, v43, vcc
	v_add_co_u32_e32 v20, vcc, s29, v42
	s_nop 1
	v_addc_co_u32_e32 v21, vcc, 0, v43, vcc
	v_add_co_u32_e32 v22, vcc, s30, v42
	s_nop 1
	v_addc_co_u32_e32 v23, vcc, 0, v43, vcc
	v_add_co_u32_e32 v24, vcc, s31, v42
	s_nop 1
	v_addc_co_u32_e32 v25, vcc, 0, v43, vcc
	v_add_co_u32_e32 v26, vcc, s33, v42
	s_nop 1
	v_addc_co_u32_e32 v27, vcc, 0, v43, vcc
	v_add_co_u32_e32 v28, vcc, s34, v42
	s_nop 1
	v_addc_co_u32_e32 v29, vcc, 0, v43, vcc
	v_add_co_u32_e32 v30, vcc, s35, v42
	s_nop 1
	v_addc_co_u32_e32 v31, vcc, 0, v43, vcc
	global_load_dword v16, v[42:43], off nt
	global_load_dword v17, v[18:19], off nt
	s_nop 0
	global_load_dword v20, v[20:21], off nt
	s_nop 0
	global_load_dword v21, v[22:23], off nt
	global_load_dword v18, v[24:25], off nt
	global_load_dword v19, v[26:27], off nt
	s_nop 0
	global_load_dword v22, v[28:29], off nt
	global_load_dword v23, v[30:31], off nt
	v_add_co_u32_e32 v24, vcc, s36, v42
	s_nop 1
	v_addc_co_u32_e32 v25, vcc, 0, v43, vcc
	v_add_co_u32_e32 v26, vcc, s37, v42
	s_nop 1
	v_addc_co_u32_e32 v27, vcc, 0, v43, vcc
	v_add_co_u32_e32 v28, vcc, s38, v42
	s_nop 1
	v_addc_co_u32_e32 v29, vcc, 0, v43, vcc
	v_add_co_u32_e32 v30, vcc, s39, v42
	s_nop 1
	v_addc_co_u32_e32 v31, vcc, 0, v43, vcc
	v_add_co_u32_e32 v32, vcc, s40, v42
	s_nop 1
	v_addc_co_u32_e32 v33, vcc, 0, v43, vcc
	v_add_co_u32_e32 v36, vcc, s41, v42
	s_nop 1
	v_addc_co_u32_e32 v37, vcc, 0, v43, vcc
	v_add_co_u32_e32 v38, vcc, s42, v42
	s_nop 1
	v_addc_co_u32_e32 v39, vcc, 0, v43, vcc
	v_add_co_u32_e32 v40, vcc, s43, v42
	s_nop 1
	v_addc_co_u32_e32 v41, vcc, 0, v43, vcc
	global_load_dword v24, v[24:25], off nt
	s_nop 0
	global_load_dword v25, v[26:27], off nt
	s_nop 0
	global_load_dword v28, v[28:29], off nt
	s_nop 0
	global_load_dword v29, v[30:31], off nt
	global_load_dword v26, v[32:33], off nt
	global_load_dword v27, v[36:37], off nt
	s_nop 0
	global_load_dword v30, v[38:39], off nt
	global_load_dword v31, v[40:41], off nt
	v_add_co_u32_e32 v32, vcc, s44, v42
	s_nop 1
	v_addc_co_u32_e32 v33, vcc, 0, v43, vcc
	v_add_co_u32_e32 v36, vcc, s45, v42
	s_nop 1
	v_addc_co_u32_e32 v37, vcc, 0, v43, vcc
	v_add_co_u32_e32 v38, vcc, s46, v42
	s_nop 1
	v_addc_co_u32_e32 v39, vcc, 0, v43, vcc
	v_add_co_u32_e32 v40, vcc, s47, v42
	s_nop 1
	v_addc_co_u32_e32 v41, vcc, 0, v43, vcc
	v_add_co_u32_e32 v44, vcc, s48, v42
	s_nop 1
	v_addc_co_u32_e32 v45, vcc, 0, v43, vcc
	v_add_co_u32_e32 v46, vcc, s49, v42
	s_nop 1
	v_addc_co_u32_e32 v47, vcc, 0, v43, vcc
	v_add_co_u32_e32 v48, vcc, s50, v42
	s_nop 1
	v_addc_co_u32_e32 v49, vcc, 0, v43, vcc
	v_add_co_u32_e32 v58, vcc, s51, v42
	s_nop 1
	v_addc_co_u32_e32 v59, vcc, 0, v43, vcc
	global_load_dword v32, v[32:33], off nt
	s_nop 0
	global_load_dword v33, v[36:37], off nt
	s_nop 0
	global_load_dword v38, v[38:39], off nt
	s_nop 0
	global_load_dword v39, v[40:41], off nt
	global_load_dword v36, v[44:45], off nt
	global_load_dword v37, v[46:47], off nt
	s_nop 0
	global_load_dword v40, v[48:49], off nt
	global_load_dword v41, v[58:59], off nt
	v_add_co_u32_e32 v44, vcc, s53, v42
	s_nop 1
	v_addc_co_u32_e32 v45, vcc, 0, v43, vcc
	v_add_co_u32_e32 v46, vcc, s54, v42
	s_nop 1
	v_addc_co_u32_e32 v47, vcc, 0, v43, vcc
	v_add_co_u32_e32 v48, vcc, s55, v42
	s_nop 1
	v_addc_co_u32_e32 v49, vcc, 0, v43, vcc
	v_add_co_u32_e32 v58, vcc, s56, v42
	s_nop 1
	v_addc_co_u32_e32 v59, vcc, 0, v43, vcc
	v_add_co_u32_e32 v60, vcc, s57, v42
	s_nop 1
	v_addc_co_u32_e32 v61, vcc, 0, v43, vcc
	v_add_co_u32_e32 v62, vcc, 0x2b8000, v42
	s_nop 1
	v_addc_co_u32_e32 v63, vcc, 0, v43, vcc
	v_add_co_u32_e32 v64, vcc, 0x2d0000, v42
	s_nop 1
	v_addc_co_u32_e32 v65, vcc, 0, v43, vcc
	v_add_co_u32_e32 v66, vcc, 0x2e8000, v42
	s_nop 1
	v_addc_co_u32_e32 v67, vcc, 0, v43, vcc
	global_load_dword v42, v[44:45], off nt
	global_load_dword v43, v[46:47], off nt
	s_nop 0
	global_load_dword v48, v[48:49], off nt
	s_nop 0
	global_load_dword v49, v[58:59], off nt
	global_load_dword v46, v[60:61], off nt
	global_load_dword v47, v[62:63], off nt
	global_load_dword v44, v[64:65], off nt
	global_load_dword v45, v[66:67], off nt
	s_andn2_b64 vcc, exec, s[24:25]
	s_cbranch_vccnz .LBB0_26
	v_ashrrev_i32_e32 v51, 31, v50
	v_lshl_add_u64 v[50:51], v[50:51], 2, s[18:19]
	global_load_dword v58, v[50:51], off
	global_load_dword v59, v[50:51], off offset:8
	global_load_dword v60, v[50:51], off offset:16
	global_load_dword v61, v[50:51], off offset:24
	global_load_dword v62, v[50:51], off offset:32
	global_load_dword v63, v[50:51], off offset:40
	global_load_dword v64, v[50:51], off offset:48
	global_load_dword v65, v[50:51], off offset:56
	global_load_dword v66, v[50:51], off offset:64
	global_load_dword v67, v[50:51], off offset:72
	global_load_dword v68, v[50:51], off offset:80
	global_load_dword v69, v[50:51], off offset:88
	global_load_dword v70, v[50:51], off offset:96
	global_load_dword v71, v[50:51], off offset:104
	global_load_dword v72, v[50:51], off offset:112
	global_load_dword v73, v[50:51], off offset:120
	global_load_dword v74, v[50:51], off offset:128
	global_load_dword v75, v[50:51], off offset:136
	global_load_dword v76, v[50:51], off offset:144
	global_load_dword v77, v[50:51], off offset:152
	global_load_dword v78, v[50:51], off offset:160
	global_load_dword v79, v[50:51], off offset:168
	global_load_dword v80, v[50:51], off offset:176
	global_load_dword v81, v[50:51], off offset:184
	global_load_dword v82, v[50:51], off offset:192
	global_load_dword v83, v[50:51], off offset:200
	global_load_dword v84, v[50:51], off offset:208
	global_load_dword v85, v[50:51], off offset:216
	global_load_dword v86, v[50:51], off offset:224
	global_load_dword v87, v[50:51], off offset:232
	global_load_dword v88, v[50:51], off offset:240
	global_load_dword v89, v[50:51], off offset:248
	s_waitcnt vmcnt(0) lgkmcnt(0)
	v_pk_mul_f32 v[16:17], v[16:17], v[58:59]
	v_pk_mul_f32 v[20:21], v[20:21], v[60:61]
	v_pk_mul_f32 v[18:19], v[18:19], v[62:63]
	v_pk_mul_f32 v[22:23], v[22:23], v[64:65]
	v_pk_mul_f32 v[24:25], v[24:25], v[66:67]
	v_pk_mul_f32 v[28:29], v[28:29], v[68:69]
	v_pk_mul_f32 v[26:27], v[26:27], v[70:71]
	v_pk_mul_f32 v[30:31], v[30:31], v[72:73]
	v_pk_mul_f32 v[32:33], v[32:33], v[74:75]
	v_pk_mul_f32 v[38:39], v[38:39], v[76:77]
	v_pk_mul_f32 v[36:37], v[36:37], v[78:79]
	v_pk_mul_f32 v[40:41], v[40:41], v[80:81]
	v_pk_mul_f32 v[42:43], v[42:43], v[82:83]
	v_pk_mul_f32 v[48:49], v[48:49], v[84:85]
	v_pk_mul_f32 v[46:47], v[46:47], v[86:87]
	v_pk_mul_f32 v[44:45], v[44:45], v[88:89]
	s_branch .LBB0_26

.LBB0_31:
	v_ashrrev_i32_e32 v14, 31, v13
	v_lshrrev_b32_e32 v14, 26, v14
	v_add_u32_e32 v15, v13, v14
	v_and_b32_e32 v14, 0xffffffc0, v15
	v_lshlrev_b32_e32 v15, 5, v15
	v_or_b32_e32 v16, v14, v1
	v_and_b32_e32 v15, 0xfffff800, v15
	v_ashrrev_i32_e32 v17, 31, v16
	v_sub_u32_e32 v18, v12, v15
	v_lshlrev_b64 v[16:17], 13, v[16:17]
	v_ashrrev_i32_e32 v19, 31, v18
	v_lshl_add_u64 v[16:17], s[18:19], 0, v[16:17]
	v_lshl_add_u64 v[16:17], v[18:19], 2, v[16:17]
	v_lshl_add_u64 v[16:17], v[16:17], 0, v[2:3]
	v_add_co_u32_e32 v20, vcc, s59, v16
	v_ashrrev_i32_e32 v15, 31, v14
	s_nop 0
	v_addc_co_u32_e32 v21, vcc, 0, v17, vcc
	v_add_co_u32_e32 v22, vcc, s60, v16
	v_add_u32_e32 v18, v18, v53
	s_nop 0
	v_addc_co_u32_e32 v23, vcc, 0, v17, vcc
	v_add_co_u32_e32 v24, vcc, s27, v16
	v_ashrrev_i32_e32 v19, 31, v18
	s_nop 0
	v_addc_co_u32_e32 v25, vcc, 0, v17, vcc
	v_add_co_u32_e32 v26, vcc, s61, v16
	v_add_u32_e32 v13, s52, v13
	s_nop 0
	v_addc_co_u32_e32 v27, vcc, 0, v17, vcc
	v_add_co_u32_e32 v28, vcc, s62, v16
	v_add_u32_e32 v12, s3, v12
	s_nop 0
	v_addc_co_u32_e32 v29, vcc, 0, v17, vcc
	v_add_co_u32_e32 v30, vcc, s28, v16
	s_nop 1
	v_addc_co_u32_e32 v31, vcc, 0, v17, vcc
	v_add_co_u32_e32 v32, vcc, s63, v16
	s_nop 1
	v_addc_co_u32_e32 v33, vcc, 0, v17, vcc
	v_add_co_u32_e32 v36, vcc, s64, v16
	s_nop 1
	v_addc_co_u32_e32 v37, vcc, 0, v17, vcc
	v_add_co_u32_e32 v38, vcc, s65, v16
	s_nop 1
	v_addc_co_u32_e32 v39, vcc, 0, v17, vcc
	v_add_co_u32_e32 v40, vcc, s66, v16
	s_nop 1
	v_addc_co_u32_e32 v41, vcc, 0, v17, vcc
	v_add_co_u32_e32 v42, vcc, s67, v16
	s_nop 1
	v_addc_co_u32_e32 v43, vcc, 0, v17, vcc
	v_add_co_u32_e32 v44, vcc, s29, v16
	s_nop 1
	v_addc_co_u32_e32 v45, vcc, 0, v17, vcc
	v_add_co_u32_e32 v46, vcc, s68, v16
	s_nop 1
	v_addc_co_u32_e32 v47, vcc, 0, v17, vcc
	v_add_co_u32_e32 v48, vcc, s69, v16
	s_nop 1
	v_addc_co_u32_e32 v49, vcc, 0, v17, vcc
	v_add_co_u32_e32 v50, vcc, s70, v16
	s_nop 1
	v_addc_co_u32_e32 v51, vcc, 0, v17, vcc
	v_add_co_u32_e32 v56, vcc, s71, v16
	s_nop 1
	v_addc_co_u32_e32 v57, vcc, 0, v17, vcc
	v_add_co_u32_e32 v58, vcc, s72, v16
	s_nop 1
	v_addc_co_u32_e32 v59, vcc, 0, v17, vcc
	v_add_co_u32_e32 v60, vcc, s30, v16
	s_nop 1
	v_addc_co_u32_e32 v61, vcc, 0, v17, vcc
	v_add_co_u32_e32 v62, vcc, s73, v16
	s_nop 1
	v_addc_co_u32_e32 v63, vcc, 0, v17, vcc
	v_add_co_u32_e32 v64, vcc, s74, v16
	s_nop 1
	v_addc_co_u32_e32 v65, vcc, 0, v17, vcc
	v_add_co_u32_e32 v66, vcc, s75, v16
	s_nop 1
	v_addc_co_u32_e32 v67, vcc, 0, v17, vcc
	v_add_co_u32_e32 v68, vcc, s76, v16
	s_nop 1
	v_addc_co_u32_e32 v69, vcc, 0, v17, vcc
	v_add_co_u32_e32 v70, vcc, s77, v16
	s_nop 1
	v_addc_co_u32_e32 v71, vcc, 0, v17, vcc
	v_add_co_u32_e32 v72, vcc, s31, v16
	s_nop 1
	v_addc_co_u32_e32 v73, vcc, 0, v17, vcc
	v_add_co_u32_e32 v74, vcc, s78, v16
	s_nop 1
	v_addc_co_u32_e32 v75, vcc, 0, v17, vcc
	v_add_co_u32_e32 v76, vcc, s79, v16
	s_nop 1
	v_addc_co_u32_e32 v77, vcc, 0, v17, vcc
	v_add_co_u32_e32 v78, vcc, s80, v16
	s_nop 1
	v_addc_co_u32_e32 v79, vcc, 0, v17, vcc
	v_add_co_u32_e32 v80, vcc, s81, v16
	s_nop 1
	v_addc_co_u32_e32 v81, vcc, 0, v17, vcc
	v_add_co_u32_e32 v82, vcc, s82, v16
	s_nop 1
	v_addc_co_u32_e32 v83, vcc, 0, v17, vcc
	v_add_co_u32_e32 v84, vcc, s33, v16
	s_nop 1
	v_addc_co_u32_e32 v85, vcc, 0, v17, vcc
	v_add_co_u32_e32 v86, vcc, s83, v16
	s_nop 1
	v_addc_co_u32_e32 v87, vcc, 0, v17, vcc
	global_load_dword v55, v[16:17], off nt
	global_load_dword v88, v[20:21], off nt
	global_load_dword v89, v[22:23], off nt
	global_load_dword v90, v[24:25], off nt
	global_load_dword v91, v[26:27], off nt
	s_nop 0
	global_load_dword v28, v[28:29], off nt
	s_nop 0
	global_load_dword v29, v[30:31], off nt
	s_nop 0
	global_load_dword v30, v[32:33], off nt
	global_load_dword v31, v[36:37], off nt
	s_nop 0
	global_load_dword v32, v[38:39], off nt
	global_load_dword v33, v[40:41], off nt
	global_load_dword v36, v[42:43], off nt
	global_load_dword v37, v[44:45], off nt
	s_nop 0
	global_load_dword v38, v[46:47], off nt
	global_load_dword v39, v[48:49], off nt
	global_load_dword v40, v[50:51], off nt
	global_load_dword v41, v[56:57], off nt
	global_load_dword v42, v[58:59], off nt
	global_load_dword v43, v[60:61], off nt
	global_load_dword v44, v[62:63], off nt
	global_load_dword v45, v[64:65], off nt
	global_load_dword v46, v[66:67], off nt
	global_load_dword v47, v[68:69], off nt
	global_load_dword v48, v[70:71], off nt
	global_load_dword v49, v[72:73], off nt
	global_load_dword v50, v[74:75], off nt
	global_load_dword v51, v[76:77], off nt
	global_load_dword v56, v[78:79], off nt
	global_load_dword v57, v[80:81], off nt
	global_load_dword v58, v[82:83], off nt
	global_load_dword v59, v[84:85], off nt
	global_load_dword v60, v[86:87], off nt
	v_lshl_add_u64 v[20:21], v[14:15], 1, v[10:11]
	v_add_u32_e32 v14, 8, v18
	v_add_u32_e32 v61, 0x400, v35
	v_add_u32_e32 v62, 0x800, v35
	v_add_u32_e32 v63, 0xc00, v35
	v_add_u32_e32 v64, 0x1000, v35
	v_add_u32_e32 v65, 0x1400, v35
	v_add_u32_e32 v66, 0x1800, v35
	v_add_u32_e32 v67, 0x1c00, v35
	v_add_u32_e32 v16, 16, v18
	v_ashrrev_i32_e32 v15, 31, v14
	s_waitcnt vmcnt(0) lgkmcnt(0)
	ds_write2_b32 v35, v55, v88 offset1:66
	ds_write2_b32 v35, v89, v90 offset0:132 offset1:198
	ds_write2_b32 v61, v91, v28 offset0:8 offset1:74
	ds_write2_b32 v61, v29, v30 offset0:140 offset1:206
	ds_write2_b32 v62, v31, v32 offset0:16 offset1:82
	ds_write2_b32 v62, v33, v36 offset0:148 offset1:214
	ds_write2_b32 v63, v37, v38 offset0:24 offset1:90
	ds_write2_b32 v63, v39, v40 offset0:156 offset1:222
	ds_write2_b32 v64, v41, v42 offset0:32 offset1:98
	ds_write2_b32 v64, v43, v44 offset0:164 offset1:230
	ds_write2_b32 v65, v45, v46 offset0:40 offset1:106
	ds_write2_b32 v65, v47, v48 offset0:172 offset1:238
	ds_write2_b32 v66, v49, v50 offset0:48 offset1:114
	ds_write2_b32 v66, v51, v56 offset0:180 offset1:246
	ds_write2_b32 v67, v57, v58 offset0:56 offset1:122
	ds_write2_b32 v67, v59, v60 offset0:188 offset1:254
	v_ashrrev_i32_e32 v17, 31, v16
	v_lshlrev_b64 v[14:15], 13, v[14:15]
	s_waitcnt lgkmcnt(0)
	v_lshlrev_b64 v[16:17], 13, v[16:17]
	v_lshl_add_u64 v[24:25], v[20:21], 0, v[14:15]
	ds_read2_b32 v[14:15], v54 offset1:33
	v_lshl_add_u64 v[26:27], v[20:21], 0, v[16:17]
	s_waitcnt lgkmcnt(0)
	v_cvt_pk_bf16_f32 v14, v14, v15
	ds_read2_b32 v[16:17], v54 offset0:66 offset1:99
	v_lshlrev_b64 v[22:23], 13, v[18:19]
	s_waitcnt lgkmcnt(0)
	v_cvt_pk_bf16_f32 v15, v16, v17
	ds_read2_b32 v[16:17], v54 offset0:132 offset1:165
	v_lshl_add_u64 v[22:23], v[20:21], 0, v[22:23]
	s_waitcnt lgkmcnt(0)
	v_cvt_pk_bf16_f32 v16, v16, v17
	ds_read2_b32 v[28:29], v54 offset0:198 offset1:231
	s_waitcnt lgkmcnt(0)
	v_cvt_pk_bf16_f32 v17, v28, v29
	ds_read2_b32 v[28:29], v54 offset0:8 offset1:41
	global_store_dwordx4 v[22:23], v[14:17], off
	v_add_u32_e32 v18, 24, v18
	v_ashrrev_i32_e32 v19, 31, v18
	s_waitcnt lgkmcnt(0)
	v_cvt_pk_bf16_f32 v14, v28, v29
	ds_read2_b32 v[16:17], v54 offset0:74 offset1:107
	s_waitcnt lgkmcnt(0)
	v_cvt_pk_bf16_f32 v15, v16, v17
	ds_read2_b32 v[16:17], v54 offset0:140 offset1:173
	s_waitcnt lgkmcnt(0)
	v_cvt_pk_bf16_f32 v16, v16, v17
	ds_read2_b32 v[22:23], v54 offset0:206 offset1:239
	s_waitcnt lgkmcnt(0)
	v_cvt_pk_bf16_f32 v17, v22, v23
	ds_read2_b32 v[22:23], v54 offset0:16 offset1:49
	global_store_dwordx4 v[24:25], v[14:17], off
	v_lshlrev_b64 v[18:19], 13, v[18:19]
	v_lshl_add_u64 v[18:19], v[20:21], 0, v[18:19]
	s_waitcnt lgkmcnt(0)
	v_cvt_pk_bf16_f32 v14, v22, v23
	ds_read2_b32 v[16:17], v54 offset0:82 offset1:115
	s_waitcnt lgkmcnt(0)
	v_cvt_pk_bf16_f32 v15, v16, v17
	ds_read2_b32 v[16:17], v54 offset0:148 offset1:181
	s_waitcnt lgkmcnt(0)
	v_cvt_pk_bf16_f32 v16, v16, v17
	ds_read2_b32 v[22:23], v54 offset0:214 offset1:247
	s_waitcnt lgkmcnt(0)
	v_cvt_pk_bf16_f32 v17, v22, v23
	ds_read2_b32 v[22:23], v54 offset0:24 offset1:57
	global_store_dwordx4 v[26:27], v[14:17], off
	v_cmp_lt_i32_e32 vcc, s84, v13
	s_or_b64 s[22:23], vcc, s[22:23]
	s_waitcnt lgkmcnt(0)
	v_cvt_pk_bf16_f32 v14, v22, v23
	ds_read2_b32 v[16:17], v54 offset0:90 offset1:123
	s_waitcnt lgkmcnt(0)
	v_cvt_pk_bf16_f32 v15, v16, v17
	ds_read2_b32 v[16:17], v54 offset0:156 offset1:189
	s_waitcnt lgkmcnt(0)
	v_cvt_pk_bf16_f32 v16, v16, v17
	ds_read2_b32 v[22:23], v54 offset0:222 offset1:255
	s_waitcnt lgkmcnt(0)
	v_cvt_pk_bf16_f32 v17, v22, v23
	global_store_dwordx4 v[18:19], v[14:17], off
	s_waitcnt lgkmcnt(0)
	s_andn2_b64 exec, exec, s[22:23]
	s_cbranch_execnz .LBB0_31
	s_branch .LBB0_23

.LBB0_35:
	v_ashrrev_i32_e32 v8, 31, v5
	v_add_u32_sdwa v8, v5, v8 dst_sel:DWORD dst_unused:UNUSED_PAD src0_sel:DWORD src1_sel:BYTE_3
	v_ashrrev_i32_e32 v8, 8, v8
	v_mul_i32_i24_e32 v9, 0x100, v8
	v_lshlrev_b32_e32 v8, 6, v8
	v_or_b32_e32 v44, v8, v1
	v_lshlrev_b32_e32 v9, 5, v9
	v_ashrrev_i32_e32 v45, 31, v44
	v_sub_u32_e32 v10, v46, v9
	v_lshlrev_b64 v[12:13], 15, v[44:45]
	v_lshl_add_u64 v[12:13], s[6:7], 0, v[12:13]
	v_ashrrev_i32_e32 v11, 31, v10
	v_lshl_add_u64 v[10:11], v[10:11], 2, v[12:13]
	v_lshl_add_u64 v[36:37], v[10:11], 0, v[2:3]
	v_add_co_u32_e32 v12, vcc, s14, v36
	s_nop 1
	v_addc_co_u32_e32 v13, vcc, 0, v37, vcc
	v_add_co_u32_e32 v14, vcc, s15, v36
	s_nop 1
	v_addc_co_u32_e32 v15, vcc, 0, v37, vcc
	v_add_co_u32_e32 v16, vcc, s16, v36
	s_nop 1
	v_addc_co_u32_e32 v17, vcc, 0, v37, vcc
	v_add_co_u32_e32 v18, vcc, s17, v36
	s_nop 1
	v_addc_co_u32_e32 v19, vcc, 0, v37, vcc
	v_add_co_u32_e32 v20, vcc, s18, v36
	s_nop 1
	v_addc_co_u32_e32 v21, vcc, 0, v37, vcc
	v_add_co_u32_e32 v22, vcc, s19, v36
	s_nop 1
	v_addc_co_u32_e32 v23, vcc, 0, v37, vcc
	v_add_co_u32_e32 v24, vcc, s22, v36
	s_nop 1
	v_addc_co_u32_e32 v25, vcc, 0, v37, vcc
	global_load_dword v10, v[36:37], off nt
	global_load_dword v11, v[12:13], off nt
	s_nop 0
	global_load_dword v14, v[14:15], off nt
	s_nop 0
	global_load_dword v15, v[16:17], off nt
	global_load_dword v12, v[18:19], off nt
	global_load_dword v13, v[20:21], off nt
	s_nop 0
	global_load_dword v16, v[22:23], off nt
	global_load_dword v17, v[24:25], off nt
	v_add_co_u32_e32 v18, vcc, s23, v36
	s_nop 1
	v_addc_co_u32_e32 v19, vcc, 0, v37, vcc
	v_add_co_u32_e32 v20, vcc, s24, v36
	s_nop 1
	v_addc_co_u32_e32 v21, vcc, 0, v37, vcc
	v_add_co_u32_e32 v22, vcc, s25, v36
	s_nop 1
	v_addc_co_u32_e32 v23, vcc, 0, v37, vcc
	v_add_co_u32_e32 v24, vcc, s26, v36
	s_nop 1
	v_addc_co_u32_e32 v25, vcc, 0, v37, vcc
	v_add_co_u32_e32 v26, vcc, s27, v36
	s_nop 1
	v_addc_co_u32_e32 v27, vcc, 0, v37, vcc
	v_add_co_u32_e32 v28, vcc, s28, v36
	s_nop 1
	v_addc_co_u32_e32 v29, vcc, 0, v37, vcc
	v_add_co_u32_e32 v30, vcc, s29, v36
	s_nop 1
	v_addc_co_u32_e32 v31, vcc, 0, v37, vcc
	v_add_co_u32_e32 v32, vcc, s30, v36
	s_nop 1
	v_addc_co_u32_e32 v33, vcc, 0, v37, vcc
	global_load_dword v18, v[18:19], off nt
	s_nop 0
	global_load_dword v19, v[20:21], off nt
	s_nop 0
	global_load_dword v22, v[22:23], off nt
	s_nop 0
	global_load_dword v23, v[24:25], off nt
	global_load_dword v20, v[26:27], off nt
	global_load_dword v21, v[28:29], off nt
	s_nop 0
	global_load_dword v24, v[30:31], off nt
	global_load_dword v25, v[32:33], off nt
	v_add_co_u32_e32 v26, vcc, s31, v36
	s_nop 1
	v_addc_co_u32_e32 v27, vcc, 0, v37, vcc
	v_add_co_u32_e32 v28, vcc, s33, v36
	s_nop 1
	v_addc_co_u32_e32 v29, vcc, 0, v37, vcc
	v_add_co_u32_e32 v30, vcc, s34, v36
	s_nop 1
	v_addc_co_u32_e32 v31, vcc, 0, v37, vcc
	v_add_co_u32_e32 v32, vcc, s35, v36
	s_nop 1
	v_addc_co_u32_e32 v33, vcc, 0, v37, vcc
	v_add_co_u32_e32 v38, vcc, s36, v36
	s_nop 1
	v_addc_co_u32_e32 v39, vcc, 0, v37, vcc
	v_add_co_u32_e32 v40, vcc, s37, v36
	s_nop 1
	v_addc_co_u32_e32 v41, vcc, 0, v37, vcc
	v_add_co_u32_e32 v42, vcc, s38, v36
	s_nop 1
	v_addc_co_u32_e32 v43, vcc, 0, v37, vcc
	v_add_co_u32_e32 v48, vcc, s39, v36
	s_nop 1
	v_addc_co_u32_e32 v49, vcc, 0, v37, vcc
	global_load_dword v26, v[26:27], off nt
	s_nop 0
	global_load_dword v27, v[28:29], off nt
	s_nop 0
	global_load_dword v30, v[30:31], off nt
	s_nop 0
	global_load_dword v31, v[32:33], off nt
	global_load_dword v28, v[38:39], off nt
	global_load_dword v29, v[40:41], off nt
	s_nop 0
	global_load_dword v32, v[42:43], off nt
	global_load_dword v33, v[48:49], off nt
	v_add_co_u32_e32 v38, vcc, s40, v36
	s_nop 1
	v_addc_co_u32_e32 v39, vcc, 0, v37, vcc
	v_add_co_u32_e32 v40, vcc, s41, v36
	s_nop 1
	v_addc_co_u32_e32 v41, vcc, 0, v37, vcc
	v_add_co_u32_e32 v42, vcc, s42, v36
	s_nop 1
	v_addc_co_u32_e32 v43, vcc, 0, v37, vcc
	v_add_co_u32_e32 v48, vcc, s43, v36
	s_nop 1
	v_addc_co_u32_e32 v49, vcc, 0, v37, vcc
	v_add_co_u32_e32 v50, vcc, s44, v36
	s_nop 1
	v_addc_co_u32_e32 v51, vcc, 0, v37, vcc
	v_add_co_u32_e32 v56, vcc, 0x1d0000, v36
	s_nop 1
	v_addc_co_u32_e32 v57, vcc, 0, v37, vcc
	v_add_co_u32_e32 v58, vcc, 0x1e0000, v36
	s_nop 1
	v_addc_co_u32_e32 v59, vcc, 0, v37, vcc
	v_add_co_u32_e32 v60, vcc, 0x1f0000, v36
	s_nop 1
	v_addc_co_u32_e32 v61, vcc, 0, v37, vcc
	global_load_dword v36, v[38:39], off nt
	global_load_dword v37, v[40:41], off nt
	s_nop 0
	global_load_dword v42, v[42:43], off nt
	s_nop 0
	global_load_dword v43, v[48:49], off nt
	global_load_dword v40, v[50:51], off nt
	global_load_dword v41, v[56:57], off nt
	global_load_dword v38, v[58:59], off nt
	global_load_dword v39, v[60:61], off nt
	s_and_b64 vcc, exec, s[4:5]
	s_cbranch_vccnz .LBB0_34
	v_lshl_add_u64 v[44:45], v[44:45], 2, s[8:9]
	global_load_dword v48, v[44:45], off
	global_load_dword v49, v[44:45], off offset:8
	global_load_dword v50, v[44:45], off offset:16
	global_load_dword v51, v[44:45], off offset:24
	global_load_dword v56, v[44:45], off offset:32
	global_load_dword v57, v[44:45], off offset:40
	global_load_dword v58, v[44:45], off offset:48
	global_load_dword v59, v[44:45], off offset:56
	global_load_dword v60, v[44:45], off offset:64
	global_load_dword v61, v[44:45], off offset:72
	global_load_dword v62, v[44:45], off offset:80
	global_load_dword v63, v[44:45], off offset:88
	global_load_dword v64, v[44:45], off offset:96
	global_load_dword v65, v[44:45], off offset:104
	global_load_dword v66, v[44:45], off offset:112
	global_load_dword v67, v[44:45], off offset:120
	global_load_dword v68, v[44:45], off offset:128
	global_load_dword v69, v[44:45], off offset:136
	global_load_dword v70, v[44:45], off offset:144
	global_load_dword v71, v[44:45], off offset:152
	global_load_dword v72, v[44:45], off offset:160
	global_load_dword v73, v[44:45], off offset:168
	global_load_dword v74, v[44:45], off offset:176
	global_load_dword v75, v[44:45], off offset:184
	global_load_dword v76, v[44:45], off offset:192
	global_load_dword v77, v[44:45], off offset:200
	global_load_dword v78, v[44:45], off offset:208
	global_load_dword v79, v[44:45], off offset:216
	global_load_dword v80, v[44:45], off offset:224
	global_load_dword v81, v[44:45], off offset:232
	global_load_dword v82, v[44:45], off offset:240
	global_load_dword v83, v[44:45], off offset:248
	s_waitcnt vmcnt(0) lgkmcnt(0)
	v_pk_mul_f32 v[10:11], v[10:11], v[48:49]
	v_pk_mul_f32 v[14:15], v[14:15], v[50:51]
	v_pk_mul_f32 v[12:13], v[12:13], v[56:57]
	v_pk_mul_f32 v[16:17], v[16:17], v[58:59]
	v_pk_mul_f32 v[18:19], v[18:19], v[60:61]
	v_pk_mul_f32 v[22:23], v[22:23], v[62:63]
	v_pk_mul_f32 v[20:21], v[20:21], v[64:65]
	v_pk_mul_f32 v[24:25], v[24:25], v[66:67]
	v_pk_mul_f32 v[26:27], v[26:27], v[68:69]
	v_pk_mul_f32 v[30:31], v[30:31], v[70:71]
	v_pk_mul_f32 v[28:29], v[28:29], v[72:73]
	v_pk_mul_f32 v[32:33], v[32:33], v[74:75]
	v_pk_mul_f32 v[36:37], v[36:37], v[76:77]
	v_pk_mul_f32 v[42:43], v[42:43], v[78:79]
	v_pk_mul_f32 v[40:41], v[40:41], v[80:81]
	v_pk_mul_f32 v[38:39], v[38:39], v[82:83]
	s_branch .LBB0_34

.LBB0_39:
	v_ashrrev_i32_e32 v14, 31, v34
	v_lshrrev_b32_e32 v14, 26, v14
	v_add_u32_e32 v15, v34, v14
	v_and_b32_e32 v14, 0xffffffc0, v15
	v_lshlrev_b32_e32 v15, 5, v15
	v_or_b32_e32 v16, v14, v1
	v_and_b32_e32 v15, 0xfffff800, v15
	v_ashrrev_i32_e32 v17, 31, v16
	v_sub_u32_e32 v18, v4, v15
	v_lshlrev_b64 v[16:17], 13, v[16:17]
	v_ashrrev_i32_e32 v19, 31, v18
	v_lshl_add_u64 v[16:17], s[4:5], 0, v[16:17]
	v_lshl_add_u64 v[16:17], v[18:19], 2, v[16:17]
	v_lshl_add_u64 v[16:17], v[16:17], 0, v[2:3]
	v_add_co_u32_e32 v20, vcc, s8, v16
	v_ashrrev_i32_e32 v15, 31, v14
	s_nop 0
	v_addc_co_u32_e32 v21, vcc, 0, v17, vcc
	v_add_co_u32_e32 v22, vcc, s9, v16
	v_add_u32_e32 v18, v18, v53
	s_nop 0
	v_addc_co_u32_e32 v23, vcc, 0, v17, vcc
	v_add_co_u32_e32 v24, vcc, s10, v16
	v_ashrrev_i32_e32 v19, 31, v18
	s_nop 0
	v_addc_co_u32_e32 v25, vcc, 0, v17, vcc
	v_add_co_u32_e32 v26, vcc, s11, v16
	v_add_u32_e32 v34, s52, v34
	s_nop 0
	v_addc_co_u32_e32 v27, vcc, 0, v17, vcc
	v_add_co_u32_e32 v28, vcc, s12, v16
	v_add_u32_e32 v4, s3, v4
	s_nop 0
	v_addc_co_u32_e32 v29, vcc, 0, v17, vcc
	v_add_co_u32_e32 v30, vcc, s13, v16
	s_nop 1
	v_addc_co_u32_e32 v31, vcc, 0, v17, vcc
	v_add_co_u32_e32 v32, vcc, s14, v16
	s_nop 1
	v_addc_co_u32_e32 v33, vcc, 0, v17, vcc
	v_add_co_u32_e32 v36, vcc, s15, v16
	s_nop 1
	v_addc_co_u32_e32 v37, vcc, 0, v17, vcc
	v_add_co_u32_e32 v38, vcc, s16, v16
	s_nop 1
	v_addc_co_u32_e32 v39, vcc, 0, v17, vcc
	v_add_co_u32_e32 v40, vcc, s17, v16
	s_nop 1
	v_addc_co_u32_e32 v41, vcc, 0, v17, vcc
	v_add_co_u32_e32 v42, vcc, s18, v16
	s_nop 1
	v_addc_co_u32_e32 v43, vcc, 0, v17, vcc
	v_add_co_u32_e32 v44, vcc, s19, v16
	s_nop 1
	v_addc_co_u32_e32 v45, vcc, 0, v17, vcc
	v_add_co_u32_e32 v46, vcc, s22, v16
	s_nop 1
	v_addc_co_u32_e32 v47, vcc, 0, v17, vcc
	v_add_co_u32_e32 v48, vcc, s23, v16
	s_nop 1
	v_addc_co_u32_e32 v49, vcc, 0, v17, vcc
	v_add_co_u32_e32 v50, vcc, s24, v16
	s_nop 1
	v_addc_co_u32_e32 v51, vcc, 0, v17, vcc
	v_add_co_u32_e32 v56, vcc, s25, v16
	s_nop 1
	v_addc_co_u32_e32 v57, vcc, 0, v17, vcc
	v_add_co_u32_e32 v58, vcc, s26, v16
	s_nop 1
	v_addc_co_u32_e32 v59, vcc, 0, v17, vcc
	v_add_co_u32_e32 v60, vcc, s27, v16
	s_nop 1
	v_addc_co_u32_e32 v61, vcc, 0, v17, vcc
	v_add_co_u32_e32 v62, vcc, s28, v16
	s_nop 1
	v_addc_co_u32_e32 v63, vcc, 0, v17, vcc
	v_add_co_u32_e32 v64, vcc, s29, v16
	s_nop 1
	v_addc_co_u32_e32 v65, vcc, 0, v17, vcc
	v_add_co_u32_e32 v66, vcc, s30, v16
	s_nop 1
	v_addc_co_u32_e32 v67, vcc, 0, v17, vcc
	v_add_co_u32_e32 v68, vcc, s31, v16
	s_nop 1
	v_addc_co_u32_e32 v69, vcc, 0, v17, vcc
	v_add_co_u32_e32 v70, vcc, s33, v16
	s_nop 1
	v_addc_co_u32_e32 v71, vcc, 0, v17, vcc
	v_add_co_u32_e32 v72, vcc, s34, v16
	s_nop 1
	v_addc_co_u32_e32 v73, vcc, 0, v17, vcc
	v_add_co_u32_e32 v74, vcc, s35, v16
	s_nop 1
	v_addc_co_u32_e32 v75, vcc, 0, v17, vcc
	v_add_co_u32_e32 v76, vcc, s36, v16
	s_nop 1
	v_addc_co_u32_e32 v77, vcc, 0, v17, vcc
	v_add_co_u32_e32 v78, vcc, s37, v16
	s_nop 1
	v_addc_co_u32_e32 v79, vcc, 0, v17, vcc
	v_add_co_u32_e32 v80, vcc, s38, v16
	s_nop 1
	v_addc_co_u32_e32 v81, vcc, 0, v17, vcc
	v_add_co_u32_e32 v82, vcc, s39, v16
	s_nop 1
	v_addc_co_u32_e32 v83, vcc, 0, v17, vcc
	v_add_co_u32_e32 v84, vcc, s40, v16
	s_nop 1
	v_addc_co_u32_e32 v85, vcc, 0, v17, vcc
	v_add_co_u32_e32 v86, vcc, s41, v16
	s_nop 1
	v_addc_co_u32_e32 v87, vcc, 0, v17, vcc
	global_load_dword v55, v[16:17], off nt
	global_load_dword v88, v[20:21], off nt
	global_load_dword v89, v[22:23], off nt
	global_load_dword v90, v[24:25], off nt
	global_load_dword v91, v[26:27], off nt
	s_nop 0
	global_load_dword v28, v[28:29], off nt
	s_nop 0
	global_load_dword v29, v[30:31], off nt
	s_nop 0
	global_load_dword v30, v[32:33], off nt
	global_load_dword v31, v[36:37], off nt
	s_nop 0
	global_load_dword v32, v[38:39], off nt
	global_load_dword v33, v[40:41], off nt
	global_load_dword v36, v[42:43], off nt
	global_load_dword v37, v[44:45], off nt
	s_nop 0
	global_load_dword v38, v[46:47], off nt
	global_load_dword v39, v[48:49], off nt
	global_load_dword v40, v[50:51], off nt
	global_load_dword v41, v[56:57], off nt
	global_load_dword v42, v[58:59], off nt
	global_load_dword v43, v[60:61], off nt
	global_load_dword v44, v[62:63], off nt
	global_load_dword v45, v[64:65], off nt
	global_load_dword v46, v[66:67], off nt
	global_load_dword v47, v[68:69], off nt
	global_load_dword v48, v[70:71], off nt
	global_load_dword v49, v[72:73], off nt
	global_load_dword v50, v[74:75], off nt
	global_load_dword v51, v[76:77], off nt
	global_load_dword v56, v[78:79], off nt
	global_load_dword v57, v[80:81], off nt
	global_load_dword v58, v[82:83], off nt
	global_load_dword v59, v[84:85], off nt
	global_load_dword v60, v[86:87], off nt
	v_lshl_add_u64 v[20:21], v[14:15], 1, v[6:7]
	v_add_u32_e32 v14, 8, v18
	v_add_u32_e32 v16, 16, v18
	v_ashrrev_i32_e32 v15, 31, v14
	s_waitcnt vmcnt(0) lgkmcnt(0)
	ds_write2_b32 v35, v55, v88 offset1:66
	ds_write2_b32 v35, v89, v90 offset0:132 offset1:198
	ds_write2_b32 v5, v91, v28 offset0:8 offset1:74
	ds_write2_b32 v5, v29, v30 offset0:140 offset1:206
	ds_write2_b32 v8, v31, v32 offset0:16 offset1:82
	ds_write2_b32 v8, v33, v36 offset0:148 offset1:214
	ds_write2_b32 v9, v37, v38 offset0:24 offset1:90
	ds_write2_b32 v9, v39, v40 offset0:156 offset1:222
	ds_write2_b32 v10, v41, v42 offset0:32 offset1:98
	ds_write2_b32 v10, v43, v44 offset0:164 offset1:230
	ds_write2_b32 v11, v45, v46 offset0:40 offset1:106
	ds_write2_b32 v11, v47, v48 offset0:172 offset1:238
	ds_write2_b32 v12, v49, v50 offset0:48 offset1:114
	ds_write2_b32 v12, v51, v56 offset0:180 offset1:246
	ds_write2_b32 v13, v57, v58 offset0:56 offset1:122
	ds_write2_b32 v13, v59, v60 offset0:188 offset1:254
	v_ashrrev_i32_e32 v17, 31, v16
	v_lshlrev_b64 v[14:15], 14, v[14:15]
	s_waitcnt lgkmcnt(0)
	v_lshlrev_b64 v[16:17], 14, v[16:17]
	v_lshl_add_u64 v[24:25], v[20:21], 0, v[14:15]
	ds_read2_b32 v[14:15], v54 offset1:33
	v_lshl_add_u64 v[26:27], v[20:21], 0, v[16:17]
	s_waitcnt lgkmcnt(0)
	v_cvt_pk_bf16_f32 v14, v14, v15
	ds_read2_b32 v[16:17], v54 offset0:66 offset1:99
	v_lshlrev_b64 v[22:23], 14, v[18:19]
	s_waitcnt lgkmcnt(0)
	v_cvt_pk_bf16_f32 v15, v16, v17
	ds_read2_b32 v[16:17], v54 offset0:132 offset1:165
	v_lshl_add_u64 v[22:23], v[20:21], 0, v[22:23]
	s_waitcnt lgkmcnt(0)
	v_cvt_pk_bf16_f32 v16, v16, v17
	ds_read2_b32 v[28:29], v54 offset0:198 offset1:231
	s_waitcnt lgkmcnt(0)
	v_cvt_pk_bf16_f32 v17, v28, v29
	ds_read2_b32 v[28:29], v54 offset0:8 offset1:41
	global_store_dwordx4 v[22:23], v[14:17], off
	v_add_u32_e32 v18, 24, v18
	v_ashrrev_i32_e32 v19, 31, v18
	s_waitcnt lgkmcnt(0)
	v_cvt_pk_bf16_f32 v14, v28, v29
	ds_read2_b32 v[16:17], v54 offset0:74 offset1:107
	s_waitcnt lgkmcnt(0)
	v_cvt_pk_bf16_f32 v15, v16, v17
	ds_read2_b32 v[16:17], v54 offset0:140 offset1:173
	s_waitcnt lgkmcnt(0)
	v_cvt_pk_bf16_f32 v16, v16, v17
	ds_read2_b32 v[22:23], v54 offset0:206 offset1:239
	s_waitcnt lgkmcnt(0)
	v_cvt_pk_bf16_f32 v17, v22, v23
	ds_read2_b32 v[22:23], v54 offset0:16 offset1:49
	global_store_dwordx4 v[24:25], v[14:17], off
	v_lshlrev_b64 v[18:19], 14, v[18:19]
	v_lshl_add_u64 v[18:19], v[20:21], 0, v[18:19]
	s_waitcnt lgkmcnt(0)
	v_cvt_pk_bf16_f32 v14, v22, v23
	ds_read2_b32 v[16:17], v54 offset0:82 offset1:115
	s_waitcnt lgkmcnt(0)
	v_cvt_pk_bf16_f32 v15, v16, v17
	ds_read2_b32 v[16:17], v54 offset0:148 offset1:181
	s_waitcnt lgkmcnt(0)
	v_cvt_pk_bf16_f32 v16, v16, v17
	ds_read2_b32 v[22:23], v54 offset0:214 offset1:247
	s_waitcnt lgkmcnt(0)
	v_cvt_pk_bf16_f32 v17, v22, v23
	ds_read2_b32 v[22:23], v54 offset0:24 offset1:57
	global_store_dwordx4 v[26:27], v[14:17], off
	v_cmp_lt_i32_e32 vcc, s42, v34
	s_or_b64 s[0:1], vcc, s[0:1]
	s_waitcnt lgkmcnt(0)
	v_cvt_pk_bf16_f32 v14, v22, v23
	ds_read2_b32 v[16:17], v54 offset0:90 offset1:123
	s_waitcnt lgkmcnt(0)
	v_cvt_pk_bf16_f32 v15, v16, v17
	ds_read2_b32 v[16:17], v54 offset0:156 offset1:189
	s_waitcnt lgkmcnt(0)
	v_cvt_pk_bf16_f32 v16, v16, v17
	ds_read2_b32 v[22:23], v54 offset0:222 offset1:255
	s_waitcnt lgkmcnt(0)
	v_cvt_pk_bf16_f32 v17, v22, v23
	global_store_dwordx4 v[18:19], v[14:17], off
	s_waitcnt lgkmcnt(0)
	s_andn2_b64 exec, exec, s[0:1]
	s_cbranch_execnz .LBB0_39

.LBB0_57:
	v_readlane_b32 s4, v253, 1
	v_readlane_b32 s5, v253, 2
	v_readlane_b32 s6, v253, 3
	v_readlane_b32 s7, v253, 4
	s_mov_b64 s[0:1], s[4:5]
	s_mov_b64 s[8:9], s[6:7]
	s_nop 0
	v_writelane_b32 v254, s0, 22
	s_nop 1
	v_writelane_b32 v254, s1, 23
	s_add_u32 s0, s8, 0x5500000
	s_addc_u32 s1, s9, 0
	v_writelane_b32 v254, s0, 24
	s_nop 1
	v_writelane_b32 v254, s1, 25
	s_add_u32 s0, s8, 0x7500000
	s_addc_u32 s1, s9, 0
	v_writelane_b32 v254, s0, 26
	s_cmp_eq_u32 s73, 0
	s_nop 0
	v_writelane_b32 v254, s1, 27
	s_cselect_b64 s[0:1], -1, 0
	v_writelane_b32 v254, s0, 28
	s_and_b64 vcc, exec, s[0:1]
	s_nop 0
	v_writelane_b32 v254, s1, 29
	s_cbranch_vccnz .LBB0_67
	v_mov_b32_e32 v2, s8
	v_add_co_u32_e32 v2, vcc, 0xd0000, v2
	s_waitcnt lgkmcnt(0)
	v_mov_b32_e32 v3, s9
	v_mov_b32_e32 v0, v206
	v_addc_co_u32_e32 v3, vcc, 0, v3, vcc
	global_load_dwordx2 v[4:5], v[2:3], off offset:144 sc1
	global_load_dwordx2 v[6:7], v[2:3], off offset:24 sc1
	v_and_b32_e32 v8, 63, v0
	v_ashrrev_i32_e32 v9, 6, v0
	v_readlane_b32 s0, v254, 19
	v_and_b32_e32 v2, 31, v0
	v_lshl_add_u32 v3, v9, 14, 0
	v_add_u32_e32 v42, s0, v9
	v_lshrrev_b32_e32 v43, 5, v8
	v_lshrrev_b32_e32 v44, 3, v8
	v_lshlrev_b32_e32 v0, 3, v8
	s_movk_i32 s0, 0x2000
	s_lshl_b32 s2, s73, 26
	v_cmp_gt_i32_e64 s[36:37], s0, v42
	v_lshl_add_u32 v46, v2, 2, v3
	v_mul_u32_u24_e32 v47, 0x84, v43
	v_and_b32_e32 v49, 56, v0
	v_lshlrev_b32_e32 v48, 2, v44
	v_lshlrev_b32_e32 v45, 5, v42
	s_waitcnt vmcnt(0) lgkmcnt(0)
	v_readfirstlane_b32 s5, v5
	v_readfirstlane_b32 s4, v4
	v_readfirstlane_b32 s13, v7
	v_readfirstlane_b32 s12, v6
	s_and_saveexec_b64 s[0:1], s[36:37]
	s_cbranch_execz .LBB0_63
	s_add_u32 s4, s4, s2
	s_addc_u32 s5, s5, 0
	s_lshl_b32 s54, s73, 11
	s_lshl_b64 s[6:7], s[54:55], 2
	s_add_u32 s6, s12, s6
	s_addc_u32 s7, s13, s7
	s_cmp_lg_u64 s[12:13], 0
	v_readlane_b32 s12, v254, 24
	v_mul_u32_u24_e32 v6, 0x84, v49
	v_lshlrev_b32_e32 v0, 1, v49
	v_readlane_b32 s13, v254, 25
	s_mov_b32 s54, 0x34000
	s_mov_b64 s[10:11], 0
	v_lshl_add_u64 v[4:5], s[12:13], 0, v[0:1]
	v_add3_u32 v50, v3, v6, v48
	v_lshlrev_b32_e32 v51, 5, v42
	v_lshlrev_b32_e32 v0, 2, v2
	s_cselect_b64 s[12:13], -1, 0
	v_add_u32_e32 v52, v46, v47
	v_mov_b32_e32 v53, v42
	s_branch .LBB0_61
.LBB0_60:
	s_waitcnt vmcnt(0) lgkmcnt(0)
	ds_write2_b32 v52, v8, v9 offset1:66
	ds_write2_b32 v52, v12, v13 offset0:132 offset1:198
	v_add_u32_e32 v8, 0x400, v52
	ds_write2_b32 v8, v10, v11 offset0:8 offset1:74
	ds_write2_b32 v8, v14, v15 offset0:140 offset1:206
	v_add_u32_e32 v8, 0x800, v52
	ds_write2_b32 v8, v16, v17 offset0:16 offset1:82
	ds_write2_b32 v8, v20, v21 offset0:148 offset1:214
	v_add_u32_e32 v8, 0xc00, v52
	ds_write2_b32 v8, v18, v19 offset0:24 offset1:90
	ds_write2_b32 v8, v22, v23 offset0:156 offset1:222
	v_add_u32_e32 v8, 0x1000, v52
	ds_write2_b32 v8, v24, v25 offset0:32 offset1:98
	ds_write2_b32 v8, v28, v29 offset0:164 offset1:230
	v_add_u32_e32 v8, 0x1400, v52
	ds_write2_b32 v8, v26, v27 offset0:40 offset1:106
	ds_write2_b32 v8, v30, v31 offset0:172 offset1:238
	v_add_u32_e32 v8, 0x1800, v52
	ds_write2_b32 v8, v32, v33 offset0:48 offset1:114
	ds_write2_b32 v8, v38, v39 offset0:180 offset1:246
	v_add_u32_e32 v8, 0x1c00, v52
	ds_write2_b32 v8, v36, v37 offset0:56 offset1:122
	ds_write2_b32 v8, v34, v35 offset0:188 offset1:254
	s_waitcnt lgkmcnt(0)
	ds_read2_b32 v[8:9], v50 offset1:33
	s_waitcnt lgkmcnt(0)
	v_cvt_pk_bf16_f32 v8, v8, v9
	ds_read2_b32 v[10:11], v50 offset0:66 offset1:99
	s_waitcnt lgkmcnt(0)
	v_cvt_pk_bf16_f32 v9, v10, v11
	ds_read2_b32 v[10:11], v50 offset0:132 offset1:165
	s_waitcnt lgkmcnt(0)
	v_cvt_pk_bf16_f32 v10, v10, v11
	ds_read2_b32 v[12:13], v50 offset0:198 offset1:231
	v_sub_u32_e32 v16, 0, v7
	s_waitcnt lgkmcnt(0)
	v_cvt_pk_bf16_f32 v11, v12, v13
	v_add3_u32 v12, v44, v51, v16
	v_ashrrev_i32_e32 v7, 31, v6
	v_ashrrev_i32_e32 v13, 31, v12
	v_lshl_add_u64 v[14:15], v[6:7], 1, v[4:5]
	v_lshlrev_b64 v[6:7], 12, v[12:13]
	v_lshl_add_u64 v[6:7], v[14:15], 0, v[6:7]
	global_store_dwordx4 v[6:7], v[8:11], off
	ds_read2_b32 v[6:7], v50 offset0:8 offset1:41
	s_waitcnt lgkmcnt(0)
	v_cvt_pk_bf16_f32 v6, v6, v7
	ds_read2_b32 v[8:9], v50 offset0:74 offset1:107
	s_waitcnt lgkmcnt(0)
	v_cvt_pk_bf16_f32 v7, v8, v9
	ds_read2_b32 v[8:9], v50 offset0:140 offset1:173
	s_waitcnt lgkmcnt(0)
	v_cvt_pk_bf16_f32 v8, v8, v9
	ds_read2_b32 v[10:11], v50 offset0:206 offset1:239
	s_waitcnt lgkmcnt(0)
	v_cvt_pk_bf16_f32 v9, v10, v11
	v_add_u32_e32 v10, 8, v12
	v_ashrrev_i32_e32 v11, 31, v10
	v_lshlrev_b64 v[10:11], 12, v[10:11]
	v_lshl_add_u64 v[10:11], v[14:15], 0, v[10:11]
	global_store_dwordx4 v[10:11], v[6:9], off
	v_add_u32_e32 v16, 16, v12
	ds_read2_b32 v[6:7], v50 offset0:16 offset1:49
	v_ashrrev_i32_e32 v17, 31, v16
	s_waitcnt lgkmcnt(0)
	v_cvt_pk_bf16_f32 v6, v6, v7
	ds_read2_b32 v[8:9], v50 offset0:82 offset1:115
	v_lshlrev_b64 v[16:17], 12, v[16:17]
	s_waitcnt lgkmcnt(0)
	v_cvt_pk_bf16_f32 v7, v8, v9
	ds_read2_b32 v[8:9], v50 offset0:148 offset1:181
	v_lshl_add_u64 v[16:17], v[14:15], 0, v[16:17]
	s_waitcnt lgkmcnt(0)
	v_cvt_pk_bf16_f32 v8, v8, v9
	ds_read2_b32 v[10:11], v50 offset0:214 offset1:247
	s_waitcnt lgkmcnt(0)
	v_cvt_pk_bf16_f32 v9, v10, v11
	global_store_dwordx4 v[16:17], v[6:9], off
	v_add_u32_e32 v12, 24, v12
	ds_read2_b32 v[6:7], v50 offset0:24 offset1:57
	v_ashrrev_i32_e32 v13, 31, v12
	s_waitcnt lgkmcnt(0)
	v_cvt_pk_bf16_f32 v6, v6, v7
	ds_read2_b32 v[8:9], v50 offset0:90 offset1:123
	v_lshlrev_b64 v[12:13], 12, v[12:13]
	s_waitcnt lgkmcnt(0)
	v_cvt_pk_bf16_f32 v7, v8, v9
	ds_read2_b32 v[8:9], v50 offset0:156 offset1:189
	v_lshl_add_u64 v[12:13], v[14:15], 0, v[12:13]
	s_waitcnt lgkmcnt(0)
	v_cvt_pk_bf16_f32 v8, v8, v9
	ds_read2_b32 v[10:11], v50 offset0:222 offset1:255
	s_waitcnt lgkmcnt(0)
	v_cvt_pk_bf16_f32 v9, v10, v11
	global_store_dwordx4 v[12:13], v[6:9], off
	s_waitcnt lgkmcnt(0)
	v_add_u32_e32 v53, s52, v53
	v_cmp_lt_i32_e32 vcc, s19, v53
	s_or_b64 s[10:11], vcc, s[10:11]
	v_add_u32_e32 v51, s3, v51
	s_andn2_b64 exec, exec, s[10:11]
	s_cbranch_execz .LBB0_63
.LBB0_61:
	v_ashrrev_i32_e32 v6, 31, v53
	v_add_u32_sdwa v6, v53, v6 dst_sel:DWORD dst_unused:UNUSED_PAD src0_sel:DWORD src1_sel:BYTE_3
	v_ashrrev_i32_e32 v6, 8, v6
	v_mul_i32_i24_e32 v7, 0x100, v6
	v_lshlrev_b32_e32 v6, 6, v6
	v_or_b32_e32 v40, v6, v43
	v_lshlrev_b32_e32 v7, 5, v7
	v_ashrrev_i32_e32 v41, 31, v40
	v_sub_u32_e32 v8, v51, v7
	v_lshlrev_b64 v[10:11], 15, v[40:41]
	v_lshl_add_u64 v[10:11], s[4:5], 0, v[10:11]
	v_ashrrev_i32_e32 v9, 31, v8
	v_lshl_add_u64 v[8:9], v[8:9], 2, v[10:11]
	v_lshl_add_u64 v[32:33], v[8:9], 0, v[0:1]
	v_add_co_u32_e32 v10, vcc, s56, v32
	s_mov_b32 s14, 0x50000
	s_nop 0
	v_addc_co_u32_e32 v11, vcc, 0, v33, vcc
	v_add_co_u32_e32 v12, vcc, s57, v32
	s_nop 1
	v_addc_co_u32_e32 v13, vcc, 0, v33, vcc
	v_add_co_u32_e32 v14, vcc, s83, v32
	s_nop 1
	v_addc_co_u32_e32 v15, vcc, 0, v33, vcc
	v_add_co_u32_e32 v16, vcc, s18, v32
	s_nop 1
	v_addc_co_u32_e32 v17, vcc, 0, v33, vcc
	v_add_co_u32_e32 v18, vcc, s14, v32
	s_mov_b32 s14, 0x70000
	s_nop 0
	v_addc_co_u32_e32 v19, vcc, 0, v33, vcc
	v_add_co_u32_e32 v20, vcc, s86, v32
	s_nop 1
	v_addc_co_u32_e32 v21, vcc, 0, v33, vcc
	v_add_co_u32_e32 v22, vcc, s14, v32
	s_mov_b32 s14, 0x80000
	s_nop 0
	v_addc_co_u32_e32 v23, vcc, 0, v33, vcc
	global_load_dword v8, v[32:33], off nt
	global_load_dword v9, v[10:11], off nt
	s_nop 0
	global_load_dword v12, v[12:13], off nt
	s_nop 0
	global_load_dword v13, v[14:15], off nt
	global_load_dword v10, v[16:17], off nt
	global_load_dword v11, v[18:19], off nt
	s_nop 0
	global_load_dword v14, v[20:21], off nt
	global_load_dword v15, v[22:23], off nt
	v_add_co_u32_e32 v16, vcc, s14, v32
	s_mov_b32 s14, 0x90000
	s_nop 0
	v_addc_co_u32_e32 v17, vcc, 0, v33, vcc
	v_add_co_u32_e32 v18, vcc, s14, v32
	s_mov_b32 s14, 0xa0000
	s_nop 0
	v_addc_co_u32_e32 v19, vcc, 0, v33, vcc
	v_add_co_u32_e32 v20, vcc, s14, v32
	s_mov_b32 s14, 0xb0000
	s_nop 0
	v_addc_co_u32_e32 v21, vcc, 0, v33, vcc
	v_add_co_u32_e32 v22, vcc, s14, v32
	s_mov_b32 s14, 0xc0000
	s_nop 0
	v_addc_co_u32_e32 v23, vcc, 0, v33, vcc
	v_add_co_u32_e32 v24, vcc, s14, v32
	s_mov_b32 s14, 0xd0000
	s_nop 0
	v_addc_co_u32_e32 v25, vcc, 0, v33, vcc
	v_add_co_u32_e32 v26, vcc, s14, v32
	s_mov_b32 s14, 0xe0000
	s_nop 0
	v_addc_co_u32_e32 v27, vcc, 0, v33, vcc
	v_add_co_u32_e32 v28, vcc, s14, v32
	s_mov_b32 s14, 0xf0000
	s_nop 0
	v_addc_co_u32_e32 v29, vcc, 0, v33, vcc
	v_add_co_u32_e32 v30, vcc, s14, v32
	s_mov_b32 s14, 0x100000
	s_nop 0
	v_addc_co_u32_e32 v31, vcc, 0, v33, vcc
	global_load_dword v16, v[16:17], off nt
	s_nop 0
	global_load_dword v17, v[18:19], off nt
	s_nop 0
	global_load_dword v20, v[20:21], off nt
	s_nop 0
	global_load_dword v21, v[22:23], off nt
	global_load_dword v18, v[24:25], off nt
	global_load_dword v19, v[26:27], off nt
	s_nop 0
	global_load_dword v22, v[28:29], off nt
	global_load_dword v23, v[30:31], off nt
	v_add_co_u32_e32 v24, vcc, s14, v32
	s_mov_b32 s14, 0x110000
	s_nop 0
	v_addc_co_u32_e32 v25, vcc, 0, v33, vcc
	v_add_co_u32_e32 v26, vcc, s14, v32
	s_mov_b32 s14, 0x120000
	s_nop 0
	v_addc_co_u32_e32 v27, vcc, 0, v33, vcc
	v_add_co_u32_e32 v28, vcc, s14, v32
	s_mov_b32 s14, 0x130000
	s_nop 0
	v_addc_co_u32_e32 v29, vcc, 0, v33, vcc
	v_add_co_u32_e32 v30, vcc, s14, v32
	s_mov_b32 s14, 0x140000
	s_nop 0
	v_addc_co_u32_e32 v31, vcc, 0, v33, vcc
	v_add_co_u32_e32 v34, vcc, s14, v32
	s_mov_b32 s14, 0x150000
	s_nop 0
	v_addc_co_u32_e32 v35, vcc, 0, v33, vcc
	v_add_co_u32_e32 v36, vcc, s14, v32
	s_mov_b32 s14, 0x160000
	s_nop 0
	v_addc_co_u32_e32 v37, vcc, 0, v33, vcc
	v_add_co_u32_e32 v38, vcc, s14, v32
	s_mov_b32 s14, 0x170000
	s_nop 0
	v_addc_co_u32_e32 v39, vcc, 0, v33, vcc
	v_add_co_u32_e32 v54, vcc, s14, v32
	s_mov_b32 s14, 0x180000
	s_nop 0
	v_addc_co_u32_e32 v55, vcc, 0, v33, vcc
	global_load_dword v24, v[24:25], off nt
	s_nop 0
	global_load_dword v25, v[26:27], off nt
	s_nop 0
	global_load_dword v28, v[28:29], off nt
	s_nop 0
	global_load_dword v29, v[30:31], off nt
	global_load_dword v26, v[34:35], off nt
	global_load_dword v27, v[36:37], off nt
	s_nop 0
	global_load_dword v30, v[38:39], off nt
	global_load_dword v31, v[54:55], off nt
	v_add_co_u32_e32 v34, vcc, s14, v32
	s_mov_b32 s14, 0x190000
	s_nop 0
	v_addc_co_u32_e32 v35, vcc, 0, v33, vcc
	v_add_co_u32_e32 v36, vcc, s14, v32
	s_mov_b32 s14, 0x1a0000
	s_nop 0
	v_addc_co_u32_e32 v37, vcc, 0, v33, vcc
	v_add_co_u32_e32 v38, vcc, s14, v32
	s_mov_b32 s14, 0x1b0000
	s_nop 0
	v_addc_co_u32_e32 v39, vcc, 0, v33, vcc
	v_add_co_u32_e32 v54, vcc, s14, v32
	s_mov_b32 s14, 0x1c0000
	s_nop 0
	v_addc_co_u32_e32 v55, vcc, 0, v33, vcc
	v_add_co_u32_e32 v56, vcc, s14, v32
	s_nop 1
	v_addc_co_u32_e32 v57, vcc, 0, v33, vcc
	v_add_co_u32_e32 v58, vcc, 0x1d0000, v32
	s_nop 1
	v_addc_co_u32_e32 v59, vcc, 0, v33, vcc
	v_add_co_u32_e32 v60, vcc, 0x1e0000, v32
	s_nop 1
	v_addc_co_u32_e32 v61, vcc, 0, v33, vcc
	v_add_co_u32_e32 v62, vcc, 0x1f0000, v32
	s_nop 1
	v_addc_co_u32_e32 v63, vcc, 0, v33, vcc
	global_load_dword v32, v[34:35], off nt
	global_load_dword v33, v[36:37], off nt
	s_nop 0
	global_load_dword v38, v[38:39], off nt
	s_nop 0
	global_load_dword v39, v[54:55], off nt
	global_load_dword v36, v[56:57], off nt
	global_load_dword v37, v[58:59], off nt
	global_load_dword v34, v[60:61], off nt
	global_load_dword v35, v[62:63], off nt
	s_andn2_b64 vcc, exec, s[12:13]
	s_cbranch_vccnz .LBB0_60
	v_lshl_add_u64 v[40:41], v[40:41], 2, s[6:7]
	global_load_dword v54, v[40:41], off
	global_load_dword v55, v[40:41], off offset:8
	global_load_dword v56, v[40:41], off offset:16
	global_load_dword v57, v[40:41], off offset:24
	global_load_dword v58, v[40:41], off offset:32
	global_load_dword v59, v[40:41], off offset:40
	global_load_dword v60, v[40:41], off offset:48
	global_load_dword v61, v[40:41], off offset:56
	global_load_dword v62, v[40:41], off offset:64
	global_load_dword v63, v[40:41], off offset:72
	global_load_dword v64, v[40:41], off offset:80
	global_load_dword v65, v[40:41], off offset:88
	global_load_dword v66, v[40:41], off offset:96
	global_load_dword v67, v[40:41], off offset:104
	global_load_dword v68, v[40:41], off offset:112
	global_load_dword v69, v[40:41], off offset:120
	global_load_dword v70, v[40:41], off offset:128
	global_load_dword v71, v[40:41], off offset:136
	global_load_dword v72, v[40:41], off offset:144
	global_load_dword v73, v[40:41], off offset:152
	global_load_dword v74, v[40:41], off offset:160
	global_load_dword v75, v[40:41], off offset:168
	global_load_dword v76, v[40:41], off offset:176
	global_load_dword v77, v[40:41], off offset:184
	global_load_dword v78, v[40:41], off offset:192
	global_load_dword v79, v[40:41], off offset:200
	global_load_dword v80, v[40:41], off offset:208
	global_load_dword v81, v[40:41], off offset:216
	global_load_dword v82, v[40:41], off offset:224
	global_load_dword v83, v[40:41], off offset:232
	global_load_dword v84, v[40:41], off offset:240
	global_load_dword v85, v[40:41], off offset:248
	s_waitcnt vmcnt(0) lgkmcnt(0)
	v_pk_mul_f32 v[8:9], v[8:9], v[54:55]
	v_pk_mul_f32 v[12:13], v[12:13], v[56:57]
	v_pk_mul_f32 v[10:11], v[10:11], v[58:59]
	v_pk_mul_f32 v[14:15], v[14:15], v[60:61]
	v_pk_mul_f32 v[16:17], v[16:17], v[62:63]
	v_pk_mul_f32 v[20:21], v[20:21], v[64:65]
	v_pk_mul_f32 v[18:19], v[18:19], v[66:67]
	v_pk_mul_f32 v[22:23], v[22:23], v[68:69]
	v_pk_mul_f32 v[24:25], v[24:25], v[70:71]
	v_pk_mul_f32 v[28:29], v[28:29], v[72:73]
	v_pk_mul_f32 v[26:27], v[26:27], v[74:75]
	v_pk_mul_f32 v[30:31], v[30:31], v[76:77]
	v_pk_mul_f32 v[32:33], v[32:33], v[78:79]
	v_pk_mul_f32 v[38:39], v[38:39], v[80:81]
	v_pk_mul_f32 v[36:37], v[36:37], v[82:83]
	v_pk_mul_f32 v[34:35], v[34:35], v[84:85]
	s_branch .LBB0_60
.LBB0_63:
	s_or_b64 exec, exec, s[0:1]
	v_mov_b32_e32 v0, s8
	v_add_co_u32_e32 v4, vcc, 0xd0000, v0
	v_mov_b32_e32 v0, s9
	s_nop 0
	v_addc_co_u32_e32 v5, vcc, 0, v0, vcc
	global_load_dwordx2 v[4:5], v[4:5], off offset:152 sc1
	s_waitcnt vmcnt(0) lgkmcnt(0)
	v_readfirstlane_b32 s5, v5
	v_readfirstlane_b32 s4, v4
	s_and_saveexec_b64 s[0:1], s[36:37]
	s_mov_b32 s10, 0x50000
	s_mov_b32 s11, 0x70000
	s_movk_i32 s12, 0x4000
	s_mov_b32 s13, 0x14000
	s_mov_b32 s14, 0x38000
	s_mov_b32 s15, 0x44000
	s_mov_b32 s16, 0x4c000
	s_mov_b32 s17, 0x58000
	s_mov_b32 s36, 0x5c000
	s_mov_b32 s37, 0x64000
	s_mov_b32 s38, 0x68000
	s_cbranch_execz .LBB0_66
	v_readlane_b32 s6, v254, 26
	s_add_u32 s4, s4, s2
	v_mul_u32_u24_e32 v6, 0x84, v49
	v_lshlrev_b32_e32 v0, 1, v49
	v_readlane_b32 s7, v254, 27
	s_addc_u32 s5, s5, 0
	v_add3_u32 v8, v3, v6, v48
	v_lshl_add_u64 v[4:5], s[6:7], 0, v[0:1]
	s_mov_b64 s[6:7], 0
	v_lshlrev_b32_e32 v0, 2, v2
	v_add_u32_e32 v9, v46, v47
.LBB0_65:
	v_ashrrev_i32_e32 v2, 31, v42
	v_lshrrev_b32_e32 v2, 26, v2
	v_add_u32_e32 v2, v42, v2
	v_and_b32_e32 v6, 0xffffffc0, v2
	v_lshlrev_b32_e32 v2, 5, v2
	v_or_b32_e32 v10, v6, v43
	v_and_b32_e32 v2, 0xfffff800, v2
	v_ashrrev_i32_e32 v11, 31, v10
	v_sub_u32_e32 v2, v45, v2
	v_lshlrev_b64 v[10:11], 13, v[10:11]
	v_ashrrev_i32_e32 v3, 31, v2
	v_lshl_add_u64 v[10:11], s[4:5], 0, v[10:11]
	v_lshl_add_u64 v[10:11], v[2:3], 2, v[10:11]
	v_lshl_add_u64 v[10:11], v[10:11], 0, v[0:1]
	v_add_co_u32_e32 v12, vcc, s12, v10
	v_add_u32_e32 v2, v2, v44
	s_nop 0
	v_addc_co_u32_e32 v13, vcc, 0, v11, vcc
	v_add_co_u32_e32 v14, vcc, s30, v10
	v_ashrrev_i32_e32 v7, 31, v6
	s_nop 0
	v_addc_co_u32_e32 v15, vcc, 0, v11, vcc
	v_add_co_u32_e32 v16, vcc, s91, v10
	v_lshl_add_u64 v[6:7], v[6:7], 1, v[4:5]
	s_nop 0
	v_addc_co_u32_e32 v17, vcc, 0, v11, vcc
	v_add_co_u32_e32 v18, vcc, s56, v10
	v_ashrrev_i32_e32 v3, 31, v2
	s_nop 0
	v_addc_co_u32_e32 v19, vcc, 0, v11, vcc
	v_add_co_u32_e32 v20, vcc, s13, v10
	v_add_u32_e32 v42, s52, v42
	s_nop 0
	v_addc_co_u32_e32 v21, vcc, 0, v11, vcc
	v_add_co_u32_e32 v22, vcc, s93, v10
	v_add_u32_e32 v45, s3, v45
	s_nop 0
	v_addc_co_u32_e32 v23, vcc, 0, v11, vcc
	v_add_co_u32_e32 v24, vcc, s31, v10
	s_nop 1
	v_addc_co_u32_e32 v25, vcc, 0, v11, vcc
	v_add_co_u32_e32 v26, vcc, s57, v10
	s_nop 1
	v_addc_co_u32_e32 v27, vcc, 0, v11, vcc
	v_add_co_u32_e32 v28, vcc, s95, v10
	s_nop 1
	v_addc_co_u32_e32 v29, vcc, 0, v11, vcc
	v_add_co_u32_e32 v30, vcc, s34, v10
	s_nop 1
	v_addc_co_u32_e32 v31, vcc, 0, v11, vcc
	v_add_co_u32_e32 v32, vcc, s35, v10
	s_nop 1
	v_addc_co_u32_e32 v33, vcc, 0, v11, vcc
	v_add_co_u32_e32 v34, vcc, s83, v10
	s_nop 1
	v_addc_co_u32_e32 v35, vcc, 0, v11, vcc
	v_add_co_u32_e32 v36, vcc, s54, v10
	s_nop 1
	v_addc_co_u32_e32 v37, vcc, 0, v11, vcc
	v_add_co_u32_e32 v38, vcc, s14, v10
	s_nop 1
	v_addc_co_u32_e32 v39, vcc, 0, v11, vcc
	v_add_co_u32_e32 v40, vcc, s33, v10
	s_nop 1
	v_addc_co_u32_e32 v41, vcc, 0, v11, vcc
	v_add_co_u32_e32 v46, vcc, s18, v10
	s_nop 1
	v_addc_co_u32_e32 v47, vcc, 0, v11, vcc
	v_add_co_u32_e32 v48, vcc, s15, v10
	s_nop 1
	v_addc_co_u32_e32 v49, vcc, 0, v11, vcc
	v_add_co_u32_e32 v50, vcc, s80, v10
	s_nop 1
	v_addc_co_u32_e32 v51, vcc, 0, v11, vcc
	v_add_co_u32_e32 v52, vcc, s16, v10
	s_nop 1
	v_addc_co_u32_e32 v53, vcc, 0, v11, vcc
	v_add_co_u32_e32 v54, vcc, s10, v10
	s_nop 1
	v_addc_co_u32_e32 v55, vcc, 0, v11, vcc
	v_add_co_u32_e32 v56, vcc, s97, v10
	s_nop 1
	v_addc_co_u32_e32 v57, vcc, 0, v11, vcc
	v_add_co_u32_e32 v58, vcc, s17, v10
	s_nop 1
	v_addc_co_u32_e32 v59, vcc, 0, v11, vcc
	v_add_co_u32_e32 v60, vcc, s36, v10
	s_nop 1
	v_addc_co_u32_e32 v61, vcc, 0, v11, vcc
	v_add_co_u32_e32 v62, vcc, s86, v10
	s_nop 1
	v_addc_co_u32_e32 v63, vcc, 0, v11, vcc
	v_add_co_u32_e32 v64, vcc, s37, v10
	s_nop 1
	v_addc_co_u32_e32 v65, vcc, 0, v11, vcc
	v_add_co_u32_e32 v66, vcc, s38, v10
	s_nop 1
	v_addc_co_u32_e32 v67, vcc, 0, v11, vcc
	v_add_co_u32_e32 v68, vcc, s94, v10
	s_nop 1
	v_addc_co_u32_e32 v69, vcc, 0, v11, vcc
	v_add_co_u32_e32 v70, vcc, s11, v10
	s_nop 1
	v_addc_co_u32_e32 v71, vcc, 0, v11, vcc
	v_add_co_u32_e32 v72, vcc, s90, v10
	s_nop 1
	v_addc_co_u32_e32 v73, vcc, 0, v11, vcc
	v_add_co_u32_e32 v74, vcc, s88, v10
	s_nop 1
	v_addc_co_u32_e32 v75, vcc, 0, v11, vcc
	v_add_co_u32_e32 v76, vcc, s82, v10
	s_nop 1
	v_addc_co_u32_e32 v77, vcc, 0, v11, vcc
	global_load_dword v78, v[10:11], off nt
	global_load_dword v79, v[12:13], off nt
	global_load_dword v80, v[14:15], off nt
	global_load_dword v81, v[16:17], off nt
	global_load_dword v82, v[18:19], off nt
	s_nop 0
	global_load_dword v20, v[20:21], off nt
	s_nop 0
	global_load_dword v21, v[22:23], off nt
	s_nop 0
	global_load_dword v22, v[24:25], off nt
	global_load_dword v23, v[26:27], off nt
	s_nop 0
	global_load_dword v24, v[28:29], off nt
	global_load_dword v25, v[30:31], off nt
	global_load_dword v26, v[32:33], off nt
	global_load_dword v27, v[34:35], off nt
	s_nop 0
	global_load_dword v28, v[36:37], off nt
	global_load_dword v29, v[38:39], off nt
	global_load_dword v30, v[40:41], off nt
	global_load_dword v31, v[46:47], off nt
	global_load_dword v32, v[48:49], off nt
	global_load_dword v33, v[50:51], off nt
	global_load_dword v34, v[52:53], off nt
	global_load_dword v35, v[54:55], off nt
	global_load_dword v36, v[56:57], off nt
	global_load_dword v37, v[58:59], off nt
	global_load_dword v38, v[60:61], off nt
	global_load_dword v39, v[62:63], off nt
	global_load_dword v40, v[64:65], off nt
	global_load_dword v41, v[66:67], off nt
	global_load_dword v46, v[68:69], off nt
	global_load_dword v47, v[70:71], off nt
	global_load_dword v48, v[72:73], off nt
	global_load_dword v49, v[74:75], off nt
	global_load_dword v50, v[76:77], off nt
	v_add_u32_e32 v10, 8, v2
	v_add_u32_e32 v51, 0x400, v9
	v_add_u32_e32 v52, 0x800, v9
	v_add_u32_e32 v53, 0xc00, v9
	v_add_u32_e32 v54, 0x1000, v9
	v_add_u32_e32 v55, 0x1400, v9
	v_add_u32_e32 v56, 0x1800, v9
	v_add_u32_e32 v57, 0x1c00, v9
	v_ashrrev_i32_e32 v11, 31, v10
	s_waitcnt vmcnt(0) lgkmcnt(0)
	ds_write2_b32 v9, v78, v79 offset1:66
	ds_write2_b32 v9, v80, v81 offset0:132 offset1:198
	ds_write2_b32 v51, v82, v20 offset0:8 offset1:74
	ds_write2_b32 v51, v21, v22 offset0:140 offset1:206
	ds_write2_b32 v52, v23, v24 offset0:16 offset1:82
	ds_write2_b32 v52, v25, v26 offset0:148 offset1:214
	ds_write2_b32 v53, v27, v28 offset0:24 offset1:90
	ds_write2_b32 v53, v29, v30 offset0:156 offset1:222
	ds_write2_b32 v54, v31, v32 offset0:32 offset1:98
	ds_write2_b32 v54, v33, v34 offset0:164 offset1:230
	ds_write2_b32 v55, v35, v36 offset0:40 offset1:106
	ds_write2_b32 v55, v37, v38 offset0:172 offset1:238
	ds_write2_b32 v56, v39, v40 offset0:48 offset1:114
	ds_write2_b32 v56, v41, v46 offset0:180 offset1:246
	ds_write2_b32 v57, v47, v48 offset0:56 offset1:122
	ds_write2_b32 v57, v49, v50 offset0:188 offset1:254
	v_add_u32_e32 v12, 16, v2
	v_lshlrev_b64 v[10:11], 14, v[10:11]
	s_waitcnt lgkmcnt(0)
	v_ashrrev_i32_e32 v13, 31, v12
	v_lshl_add_u64 v[18:19], v[6:7], 0, v[10:11]
	ds_read2_b32 v[10:11], v8 offset1:33
	v_lshlrev_b64 v[14:15], 14, v[2:3]
	v_lshlrev_b64 v[16:17], 14, v[12:13]
	s_waitcnt lgkmcnt(0)
	v_cvt_pk_bf16_f32 v10, v10, v11
	ds_read2_b32 v[12:13], v8 offset0:66 offset1:99
	v_lshl_add_u64 v[14:15], v[6:7], 0, v[14:15]
	s_waitcnt lgkmcnt(0)
	v_cvt_pk_bf16_f32 v11, v12, v13
	ds_read2_b32 v[12:13], v8 offset0:132 offset1:165
	s_waitcnt lgkmcnt(0)
	v_cvt_pk_bf16_f32 v12, v12, v13
	ds_read2_b32 v[20:21], v8 offset0:198 offset1:231
	s_waitcnt lgkmcnt(0)
	v_cvt_pk_bf16_f32 v13, v20, v21
	global_store_dwordx4 v[14:15], v[10:13], off
	ds_read2_b32 v[10:11], v8 offset0:8 offset1:41
	v_lshl_add_u64 v[16:17], v[6:7], 0, v[16:17]
	s_waitcnt lgkmcnt(0)
	v_cvt_pk_bf16_f32 v10, v10, v11
	ds_read2_b32 v[12:13], v8 offset0:74 offset1:107
	s_waitcnt lgkmcnt(0)
	v_cvt_pk_bf16_f32 v11, v12, v13
	ds_read2_b32 v[12:13], v8 offset0:140 offset1:173
	s_waitcnt lgkmcnt(0)
	v_cvt_pk_bf16_f32 v12, v12, v13
	ds_read2_b32 v[14:15], v8 offset0:206 offset1:239
	s_waitcnt lgkmcnt(0)
	v_cvt_pk_bf16_f32 v13, v14, v15
	global_store_dwordx4 v[18:19], v[10:13], off
	ds_read2_b32 v[10:11], v8 offset0:16 offset1:49
	v_add_u32_e32 v2, 24, v2
	s_waitcnt lgkmcnt(0)
	v_cvt_pk_bf16_f32 v10, v10, v11
	ds_read2_b32 v[12:13], v8 offset0:82 offset1:115
	s_waitcnt lgkmcnt(0)
	v_cvt_pk_bf16_f32 v11, v12, v13
	ds_read2_b32 v[12:13], v8 offset0:148 offset1:181
	s_waitcnt lgkmcnt(0)
	v_cvt_pk_bf16_f32 v12, v12, v13
	ds_read2_b32 v[14:15], v8 offset0:214 offset1:247
	s_waitcnt lgkmcnt(0)
	v_cvt_pk_bf16_f32 v13, v14, v15
	global_store_dwordx4 v[16:17], v[10:13], off
	ds_read2_b32 v[10:11], v8 offset0:24 offset1:57
	v_ashrrev_i32_e32 v3, 31, v2
	s_waitcnt lgkmcnt(0)
	v_cvt_pk_bf16_f32 v10, v10, v11
	ds_read2_b32 v[12:13], v8 offset0:90 offset1:123
	v_lshlrev_b64 v[2:3], 14, v[2:3]
	s_waitcnt lgkmcnt(0)
	v_cvt_pk_bf16_f32 v11, v12, v13
	ds_read2_b32 v[12:13], v8 offset0:156 offset1:189
	v_lshl_add_u64 v[2:3], v[6:7], 0, v[2:3]
	s_waitcnt lgkmcnt(0)
	v_cvt_pk_bf16_f32 v12, v12, v13
	ds_read2_b32 v[14:15], v8 offset0:222 offset1:255
	s_waitcnt lgkmcnt(0)
	v_cvt_pk_bf16_f32 v13, v14, v15
	global_store_dwordx4 v[2:3], v[10:13], off
	s_waitcnt lgkmcnt(0)
	v_cmp_lt_i32_e32 vcc, s19, v42
	s_or_b64 s[6:7], vcc, s[6:7]
	s_andn2_b64 exec, exec, s[6:7]
	s_cbranch_execnz .LBB0_65

.LBB0_82:
	v_lshl_add_u32 v146, s42, 8, v139
	v_readlane_b32 s28, v254, 32
	v_ashrrev_i32_e32 v147, 31, v146
	v_readlane_b32 s29, v254, 33
	s_add_i32 s6, s40, s2
	s_cmp_lg_u32 s6, 2
	v_lshl_add_u64 v[150:151], v[146:147], 2, s[28:29]
	global_load_dword v0, v[150:151], off
	global_load_dword v159, v[150:151], off offset:64
	global_load_dword v158, v[150:151], off offset:128
	global_load_dword v157, v[150:151], off offset:192
	global_load_dword v156, v[150:151], off offset:512
	global_load_dword v155, v[150:151], off offset:576
	global_load_dword v154, v[150:151], off offset:640
	global_load_dword v153, v[150:151], off offset:704
	s_cselect_b64 s[42:43], -1, 0
	s_cmp_gt_i32 s6, 1
	s_cselect_b64 s[64:65], -1, 0
	s_lshl_b32 s62, s6, 8
	s_add_i32 s54, s62, 0xfffffd00
	s_ashr_i32 s63, s62, 31
	s_mov_b64 s[40:41], -1
	s_mov_b32 s57, 0x20000
	s_waitcnt vmcnt(0) lgkmcnt(0)
	v_fmamk_f32 v0, v0, 0x3a000000, v207
	v_cmp_gt_f32_e32 vcc, s87, v0
	v_mul_f32_e32 v148, 0x4b800000, v0
	s_nop 0
	v_cndmask_b32_e32 v0, v0, v148, vcc
	v_rsq_f32_e32 v0, v0
	s_nop 0
	v_mul_f32_e32 v148, 0x45800000, v0
	v_cndmask_b32_e32 v148, v0, v148, vcc
	s_and_b64 vcc, exec, s[42:43]
	s_cbranch_vccz .LBB0_90
	s_and_b64 vcc, exec, s[64:65]
	s_cbranch_vccz .LBB0_85
	v_mov_b64_e32 v[150:151], s[14:15]
	s_movk_i32 s6, 0xc00
	v_mad_i64_i32 v[150:151], s[6:7], v146, s6, v[150:151]
	v_lshl_add_u64 v[150:151], s[54:55], 1, v[150:151]
	s_mov_b64 s[40:41], 0

.LBB0_87:
	v_lshlrev_b32_e32 v0, 1, v138
	v_pk_mul_f32 v[162:163], v[120:121], v[148:149] op_sel_hi:[1,0]
	v_pk_mul_f32 v[160:161], v[118:119], v[148:149] op_sel_hi:[1,0]
	v_lshl_add_u64 v[150:151], v[150:151], 0, v[0:1]
	v_mul_f32_e32 v0, v161, v161
	v_mul_f32_e32 v168, v163, v163
	v_pk_mul_f32 v[166:167], v[114:115], v[148:149] op_sel_hi:[1,0]
	v_fmac_f32_e32 v0, v160, v160
	v_fmac_f32_e32 v168, v162, v162
	v_add_f32_e32 v0, v0, v168
	v_mul_f32_e32 v168, v167, v167
	v_pk_mul_f32 v[128:129], v[128:129], v[148:149] op_sel_hi:[1,0]
	v_pk_mul_f32 v[126:127], v[126:127], v[148:149] op_sel_hi:[1,0]
	v_pk_mul_f32 v[164:165], v[116:117], v[148:149] op_sel_hi:[1,0]
	v_fmac_f32_e32 v168, v166, v166
	v_pk_mul_f32 v[170:171], v[122:123], v[148:149] op_sel_hi:[1,0]
	v_mul_f32_e32 v122, v127, v127
	v_mul_f32_e32 v123, v129, v129
	v_add_f32_e32 v0, v168, v0
	v_mul_f32_e32 v168, v165, v165
	v_fmac_f32_e32 v122, v126, v126
	v_fmac_f32_e32 v123, v128, v128
	v_fmac_f32_e32 v168, v164, v164
	v_add_f32_e32 v122, v122, v123
	v_mul_f32_e32 v123, v171, v171
	v_add_f32_e32 v0, v168, v0
	v_pk_mul_f32 v[168:169], v[124:125], v[148:149] op_sel_hi:[1,0]
	v_fmac_f32_e32 v123, v170, v170
	v_add_f32_e32 v122, v123, v122
	v_mul_f32_e32 v123, v169, v169
	v_fmac_f32_e32 v123, v168, v168
	v_add_f32_e32 v122, v123, v122
	v_and_b32_e32 v123, 64, v228
	v_add_f32_e32 v0, v0, v122
	v_xor_b32_e32 v122, 16, v228
	v_add_u32_e32 v123, 64, v123
	v_cmp_lt_i32_e32 vcc, v122, v123
	v_cvt_pk_bf16_f32 v160, v160, v161
	v_cvt_pk_bf16_f32 v161, v162, v163
	v_cvt_pk_bf16_f32 v162, v166, v167
	v_cvt_pk_bf16_f32 v163, v164, v165
	global_store_dwordx4 v[150:151], v[160:163], off
	s_nop 0
	v_cndmask_b32_e32 v122, v228, v122, vcc
	v_lshlrev_b32_e32 v122, 2, v122
	ds_bpermute_b32 v122, v122, v0
	v_cvt_pk_bf16_f32 v124, v126, v127
	v_cvt_pk_bf16_f32 v125, v128, v129
	v_cvt_pk_bf16_f32 v126, v170, v171
	v_cvt_pk_bf16_f32 v127, v168, v169
	s_waitcnt lgkmcnt(0)
	v_add_f32_e32 v0, v0, v122
	v_xor_b32_e32 v122, 32, v228
	v_cmp_lt_i32_e32 vcc, v122, v123
	global_store_dwordx4 v[150:151], v[124:127], off offset:256
	s_nop 0
	v_cndmask_b32_e32 v122, v228, v122, vcc
	v_lshlrev_b32_e32 v122, 2, v122
	ds_bpermute_b32 v122, v122, v0
	s_and_saveexec_b64 s[44:45], s[36:37]
	s_cbranch_execz .LBB0_89
	v_lshl_add_u64 v[124:125], v[146:147], 2, s[40:41]
	s_waitcnt lgkmcnt(0)
	v_add_f32_e32 v0, v0, v122
	global_atomic_add_f32 v[124:125], v0, off

.LBB0_90:
	v_cndmask_b32_e64 v0, 0, 1, s[30:31]
	s_and_b64 vcc, exec, s[40:41]
	v_cmp_ne_u32_e64 s[40:41], 1, v0
	s_cbranch_vccz .LBB0_93
	s_and_b64 vcc, exec, s[40:41]
	s_cbranch_vccnz .LBB0_93
	s_waitcnt lgkmcnt(0)
	v_lshlrev_b64 v[122:123], 8, v[146:147]
	v_lshl_add_u64 v[122:123], v[140:141], 0, v[122:123]
	v_pk_mul_f32 v[120:121], v[120:121], v[148:149] op_sel_hi:[1,0]
	v_pk_mul_f32 v[118:119], v[118:119], v[148:149] op_sel_hi:[1,0]
	v_pk_mul_f32 v[116:117], v[116:117], v[148:149] op_sel_hi:[1,0]
	v_pk_mul_f32 v[114:115], v[114:115], v[148:149] op_sel_hi:[1,0]
	global_store_dwordx4 v[122:123], v[118:121], off
	global_store_dwordx4 v[122:123], v[114:117], off offset:16

.LBB0_98:
	v_lshlrev_b32_e32 v0, 1, v138
	s_waitcnt lgkmcnt(0)
	v_lshl_add_u64 v[122:123], v[118:119], 0, v[0:1]
	v_pk_mul_f32 v[120:121], v[104:105], v[114:115] op_sel_hi:[1,0]
	v_pk_mul_f32 v[118:119], v[102:103], v[114:115] op_sel_hi:[1,0]
	v_pk_mul_f32 v[124:125], v[100:101], v[114:115] op_sel_hi:[1,0]
	v_pk_mul_f32 v[126:127], v[98:99], v[114:115] op_sel_hi:[1,0]
	v_mul_f32_e32 v0, v119, v119
	v_mul_f32_e32 v115, v121, v121
	v_fmac_f32_e32 v0, v118, v118
	v_fmac_f32_e32 v115, v120, v120
	v_add_f32_e32 v0, v0, v115
	v_mul_f32_e32 v115, v127, v127
	v_fmac_f32_e32 v115, v126, v126
	v_add_f32_e32 v0, v115, v0
	v_mul_f32_e32 v115, v125, v125
	v_fmac_f32_e32 v115, v124, v124
	v_pk_mul_f32 v[112:113], v[112:113], v[114:115] op_sel_hi:[1,0]
	v_pk_mul_f32 v[110:111], v[110:111], v[114:115] op_sel_hi:[1,0]
	v_pk_mul_f32 v[150:151], v[106:107], v[114:115] op_sel_hi:[1,0]
	v_mul_f32_e32 v106, v111, v111
	v_mul_f32_e32 v107, v113, v113
	v_fmac_f32_e32 v106, v110, v110
	v_fmac_f32_e32 v107, v112, v112
	v_add_f32_e32 v106, v106, v107
	v_mul_f32_e32 v107, v151, v151
	v_pk_mul_f32 v[128:129], v[108:109], v[114:115] op_sel_hi:[1,0]
	v_fmac_f32_e32 v107, v150, v150
	v_add_f32_e32 v106, v107, v106
	v_mul_f32_e32 v107, v129, v129
	v_fmac_f32_e32 v107, v128, v128
	v_add_f32_e32 v0, v115, v0
	v_add_f32_e32 v106, v107, v106
	v_and_b32_e32 v107, 64, v228
	v_add_f32_e32 v0, v0, v106
	v_xor_b32_e32 v106, 16, v228
	v_add_u32_e32 v107, 64, v107
	v_cmp_lt_i32_e32 vcc, v106, v107
	v_cvt_pk_bf16_f32 v118, v118, v119
	v_cvt_pk_bf16_f32 v119, v120, v121
	v_cvt_pk_bf16_f32 v120, v126, v127
	v_cvt_pk_bf16_f32 v121, v124, v125
	global_store_dwordx4 v[122:123], v[118:121], off
	s_nop 0
	v_cndmask_b32_e32 v106, v228, v106, vcc
	v_lshlrev_b32_e32 v106, 2, v106
	ds_bpermute_b32 v106, v106, v0
	v_cvt_pk_bf16_f32 v108, v110, v111
	v_cvt_pk_bf16_f32 v109, v112, v113
	v_cvt_pk_bf16_f32 v110, v150, v151
	v_cvt_pk_bf16_f32 v111, v128, v129
	s_waitcnt lgkmcnt(0)
	v_add_f32_e32 v0, v0, v106
	v_xor_b32_e32 v106, 32, v228
	v_cmp_lt_i32_e32 vcc, v106, v107
	global_store_dwordx4 v[122:123], v[108:111], off offset:256
	s_nop 0
	v_cndmask_b32_e32 v106, v228, v106, vcc
	v_lshlrev_b32_e32 v106, 2, v106
	ds_bpermute_b32 v106, v106, v0
	s_and_saveexec_b64 s[66:67], s[36:37]
	s_cbranch_execz .LBB0_100
	v_lshl_add_u64 v[108:109], v[146:147], 2, s[64:65]
	s_waitcnt lgkmcnt(0)
	v_add_f32_e32 v0, v0, v106
	global_atomic_add_f32 v[108:109], v0, off offset:64

.LBB0_101:
	s_and_b64 vcc, exec, s[66:67]
	s_cbranch_vccz .LBB0_104
	s_and_b64 vcc, exec, s[40:41]
	s_cbranch_vccnz .LBB0_104
	s_waitcnt lgkmcnt(0)
	v_lshlrev_b64 v[106:107], 8, v[116:117]
	v_lshl_add_u64 v[106:107], v[140:141], 0, v[106:107]
	v_pk_mul_f32 v[104:105], v[104:105], v[114:115] op_sel_hi:[1,0]
	v_pk_mul_f32 v[102:103], v[102:103], v[114:115] op_sel_hi:[1,0]
	v_pk_mul_f32 v[100:101], v[100:101], v[114:115] op_sel_hi:[1,0]
	v_pk_mul_f32 v[98:99], v[98:99], v[114:115] op_sel_hi:[1,0]
	global_store_dwordx4 v[106:107], v[102:105], off
	global_store_dwordx4 v[106:107], v[98:101], off offset:16

.LBB0_109:
	v_lshlrev_b32_e32 v0, 1, v138
	s_waitcnt lgkmcnt(0)
	v_lshl_add_u64 v[106:107], v[102:103], 0, v[0:1]
	v_pk_mul_f32 v[104:105], v[88:89], v[98:99] op_sel_hi:[1,0]
	v_pk_mul_f32 v[102:103], v[86:87], v[98:99] op_sel_hi:[1,0]
	v_pk_mul_f32 v[108:109], v[84:85], v[98:99] op_sel_hi:[1,0]
	v_pk_mul_f32 v[110:111], v[82:83], v[98:99] op_sel_hi:[1,0]
	v_mul_f32_e32 v0, v103, v103
	v_mul_f32_e32 v99, v105, v105
	v_fmac_f32_e32 v0, v102, v102
	v_fmac_f32_e32 v99, v104, v104
	v_add_f32_e32 v0, v0, v99
	v_mul_f32_e32 v99, v111, v111
	v_fmac_f32_e32 v99, v110, v110
	v_add_f32_e32 v0, v99, v0
	v_mul_f32_e32 v99, v109, v109
	v_fmac_f32_e32 v99, v108, v108
	v_pk_mul_f32 v[96:97], v[96:97], v[98:99] op_sel_hi:[1,0]
	v_pk_mul_f32 v[94:95], v[94:95], v[98:99] op_sel_hi:[1,0]
	v_pk_mul_f32 v[114:115], v[90:91], v[98:99] op_sel_hi:[1,0]
	v_mul_f32_e32 v90, v95, v95
	v_mul_f32_e32 v91, v97, v97
	v_fmac_f32_e32 v90, v94, v94
	v_fmac_f32_e32 v91, v96, v96
	v_add_f32_e32 v90, v90, v91
	v_mul_f32_e32 v91, v115, v115
	v_pk_mul_f32 v[112:113], v[92:93], v[98:99] op_sel_hi:[1,0]
	v_fmac_f32_e32 v91, v114, v114
	v_add_f32_e32 v90, v91, v90
	v_mul_f32_e32 v91, v113, v113
	v_fmac_f32_e32 v91, v112, v112
	v_add_f32_e32 v0, v99, v0
	v_add_f32_e32 v90, v91, v90
	v_and_b32_e32 v91, 64, v228
	v_add_f32_e32 v0, v0, v90
	v_xor_b32_e32 v90, 16, v228
	v_add_u32_e32 v91, 64, v91
	v_cmp_lt_i32_e32 vcc, v90, v91
	v_cvt_pk_bf16_f32 v102, v102, v103
	v_cvt_pk_bf16_f32 v103, v104, v105
	v_cvt_pk_bf16_f32 v104, v110, v111
	v_cvt_pk_bf16_f32 v105, v108, v109
	global_store_dwordx4 v[106:107], v[102:105], off
	s_nop 0
	v_cndmask_b32_e32 v90, v228, v90, vcc
	v_lshlrev_b32_e32 v90, 2, v90
	ds_bpermute_b32 v90, v90, v0
	v_cvt_pk_bf16_f32 v92, v94, v95
	v_cvt_pk_bf16_f32 v93, v96, v97
	v_cvt_pk_bf16_f32 v94, v114, v115
	v_cvt_pk_bf16_f32 v95, v112, v113
	s_waitcnt lgkmcnt(0)
	v_add_f32_e32 v0, v0, v90
	v_xor_b32_e32 v90, 32, v228
	v_cmp_lt_i32_e32 vcc, v90, v91
	global_store_dwordx4 v[106:107], v[92:95], off offset:256
	s_nop 0
	v_cndmask_b32_e32 v90, v228, v90, vcc
	v_lshlrev_b32_e32 v90, 2, v90
	ds_bpermute_b32 v90, v90, v0
	s_and_saveexec_b64 s[66:67], s[36:37]
	s_cbranch_execz .LBB0_111
	v_lshl_add_u64 v[92:93], v[146:147], 2, s[64:65]
	s_waitcnt lgkmcnt(0)
	v_add_f32_e32 v0, v0, v90
	global_atomic_add_f32 v[92:93], v0, off offset:128

.LBB0_112:
	s_and_b64 vcc, exec, s[64:65]
	s_cbranch_vccz .LBB0_115
	s_and_b64 vcc, exec, s[40:41]
	s_cbranch_vccnz .LBB0_115
	s_waitcnt lgkmcnt(0)
	v_lshlrev_b64 v[90:91], 8, v[100:101]
	v_lshl_add_u64 v[90:91], v[140:141], 0, v[90:91]
	v_pk_mul_f32 v[88:89], v[88:89], v[98:99] op_sel_hi:[1,0]
	v_pk_mul_f32 v[86:87], v[86:87], v[98:99] op_sel_hi:[1,0]
	v_pk_mul_f32 v[84:85], v[84:85], v[98:99] op_sel_hi:[1,0]
	v_pk_mul_f32 v[82:83], v[82:83], v[98:99] op_sel_hi:[1,0]
	global_store_dwordx4 v[90:91], v[86:89], off
	global_store_dwordx4 v[90:91], v[82:85], off offset:16

.LBB0_120:
	v_lshlrev_b32_e32 v0, 1, v138
	s_waitcnt lgkmcnt(0)
	v_lshl_add_u64 v[90:91], v[86:87], 0, v[0:1]
	v_pk_mul_f32 v[88:89], v[72:73], v[82:83] op_sel_hi:[1,0]
	v_pk_mul_f32 v[86:87], v[70:71], v[82:83] op_sel_hi:[1,0]
	v_pk_mul_f32 v[92:93], v[68:69], v[82:83] op_sel_hi:[1,0]
	v_pk_mul_f32 v[94:95], v[66:67], v[82:83] op_sel_hi:[1,0]
	v_mul_f32_e32 v0, v87, v87
	v_mul_f32_e32 v83, v89, v89
	v_fmac_f32_e32 v0, v86, v86
	v_fmac_f32_e32 v83, v88, v88
	v_add_f32_e32 v0, v0, v83
	v_mul_f32_e32 v83, v95, v95
	v_fmac_f32_e32 v83, v94, v94
	v_add_f32_e32 v0, v83, v0
	v_mul_f32_e32 v83, v93, v93
	v_fmac_f32_e32 v83, v92, v92
	v_pk_mul_f32 v[80:81], v[80:81], v[82:83] op_sel_hi:[1,0]
	v_pk_mul_f32 v[78:79], v[78:79], v[82:83] op_sel_hi:[1,0]
	v_pk_mul_f32 v[98:99], v[74:75], v[82:83] op_sel_hi:[1,0]
	v_mul_f32_e32 v74, v79, v79
	v_mul_f32_e32 v75, v81, v81
	v_fmac_f32_e32 v74, v78, v78
	v_fmac_f32_e32 v75, v80, v80
	v_add_f32_e32 v74, v74, v75
	v_mul_f32_e32 v75, v99, v99
	v_pk_mul_f32 v[96:97], v[76:77], v[82:83] op_sel_hi:[1,0]
	v_fmac_f32_e32 v75, v98, v98
	v_add_f32_e32 v74, v75, v74
	v_mul_f32_e32 v75, v97, v97
	v_fmac_f32_e32 v75, v96, v96
	v_add_f32_e32 v0, v83, v0
	v_add_f32_e32 v74, v75, v74
	v_and_b32_e32 v75, 64, v228
	v_add_f32_e32 v0, v0, v74
	v_xor_b32_e32 v74, 16, v228
	v_add_u32_e32 v75, 64, v75
	v_cmp_lt_i32_e32 vcc, v74, v75
	v_cvt_pk_bf16_f32 v86, v86, v87
	v_cvt_pk_bf16_f32 v87, v88, v89
	v_cvt_pk_bf16_f32 v88, v94, v95
	v_cvt_pk_bf16_f32 v89, v92, v93
	global_store_dwordx4 v[90:91], v[86:89], off
	s_nop 0
	v_cndmask_b32_e32 v74, v228, v74, vcc
	v_lshlrev_b32_e32 v74, 2, v74
	ds_bpermute_b32 v74, v74, v0
	v_cvt_pk_bf16_f32 v76, v78, v79
	v_cvt_pk_bf16_f32 v77, v80, v81
	v_cvt_pk_bf16_f32 v78, v98, v99
	v_cvt_pk_bf16_f32 v79, v96, v97
	s_waitcnt lgkmcnt(0)
	v_add_f32_e32 v0, v0, v74
	v_xor_b32_e32 v74, 32, v228
	v_cmp_lt_i32_e32 vcc, v74, v75
	global_store_dwordx4 v[90:91], v[76:79], off offset:256
	s_nop 0
	v_cndmask_b32_e32 v74, v228, v74, vcc
	v_lshlrev_b32_e32 v74, 2, v74
	ds_bpermute_b32 v74, v74, v0
	s_and_saveexec_b64 s[66:67], s[36:37]
	s_cbranch_execz .LBB0_122
	v_lshl_add_u64 v[76:77], v[146:147], 2, s[64:65]
	s_waitcnt lgkmcnt(0)
	v_add_f32_e32 v0, v0, v74
	global_atomic_add_f32 v[76:77], v0, off offset:192

.LBB0_123:
	s_and_b64 vcc, exec, s[64:65]
	s_cbranch_vccz .LBB0_126
	s_and_b64 vcc, exec, s[40:41]
	s_cbranch_vccnz .LBB0_126
	s_waitcnt lgkmcnt(0)
	v_lshlrev_b64 v[74:75], 8, v[84:85]
	v_lshl_add_u64 v[74:75], v[140:141], 0, v[74:75]
	v_pk_mul_f32 v[72:73], v[72:73], v[82:83] op_sel_hi:[1,0]
	v_pk_mul_f32 v[70:71], v[70:71], v[82:83] op_sel_hi:[1,0]
	v_pk_mul_f32 v[68:69], v[68:69], v[82:83] op_sel_hi:[1,0]
	v_pk_mul_f32 v[66:67], v[66:67], v[82:83] op_sel_hi:[1,0]
	global_store_dwordx4 v[74:75], v[70:73], off
	global_store_dwordx4 v[74:75], v[66:69], off offset:16

.LBB0_131:
	v_lshlrev_b32_e32 v0, 1, v138
	s_waitcnt lgkmcnt(0)
	v_lshl_add_u64 v[74:75], v[70:71], 0, v[0:1]
	v_pk_mul_f32 v[72:73], v[56:57], v[66:67] op_sel_hi:[1,0]
	v_pk_mul_f32 v[70:71], v[54:55], v[66:67] op_sel_hi:[1,0]
	v_pk_mul_f32 v[76:77], v[52:53], v[66:67] op_sel_hi:[1,0]
	v_pk_mul_f32 v[78:79], v[50:51], v[66:67] op_sel_hi:[1,0]
	v_mul_f32_e32 v0, v71, v71
	v_mul_f32_e32 v67, v73, v73
	v_fmac_f32_e32 v0, v70, v70
	v_fmac_f32_e32 v67, v72, v72
	v_add_f32_e32 v0, v0, v67
	v_mul_f32_e32 v67, v79, v79
	v_fmac_f32_e32 v67, v78, v78
	v_add_f32_e32 v0, v67, v0
	v_mul_f32_e32 v67, v77, v77
	v_fmac_f32_e32 v67, v76, v76
	v_pk_mul_f32 v[64:65], v[64:65], v[66:67] op_sel_hi:[1,0]
	v_pk_mul_f32 v[62:63], v[62:63], v[66:67] op_sel_hi:[1,0]
	v_pk_mul_f32 v[82:83], v[58:59], v[66:67] op_sel_hi:[1,0]
	v_mul_f32_e32 v58, v63, v63
	v_mul_f32_e32 v59, v65, v65
	v_fmac_f32_e32 v58, v62, v62
	v_fmac_f32_e32 v59, v64, v64
	v_add_f32_e32 v58, v58, v59
	v_mul_f32_e32 v59, v83, v83
	v_pk_mul_f32 v[80:81], v[60:61], v[66:67] op_sel_hi:[1,0]
	v_fmac_f32_e32 v59, v82, v82
	v_add_f32_e32 v58, v59, v58
	v_mul_f32_e32 v59, v81, v81
	v_fmac_f32_e32 v59, v80, v80
	v_add_f32_e32 v0, v67, v0
	v_add_f32_e32 v58, v59, v58
	v_and_b32_e32 v59, 64, v228
	v_add_f32_e32 v0, v0, v58
	v_xor_b32_e32 v58, 16, v228
	v_add_u32_e32 v59, 64, v59
	v_cmp_lt_i32_e32 vcc, v58, v59
	v_cvt_pk_bf16_f32 v70, v70, v71
	v_cvt_pk_bf16_f32 v71, v72, v73
	v_cvt_pk_bf16_f32 v72, v78, v79
	v_cvt_pk_bf16_f32 v73, v76, v77
	global_store_dwordx4 v[74:75], v[70:73], off
	s_nop 0
	v_cndmask_b32_e32 v58, v228, v58, vcc
	v_lshlrev_b32_e32 v58, 2, v58
	ds_bpermute_b32 v58, v58, v0
	v_cvt_pk_bf16_f32 v60, v62, v63
	v_cvt_pk_bf16_f32 v61, v64, v65
	v_cvt_pk_bf16_f32 v62, v82, v83
	v_cvt_pk_bf16_f32 v63, v80, v81
	s_waitcnt lgkmcnt(0)
	v_add_f32_e32 v0, v0, v58
	v_xor_b32_e32 v58, 32, v228
	v_cmp_lt_i32_e32 vcc, v58, v59
	global_store_dwordx4 v[74:75], v[60:63], off offset:256
	s_nop 0
	v_cndmask_b32_e32 v58, v228, v58, vcc
	v_lshlrev_b32_e32 v58, 2, v58
	ds_bpermute_b32 v58, v58, v0
	s_and_saveexec_b64 s[66:67], s[36:37]
	s_cbranch_execz .LBB0_133
	v_lshl_add_u64 v[60:61], v[146:147], 2, s[64:65]
	s_waitcnt lgkmcnt(0)
	v_add_f32_e32 v0, v0, v58
	global_atomic_add_f32 v[60:61], v0, off offset:512

.LBB0_134:
	s_and_b64 vcc, exec, s[64:65]
	s_cbranch_vccz .LBB0_137
	s_and_b64 vcc, exec, s[40:41]
	s_cbranch_vccnz .LBB0_137
	s_waitcnt lgkmcnt(0)
	v_lshlrev_b64 v[58:59], 8, v[68:69]
	v_lshl_add_u64 v[58:59], v[140:141], 0, v[58:59]
	v_pk_mul_f32 v[56:57], v[56:57], v[66:67] op_sel_hi:[1,0]
	v_pk_mul_f32 v[54:55], v[54:55], v[66:67] op_sel_hi:[1,0]
	v_pk_mul_f32 v[52:53], v[52:53], v[66:67] op_sel_hi:[1,0]
	v_pk_mul_f32 v[50:51], v[50:51], v[66:67] op_sel_hi:[1,0]
	global_store_dwordx4 v[58:59], v[54:57], off
	global_store_dwordx4 v[58:59], v[50:53], off offset:16

.LBB0_142:
	v_lshlrev_b32_e32 v0, 1, v138
	s_waitcnt lgkmcnt(0)
	v_lshl_add_u64 v[58:59], v[54:55], 0, v[0:1]
	v_pk_mul_f32 v[56:57], v[40:41], v[50:51] op_sel_hi:[1,0]
	v_pk_mul_f32 v[54:55], v[38:39], v[50:51] op_sel_hi:[1,0]
	v_pk_mul_f32 v[60:61], v[36:37], v[50:51] op_sel_hi:[1,0]
	v_pk_mul_f32 v[62:63], v[34:35], v[50:51] op_sel_hi:[1,0]
	v_mul_f32_e32 v0, v55, v55
	v_mul_f32_e32 v51, v57, v57
	v_fmac_f32_e32 v0, v54, v54
	v_fmac_f32_e32 v51, v56, v56
	v_add_f32_e32 v0, v0, v51
	v_mul_f32_e32 v51, v63, v63
	v_fmac_f32_e32 v51, v62, v62
	v_add_f32_e32 v0, v51, v0
	v_mul_f32_e32 v51, v61, v61
	v_fmac_f32_e32 v51, v60, v60
	v_pk_mul_f32 v[48:49], v[48:49], v[50:51] op_sel_hi:[1,0]
	v_pk_mul_f32 v[46:47], v[46:47], v[50:51] op_sel_hi:[1,0]
	v_pk_mul_f32 v[66:67], v[42:43], v[50:51] op_sel_hi:[1,0]
	v_mul_f32_e32 v42, v47, v47
	v_mul_f32_e32 v43, v49, v49
	v_fmac_f32_e32 v42, v46, v46
	v_fmac_f32_e32 v43, v48, v48
	v_add_f32_e32 v42, v42, v43
	v_mul_f32_e32 v43, v67, v67
	v_pk_mul_f32 v[64:65], v[44:45], v[50:51] op_sel_hi:[1,0]
	v_fmac_f32_e32 v43, v66, v66
	v_add_f32_e32 v42, v43, v42
	v_mul_f32_e32 v43, v65, v65
	v_fmac_f32_e32 v43, v64, v64
	v_add_f32_e32 v0, v51, v0
	v_add_f32_e32 v42, v43, v42
	v_and_b32_e32 v43, 64, v228
	v_add_f32_e32 v0, v0, v42
	v_xor_b32_e32 v42, 16, v228
	v_add_u32_e32 v43, 64, v43
	v_cmp_lt_i32_e32 vcc, v42, v43
	v_cvt_pk_bf16_f32 v54, v54, v55
	v_cvt_pk_bf16_f32 v55, v56, v57
	v_cvt_pk_bf16_f32 v56, v62, v63
	v_cvt_pk_bf16_f32 v57, v60, v61
	global_store_dwordx4 v[58:59], v[54:57], off
	s_nop 0
	v_cndmask_b32_e32 v42, v228, v42, vcc
	v_lshlrev_b32_e32 v42, 2, v42
	ds_bpermute_b32 v42, v42, v0
	v_cvt_pk_bf16_f32 v44, v46, v47
	v_cvt_pk_bf16_f32 v45, v48, v49
	v_cvt_pk_bf16_f32 v46, v66, v67
	v_cvt_pk_bf16_f32 v47, v64, v65
	s_waitcnt lgkmcnt(0)
	v_add_f32_e32 v0, v0, v42
	v_xor_b32_e32 v42, 32, v228
	v_cmp_lt_i32_e32 vcc, v42, v43
	global_store_dwordx4 v[58:59], v[44:47], off offset:256
	s_nop 0
	v_cndmask_b32_e32 v42, v228, v42, vcc
	v_lshlrev_b32_e32 v42, 2, v42
	ds_bpermute_b32 v42, v42, v0
	s_and_saveexec_b64 s[66:67], s[36:37]
	s_cbranch_execz .LBB0_144
	v_lshl_add_u64 v[44:45], v[146:147], 2, s[64:65]
	s_waitcnt lgkmcnt(0)
	v_add_f32_e32 v0, v0, v42
	global_atomic_add_f32 v[44:45], v0, off offset:576

.LBB0_145:
	s_and_b64 vcc, exec, s[64:65]
	s_cbranch_vccz .LBB0_148
	s_and_b64 vcc, exec, s[40:41]
	s_cbranch_vccnz .LBB0_148
	s_waitcnt lgkmcnt(0)
	v_lshlrev_b64 v[42:43], 8, v[52:53]
	v_lshl_add_u64 v[42:43], v[140:141], 0, v[42:43]
	v_pk_mul_f32 v[40:41], v[40:41], v[50:51] op_sel_hi:[1,0]
	v_pk_mul_f32 v[38:39], v[38:39], v[50:51] op_sel_hi:[1,0]
	v_pk_mul_f32 v[36:37], v[36:37], v[50:51] op_sel_hi:[1,0]
	v_pk_mul_f32 v[34:35], v[34:35], v[50:51] op_sel_hi:[1,0]
	global_store_dwordx4 v[42:43], v[38:41], off
	global_store_dwordx4 v[42:43], v[34:37], off offset:16

.LBB0_153:
	v_lshlrev_b32_e32 v0, 1, v138
	s_waitcnt lgkmcnt(0)
	v_lshl_add_u64 v[42:43], v[38:39], 0, v[0:1]
	v_pk_mul_f32 v[40:41], v[24:25], v[34:35] op_sel_hi:[1,0]
	v_pk_mul_f32 v[38:39], v[22:23], v[34:35] op_sel_hi:[1,0]
	v_pk_mul_f32 v[44:45], v[20:21], v[34:35] op_sel_hi:[1,0]
	v_pk_mul_f32 v[46:47], v[18:19], v[34:35] op_sel_hi:[1,0]
	v_mul_f32_e32 v0, v39, v39
	v_mul_f32_e32 v35, v41, v41
	v_fmac_f32_e32 v0, v38, v38
	v_fmac_f32_e32 v35, v40, v40
	v_add_f32_e32 v0, v0, v35
	v_mul_f32_e32 v35, v47, v47
	v_fmac_f32_e32 v35, v46, v46
	v_add_f32_e32 v0, v35, v0
	v_mul_f32_e32 v35, v45, v45
	v_fmac_f32_e32 v35, v44, v44
	v_pk_mul_f32 v[32:33], v[32:33], v[34:35] op_sel_hi:[1,0]
	v_pk_mul_f32 v[30:31], v[30:31], v[34:35] op_sel_hi:[1,0]
	v_pk_mul_f32 v[50:51], v[26:27], v[34:35] op_sel_hi:[1,0]
	v_mul_f32_e32 v26, v31, v31
	v_mul_f32_e32 v27, v33, v33
	v_fmac_f32_e32 v26, v30, v30
	v_fmac_f32_e32 v27, v32, v32
	v_add_f32_e32 v26, v26, v27
	v_mul_f32_e32 v27, v51, v51
	v_pk_mul_f32 v[48:49], v[28:29], v[34:35] op_sel_hi:[1,0]
	v_fmac_f32_e32 v27, v50, v50
	v_add_f32_e32 v26, v27, v26
	v_mul_f32_e32 v27, v49, v49
	v_fmac_f32_e32 v27, v48, v48
	v_add_f32_e32 v0, v35, v0
	v_add_f32_e32 v26, v27, v26
	v_and_b32_e32 v27, 64, v228
	v_add_f32_e32 v0, v0, v26
	v_xor_b32_e32 v26, 16, v228
	v_add_u32_e32 v27, 64, v27
	v_cmp_lt_i32_e32 vcc, v26, v27
	v_cvt_pk_bf16_f32 v38, v38, v39
	v_cvt_pk_bf16_f32 v39, v40, v41
	v_cvt_pk_bf16_f32 v40, v46, v47
	v_cvt_pk_bf16_f32 v41, v44, v45
	global_store_dwordx4 v[42:43], v[38:41], off
	s_nop 0
	v_cndmask_b32_e32 v26, v228, v26, vcc
	v_lshlrev_b32_e32 v26, 2, v26
	ds_bpermute_b32 v26, v26, v0
	v_cvt_pk_bf16_f32 v28, v30, v31
	v_cvt_pk_bf16_f32 v29, v32, v33
	v_cvt_pk_bf16_f32 v30, v50, v51
	v_cvt_pk_bf16_f32 v31, v48, v49
	s_waitcnt lgkmcnt(0)
	v_add_f32_e32 v0, v0, v26
	v_xor_b32_e32 v26, 32, v228
	v_cmp_lt_i32_e32 vcc, v26, v27
	global_store_dwordx4 v[42:43], v[28:31], off offset:256
	s_nop 0
	v_cndmask_b32_e32 v26, v228, v26, vcc
	v_lshlrev_b32_e32 v26, 2, v26
	ds_bpermute_b32 v26, v26, v0
	s_and_saveexec_b64 s[66:67], s[36:37]
	s_cbranch_execz .LBB0_155
	v_lshl_add_u64 v[28:29], v[146:147], 2, s[64:65]
	s_waitcnt lgkmcnt(0)
	v_add_f32_e32 v0, v0, v26
	global_atomic_add_f32 v[28:29], v0, off offset:640

.LBB0_156:
	s_and_b64 vcc, exec, s[64:65]
	v_readlane_b32 s64, v254, 12
	v_readlane_b32 s65, v254, 13
	s_cbranch_vccz .LBB0_159
	s_and_b64 vcc, exec, s[40:41]
	s_cbranch_vccnz .LBB0_159
	s_waitcnt lgkmcnt(0)
	v_lshlrev_b64 v[26:27], 8, v[36:37]
	v_lshl_add_u64 v[26:27], v[140:141], 0, v[26:27]
	v_pk_mul_f32 v[24:25], v[24:25], v[34:35] op_sel_hi:[1,0]
	v_pk_mul_f32 v[22:23], v[22:23], v[34:35] op_sel_hi:[1,0]
	v_pk_mul_f32 v[20:21], v[20:21], v[34:35] op_sel_hi:[1,0]
	v_pk_mul_f32 v[18:19], v[18:19], v[34:35] op_sel_hi:[1,0]
	global_store_dwordx4 v[26:27], v[22:25], off
	global_store_dwordx4 v[26:27], v[18:21], off offset:16

.LBB0_164:
	v_lshlrev_b32_e32 v0, 1, v138
	s_waitcnt lgkmcnt(0)
	v_lshl_add_u64 v[26:27], v[22:23], 0, v[0:1]
	v_pk_mul_f32 v[24:25], v[8:9], v[18:19] op_sel_hi:[1,0]
	v_pk_mul_f32 v[22:23], v[6:7], v[18:19] op_sel_hi:[1,0]
	v_pk_mul_f32 v[28:29], v[4:5], v[18:19] op_sel_hi:[1,0]
	v_pk_mul_f32 v[30:31], v[2:3], v[18:19] op_sel_hi:[1,0]
	v_mul_f32_e32 v0, v23, v23
	v_mul_f32_e32 v19, v25, v25
	v_fmac_f32_e32 v0, v22, v22
	v_fmac_f32_e32 v19, v24, v24
	v_add_f32_e32 v0, v0, v19
	v_mul_f32_e32 v19, v31, v31
	v_fmac_f32_e32 v19, v30, v30
	v_add_f32_e32 v0, v19, v0
	v_mul_f32_e32 v19, v29, v29
	v_fmac_f32_e32 v19, v28, v28
	v_pk_mul_f32 v[16:17], v[16:17], v[18:19] op_sel_hi:[1,0]
	v_pk_mul_f32 v[14:15], v[14:15], v[18:19] op_sel_hi:[1,0]
	v_pk_mul_f32 v[34:35], v[10:11], v[18:19] op_sel_hi:[1,0]
	v_mul_f32_e32 v10, v15, v15
	v_mul_f32_e32 v11, v17, v17
	v_fmac_f32_e32 v10, v14, v14
	v_fmac_f32_e32 v11, v16, v16
	v_add_f32_e32 v10, v10, v11
	v_mul_f32_e32 v11, v35, v35
	v_pk_mul_f32 v[32:33], v[12:13], v[18:19] op_sel_hi:[1,0]
	v_fmac_f32_e32 v11, v34, v34
	v_add_f32_e32 v10, v11, v10
	v_mul_f32_e32 v11, v33, v33
	v_fmac_f32_e32 v11, v32, v32
	v_add_f32_e32 v0, v19, v0
	v_add_f32_e32 v10, v11, v10
	v_and_b32_e32 v11, 64, v228
	v_add_f32_e32 v0, v0, v10
	v_xor_b32_e32 v10, 16, v228
	v_add_u32_e32 v11, 64, v11
	v_cmp_lt_i32_e32 vcc, v10, v11
	v_cvt_pk_bf16_f32 v22, v22, v23
	v_cvt_pk_bf16_f32 v23, v24, v25
	v_cvt_pk_bf16_f32 v24, v30, v31
	v_cvt_pk_bf16_f32 v25, v28, v29
	global_store_dwordx4 v[26:27], v[22:25], off
	s_nop 0
	v_cndmask_b32_e32 v10, v228, v10, vcc
	v_lshlrev_b32_e32 v10, 2, v10
	ds_bpermute_b32 v10, v10, v0
	v_cvt_pk_bf16_f32 v12, v14, v15
	v_cvt_pk_bf16_f32 v13, v16, v17
	v_cvt_pk_bf16_f32 v14, v34, v35
	v_cvt_pk_bf16_f32 v15, v32, v33
	s_waitcnt lgkmcnt(0)
	v_add_f32_e32 v0, v0, v10
	v_xor_b32_e32 v10, 32, v228
	v_cmp_lt_i32_e32 vcc, v10, v11
	global_store_dwordx4 v[26:27], v[12:15], off offset:256
	s_nop 0
	v_cndmask_b32_e32 v10, v228, v10, vcc
	v_lshlrev_b32_e32 v10, 2, v10
	ds_bpermute_b32 v10, v10, v0
	s_and_saveexec_b64 s[44:45], s[36:37]
	s_cbranch_execz .LBB0_166
	v_lshl_add_u64 v[12:13], v[146:147], 2, s[42:43]
	s_waitcnt lgkmcnt(0)
	v_add_f32_e32 v0, v0, v10
	global_atomic_add_f32 v[12:13], v0, off offset:704

.LBB0_167:
	s_and_b64 vcc, exec, s[44:45]
	s_cbranch_vccz .LBB0_170
	s_and_b64 vcc, exec, s[40:41]
	s_cbranch_vccnz .LBB0_170
	s_waitcnt lgkmcnt(0)
	v_lshlrev_b64 v[10:11], 8, v[20:21]
	v_lshl_add_u64 v[10:11], v[140:141], 0, v[10:11]
	v_pk_mul_f32 v[8:9], v[8:9], v[18:19] op_sel_hi:[1,0]
	v_pk_mul_f32 v[6:7], v[6:7], v[18:19] op_sel_hi:[1,0]
	v_pk_mul_f32 v[4:5], v[4:5], v[18:19] op_sel_hi:[1,0]
	v_pk_mul_f32 v[2:3], v[2:3], v[18:19] op_sel_hi:[1,0]
	global_store_dwordx4 v[10:11], v[6:9], off
	global_store_dwordx4 v[10:11], v[2:5], off offset:16

.LBB0_243:
	v_lshl_add_u32 v144, s6, 8, v139
	v_ashrrev_i32_e32 v145, 31, v144
	v_lshl_add_u64 v[150:151], v[144:145], 2, s[16:17]
	global_load_dword v0, v[150:151], off
	s_lshl_b32 s4, s2, 7
	s_ashr_i32 s5, s4, 31
	v_or_b32_e32 v148, s4, v138
	s_lshl_b64 s[48:49], s[4:5], 1
	v_ashrrev_i32_e32 v149, 31, v148
	v_lshlrev_b64 v[148:149], 15, v[148:149]
	s_movk_i32 s4, 0x7fff
	s_mov_b32 s2, 0x8000
	v_readlane_b32 s68, v254, 6
	v_readlane_b32 s69, v254, 7
	s_waitcnt vmcnt(0) lgkmcnt(0)
	v_fmamk_f32 v0, v0, 0x3b000000, v207
	v_cmp_gt_f32_e32 vcc, s87, v0
	v_mul_f32_e32 v150, 0x4b800000, v0
	s_nop 0
	v_cndmask_b32_e32 v0, v0, v150, vcc
	v_rsq_f32_e32 v0, v0
	s_nop 0
	v_mul_f32_e32 v150, 0x45800000, v0
	v_cndmask_b32_e32 v150, v0, v150, vcc
	v_pk_mul_f32 v[126:127], v[126:127], v[150:151] op_sel_hi:[1,0]
	v_pk_mul_f32 v[152:153], v[124:125], v[150:151] op_sel_hi:[1,0]
	v_pk_mul_f32 v[124:125], v[122:123], v[150:151] op_sel_hi:[1,0]
	v_cvt_pk_bf16_f32 v122, v126, v127
	v_lshlrev_b64 v[126:127], 12, v[144:145]
	v_lshl_add_u64 v[126:127], s[40:41], 0, v[126:127]
	v_lshl_add_u64 v[126:127], v[126:127], 0, s[48:49]
	v_lshlrev_b32_e32 v0, 1, v138
	v_pk_mul_f32 v[128:129], v[128:129], v[150:151] op_sel_hi:[1,0]
	v_lshl_add_u64 v[126:127], v[126:127], 0, v[0:1]
	v_cvt_pk_bf16_f32 v123, v128, v129
	v_cvt_pk_bf16_f32 v124, v124, v125
	v_mul_f32_e32 v118, v118, v150
	v_cvt_pk_bf16_f32 v125, v152, v153
	global_store_dwordx4 v[126:127], v[122:125], off
	v_mul_f32_e32 v120, v120, v150
	v_mul_f32_e32 v114, v114, v150
	v_lshl_add_u64 v[122:123], s[42:43], 0, v[148:149]
	v_bfe_u32 v124, v118, 16, 1
	v_lshl_add_u64 v[122:123], v[144:145], 1, v[122:123]
	v_add3_u32 v118, v118, v124, s4
	global_store_short_d16_hi v[122:123], v118, off
	v_mul_f32_e32 v118, v119, v150
	v_bfe_u32 v119, v118, 16, 1
	v_add3_u32 v124, v118, v119, s4
	v_add_co_u32_e32 v118, vcc, s2, v122
	s_mov_b32 s2, 0x28000
	s_nop 0
	v_addc_co_u32_e32 v119, vcc, 0, v123, vcc
	global_store_short_d16_hi v[118:119], v124, off
	v_bfe_u32 v124, v120, 16, 1
	v_add3_u32 v120, v120, v124, s4
	v_add_co_u32_e32 v124, vcc, s71, v122
	v_mul_f32_e32 v116, v116, v150
	s_nop 0
	v_addc_co_u32_e32 v125, vcc, 0, v123, vcc
	global_store_short_d16_hi v[124:125], v120, off
	v_mul_f32_e32 v120, v121, v150
	v_bfe_u32 v121, v120, 16, 1
	v_add3_u32 v126, v120, v121, s4
	v_add_co_u32_e32 v120, vcc, s93, v122
	v_or_b32_e32 v148, 16, v144
	s_nop 0
	v_addc_co_u32_e32 v121, vcc, 0, v123, vcc
	global_store_short_d16_hi v[120:121], v126, off
	v_bfe_u32 v126, v114, 16, 1
	v_add3_u32 v114, v114, v126, s4
	v_add_co_u32_e32 v126, vcc, s78, v122
	v_ashrrev_i32_e32 v149, 31, v148
	s_nop 0
	v_addc_co_u32_e32 v127, vcc, 0, v123, vcc
	global_store_short_d16_hi v[126:127], v114, off
	v_mul_f32_e32 v114, v115, v150
	v_bfe_u32 v115, v114, 16, 1
	v_add3_u32 v128, v114, v115, s4
	v_add_co_u32_e32 v114, vcc, s2, v122
	s_mov_b32 s2, 0x38000
	s_nop 0
	v_addc_co_u32_e32 v115, vcc, 0, v123, vcc
	global_store_short_d16_hi v[114:115], v128, off
	v_bfe_u32 v128, v116, 16, 1
	v_add3_u32 v116, v116, v128, s4
	v_add_co_u32_e32 v128, vcc, s83, v122
	s_nop 1
	v_addc_co_u32_e32 v129, vcc, 0, v123, vcc
	global_store_short_d16_hi v[128:129], v116, off
	v_mul_f32_e32 v116, v117, v150
	v_bfe_u32 v117, v116, 16, 1
	v_add3_u32 v145, v116, v117, s4
	v_add_co_u32_e32 v116, vcc, s2, v122
	v_lshl_add_u64 v[150:151], v[148:149], 2, s[16:17]
	s_nop 0
	v_addc_co_u32_e32 v117, vcc, 0, v123, vcc
	global_store_short_d16_hi v[116:117], v145, off
	global_load_dword v145, v[150:151], off
	s_waitcnt vmcnt(0) lgkmcnt(0)
	v_fmamk_f32 v145, v145, 0x3b000000, v207
	v_cmp_gt_f32_e32 vcc, s87, v145
	v_mul_f32_e32 v150, 0x4b800000, v145
	s_nop 0
	v_cndmask_b32_e32 v145, v145, v150, vcc
	v_rsq_f32_e32 v145, v145
	s_nop 0
	v_mul_f32_e32 v150, 0x45800000, v145
	v_cndmask_b32_e32 v150, v145, v150, vcc
	v_pk_mul_f32 v[110:111], v[110:111], v[150:151] op_sel_hi:[1,0]
	v_pk_mul_f32 v[152:153], v[108:109], v[150:151] op_sel_hi:[1,0]
	v_pk_mul_f32 v[108:109], v[106:107], v[150:151] op_sel_hi:[1,0]
	v_cvt_pk_bf16_f32 v106, v110, v111
	v_lshlrev_b64 v[110:111], 12, v[148:149]
	v_lshl_add_u64 v[110:111], s[40:41], 0, v[110:111]
	v_lshl_add_u64 v[110:111], v[110:111], 0, s[48:49]
	v_lshl_add_u64 v[110:111], v[110:111], 0, v[0:1]
	v_mul_f32_e32 v102, v102, v150
	v_pk_mul_f32 v[112:113], v[112:113], v[150:151] op_sel_hi:[1,0]
	v_mul_f32_e32 v98, v98, v150
	v_cvt_pk_bf16_f32 v107, v112, v113
	v_cvt_pk_bf16_f32 v108, v108, v109
	v_cvt_pk_bf16_f32 v109, v152, v153
	global_store_dwordx4 v[110:111], v[106:109], off
	s_nop 1
	v_bfe_u32 v106, v102, 16, 1
	v_add3_u32 v102, v102, v106, s4
	global_store_short_d16_hi v[122:123], v102, off offset:32
	v_mul_f32_e32 v102, v103, v150
	v_bfe_u32 v103, v102, 16, 1
	v_add3_u32 v102, v102, v103, s4
	global_store_short_d16_hi v[118:119], v102, off offset:32
	v_mul_f32_e32 v102, v104, v150
	v_bfe_u32 v103, v102, 16, 1
	v_add3_u32 v102, v102, v103, s4
	global_store_short_d16_hi v[124:125], v102, off offset:32
	v_mul_f32_e32 v102, v105, v150
	v_bfe_u32 v103, v102, 16, 1
	v_add3_u32 v102, v102, v103, s4
	global_store_short_d16_hi v[120:121], v102, off offset:32
	v_bfe_u32 v102, v98, 16, 1
	v_add3_u32 v98, v98, v102, s4
	global_store_short_d16_hi v[126:127], v98, off offset:32
	v_mul_f32_e32 v98, v99, v150
	v_bfe_u32 v99, v98, 16, 1
	v_add3_u32 v98, v98, v99, s4
	global_store_short_d16_hi v[114:115], v98, off offset:32
	v_mul_f32_e32 v98, v100, v150
	v_bfe_u32 v99, v98, 16, 1
	v_add3_u32 v98, v98, v99, s4
	global_store_short_d16_hi v[128:129], v98, off offset:32
	v_mul_f32_e32 v98, v101, v150
	v_bfe_u32 v99, v98, 16, 1
	v_add3_u32 v98, v98, v99, s4
	global_store_short_d16_hi v[116:117], v98, off offset:32
	v_or_b32_e32 v98, 32, v144
	v_ashrrev_i32_e32 v99, 31, v98
	v_lshl_add_u64 v[100:101], v[98:99], 2, s[16:17]
	global_load_dword v100, v[100:101], off
	s_waitcnt vmcnt(0) lgkmcnt(0)
	v_fmamk_f32 v100, v100, 0x3b000000, v207
	v_cmp_gt_f32_e32 vcc, s87, v100
	v_mul_f32_e32 v101, 0x4b800000, v100
	s_nop 0
	v_cndmask_b32_e32 v100, v100, v101, vcc
	v_rsq_f32_e32 v100, v100
	s_nop 0
	v_mul_f32_e32 v101, 0x45800000, v100
	v_cndmask_b32_e32 v100, v100, v101, vcc
	v_pk_mul_f32 v[94:95], v[94:95], v[100:101] op_sel_hi:[1,0]
	v_pk_mul_f32 v[102:103], v[92:93], v[100:101] op_sel_hi:[1,0]
	v_pk_mul_f32 v[92:93], v[90:91], v[100:101] op_sel_hi:[1,0]
	v_cvt_pk_bf16_f32 v90, v94, v95
	v_lshlrev_b64 v[94:95], 12, v[98:99]
	v_lshl_add_u64 v[94:95], s[40:41], 0, v[94:95]
	v_lshl_add_u64 v[94:95], v[94:95], 0, s[48:49]
	v_lshl_add_u64 v[94:95], v[94:95], 0, v[0:1]
	v_mul_f32_e32 v86, v86, v100
	v_pk_mul_f32 v[96:97], v[96:97], v[100:101] op_sel_hi:[1,0]
	v_mul_f32_e32 v82, v82, v100
	v_cvt_pk_bf16_f32 v91, v96, v97
	v_cvt_pk_bf16_f32 v92, v92, v93
	v_cvt_pk_bf16_f32 v93, v102, v103
	global_store_dwordx4 v[94:95], v[90:93], off
	s_nop 1
	v_bfe_u32 v90, v86, 16, 1
	v_add3_u32 v86, v86, v90, s4
	global_store_short_d16_hi v[122:123], v86, off offset:64
	v_mul_f32_e32 v86, v87, v100
	v_bfe_u32 v87, v86, 16, 1
	v_add3_u32 v86, v86, v87, s4
	global_store_short_d16_hi v[118:119], v86, off offset:64
	v_mul_f32_e32 v86, v88, v100
	v_bfe_u32 v87, v86, 16, 1
	v_add3_u32 v86, v86, v87, s4
	global_store_short_d16_hi v[124:125], v86, off offset:64
	v_mul_f32_e32 v86, v89, v100
	v_bfe_u32 v87, v86, 16, 1
	v_add3_u32 v86, v86, v87, s4
	global_store_short_d16_hi v[120:121], v86, off offset:64
	v_bfe_u32 v86, v82, 16, 1
	v_add3_u32 v82, v82, v86, s4
	global_store_short_d16_hi v[126:127], v82, off offset:64
	v_mul_f32_e32 v82, v83, v100
	v_bfe_u32 v83, v82, 16, 1
	v_add3_u32 v82, v82, v83, s4
	global_store_short_d16_hi v[114:115], v82, off offset:64
	v_mul_f32_e32 v82, v84, v100
	v_bfe_u32 v83, v82, 16, 1
	v_add3_u32 v82, v82, v83, s4
	global_store_short_d16_hi v[128:129], v82, off offset:64
	v_mul_f32_e32 v82, v85, v100
	v_bfe_u32 v83, v82, 16, 1
	v_add3_u32 v82, v82, v83, s4
	global_store_short_d16_hi v[116:117], v82, off offset:64
	v_or_b32_e32 v82, 48, v144
	v_ashrrev_i32_e32 v83, 31, v82
	v_lshl_add_u64 v[84:85], v[82:83], 2, s[16:17]
	global_load_dword v84, v[84:85], off
	s_waitcnt vmcnt(0) lgkmcnt(0)
	v_fmamk_f32 v84, v84, 0x3b000000, v207
	v_cmp_gt_f32_e32 vcc, s87, v84
	v_mul_f32_e32 v85, 0x4b800000, v84
	s_nop 0
	v_cndmask_b32_e32 v84, v84, v85, vcc
	v_rsq_f32_e32 v84, v84
	s_nop 0
	v_mul_f32_e32 v85, 0x45800000, v84
	v_cndmask_b32_e32 v84, v84, v85, vcc
	v_pk_mul_f32 v[78:79], v[78:79], v[84:85] op_sel_hi:[1,0]
	v_pk_mul_f32 v[86:87], v[76:77], v[84:85] op_sel_hi:[1,0]
	v_pk_mul_f32 v[76:77], v[74:75], v[84:85] op_sel_hi:[1,0]
	v_cvt_pk_bf16_f32 v74, v78, v79
	v_lshlrev_b64 v[78:79], 12, v[82:83]
	v_lshl_add_u64 v[78:79], s[40:41], 0, v[78:79]
	v_lshl_add_u64 v[78:79], v[78:79], 0, s[48:49]
	v_lshl_add_u64 v[78:79], v[78:79], 0, v[0:1]
	v_mul_f32_e32 v70, v70, v84
	v_pk_mul_f32 v[80:81], v[80:81], v[84:85] op_sel_hi:[1,0]
	v_mul_f32_e32 v66, v66, v84
	v_cvt_pk_bf16_f32 v75, v80, v81
	v_cvt_pk_bf16_f32 v76, v76, v77
	v_cvt_pk_bf16_f32 v77, v86, v87
	global_store_dwordx4 v[78:79], v[74:77], off
	s_nop 1
	v_bfe_u32 v74, v70, 16, 1
	v_add3_u32 v70, v70, v74, s4
	global_store_short_d16_hi v[122:123], v70, off offset:96
	v_mul_f32_e32 v70, v71, v84
	v_bfe_u32 v71, v70, 16, 1
	v_add3_u32 v70, v70, v71, s4
	global_store_short_d16_hi v[118:119], v70, off offset:96
	v_mul_f32_e32 v70, v72, v84
	v_bfe_u32 v71, v70, 16, 1
	v_add3_u32 v70, v70, v71, s4
	global_store_short_d16_hi v[124:125], v70, off offset:96
	v_mul_f32_e32 v70, v73, v84
	v_bfe_u32 v71, v70, 16, 1
	v_add3_u32 v70, v70, v71, s4
	global_store_short_d16_hi v[120:121], v70, off offset:96
	v_bfe_u32 v70, v66, 16, 1
	v_add3_u32 v66, v66, v70, s4
	global_store_short_d16_hi v[126:127], v66, off offset:96
	v_mul_f32_e32 v66, v67, v84
	v_bfe_u32 v67, v66, 16, 1
	v_add3_u32 v66, v66, v67, s4
	global_store_short_d16_hi v[114:115], v66, off offset:96
	v_mul_f32_e32 v66, v68, v84
	v_bfe_u32 v67, v66, 16, 1
	v_add3_u32 v66, v66, v67, s4
	global_store_short_d16_hi v[128:129], v66, off offset:96
	v_mul_f32_e32 v66, v69, v84
	v_bfe_u32 v67, v66, 16, 1
	v_add3_u32 v66, v66, v67, s4
	global_store_short_d16_hi v[116:117], v66, off offset:96
	v_add_u32_e32 v66, 0x80, v144
	v_ashrrev_i32_e32 v67, 31, v66
	v_lshl_add_u64 v[68:69], v[66:67], 2, s[16:17]
	global_load_dword v68, v[68:69], off
	s_waitcnt vmcnt(0) lgkmcnt(0)
	v_fmamk_f32 v68, v68, 0x3b000000, v207
	v_cmp_gt_f32_e32 vcc, s87, v68
	v_mul_f32_e32 v69, 0x4b800000, v68
	s_nop 0
	v_cndmask_b32_e32 v68, v68, v69, vcc
	v_rsq_f32_e32 v68, v68
	s_nop 0
	v_mul_f32_e32 v69, 0x45800000, v68
	v_cndmask_b32_e32 v68, v68, v69, vcc
	v_pk_mul_f32 v[62:63], v[62:63], v[68:69] op_sel_hi:[1,0]
	v_pk_mul_f32 v[70:71], v[60:61], v[68:69] op_sel_hi:[1,0]
	v_pk_mul_f32 v[60:61], v[58:59], v[68:69] op_sel_hi:[1,0]
	v_cvt_pk_bf16_f32 v58, v62, v63
	v_lshlrev_b64 v[62:63], 12, v[66:67]
	v_lshl_add_u64 v[62:63], s[40:41], 0, v[62:63]
	v_lshl_add_u64 v[62:63], v[62:63], 0, s[48:49]
	v_lshl_add_u64 v[62:63], v[62:63], 0, v[0:1]
	v_mul_f32_e32 v54, v54, v68
	v_pk_mul_f32 v[64:65], v[64:65], v[68:69] op_sel_hi:[1,0]
	v_mul_f32_e32 v50, v50, v68
	v_cvt_pk_bf16_f32 v59, v64, v65
	v_cvt_pk_bf16_f32 v60, v60, v61
	v_cvt_pk_bf16_f32 v61, v70, v71
	global_store_dwordx4 v[62:63], v[58:61], off
	s_nop 1
	v_bfe_u32 v58, v54, 16, 1
	v_add3_u32 v54, v54, v58, s4
	global_store_short_d16_hi v[122:123], v54, off offset:256
	v_mul_f32_e32 v54, v55, v68
	v_bfe_u32 v55, v54, 16, 1
	v_add3_u32 v54, v54, v55, s4
	global_store_short_d16_hi v[118:119], v54, off offset:256
	v_mul_f32_e32 v54, v56, v68
	v_bfe_u32 v55, v54, 16, 1
	v_add3_u32 v54, v54, v55, s4
	global_store_short_d16_hi v[124:125], v54, off offset:256
	v_mul_f32_e32 v54, v57, v68
	v_bfe_u32 v55, v54, 16, 1
	v_add3_u32 v54, v54, v55, s4
	global_store_short_d16_hi v[120:121], v54, off offset:256
	v_bfe_u32 v54, v50, 16, 1
	v_add3_u32 v50, v50, v54, s4
	global_store_short_d16_hi v[126:127], v50, off offset:256
	v_mul_f32_e32 v50, v51, v68
	v_bfe_u32 v51, v50, 16, 1
	v_add3_u32 v50, v50, v51, s4
	global_store_short_d16_hi v[114:115], v50, off offset:256
	v_mul_f32_e32 v50, v52, v68
	v_bfe_u32 v51, v50, 16, 1
	v_add3_u32 v50, v50, v51, s4
	global_store_short_d16_hi v[128:129], v50, off offset:256
	v_mul_f32_e32 v50, v53, v68
	v_bfe_u32 v51, v50, 16, 1
	v_add3_u32 v50, v50, v51, s4
	global_store_short_d16_hi v[116:117], v50, off offset:256
	v_add_u32_e32 v50, 0x90, v144
	v_ashrrev_i32_e32 v51, 31, v50
	v_lshl_add_u64 v[52:53], v[50:51], 2, s[16:17]
	global_load_dword v52, v[52:53], off
	s_waitcnt vmcnt(0) lgkmcnt(0)
	v_fmamk_f32 v52, v52, 0x3b000000, v207
	v_cmp_gt_f32_e32 vcc, s87, v52
	v_mul_f32_e32 v53, 0x4b800000, v52
	s_nop 0
	v_cndmask_b32_e32 v52, v52, v53, vcc
	v_rsq_f32_e32 v52, v52
	s_nop 0
	v_mul_f32_e32 v53, 0x45800000, v52
	v_cndmask_b32_e32 v52, v52, v53, vcc
	v_pk_mul_f32 v[46:47], v[46:47], v[52:53] op_sel_hi:[1,0]
	v_pk_mul_f32 v[54:55], v[44:45], v[52:53] op_sel_hi:[1,0]
	v_pk_mul_f32 v[44:45], v[42:43], v[52:53] op_sel_hi:[1,0]
	v_cvt_pk_bf16_f32 v42, v46, v47
	v_lshlrev_b64 v[46:47], 12, v[50:51]
	v_lshl_add_u64 v[46:47], s[40:41], 0, v[46:47]
	v_lshl_add_u64 v[46:47], v[46:47], 0, s[48:49]
	v_lshl_add_u64 v[46:47], v[46:47], 0, v[0:1]
	v_mul_f32_e32 v38, v38, v52
	v_pk_mul_f32 v[48:49], v[48:49], v[52:53] op_sel_hi:[1,0]
	v_mul_f32_e32 v34, v34, v52
	v_cvt_pk_bf16_f32 v43, v48, v49
	v_cvt_pk_bf16_f32 v44, v44, v45
	v_cvt_pk_bf16_f32 v45, v54, v55
	global_store_dwordx4 v[46:47], v[42:45], off
	s_nop 1
	v_bfe_u32 v42, v38, 16, 1
	v_add3_u32 v38, v38, v42, s4
	global_store_short_d16_hi v[122:123], v38, off offset:288
	v_mul_f32_e32 v38, v39, v52
	v_bfe_u32 v39, v38, 16, 1
	v_add3_u32 v38, v38, v39, s4
	global_store_short_d16_hi v[118:119], v38, off offset:288
	v_mul_f32_e32 v38, v40, v52
	v_bfe_u32 v39, v38, 16, 1
	v_add3_u32 v38, v38, v39, s4
	global_store_short_d16_hi v[124:125], v38, off offset:288
	v_mul_f32_e32 v38, v41, v52
	v_bfe_u32 v39, v38, 16, 1
	v_add3_u32 v38, v38, v39, s4
	global_store_short_d16_hi v[120:121], v38, off offset:288
	v_bfe_u32 v38, v34, 16, 1
	v_add3_u32 v34, v34, v38, s4
	global_store_short_d16_hi v[126:127], v34, off offset:288
	v_mul_f32_e32 v34, v35, v52
	v_bfe_u32 v35, v34, 16, 1
	v_add3_u32 v34, v34, v35, s4
	global_store_short_d16_hi v[114:115], v34, off offset:288
	v_mul_f32_e32 v34, v36, v52
	v_bfe_u32 v35, v34, 16, 1
	v_add3_u32 v34, v34, v35, s4
	global_store_short_d16_hi v[128:129], v34, off offset:288
	v_mul_f32_e32 v34, v37, v52
	v_bfe_u32 v35, v34, 16, 1
	v_add3_u32 v34, v34, v35, s4
	global_store_short_d16_hi v[116:117], v34, off offset:288
	v_add_u32_e32 v34, 0xa0, v144
	v_ashrrev_i32_e32 v35, 31, v34
	v_lshl_add_u64 v[36:37], v[34:35], 2, s[16:17]
	global_load_dword v36, v[36:37], off
	s_waitcnt vmcnt(0) lgkmcnt(0)
	v_fmamk_f32 v36, v36, 0x3b000000, v207
	v_cmp_gt_f32_e32 vcc, s87, v36
	v_mul_f32_e32 v37, 0x4b800000, v36
	s_nop 0
	v_cndmask_b32_e32 v36, v36, v37, vcc
	v_rsq_f32_e32 v36, v36
	s_nop 0
	v_mul_f32_e32 v37, 0x45800000, v36
	v_cndmask_b32_e32 v36, v36, v37, vcc
	v_pk_mul_f32 v[30:31], v[30:31], v[36:37] op_sel_hi:[1,0]
	v_pk_mul_f32 v[38:39], v[28:29], v[36:37] op_sel_hi:[1,0]
	v_pk_mul_f32 v[28:29], v[26:27], v[36:37] op_sel_hi:[1,0]
	v_cvt_pk_bf16_f32 v26, v30, v31
	v_lshlrev_b64 v[30:31], 12, v[34:35]
	v_lshl_add_u64 v[30:31], s[40:41], 0, v[30:31]
	v_lshl_add_u64 v[30:31], v[30:31], 0, s[48:49]
	v_lshl_add_u64 v[30:31], v[30:31], 0, v[0:1]
	v_mul_f32_e32 v22, v22, v36
	v_pk_mul_f32 v[32:33], v[32:33], v[36:37] op_sel_hi:[1,0]
	v_mul_f32_e32 v18, v18, v36
	v_cvt_pk_bf16_f32 v27, v32, v33
	v_cvt_pk_bf16_f32 v28, v28, v29
	v_cvt_pk_bf16_f32 v29, v38, v39
	global_store_dwordx4 v[30:31], v[26:29], off
	s_nop 1
	v_bfe_u32 v26, v22, 16, 1
	v_add3_u32 v22, v22, v26, s4
	global_store_short_d16_hi v[122:123], v22, off offset:320
	v_mul_f32_e32 v22, v23, v36
	v_bfe_u32 v23, v22, 16, 1
	v_add3_u32 v22, v22, v23, s4
	global_store_short_d16_hi v[118:119], v22, off offset:320
	v_mul_f32_e32 v22, v24, v36
	v_bfe_u32 v23, v22, 16, 1
	v_add3_u32 v22, v22, v23, s4
	global_store_short_d16_hi v[124:125], v22, off offset:320
	v_mul_f32_e32 v22, v25, v36
	v_bfe_u32 v23, v22, 16, 1
	v_add3_u32 v22, v22, v23, s4
	global_store_short_d16_hi v[120:121], v22, off offset:320
	v_bfe_u32 v22, v18, 16, 1
	v_add3_u32 v18, v18, v22, s4
	global_store_short_d16_hi v[126:127], v18, off offset:320
	v_mul_f32_e32 v18, v19, v36
	v_bfe_u32 v19, v18, 16, 1
	v_add3_u32 v18, v18, v19, s4
	global_store_short_d16_hi v[114:115], v18, off offset:320
	v_mul_f32_e32 v18, v20, v36
	v_bfe_u32 v19, v18, 16, 1
	v_add3_u32 v18, v18, v19, s4
	global_store_short_d16_hi v[128:129], v18, off offset:320
	v_mul_f32_e32 v18, v21, v36
	v_bfe_u32 v19, v18, 16, 1
	v_add3_u32 v18, v18, v19, s4
	global_store_short_d16_hi v[116:117], v18, off offset:320
	v_add_u32_e32 v18, 0xb0, v144
	v_ashrrev_i32_e32 v19, 31, v18
	v_lshl_add_u64 v[20:21], v[18:19], 2, s[16:17]
	global_load_dword v20, v[20:21], off
	s_waitcnt vmcnt(0) lgkmcnt(0)
	v_fmamk_f32 v20, v20, 0x3b000000, v207
	v_cmp_gt_f32_e32 vcc, s87, v20
	v_mul_f32_e32 v21, 0x4b800000, v20
	s_nop 0
	v_cndmask_b32_e32 v20, v20, v21, vcc
	v_rsq_f32_e32 v20, v20
	s_nop 0
	v_mul_f32_e32 v21, 0x45800000, v20
	v_cndmask_b32_e32 v20, v20, v21, vcc
	v_pk_mul_f32 v[14:15], v[14:15], v[20:21] op_sel_hi:[1,0]
	v_pk_mul_f32 v[22:23], v[12:13], v[20:21] op_sel_hi:[1,0]
	v_pk_mul_f32 v[12:13], v[10:11], v[20:21] op_sel_hi:[1,0]
	v_cvt_pk_bf16_f32 v10, v14, v15
	v_lshlrev_b64 v[14:15], 12, v[18:19]
	v_lshl_add_u64 v[14:15], s[40:41], 0, v[14:15]
	v_lshl_add_u64 v[14:15], v[14:15], 0, s[48:49]
	v_lshl_add_u64 v[14:15], v[14:15], 0, v[0:1]
	v_mul_f32_e32 v0, v6, v20
	v_bfe_u32 v6, v0, 16, 1
	v_add3_u32 v0, v0, v6, s4
	v_pk_mul_f32 v[16:17], v[16:17], v[20:21] op_sel_hi:[1,0]
	s_andn2_b64 vcc, exec, s[38:39]
	v_cvt_pk_bf16_f32 v11, v16, v17
	v_cvt_pk_bf16_f32 v12, v12, v13
	v_cvt_pk_bf16_f32 v13, v22, v23
	global_store_dwordx4 v[14:15], v[10:13], off
	global_store_short_d16_hi v[122:123], v0, off offset:352
	v_mul_f32_e32 v0, v7, v20
	v_bfe_u32 v6, v0, 16, 1
	v_add3_u32 v0, v0, v6, s4
	global_store_short_d16_hi v[118:119], v0, off offset:352
	v_mul_f32_e32 v0, v8, v20
	v_bfe_u32 v6, v0, 16, 1
	v_add3_u32 v0, v0, v6, s4
	global_store_short_d16_hi v[124:125], v0, off offset:352
	v_mul_f32_e32 v0, v9, v20
	v_bfe_u32 v6, v0, 16, 1
	v_add3_u32 v0, v0, v6, s4
	global_store_short_d16_hi v[120:121], v0, off offset:352
	v_mul_f32_e32 v0, v2, v20
	v_bfe_u32 v2, v0, 16, 1
	v_add3_u32 v0, v0, v2, s4
	global_store_short_d16_hi v[126:127], v0, off offset:352
	v_mul_f32_e32 v0, v3, v20
	v_bfe_u32 v2, v0, 16, 1
	v_add3_u32 v0, v0, v2, s4
	global_store_short_d16_hi v[114:115], v0, off offset:352
	v_mul_f32_e32 v0, v4, v20
	v_bfe_u32 v2, v0, 16, 1
	v_add3_u32 v0, v0, v2, s4
	global_store_short_d16_hi v[128:129], v0, off offset:352
	v_mul_f32_e32 v0, v5, v20
	v_bfe_u32 v2, v0, 16, 1
	v_add3_u32 v0, v0, v2, s4
	s_mov_b64 s[4:5], -1
	global_store_short_d16_hi v[116:117], v0, off offset:352
	s_cbranch_vccnz .LBB0_232
	s_andn2_b64 vcc, exec, s[18:19]
	s_cbranch_vccnz .LBB0_231
	s_barrier
	s_branch .LBB0_231

.LBB0_263:
	v_lshl_add_u32 v140, s2, 8, v142
	v_ashrrev_i32_e32 v141, 31, v140
	v_lshl_add_u64 v[148:149], v[140:141], 2, s[12:13]
	global_load_dword v141, v[148:149], off
	v_lshl_or_b32 v146, s6, 8, v144
	v_ashrrev_i32_e32 v147, 31, v146
	s_waitcnt vmcnt(0) lgkmcnt(0)
	v_fmamk_f32 v141, v141, 0x3a2aaaab, v207
	v_cmp_gt_f32_e32 vcc, s87, v141
	v_mul_f32_e32 v148, 0x4b800000, v141
	s_nop 0
	v_cndmask_b32_e32 v141, v141, v148, vcc
	v_rsq_f32_e32 v141, v141
	s_nop 0
	v_mul_f32_e32 v148, 0x45800000, v141
	v_cndmask_b32_e32 v148, v141, v148, vcc
	v_pk_mul_f32 v[128:129], v[128:129], v[148:149] op_sel_hi:[1,0]
	v_pk_mul_f32 v[126:127], v[126:127], v[148:149] op_sel_hi:[1,0]
	v_pk_mul_f32 v[122:123], v[122:123], v[148:149] op_sel_hi:[1,0]
	v_pk_mul_f32 v[124:125], v[124:125], v[148:149] op_sel_hi:[1,0]
	v_cvt_pk_bf16_f32 v126, v126, v127
	v_cvt_pk_bf16_f32 v127, v128, v129
	v_cvt_pk_bf16_f32 v128, v122, v123
	v_mov_b64_e32 v[122:123], s[16:17]
	v_cvt_pk_bf16_f32 v129, v124, v125
	v_mad_i64_i32 v[150:151], s[4:5], v140, s89, v[122:123]
	v_lshlrev_b64 v[124:125], 1, v[146:147]
	v_lshl_add_u64 v[146:147], v[150:151], 0, v[124:125]
	global_store_dwordx4 v[146:147], v[126:129], off
	v_pk_mul_f32 v[118:119], v[118:119], v[148:149] op_sel_hi:[1,0]
	v_pk_mul_f32 v[120:121], v[120:121], v[148:149] op_sel_hi:[1,0]
	v_pk_mul_f32 v[126:127], v[116:117], v[148:149] op_sel_hi:[1,0]
	v_pk_mul_f32 v[116:117], v[114:115], v[148:149] op_sel_hi:[1,0]
	v_cvt_pk_bf16_f32 v114, v118, v119
	v_cvt_pk_bf16_f32 v115, v120, v121
	s_nop 0
	v_cvt_pk_bf16_f32 v116, v116, v117
	v_cvt_pk_bf16_f32 v117, v126, v127
	global_store_dwordx4 v[146:147], v[114:117], off offset:256
	s_nop 1
	v_or_b32_e32 v114, 16, v140
	v_ashrrev_i32_e32 v115, 31, v114
	v_lshl_add_u64 v[116:117], v[114:115], 2, s[12:13]
	global_load_dword v115, v[116:117], off
	s_waitcnt vmcnt(0) lgkmcnt(0)
	v_fmamk_f32 v115, v115, 0x3a2aaaab, v207
	v_cmp_gt_f32_e32 vcc, s87, v115
	v_mul_f32_e32 v116, 0x4b800000, v115
	s_nop 0
	v_cndmask_b32_e32 v115, v115, v116, vcc
	v_rsq_f32_e32 v115, v115
	s_nop 0
	v_mul_f32_e32 v116, 0x45800000, v115
	v_cndmask_b32_e32 v116, v115, v116, vcc
	v_pk_mul_f32 v[110:111], v[110:111], v[116:117] op_sel_hi:[1,0]
	v_pk_mul_f32 v[118:119], v[108:109], v[116:117] op_sel_hi:[1,0]
	v_pk_mul_f32 v[108:109], v[106:107], v[116:117] op_sel_hi:[1,0]
	v_cvt_pk_bf16_f32 v106, v110, v111
	v_mad_i64_i32 v[110:111], s[4:5], v114, s89, v[122:123]
	v_pk_mul_f32 v[112:113], v[112:113], v[116:117] op_sel_hi:[1,0]
	v_lshl_add_u64 v[110:111], v[110:111], 0, v[124:125]
	v_cvt_pk_bf16_f32 v107, v112, v113
	v_cvt_pk_bf16_f32 v108, v108, v109
	v_cvt_pk_bf16_f32 v109, v118, v119
	global_store_dwordx4 v[110:111], v[106:109], off
	v_pk_mul_f32 v[102:103], v[102:103], v[116:117] op_sel_hi:[1,0]
	v_pk_mul_f32 v[104:105], v[104:105], v[116:117] op_sel_hi:[1,0]
	v_pk_mul_f32 v[106:107], v[100:101], v[116:117] op_sel_hi:[1,0]
	v_pk_mul_f32 v[100:101], v[98:99], v[116:117] op_sel_hi:[1,0]
	v_cvt_pk_bf16_f32 v98, v102, v103
	v_cvt_pk_bf16_f32 v99, v104, v105
	s_nop 0
	v_cvt_pk_bf16_f32 v100, v100, v101
	v_cvt_pk_bf16_f32 v101, v106, v107
	global_store_dwordx4 v[110:111], v[98:101], off offset:256
	s_nop 1
	v_or_b32_e32 v98, 32, v140
	v_ashrrev_i32_e32 v99, 31, v98
	v_lshl_add_u64 v[100:101], v[98:99], 2, s[12:13]
	global_load_dword v99, v[100:101], off
	s_waitcnt vmcnt(0) lgkmcnt(0)
	v_fmamk_f32 v99, v99, 0x3a2aaaab, v207
	v_cmp_gt_f32_e32 vcc, s87, v99
	v_mul_f32_e32 v100, 0x4b800000, v99
	s_nop 0
	v_cndmask_b32_e32 v99, v99, v100, vcc
	v_rsq_f32_e32 v99, v99
	s_nop 0
	v_mul_f32_e32 v100, 0x45800000, v99
	v_cndmask_b32_e32 v100, v99, v100, vcc
	v_pk_mul_f32 v[94:95], v[94:95], v[100:101] op_sel_hi:[1,0]
	v_pk_mul_f32 v[102:103], v[92:93], v[100:101] op_sel_hi:[1,0]
	v_pk_mul_f32 v[92:93], v[90:91], v[100:101] op_sel_hi:[1,0]
	v_cvt_pk_bf16_f32 v90, v94, v95
	v_mad_i64_i32 v[94:95], s[4:5], v98, s89, v[122:123]
	v_pk_mul_f32 v[96:97], v[96:97], v[100:101] op_sel_hi:[1,0]
	v_lshl_add_u64 v[94:95], v[94:95], 0, v[124:125]
	v_cvt_pk_bf16_f32 v91, v96, v97
	v_cvt_pk_bf16_f32 v92, v92, v93
	v_cvt_pk_bf16_f32 v93, v102, v103
	global_store_dwordx4 v[94:95], v[90:93], off
	v_pk_mul_f32 v[86:87], v[86:87], v[100:101] op_sel_hi:[1,0]
	v_pk_mul_f32 v[88:89], v[88:89], v[100:101] op_sel_hi:[1,0]
	v_pk_mul_f32 v[90:91], v[84:85], v[100:101] op_sel_hi:[1,0]
	v_pk_mul_f32 v[84:85], v[82:83], v[100:101] op_sel_hi:[1,0]
	v_cvt_pk_bf16_f32 v82, v86, v87
	v_cvt_pk_bf16_f32 v83, v88, v89
	s_nop 0
	v_cvt_pk_bf16_f32 v84, v84, v85
	v_cvt_pk_bf16_f32 v85, v90, v91
	global_store_dwordx4 v[94:95], v[82:85], off offset:256
	s_nop 1
	v_or_b32_e32 v82, 48, v140
	v_ashrrev_i32_e32 v83, 31, v82
	v_lshl_add_u64 v[84:85], v[82:83], 2, s[12:13]
	global_load_dword v83, v[84:85], off
	s_waitcnt vmcnt(0) lgkmcnt(0)
	v_fmamk_f32 v83, v83, 0x3a2aaaab, v207
	v_cmp_gt_f32_e32 vcc, s87, v83
	v_mul_f32_e32 v84, 0x4b800000, v83
	s_nop 0
	v_cndmask_b32_e32 v83, v83, v84, vcc
	v_rsq_f32_e32 v83, v83
	s_nop 0
	v_mul_f32_e32 v84, 0x45800000, v83
	v_cndmask_b32_e32 v84, v83, v84, vcc
	v_pk_mul_f32 v[78:79], v[78:79], v[84:85] op_sel_hi:[1,0]
	v_pk_mul_f32 v[86:87], v[76:77], v[84:85] op_sel_hi:[1,0]
	v_pk_mul_f32 v[76:77], v[74:75], v[84:85] op_sel_hi:[1,0]
	v_cvt_pk_bf16_f32 v74, v78, v79
	v_mad_i64_i32 v[78:79], s[4:5], v82, s89, v[122:123]
	v_pk_mul_f32 v[80:81], v[80:81], v[84:85] op_sel_hi:[1,0]
	v_lshl_add_u64 v[78:79], v[78:79], 0, v[124:125]
	v_cvt_pk_bf16_f32 v75, v80, v81
	v_cvt_pk_bf16_f32 v76, v76, v77
	v_cvt_pk_bf16_f32 v77, v86, v87
	global_store_dwordx4 v[78:79], v[74:77], off
	v_pk_mul_f32 v[70:71], v[70:71], v[84:85] op_sel_hi:[1,0]
	v_pk_mul_f32 v[72:73], v[72:73], v[84:85] op_sel_hi:[1,0]
	v_pk_mul_f32 v[74:75], v[68:69], v[84:85] op_sel_hi:[1,0]
	v_pk_mul_f32 v[68:69], v[66:67], v[84:85] op_sel_hi:[1,0]
	v_cvt_pk_bf16_f32 v66, v70, v71
	v_cvt_pk_bf16_f32 v67, v72, v73
	s_nop 0
	v_cvt_pk_bf16_f32 v68, v68, v69
	v_cvt_pk_bf16_f32 v69, v74, v75
	global_store_dwordx4 v[78:79], v[66:69], off offset:256
	s_nop 1
	v_add_u32_e32 v66, 0x80, v140
	v_ashrrev_i32_e32 v67, 31, v66
	v_lshl_add_u64 v[68:69], v[66:67], 2, s[12:13]
	global_load_dword v67, v[68:69], off
	s_waitcnt vmcnt(0) lgkmcnt(0)
	v_fmamk_f32 v67, v67, 0x3a2aaaab, v207
	v_cmp_gt_f32_e32 vcc, s87, v67
	v_mul_f32_e32 v68, 0x4b800000, v67
	s_nop 0
	v_cndmask_b32_e32 v67, v67, v68, vcc
	v_rsq_f32_e32 v67, v67
	s_nop 0
	v_mul_f32_e32 v68, 0x45800000, v67
	v_cndmask_b32_e32 v68, v67, v68, vcc
	v_pk_mul_f32 v[62:63], v[62:63], v[68:69] op_sel_hi:[1,0]
	v_pk_mul_f32 v[70:71], v[60:61], v[68:69] op_sel_hi:[1,0]
	v_pk_mul_f32 v[60:61], v[58:59], v[68:69] op_sel_hi:[1,0]
	v_cvt_pk_bf16_f32 v58, v62, v63
	v_mad_i64_i32 v[62:63], s[4:5], v66, s89, v[122:123]
	v_pk_mul_f32 v[64:65], v[64:65], v[68:69] op_sel_hi:[1,0]
	v_lshl_add_u64 v[62:63], v[62:63], 0, v[124:125]
	v_cvt_pk_bf16_f32 v59, v64, v65
	v_cvt_pk_bf16_f32 v60, v60, v61
	v_cvt_pk_bf16_f32 v61, v70, v71
	global_store_dwordx4 v[62:63], v[58:61], off
	v_pk_mul_f32 v[54:55], v[54:55], v[68:69] op_sel_hi:[1,0]
	v_pk_mul_f32 v[56:57], v[56:57], v[68:69] op_sel_hi:[1,0]
	v_pk_mul_f32 v[58:59], v[52:53], v[68:69] op_sel_hi:[1,0]
	v_pk_mul_f32 v[52:53], v[50:51], v[68:69] op_sel_hi:[1,0]
	v_cvt_pk_bf16_f32 v50, v54, v55
	v_cvt_pk_bf16_f32 v51, v56, v57
	s_nop 0
	v_cvt_pk_bf16_f32 v52, v52, v53
	v_cvt_pk_bf16_f32 v53, v58, v59
	global_store_dwordx4 v[62:63], v[50:53], off offset:256
	s_nop 1
	v_add_u32_e32 v50, 0x90, v140
	v_ashrrev_i32_e32 v51, 31, v50
	v_lshl_add_u64 v[52:53], v[50:51], 2, s[12:13]
	global_load_dword v51, v[52:53], off
	s_waitcnt vmcnt(0) lgkmcnt(0)
	v_fmamk_f32 v51, v51, 0x3a2aaaab, v207
	v_cmp_gt_f32_e32 vcc, s87, v51
	v_mul_f32_e32 v52, 0x4b800000, v51
	s_nop 0
	v_cndmask_b32_e32 v51, v51, v52, vcc
	v_rsq_f32_e32 v51, v51
	s_nop 0
	v_mul_f32_e32 v52, 0x45800000, v51
	v_cndmask_b32_e32 v52, v51, v52, vcc
	v_pk_mul_f32 v[46:47], v[46:47], v[52:53] op_sel_hi:[1,0]
	v_pk_mul_f32 v[54:55], v[44:45], v[52:53] op_sel_hi:[1,0]
	v_pk_mul_f32 v[44:45], v[42:43], v[52:53] op_sel_hi:[1,0]
	v_cvt_pk_bf16_f32 v42, v46, v47
	v_mad_i64_i32 v[46:47], s[4:5], v50, s89, v[122:123]
	v_pk_mul_f32 v[48:49], v[48:49], v[52:53] op_sel_hi:[1,0]
	v_lshl_add_u64 v[46:47], v[46:47], 0, v[124:125]
	v_cvt_pk_bf16_f32 v43, v48, v49
	v_cvt_pk_bf16_f32 v44, v44, v45
	v_cvt_pk_bf16_f32 v45, v54, v55
	global_store_dwordx4 v[46:47], v[42:45], off
	v_pk_mul_f32 v[38:39], v[38:39], v[52:53] op_sel_hi:[1,0]
	v_pk_mul_f32 v[40:41], v[40:41], v[52:53] op_sel_hi:[1,0]
	v_pk_mul_f32 v[42:43], v[36:37], v[52:53] op_sel_hi:[1,0]
	v_pk_mul_f32 v[36:37], v[34:35], v[52:53] op_sel_hi:[1,0]
	v_cvt_pk_bf16_f32 v34, v38, v39
	v_cvt_pk_bf16_f32 v35, v40, v41
	s_nop 0
	v_cvt_pk_bf16_f32 v36, v36, v37
	v_cvt_pk_bf16_f32 v37, v42, v43
	global_store_dwordx4 v[46:47], v[34:37], off offset:256
	s_nop 1
	v_add_u32_e32 v34, 0xa0, v140
	v_ashrrev_i32_e32 v35, 31, v34
	v_lshl_add_u64 v[36:37], v[34:35], 2, s[12:13]
	global_load_dword v35, v[36:37], off
	s_waitcnt vmcnt(0) lgkmcnt(0)
	v_fmamk_f32 v35, v35, 0x3a2aaaab, v207
	v_cmp_gt_f32_e32 vcc, s87, v35
	v_mul_f32_e32 v36, 0x4b800000, v35
	s_nop 0
	v_cndmask_b32_e32 v35, v35, v36, vcc
	v_rsq_f32_e32 v35, v35
	s_nop 0
	v_mul_f32_e32 v36, 0x45800000, v35
	v_cndmask_b32_e32 v36, v35, v36, vcc
	v_pk_mul_f32 v[30:31], v[30:31], v[36:37] op_sel_hi:[1,0]
	v_pk_mul_f32 v[38:39], v[28:29], v[36:37] op_sel_hi:[1,0]
	v_pk_mul_f32 v[28:29], v[26:27], v[36:37] op_sel_hi:[1,0]
	v_cvt_pk_bf16_f32 v26, v30, v31
	v_mad_i64_i32 v[30:31], s[4:5], v34, s89, v[122:123]
	v_pk_mul_f32 v[32:33], v[32:33], v[36:37] op_sel_hi:[1,0]
	v_lshl_add_u64 v[30:31], v[30:31], 0, v[124:125]
	v_cvt_pk_bf16_f32 v27, v32, v33
	v_cvt_pk_bf16_f32 v28, v28, v29
	v_cvt_pk_bf16_f32 v29, v38, v39
	global_store_dwordx4 v[30:31], v[26:29], off
	v_pk_mul_f32 v[22:23], v[22:23], v[36:37] op_sel_hi:[1,0]
	v_pk_mul_f32 v[24:25], v[24:25], v[36:37] op_sel_hi:[1,0]
	v_pk_mul_f32 v[26:27], v[20:21], v[36:37] op_sel_hi:[1,0]
	v_pk_mul_f32 v[20:21], v[18:19], v[36:37] op_sel_hi:[1,0]
	v_cvt_pk_bf16_f32 v18, v22, v23
	v_cvt_pk_bf16_f32 v19, v24, v25
	s_nop 0
	v_cvt_pk_bf16_f32 v20, v20, v21
	v_cvt_pk_bf16_f32 v21, v26, v27
	global_store_dwordx4 v[30:31], v[18:21], off offset:256
	s_nop 1
	v_add_u32_e32 v18, 0xb0, v140
	v_ashrrev_i32_e32 v19, 31, v18
	v_lshl_add_u64 v[20:21], v[18:19], 2, s[12:13]
	global_load_dword v19, v[20:21], off
	s_waitcnt vmcnt(0) lgkmcnt(0)
	v_fmamk_f32 v19, v19, 0x3a2aaaab, v207
	v_cmp_gt_f32_e32 vcc, s87, v19
	v_mul_f32_e32 v20, 0x4b800000, v19
	s_nop 0
	v_cndmask_b32_e32 v19, v19, v20, vcc
	v_rsq_f32_e32 v19, v19
	s_nop 0
	v_mul_f32_e32 v20, 0x45800000, v19
	v_cndmask_b32_e32 v20, v19, v20, vcc
	v_pk_mul_f32 v[14:15], v[14:15], v[20:21] op_sel_hi:[1,0]
	v_pk_mul_f32 v[22:23], v[12:13], v[20:21] op_sel_hi:[1,0]
	v_pk_mul_f32 v[12:13], v[10:11], v[20:21] op_sel_hi:[1,0]
	v_cvt_pk_bf16_f32 v10, v14, v15
	v_mad_i64_i32 v[14:15], s[4:5], v18, s89, v[122:123]
	v_pk_mul_f32 v[16:17], v[16:17], v[20:21] op_sel_hi:[1,0]
	v_lshl_add_u64 v[14:15], v[14:15], 0, v[124:125]
	v_cvt_pk_bf16_f32 v11, v16, v17
	v_cvt_pk_bf16_f32 v12, v12, v13
	v_cvt_pk_bf16_f32 v13, v22, v23
	global_store_dwordx4 v[14:15], v[10:13], off
	s_mov_b64 s[4:5], -1
	s_and_b64 vcc, exec, s[38:39]
	v_pk_mul_f32 v[10:11], v[4:5], v[20:21] op_sel_hi:[1,0]
	v_pk_mul_f32 v[4:5], v[2:3], v[20:21] op_sel_hi:[1,0]
	v_pk_mul_f32 v[8:9], v[8:9], v[20:21] op_sel_hi:[1,0]
	v_pk_mul_f32 v[6:7], v[6:7], v[20:21] op_sel_hi:[1,0]
	s_nop 0
	v_cvt_pk_bf16_f32 v2, v6, v7
	v_cvt_pk_bf16_f32 v3, v8, v9
	v_cvt_pk_bf16_f32 v4, v4, v5
	v_cvt_pk_bf16_f32 v5, v10, v11
	global_store_dwordx4 v[14:15], v[2:5], off offset:256
	s_cbranch_vccnz .LBB0_252
	s_andn2_b64 vcc, exec, s[18:19]
	s_cbranch_vccnz .LBB0_251
	s_barrier
	s_branch .LBB0_251

.LBB0_319:
	s_or_b64 exec, exec, s[0:1]
	s_and_b64 vcc, exec, s[78:79]
	s_waitcnt lgkmcnt(0)
	s_barrier
	s_cbranch_vccnz .LBB0_376
	v_mov_b32_e32 v3, v206
	v_readlane_b32 s0, v254, 19
	v_ashrrev_i32_e32 v0, 6, v3
	s_nop 0
	v_add_u32_e32 v2, s0, v0
	v_mov_b32_e32 v0, s8
	v_add_co_u32_e32 v4, vcc, 0xd0000, v0
	v_mov_b32_e32 v0, s9
	s_nop 0
	v_addc_co_u32_e32 v5, vcc, 0, v0, vcc
	global_load_dwordx2 v[6:7], v[4:5], off offset:80 sc1
	s_movk_i32 s0, 0x4000
	global_load_dwordx2 v[4:5], v[4:5], off offset:88 sc1
	v_cmp_gt_i32_e32 vcc, s0, v2
	s_waitcnt vmcnt(0) lgkmcnt(0)
	v_readfirstlane_b32 s5, v7
	v_readfirstlane_b32 s4, v6
	v_readfirstlane_b32 s13, v5
	v_readfirstlane_b32 s12, v4
	s_and_saveexec_b64 s[0:1], vcc
	v_readlane_b32 s14, v255, 60
	v_readlane_b32 s18, v255, 62
	v_readlane_b32 s30, v254, 0
	s_movk_i32 s10, 0x7fff
	v_readlane_b32 s15, v255, 61
	v_readlane_b32 s19, v255, 63
	v_readlane_b32 s31, v254, 1
	s_cbranch_execz .LBB0_323
	v_and_b32_e32 v4, 64, v228
	v_xor_b32_e32 v0, 1, v228
	v_add_u32_e32 v8, 64, v4
	v_cmp_lt_i32_e32 vcc, v0, v8
	v_and_b32_e32 v16, 63, v3
	v_and_b32_e32 v9, 31, v3
	v_cndmask_b32_e32 v0, v228, v0, vcc
	v_lshlrev_b32_e32 v26, 2, v0
	v_xor_b32_e32 v0, 2, v228
	v_cmp_lt_i32_e32 vcc, v0, v8
	v_cmp_gt_u32_e64 s[36:37], 32, v16
	s_nop 0
	v_cndmask_b32_e32 v0, v228, v0, vcc
	v_lshlrev_b32_e32 v27, 2, v0
	v_xor_b32_e32 v0, 4, v228
	v_cmp_lt_i32_e32 vcc, v0, v8
	s_nop 1
	v_cndmask_b32_e32 v0, v228, v0, vcc
	v_lshlrev_b32_e32 v28, 2, v0
	v_xor_b32_e32 v0, 8, v228
	v_cmp_lt_i32_e32 vcc, v0, v8
	s_nop 1
	v_cndmask_b32_e32 v0, v228, v0, vcc
	v_lshlrev_b32_e32 v29, 2, v0
	v_lshlrev_b32_e32 v0, 5, v3
	v_xor_b32_e32 v3, 16, v228
	v_cmp_lt_i32_e32 vcc, v3, v8
	v_and_b32_e32 v0, 0x1e0, v0
	v_lshl_add_u64 v[4:5], s[4:5], 0, v[0:1]
	v_cndmask_b32_e32 v3, v228, v3, vcc
	v_lshlrev_b32_e32 v30, 2, v3
	v_xor_b32_e32 v3, 32, v228
	v_cmp_lt_i32_e32 vcc, v3, v8
	v_lshlrev_b32_e32 v0, 2, v16
	s_mov_b64 s[4:5], 0x30f00000
	v_cndmask_b32_e32 v3, v228, v3, vcc
	v_lshlrev_b32_e32 v31, 2, v3
	v_ashrrev_i32_e32 v3, 31, v2
	v_lshlrev_b64 v[10:11], 7, v[2:3]
	v_lshl_or_b32 v8, v9, 2, v10
	v_lshl_or_b32 v10, v16, 1, v10
	v_lshlrev_b64 v[12:13], 8, v[2:3]
	v_mov_b32_e32 v9, v11
	v_lshl_add_u64 v[10:11], v[10:11], 0, s[4:5]
	v_or_b32_e32 v12, v12, v0
	s_mov_b64 s[4:5], 0x25b00000
	v_lshlrev_b64 v[14:15], 12, v[2:3]
	v_lshl_add_u64 v[6:7], s[12:13], 0, v[0:1]
	v_lshl_add_u64 v[12:13], v[12:13], 0, s[4:5]
	v_lshl_or_b32 v14, v16, 4, v14
	s_mov_b64 s[4:5], 0
	global_load_dwordx2 v[176:177], v[4:5], off
	global_load_dwordx2 v[178:179], v[4:5], off offset:8
	global_load_dwordx2 v[180:181], v[4:5], off offset:16
	global_load_dwordx2 v[182:183], v[4:5], off offset:24
	s_waitcnt vmcnt(0) lgkmcnt(0)
.LBB0_322:
	v_lshl_add_u64 v[16:17], s[8:9], 0, v[14:15]
	v_add_co_u32_e32 v16, vcc, 0x28f00000, v16
	s_mov_b32 s2, 0x1100000
	s_nop 0
	v_addc_co_u32_e32 v17, vcc, 0, v17, vcc
	global_load_dwordx4 v[32:35], v[16:17], off
	global_load_dwordx4 v[184:187], v[16:17], off offset:1024
	global_load_dwordx4 v[188:191], v[16:17], off offset:2048
	global_load_dwordx4 v[192:195], v[16:17], off offset:3072
	v_add_u32_e32 v2, s52, v2
	v_lshl_add_u64 v[14:15], v[14:15], 0, s[30:31]
	s_waitcnt vmcnt(0) lgkmcnt(0)
	v_and_b32_e32 v23, 0xffff0000, v33
	v_and_b32_e32 v22, 0xffff0000, v32
	v_lshlrev_b32_e32 v25, 16, v33
	v_lshlrev_b32_e32 v24, 16, v32
	v_pk_mul_f32 v[18:19], v[22:23], v[22:23]
	v_lshlrev_b32_e32 v21, 16, v35
	v_pk_fma_f32 v[32:33], v[24:25], v[24:25], v[18:19]
	v_and_b32_e32 v19, 0xffff0000, v35
	v_add_f32_e32 v0, v32, v33
	v_mov_b32_e32 v32, v176
	v_mov_b32_e32 v33, v177
	v_and_b32_e32 v18, 0xffff0000, v34
	v_lshlrev_b32_e32 v20, 16, v34
	v_pk_mul_f32 v[34:35], v[18:19], v[18:19]
	s_nop 0
	v_pk_fma_f32 v[34:35], v[20:21], v[20:21], v[34:35]
	s_nop 0
	v_add_f32_e32 v0, v34, v0
	v_add_f32_e32 v0, v35, v0
	ds_bpermute_b32 v3, v26, v0
	s_waitcnt lgkmcnt(0)
	v_add_f32_e32 v0, v0, v3
	ds_bpermute_b32 v3, v27, v0
	s_waitcnt lgkmcnt(0)
	v_add_f32_e32 v0, v0, v3
	ds_bpermute_b32 v3, v28, v0
	s_waitcnt lgkmcnt(0)
	v_add_f32_e32 v0, v0, v3
	ds_bpermute_b32 v3, v29, v0
	s_waitcnt lgkmcnt(0)
	v_add_f32_e32 v0, v0, v3
	v_fmamk_f32 v0, v0, 0x3c000000, v207
	v_cmp_gt_f32_e32 vcc, s87, v0
	v_mul_f32_e32 v3, 0x4b800000, v0
	s_nop 0
	v_cndmask_b32_e32 v0, v0, v3, vcc
	v_rsq_f32_e32 v0, v0
	s_nop 0
	v_mul_f32_e32 v3, 0x45800000, v0
	v_cndmask_b32_e32 v0, v0, v3, vcc
	v_mul_f32_e32 v3, v0, v24
	v_mul_f32_e32 v22, v0, v22
	v_mul_f32_e32 v23, v0, v23
	v_mul_f32_e32 v18, v0, v18

	v_mul_f32_e32 v3, v32, v3
	v_mul_f32_e32 v22, v33, v22
	v_cvt_pk_bf16_f32 v22, v3, v22
	v_mul_f32_e32 v3, v0, v25
	v_mov_b32_e32 v24, v178
	v_mov_b32_e32 v25, v179
	v_mul_f32_e32 v23, v25, v23
	v_mul_f32_e32 v3, v24, v3
	v_cvt_pk_bf16_f32 v23, v3, v23
	v_mov_b32_e32 v24, v180
	v_mov_b32_e32 v25, v181
	v_mul_f32_e32 v3, v0, v20
	v_mul_f32_e32 v3, v24, v3
	v_mul_f32_e32 v18, v25, v18
	v_cvt_pk_bf16_f32 v24, v3, v18
	v_mul_f32_e32 v3, v0, v21
	v_mov_b32_e32 v20, v182
	v_mov_b32_e32 v21, v183
	v_mul_f32_e32 v0, v0, v19
	v_mul_f32_e32 v3, v20, v3
	v_mul_f32_e32 v0, v21, v0
	v_cvt_pk_bf16_f32 v25, v3, v0
	v_mov_b32_e32 v32, v184
	v_mov_b32_e32 v33, v185
	v_mov_b32_e32 v34, v186
	v_mov_b32_e32 v35, v187
	v_lshlrev_b32_e32 v21, 16, v35
	global_store_dwordx4 v[16:17], v[22:25], off
	v_lshlrev_b32_e32 v20, 16, v34
	s_nop 0
	v_and_b32_e32 v23, 0xffff0000, v33
	v_and_b32_e32 v22, 0xffff0000, v32
	v_lshlrev_b32_e32 v25, 16, v33
	v_lshlrev_b32_e32 v24, 16, v32
	v_pk_mul_f32 v[18:19], v[22:23], v[22:23]
	s_nop 0
	v_pk_fma_f32 v[32:33], v[24:25], v[24:25], v[18:19]
	v_and_b32_e32 v19, 0xffff0000, v35
	v_add_f32_e32 v0, v32, v33
	v_mov_b32_e32 v32, v176
	v_mov_b32_e32 v33, v177
	v_and_b32_e32 v18, 0xffff0000, v34
	v_pk_mul_f32 v[34:35], v[18:19], v[18:19]
	s_nop 0
	v_pk_fma_f32 v[34:35], v[20:21], v[20:21], v[34:35]
	s_nop 0
	v_add_f32_e32 v0, v34, v0
	v_add_f32_e32 v0, v35, v0
	ds_bpermute_b32 v3, v26, v0
	s_waitcnt lgkmcnt(0)
	v_add_f32_e32 v0, v0, v3
	ds_bpermute_b32 v3, v27, v0
	s_waitcnt lgkmcnt(0)
	v_add_f32_e32 v0, v0, v3
	ds_bpermute_b32 v3, v28, v0
	s_waitcnt lgkmcnt(0)
	v_add_f32_e32 v0, v0, v3
	ds_bpermute_b32 v3, v29, v0
	s_waitcnt lgkmcnt(0)
	v_add_f32_e32 v0, v0, v3
	v_fmamk_f32 v0, v0, 0x3c000000, v207
	v_cmp_gt_f32_e32 vcc, s87, v0
	v_mul_f32_e32 v3, 0x4b800000, v0
	s_nop 0
	v_cndmask_b32_e32 v0, v0, v3, vcc
	v_rsq_f32_e32 v0, v0
	s_nop 0
	v_mul_f32_e32 v3, 0x45800000, v0
	v_cndmask_b32_e32 v0, v0, v3, vcc
	v_mul_f32_e32 v3, v0, v24
	v_mul_f32_e32 v22, v0, v22
	v_mul_f32_e32 v23, v0, v23
	v_mul_f32_e32 v18, v0, v18

	v_mul_f32_e32 v3, v32, v3
	v_mul_f32_e32 v22, v33, v22
	v_cvt_pk_bf16_f32 v22, v3, v22
	v_mul_f32_e32 v3, v0, v25
	v_mov_b32_e32 v24, v178
	v_mov_b32_e32 v25, v179
	v_mul_f32_e32 v23, v25, v23
	v_mul_f32_e32 v3, v24, v3
	v_cvt_pk_bf16_f32 v23, v3, v23
	v_mov_b32_e32 v24, v180
	v_mov_b32_e32 v25, v181
	v_mul_f32_e32 v3, v0, v20
	v_mul_f32_e32 v3, v24, v3
	v_mul_f32_e32 v18, v25, v18
	v_cvt_pk_bf16_f32 v24, v3, v18
	v_mul_f32_e32 v3, v0, v21
	v_mov_b32_e32 v20, v182
	v_mov_b32_e32 v21, v183
	v_mul_f32_e32 v0, v0, v19
	v_mul_f32_e32 v3, v20, v3
	v_mul_f32_e32 v0, v21, v0
	v_cvt_pk_bf16_f32 v25, v3, v0
	v_mov_b32_e32 v32, v188
	v_mov_b32_e32 v33, v189
	v_mov_b32_e32 v34, v190
	v_mov_b32_e32 v35, v191
	v_lshlrev_b32_e32 v21, 16, v35
	global_store_dwordx4 v[16:17], v[22:25], off offset:1024
	v_lshlrev_b32_e32 v20, 16, v34
	s_nop 0
	v_and_b32_e32 v23, 0xffff0000, v33
	v_and_b32_e32 v22, 0xffff0000, v32
	v_lshlrev_b32_e32 v25, 16, v33
	v_lshlrev_b32_e32 v24, 16, v32
	v_pk_mul_f32 v[18:19], v[22:23], v[22:23]
	s_nop 0
	v_pk_fma_f32 v[32:33], v[24:25], v[24:25], v[18:19]
	v_and_b32_e32 v19, 0xffff0000, v35
	v_add_f32_e32 v0, v32, v33
	v_mov_b32_e32 v32, v176
	v_mov_b32_e32 v33, v177
	v_and_b32_e32 v18, 0xffff0000, v34
	v_pk_mul_f32 v[34:35], v[18:19], v[18:19]
	s_nop 0
	v_pk_fma_f32 v[34:35], v[20:21], v[20:21], v[34:35]
	s_nop 0
	v_add_f32_e32 v0, v34, v0
	v_add_f32_e32 v0, v35, v0
	ds_bpermute_b32 v3, v26, v0
	s_waitcnt lgkmcnt(0)
	v_add_f32_e32 v0, v0, v3
	ds_bpermute_b32 v3, v27, v0
	s_waitcnt lgkmcnt(0)
	v_add_f32_e32 v0, v0, v3
	ds_bpermute_b32 v3, v28, v0
	s_waitcnt lgkmcnt(0)
	v_add_f32_e32 v0, v0, v3
	ds_bpermute_b32 v3, v29, v0
	s_waitcnt lgkmcnt(0)
	v_add_f32_e32 v0, v0, v3
	v_fmamk_f32 v0, v0, 0x3c000000, v207
	v_cmp_gt_f32_e32 vcc, s87, v0
	v_mul_f32_e32 v3, 0x4b800000, v0
	s_nop 0
	v_cndmask_b32_e32 v0, v0, v3, vcc
	v_rsq_f32_e32 v0, v0
	s_nop 0
	v_mul_f32_e32 v3, 0x45800000, v0
	v_cndmask_b32_e32 v0, v0, v3, vcc
	v_mul_f32_e32 v3, v0, v24
	v_mul_f32_e32 v22, v0, v22
	v_mul_f32_e32 v23, v0, v23
	v_mul_f32_e32 v18, v0, v18

	v_mul_f32_e32 v3, v32, v3
	v_mul_f32_e32 v22, v33, v22
	v_cvt_pk_bf16_f32 v22, v3, v22
	v_mul_f32_e32 v3, v0, v25
	v_mov_b32_e32 v24, v178
	v_mov_b32_e32 v25, v179
	v_mul_f32_e32 v23, v25, v23
	v_mul_f32_e32 v3, v24, v3
	v_cvt_pk_bf16_f32 v23, v3, v23
	v_mov_b32_e32 v24, v180
	v_mov_b32_e32 v25, v181
	v_mul_f32_e32 v3, v0, v20
	v_mul_f32_e32 v3, v24, v3
	v_mul_f32_e32 v18, v25, v18
	v_cvt_pk_bf16_f32 v24, v3, v18
	v_mul_f32_e32 v3, v0, v21
	v_mov_b32_e32 v20, v182
	v_mov_b32_e32 v21, v183
	v_mul_f32_e32 v0, v0, v19
	v_mul_f32_e32 v3, v20, v3
	v_mul_f32_e32 v0, v21, v0
	v_cvt_pk_bf16_f32 v25, v3, v0
	v_mov_b32_e32 v32, v192
	v_mov_b32_e32 v33, v193
	v_mov_b32_e32 v34, v194
	v_mov_b32_e32 v35, v195
	v_lshlrev_b32_e32 v21, 16, v35
	global_store_dwordx4 v[16:17], v[22:25], off offset:2048
	v_lshlrev_b32_e32 v20, 16, v34
	s_nop 0
	v_and_b32_e32 v23, 0xffff0000, v33
	v_and_b32_e32 v22, 0xffff0000, v32
	v_lshlrev_b32_e32 v25, 16, v33
	v_lshlrev_b32_e32 v24, 16, v32
	v_pk_mul_f32 v[18:19], v[22:23], v[22:23]
	s_nop 0
	v_pk_fma_f32 v[32:33], v[24:25], v[24:25], v[18:19]
	v_and_b32_e32 v19, 0xffff0000, v35
	v_add_f32_e32 v0, v32, v33
	v_mov_b32_e32 v32, v176
	v_mov_b32_e32 v33, v177
	v_and_b32_e32 v18, 0xffff0000, v34
	v_pk_mul_f32 v[34:35], v[18:19], v[18:19]
	s_nop 0
	v_pk_fma_f32 v[34:35], v[20:21], v[20:21], v[34:35]
	s_nop 0
	v_add_f32_e32 v0, v34, v0
	v_add_f32_e32 v0, v35, v0
	ds_bpermute_b32 v3, v26, v0
	s_waitcnt lgkmcnt(0)
	v_add_f32_e32 v0, v0, v3
	ds_bpermute_b32 v3, v27, v0
	s_waitcnt lgkmcnt(0)
	v_add_f32_e32 v0, v0, v3
	ds_bpermute_b32 v3, v28, v0
	s_waitcnt lgkmcnt(0)
	v_add_f32_e32 v0, v0, v3
	ds_bpermute_b32 v3, v29, v0
	s_waitcnt lgkmcnt(0)
	v_add_f32_e32 v0, v0, v3
	v_fmamk_f32 v0, v0, 0x3c000000, v207
	v_cmp_gt_f32_e32 vcc, s87, v0
	v_mul_f32_e32 v3, 0x4b800000, v0
	s_nop 0
	v_cndmask_b32_e32 v0, v0, v3, vcc
	v_rsq_f32_e32 v0, v0
	s_nop 0
	v_mul_f32_e32 v3, 0x45800000, v0
	v_cndmask_b32_e32 v0, v0, v3, vcc
	v_mul_f32_e32 v3, v0, v24
	v_mul_f32_e32 v22, v0, v22
	v_mul_f32_e32 v23, v0, v23
	v_mul_f32_e32 v18, v0, v18

	v_mul_f32_e32 v3, v32, v3
	v_mul_f32_e32 v22, v33, v22
	v_cvt_pk_bf16_f32 v22, v3, v22
	v_mul_f32_e32 v3, v0, v25
	v_mov_b32_e32 v24, v178
	v_mov_b32_e32 v25, v179
	v_mul_f32_e32 v23, v25, v23
	v_mul_f32_e32 v3, v24, v3
	v_cvt_pk_bf16_f32 v23, v3, v23
	v_mov_b32_e32 v24, v180
	v_mov_b32_e32 v25, v181
	v_mul_f32_e32 v3, v0, v20
	v_mul_f32_e32 v3, v24, v3
	v_mul_f32_e32 v18, v25, v18
	v_cvt_pk_bf16_f32 v24, v3, v18
	v_mul_f32_e32 v3, v0, v21
	v_mov_b32_e32 v20, v182
	v_mov_b32_e32 v21, v183
	v_mul_f32_e32 v0, v0, v19
	v_mul_f32_e32 v3, v20, v3
	v_mul_f32_e32 v0, v21, v0
	v_cvt_pk_bf16_f32 v25, v3, v0
	global_store_dwordx4 v[16:17], v[22:25], off offset:3072
	v_lshl_add_u64 v[16:17], s[8:9], 0, v[12:13]
	global_load_dword v0, v[16:17], off
	v_lshl_add_u64 v[12:13], v[12:13], 0, s[18:19]
	s_waitcnt vmcnt(0) lgkmcnt(0)
	v_mul_f32_e32 v3, v0, v0
	ds_bpermute_b32 v3, v26, v3
	s_waitcnt lgkmcnt(0)
	v_fmac_f32_e32 v3, v0, v0
	ds_bpermute_b32 v16, v27, v3
	s_waitcnt lgkmcnt(0)
	v_add_f32_e32 v3, v3, v16
	ds_bpermute_b32 v16, v28, v3
	s_waitcnt lgkmcnt(0)
	v_add_f32_e32 v3, v3, v16
	ds_bpermute_b32 v16, v29, v3
	s_waitcnt lgkmcnt(0)
	v_add_f32_e32 v3, v3, v16
	ds_bpermute_b32 v16, v30, v3
	s_waitcnt lgkmcnt(0)
	v_add_f32_e32 v3, v3, v16
	ds_bpermute_b32 v16, v31, v3
	s_waitcnt lgkmcnt(0)
	v_add_f32_e32 v3, v3, v16
	v_fmamk_f32 v3, v3, 0x3c800000, v207
	v_cmp_gt_f32_e32 vcc, s87, v3
	v_mul_f32_e32 v16, 0x4b800000, v3
	s_nop 0
	v_cndmask_b32_e32 v3, v3, v16, vcc
	v_rsq_f32_e32 v3, v3
	s_nop 0
	v_mul_f32_e32 v16, 0x45800000, v3
	v_cndmask_b32_e32 v3, v3, v16, vcc
	v_mul_f32_e32 v0, v0, v3
	global_load_dword v3, v[6:7], off
	v_lshl_add_u64 v[16:17], s[8:9], 0, v[8:9]
	v_add_co_u32_e32 v18, vcc, s2, v16
	s_mov_b32 s2, 0x1300000
	s_nop 0
	v_addc_co_u32_e32 v19, vcc, 0, v17, vcc
	v_add_co_u32_e32 v16, vcc, s2, v16
	global_load_dword v18, v[18:19], off
	s_nop 0
	v_addc_co_u32_e32 v17, vcc, 0, v17, vcc
	global_load_dword v16, v[16:17], off
	s_movk_i32 s2, 0x3fff
	v_cmp_lt_i32_e32 vcc, s2, v2
	v_lshl_add_u64 v[8:9], v[8:9], 0, s[14:15]
	s_or_b64 s[4:5], vcc, s[4:5]
	s_waitcnt vmcnt(0) lgkmcnt(0)
	v_mul_f32_e32 v0, v3, v0
	ds_bpermute_b32 v3, v31, v0
	s_waitcnt lgkmcnt(0)
	v_mul_f32_e32 v3, v16, v3
	v_cndmask_b32_e64 v3, v3, -v3, s[36:37]
	v_fmac_f32_e32 v3, v18, v0
	v_bfe_u32 v0, v3, 16, 1
	v_add3_u32 v0, v3, v0, s10
	v_lshl_add_u64 v[16:17], s[8:9], 0, v[10:11]
	v_lshl_add_u64 v[10:11], v[10:11], 0, s[14:15]
	global_store_short_d16_hi v[16:17], v0, off
	s_andn2_b64 exec, exec, s[4:5]
	s_cbranch_execnz .LBB0_322

.LBB0_376:
	v_mov_b32_e32 v2, s8
	s_mov_b32 s2, 0xd0000
	v_add_co_u32_e32 v2, vcc, s2, v2
	v_mov_b32_e32 v3, s9
	v_mov_b32_e32 v0, v206
	v_addc_co_u32_e32 v3, vcc, 0, v3, vcc
	global_load_dwordx2 v[4:5], v[2:3], off offset:120 sc1
	s_add_u32 s12, s8, 0xd0078
	s_addc_u32 s13, s9, 0
	s_lshl_b32 s54, s66, 7
	s_add_u32 s14, s8, 0xd0080
	s_addc_u32 s15, s9, 0
	v_writelane_b32 v254, s66, 34
	s_lshl_b32 s0, s66, 6
	s_add_u32 s78, s8, 0x37100000
	s_addc_u32 s79, s9, 0
	s_lshl_b64 s[18:19], s[54:55], 2
	v_and_b32_e32 v0, 63, v0
	s_mov_b32 s1, s55
	v_lshlrev_b32_e32 v0, 2, v0
	v_writelane_b32 v254, s67, 35
	s_waitcnt vmcnt(0) lgkmcnt(0)
	v_readfirstlane_b32 s2, v5
	v_readfirstlane_b32 s4, v4
	global_load_dwordx2 v[4:5], v[2:3], off offset:128 sc1
	s_add_u32 s30, s4, s18
	s_addc_u32 s31, s2, s19
	s_lshl_b64 s[40:41], s[0:1], 2
	s_waitcnt vmcnt(0) lgkmcnt(0)
	v_readfirstlane_b32 s2, v5
	v_readfirstlane_b32 s4, v4
	global_load_dwordx2 v[4:5], v[2:3], off offset:80 sc1
	s_add_u32 s6, s4, s40
	global_load_dwordx2 v[2:3], v[2:3], off offset:88 sc1
	s_addc_u32 s7, s2, s41
	s_waitcnt vmcnt(0) lgkmcnt(0)
	v_readfirstlane_b32 s4, v4
	v_readfirstlane_b32 s5, v5
	v_readfirstlane_b32 s1, v3
	v_readfirstlane_b32 s0, v2
	v_lshl_add_u64 v[2:3], s[30:31], 0, v[0:1]
	global_load_dword v4, v[2:3], off
	s_nop 0
	global_load_dword v2, v[2:3], off offset:256
	s_waitcnt vmcnt(0) lgkmcnt(0)
	v_max_f32_e64 v3, |v4|, |v4|
	v_max_f32_e64 v2, |v2|, |v2|
	v_max_f32_e32 v4, v3, v2
	v_lshl_add_u64 v[2:3], s[6:7], 0, v[0:1]
	global_load_dword v5, v[2:3], off
	v_lshl_add_u64 v[2:3], s[4:5], 0, v[0:1]
	global_load_dword v7, v[2:3], off
	s_nop 0
	global_load_dword v2, v[2:3], off offset:256
	s_waitcnt vmcnt(0) lgkmcnt(0)
	v_and_b32_e32 v6, 0x7fffffff, v5
	v_max_f32_e64 v3, |v7|, |v7|
	v_max_f32_e64 v2, |v2|, |v2|
	v_max_f32_e32 v7, v3, v2
	v_lshl_add_u64 v[2:3], s[0:1], 0, v[0:1]
	global_load_dword v0, v[2:3], off
	v_and_b32_e32 v3, 64, v228
	v_add_u32_e32 v8, 64, v3
	v_xor_b32_e32 v3, 1, v228
	v_cmp_lt_i32_e32 vcc, v3, v8
	v_max_f32_e64 v5, |v5|, |v5|
	v_readlane_b32 s0, v255, 12
	v_cndmask_b32_e32 v3, v228, v3, vcc
	v_lshlrev_b32_e32 v3, 2, v3
	ds_bpermute_b32 v9, v3, v4
	ds_bpermute_b32 v6, v3, v6
	v_readlane_b32 s1, v255, 13
	s_waitcnt lgkmcnt(0)
	v_max_f32_e32 v9, v9, v9
	v_max_f32_e32 v4, v4, v9
	v_max_f32_e32 v6, v6, v6
	v_max_f32_e32 v5, v5, v6
	ds_bpermute_b32 v6, v3, v7
	s_waitcnt lgkmcnt(0)
	v_max_f32_e32 v6, v6, v6
	v_max_f32_e32 v6, v7, v6
	s_waitcnt vmcnt(0)
	v_and_b32_e32 v2, 0x7fffffff, v0
	ds_bpermute_b32 v2, v3, v2
	v_max_f32_e64 v0, |v0|, |v0|
	s_waitcnt lgkmcnt(0)
	v_max_f32_e32 v2, v2, v2
	v_max_f32_e32 v0, v0, v2
	v_xor_b32_e32 v2, 2, v228
	v_cmp_lt_i32_e32 vcc, v2, v8
	s_nop 1
	v_cndmask_b32_e32 v2, v228, v2, vcc
	v_lshlrev_b32_e32 v2, 2, v2
	ds_bpermute_b32 v3, v2, v4
	s_waitcnt lgkmcnt(0)
	v_max_f32_e32 v3, v3, v3
	v_max_f32_e32 v3, v4, v3
	ds_bpermute_b32 v4, v2, v5
	s_waitcnt lgkmcnt(0)
	v_max_f32_e32 v4, v4, v4
	v_max_f32_e32 v4, v5, v4
	ds_bpermute_b32 v5, v2, v6
	ds_bpermute_b32 v2, v2, v0
	s_waitcnt lgkmcnt(1)
	v_max_f32_e32 v5, v5, v5
	s_waitcnt lgkmcnt(0)
	v_max_f32_e32 v2, v2, v2
	v_max_f32_e32 v0, v0, v2
	v_xor_b32_e32 v2, 4, v228
	v_cmp_lt_i32_e32 vcc, v2, v8
	v_max_f32_e32 v5, v6, v5
	s_nop 0
	v_cndmask_b32_e32 v2, v228, v2, vcc
	v_lshlrev_b32_e32 v2, 2, v2
	ds_bpermute_b32 v6, v2, v3
	s_waitcnt lgkmcnt(0)
	v_max_f32_e32 v6, v6, v6
	v_max_f32_e32 v3, v3, v6
	ds_bpermute_b32 v6, v2, v4
	s_waitcnt lgkmcnt(0)
	v_max_f32_e32 v6, v6, v6
	v_max_f32_e32 v4, v4, v6
	ds_bpermute_b32 v6, v2, v5
	ds_bpermute_b32 v2, v2, v0
	s_waitcnt lgkmcnt(1)
	v_max_f32_e32 v6, v6, v6
	s_waitcnt lgkmcnt(0)
	v_max_f32_e32 v2, v2, v2
	v_max_f32_e32 v0, v0, v2
	v_xor_b32_e32 v2, 8, v228
	v_cmp_lt_i32_e32 vcc, v2, v8
	v_max_f32_e32 v5, v5, v6
	s_nop 0
	v_cndmask_b32_e32 v2, v228, v2, vcc
	v_lshlrev_b32_e32 v2, 2, v2
	ds_bpermute_b32 v6, v2, v3
	s_waitcnt lgkmcnt(0)
	v_max_f32_e32 v6, v6, v6
	v_max_f32_e32 v3, v3, v6
	ds_bpermute_b32 v6, v2, v4
	s_waitcnt lgkmcnt(0)
	v_max_f32_e32 v6, v6, v6
	v_max_f32_e32 v4, v4, v6
	ds_bpermute_b32 v6, v2, v5
	ds_bpermute_b32 v2, v2, v0
	s_waitcnt lgkmcnt(1)
	v_max_f32_e32 v6, v6, v6
	s_waitcnt lgkmcnt(0)
	v_max_f32_e32 v2, v2, v2
	v_max_f32_e32 v5, v5, v6
	v_max_f32_e32 v6, v0, v2
	v_xor_b32_e32 v0, 16, v228
	v_cmp_lt_i32_e32 vcc, v0, v8
	s_nop 1
	v_cndmask_b32_e32 v0, v228, v0, vcc
	v_lshlrev_b32_e32 v7, 2, v0
	ds_bpermute_b32 v0, v7, v3
	ds_bpermute_b32 v2, v7, v4
	s_waitcnt lgkmcnt(1)
	v_max_f32_e32 v0, v0, v0
	v_max_f32_e32 v0, v3, v0
	ds_bpermute_b32 v3, v7, v5
	s_waitcnt lgkmcnt(1)
	v_max_f32_e32 v2, v2, v2
	v_max_f32_e32 v2, v4, v2
	ds_bpermute_b32 v4, v7, v6
	s_waitcnt lgkmcnt(1)
	v_max_f32_e32 v3, v3, v3
	v_max_f32_e32 v3, v5, v3
	v_xor_b32_e32 v5, 32, v228
	v_cmp_lt_i32_e32 vcc, v5, v8
	s_waitcnt lgkmcnt(0)
	v_max_f32_e32 v4, v4, v4
	v_max_f32_e32 v4, v6, v4
	v_cndmask_b32_e32 v5, v228, v5, vcc
	v_lshlrev_b32_e32 v8, 2, v5
	ds_bpermute_b32 v5, v8, v0
	ds_bpermute_b32 v6, v8, v2
	ds_bpermute_b32 v7, v8, v3
	ds_bpermute_b32 v8, v8, v4
	s_and_b64 vcc, exec, s[0:1]
	s_cbranch_vccz .LBB0_405
	s_add_u32 s53, s8, 0x28f00000
	s_waitcnt lgkmcnt(0)
	v_max_f32_e32 v8, v8, v8
	v_max_f32_e32 v4, v4, v4
	s_addc_u32 s10, s9, 0
	v_max_f32_e32 v9, v4, v8
	v_max_f32_e32 v4, v7, v7
	v_max_f32_e32 v3, v3, v3
	s_add_u32 s44, s8, 0x2cf00000
	v_max_f32_e32 v8, v3, v4
	v_max_f32_e32 v3, v6, v6
	v_max_f32_e32 v2, v2, v2
	s_addc_u32 s45, s9, 0
	v_max_f32_e32 v3, v2, v3
	v_max_f32_e32 v2, v5, v5
	v_max_f32_e32 v0, v0, v0
	s_mov_b32 s0, 0x43000000
	s_add_u32 s46, s8, 0x1100000
	v_max_f32_e32 v2, v0, v2
	s_mov_b32 s1, 0x42800000
	s_addc_u32 s47, s9, 0
	v_pk_mul_f32 v[2:3], v[2:3], s[0:1]
	s_add_u32 s11, s8, 0x30f00000
	v_pk_mul_f32 v[2:3], v[2:3], v[8:9]
	v_writelane_b32 v254, s78, 36
	s_addc_u32 s42, s9, 0
	v_add_f32_e32 v0, v2, v3
	v_writelane_b32 v254, s79, 37
	s_add_u32 s48, s8, 0x1300000
	v_mul_f32_e32 v16, 0xbddba134, v0
	v_writelane_b32 v254, s73, 38
	s_addc_u32 s49, s9, 0
	v_mov_b32_e32 v17, v16
	v_mov_b32_e32 v18, v16
	v_mov_b32_e32 v19, v16
	v_mov_b32_e32 v20, v16
	v_mov_b32_e32 v21, v16
	v_mov_b32_e32 v22, v16
	v_mov_b32_e32 v23, v16
	v_mov_b32_e32 v24, v16
	v_mov_b32_e32 v25, v16
	v_mov_b32_e32 v26, v16
	v_mov_b32_e32 v27, v16
	v_mov_b32_e32 v28, v16
	v_mov_b32_e32 v29, v16
	v_mov_b32_e32 v30, v16
	v_mov_b32_e32 v31, v16
	s_mov_b32 s43, s85
	s_branch .LBB0_379

.LBB0_380:
	s_setprio 0
	v_mov_b32_e32 v0, v238
	s_nop 1
	v_permlane32_swap_b32_e32 v238, v0
	v_add_f32_e32 v0, v238, v0
	v_div_scale_f32 v2, s[0:1], v0, v0, 1.0
	v_rcp_f32_e32 v3, v2
	s_mov_b64 s[76:77], 0
	v_fma_f32 v4, -v2, v3, 1.0
	v_fmac_f32_e32 v3, v4, v3
	v_div_scale_f32 v4, vcc, 1.0, v0, 1.0
	v_mul_f32_e32 v5, v4, v3
	v_fma_f32 v6, -v2, v5, v4
	v_fmac_f32_e32 v5, v6, v3
	v_fma_f32 v2, -v2, v5, v4
	v_div_fmas_f32 v2, v2, v3, v5
	v_div_fixup_f32 v6, v2, v0, 1.0
	v_lshlrev_b64 v[2:3], 12, v[196:197]
	v_lshl_add_u64 v[2:3], s[58:59], 0, v[2:3]
	v_lshlrev_b32_e32 v0, 1, v234
	v_lshl_add_u64 v[2:3], v[2:3], 0, v[0:1]
	v_mul_f32_e32 v0, v80, v6
	v_mul_f32_e32 v4, v81, v6
	v_mul_f32_e32 v5, v83, v6
	v_cvt_pk_bf16_f32 v4, v0, v4
	v_mul_f32_e32 v0, v82, v6
	v_cvt_pk_bf16_f32 v5, v0, v5
	global_store_dwordx2 v[2:3], v[4:5], off
	v_mul_f32_e32 v0, v84, v6
	v_mul_f32_e32 v4, v85, v6
	v_mul_f32_e32 v5, v87, v6
	v_cvt_pk_bf16_f32 v4, v0, v4
	v_mul_f32_e32 v0, v86, v6
	v_cvt_pk_bf16_f32 v5, v0, v5
	global_store_dwordx2 v[2:3], v[4:5], off offset:16
	v_mul_f32_e32 v0, v88, v6
	v_mul_f32_e32 v4, v89, v6
	v_mul_f32_e32 v5, v91, v6
	v_cvt_pk_bf16_f32 v4, v0, v4
	v_mul_f32_e32 v0, v90, v6
	v_cvt_pk_bf16_f32 v5, v0, v5
	global_store_dwordx2 v[2:3], v[4:5], off offset:32
	v_mul_f32_e32 v0, v92, v6
	v_mul_f32_e32 v4, v93, v6
	v_mul_f32_e32 v5, v95, v6
	v_cvt_pk_bf16_f32 v4, v0, v4
	v_mul_f32_e32 v0, v94, v6
	v_cvt_pk_bf16_f32 v5, v0, v5
	global_store_dwordx2 v[2:3], v[4:5], off offset:48
	v_mul_f32_e32 v0, v64, v6
	v_mul_f32_e32 v4, v65, v6
	v_mul_f32_e32 v5, v67, v6
	v_cvt_pk_bf16_f32 v4, v0, v4
	v_mul_f32_e32 v0, v66, v6
	v_cvt_pk_bf16_f32 v5, v0, v5
	global_store_dwordx2 v[2:3], v[4:5], off offset:64
	v_mul_f32_e32 v0, v68, v6
	v_mul_f32_e32 v4, v69, v6
	v_mul_f32_e32 v5, v71, v6
	v_cvt_pk_bf16_f32 v4, v0, v4
	v_mul_f32_e32 v0, v70, v6
	v_cvt_pk_bf16_f32 v5, v0, v5
	global_store_dwordx2 v[2:3], v[4:5], off offset:80
	v_mul_f32_e32 v0, v72, v6
	v_mul_f32_e32 v4, v73, v6
	v_mul_f32_e32 v5, v75, v6
	v_cvt_pk_bf16_f32 v4, v0, v4
	v_mul_f32_e32 v0, v74, v6
	v_cvt_pk_bf16_f32 v5, v0, v5
	global_store_dwordx2 v[2:3], v[4:5], off offset:96
	v_mul_f32_e32 v0, v76, v6
	v_mul_f32_e32 v4, v77, v6
	v_mul_f32_e32 v5, v79, v6
	v_cvt_pk_bf16_f32 v4, v0, v4
	v_mul_f32_e32 v0, v78, v6
	v_cvt_pk_bf16_f32 v5, v0, v5
	global_store_dwordx2 v[2:3], v[4:5], off offset:112
	v_mul_f32_e32 v0, v48, v6
	v_mul_f32_e32 v4, v49, v6
	v_mul_f32_e32 v5, v51, v6
	v_cvt_pk_bf16_f32 v4, v0, v4
	v_mul_f32_e32 v0, v50, v6
	v_cvt_pk_bf16_f32 v5, v0, v5
	global_store_dwordx2 v[2:3], v[4:5], off offset:128
	v_mul_f32_e32 v0, v52, v6
	v_mul_f32_e32 v4, v53, v6
	v_mul_f32_e32 v5, v55, v6
	v_cvt_pk_bf16_f32 v4, v0, v4
	v_mul_f32_e32 v0, v54, v6
	v_cvt_pk_bf16_f32 v5, v0, v5
	global_store_dwordx2 v[2:3], v[4:5], off offset:144
	v_mul_f32_e32 v0, v56, v6
	v_mul_f32_e32 v4, v57, v6
	v_mul_f32_e32 v5, v59, v6
	v_cvt_pk_bf16_f32 v4, v0, v4
	v_mul_f32_e32 v0, v58, v6
	v_cvt_pk_bf16_f32 v5, v0, v5
	global_store_dwordx2 v[2:3], v[4:5], off offset:160
	v_mul_f32_e32 v0, v60, v6
	v_mul_f32_e32 v4, v61, v6
	v_mul_f32_e32 v5, v63, v6
	v_cvt_pk_bf16_f32 v4, v0, v4
	v_mul_f32_e32 v0, v62, v6
	v_cvt_pk_bf16_f32 v5, v0, v5
	global_store_dwordx2 v[2:3], v[4:5], off offset:176
	v_mul_f32_e32 v0, v32, v6
	v_mul_f32_e32 v4, v33, v6
	v_mul_f32_e32 v5, v35, v6
	v_cvt_pk_bf16_f32 v4, v0, v4
	v_mul_f32_e32 v0, v34, v6
	v_cvt_pk_bf16_f32 v5, v0, v5
	global_store_dwordx2 v[2:3], v[4:5], off offset:192
	v_mul_f32_e32 v0, v36, v6
	v_mul_f32_e32 v4, v37, v6
	v_mul_f32_e32 v5, v39, v6
	v_cvt_pk_bf16_f32 v4, v0, v4
	v_mul_f32_e32 v0, v38, v6
	v_cvt_pk_bf16_f32 v5, v0, v5
	global_store_dwordx2 v[2:3], v[4:5], off offset:208
	v_mul_f32_e32 v0, v40, v6
	v_mul_f32_e32 v4, v41, v6
	v_mul_f32_e32 v5, v43, v6
	v_cvt_pk_bf16_f32 v4, v0, v4
	v_mul_f32_e32 v0, v42, v6
	v_cvt_pk_bf16_f32 v5, v0, v5
	global_store_dwordx2 v[2:3], v[4:5], off offset:224
	v_mul_f32_e32 v0, v44, v6
	v_mul_f32_e32 v4, v45, v6
	v_mul_f32_e32 v5, v47, v6
	s_and_b64 vcc, exec, s[78:79]
	v_cvt_pk_bf16_f32 v4, v0, v4
	v_mul_f32_e32 v0, v46, v6
	v_cvt_pk_bf16_f32 v5, v0, v5
	global_store_dwordx2 v[2:3], v[4:5], off offset:240
	s_cbranch_vccnz .LBB0_378
.LBB0_381:
	s_and_b64 s[0:1], s[76:77], exec
	s_cselect_b32 s6, s2, s90
	v_mov_b32_e32 v56, v206
	s_lshl_b32 s68, s6, 8
	v_ashrrev_i32_e32 v60, 6, v56
	v_and_b32_e32 v57, 31, v56
	v_lshl_add_u32 v59, v60, 5, s68
	v_or_b32_e32 v198, v59, v57
	v_ashrrev_i32_e32 v199, 31, v198
	v_lshl_add_u64 v[196:197], s[64:65], 0, v[198:199]
	v_mov_b64_e32 v[2:3], s[16:17]
	v_mad_u64_u32 v[2:3], s[0:1], v196, s89, v[2:3]
	v_bfe_u32 v58, v56, 5, 1
	v_mad_i32_i24 v3, v197, s89, v3
	s_lshl_b32 s0, s82, 1
	s_mov_b32 s1, s55
	v_lshl_add_u64 v[4:5], v[2:3], 0, s[0:1]
	v_lshlrev_b32_e32 v0, 4, v58
	v_lshl_add_u64 v[4:5], v[4:5], 0, v[0:1]
	global_load_dwordx4 v[48:51], v[4:5], off
	global_load_dwordx4 v[44:47], v[4:5], off offset:32
	global_load_dwordx4 v[36:39], v[4:5], off offset:64
	global_load_dwordx4 v[40:43], v[4:5], off offset:96
	v_lshl_add_u64 v[2:3], v[2:3], 0, s[54:55]
	v_lshl_add_u64 v[2:3], v[2:3], 0, v[0:1]
	s_movk_i32 s0, 0x1000
	v_add_co_u32_e32 v32, vcc, s0, v2
	v_mov_b64_e32 v[14:15], s[12:13]
	s_nop 0
	v_addc_co_u32_e32 v33, vcc, 0, v3, vcc
	global_load_dwordx4 v[52:55], v[4:5], off offset:128
	global_load_dwordx4 v[62:65], v[4:5], off offset:160
	global_load_dwordx4 v[66:69], v[4:5], off offset:192
	global_load_dwordx4 v[70:73], v[4:5], off offset:224
	s_nop 0
	global_load_dwordx4 v[2:5], v[32:33], off
	global_load_dwordx4 v[10:13], v[32:33], off offset:32
	global_load_dwordx4 v[6:9], v[32:33], off offset:64
	s_nop 0
	global_load_dwordx4 v[32:35], v[32:33], off offset:96
	s_nop 0
	global_load_dwordx2 v[14:15], v[14:15], off sc1
	s_waitcnt vmcnt(0) lgkmcnt(0)
	v_and_b32_e32 v75, 0xffff0000, v49
	v_and_b32_e32 v79, 0xffff0000, v48
	v_and_b32_e32 v78, 0xffff0000, v50
	v_lshlrev_b32_e32 v74, 16, v49
	v_lshlrev_b32_e32 v77, 16, v48
	v_lshlrev_b32_e32 v76, 16, v50
	v_lshlrev_b32_e32 v90, 16, v36
	v_and_b32_e32 v91, 0xffff0000, v36
	v_lshlrev_b32_e32 v92, 16, v37
	v_and_b32_e32 v93, 0xffff0000, v37
	v_lshlrev_b32_e32 v94, 16, v38
	v_and_b32_e32 v96, 0xffff0000, v38
	v_pk_mov_b32 v[36:37], v[38:39], v[42:43] op_sel:[1,0]
	v_lshlrev_b32_e32 v50, 16, v39
	v_mul_f32_e32 v0, v75, v75
	v_pk_mul_f32 v[38:39], v[78:79], v[78:79]
	v_lshlrev_b32_e32 v61, 16, v41
	v_and_b32_e32 v122, 0xffff0000, v41
	v_lshlrev_b32_e32 v41, 16, v43
	v_lshlrev_b32_e32 v95, 16, v40
	v_and_b32_e32 v97, 0xffff0000, v40
	v_mul_f32_e32 v40, v91, v91
	v_mul_f32_e32 v48, v93, v93
	v_pk_fma_f32 v[98:99], v[74:75], v[74:75], v[0:1] op_sel_hi:[1,1,0]
	v_pk_fma_f32 v[38:39], v[76:77], v[76:77], v[38:39]
	v_mul_f32_e32 v102, v61, v61
	v_mul_f32_e32 v103, v122, v122
	v_pk_fma_f32 v[100:101], v[90:91], v[90:91], v[40:41] op_sel_hi:[1,1,0]
	v_pk_fma_f32 v[48:49], v[92:93], v[92:93], v[48:49] op_sel_hi:[1,1,0]
	v_pk_add_f32 v[98:99], v[38:39], v[98:99] op_sel:[1,0] op_sel_hi:[0,1]
	v_and_b32_e32 v85, 0xffff0000, v45
	v_and_b32_e32 v84, 0xffff0000, v44
	v_lshlrev_b32_e32 v87, 16, v47
	v_lshlrev_b32_e32 v86, 16, v46
	v_and_b32_e32 v89, 0xffff0000, v47
	v_and_b32_e32 v88, 0xffff0000, v46
	v_pk_mul_f32 v[46:47], v[96:97], v[96:97]
	v_mov_b32_e32 v101, v102
	v_mov_b32_e32 v49, v103
	v_pk_add_f32 v[38:39], v[38:39], v[98:99]
	v_and_b32_e32 v99, 0xffff0000, v37
	v_and_b32_e32 v98, 0xffff0000, v36
	v_lshlrev_b32_e32 v80, 16, v51
	v_and_b32_e32 v81, 0xffff0000, v51
	v_lshlrev_b32_e32 v83, 16, v45
	v_lshlrev_b32_e32 v82, 16, v44
	v_and_b32_e32 v123, 0xffff0000, v43
	v_lshlrev_b32_e32 v51, 16, v42
	v_pk_mul_f32 v[42:43], v[84:85], v[84:85]
	v_pk_fma_f32 v[46:47], v[94:95], v[94:95], v[46:47]
	v_pk_add_f32 v[48:49], v[100:101], v[48:49]
	v_pk_mul_f32 v[36:37], v[98:99], v[98:99]
	v_pk_mul_f32 v[44:45], v[88:89], v[88:89]
	v_pk_fma_f32 v[42:43], v[82:83], v[82:83], v[42:43]
	v_pk_add_f32 v[46:47], v[46:47], v[48:49]
	v_pk_fma_f32 v[36:37], v[50:51], v[50:51], v[36:37]
	v_mul_f32_e32 v0, v81, v81
	v_pk_fma_f32 v[44:45], v[86:87], v[86:87], v[44:45]
	v_pk_add_f32 v[42:43], v[42:43], v[42:43] op_sel:[0,1] op_sel_hi:[1,0]
	v_pk_add_f32 v[36:37], v[36:37], v[46:47]
	v_pk_fma_f32 v[46:47], v[80:81], v[80:81], v[0:1] op_sel_hi:[1,1,0]
	v_pk_add_f32 v[42:43], v[44:45], v[42:43]
	v_mov_b32_e32 v40, v46
	v_mov_b32_e32 v48, v38
	v_mov_b32_e32 v49, v41
	v_mul_f32_e32 v104, v123, v123
	v_pk_add_f32 v[38:39], v[46:47], v[38:39]
	v_pk_mul_f32 v[46:47], v[40:41], v[48:49]
	v_pk_add_f32 v[42:43], v[44:45], v[42:43] op_sel:[1,0] op_sel_hi:[0,1]
	v_mov_b32_e32 v39, v47
	v_mov_b32_e32 v43, v104
	v_pk_add_f32 v[38:39], v[38:39], v[42:43]
	v_and_b32_e32 v105, 0xffff0000, v53
	v_and_b32_e32 v104, 0xffff0000, v52
	v_readfirstlane_b32 s0, v14
	v_pk_add_f32 v[100:101], v[38:39], v[36:37]
	v_lshlrev_b32_e32 v103, 16, v53
	v_lshlrev_b32_e32 v102, 16, v52
	v_pk_mul_f32 v[36:37], v[104:105], v[104:105]
	v_readfirstlane_b32 s1, v15
	s_add_u32 s0, s0, s18
	v_pk_fma_f32 v[36:37], v[102:103], v[102:103], v[36:37]
	s_addc_u32 s1, s1, s19
	v_lshlrev_b32_e32 v0, 5, v58
	v_pk_add_f32 v[38:39], v[36:37], v[36:37] op_sel:[0,1] op_sel_hi:[1,0]
	v_mov_b64_e32 v[14:15], s[14:15]
	v_lshl_add_u64 v[36:37], s[0:1], 0, v[0:1]
	global_load_dwordx2 v[14:15], v[14:15], off sc1
	v_lshlrev_b32_e32 v107, 16, v55
	global_load_dwordx2 v[108:109], v[36:37], off
	global_load_dwordx2 v[164:165], v[36:37], off offset:8
	global_load_dwordx2 v[166:167], v[36:37], off offset:16
	global_load_dwordx2 v[168:169], v[36:37], off offset:24
	global_load_dwordx2 v[170:171], v[36:37], off offset:64
	global_load_dwordx2 v[172:173], v[36:37], off offset:72
	global_load_dwordx2 v[174:175], v[36:37], off offset:80
	global_load_dwordx2 v[176:177], v[36:37], off offset:88
	global_load_dwordx2 v[178:179], v[36:37], off offset:128
	global_load_dwordx2 v[180:181], v[36:37], off offset:136
	global_load_dwordx2 v[182:183], v[36:37], off offset:144
	global_load_dwordx2 v[184:185], v[36:37], off offset:152
	global_load_dwordx2 v[186:187], v[36:37], off offset:192
	global_load_dwordx2 v[188:189], v[36:37], off offset:200
	global_load_dwordx2 v[190:191], v[36:37], off offset:208
	global_load_dwordx2 v[192:193], v[36:37], off offset:216
	global_load_dwordx2 v[194:195], v[36:37], off offset:256
	global_load_dwordx2 v[208:209], v[36:37], off offset:264
	global_load_dwordx2 v[210:211], v[36:37], off offset:272
	global_load_dwordx2 v[240:241], v[36:37], off offset:280
	global_load_dwordx2 v[242:243], v[36:37], off offset:320
	v_lshlrev_b32_e32 v106, 16, v54
	v_and_b32_e32 v55, 0xffff0000, v55
	v_and_b32_e32 v54, 0xffff0000, v54
	v_pk_mul_f32 v[42:43], v[54:55], v[54:55]
	v_lshlrev_b32_e32 v113, 16, v63
	v_pk_fma_f32 v[42:43], v[106:107], v[106:107], v[42:43]
	v_lshlrev_b32_e32 v112, 16, v62
	v_pk_add_f32 v[38:39], v[42:43], v[38:39]
	v_and_b32_e32 v63, 0xffff0000, v63
	v_and_b32_e32 v62, 0xffff0000, v62
	v_lshlrev_b32_e32 v115, 16, v65
	v_lshlrev_b32_e32 v114, 16, v64
	v_and_b32_e32 v65, 0xffff0000, v65
	v_and_b32_e32 v64, 0xffff0000, v64
	v_and_b32_e32 v121, 0xffff0000, v66
	v_pk_add_f32 v[110:111], v[42:43], v[38:39] op_sel:[1,0] op_sel_hi:[0,1]
	v_pk_mul_f32 v[38:39], v[62:63], v[62:63]
	v_pk_mul_f32 v[42:43], v[64:65], v[64:65]
	v_lshlrev_b32_e32 v120, 16, v66
	v_and_b32_e32 v53, 0xffff0000, v67
	v_mul_f32_e32 v40, v121, v121
	v_pk_fma_f32 v[38:39], v[112:113], v[112:113], v[38:39]
	v_pk_fma_f32 v[116:117], v[114:115], v[114:115], v[42:43]
	v_lshlrev_b32_e32 v52, 16, v67
	v_lshlrev_b32_e32 v124, 16, v71
	v_and_b32_e32 v125, 0xffff0000, v71
	v_pk_fma_f32 v[42:43], v[120:121], v[120:121], v[40:41] op_sel_hi:[1,1,0]
	v_mul_f32_e32 v40, v53, v53
	v_pk_add_f32 v[38:39], v[38:39], v[38:39] op_sel:[0,1] op_sel_hi:[1,0]
	v_mul_f32_e32 v46, v124, v124
	v_mul_f32_e32 v71, v125, v125
	v_and_b32_e32 v45, 0xffff0000, v70
	v_and_b32_e32 v44, 0xffff0000, v68
	v_pk_fma_f32 v[66:67], v[52:53], v[52:53], v[40:41] op_sel_hi:[1,1,0]
	v_pk_add_f32 v[118:119], v[116:117], v[38:39]
	v_lshlrev_b32_e32 v49, 16, v70
	v_lshlrev_b32_e32 v48, 16, v68
	v_pk_mul_f32 v[38:39], v[44:45], v[44:45]
	v_mov_b32_e32 v43, v46
	v_mov_b32_e32 v67, v71
	v_pk_fma_f32 v[38:39], v[48:49], v[48:49], v[38:39]
	v_pk_add_f32 v[42:43], v[42:43], v[66:67]
	v_lshlrev_b32_e32 v47, 16, v73
	v_pk_add_f32 v[66:67], v[38:39], v[42:43]
	v_pk_mov_b32 v[38:39], v[68:69], v[72:73] op_sel:[1,0]
	v_lshlrev_b32_e32 v43, 16, v72
	v_and_b32_e32 v39, 0xffff0000, v39
	v_and_b32_e32 v38, 0xffff0000, v38
	v_lshlrev_b32_e32 v42, 16, v69
	v_pk_mul_f32 v[68:69], v[38:39], v[38:39]
	v_mov_b32_e32 v70, v110
	v_pk_fma_f32 v[68:69], v[42:43], v[42:43], v[68:69]
	v_mov_b32_e32 v71, v47
	v_pk_add_f32 v[66:67], v[68:69], v[66:67]
	v_pk_add_f32 v[68:69], v[100:101], v[100:101] op_sel:[0,1] op_sel_hi:[1,0]
	v_and_b32_e32 v126, 0xffff0000, v73
	v_mov_b32_e32 v46, v68
	v_pk_add_f32 v[68:69], v[68:69], v[110:111]
	v_pk_mul_f32 v[70:71], v[46:47], v[70:71]
	v_mul_f32_e32 v127, v126, v126
	v_mov_b32_e32 v69, v71
	v_pk_add_f32 v[70:71], v[116:117], v[118:119] op_sel:[1,0] op_sel_hi:[0,1]
	v_mov_b32_e32 v71, v127
	v_pk_add_f32 v[68:69], v[68:69], v[70:71]
	s_waitcnt vmcnt(0) lgkmcnt(0)
	v_readfirstlane_b32 s0, v14
	v_pk_add_f32 v[66:67], v[68:69], v[66:67]
	v_readfirstlane_b32 s1, v15
	v_pk_add_f32 v[66:67], v[66:67], v[66:67] op_sel:[0,1] op_sel_hi:[1,0]
	s_add_u32 s0, s0, s40
	v_mov_b32_e32 v40, v66
	s_nop 1
	v_permlane32_swap_b32_e32 v66, v40
	v_add_f32_e32 v40, v66, v40
	v_fmamk_f32 v40, v40, 0x3c000000, v207
	v_mul_f32_e32 v46, 0x4b800000, v40
	v_cmp_gt_f32_e32 vcc, s87, v40
	s_addc_u32 s1, s1, s41
	v_lshlrev_b32_e32 v15, 16, v13
	v_cndmask_b32_e32 v40, v40, v46, vcc
	v_rsq_f32_e32 v40, v40
	v_lshlrev_b32_e32 v14, 16, v35
	v_mul_f32_e32 v46, 0x45800000, v40
	v_cndmask_b32_e32 v40, v40, v46, vcc
	v_mul_f32_e32 v68, 0x3dd53b94, v40
	v_mul_f32_e32 v40, v68, v77
	v_mul_f32_e32 v46, v68, v79
	v_mul_f32_e32 v40, v108, v40
	v_mul_f32_e32 v46, v109, v46
	v_cvt_pk_bf16_f32 v128, v40, v46
	v_mov_b32_e32 v66, v164
	v_mov_b32_e32 v67, v165
	v_mul_f32_e32 v40, v68, v74
	v_mul_f32_e32 v46, v68, v75
	v_mul_f32_e32 v44, v68, v44
	v_mul_f32_e32 v42, v68, v42
	v_mul_f32_e32 v38, v68, v38
	v_mul_f32_e32 v39, v68, v39
	v_mul_f32_e32 v40, v66, v40
	v_mul_f32_e32 v46, v67, v46
	v_cvt_pk_bf16_f32 v129, v40, v46
	v_mov_b32_e32 v66, v166
	v_mov_b32_e32 v67, v167
	v_mul_f32_e32 v40, v68, v76
	v_mul_f32_e32 v46, v68, v78
	v_mul_f32_e32 v40, v40, v66
	v_mul_f32_e32 v46, v46, v67
	v_cvt_pk_bf16_f32 v130, v40, v46
	v_mov_b32_e32 v66, v168
	v_mov_b32_e32 v67, v169
	v_mul_f32_e32 v40, v68, v80
	v_mul_f32_e32 v46, v68, v81
	v_mul_f32_e32 v40, v40, v66
	v_mul_f32_e32 v46, v46, v67
	v_cvt_pk_bf16_f32 v131, v40, v46
	v_mov_b32_e32 v66, v170
	v_mov_b32_e32 v67, v171
	v_mul_f32_e32 v40, v68, v82
	v_mul_f32_e32 v46, v68, v84
	v_lshlrev_b32_e32 v82, 16, v8
	v_and_b32_e32 v84, 0xffff0000, v8
	v_mov_b32_e32 v162, v84
	v_mov_b32_e32 v160, v82
	v_mul_f32_e32 v40, v40, v66
	v_mul_f32_e32 v46, v46, v67
	v_cvt_pk_bf16_f32 v132, v40, v46
	v_mov_b32_e32 v66, v172
	v_mov_b32_e32 v67, v173
	v_mul_f32_e32 v40, v68, v83
	v_mul_f32_e32 v46, v68, v85
	v_lshlrev_b32_e32 v83, 16, v4
	v_and_b32_e32 v85, 0xffff0000, v4
	v_mov_b32_e32 v111, v83
	v_mul_f32_e32 v40, v40, v66
	v_mul_f32_e32 v46, v46, v67
	v_cvt_pk_bf16_f32 v133, v40, v46
	v_mov_b32_e32 v66, v174
	v_mov_b32_e32 v67, v175
	v_mul_f32_e32 v40, v68, v86
	v_mul_f32_e32 v46, v68, v88
	v_lshlrev_b32_e32 v86, 16, v7
	v_and_b32_e32 v88, 0xffff0000, v7
	v_mul_f32_e32 v40, v40, v66
	v_mul_f32_e32 v46, v46, v67
	v_cvt_pk_bf16_f32 v134, v40, v46
	v_mov_b32_e32 v66, v176
	v_mov_b32_e32 v67, v177
	v_mul_f32_e32 v40, v68, v87
	v_mul_f32_e32 v46, v68, v89
	v_lshlrev_b32_e32 v87, 16, v3
	v_and_b32_e32 v89, 0xffff0000, v3
	v_mov_b32_e32 v119, v87
	v_mul_f32_e32 v40, v40, v66
	v_mul_f32_e32 v46, v46, v67
	v_cvt_pk_bf16_f32 v135, v40, v46
	v_mov_b32_e32 v66, v178
	v_mov_b32_e32 v67, v179
	v_mul_f32_e32 v40, v68, v90
	v_mul_f32_e32 v46, v68, v91
	v_lshlrev_b32_e32 v91, 16, v2
	v_lshlrev_b32_e32 v90, 16, v6
	v_mov_b32_e32 v116, v90
	v_mov_b32_e32 v118, v91
	v_mul_f32_e32 v40, v40, v66
	v_mul_f32_e32 v46, v46, v67
	v_cvt_pk_bf16_f32 v136, v40, v46
	v_mov_b32_e32 v66, v180
	v_mov_b32_e32 v67, v181
	v_mul_f32_e32 v40, v68, v92
	v_mul_f32_e32 v46, v68, v93
	v_and_b32_e32 v93, 0xffff0000, v2
	v_mul_f32_e32 v2, v68, v126
	v_and_b32_e32 v92, 0xffff0000, v6
	v_mov_b32_e32 v117, v92
	v_mul_f32_e32 v40, v40, v66
	v_mul_f32_e32 v46, v46, v67
	v_cvt_pk_bf16_f32 v137, v40, v46
	v_mov_b32_e32 v66, v182
	v_mov_b32_e32 v67, v183
	v_mul_f32_e32 v40, v68, v94
	v_mul_f32_e32 v46, v68, v96
	v_mul_f32_e32 v40, v40, v66
	v_mul_f32_e32 v46, v46, v67
	v_cvt_pk_bf16_f32 v138, v40, v46
	v_mov_b32_e32 v66, v184
	v_mov_b32_e32 v67, v185
	v_mul_f32_e32 v40, v68, v50
	v_mul_f32_e32 v46, v68, v98
	v_mov_b32_e32 v98, v15
	v_mul_f32_e32 v40, v40, v66
	v_mul_f32_e32 v46, v46, v67
	v_cvt_pk_bf16_f32 v139, v40, v46
	v_mov_b32_e32 v66, v186
	v_mov_b32_e32 v67, v187
	v_mul_f32_e32 v40, v68, v95
	v_mul_f32_e32 v46, v68, v97
	v_pk_mul_f32 v[94:95], v[14:15], v[14:15]
	v_mul_f32_e32 v40, v40, v66
	v_mul_f32_e32 v46, v46, v67
	v_cvt_pk_bf16_f32 v140, v40, v46
	v_mov_b32_e32 v66, v188
	v_mov_b32_e32 v67, v189
	v_mul_f32_e32 v40, v68, v61
	v_mul_f32_e32 v46, v68, v122
	v_mul_f32_e32 v122, v92, v92
	v_pk_fma_f32 v[116:117], v[116:117], v[116:117], v[122:123] op_sel_hi:[1,1,0]
	v_mul_f32_e32 v40, v40, v66
	v_mul_f32_e32 v46, v46, v67
	v_cvt_pk_bf16_f32 v141, v40, v46
	v_mov_b32_e32 v66, v190
	v_mov_b32_e32 v67, v191
	v_mul_f32_e32 v40, v68, v51
	v_mul_f32_e32 v46, v68, v99
	v_mul_f32_e32 v40, v40, v66
	v_mul_f32_e32 v46, v46, v67
	v_cvt_pk_bf16_f32 v142, v40, v46
	v_mov_b32_e32 v50, v192
	v_mov_b32_e32 v51, v193
	v_mul_f32_e32 v40, v68, v41
	v_mul_f32_e32 v41, v68, v123
	v_mul_f32_e32 v46, v68, v102
	v_mul_f32_e32 v40, v40, v50
	v_mul_f32_e32 v41, v41, v51
	v_cvt_pk_bf16_f32 v143, v40, v41
	v_mov_b32_e32 v40, v194
	v_mov_b32_e32 v41, v195
	v_mul_f32_e32 v50, v68, v104
	v_mul_f32_e32 v40, v46, v40
	v_mul_f32_e32 v41, v50, v41
	v_cvt_pk_bf16_f32 v144, v40, v41
	v_mov_b32_e32 v40, v208
	v_mov_b32_e32 v41, v209
	v_mul_f32_e32 v46, v68, v103
	v_mul_f32_e32 v50, v68, v105
	v_mul_f32_e32 v40, v46, v40
	v_mul_f32_e32 v41, v50, v41
	v_cvt_pk_bf16_f32 v145, v40, v41
	v_mov_b32_e32 v40, v210
	v_mov_b32_e32 v41, v211
	v_mul_f32_e32 v46, v68, v106
	v_mul_f32_e32 v50, v68, v54
	v_lshlrev_b32_e32 v54, 16, v9
	v_mul_f32_e32 v40, v46, v40
	v_mul_f32_e32 v41, v50, v41
	v_cvt_pk_bf16_f32 v146, v40, v41
	v_mov_b32_e32 v40, v240
	v_mov_b32_e32 v41, v241
	v_mul_f32_e32 v46, v68, v107
	v_mul_f32_e32 v50, v68, v55
	v_lshlrev_b32_e32 v55, 16, v5
	v_mov_b32_e32 v110, v55
	v_mul_f32_e32 v40, v46, v40
	v_mul_f32_e32 v41, v50, v41
	v_cvt_pk_bf16_f32 v147, v40, v41
	v_mov_b32_e32 v40, v242
	v_mov_b32_e32 v41, v243
	v_mul_f32_e32 v46, v68, v112
	v_mul_f32_e32 v50, v68, v62
	v_mul_f32_e32 v40, v46, v40
	v_mul_f32_e32 v41, v50, v41
	v_cvt_pk_bf16_f32 v148, v40, v41
	global_load_dwordx2 v[40:41], v[36:37], off offset:328
	global_load_dwordx2 v[164:165], v[36:37], off offset:336
	global_load_dwordx2 v[166:167], v[36:37], off offset:344
	global_load_dwordx2 v[168:169], v[36:37], off offset:384
	global_load_dwordx2 v[170:171], v[36:37], off offset:392
	global_load_dwordx2 v[172:173], v[36:37], off offset:400
	global_load_dwordx2 v[174:175], v[36:37], off offset:408
	global_load_dwordx2 v[176:177], v[36:37], off offset:448
	global_load_dwordx2 v[178:179], v[36:37], off offset:456
	global_load_dwordx2 v[180:181], v[36:37], off offset:464
	global_load_dwordx2 v[182:183], v[36:37], off offset:472
	v_mul_f32_e32 v46, v68, v113
	v_mul_f32_e32 v50, v68, v63
	v_mov_b32_e32 v113, v85
	s_waitcnt vmcnt(0) lgkmcnt(0)
	v_mul_f32_e32 v40, v46, v40
	v_mul_f32_e32 v41, v50, v41
	v_cvt_pk_bf16_f32 v149, v40, v41
	v_mov_b32_e32 v40, v164
	v_mov_b32_e32 v41, v165
	v_mul_f32_e32 v46, v68, v114
	v_mul_f32_e32 v50, v68, v64
	v_mov_b32_e32 v114, v86
	v_mul_f32_e32 v40, v46, v40
	v_mul_f32_e32 v41, v50, v41
	v_cvt_pk_bf16_f32 v150, v40, v41
	v_mov_b32_e32 v40, v166
	v_mov_b32_e32 v41, v167
	v_mul_f32_e32 v46, v68, v115
	v_mul_f32_e32 v50, v68, v65
	v_mov_b32_e32 v115, v88
	v_mul_f32_e32 v40, v46, v40
	v_mul_f32_e32 v41, v50, v41
	v_cvt_pk_bf16_f32 v151, v40, v41
	v_mov_b32_e32 v40, v168
	v_mov_b32_e32 v41, v169
	v_mul_f32_e32 v46, v68, v120
	v_mul_f32_e32 v50, v68, v121
	v_mov_b32_e32 v120, v93
	v_mov_b32_e32 v121, v89
	v_pk_mul_f32 v[120:121], v[120:121], v[120:121]
	v_mul_f32_e32 v40, v46, v40
	v_mul_f32_e32 v41, v50, v41
	v_cvt_pk_bf16_f32 v152, v40, v41
	v_mov_b32_e32 v40, v170
	v_mov_b32_e32 v41, v171
	v_mul_f32_e32 v46, v68, v52
	v_mul_f32_e32 v50, v68, v53
	v_and_b32_e32 v53, 0xffff0000, v5
	v_and_b32_e32 v52, 0xffff0000, v9
	v_mov_b32_e32 v112, v53
	v_pk_mul_f32 v[112:113], v[112:113], v[112:113]
	v_mov_b32_e32 v126, v52
	v_mul_f32_e32 v40, v46, v40
	v_mul_f32_e32 v41, v50, v41
	v_cvt_pk_bf16_f32 v153, v40, v41
	v_mov_b32_e32 v40, v172
	v_mov_b32_e32 v41, v173
	v_mul_f32_e32 v46, v68, v48
	v_lshlrev_b64 v[50:51], 5, v[196:197]
	v_mul_f32_e32 v40, v46, v40
	v_mul_f32_e32 v41, v44, v41
	v_cvt_pk_bf16_f32 v154, v40, v41
	v_mov_b32_e32 v40, v174
	v_mov_b32_e32 v41, v175
	v_lshlrev_b32_e32 v46, 3, v58
	v_or_b32_e32 v50, v50, v46
	v_lshlrev_b32_e32 v44, 16, v32
	v_and_b32_e32 v32, 0xffff0000, v32
	v_mov_b32_e32 v163, v32
	v_mov_b32_e32 v161, v44
	v_mul_f32_e32 v40, v42, v40
	v_mul_f32_e32 v38, v38, v41
	v_cvt_pk_bf16_f32 v155, v40, v38
	v_mov_b32_e32 v40, v176
	v_mov_b32_e32 v41, v177
	v_mul_f32_e32 v38, v68, v49
	v_mul_f32_e32 v42, v68, v45
	v_lshl_add_u64 v[48:49], s[0:1], 0, v[0:1]
	v_mul_f32_e32 v0, v68, v47
	v_lshlrev_b32_e32 v45, 16, v10
	v_mov_b32_e32 v106, v45
	v_mul_f32_e32 v38, v38, v40
	v_mul_f32_e32 v40, v42, v41
	v_cvt_pk_bf16_f32 v156, v38, v40
	v_mov_b32_e32 v40, v178
	v_mov_b32_e32 v41, v179
	v_mul_f32_e32 v38, v68, v124
	v_mul_f32_e32 v42, v68, v125
	v_mov_b32_e32 v124, v54
	v_mul_f32_e32 v38, v38, v40
	v_mul_f32_e32 v40, v42, v41
	v_cvt_pk_bf16_f32 v157, v38, v40
	v_mov_b32_e32 v40, v180
	v_mov_b32_e32 v41, v181
	v_mul_f32_e32 v38, v68, v43
	v_and_b32_e32 v43, 0xffff0000, v11
	v_and_b32_e32 v42, 0xffff0000, v33
	v_mov_b32_e32 v109, v43
	v_pk_mul_f32 v[104:105], v[42:43], v[42:43]
	v_mul_f32_e32 v38, v38, v40
	v_mul_f32_e32 v39, v39, v41
	v_cvt_pk_bf16_f32 v158, v38, v39
	v_mov_b32_e32 v62, v182
	v_mov_b32_e32 v63, v183
	v_lshlrev_b64 v[36:37], 2, v[50:51]
	v_lshl_add_u64 v[74:75], s[46:47], 0, v[36:37]
	v_lshl_add_u64 v[78:79], s[48:49], 0, v[36:37]
	v_or_b32_e32 v36, 16, v36
	v_lshl_add_u64 v[76:77], s[46:47], 0, v[36:37]
	v_lshl_add_u64 v[80:81], s[48:49], 0, v[36:37]
	v_and_b32_e32 v37, 0xffff0000, v13
	v_and_b32_e32 v36, 0xffff0000, v35
	v_lshlrev_b32_e32 v39, 16, v12
	v_and_b32_e32 v35, 0xffff0000, v12
	v_lshlrev_b32_e32 v41, 16, v11
	v_lshlrev_b32_e32 v40, 16, v33
	v_and_b32_e32 v33, 0xffff0000, v10
	v_mov_b32_e32 v100, v37
	v_mov_b32_e32 v101, v35
	v_mov_b32_e32 v108, v33
	v_mov_b32_e32 v99, v39
	v_mov_b32_e32 v107, v41
	v_pk_mul_f32 v[100:101], v[100:101], v[100:101]
	v_pk_mul_f32 v[108:109], v[108:109], v[108:109]
	v_lshlrev_b32_e32 v38, 16, v34
	v_and_b32_e32 v34, 0xffff0000, v34
	v_pk_mul_f32 v[102:103], v[40:41], v[40:41]
	v_pk_fma_f32 v[98:99], v[98:99], v[98:99], v[100:101]
	v_pk_fma_f32 v[100:101], v[106:107], v[106:107], v[108:109]
	v_pk_fma_f32 v[108:109], v[118:119], v[118:119], v[120:121]
	v_mov_b32_e32 v127, v34
	v_pk_fma_f32 v[106:107], v[110:111], v[110:111], v[112:113]
	v_mov_b32_e32 v117, v102
	v_pk_add_f32 v[100:101], v[100:101], v[100:101] op_sel:[0,1] op_sel_hi:[1,0]
	v_pk_add_f32 v[102:103], v[108:109], v[108:109] op_sel:[0,1] op_sel_hi:[1,0]
	v_pk_mul_f32 v[122:123], v[126:127], v[126:127]
	v_pk_mul_f32 v[126:127], v[162:163], v[162:163]
	v_pk_add_f32 v[100:101], v[98:99], v[100:101] op_sel:[1,0] op_sel_hi:[0,1]
	v_pk_add_f32 v[102:103], v[106:107], v[102:103] op_sel:[1,0] op_sel_hi:[0,1]
	v_pk_mul_f32 v[96:97], v[36:37], v[36:37]
	v_mov_b32_e32 v125, v38
	v_pk_fma_f32 v[112:113], v[160:161], v[160:161], v[126:127]
	v_pk_add_f32 v[98:99], v[98:99], v[100:101]
	v_pk_add_f32 v[100:101], v[106:107], v[102:103]
	v_pk_fma_f32 v[110:111], v[124:125], v[124:125], v[122:123]
	v_mov_b32_e32 v101, v94
	v_mov_b32_e32 v99, v96
	v_pk_add_f32 v[94:95], v[100:101], v[98:99]
	v_or_b32_e32 v50, 16, v50
	v_mul_f32_e32 v2, v2, v63
	v_mul_f32_e32 v0, v0, v62
	v_cvt_pk_bf16_f32 v159, v0, v2
	global_load_dwordx4 v[62:65], v[48:49], off offset:128
	global_load_dwordx4 v[66:69], v[48:49], off offset:144
	global_load_dwordx4 v[70:73], v[48:49], off
	global_load_dwordx4 v[10:13], v[48:49], off offset:16
	global_load_dwordx4 v[6:9], v[76:77], off
	global_load_dwordx4 v[2:5], v[80:81], off
	s_nop 0
	global_load_dwordx4 v[74:77], v[74:75], off
	s_nop 0
	global_load_dwordx4 v[78:81], v[78:79], off
	v_mul_f32_e32 v0, v88, v88
	v_pk_fma_f32 v[114:115], v[114:115], v[114:115], v[0:1] op_sel_hi:[1,1,0]
	s_waitcnt vmcnt(0) lgkmcnt(0)
	v_mov_b32_e32 v106, v64
	v_mov_b32_e32 v115, v104
	v_pk_add_f32 v[104:105], v[116:117], v[114:115]
	v_mov_b32_e32 v98, v68
	v_pk_add_f32 v[104:105], v[112:113], v[104:105]
	v_mov_b32_e32 v99, v12
	v_pk_add_f32 v[102:103], v[110:111], v[104:105]
	v_mov_b32_e32 v107, v72
	v_pk_add_f32 v[94:95], v[94:95], v[102:103]
	v_mov_b32_e32 v102, v66
	v_pk_add_f32 v[94:95], v[94:95], v[94:95] op_sel:[0,1] op_sel_hi:[1,0]
	v_mov_b32_e32 v103, v10
	v_mov_b32_e32 v0, v94
	s_nop 1
	v_permlane32_swap_b32_e32 v94, v0
	v_add_f32_e32 v0, v94, v0
	v_fmamk_f32 v0, v0, 0x3c800000, v207
	v_mul_f32_e32 v47, 0x4b800000, v0
	v_cmp_gt_f32_e32 vcc, s87, v0
	v_mov_b32_e32 v110, v62
	v_mov_b32_e32 v111, v70
	v_cndmask_b32_e32 v0, v0, v47, vcc
	v_rsq_f32_e32 v0, v0
	v_mov_b32_e32 v70, v63
	v_mov_b32_e32 v72, v65
	v_mov_b32_e32 v10, v67
	v_mul_f32_e32 v47, 0x45800000, v0
	v_cndmask_b32_e32 v0, v0, v47, vcc
	v_pk_mul_f32 v[90:91], v[0:1], v[90:91] op_sel_hi:[0,1]
	v_pk_mul_f32 v[92:93], v[0:1], v[92:93] op_sel_hi:[0,1]
	v_pk_mul_f32 v[86:87], v[0:1], v[86:87] op_sel_hi:[0,1]
	v_pk_mul_f32 v[88:89], v[0:1], v[88:89] op_sel_hi:[0,1]
	v_pk_mul_f32 v[82:83], v[0:1], v[82:83] op_sel_hi:[0,1]
	v_pk_mul_f32 v[84:85], v[0:1], v[84:85] op_sel_hi:[0,1]
	v_pk_mul_f32 v[54:55], v[0:1], v[54:55] op_sel_hi:[0,1]
	v_pk_mul_f32 v[52:53], v[0:1], v[52:53] op_sel_hi:[0,1]
	v_mov_b32_e32 v12, v69
	v_mov_b32_e32 v100, v8
	v_mov_b32_e32 v101, v4
	v_mov_b32_e32 v104, v6
	v_mov_b32_e32 v105, v2
	v_mov_b32_e32 v108, v76
	v_mov_b32_e32 v109, v80
	v_mov_b32_e32 v112, v74
	v_mov_b32_e32 v113, v78
	v_mov_b32_e32 v114, v78
	v_mov_b32_e32 v115, v74
	v_mov_b32_e32 v74, v79
	v_mov_b32_e32 v78, v75
	v_mov_b32_e32 v62, v80
	v_mov_b32_e32 v63, v76
	v_mov_b32_e32 v76, v81
	v_mov_b32_e32 v80, v77
	v_mov_b32_e32 v64, v2
	v_mov_b32_e32 v65, v6
	v_mov_b32_e32 v6, v3
	v_mov_b32_e32 v2, v7
	v_mov_b32_e32 v66, v4
	v_mov_b32_e32 v67, v8
	v_mov_b32_e32 v8, v5
	v_pk_mul_f32 v[68:69], v[90:91], v[110:111]
	v_pk_mul_f32 v[70:71], v[92:93], v[70:71]
	v_pk_mul_f32 v[86:87], v[86:87], v[106:107]
	v_pk_mul_f32 v[72:73], v[88:89], v[72:73]
	v_pk_mul_f32 v[82:83], v[82:83], v[102:103]
	v_pk_mul_f32 v[10:11], v[84:85], v[10:11]
	v_pk_mul_f32 v[54:55], v[54:55], v[98:99]
	v_pk_mul_f32 v[12:13], v[52:53], v[12:13]
	v_mov_b32_e32 v4, v9
	v_pk_mul_f32 v[52:53], v[68:69], v[114:115]
	v_pk_mul_f32 v[68:69], v[68:69], v[112:113]
	v_pk_mul_f32 v[74:75], v[70:71], v[74:75]
	v_pk_mul_f32 v[70:71], v[70:71], v[78:79]
	v_pk_mul_f32 v[62:63], v[86:87], v[62:63]
	v_pk_mul_f32 v[78:79], v[86:87], v[108:109]
	v_pk_mul_f32 v[76:77], v[72:73], v[76:77]
	v_pk_mul_f32 v[72:73], v[72:73], v[80:81]
	v_pk_mul_f32 v[64:65], v[82:83], v[64:65]
	v_pk_mul_f32 v[6:7], v[10:11], v[6:7]
	v_pk_mul_f32 v[2:3], v[10:11], v[2:3]
	v_pk_mul_f32 v[10:11], v[54:55], v[66:67]
	v_pk_mul_f32 v[54:55], v[54:55], v[100:101]
	v_pk_mul_f32 v[8:9], v[12:13], v[8:9]
	v_lshlrev_b64 v[94:95], 2, v[50:51]
	v_pk_mul_f32 v[80:81], v[82:83], v[104:105]
	v_pk_mul_f32 v[4:5], v[12:13], v[4:5]
	v_sub_f32_e32 v12, v53, v52
	v_add_f32_e32 v13, v68, v69
	v_sub_f32_e32 v47, v75, v74
	v_add_f32_e32 v52, v70, v71
	v_sub_f32_e32 v53, v63, v62
	v_add_f32_e32 v61, v78, v79
	v_add_f32_e32 v63, v72, v73
	v_sub_f32_e32 v64, v65, v64
	v_sub_f32_e32 v6, v7, v6
	v_add_f32_e32 v7, v54, v55
	v_sub_f32_e32 v8, v9, v8
	v_lshl_add_u64 v[50:51], s[48:49], 0, v[94:95]
	v_sub_f32_e32 v62, v77, v76
	v_add_f32_e32 v65, v80, v81
	v_add_f32_e32 v2, v2, v3
	v_sub_f32_e32 v3, v11, v10
	v_add_f32_e32 v4, v4, v5
	v_mul_f32_e32 v5, 0x3dd53b94, v12
	v_mul_f32_e32 v9, 0x3dd53b94, v13
	v_mul_f32_e32 v10, 0x3dd53b94, v47
	v_mul_f32_e32 v11, 0x3dd53b94, v52
	v_mul_f32_e32 v12, 0x3dd53b94, v53
	v_mul_f32_e32 v13, 0x3dd53b94, v61
	v_mul_f32_e32 v52, 0x3dd53b94, v63
	v_mul_f32_e32 v53, 0x3dd53b94, v64
	v_mul_f32_e32 v6, 0x3dd53b94, v6
	v_mul_f32_e32 v7, 0x3dd53b94, v7
	v_mul_f32_e32 v8, 0x3dd53b94, v8
	v_lshl_add_u64 v[96:97], s[46:47], 0, v[94:95]
	v_mul_f32_e32 v47, 0x3dd53b94, v62
	v_mul_f32_e32 v54, 0x3dd53b94, v65
	v_mul_f32_e32 v2, 0x3dd53b94, v2
	v_mul_f32_e32 v3, 0x3dd53b94, v3
	v_mul_f32_e32 v4, 0x3dd53b94, v4
	v_cvt_pk_bf16_f32 v160, v5, v10
	v_cvt_pk_bf16_f32 v161, v12, v47
	v_cvt_pk_bf16_f32 v162, v53, v6
	v_cvt_pk_bf16_f32 v163, v3, v8
	v_cvt_pk_bf16_f32 v164, v9, v11
	v_cvt_pk_bf16_f32 v165, v13, v52
	v_cvt_pk_bf16_f32 v166, v54, v2
	v_cvt_pk_bf16_f32 v167, v7, v4
	global_load_dwordx4 v[6:9], v[48:49], off offset:192
	global_load_dwordx4 v[10:13], v[48:49], off offset:64
	s_nop 0
	global_load_dwordx4 v[50:53], v[50:51], off
	s_nop 0
	global_load_dwordx4 v[62:65], v[96:97], off
	v_or_b32_e32 v94, 16, v94
	v_lshl_add_u64 v[2:3], s[46:47], 0, v[94:95]
	v_lshl_add_u64 v[4:5], s[48:49], 0, v[94:95]
	global_load_dwordx4 v[66:69], v[48:49], off offset:208
	global_load_dwordx4 v[70:73], v[48:49], off offset:80
	global_load_dwordx4 v[74:77], v[4:5], off
	global_load_dwordx4 v[78:81], v[2:3], off
	v_mul_hi_i32 v2, v56, s81
	v_lshrrev_b32_e32 v3, 31, v2
	v_ashrrev_i32_e32 v2, 2, v2
	v_pk_mul_f32 v[44:45], v[0:1], v[44:45] op_sel_hi:[0,1]
	v_add_u32_e32 v3, v2, v3
	v_pk_mul_f32 v[32:33], v[0:1], v[32:33] op_sel_hi:[0,1]
	v_pk_mul_f32 v[40:41], v[0:1], v[40:41] op_sel_hi:[0,1]
	v_pk_mul_f32 v[42:43], v[0:1], v[42:43] op_sel_hi:[0,1]
	v_pk_mul_f32 v[38:39], v[0:1], v[38:39] op_sel_hi:[0,1]
	v_pk_mul_f32 v[34:35], v[0:1], v[34:35] op_sel_hi:[0,1]
	v_pk_mul_f32 v[14:15], v[0:1], v[14:15] op_sel_hi:[0,1]
	v_pk_mul_f32 v[36:37], v[0:1], v[36:37] op_sel_hi:[0,1]
	v_mul_lo_u32 v2, v3, 24
	v_sub_u32_e32 v2, v56, v2
	v_lshlrev_b32_e32 v5, 3, v2
	v_cmp_lt_i32_e32 vcc, 15, v2
	s_waitcnt vmcnt(0) lgkmcnt(0)
	v_mov_b32_e32 v48, v6
	v_mov_b32_e32 v49, v10
	v_mov_b32_e32 v54, v50
	v_mov_b32_e32 v55, v62
	v_mov_b32_e32 v10, v7
	v_mov_b32_e32 v6, v8
	v_mov_b32_e32 v7, v12
	v_mov_b32_e32 v12, v9
	v_mov_b32_e32 v8, v66
	v_mov_b32_e32 v9, v70
	v_mov_b32_e32 v70, v67
	v_mov_b32_e32 v66, v68
	v_mov_b32_e32 v67, v72
	v_mov_b32_e32 v72, v69
	v_pk_mul_f32 v[44:45], v[44:45], v[48:49]
	v_mov_b32_e32 v82, v62
	v_mov_b32_e32 v83, v50
	v_mov_b32_e32 v62, v51
	v_mov_b32_e32 v50, v63
	v_mov_b32_e32 v84, v52
	v_mov_b32_e32 v85, v64
	v_mov_b32_e32 v86, v64
	v_mov_b32_e32 v87, v52
	v_mov_b32_e32 v64, v53
	v_mov_b32_e32 v52, v65
	v_mov_b32_e32 v88, v74
	v_mov_b32_e32 v89, v78
	v_mov_b32_e32 v90, v78
	v_mov_b32_e32 v91, v74
	v_mov_b32_e32 v78, v75
	v_mov_b32_e32 v74, v79
	v_mov_b32_e32 v92, v76
	v_mov_b32_e32 v93, v80
	v_mov_b32_e32 v94, v80
	v_mov_b32_e32 v95, v76
	v_mov_b32_e32 v80, v77
	v_mov_b32_e32 v76, v81
	v_pk_mul_f32 v[10:11], v[32:33], v[10:11]
	v_pk_mul_f32 v[6:7], v[40:41], v[6:7]
	v_pk_mul_f32 v[12:13], v[42:43], v[12:13]
	v_pk_mul_f32 v[8:9], v[38:39], v[8:9]
	v_pk_mul_f32 v[32:33], v[34:35], v[70:71]
	v_pk_mul_f32 v[14:15], v[14:15], v[66:67]
	v_pk_mul_f32 v[34:35], v[36:37], v[72:73]
	v_pk_mul_f32 v[36:37], v[44:45], v[54:55]
	v_pk_mul_f32 v[38:39], v[44:45], v[82:83]
	v_pk_mul_f32 v[40:41], v[10:11], v[62:63]
	v_pk_mul_f32 v[10:11], v[10:11], v[50:51]
	v_pk_mul_f32 v[42:43], v[6:7], v[84:85]
	v_pk_mul_f32 v[6:7], v[6:7], v[86:87]
	v_pk_mul_f32 v[44:45], v[12:13], v[64:65]
	v_pk_mul_f32 v[12:13], v[12:13], v[52:53]
	v_pk_mul_f32 v[48:49], v[8:9], v[88:89]
	v_pk_mul_f32 v[8:9], v[8:9], v[90:91]
	v_pk_mul_f32 v[50:51], v[32:33], v[78:79]
	v_pk_mul_f32 v[32:33], v[32:33], v[74:75]
	v_pk_mul_f32 v[52:53], v[14:15], v[92:93]
	v_pk_mul_f32 v[14:15], v[14:15], v[94:95]
	v_pk_mul_f32 v[54:55], v[34:35], v[80:81]
	v_pk_mul_f32 v[34:35], v[34:35], v[76:77]
	v_sub_f32_e32 v0, v37, v36
	v_add_f32_e32 v4, v38, v39
	v_sub_f32_e32 v36, v41, v40
	v_add_f32_e32 v10, v10, v11
	v_sub_f32_e32 v11, v43, v42
	v_add_f32_e32 v6, v6, v7
	v_sub_f32_e32 v7, v45, v44
	v_add_f32_e32 v12, v12, v13
	v_sub_f32_e32 v13, v49, v48
	v_add_f32_e32 v8, v8, v9
	v_sub_f32_e32 v9, v51, v50
	v_add_f32_e32 v32, v32, v33
	v_sub_f32_e32 v33, v53, v52
	v_add_f32_e32 v14, v14, v15
	v_sub_f32_e32 v15, v55, v54
	v_add_f32_e32 v34, v34, v35
	v_mul_f32_e32 v0, 0x3dd53b94, v0
	v_mul_f32_e32 v4, 0x3dd53b94, v4
	v_mul_f32_e32 v35, 0x3dd53b94, v36
	v_mul_f32_e32 v10, 0x3dd53b94, v10
	v_mul_f32_e32 v11, 0x3dd53b94, v11
	v_mul_f32_e32 v6, 0x3dd53b94, v6
	v_mul_f32_e32 v7, 0x3dd53b94, v7
	v_mul_f32_e32 v12, 0x3dd53b94, v12
	v_mul_f32_e32 v13, 0x3dd53b94, v13
	v_mul_f32_e32 v8, 0x3dd53b94, v8
	v_mul_f32_e32 v9, 0x3dd53b94, v9
	v_mul_f32_e32 v32, 0x3dd53b94, v32
	v_mul_f32_e32 v33, 0x3dd53b94, v33
	v_mul_f32_e32 v14, 0x3dd53b94, v14
	v_mul_f32_e32 v15, 0x3dd53b94, v15
	v_mul_f32_e32 v34, 0x3dd53b94, v34
	v_cvt_pk_bf16_f32 v168, v0, v35
	v_cvt_pk_bf16_f32 v169, v11, v7
	v_cvt_pk_bf16_f32 v170, v13, v9
	v_cvt_pk_bf16_f32 v171, v33, v15
	v_cvt_pk_bf16_f32 v172, v4, v10
	v_cvt_pk_bf16_f32 v173, v6, v12
	v_cvt_pk_bf16_f32 v174, v8, v32
	v_cvt_pk_bf16_f32 v175, v14, v34
	s_and_saveexec_b64 s[0:1], vcc
	s_xor_b64 s[0:1], exec, s[0:1]
	v_lshl_add_u32 v0, v3, 6, v5
	v_sub_u32_e32 v0, 0x7f, v0
	s_andn2_saveexec_b64 s[0:1], s[0:1]
	v_lshl_or_b32 v0, v3, 11, s82
	v_add_u32_e32 v0, v0, v5
	s_or_b64 exec, exec, s[0:1]
	v_add_u32_e32 v2, 0x200, v56
	v_mul_hi_i32 v4, v2, s81
	v_lshrrev_b32_e32 v6, 31, v4
	v_ashrrev_i32_e32 v4, 2, v4
	v_add_u32_e32 v6, v4, v6
	v_mul_lo_u32 v4, v6, 24
	v_sub_u32_e32 v2, v2, v4
	v_lshlrev_b32_e32 v7, 3, v2
	v_cmp_lt_i32_e32 vcc, 15, v2
	s_and_saveexec_b64 s[0:1], vcc
	s_xor_b64 s[0:1], exec, s[0:1]
	v_lshl_add_u32 v2, v6, 6, v7
	v_sub_u32_e32 v2, 0x7f, v2
	s_andn2_saveexec_b64 s[0:1], s[0:1]
	v_lshl_or_b32 v2, v6, 11, s82
	v_add_u32_e32 v2, v2, v7
	s_or_b64 exec, exec, s[0:1]
	v_add_u32_e32 v4, 0x400, v56
	v_mul_hi_i32 v8, v4, s81
	v_lshrrev_b32_e32 v9, 31, v8
	v_ashrrev_i32_e32 v8, 2, v8
	v_add_u32_e32 v8, v8, v9
	v_mul_lo_u32 v9, v8, 24
	v_sub_u32_e32 v4, v4, v9
	v_lshlrev_b32_e32 v9, 3, v4
	v_cmp_lt_i32_e32 vcc, 15, v4
	s_and_saveexec_b64 s[0:1], vcc
	s_xor_b64 s[0:1], exec, s[0:1]
	v_lshl_add_u32 v4, v8, 6, v9
	v_sub_u32_e32 v4, 0x7f, v4
	s_andn2_saveexec_b64 s[0:1], s[0:1]
	v_lshl_or_b32 v4, v8, 11, s82
	v_add_u32_e32 v4, v4, v9
	s_or_b64 exec, exec, s[0:1]
	v_mul_lo_u32 v6, v6, s84
	v_add_lshl_u32 v224, v6, v7, 1
	v_not_b32_e32 v6, v0
	v_mov_b32_e32 v7, v1
	v_lshlrev_b64 v[14:15], 1, v[0:1]
	v_lshlrev_b64 v[44:45], 1, v[6:7]
	v_lshl_add_u64 v[10:11], s[4:5], 0, v[14:15]
	v_lshl_add_u64 v[12:13], s[66:67], 0, v[44:45]
	v_cmp_gt_i32_e32 vcc, 0, v0
	v_mul_lo_u32 v3, v3, s84
	v_add_lshl_u32 v225, v3, v5, 1
	v_cndmask_b32_e32 v11, v11, v13, vcc
	v_cndmask_b32_e32 v10, v10, v12, vcc
	global_load_dwordx4 v[32:35], v[10:11], off
	v_mov_b32_e32 v3, v1
	v_not_b32_e32 v10, v2
	v_mov_b32_e32 v11, v1
	v_lshlrev_b64 v[62:63], 1, v[2:3]
	v_lshlrev_b64 v[64:65], 1, v[10:11]
	v_lshl_add_u64 v[12:13], s[4:5], 0, v[62:63]
	v_lshl_add_u64 v[36:37], s[66:67], 0, v[64:65]
	v_cmp_gt_i32_e64 s[36:37], 0, v2
	v_mov_b32_e32 v5, v1
	v_mul_lo_u32 v8, v8, s84
	v_cndmask_b32_e64 v13, v13, v37, s[36:37]
	v_cndmask_b32_e64 v12, v12, v36, s[36:37]
	global_load_dwordx4 v[36:39], v[12:13], off
	v_not_b32_e32 v12, v4
	v_mov_b32_e32 v13, v1
	v_lshlrev_b64 v[66:67], 1, v[4:5]
	v_lshlrev_b64 v[68:69], 1, v[12:13]
	v_add_lshl_u32 v199, v8, v9, 1
	v_ashrrev_i32_e32 v8, 3, v56
	v_lshl_add_u64 v[40:41], s[4:5], 0, v[66:67]
	v_lshl_add_u64 v[42:43], s[66:67], 0, v[68:69]
	v_cmp_gt_i32_e64 s[38:39], 0, v4
	v_add_u32_e32 v48, s82, v8
	v_lshlrev_b32_e32 v9, 4, v56
	v_cndmask_b32_e64 v41, v41, v43, s[38:39]
	v_cndmask_b32_e64 v40, v40, v42, s[38:39]
	global_load_dwordx4 v[40:43], v[40:41], off
	v_and_b32_e32 v70, 0x70, v9
	v_mov_b32_e32 v71, v1
	v_ashrrev_i32_e32 v49, 31, v48
	v_lshl_add_u64 v[52:53], s[56:57], 0, v[70:71]
	v_lshlrev_b64 v[72:73], 15, v[48:49]
	v_lshl_add_u64 v[48:49], v[52:53], 0, v[72:73]
	v_lshl_add_u64 v[74:75], v[72:73], 0, s[22:23]
	global_load_dwordx4 v[48:51], v[48:49], off
	v_lshl_add_u64 v[52:53], v[52:53], 0, v[74:75]
	global_load_dwordx4 v[52:55], v[52:53], off
	v_add_u32_e32 v9, 0, v225
	s_movk_i32 s0, 0x88
	v_lshl_add_u64 v[14:15], s[30:31], 0, v[14:15]
	s_waitcnt vmcnt(0) lgkmcnt(0)
	ds_write_b128 v9, v[32:35]
	v_add_u32_e32 v9, 0, v224
	v_lshl_add_u64 v[32:33], s[50:51], 0, v[44:45]
	v_cndmask_b32_e32 v15, v15, v33, vcc
	v_cndmask_b32_e32 v14, v14, v32, vcc
	v_lshl_add_u64 v[32:33], s[50:51], 0, v[64:65]
	ds_write_b128 v9, v[36:39]
	v_add_u32_e32 v9, 0, v199
	ds_write_b128 v9, v[40:43]
	v_mul_lo_u32 v9, v8, s0
	v_add3_u32 v233, 0, v70, v9
	v_add_u32_e32 v9, 0xc800, v233
	v_cmp_lt_i32_e64 s[0:1], 3, v60
	ds_write2_b64 v9, v[48:49], v[50:51] offset1:1
	v_add_u32_e32 v9, 0xea00, v233
	ds_write2_b64 v9, v[52:53], v[54:55] offset1:1
	global_load_dwordx4 v[176:179], v[14:15], off
	v_lshl_add_u64 v[14:15], s[30:31], 0, v[62:63]
	v_cndmask_b32_e64 v15, v15, v33, s[36:37]
	v_cndmask_b32_e64 v14, v14, v32, s[36:37]
	global_load_dwordx4 v[180:183], v[14:15], off
	v_lshl_add_u64 v[14:15], s[30:31], 0, v[66:67]
	v_lshl_add_u64 v[32:33], s[50:51], 0, v[68:69]
	v_cndmask_b32_e64 v15, v15, v33, s[38:39]
	v_cndmask_b32_e64 v14, v14, v32, s[38:39]
	global_load_dwordx4 v[184:187], v[14:15], off
	v_lshl_add_u64 v[14:15], s[44:45], 0, v[70:71]
	v_lshl_add_u64 v[32:33], v[14:15], 0, v[72:73]
	v_lshl_add_u64 v[14:15], v[14:15], 0, v[74:75]
	v_lshl_add_u64 v[32:33], v[32:33], 0, s[74:75]
	v_lshl_add_u64 v[14:15], v[14:15], 0, s[74:75]
	global_load_dwordx4 v[188:191], v[32:33], off
	global_load_dwordx4 v[192:195], v[14:15], off
	s_and_saveexec_b64 s[78:79], s[0:1]
	s_setprio 1
	s_or_b64 exec, exec, s[78:79]
	s_movk_i32 s0, 0x190
	v_mad_u32_u24 v9, v57, s0, 0
	v_mul_i32_i24_e32 v14, 0xfffffef8, v57
	v_lshl_add_u32 v236, v58, 4, v9
	v_add3_u32 v237, v9, v14, v46
	v_ashrrev_i32_e32 v9, 31, v8
	v_lshlrev_b64 v[14:15], 15, v[8:9]
	v_and_b32_e32 v9, 7, v56
	v_add_u32_e32 v8, s69, v8
	v_lshlrev_b32_e32 v32, 4, v9
	v_ashrrev_i32_e32 v9, 31, v8
	v_lshl_add_u64 v[14:15], s[62:63], 0, v[14:15]
	v_mov_b32_e32 v33, v1
	v_lshlrev_b64 v[8:9], 15, v[8:9]
	v_lshl_add_u64 v[200:201], v[14:15], 0, v[32:33]
	v_lshl_add_u64 v[8:9], s[60:61], 0, v[8:9]
	v_mov_b32_e32 v14, v1
	v_mov_b32_e32 v15, v1
	s_lshl_b32 s92, s6, 2
	v_or_b32_e32 v235, 31, v59
	v_lshlrev_b32_e32 v234, 2, v58
	v_lshl_add_u64 v[202:203], v[8:9], 0, v[32:33]
	v_lshl_add_u64 v[204:205], v[4:5], 1, s[70:71]
	v_lshl_add_u64 v[214:215], v[2:3], 1, s[70:71]
	v_lshl_add_u64 v[216:217], v[0:1], 1, s[70:71]
	v_lshl_add_u64 v[218:219], v[12:13], 1, s[72:73]
	v_lshl_add_u64 v[220:221], v[10:11], 1, s[72:73]
	v_lshl_add_u64 v[222:223], v[6:7], 1, s[72:73]
	v_mov_b32_e32 v0, v1
	v_mov_b32_e32 v2, v1
	v_mov_b32_e32 v3, v1
	v_mov_b32_e32 v4, v1
	v_mov_b32_e32 v5, v1
	v_mov_b32_e32 v6, v1
	v_mov_b32_e32 v7, v1
	v_mov_b32_e32 v8, v1
	v_mov_b32_e32 v9, v1
	v_mov_b32_e32 v10, v1
	v_mov_b32_e32 v11, v1
	v_mov_b32_e32 v12, v1
	v_mov_b32_e32 v13, v1
	v_mov_b64_e32 v[46:47], v[14:15]
	v_mov_b64_e32 v[62:63], v[14:15]
	v_mov_b64_e32 v[78:79], v[14:15]
	v_mov_b64_e32 v[94:95], v[14:15]
	s_xor_b64 s[78:79], s[76:77], -1
	s_mov_b32 s7, 2
	s_add_i32 s6, s92, 4
	s_addk_i32 s68, 0x100
	s_mov_b32 s85, 0
	v_mov_b32_e32 v238, 0
	v_mov_b64_e32 v[44:45], v[12:13]
	v_mov_b64_e32 v[42:43], v[10:11]
	v_mov_b64_e32 v[40:41], v[8:9]
	v_mov_b64_e32 v[38:39], v[6:7]
	v_mov_b64_e32 v[36:37], v[4:5]
	v_mov_b64_e32 v[34:35], v[2:3]
	v_mov_b64_e32 v[32:33], v[0:1]
	v_mov_b64_e32 v[60:61], v[12:13]
	v_mov_b64_e32 v[58:59], v[10:11]
	v_mov_b64_e32 v[56:57], v[8:9]
	v_mov_b64_e32 v[54:55], v[6:7]
	v_mov_b64_e32 v[52:53], v[4:5]
	v_mov_b64_e32 v[50:51], v[2:3]
	v_mov_b64_e32 v[48:49], v[0:1]
	v_mov_b64_e32 v[76:77], v[12:13]
	v_mov_b64_e32 v[74:75], v[10:11]
	v_mov_b64_e32 v[72:73], v[8:9]
	v_mov_b64_e32 v[70:71], v[6:7]
	v_mov_b64_e32 v[68:69], v[4:5]
	v_mov_b64_e32 v[66:67], v[2:3]
	v_mov_b64_e32 v[64:65], v[0:1]
	v_mov_b64_e32 v[92:93], v[12:13]
	v_mov_b64_e32 v[90:91], v[10:11]
	v_mov_b64_e32 v[88:89], v[8:9]
	v_mov_b64_e32 v[86:87], v[6:7]
	v_mov_b64_e32 v[84:85], v[4:5]
	v_mov_b64_e32 v[82:83], v[2:3]
	v_mov_b64_e32 v[80:81], v[0:1]
	v_lshl_add_u64 v[2:3], s[8:9], 0, v[216:217]
	v_lshl_add_u64 v[4:5], s[8:9], 0, v[222:223]
	v_cndmask_b32_e32 v217, v3, v5, vcc
	v_cndmask_b32_e32 v216, v2, v4, vcc
	v_lshl_add_u64 v[2:3], s[8:9], 0, v[214:215]
	v_lshl_add_u64 v[4:5], s[8:9], 0, v[220:221]
	v_cndmask_b32_e64 v215, v3, v5, s[36:37]
	v_cndmask_b32_e64 v214, v2, v4, s[36:37]
	v_lshl_add_u64 v[2:3], s[8:9], 0, v[204:205]
	v_lshl_add_u64 v[4:5], s[8:9], 0, v[218:219]
	v_cndmask_b32_e64 v205, v3, v5, s[38:39]
	v_cndmask_b32_e64 v204, v2, v4, s[38:39]
	v_mov_b32_e32 v2, s24
	v_mov_b32_e32 v3, s25
	v_mov_b32_e32 v4, s26
	v_mov_b32_e32 v5, s27
	v_cndmask_b32_e32 v222, v2, v4, vcc
	v_cndmask_b32_e32 v223, v3, v5, vcc
	v_cndmask_b32_e64 v220, v2, v4, s[36:37]
	v_cndmask_b32_e64 v221, v3, v5, s[36:37]
	v_cndmask_b32_e64 v218, v2, v4, s[38:39]
	v_cndmask_b32_e64 v219, v3, v5, s[38:39]
	v_lshl_add_u64 v[200:201], s[8:9], 0, v[200:201]
	v_lshl_add_u64 v[202:203], s[8:9], 0, v[202:203]
	s_branch .LBB0_398

.LBB0_472:
	v_readlane_b32 s10, v254, 32
	s_cmp_gt_i32 s62, 15
	s_mov_b64 s[0:1], -1
	v_readlane_b32 s11, v254, 33
	s_cbranch_scc0 .LBB0_478
	s_cmp_lt_u32 s62, 32
	s_cbranch_scc1 .LBB0_475
	s_lshl_b32 s13, s61, 8
	v_add_u32_e32 v150, s13, v139
	v_ashrrev_i32_e32 v151, 31, v150
	v_lshl_add_u64 v[148:149], v[150:151], 2, s[10:11]
	global_load_dword v0, v[148:149], off
	s_lshl_b32 s0, s62, 8
	s_add_i32 s54, s0, 0xffffe000
	v_lshlrev_b64 v[150:151], 13, v[150:151]
	s_mov_b64 s[28:29], s[78:79]
	v_lshl_add_u64 v[150:151], s[28:29], 0, v[150:151]
	s_waitcnt vmcnt(0) lgkmcnt(0)
	v_fmamk_f32 v0, v0, 0x3a000000, v207
	v_cmp_gt_f32_e32 vcc, s87, v0
	v_mul_f32_e32 v148, 0x4b800000, v0
	s_nop 0
	v_cndmask_b32_e32 v0, v0, v148, vcc
	v_rsq_f32_e32 v0, v0
	s_nop 0
	v_mul_f32_e32 v148, 0x45800000, v0
	v_cndmask_b32_e32 v148, v0, v148, vcc
	v_pk_mul_f32 v[156:157], v[126:127], v[148:149] op_sel_hi:[1,0]
	v_pk_mul_f32 v[154:155], v[128:129], v[148:149] op_sel_hi:[1,0]
	v_mul_f32_e32 v0, 0xbfb8aa3b, v156
	v_exp_f32_e32 v0, v0
	v_pk_mul_f32 v[152:153], v[120:121], v[148:149] op_sel_hi:[1,0]
	v_pk_mul_f32 v[158:159], v[118:119], v[148:149] op_sel_hi:[1,0]
	v_add_f32_e32 v0, 1.0, v0
	v_div_scale_f32 v149, s[0:1], v0, v0, v156
	v_rcp_f32_e32 v160, v149
	s_nop 0
	v_fma_f32 v161, -v149, v160, 1.0
	v_fmac_f32_e32 v160, v161, v160
	v_div_scale_f32 v161, vcc, v156, v0, v156
	v_mul_f32_e32 v162, v161, v160
	v_fma_f32 v163, -v149, v162, v161
	v_fmac_f32_e32 v162, v163, v160
	v_fma_f32 v149, -v149, v162, v161
	v_div_fmas_f32 v149, v149, v160, v162
	v_div_fixup_f32 v0, v149, v0, v156
	v_mul_f32_e32 v149, 0xbfb8aa3b, v158
	v_exp_f32_e32 v149, v149
	s_nop 0
	v_add_f32_e32 v149, 1.0, v149
	v_div_scale_f32 v156, s[0:1], v149, v149, v158
	v_rcp_f32_e32 v160, v156
	s_nop 0
	v_fma_f32 v161, -v156, v160, 1.0
	v_fmac_f32_e32 v160, v161, v160
	v_div_scale_f32 v161, vcc, v158, v149, v158
	v_mul_f32_e32 v162, v161, v160
	v_fma_f32 v163, -v156, v162, v161
	v_fmac_f32_e32 v162, v163, v160
	v_fma_f32 v156, -v156, v162, v161
	v_div_fmas_f32 v156, v156, v160, v162
	v_div_fixup_f32 v149, v156, v149, v158
	v_mul_f32_e32 v156, 0xbfb8aa3b, v157
	v_exp_f32_e32 v156, v156
	s_nop 0
	v_add_f32_e32 v156, 1.0, v156
	v_div_scale_f32 v158, s[0:1], v156, v156, v157
	v_rcp_f32_e32 v160, v158
	s_nop 0
	v_fma_f32 v161, -v158, v160, 1.0
	v_fmac_f32_e32 v160, v161, v160
	v_div_scale_f32 v161, vcc, v157, v156, v157
	v_mul_f32_e32 v162, v161, v160
	v_fma_f32 v163, -v158, v162, v161
	v_fmac_f32_e32 v162, v163, v160
	v_fma_f32 v158, -v158, v162, v161
	v_div_fmas_f32 v158, v158, v160, v162
	v_div_fixup_f32 v156, v158, v156, v157
	v_mul_f32_e32 v157, 0xbfb8aa3b, v159
	v_exp_f32_e32 v157, v157
	s_nop 0
	v_add_f32_e32 v157, 1.0, v157
	v_div_scale_f32 v158, s[0:1], v157, v157, v159
	v_rcp_f32_e32 v160, v158
	s_nop 0
	v_fma_f32 v161, -v158, v160, 1.0
	v_fmac_f32_e32 v160, v161, v160
	v_div_scale_f32 v161, vcc, v159, v157, v159
	v_mul_f32_e32 v162, v161, v160
	v_fma_f32 v163, -v158, v162, v161
	v_fmac_f32_e32 v162, v163, v160
	v_fma_f32 v158, -v158, v162, v161
	v_div_fmas_f32 v158, v158, v160, v162
	v_div_fixup_f32 v157, v158, v157, v159
	v_mul_f32_e32 v158, 0xbfb8aa3b, v154
	v_exp_f32_e32 v158, v158
	s_nop 0
	v_add_f32_e32 v158, 1.0, v158
	v_div_scale_f32 v159, s[0:1], v158, v158, v154
	v_rcp_f32_e32 v160, v159
	s_nop 0
	v_fma_f32 v161, -v159, v160, 1.0
	v_fmac_f32_e32 v160, v161, v160
	v_div_scale_f32 v161, vcc, v154, v158, v154
	v_mul_f32_e32 v162, v161, v160
	v_fma_f32 v163, -v159, v162, v161
	v_fmac_f32_e32 v162, v163, v160
	v_fma_f32 v159, -v159, v162, v161
	v_div_fmas_f32 v159, v159, v160, v162
	v_div_fixup_f32 v154, v159, v158, v154
	v_mul_f32_e32 v158, 0xbfb8aa3b, v152
	v_exp_f32_e32 v158, v158
	s_nop 0
	v_add_f32_e32 v158, 1.0, v158
	v_div_scale_f32 v159, s[0:1], v158, v158, v152
	v_rcp_f32_e32 v160, v159
	s_nop 0
	v_fma_f32 v161, -v159, v160, 1.0
	v_fmac_f32_e32 v160, v161, v160
	v_div_scale_f32 v161, vcc, v152, v158, v152
	v_mul_f32_e32 v162, v161, v160
	v_fma_f32 v163, -v159, v162, v161
	v_fmac_f32_e32 v162, v163, v160
	v_fma_f32 v159, -v159, v162, v161
	v_div_fmas_f32 v159, v159, v160, v162
	v_div_fixup_f32 v158, v159, v158, v152
	v_mul_f32_e32 v152, 0xbfb8aa3b, v155
	v_exp_f32_e32 v152, v152
	s_nop 0
	v_add_f32_e32 v152, 1.0, v152
	v_div_scale_f32 v159, s[0:1], v152, v152, v155
	v_rcp_f32_e32 v160, v159
	s_nop 0
	v_fma_f32 v161, -v159, v160, 1.0
	v_fmac_f32_e32 v160, v161, v160
	v_div_scale_f32 v161, vcc, v155, v152, v155
	v_mul_f32_e32 v162, v161, v160
	v_fma_f32 v163, -v159, v162, v161
	v_fmac_f32_e32 v162, v163, v160
	v_fma_f32 v159, -v159, v162, v161
	v_div_fmas_f32 v159, v159, v160, v162
	v_div_fixup_f32 v155, v159, v152, v155
	v_mul_f32_e32 v152, 0xbfb8aa3b, v153
	v_exp_f32_e32 v152, v152
	s_nop 0
	v_add_f32_e32 v152, 1.0, v152
	v_div_scale_f32 v159, s[0:1], v152, v152, v153
	v_rcp_f32_e32 v160, v159
	s_lshl_b64 s[0:1], s[54:55], 1
	v_lshl_add_u64 v[150:151], v[150:151], 0, s[0:1]
	s_mov_b32 s54, 0x34000
	v_fma_f32 v161, -v159, v160, 1.0
	v_fmac_f32_e32 v160, v161, v160
	v_div_scale_f32 v161, vcc, v153, v152, v153
	v_mul_f32_e32 v162, v161, v160
	v_fma_f32 v163, -v159, v162, v161
	v_fmac_f32_e32 v162, v163, v160
	v_fma_f32 v159, -v159, v162, v161
	v_div_fmas_f32 v159, v159, v160, v162
	v_div_fixup_f32 v159, v159, v152, v153
	v_cvt_pk_bf16_f32 v152, v0, v156
	v_cvt_pk_bf16_f32 v153, v154, v155
	v_cvt_pk_bf16_f32 v154, v149, v157
	v_pk_mul_f32 v[156:157], v[122:123], v[148:149] op_sel_hi:[1,0]
	v_cvt_pk_bf16_f32 v155, v158, v159
	v_lshlrev_b32_e32 v0, 1, v138
	v_mul_f32_e32 v158, 0xbfb8aa3b, v156
	v_exp_f32_e32 v158, v158
	v_lshl_add_u64 v[150:151], v[150:151], 0, v[0:1]
	global_store_dwordx4 v[150:151], v[152:155], off
	v_add_f32_e32 v158, 1.0, v158
	v_div_scale_f32 v159, s[6:7], v158, v158, v156
	v_rcp_f32_e32 v160, v159
	v_pk_mul_f32 v[154:155], v[124:125], v[148:149] op_sel_hi:[1,0]
	v_pk_mul_f32 v[152:153], v[116:117], v[148:149] op_sel_hi:[1,0]
	v_pk_mul_f32 v[148:149], v[114:115], v[148:149] op_sel_hi:[1,0]
	v_fma_f32 v161, -v159, v160, 1.0
	v_fmac_f32_e32 v160, v161, v160
	v_div_scale_f32 v161, vcc, v156, v158, v156
	v_mul_f32_e32 v162, v161, v160
	v_fma_f32 v163, -v159, v162, v161
	v_fmac_f32_e32 v162, v163, v160
	v_fma_f32 v159, -v159, v162, v161
	v_div_fmas_f32 v159, v159, v160, v162
	v_div_fixup_f32 v156, v159, v158, v156
	v_mul_f32_e32 v158, 0xbfb8aa3b, v148
	v_exp_f32_e32 v158, v158
	s_nop 0
	v_add_f32_e32 v158, 1.0, v158
	v_div_scale_f32 v159, s[6:7], v158, v158, v148
	v_rcp_f32_e32 v160, v159
	s_nop 0
	v_fma_f32 v161, -v159, v160, 1.0
	v_fmac_f32_e32 v160, v161, v160
	v_div_scale_f32 v161, vcc, v148, v158, v148
	v_mul_f32_e32 v162, v161, v160
	v_fma_f32 v163, -v159, v162, v161
	v_fmac_f32_e32 v162, v163, v160
	v_fma_f32 v159, -v159, v162, v161
	v_div_fmas_f32 v159, v159, v160, v162
	v_div_fixup_f32 v148, v159, v158, v148
	v_mul_f32_e32 v158, 0xbfb8aa3b, v157
	v_exp_f32_e32 v158, v158
	s_nop 0
	v_add_f32_e32 v158, 1.0, v158
	v_div_scale_f32 v159, s[6:7], v158, v158, v157
	v_rcp_f32_e32 v160, v159
	s_nop 0
	v_fma_f32 v161, -v159, v160, 1.0
	v_fmac_f32_e32 v160, v161, v160
	v_div_scale_f32 v161, vcc, v157, v158, v157
	v_mul_f32_e32 v162, v161, v160
	v_fma_f32 v163, -v159, v162, v161
	v_fmac_f32_e32 v162, v163, v160
	v_fma_f32 v159, -v159, v162, v161
	v_div_fmas_f32 v159, v159, v160, v162
	v_div_fixup_f32 v157, v159, v158, v157
	v_mul_f32_e32 v158, 0xbfb8aa3b, v149
	v_exp_f32_e32 v158, v158
	s_nop 0
	v_add_f32_e32 v158, 1.0, v158
	v_div_scale_f32 v159, s[6:7], v158, v158, v149
	v_rcp_f32_e32 v160, v159
	s_nop 0
	v_fma_f32 v161, -v159, v160, 1.0
	v_fmac_f32_e32 v160, v161, v160
	v_div_scale_f32 v161, vcc, v149, v158, v149
	v_mul_f32_e32 v162, v161, v160
	v_fma_f32 v163, -v159, v162, v161
	v_fmac_f32_e32 v162, v163, v160
	v_fma_f32 v159, -v159, v162, v161
	v_div_fmas_f32 v159, v159, v160, v162
	v_div_fixup_f32 v149, v159, v158, v149
	v_mul_f32_e32 v158, 0xbfb8aa3b, v154
	v_exp_f32_e32 v158, v158
	s_nop 0
	v_add_f32_e32 v158, 1.0, v158
	v_div_scale_f32 v159, s[6:7], v158, v158, v154
	v_rcp_f32_e32 v160, v159
	s_nop 0
	v_fma_f32 v161, -v159, v160, 1.0
	v_fmac_f32_e32 v160, v161, v160
	v_div_scale_f32 v161, vcc, v154, v158, v154
	v_mul_f32_e32 v162, v161, v160
	v_fma_f32 v163, -v159, v162, v161
	v_fmac_f32_e32 v162, v163, v160
	v_fma_f32 v159, -v159, v162, v161
	v_div_fmas_f32 v159, v159, v160, v162
	v_div_fixup_f32 v154, v159, v158, v154
	v_mul_f32_e32 v158, 0xbfb8aa3b, v152
	v_exp_f32_e32 v158, v158
	s_nop 0
	v_add_f32_e32 v158, 1.0, v158
	v_div_scale_f32 v159, s[6:7], v158, v158, v152
	v_rcp_f32_e32 v160, v159
	s_nop 0
	v_fma_f32 v161, -v159, v160, 1.0
	v_fmac_f32_e32 v160, v161, v160
	v_div_scale_f32 v161, vcc, v152, v158, v152
	v_mul_f32_e32 v162, v161, v160
	v_fma_f32 v163, -v159, v162, v161
	v_fmac_f32_e32 v162, v163, v160
	v_fma_f32 v159, -v159, v162, v161
	v_div_fmas_f32 v159, v159, v160, v162
	v_div_fixup_f32 v158, v159, v158, v152
	v_mul_f32_e32 v152, 0xbfb8aa3b, v155
	v_exp_f32_e32 v152, v152
	s_nop 0
	v_add_f32_e32 v152, 1.0, v152
	v_div_scale_f32 v159, s[6:7], v152, v152, v155
	v_rcp_f32_e32 v160, v159
	s_nop 0
	v_fma_f32 v161, -v159, v160, 1.0
	v_fmac_f32_e32 v160, v161, v160
	v_div_scale_f32 v161, vcc, v155, v152, v155
	v_mul_f32_e32 v162, v161, v160
	v_fma_f32 v163, -v159, v162, v161
	v_fmac_f32_e32 v162, v163, v160
	v_fma_f32 v159, -v159, v162, v161
	v_div_fmas_f32 v159, v159, v160, v162
	v_div_fixup_f32 v155, v159, v152, v155
	v_mul_f32_e32 v152, 0xbfb8aa3b, v153
	v_exp_f32_e32 v152, v152
	s_nop 0
	v_add_f32_e32 v152, 1.0, v152
	v_div_scale_f32 v159, s[6:7], v152, v152, v153
	v_rcp_f32_e32 v160, v159
	s_nop 0
	v_fma_f32 v161, -v159, v160, 1.0
	v_fmac_f32_e32 v160, v161, v160
	v_div_scale_f32 v161, vcc, v153, v152, v153
	v_mul_f32_e32 v162, v161, v160
	v_fma_f32 v163, -v159, v162, v161
	v_fmac_f32_e32 v162, v163, v160
	v_fma_f32 v159, -v159, v162, v161
	v_div_fmas_f32 v159, v159, v160, v162
	v_div_fixup_f32 v159, v159, v152, v153
	v_cvt_pk_bf16_f32 v152, v156, v157
	v_cvt_pk_bf16_f32 v153, v154, v155
	v_cvt_pk_bf16_f32 v154, v148, v149
	v_cvt_pk_bf16_f32 v155, v158, v159
	global_store_dwordx4 v[150:151], v[152:155], off offset:256
	v_add_u32_e32 v150, s13, v165
	v_ashrrev_i32_e32 v151, 31, v150
	v_lshl_add_u64 v[148:149], v[150:151], 2, s[10:11]
	global_load_dword v148, v[148:149], off
	v_lshlrev_b64 v[150:151], 13, v[150:151]
	v_lshl_add_u64 v[150:151], s[28:29], 0, v[150:151]
	v_lshl_add_u64 v[150:151], v[150:151], 0, s[0:1]
	v_lshl_add_u64 v[150:151], v[150:151], 0, v[0:1]
	s_waitcnt vmcnt(0) lgkmcnt(0)
	v_fmamk_f32 v148, v148, 0x3a000000, v207
	v_cmp_gt_f32_e32 vcc, s87, v148
	v_mul_f32_e32 v149, 0x4b800000, v148
	s_nop 0
	v_cndmask_b32_e32 v148, v148, v149, vcc
	v_rsq_f32_e32 v148, v148
	s_nop 0
	v_mul_f32_e32 v149, 0x45800000, v148
	v_cndmask_b32_e32 v148, v148, v149, vcc
	v_pk_mul_f32 v[156:157], v[110:111], v[148:149] op_sel_hi:[1,0]
	v_pk_mul_f32 v[154:155], v[112:113], v[148:149] op_sel_hi:[1,0]
	v_pk_mul_f32 v[152:153], v[104:105], v[148:149] op_sel_hi:[1,0]
	v_pk_mul_f32 v[158:159], v[102:103], v[148:149] op_sel_hi:[1,0]
	v_mul_f32_e32 v149, 0xbfb8aa3b, v156
	v_exp_f32_e32 v149, v149
	s_nop 0
	v_add_f32_e32 v149, 1.0, v149
	v_div_scale_f32 v160, s[6:7], v149, v149, v156
	v_rcp_f32_e32 v161, v160
	s_nop 0
	v_fma_f32 v162, -v160, v161, 1.0
	v_fmac_f32_e32 v161, v162, v161
	v_div_scale_f32 v162, vcc, v156, v149, v156
	v_mul_f32_e32 v163, v162, v161
	v_fma_f32 v181, -v160, v163, v162
	v_fmac_f32_e32 v163, v181, v161
	v_fma_f32 v160, -v160, v163, v162
	v_div_fmas_f32 v160, v160, v161, v163
	v_div_fixup_f32 v149, v160, v149, v156
	v_mul_f32_e32 v156, 0xbfb8aa3b, v158
	v_exp_f32_e32 v156, v156
	s_nop 0
	v_add_f32_e32 v156, 1.0, v156
	v_div_scale_f32 v160, s[6:7], v156, v156, v158
	v_rcp_f32_e32 v161, v160
	s_nop 0
	v_fma_f32 v162, -v160, v161, 1.0
	v_fmac_f32_e32 v161, v162, v161
	v_div_scale_f32 v162, vcc, v158, v156, v158
	v_mul_f32_e32 v163, v162, v161
	v_fma_f32 v181, -v160, v163, v162
	v_fmac_f32_e32 v163, v181, v161
	v_fma_f32 v160, -v160, v163, v162
	v_div_fmas_f32 v160, v160, v161, v163
	v_div_fixup_f32 v156, v160, v156, v158
	v_mul_f32_e32 v158, 0xbfb8aa3b, v157
	v_exp_f32_e32 v158, v158
	s_nop 0
	v_add_f32_e32 v158, 1.0, v158
	v_div_scale_f32 v160, s[6:7], v158, v158, v157
	v_rcp_f32_e32 v161, v160
	s_nop 0
	v_fma_f32 v162, -v160, v161, 1.0
	v_fmac_f32_e32 v161, v162, v161
	v_div_scale_f32 v162, vcc, v157, v158, v157
	v_mul_f32_e32 v163, v162, v161
	v_fma_f32 v181, -v160, v163, v162
	v_fmac_f32_e32 v163, v181, v161
	v_fma_f32 v160, -v160, v163, v162
	v_div_fmas_f32 v160, v160, v161, v163
	v_div_fixup_f32 v157, v160, v158, v157
	v_mul_f32_e32 v158, 0xbfb8aa3b, v159
	v_exp_f32_e32 v158, v158
	s_nop 0
	v_add_f32_e32 v158, 1.0, v158
	v_div_scale_f32 v160, s[6:7], v158, v158, v159
	v_rcp_f32_e32 v161, v160
	s_nop 0
	v_fma_f32 v162, -v160, v161, 1.0
	v_fmac_f32_e32 v161, v162, v161
	v_div_scale_f32 v162, vcc, v159, v158, v159
	v_mul_f32_e32 v163, v162, v161
	v_fma_f32 v181, -v160, v163, v162
	v_fmac_f32_e32 v163, v181, v161
	v_fma_f32 v160, -v160, v163, v162
	v_div_fmas_f32 v160, v160, v161, v163
	v_div_fixup_f32 v158, v160, v158, v159
	v_mul_f32_e32 v159, 0xbfb8aa3b, v154
	v_exp_f32_e32 v159, v159
	s_nop 0
	v_add_f32_e32 v159, 1.0, v159
	v_div_scale_f32 v160, s[6:7], v159, v159, v154
	v_rcp_f32_e32 v161, v160
	s_nop 0
	v_fma_f32 v162, -v160, v161, 1.0
	v_fmac_f32_e32 v161, v162, v161
	v_div_scale_f32 v162, vcc, v154, v159, v154
	v_mul_f32_e32 v163, v162, v161
	v_fma_f32 v181, -v160, v163, v162
	v_fmac_f32_e32 v163, v181, v161
	v_fma_f32 v160, -v160, v163, v162
	v_div_fmas_f32 v160, v160, v161, v163
	v_div_fixup_f32 v154, v160, v159, v154
	v_mul_f32_e32 v159, 0xbfb8aa3b, v152
	v_exp_f32_e32 v159, v159
	s_nop 0
	v_add_f32_e32 v159, 1.0, v159
	v_div_scale_f32 v160, s[6:7], v159, v159, v152
	v_rcp_f32_e32 v161, v160
	s_nop 0
	v_fma_f32 v162, -v160, v161, 1.0
	v_fmac_f32_e32 v161, v162, v161
	v_div_scale_f32 v162, vcc, v152, v159, v152
	v_mul_f32_e32 v163, v162, v161
	v_fma_f32 v181, -v160, v163, v162
	v_fmac_f32_e32 v163, v181, v161
	v_fma_f32 v160, -v160, v163, v162
	v_div_fmas_f32 v160, v160, v161, v163
	v_div_fixup_f32 v159, v160, v159, v152
	v_mul_f32_e32 v152, 0xbfb8aa3b, v155
	v_exp_f32_e32 v152, v152
	s_nop 0
	v_add_f32_e32 v152, 1.0, v152
	v_div_scale_f32 v160, s[6:7], v152, v152, v155
	v_rcp_f32_e32 v161, v160
	s_nop 0
	v_fma_f32 v162, -v160, v161, 1.0
	v_fmac_f32_e32 v161, v162, v161
	v_div_scale_f32 v162, vcc, v155, v152, v155
	v_mul_f32_e32 v163, v162, v161
	v_fma_f32 v181, -v160, v163, v162
	v_fmac_f32_e32 v163, v181, v161
	v_fma_f32 v160, -v160, v163, v162
	v_div_fmas_f32 v160, v160, v161, v163
	v_div_fixup_f32 v155, v160, v152, v155
	v_mul_f32_e32 v152, 0xbfb8aa3b, v153
	v_exp_f32_e32 v152, v152
	s_nop 0
	v_add_f32_e32 v152, 1.0, v152
	v_div_scale_f32 v160, s[6:7], v152, v152, v153
	v_rcp_f32_e32 v161, v160
	s_nop 0
	v_fma_f32 v162, -v160, v161, 1.0
	v_fmac_f32_e32 v161, v162, v161
	v_div_scale_f32 v162, vcc, v153, v152, v153
	v_mul_f32_e32 v163, v162, v161
	v_fma_f32 v181, -v160, v163, v162
	v_fmac_f32_e32 v163, v181, v161
	v_fma_f32 v160, -v160, v163, v162
	v_div_fmas_f32 v160, v160, v161, v163
	v_div_fixup_f32 v160, v160, v152, v153
	v_cvt_pk_bf16_f32 v152, v149, v157
	v_cvt_pk_bf16_f32 v153, v154, v155
	v_cvt_pk_bf16_f32 v154, v156, v158
	v_pk_mul_f32 v[156:157], v[106:107], v[148:149] op_sel_hi:[1,0]
	v_cvt_pk_bf16_f32 v155, v159, v160
	global_store_dwordx4 v[150:151], v[152:155], off
	v_mul_f32_e32 v158, 0xbfb8aa3b, v156
	v_exp_f32_e32 v158, v158
	v_pk_mul_f32 v[154:155], v[108:109], v[148:149] op_sel_hi:[1,0]
	v_pk_mul_f32 v[152:153], v[100:101], v[148:149] op_sel_hi:[1,0]
	v_pk_mul_f32 v[148:149], v[98:99], v[148:149] op_sel_hi:[1,0]
	v_add_f32_e32 v158, 1.0, v158
	v_div_scale_f32 v159, s[6:7], v158, v158, v156
	v_rcp_f32_e32 v160, v159
	s_nop 0
	v_fma_f32 v161, -v159, v160, 1.0
	v_fmac_f32_e32 v160, v161, v160
	v_div_scale_f32 v161, vcc, v156, v158, v156
	v_mul_f32_e32 v162, v161, v160
	v_fma_f32 v163, -v159, v162, v161
	v_fmac_f32_e32 v162, v163, v160
	v_fma_f32 v159, -v159, v162, v161
	v_div_fmas_f32 v159, v159, v160, v162
	v_div_fixup_f32 v156, v159, v158, v156
	v_mul_f32_e32 v158, 0xbfb8aa3b, v148
	v_exp_f32_e32 v158, v158
	s_nop 0
	v_add_f32_e32 v158, 1.0, v158
	v_div_scale_f32 v159, s[6:7], v158, v158, v148
	v_rcp_f32_e32 v160, v159
	s_nop 0
	v_fma_f32 v161, -v159, v160, 1.0
	v_fmac_f32_e32 v160, v161, v160
	v_div_scale_f32 v161, vcc, v148, v158, v148
	v_mul_f32_e32 v162, v161, v160
	v_fma_f32 v163, -v159, v162, v161
	v_fmac_f32_e32 v162, v163, v160
	v_fma_f32 v159, -v159, v162, v161
	v_div_fmas_f32 v159, v159, v160, v162
	v_div_fixup_f32 v148, v159, v158, v148
	v_mul_f32_e32 v158, 0xbfb8aa3b, v157
	v_exp_f32_e32 v158, v158
	s_nop 0
	v_add_f32_e32 v158, 1.0, v158
	v_div_scale_f32 v159, s[6:7], v158, v158, v157
	v_rcp_f32_e32 v160, v159
	s_nop 0
	v_fma_f32 v161, -v159, v160, 1.0
	v_fmac_f32_e32 v160, v161, v160
	v_div_scale_f32 v161, vcc, v157, v158, v157
	v_mul_f32_e32 v162, v161, v160
	v_fma_f32 v163, -v159, v162, v161
	v_fmac_f32_e32 v162, v163, v160
	v_fma_f32 v159, -v159, v162, v161
	v_div_fmas_f32 v159, v159, v160, v162
	v_div_fixup_f32 v157, v159, v158, v157
	v_mul_f32_e32 v158, 0xbfb8aa3b, v149
	v_exp_f32_e32 v158, v158
	s_nop 0
	v_add_f32_e32 v158, 1.0, v158
	v_div_scale_f32 v159, s[6:7], v158, v158, v149
	v_rcp_f32_e32 v160, v159
	s_nop 0
	v_fma_f32 v161, -v159, v160, 1.0
	v_fmac_f32_e32 v160, v161, v160
	v_div_scale_f32 v161, vcc, v149, v158, v149
	v_mul_f32_e32 v162, v161, v160
	v_fma_f32 v163, -v159, v162, v161
	v_fmac_f32_e32 v162, v163, v160
	v_fma_f32 v159, -v159, v162, v161
	v_div_fmas_f32 v159, v159, v160, v162
	v_div_fixup_f32 v149, v159, v158, v149
	v_mul_f32_e32 v158, 0xbfb8aa3b, v154
	v_exp_f32_e32 v158, v158
	s_nop 0
	v_add_f32_e32 v158, 1.0, v158
	v_div_scale_f32 v159, s[6:7], v158, v158, v154
	v_rcp_f32_e32 v160, v159
	s_nop 0
	v_fma_f32 v161, -v159, v160, 1.0
	v_fmac_f32_e32 v160, v161, v160
	v_div_scale_f32 v161, vcc, v154, v158, v154
	v_mul_f32_e32 v162, v161, v160
	v_fma_f32 v163, -v159, v162, v161
	v_fmac_f32_e32 v162, v163, v160
	v_fma_f32 v159, -v159, v162, v161
	v_div_fmas_f32 v159, v159, v160, v162
	v_div_fixup_f32 v154, v159, v158, v154
	v_mul_f32_e32 v158, 0xbfb8aa3b, v152
	v_exp_f32_e32 v158, v158
	s_nop 0
	v_add_f32_e32 v158, 1.0, v158
	v_div_scale_f32 v159, s[6:7], v158, v158, v152
	v_rcp_f32_e32 v160, v159
	s_nop 0
	v_fma_f32 v161, -v159, v160, 1.0
	v_fmac_f32_e32 v160, v161, v160
	v_div_scale_f32 v161, vcc, v152, v158, v152
	v_mul_f32_e32 v162, v161, v160
	v_fma_f32 v163, -v159, v162, v161
	v_fmac_f32_e32 v162, v163, v160
	v_fma_f32 v159, -v159, v162, v161
	v_div_fmas_f32 v159, v159, v160, v162
	v_div_fixup_f32 v158, v159, v158, v152
	v_mul_f32_e32 v152, 0xbfb8aa3b, v155
	v_exp_f32_e32 v152, v152
	s_nop 0
	v_add_f32_e32 v152, 1.0, v152
	v_div_scale_f32 v159, s[6:7], v152, v152, v155
	v_rcp_f32_e32 v160, v159
	s_nop 0
	v_fma_f32 v161, -v159, v160, 1.0
	v_fmac_f32_e32 v160, v161, v160
	v_div_scale_f32 v161, vcc, v155, v152, v155
	v_mul_f32_e32 v162, v161, v160
	v_fma_f32 v163, -v159, v162, v161
	v_fmac_f32_e32 v162, v163, v160
	v_fma_f32 v159, -v159, v162, v161
	v_div_fmas_f32 v159, v159, v160, v162
	v_div_fixup_f32 v155, v159, v152, v155
	v_mul_f32_e32 v152, 0xbfb8aa3b, v153
	v_exp_f32_e32 v152, v152
	s_nop 0
	v_add_f32_e32 v152, 1.0, v152
	v_div_scale_f32 v159, s[6:7], v152, v152, v153
	v_rcp_f32_e32 v160, v159
	s_nop 0
	v_fma_f32 v161, -v159, v160, 1.0
	v_fmac_f32_e32 v160, v161, v160
	v_div_scale_f32 v161, vcc, v153, v152, v153
	v_mul_f32_e32 v162, v161, v160
	v_fma_f32 v163, -v159, v162, v161
	v_fmac_f32_e32 v162, v163, v160
	v_fma_f32 v159, -v159, v162, v161
	v_div_fmas_f32 v159, v159, v160, v162
	v_div_fixup_f32 v159, v159, v152, v153
	v_cvt_pk_bf16_f32 v152, v156, v157
	v_cvt_pk_bf16_f32 v153, v154, v155
	v_cvt_pk_bf16_f32 v154, v148, v149
	v_cvt_pk_bf16_f32 v155, v158, v159
	global_store_dwordx4 v[150:151], v[152:155], off offset:256
	v_add_u32_e32 v150, s13, v166
	v_ashrrev_i32_e32 v151, 31, v150
	v_lshl_add_u64 v[148:149], v[150:151], 2, s[10:11]
	global_load_dword v148, v[148:149], off
	v_lshlrev_b64 v[150:151], 13, v[150:151]
	v_lshl_add_u64 v[150:151], s[28:29], 0, v[150:151]
	v_lshl_add_u64 v[150:151], v[150:151], 0, s[0:1]
	v_lshl_add_u64 v[150:151], v[150:151], 0, v[0:1]
	s_waitcnt vmcnt(0) lgkmcnt(0)
	v_fmamk_f32 v148, v148, 0x3a000000, v207
	v_cmp_gt_f32_e32 vcc, s87, v148
	v_mul_f32_e32 v149, 0x4b800000, v148
	s_nop 0
	v_cndmask_b32_e32 v148, v148, v149, vcc
	v_rsq_f32_e32 v148, v148
	s_nop 0
	v_mul_f32_e32 v149, 0x45800000, v148
	v_cndmask_b32_e32 v148, v148, v149, vcc
	v_pk_mul_f32 v[156:157], v[94:95], v[148:149] op_sel_hi:[1,0]
	v_pk_mul_f32 v[154:155], v[96:97], v[148:149] op_sel_hi:[1,0]
	v_pk_mul_f32 v[152:153], v[88:89], v[148:149] op_sel_hi:[1,0]
	v_pk_mul_f32 v[158:159], v[86:87], v[148:149] op_sel_hi:[1,0]
	v_mul_f32_e32 v149, 0xbfb8aa3b, v156
	v_exp_f32_e32 v149, v149
	s_nop 0
	v_add_f32_e32 v149, 1.0, v149
	v_div_scale_f32 v160, s[6:7], v149, v149, v156
	v_rcp_f32_e32 v161, v160
	s_nop 0
	v_fma_f32 v162, -v160, v161, 1.0
	v_fmac_f32_e32 v161, v162, v161
	v_div_scale_f32 v162, vcc, v156, v149, v156
	v_mul_f32_e32 v163, v162, v161
	v_fma_f32 v181, -v160, v163, v162
	v_fmac_f32_e32 v163, v181, v161
	v_fma_f32 v160, -v160, v163, v162
	v_div_fmas_f32 v160, v160, v161, v163
	v_div_fixup_f32 v149, v160, v149, v156
	v_mul_f32_e32 v156, 0xbfb8aa3b, v158
	v_exp_f32_e32 v156, v156
	s_nop 0
	v_add_f32_e32 v156, 1.0, v156
	v_div_scale_f32 v160, s[6:7], v156, v156, v158
	v_rcp_f32_e32 v161, v160
	s_nop 0
	v_fma_f32 v162, -v160, v161, 1.0
	v_fmac_f32_e32 v161, v162, v161
	v_div_scale_f32 v162, vcc, v158, v156, v158
	v_mul_f32_e32 v163, v162, v161
	v_fma_f32 v181, -v160, v163, v162
	v_fmac_f32_e32 v163, v181, v161
	v_fma_f32 v160, -v160, v163, v162
	v_div_fmas_f32 v160, v160, v161, v163
	v_div_fixup_f32 v156, v160, v156, v158
	v_mul_f32_e32 v158, 0xbfb8aa3b, v157
	v_exp_f32_e32 v158, v158
	s_nop 0
	v_add_f32_e32 v158, 1.0, v158
	v_div_scale_f32 v160, s[6:7], v158, v158, v157
	v_rcp_f32_e32 v161, v160
	s_nop 0
	v_fma_f32 v162, -v160, v161, 1.0
	v_fmac_f32_e32 v161, v162, v161
	v_div_scale_f32 v162, vcc, v157, v158, v157
	v_mul_f32_e32 v163, v162, v161
	v_fma_f32 v181, -v160, v163, v162
	v_fmac_f32_e32 v163, v181, v161
	v_fma_f32 v160, -v160, v163, v162
	v_div_fmas_f32 v160, v160, v161, v163
	v_div_fixup_f32 v157, v160, v158, v157
	v_mul_f32_e32 v158, 0xbfb8aa3b, v159
	v_exp_f32_e32 v158, v158
	s_nop 0
	v_add_f32_e32 v158, 1.0, v158
	v_div_scale_f32 v160, s[6:7], v158, v158, v159
	v_rcp_f32_e32 v161, v160
	s_nop 0
	v_fma_f32 v162, -v160, v161, 1.0
	v_fmac_f32_e32 v161, v162, v161
	v_div_scale_f32 v162, vcc, v159, v158, v159
	v_mul_f32_e32 v163, v162, v161
	v_fma_f32 v181, -v160, v163, v162
	v_fmac_f32_e32 v163, v181, v161
	v_fma_f32 v160, -v160, v163, v162
	v_div_fmas_f32 v160, v160, v161, v163
	v_div_fixup_f32 v158, v160, v158, v159
	v_mul_f32_e32 v159, 0xbfb8aa3b, v154
	v_exp_f32_e32 v159, v159
	s_nop 0
	v_add_f32_e32 v159, 1.0, v159
	v_div_scale_f32 v160, s[6:7], v159, v159, v154
	v_rcp_f32_e32 v161, v160
	s_nop 0
	v_fma_f32 v162, -v160, v161, 1.0
	v_fmac_f32_e32 v161, v162, v161
	v_div_scale_f32 v162, vcc, v154, v159, v154
	v_mul_f32_e32 v163, v162, v161
	v_fma_f32 v181, -v160, v163, v162
	v_fmac_f32_e32 v163, v181, v161
	v_fma_f32 v160, -v160, v163, v162
	v_div_fmas_f32 v160, v160, v161, v163
	v_div_fixup_f32 v154, v160, v159, v154
	v_mul_f32_e32 v159, 0xbfb8aa3b, v152
	v_exp_f32_e32 v159, v159
	s_nop 0
	v_add_f32_e32 v159, 1.0, v159
	v_div_scale_f32 v160, s[6:7], v159, v159, v152
	v_rcp_f32_e32 v161, v160
	s_nop 0
	v_fma_f32 v162, -v160, v161, 1.0
	v_fmac_f32_e32 v161, v162, v161
	v_div_scale_f32 v162, vcc, v152, v159, v152
	v_mul_f32_e32 v163, v162, v161
	v_fma_f32 v181, -v160, v163, v162
	v_fmac_f32_e32 v163, v181, v161
	v_fma_f32 v160, -v160, v163, v162
	v_div_fmas_f32 v160, v160, v161, v163
	v_div_fixup_f32 v159, v160, v159, v152
	v_mul_f32_e32 v152, 0xbfb8aa3b, v155
	v_exp_f32_e32 v152, v152
	s_nop 0
	v_add_f32_e32 v152, 1.0, v152
	v_div_scale_f32 v160, s[6:7], v152, v152, v155
	v_rcp_f32_e32 v161, v160
	s_nop 0
	v_fma_f32 v162, -v160, v161, 1.0
	v_fmac_f32_e32 v161, v162, v161
	v_div_scale_f32 v162, vcc, v155, v152, v155
	v_mul_f32_e32 v163, v162, v161
	v_fma_f32 v181, -v160, v163, v162
	v_fmac_f32_e32 v163, v181, v161
	v_fma_f32 v160, -v160, v163, v162
	v_div_fmas_f32 v160, v160, v161, v163
	v_div_fixup_f32 v155, v160, v152, v155
	v_mul_f32_e32 v152, 0xbfb8aa3b, v153
	v_exp_f32_e32 v152, v152
	s_nop 0
	v_add_f32_e32 v152, 1.0, v152
	v_div_scale_f32 v160, s[6:7], v152, v152, v153
	v_rcp_f32_e32 v161, v160
	s_nop 0
	v_fma_f32 v162, -v160, v161, 1.0
	v_fmac_f32_e32 v161, v162, v161
	v_div_scale_f32 v162, vcc, v153, v152, v153
	v_mul_f32_e32 v163, v162, v161
	v_fma_f32 v181, -v160, v163, v162
	v_fmac_f32_e32 v163, v181, v161
	v_fma_f32 v160, -v160, v163, v162
	v_div_fmas_f32 v160, v160, v161, v163
	v_div_fixup_f32 v160, v160, v152, v153
	v_cvt_pk_bf16_f32 v152, v149, v157
	v_cvt_pk_bf16_f32 v153, v154, v155
	v_cvt_pk_bf16_f32 v154, v156, v158
	v_pk_mul_f32 v[156:157], v[90:91], v[148:149] op_sel_hi:[1,0]
	v_cvt_pk_bf16_f32 v155, v159, v160
	global_store_dwordx4 v[150:151], v[152:155], off
	v_mul_f32_e32 v158, 0xbfb8aa3b, v156
	v_exp_f32_e32 v158, v158
	v_pk_mul_f32 v[154:155], v[92:93], v[148:149] op_sel_hi:[1,0]
	v_pk_mul_f32 v[152:153], v[84:85], v[148:149] op_sel_hi:[1,0]
	v_pk_mul_f32 v[148:149], v[82:83], v[148:149] op_sel_hi:[1,0]
	v_add_f32_e32 v158, 1.0, v158
	v_div_scale_f32 v159, s[6:7], v158, v158, v156
	v_rcp_f32_e32 v160, v159
	s_nop 0
	v_fma_f32 v161, -v159, v160, 1.0
	v_fmac_f32_e32 v160, v161, v160
	v_div_scale_f32 v161, vcc, v156, v158, v156
	v_mul_f32_e32 v162, v161, v160
	v_fma_f32 v163, -v159, v162, v161
	v_fmac_f32_e32 v162, v163, v160
	v_fma_f32 v159, -v159, v162, v161
	v_div_fmas_f32 v159, v159, v160, v162
	v_div_fixup_f32 v156, v159, v158, v156
	v_mul_f32_e32 v158, 0xbfb8aa3b, v148
	v_exp_f32_e32 v158, v158
	s_nop 0
	v_add_f32_e32 v158, 1.0, v158
	v_div_scale_f32 v159, s[6:7], v158, v158, v148
	v_rcp_f32_e32 v160, v159
	s_nop 0
	v_fma_f32 v161, -v159, v160, 1.0
	v_fmac_f32_e32 v160, v161, v160
	v_div_scale_f32 v161, vcc, v148, v158, v148
	v_mul_f32_e32 v162, v161, v160
	v_fma_f32 v163, -v159, v162, v161
	v_fmac_f32_e32 v162, v163, v160
	v_fma_f32 v159, -v159, v162, v161
	v_div_fmas_f32 v159, v159, v160, v162
	v_div_fixup_f32 v148, v159, v158, v148
	v_mul_f32_e32 v158, 0xbfb8aa3b, v157
	v_exp_f32_e32 v158, v158
	s_nop 0
	v_add_f32_e32 v158, 1.0, v158
	v_div_scale_f32 v159, s[6:7], v158, v158, v157
	v_rcp_f32_e32 v160, v159
	s_nop 0
	v_fma_f32 v161, -v159, v160, 1.0
	v_fmac_f32_e32 v160, v161, v160
	v_div_scale_f32 v161, vcc, v157, v158, v157
	v_mul_f32_e32 v162, v161, v160
	v_fma_f32 v163, -v159, v162, v161
	v_fmac_f32_e32 v162, v163, v160
	v_fma_f32 v159, -v159, v162, v161
	v_div_fmas_f32 v159, v159, v160, v162
	v_div_fixup_f32 v157, v159, v158, v157
	v_mul_f32_e32 v158, 0xbfb8aa3b, v149
	v_exp_f32_e32 v158, v158
	s_nop 0
	v_add_f32_e32 v158, 1.0, v158
	v_div_scale_f32 v159, s[6:7], v158, v158, v149
	v_rcp_f32_e32 v160, v159
	s_nop 0
	v_fma_f32 v161, -v159, v160, 1.0
	v_fmac_f32_e32 v160, v161, v160
	v_div_scale_f32 v161, vcc, v149, v158, v149
	v_mul_f32_e32 v162, v161, v160
	v_fma_f32 v163, -v159, v162, v161
	v_fmac_f32_e32 v162, v163, v160
	v_fma_f32 v159, -v159, v162, v161
	v_div_fmas_f32 v159, v159, v160, v162
	v_div_fixup_f32 v149, v159, v158, v149
	v_mul_f32_e32 v158, 0xbfb8aa3b, v154
	v_exp_f32_e32 v158, v158
	s_nop 0
	v_add_f32_e32 v158, 1.0, v158
	v_div_scale_f32 v159, s[6:7], v158, v158, v154
	v_rcp_f32_e32 v160, v159
	s_nop 0
	v_fma_f32 v161, -v159, v160, 1.0
	v_fmac_f32_e32 v160, v161, v160
	v_div_scale_f32 v161, vcc, v154, v158, v154
	v_mul_f32_e32 v162, v161, v160
	v_fma_f32 v163, -v159, v162, v161
	v_fmac_f32_e32 v162, v163, v160
	v_fma_f32 v159, -v159, v162, v161
	v_div_fmas_f32 v159, v159, v160, v162
	v_div_fixup_f32 v154, v159, v158, v154
	v_mul_f32_e32 v158, 0xbfb8aa3b, v152
	v_exp_f32_e32 v158, v158
	s_nop 0
	v_add_f32_e32 v158, 1.0, v158
	v_div_scale_f32 v159, s[6:7], v158, v158, v152
	v_rcp_f32_e32 v160, v159
	s_nop 0
	v_fma_f32 v161, -v159, v160, 1.0
	v_fmac_f32_e32 v160, v161, v160
	v_div_scale_f32 v161, vcc, v152, v158, v152
	v_mul_f32_e32 v162, v161, v160
	v_fma_f32 v163, -v159, v162, v161
	v_fmac_f32_e32 v162, v163, v160
	v_fma_f32 v159, -v159, v162, v161
	v_div_fmas_f32 v159, v159, v160, v162
	v_div_fixup_f32 v158, v159, v158, v152
	v_mul_f32_e32 v152, 0xbfb8aa3b, v155
	v_exp_f32_e32 v152, v152
	s_nop 0
	v_add_f32_e32 v152, 1.0, v152
	v_div_scale_f32 v159, s[6:7], v152, v152, v155
	v_rcp_f32_e32 v160, v159
	s_nop 0
	v_fma_f32 v161, -v159, v160, 1.0
	v_fmac_f32_e32 v160, v161, v160
	v_div_scale_f32 v161, vcc, v155, v152, v155
	v_mul_f32_e32 v162, v161, v160
	v_fma_f32 v163, -v159, v162, v161
	v_fmac_f32_e32 v162, v163, v160
	v_fma_f32 v159, -v159, v162, v161
	v_div_fmas_f32 v159, v159, v160, v162
	v_div_fixup_f32 v155, v159, v152, v155
	v_mul_f32_e32 v152, 0xbfb8aa3b, v153
	v_exp_f32_e32 v152, v152
	s_nop 0
	v_add_f32_e32 v152, 1.0, v152
	v_div_scale_f32 v159, s[6:7], v152, v152, v153
	v_rcp_f32_e32 v160, v159
	s_nop 0
	v_fma_f32 v161, -v159, v160, 1.0
	v_fmac_f32_e32 v160, v161, v160
	v_div_scale_f32 v161, vcc, v153, v152, v153
	v_mul_f32_e32 v162, v161, v160
	v_fma_f32 v163, -v159, v162, v161
	v_fmac_f32_e32 v162, v163, v160
	v_fma_f32 v159, -v159, v162, v161
	v_div_fmas_f32 v159, v159, v160, v162
	v_div_fixup_f32 v159, v159, v152, v153
	v_cvt_pk_bf16_f32 v152, v156, v157
	v_cvt_pk_bf16_f32 v153, v154, v155
	v_cvt_pk_bf16_f32 v154, v148, v149
	v_cvt_pk_bf16_f32 v155, v158, v159
	global_store_dwordx4 v[150:151], v[152:155], off offset:256
	v_add_u32_e32 v150, s13, v167
	v_ashrrev_i32_e32 v151, 31, v150
	v_lshl_add_u64 v[148:149], v[150:151], 2, s[10:11]
	global_load_dword v148, v[148:149], off
	v_lshlrev_b64 v[150:151], 13, v[150:151]
	v_lshl_add_u64 v[150:151], s[28:29], 0, v[150:151]
	v_lshl_add_u64 v[150:151], v[150:151], 0, s[0:1]
	v_lshl_add_u64 v[150:151], v[150:151], 0, v[0:1]
	s_waitcnt vmcnt(0) lgkmcnt(0)
	v_fmamk_f32 v148, v148, 0x3a000000, v207
	v_cmp_gt_f32_e32 vcc, s87, v148
	v_mul_f32_e32 v149, 0x4b800000, v148
	s_nop 0
	v_cndmask_b32_e32 v148, v148, v149, vcc
	v_rsq_f32_e32 v148, v148
	s_nop 0
	v_mul_f32_e32 v149, 0x45800000, v148
	v_cndmask_b32_e32 v148, v148, v149, vcc
	v_pk_mul_f32 v[156:157], v[78:79], v[148:149] op_sel_hi:[1,0]
	v_pk_mul_f32 v[154:155], v[80:81], v[148:149] op_sel_hi:[1,0]
	v_pk_mul_f32 v[152:153], v[72:73], v[148:149] op_sel_hi:[1,0]
	v_pk_mul_f32 v[158:159], v[70:71], v[148:149] op_sel_hi:[1,0]
	v_mul_f32_e32 v149, 0xbfb8aa3b, v156
	v_exp_f32_e32 v149, v149
	s_nop 0
	v_add_f32_e32 v149, 1.0, v149
	v_div_scale_f32 v160, s[6:7], v149, v149, v156
	v_rcp_f32_e32 v161, v160
	s_nop 0
	v_fma_f32 v162, -v160, v161, 1.0
	v_fmac_f32_e32 v161, v162, v161
	v_div_scale_f32 v162, vcc, v156, v149, v156
	v_mul_f32_e32 v163, v162, v161
	v_fma_f32 v181, -v160, v163, v162
	v_fmac_f32_e32 v163, v181, v161
	v_fma_f32 v160, -v160, v163, v162
	v_div_fmas_f32 v160, v160, v161, v163
	v_div_fixup_f32 v149, v160, v149, v156
	v_mul_f32_e32 v156, 0xbfb8aa3b, v158
	v_exp_f32_e32 v156, v156
	s_nop 0
	v_add_f32_e32 v156, 1.0, v156
	v_div_scale_f32 v160, s[6:7], v156, v156, v158
	v_rcp_f32_e32 v161, v160
	s_nop 0
	v_fma_f32 v162, -v160, v161, 1.0
	v_fmac_f32_e32 v161, v162, v161
	v_div_scale_f32 v162, vcc, v158, v156, v158
	v_mul_f32_e32 v163, v162, v161
	v_fma_f32 v181, -v160, v163, v162
	v_fmac_f32_e32 v163, v181, v161
	v_fma_f32 v160, -v160, v163, v162
	v_div_fmas_f32 v160, v160, v161, v163
	v_div_fixup_f32 v156, v160, v156, v158
	v_mul_f32_e32 v158, 0xbfb8aa3b, v157
	v_exp_f32_e32 v158, v158
	s_nop 0
	v_add_f32_e32 v158, 1.0, v158
	v_div_scale_f32 v160, s[6:7], v158, v158, v157
	v_rcp_f32_e32 v161, v160
	s_nop 0
	v_fma_f32 v162, -v160, v161, 1.0
	v_fmac_f32_e32 v161, v162, v161
	v_div_scale_f32 v162, vcc, v157, v158, v157
	v_mul_f32_e32 v163, v162, v161
	v_fma_f32 v181, -v160, v163, v162
	v_fmac_f32_e32 v163, v181, v161
	v_fma_f32 v160, -v160, v163, v162
	v_div_fmas_f32 v160, v160, v161, v163
	v_div_fixup_f32 v157, v160, v158, v157
	v_mul_f32_e32 v158, 0xbfb8aa3b, v159
	v_exp_f32_e32 v158, v158
	s_nop 0
	v_add_f32_e32 v158, 1.0, v158
	v_div_scale_f32 v160, s[6:7], v158, v158, v159
	v_rcp_f32_e32 v161, v160
	s_nop 0
	v_fma_f32 v162, -v160, v161, 1.0
	v_fmac_f32_e32 v161, v162, v161
	v_div_scale_f32 v162, vcc, v159, v158, v159
	v_mul_f32_e32 v163, v162, v161
	v_fma_f32 v181, -v160, v163, v162
	v_fmac_f32_e32 v163, v181, v161
	v_fma_f32 v160, -v160, v163, v162
	v_div_fmas_f32 v160, v160, v161, v163
	v_div_fixup_f32 v158, v160, v158, v159
	v_mul_f32_e32 v159, 0xbfb8aa3b, v154
	v_exp_f32_e32 v159, v159
	s_nop 0
	v_add_f32_e32 v159, 1.0, v159
	v_div_scale_f32 v160, s[6:7], v159, v159, v154
	v_rcp_f32_e32 v161, v160
	s_nop 0
	v_fma_f32 v162, -v160, v161, 1.0
	v_fmac_f32_e32 v161, v162, v161
	v_div_scale_f32 v162, vcc, v154, v159, v154
	v_mul_f32_e32 v163, v162, v161
	v_fma_f32 v181, -v160, v163, v162
	v_fmac_f32_e32 v163, v181, v161
	v_fma_f32 v160, -v160, v163, v162
	v_div_fmas_f32 v160, v160, v161, v163
	v_div_fixup_f32 v154, v160, v159, v154
	v_mul_f32_e32 v159, 0xbfb8aa3b, v152
	v_exp_f32_e32 v159, v159
	s_nop 0
	v_add_f32_e32 v159, 1.0, v159
	v_div_scale_f32 v160, s[6:7], v159, v159, v152
	v_rcp_f32_e32 v161, v160
	s_nop 0
	v_fma_f32 v162, -v160, v161, 1.0
	v_fmac_f32_e32 v161, v162, v161
	v_div_scale_f32 v162, vcc, v152, v159, v152
	v_mul_f32_e32 v163, v162, v161
	v_fma_f32 v181, -v160, v163, v162
	v_fmac_f32_e32 v163, v181, v161
	v_fma_f32 v160, -v160, v163, v162
	v_div_fmas_f32 v160, v160, v161, v163
	v_div_fixup_f32 v159, v160, v159, v152
	v_mul_f32_e32 v152, 0xbfb8aa3b, v155
	v_exp_f32_e32 v152, v152
	s_nop 0
	v_add_f32_e32 v152, 1.0, v152
	v_div_scale_f32 v160, s[6:7], v152, v152, v155
	v_rcp_f32_e32 v161, v160
	s_nop 0
	v_fma_f32 v162, -v160, v161, 1.0
	v_fmac_f32_e32 v161, v162, v161
	v_div_scale_f32 v162, vcc, v155, v152, v155
	v_mul_f32_e32 v163, v162, v161
	v_fma_f32 v181, -v160, v163, v162
	v_fmac_f32_e32 v163, v181, v161
	v_fma_f32 v160, -v160, v163, v162
	v_div_fmas_f32 v160, v160, v161, v163
	v_div_fixup_f32 v155, v160, v152, v155
	v_mul_f32_e32 v152, 0xbfb8aa3b, v153
	v_exp_f32_e32 v152, v152
	s_nop 0
	v_add_f32_e32 v152, 1.0, v152
	v_div_scale_f32 v160, s[6:7], v152, v152, v153
	v_rcp_f32_e32 v161, v160
	s_nop 0
	v_fma_f32 v162, -v160, v161, 1.0
	v_fmac_f32_e32 v161, v162, v161
	v_div_scale_f32 v162, vcc, v153, v152, v153
	v_mul_f32_e32 v163, v162, v161
	v_fma_f32 v181, -v160, v163, v162
	v_fmac_f32_e32 v163, v181, v161
	v_fma_f32 v160, -v160, v163, v162
	v_div_fmas_f32 v160, v160, v161, v163
	v_div_fixup_f32 v160, v160, v152, v153
	v_cvt_pk_bf16_f32 v152, v149, v157
	v_cvt_pk_bf16_f32 v153, v154, v155
	v_cvt_pk_bf16_f32 v154, v156, v158
	v_pk_mul_f32 v[156:157], v[74:75], v[148:149] op_sel_hi:[1,0]
	v_cvt_pk_bf16_f32 v155, v159, v160
	global_store_dwordx4 v[150:151], v[152:155], off
	v_mul_f32_e32 v158, 0xbfb8aa3b, v156
	v_exp_f32_e32 v158, v158
	v_pk_mul_f32 v[154:155], v[76:77], v[148:149] op_sel_hi:[1,0]
	v_pk_mul_f32 v[152:153], v[68:69], v[148:149] op_sel_hi:[1,0]
	v_pk_mul_f32 v[148:149], v[66:67], v[148:149] op_sel_hi:[1,0]
	v_add_f32_e32 v158, 1.0, v158
	v_div_scale_f32 v159, s[6:7], v158, v158, v156
	v_rcp_f32_e32 v160, v159
	s_nop 0
	v_fma_f32 v161, -v159, v160, 1.0
	v_fmac_f32_e32 v160, v161, v160
	v_div_scale_f32 v161, vcc, v156, v158, v156
	v_mul_f32_e32 v162, v161, v160
	v_fma_f32 v163, -v159, v162, v161
	v_fmac_f32_e32 v162, v163, v160
	v_fma_f32 v159, -v159, v162, v161
	v_div_fmas_f32 v159, v159, v160, v162
	v_div_fixup_f32 v156, v159, v158, v156
	v_mul_f32_e32 v158, 0xbfb8aa3b, v148
	v_exp_f32_e32 v158, v158
	s_nop 0
	v_add_f32_e32 v158, 1.0, v158
	v_div_scale_f32 v159, s[6:7], v158, v158, v148
	v_rcp_f32_e32 v160, v159
	s_nop 0
	v_fma_f32 v161, -v159, v160, 1.0
	v_fmac_f32_e32 v160, v161, v160
	v_div_scale_f32 v161, vcc, v148, v158, v148
	v_mul_f32_e32 v162, v161, v160
	v_fma_f32 v163, -v159, v162, v161
	v_fmac_f32_e32 v162, v163, v160
	v_fma_f32 v159, -v159, v162, v161
	v_div_fmas_f32 v159, v159, v160, v162
	v_div_fixup_f32 v148, v159, v158, v148
	v_mul_f32_e32 v158, 0xbfb8aa3b, v157
	v_exp_f32_e32 v158, v158
	s_nop 0
	v_add_f32_e32 v158, 1.0, v158
	v_div_scale_f32 v159, s[6:7], v158, v158, v157
	v_rcp_f32_e32 v160, v159
	s_nop 0
	v_fma_f32 v161, -v159, v160, 1.0
	v_fmac_f32_e32 v160, v161, v160
	v_div_scale_f32 v161, vcc, v157, v158, v157
	v_mul_f32_e32 v162, v161, v160
	v_fma_f32 v163, -v159, v162, v161
	v_fmac_f32_e32 v162, v163, v160
	v_fma_f32 v159, -v159, v162, v161
	v_div_fmas_f32 v159, v159, v160, v162
	v_div_fixup_f32 v157, v159, v158, v157
	v_mul_f32_e32 v158, 0xbfb8aa3b, v149
	v_exp_f32_e32 v158, v158
	s_nop 0
	v_add_f32_e32 v158, 1.0, v158
	v_div_scale_f32 v159, s[6:7], v158, v158, v149
	v_rcp_f32_e32 v160, v159
	s_nop 0
	v_fma_f32 v161, -v159, v160, 1.0
	v_fmac_f32_e32 v160, v161, v160
	v_div_scale_f32 v161, vcc, v149, v158, v149
	v_mul_f32_e32 v162, v161, v160
	v_fma_f32 v163, -v159, v162, v161
	v_fmac_f32_e32 v162, v163, v160
	v_fma_f32 v159, -v159, v162, v161
	v_div_fmas_f32 v159, v159, v160, v162
	v_div_fixup_f32 v149, v159, v158, v149
	v_mul_f32_e32 v158, 0xbfb8aa3b, v154
	v_exp_f32_e32 v158, v158
	s_nop 0
	v_add_f32_e32 v158, 1.0, v158
	v_div_scale_f32 v159, s[6:7], v158, v158, v154
	v_rcp_f32_e32 v160, v159
	s_nop 0
	v_fma_f32 v161, -v159, v160, 1.0
	v_fmac_f32_e32 v160, v161, v160
	v_div_scale_f32 v161, vcc, v154, v158, v154
	v_mul_f32_e32 v162, v161, v160
	v_fma_f32 v163, -v159, v162, v161
	v_fmac_f32_e32 v162, v163, v160
	v_fma_f32 v159, -v159, v162, v161
	v_div_fmas_f32 v159, v159, v160, v162
	v_div_fixup_f32 v154, v159, v158, v154
	v_mul_f32_e32 v158, 0xbfb8aa3b, v152
	v_exp_f32_e32 v158, v158
	s_nop 0
	v_add_f32_e32 v158, 1.0, v158
	v_div_scale_f32 v159, s[6:7], v158, v158, v152
	v_rcp_f32_e32 v160, v159
	s_nop 0
	v_fma_f32 v161, -v159, v160, 1.0
	v_fmac_f32_e32 v160, v161, v160
	v_div_scale_f32 v161, vcc, v152, v158, v152
	v_mul_f32_e32 v162, v161, v160
	v_fma_f32 v163, -v159, v162, v161
	v_fmac_f32_e32 v162, v163, v160
	v_fma_f32 v159, -v159, v162, v161
	v_div_fmas_f32 v159, v159, v160, v162
	v_div_fixup_f32 v158, v159, v158, v152
	v_mul_f32_e32 v152, 0xbfb8aa3b, v155
	v_exp_f32_e32 v152, v152
	s_nop 0
	v_add_f32_e32 v152, 1.0, v152
	v_div_scale_f32 v159, s[6:7], v152, v152, v155
	v_rcp_f32_e32 v160, v159
	s_nop 0
	v_fma_f32 v161, -v159, v160, 1.0
	v_fmac_f32_e32 v160, v161, v160
	v_div_scale_f32 v161, vcc, v155, v152, v155
	v_mul_f32_e32 v162, v161, v160
	v_fma_f32 v163, -v159, v162, v161
	v_fmac_f32_e32 v162, v163, v160
	v_fma_f32 v159, -v159, v162, v161
	v_div_fmas_f32 v159, v159, v160, v162
	v_div_fixup_f32 v155, v159, v152, v155
	v_mul_f32_e32 v152, 0xbfb8aa3b, v153
	v_exp_f32_e32 v152, v152
	s_nop 0
	v_add_f32_e32 v152, 1.0, v152
	v_div_scale_f32 v159, s[6:7], v152, v152, v153
	v_rcp_f32_e32 v160, v159
	s_nop 0
	v_fma_f32 v161, -v159, v160, 1.0
	v_fmac_f32_e32 v160, v161, v160
	v_div_scale_f32 v161, vcc, v153, v152, v153
	v_mul_f32_e32 v162, v161, v160
	v_fma_f32 v163, -v159, v162, v161
	v_fmac_f32_e32 v162, v163, v160
	v_fma_f32 v159, -v159, v162, v161
	v_div_fmas_f32 v159, v159, v160, v162
	v_div_fixup_f32 v159, v159, v152, v153
	v_cvt_pk_bf16_f32 v152, v156, v157
	v_cvt_pk_bf16_f32 v153, v154, v155
	v_cvt_pk_bf16_f32 v154, v148, v149
	v_cvt_pk_bf16_f32 v155, v158, v159
	global_store_dwordx4 v[150:151], v[152:155], off offset:256
	v_add_u32_e32 v150, s13, v168
	v_ashrrev_i32_e32 v151, 31, v150
	v_lshl_add_u64 v[148:149], v[150:151], 2, s[10:11]
	global_load_dword v148, v[148:149], off
	v_lshlrev_b64 v[150:151], 13, v[150:151]
	v_lshl_add_u64 v[150:151], s[28:29], 0, v[150:151]
	v_lshl_add_u64 v[150:151], v[150:151], 0, s[0:1]
	v_lshl_add_u64 v[150:151], v[150:151], 0, v[0:1]
	s_waitcnt vmcnt(0) lgkmcnt(0)
	v_fmamk_f32 v148, v148, 0x3a000000, v207
	v_cmp_gt_f32_e32 vcc, s87, v148
	v_mul_f32_e32 v149, 0x4b800000, v148
	s_nop 0
	v_cndmask_b32_e32 v148, v148, v149, vcc
	v_rsq_f32_e32 v148, v148
	s_nop 0
	v_mul_f32_e32 v149, 0x45800000, v148
	v_cndmask_b32_e32 v148, v148, v149, vcc
	v_pk_mul_f32 v[156:157], v[62:63], v[148:149] op_sel_hi:[1,0]
	v_pk_mul_f32 v[154:155], v[64:65], v[148:149] op_sel_hi:[1,0]
	v_pk_mul_f32 v[152:153], v[56:57], v[148:149] op_sel_hi:[1,0]
	v_pk_mul_f32 v[158:159], v[54:55], v[148:149] op_sel_hi:[1,0]
	v_mul_f32_e32 v149, 0xbfb8aa3b, v156
	v_exp_f32_e32 v149, v149
	s_nop 0
	v_add_f32_e32 v149, 1.0, v149
	v_div_scale_f32 v160, s[6:7], v149, v149, v156
	v_rcp_f32_e32 v161, v160
	s_nop 0
	v_fma_f32 v162, -v160, v161, 1.0
	v_fmac_f32_e32 v161, v162, v161
	v_div_scale_f32 v162, vcc, v156, v149, v156
	v_mul_f32_e32 v163, v162, v161
	v_fma_f32 v181, -v160, v163, v162
	v_fmac_f32_e32 v163, v181, v161
	v_fma_f32 v160, -v160, v163, v162
	v_div_fmas_f32 v160, v160, v161, v163
	v_div_fixup_f32 v149, v160, v149, v156
	v_mul_f32_e32 v156, 0xbfb8aa3b, v158
	v_exp_f32_e32 v156, v156
	s_nop 0
	v_add_f32_e32 v156, 1.0, v156
	v_div_scale_f32 v160, s[6:7], v156, v156, v158
	v_rcp_f32_e32 v161, v160
	s_nop 0
	v_fma_f32 v162, -v160, v161, 1.0
	v_fmac_f32_e32 v161, v162, v161
	v_div_scale_f32 v162, vcc, v158, v156, v158
	v_mul_f32_e32 v163, v162, v161
	v_fma_f32 v181, -v160, v163, v162
	v_fmac_f32_e32 v163, v181, v161
	v_fma_f32 v160, -v160, v163, v162
	v_div_fmas_f32 v160, v160, v161, v163
	v_div_fixup_f32 v156, v160, v156, v158
	v_mul_f32_e32 v158, 0xbfb8aa3b, v157
	v_exp_f32_e32 v158, v158
	s_nop 0
	v_add_f32_e32 v158, 1.0, v158
	v_div_scale_f32 v160, s[6:7], v158, v158, v157
	v_rcp_f32_e32 v161, v160
	s_nop 0
	v_fma_f32 v162, -v160, v161, 1.0
	v_fmac_f32_e32 v161, v162, v161
	v_div_scale_f32 v162, vcc, v157, v158, v157
	v_mul_f32_e32 v163, v162, v161
	v_fma_f32 v181, -v160, v163, v162
	v_fmac_f32_e32 v163, v181, v161
	v_fma_f32 v160, -v160, v163, v162
	v_div_fmas_f32 v160, v160, v161, v163
	v_div_fixup_f32 v157, v160, v158, v157
	v_mul_f32_e32 v158, 0xbfb8aa3b, v159
	v_exp_f32_e32 v158, v158
	s_nop 0
	v_add_f32_e32 v158, 1.0, v158
	v_div_scale_f32 v160, s[6:7], v158, v158, v159
	v_rcp_f32_e32 v161, v160
	s_nop 0
	v_fma_f32 v162, -v160, v161, 1.0
	v_fmac_f32_e32 v161, v162, v161
	v_div_scale_f32 v162, vcc, v159, v158, v159
	v_mul_f32_e32 v163, v162, v161
	v_fma_f32 v181, -v160, v163, v162
	v_fmac_f32_e32 v163, v181, v161
	v_fma_f32 v160, -v160, v163, v162
	v_div_fmas_f32 v160, v160, v161, v163
	v_div_fixup_f32 v158, v160, v158, v159
	v_mul_f32_e32 v159, 0xbfb8aa3b, v154
	v_exp_f32_e32 v159, v159
	s_nop 0
	v_add_f32_e32 v159, 1.0, v159
	v_div_scale_f32 v160, s[6:7], v159, v159, v154
	v_rcp_f32_e32 v161, v160
	s_nop 0
	v_fma_f32 v162, -v160, v161, 1.0
	v_fmac_f32_e32 v161, v162, v161
	v_div_scale_f32 v162, vcc, v154, v159, v154
	v_mul_f32_e32 v163, v162, v161
	v_fma_f32 v181, -v160, v163, v162
	v_fmac_f32_e32 v163, v181, v161
	v_fma_f32 v160, -v160, v163, v162
	v_div_fmas_f32 v160, v160, v161, v163
	v_div_fixup_f32 v154, v160, v159, v154
	v_mul_f32_e32 v159, 0xbfb8aa3b, v152
	v_exp_f32_e32 v159, v159
	s_nop 0
	v_add_f32_e32 v159, 1.0, v159
	v_div_scale_f32 v160, s[6:7], v159, v159, v152
	v_rcp_f32_e32 v161, v160
	s_nop 0
	v_fma_f32 v162, -v160, v161, 1.0
	v_fmac_f32_e32 v161, v162, v161
	v_div_scale_f32 v162, vcc, v152, v159, v152
	v_mul_f32_e32 v163, v162, v161
	v_fma_f32 v181, -v160, v163, v162
	v_fmac_f32_e32 v163, v181, v161
	v_fma_f32 v160, -v160, v163, v162
	v_div_fmas_f32 v160, v160, v161, v163
	v_div_fixup_f32 v159, v160, v159, v152
	v_mul_f32_e32 v152, 0xbfb8aa3b, v155
	v_exp_f32_e32 v152, v152
	s_nop 0
	v_add_f32_e32 v152, 1.0, v152
	v_div_scale_f32 v160, s[6:7], v152, v152, v155
	v_rcp_f32_e32 v161, v160
	s_nop 0
	v_fma_f32 v162, -v160, v161, 1.0
	v_fmac_f32_e32 v161, v162, v161
	v_div_scale_f32 v162, vcc, v155, v152, v155
	v_mul_f32_e32 v163, v162, v161
	v_fma_f32 v181, -v160, v163, v162
	v_fmac_f32_e32 v163, v181, v161
	v_fma_f32 v160, -v160, v163, v162
	v_div_fmas_f32 v160, v160, v161, v163
	v_div_fixup_f32 v155, v160, v152, v155
	v_mul_f32_e32 v152, 0xbfb8aa3b, v153
	v_exp_f32_e32 v152, v152
	s_nop 0
	v_add_f32_e32 v152, 1.0, v152
	v_div_scale_f32 v160, s[6:7], v152, v152, v153
	v_rcp_f32_e32 v161, v160
	s_nop 0
	v_fma_f32 v162, -v160, v161, 1.0
	v_fmac_f32_e32 v161, v162, v161
	v_div_scale_f32 v162, vcc, v153, v152, v153
	v_mul_f32_e32 v163, v162, v161
	v_fma_f32 v181, -v160, v163, v162
	v_fmac_f32_e32 v163, v181, v161
	v_fma_f32 v160, -v160, v163, v162
	v_div_fmas_f32 v160, v160, v161, v163
	v_div_fixup_f32 v160, v160, v152, v153
	v_cvt_pk_bf16_f32 v152, v149, v157
	v_cvt_pk_bf16_f32 v153, v154, v155
	v_cvt_pk_bf16_f32 v154, v156, v158
	v_pk_mul_f32 v[156:157], v[58:59], v[148:149] op_sel_hi:[1,0]
	v_cvt_pk_bf16_f32 v155, v159, v160
	global_store_dwordx4 v[150:151], v[152:155], off
	v_mul_f32_e32 v158, 0xbfb8aa3b, v156
	v_exp_f32_e32 v158, v158
	v_pk_mul_f32 v[154:155], v[60:61], v[148:149] op_sel_hi:[1,0]
	v_pk_mul_f32 v[152:153], v[52:53], v[148:149] op_sel_hi:[1,0]
	v_pk_mul_f32 v[148:149], v[50:51], v[148:149] op_sel_hi:[1,0]
	v_add_f32_e32 v158, 1.0, v158
	v_div_scale_f32 v159, s[6:7], v158, v158, v156
	v_rcp_f32_e32 v160, v159
	s_nop 0
	v_fma_f32 v161, -v159, v160, 1.0
	v_fmac_f32_e32 v160, v161, v160
	v_div_scale_f32 v161, vcc, v156, v158, v156
	v_mul_f32_e32 v162, v161, v160
	v_fma_f32 v163, -v159, v162, v161
	v_fmac_f32_e32 v162, v163, v160
	v_fma_f32 v159, -v159, v162, v161
	v_div_fmas_f32 v159, v159, v160, v162
	v_div_fixup_f32 v156, v159, v158, v156
	v_mul_f32_e32 v158, 0xbfb8aa3b, v148
	v_exp_f32_e32 v158, v158
	s_nop 0
	v_add_f32_e32 v158, 1.0, v158
	v_div_scale_f32 v159, s[6:7], v158, v158, v148
	v_rcp_f32_e32 v160, v159
	s_nop 0
	v_fma_f32 v161, -v159, v160, 1.0
	v_fmac_f32_e32 v160, v161, v160
	v_div_scale_f32 v161, vcc, v148, v158, v148
	v_mul_f32_e32 v162, v161, v160
	v_fma_f32 v163, -v159, v162, v161
	v_fmac_f32_e32 v162, v163, v160
	v_fma_f32 v159, -v159, v162, v161
	v_div_fmas_f32 v159, v159, v160, v162
	v_div_fixup_f32 v148, v159, v158, v148
	v_mul_f32_e32 v158, 0xbfb8aa3b, v157
	v_exp_f32_e32 v158, v158
	s_nop 0
	v_add_f32_e32 v158, 1.0, v158
	v_div_scale_f32 v159, s[6:7], v158, v158, v157
	v_rcp_f32_e32 v160, v159
	s_nop 0
	v_fma_f32 v161, -v159, v160, 1.0
	v_fmac_f32_e32 v160, v161, v160
	v_div_scale_f32 v161, vcc, v157, v158, v157
	v_mul_f32_e32 v162, v161, v160
	v_fma_f32 v163, -v159, v162, v161
	v_fmac_f32_e32 v162, v163, v160
	v_fma_f32 v159, -v159, v162, v161
	v_div_fmas_f32 v159, v159, v160, v162
	v_div_fixup_f32 v157, v159, v158, v157
	v_mul_f32_e32 v158, 0xbfb8aa3b, v149
	v_exp_f32_e32 v158, v158
	s_nop 0
	v_add_f32_e32 v158, 1.0, v158
	v_div_scale_f32 v159, s[6:7], v158, v158, v149
	v_rcp_f32_e32 v160, v159
	s_nop 0
	v_fma_f32 v161, -v159, v160, 1.0
	v_fmac_f32_e32 v160, v161, v160
	v_div_scale_f32 v161, vcc, v149, v158, v149
	v_mul_f32_e32 v162, v161, v160
	v_fma_f32 v163, -v159, v162, v161
	v_fmac_f32_e32 v162, v163, v160
	v_fma_f32 v159, -v159, v162, v161
	v_div_fmas_f32 v159, v159, v160, v162
	v_div_fixup_f32 v149, v159, v158, v149
	v_mul_f32_e32 v158, 0xbfb8aa3b, v154
	v_exp_f32_e32 v158, v158
	s_nop 0
	v_add_f32_e32 v158, 1.0, v158
	v_div_scale_f32 v159, s[6:7], v158, v158, v154
	v_rcp_f32_e32 v160, v159
	s_nop 0
	v_fma_f32 v161, -v159, v160, 1.0
	v_fmac_f32_e32 v160, v161, v160
	v_div_scale_f32 v161, vcc, v154, v158, v154
	v_mul_f32_e32 v162, v161, v160
	v_fma_f32 v163, -v159, v162, v161
	v_fmac_f32_e32 v162, v163, v160
	v_fma_f32 v159, -v159, v162, v161
	v_div_fmas_f32 v159, v159, v160, v162
	v_div_fixup_f32 v154, v159, v158, v154
	v_mul_f32_e32 v158, 0xbfb8aa3b, v152
	v_exp_f32_e32 v158, v158
	s_nop 0
	v_add_f32_e32 v158, 1.0, v158
	v_div_scale_f32 v159, s[6:7], v158, v158, v152
	v_rcp_f32_e32 v160, v159
	s_nop 0
	v_fma_f32 v161, -v159, v160, 1.0
	v_fmac_f32_e32 v160, v161, v160
	v_div_scale_f32 v161, vcc, v152, v158, v152
	v_mul_f32_e32 v162, v161, v160
	v_fma_f32 v163, -v159, v162, v161
	v_fmac_f32_e32 v162, v163, v160
	v_fma_f32 v159, -v159, v162, v161
	v_div_fmas_f32 v159, v159, v160, v162
	v_div_fixup_f32 v158, v159, v158, v152
	v_mul_f32_e32 v152, 0xbfb8aa3b, v155
	v_exp_f32_e32 v152, v152
	s_nop 0
	v_add_f32_e32 v152, 1.0, v152
	v_div_scale_f32 v159, s[6:7], v152, v152, v155
	v_rcp_f32_e32 v160, v159
	s_nop 0
	v_fma_f32 v161, -v159, v160, 1.0
	v_fmac_f32_e32 v160, v161, v160
	v_div_scale_f32 v161, vcc, v155, v152, v155
	v_mul_f32_e32 v162, v161, v160
	v_fma_f32 v163, -v159, v162, v161
	v_fmac_f32_e32 v162, v163, v160
	v_fma_f32 v159, -v159, v162, v161
	v_div_fmas_f32 v159, v159, v160, v162
	v_div_fixup_f32 v155, v159, v152, v155
	v_mul_f32_e32 v152, 0xbfb8aa3b, v153
	v_exp_f32_e32 v152, v152
	s_nop 0
	v_add_f32_e32 v152, 1.0, v152
	v_div_scale_f32 v159, s[6:7], v152, v152, v153
	v_rcp_f32_e32 v160, v159
	s_nop 0
	v_fma_f32 v161, -v159, v160, 1.0
	v_fmac_f32_e32 v160, v161, v160
	v_div_scale_f32 v161, vcc, v153, v152, v153
	v_mul_f32_e32 v162, v161, v160
	v_fma_f32 v163, -v159, v162, v161
	v_fmac_f32_e32 v162, v163, v160
	v_fma_f32 v159, -v159, v162, v161
	v_div_fmas_f32 v159, v159, v160, v162
	v_div_fixup_f32 v159, v159, v152, v153
	v_cvt_pk_bf16_f32 v152, v156, v157
	v_cvt_pk_bf16_f32 v153, v154, v155
	v_cvt_pk_bf16_f32 v154, v148, v149
	v_cvt_pk_bf16_f32 v155, v158, v159
	global_store_dwordx4 v[150:151], v[152:155], off offset:256
	v_add_u32_e32 v150, s13, v169
	v_ashrrev_i32_e32 v151, 31, v150
	v_lshl_add_u64 v[148:149], v[150:151], 2, s[10:11]
	global_load_dword v148, v[148:149], off
	v_lshlrev_b64 v[150:151], 13, v[150:151]
	v_lshl_add_u64 v[150:151], s[28:29], 0, v[150:151]
	v_lshl_add_u64 v[150:151], v[150:151], 0, s[0:1]
	v_lshl_add_u64 v[150:151], v[150:151], 0, v[0:1]
	s_waitcnt vmcnt(0) lgkmcnt(0)
	v_fmamk_f32 v148, v148, 0x3a000000, v207
	v_cmp_gt_f32_e32 vcc, s87, v148
	v_mul_f32_e32 v149, 0x4b800000, v148
	s_nop 0
	v_cndmask_b32_e32 v148, v148, v149, vcc
	v_rsq_f32_e32 v148, v148
	s_nop 0
	v_mul_f32_e32 v149, 0x45800000, v148
	v_cndmask_b32_e32 v148, v148, v149, vcc
	v_pk_mul_f32 v[156:157], v[46:47], v[148:149] op_sel_hi:[1,0]
	v_pk_mul_f32 v[154:155], v[48:49], v[148:149] op_sel_hi:[1,0]
	v_pk_mul_f32 v[152:153], v[40:41], v[148:149] op_sel_hi:[1,0]
	v_pk_mul_f32 v[158:159], v[38:39], v[148:149] op_sel_hi:[1,0]
	v_mul_f32_e32 v149, 0xbfb8aa3b, v156
	v_exp_f32_e32 v149, v149
	s_nop 0
	v_add_f32_e32 v149, 1.0, v149
	v_div_scale_f32 v160, s[6:7], v149, v149, v156
	v_rcp_f32_e32 v161, v160
	s_nop 0
	v_fma_f32 v162, -v160, v161, 1.0
	v_fmac_f32_e32 v161, v162, v161
	v_div_scale_f32 v162, vcc, v156, v149, v156
	v_mul_f32_e32 v163, v162, v161
	v_fma_f32 v181, -v160, v163, v162
	v_fmac_f32_e32 v163, v181, v161
	v_fma_f32 v160, -v160, v163, v162
	v_div_fmas_f32 v160, v160, v161, v163
	v_div_fixup_f32 v149, v160, v149, v156
	v_mul_f32_e32 v156, 0xbfb8aa3b, v158
	v_exp_f32_e32 v156, v156
	s_nop 0
	v_add_f32_e32 v156, 1.0, v156
	v_div_scale_f32 v160, s[6:7], v156, v156, v158
	v_rcp_f32_e32 v161, v160
	s_nop 0
	v_fma_f32 v162, -v160, v161, 1.0
	v_fmac_f32_e32 v161, v162, v161
	v_div_scale_f32 v162, vcc, v158, v156, v158
	v_mul_f32_e32 v163, v162, v161
	v_fma_f32 v181, -v160, v163, v162
	v_fmac_f32_e32 v163, v181, v161
	v_fma_f32 v160, -v160, v163, v162
	v_div_fmas_f32 v160, v160, v161, v163
	v_div_fixup_f32 v156, v160, v156, v158
	v_mul_f32_e32 v158, 0xbfb8aa3b, v157
	v_exp_f32_e32 v158, v158
	s_nop 0
	v_add_f32_e32 v158, 1.0, v158
	v_div_scale_f32 v160, s[6:7], v158, v158, v157
	v_rcp_f32_e32 v161, v160
	s_nop 0
	v_fma_f32 v162, -v160, v161, 1.0
	v_fmac_f32_e32 v161, v162, v161
	v_div_scale_f32 v162, vcc, v157, v158, v157
	v_mul_f32_e32 v163, v162, v161
	v_fma_f32 v181, -v160, v163, v162
	v_fmac_f32_e32 v163, v181, v161
	v_fma_f32 v160, -v160, v163, v162
	v_div_fmas_f32 v160, v160, v161, v163
	v_div_fixup_f32 v157, v160, v158, v157
	v_mul_f32_e32 v158, 0xbfb8aa3b, v159
	v_exp_f32_e32 v158, v158
	s_nop 0
	v_add_f32_e32 v158, 1.0, v158
	v_div_scale_f32 v160, s[6:7], v158, v158, v159
	v_rcp_f32_e32 v161, v160
	s_nop 0
	v_fma_f32 v162, -v160, v161, 1.0
	v_fmac_f32_e32 v161, v162, v161
	v_div_scale_f32 v162, vcc, v159, v158, v159
	v_mul_f32_e32 v163, v162, v161
	v_fma_f32 v181, -v160, v163, v162
	v_fmac_f32_e32 v163, v181, v161
	v_fma_f32 v160, -v160, v163, v162
	v_div_fmas_f32 v160, v160, v161, v163
	v_div_fixup_f32 v158, v160, v158, v159
	v_mul_f32_e32 v159, 0xbfb8aa3b, v154
	v_exp_f32_e32 v159, v159
	s_nop 0
	v_add_f32_e32 v159, 1.0, v159
	v_div_scale_f32 v160, s[6:7], v159, v159, v154
	v_rcp_f32_e32 v161, v160
	s_nop 0
	v_fma_f32 v162, -v160, v161, 1.0
	v_fmac_f32_e32 v161, v162, v161
	v_div_scale_f32 v162, vcc, v154, v159, v154
	v_mul_f32_e32 v163, v162, v161
	v_fma_f32 v181, -v160, v163, v162
	v_fmac_f32_e32 v163, v181, v161
	v_fma_f32 v160, -v160, v163, v162
	v_div_fmas_f32 v160, v160, v161, v163
	v_div_fixup_f32 v154, v160, v159, v154
	v_mul_f32_e32 v159, 0xbfb8aa3b, v152
	v_exp_f32_e32 v159, v159
	s_nop 0
	v_add_f32_e32 v159, 1.0, v159
	v_div_scale_f32 v160, s[6:7], v159, v159, v152
	v_rcp_f32_e32 v161, v160
	s_nop 0
	v_fma_f32 v162, -v160, v161, 1.0
	v_fmac_f32_e32 v161, v162, v161
	v_div_scale_f32 v162, vcc, v152, v159, v152
	v_mul_f32_e32 v163, v162, v161
	v_fma_f32 v181, -v160, v163, v162
	v_fmac_f32_e32 v163, v181, v161
	v_fma_f32 v160, -v160, v163, v162
	v_div_fmas_f32 v160, v160, v161, v163
	v_div_fixup_f32 v159, v160, v159, v152
	v_mul_f32_e32 v152, 0xbfb8aa3b, v155
	v_exp_f32_e32 v152, v152
	s_nop 0
	v_add_f32_e32 v152, 1.0, v152
	v_div_scale_f32 v160, s[6:7], v152, v152, v155
	v_rcp_f32_e32 v161, v160
	s_nop 0
	v_fma_f32 v162, -v160, v161, 1.0
	v_fmac_f32_e32 v161, v162, v161
	v_div_scale_f32 v162, vcc, v155, v152, v155
	v_mul_f32_e32 v163, v162, v161
	v_fma_f32 v181, -v160, v163, v162
	v_fmac_f32_e32 v163, v181, v161
	v_fma_f32 v160, -v160, v163, v162
	v_div_fmas_f32 v160, v160, v161, v163
	v_div_fixup_f32 v155, v160, v152, v155
	v_mul_f32_e32 v152, 0xbfb8aa3b, v153
	v_exp_f32_e32 v152, v152
	s_nop 0
	v_add_f32_e32 v152, 1.0, v152
	v_div_scale_f32 v160, s[6:7], v152, v152, v153
	v_rcp_f32_e32 v161, v160
	s_nop 0
	v_fma_f32 v162, -v160, v161, 1.0
	v_fmac_f32_e32 v161, v162, v161
	v_div_scale_f32 v162, vcc, v153, v152, v153
	v_mul_f32_e32 v163, v162, v161
	v_fma_f32 v181, -v160, v163, v162
	v_fmac_f32_e32 v163, v181, v161
	v_fma_f32 v160, -v160, v163, v162
	v_div_fmas_f32 v160, v160, v161, v163
	v_div_fixup_f32 v160, v160, v152, v153
	v_cvt_pk_bf16_f32 v152, v149, v157
	v_cvt_pk_bf16_f32 v153, v154, v155
	v_cvt_pk_bf16_f32 v154, v156, v158
	v_pk_mul_f32 v[156:157], v[42:43], v[148:149] op_sel_hi:[1,0]
	v_cvt_pk_bf16_f32 v155, v159, v160
	global_store_dwordx4 v[150:151], v[152:155], off
	v_mul_f32_e32 v158, 0xbfb8aa3b, v156
	v_exp_f32_e32 v158, v158
	v_pk_mul_f32 v[154:155], v[44:45], v[148:149] op_sel_hi:[1,0]
	v_pk_mul_f32 v[152:153], v[36:37], v[148:149] op_sel_hi:[1,0]
	v_pk_mul_f32 v[148:149], v[34:35], v[148:149] op_sel_hi:[1,0]
	v_add_f32_e32 v158, 1.0, v158
	v_div_scale_f32 v159, s[6:7], v158, v158, v156
	v_rcp_f32_e32 v160, v159
	s_nop 0
	v_fma_f32 v161, -v159, v160, 1.0
	v_fmac_f32_e32 v160, v161, v160
	v_div_scale_f32 v161, vcc, v156, v158, v156
	v_mul_f32_e32 v162, v161, v160
	v_fma_f32 v163, -v159, v162, v161
	v_fmac_f32_e32 v162, v163, v160
	v_fma_f32 v159, -v159, v162, v161
	v_div_fmas_f32 v159, v159, v160, v162
	v_div_fixup_f32 v156, v159, v158, v156
	v_mul_f32_e32 v158, 0xbfb8aa3b, v148
	v_exp_f32_e32 v158, v158
	s_nop 0
	v_add_f32_e32 v158, 1.0, v158
	v_div_scale_f32 v159, s[6:7], v158, v158, v148
	v_rcp_f32_e32 v160, v159
	s_nop 0
	v_fma_f32 v161, -v159, v160, 1.0
	v_fmac_f32_e32 v160, v161, v160
	v_div_scale_f32 v161, vcc, v148, v158, v148
	v_mul_f32_e32 v162, v161, v160
	v_fma_f32 v163, -v159, v162, v161
	v_fmac_f32_e32 v162, v163, v160
	v_fma_f32 v159, -v159, v162, v161
	v_div_fmas_f32 v159, v159, v160, v162
	v_div_fixup_f32 v148, v159, v158, v148
	v_mul_f32_e32 v158, 0xbfb8aa3b, v157
	v_exp_f32_e32 v158, v158
	s_nop 0
	v_add_f32_e32 v158, 1.0, v158
	v_div_scale_f32 v159, s[6:7], v158, v158, v157
	v_rcp_f32_e32 v160, v159
	s_nop 0
	v_fma_f32 v161, -v159, v160, 1.0
	v_fmac_f32_e32 v160, v161, v160
	v_div_scale_f32 v161, vcc, v157, v158, v157
	v_mul_f32_e32 v162, v161, v160
	v_fma_f32 v163, -v159, v162, v161
	v_fmac_f32_e32 v162, v163, v160
	v_fma_f32 v159, -v159, v162, v161
	v_div_fmas_f32 v159, v159, v160, v162
	v_div_fixup_f32 v157, v159, v158, v157
	v_mul_f32_e32 v158, 0xbfb8aa3b, v149
	v_exp_f32_e32 v158, v158
	s_nop 0
	v_add_f32_e32 v158, 1.0, v158
	v_div_scale_f32 v159, s[6:7], v158, v158, v149
	v_rcp_f32_e32 v160, v159
	s_nop 0
	v_fma_f32 v161, -v159, v160, 1.0
	v_fmac_f32_e32 v160, v161, v160
	v_div_scale_f32 v161, vcc, v149, v158, v149
	v_mul_f32_e32 v162, v161, v160
	v_fma_f32 v163, -v159, v162, v161
	v_fmac_f32_e32 v162, v163, v160
	v_fma_f32 v159, -v159, v162, v161
	v_div_fmas_f32 v159, v159, v160, v162
	v_div_fixup_f32 v149, v159, v158, v149
	v_mul_f32_e32 v158, 0xbfb8aa3b, v154
	v_exp_f32_e32 v158, v158
	s_nop 0
	v_add_f32_e32 v158, 1.0, v158
	v_div_scale_f32 v159, s[6:7], v158, v158, v154
	v_rcp_f32_e32 v160, v159
	s_nop 0
	v_fma_f32 v161, -v159, v160, 1.0
	v_fmac_f32_e32 v160, v161, v160
	v_div_scale_f32 v161, vcc, v154, v158, v154
	v_mul_f32_e32 v162, v161, v160
	v_fma_f32 v163, -v159, v162, v161
	v_fmac_f32_e32 v162, v163, v160
	v_fma_f32 v159, -v159, v162, v161
	v_div_fmas_f32 v159, v159, v160, v162
	v_div_fixup_f32 v154, v159, v158, v154
	v_mul_f32_e32 v158, 0xbfb8aa3b, v152
	v_exp_f32_e32 v158, v158
	s_nop 0
	v_add_f32_e32 v158, 1.0, v158
	v_div_scale_f32 v159, s[6:7], v158, v158, v152
	v_rcp_f32_e32 v160, v159
	s_nop 0
	v_fma_f32 v161, -v159, v160, 1.0
	v_fmac_f32_e32 v160, v161, v160
	v_div_scale_f32 v161, vcc, v152, v158, v152
	v_mul_f32_e32 v162, v161, v160
	v_fma_f32 v163, -v159, v162, v161
	v_fmac_f32_e32 v162, v163, v160
	v_fma_f32 v159, -v159, v162, v161
	v_div_fmas_f32 v159, v159, v160, v162
	v_div_fixup_f32 v158, v159, v158, v152
	v_mul_f32_e32 v152, 0xbfb8aa3b, v155
	v_exp_f32_e32 v152, v152
	s_nop 0
	v_add_f32_e32 v152, 1.0, v152
	v_div_scale_f32 v159, s[6:7], v152, v152, v155
	v_rcp_f32_e32 v160, v159
	s_nop 0
	v_fma_f32 v161, -v159, v160, 1.0
	v_fmac_f32_e32 v160, v161, v160
	v_div_scale_f32 v161, vcc, v155, v152, v155
	v_mul_f32_e32 v162, v161, v160
	v_fma_f32 v163, -v159, v162, v161
	v_fmac_f32_e32 v162, v163, v160
	v_fma_f32 v159, -v159, v162, v161
	v_div_fmas_f32 v159, v159, v160, v162
	v_div_fixup_f32 v155, v159, v152, v155
	v_mul_f32_e32 v152, 0xbfb8aa3b, v153
	v_exp_f32_e32 v152, v152
	s_nop 0
	v_add_f32_e32 v152, 1.0, v152
	v_div_scale_f32 v159, s[6:7], v152, v152, v153
	v_rcp_f32_e32 v160, v159
	s_nop 0
	v_fma_f32 v161, -v159, v160, 1.0
	v_fmac_f32_e32 v160, v161, v160
	v_div_scale_f32 v161, vcc, v153, v152, v153
	v_mul_f32_e32 v162, v161, v160
	v_fma_f32 v163, -v159, v162, v161
	v_fmac_f32_e32 v162, v163, v160
	v_fma_f32 v159, -v159, v162, v161
	v_div_fmas_f32 v159, v159, v160, v162
	v_div_fixup_f32 v159, v159, v152, v153
	v_cvt_pk_bf16_f32 v152, v156, v157
	v_cvt_pk_bf16_f32 v153, v154, v155
	v_cvt_pk_bf16_f32 v154, v148, v149
	v_cvt_pk_bf16_f32 v155, v158, v159
	global_store_dwordx4 v[150:151], v[152:155], off offset:256
	v_add_u32_e32 v150, s13, v170
	v_ashrrev_i32_e32 v151, 31, v150
	v_lshl_add_u64 v[148:149], v[150:151], 2, s[10:11]
	global_load_dword v148, v[148:149], off
	v_lshlrev_b64 v[150:151], 13, v[150:151]
	v_lshl_add_u64 v[150:151], s[28:29], 0, v[150:151]
	v_lshl_add_u64 v[150:151], v[150:151], 0, s[0:1]
	v_lshl_add_u64 v[150:151], v[150:151], 0, v[0:1]
	s_waitcnt vmcnt(0) lgkmcnt(0)
	v_fmamk_f32 v148, v148, 0x3a000000, v207
	v_cmp_gt_f32_e32 vcc, s87, v148
	v_mul_f32_e32 v149, 0x4b800000, v148
	s_nop 0
	v_cndmask_b32_e32 v148, v148, v149, vcc
	v_rsq_f32_e32 v148, v148
	s_nop 0
	v_mul_f32_e32 v149, 0x45800000, v148
	v_cndmask_b32_e32 v148, v148, v149, vcc
	v_pk_mul_f32 v[156:157], v[30:31], v[148:149] op_sel_hi:[1,0]
	v_pk_mul_f32 v[154:155], v[32:33], v[148:149] op_sel_hi:[1,0]
	v_pk_mul_f32 v[152:153], v[24:25], v[148:149] op_sel_hi:[1,0]
	v_pk_mul_f32 v[158:159], v[22:23], v[148:149] op_sel_hi:[1,0]
	v_mul_f32_e32 v149, 0xbfb8aa3b, v156
	v_exp_f32_e32 v149, v149
	s_nop 0
	v_add_f32_e32 v149, 1.0, v149
	v_div_scale_f32 v160, s[6:7], v149, v149, v156
	v_rcp_f32_e32 v161, v160
	s_nop 0
	v_fma_f32 v162, -v160, v161, 1.0
	v_fmac_f32_e32 v161, v162, v161
	v_div_scale_f32 v162, vcc, v156, v149, v156
	v_mul_f32_e32 v163, v162, v161
	v_fma_f32 v181, -v160, v163, v162
	v_fmac_f32_e32 v163, v181, v161
	v_fma_f32 v160, -v160, v163, v162
	v_div_fmas_f32 v160, v160, v161, v163
	v_div_fixup_f32 v149, v160, v149, v156
	v_mul_f32_e32 v156, 0xbfb8aa3b, v158
	v_exp_f32_e32 v156, v156
	s_nop 0
	v_add_f32_e32 v156, 1.0, v156
	v_div_scale_f32 v160, s[6:7], v156, v156, v158
	v_rcp_f32_e32 v161, v160
	s_nop 0
	v_fma_f32 v162, -v160, v161, 1.0
	v_fmac_f32_e32 v161, v162, v161
	v_div_scale_f32 v162, vcc, v158, v156, v158
	v_mul_f32_e32 v163, v162, v161
	v_fma_f32 v181, -v160, v163, v162
	v_fmac_f32_e32 v163, v181, v161
	v_fma_f32 v160, -v160, v163, v162
	v_div_fmas_f32 v160, v160, v161, v163
	v_div_fixup_f32 v156, v160, v156, v158
	v_mul_f32_e32 v158, 0xbfb8aa3b, v157
	v_exp_f32_e32 v158, v158
	s_nop 0
	v_add_f32_e32 v158, 1.0, v158
	v_div_scale_f32 v160, s[6:7], v158, v158, v157
	v_rcp_f32_e32 v161, v160
	s_nop 0
	v_fma_f32 v162, -v160, v161, 1.0
	v_fmac_f32_e32 v161, v162, v161
	v_div_scale_f32 v162, vcc, v157, v158, v157
	v_mul_f32_e32 v163, v162, v161
	v_fma_f32 v181, -v160, v163, v162
	v_fmac_f32_e32 v163, v181, v161
	v_fma_f32 v160, -v160, v163, v162
	v_div_fmas_f32 v160, v160, v161, v163
	v_div_fixup_f32 v157, v160, v158, v157
	v_mul_f32_e32 v158, 0xbfb8aa3b, v159
	v_exp_f32_e32 v158, v158
	s_nop 0
	v_add_f32_e32 v158, 1.0, v158
	v_div_scale_f32 v160, s[6:7], v158, v158, v159
	v_rcp_f32_e32 v161, v160
	s_nop 0
	v_fma_f32 v162, -v160, v161, 1.0
	v_fmac_f32_e32 v161, v162, v161
	v_div_scale_f32 v162, vcc, v159, v158, v159
	v_mul_f32_e32 v163, v162, v161
	v_fma_f32 v181, -v160, v163, v162
	v_fmac_f32_e32 v163, v181, v161
	v_fma_f32 v160, -v160, v163, v162
	v_div_fmas_f32 v160, v160, v161, v163
	v_div_fixup_f32 v158, v160, v158, v159
	v_mul_f32_e32 v159, 0xbfb8aa3b, v154
	v_exp_f32_e32 v159, v159
	s_nop 0
	v_add_f32_e32 v159, 1.0, v159
	v_div_scale_f32 v160, s[6:7], v159, v159, v154
	v_rcp_f32_e32 v161, v160
	s_nop 0
	v_fma_f32 v162, -v160, v161, 1.0
	v_fmac_f32_e32 v161, v162, v161
	v_div_scale_f32 v162, vcc, v154, v159, v154
	v_mul_f32_e32 v163, v162, v161
	v_fma_f32 v181, -v160, v163, v162
	v_fmac_f32_e32 v163, v181, v161
	v_fma_f32 v160, -v160, v163, v162
	v_div_fmas_f32 v160, v160, v161, v163
	v_div_fixup_f32 v154, v160, v159, v154
	v_mul_f32_e32 v159, 0xbfb8aa3b, v152
	v_exp_f32_e32 v159, v159
	s_nop 0
	v_add_f32_e32 v159, 1.0, v159
	v_div_scale_f32 v160, s[6:7], v159, v159, v152
	v_rcp_f32_e32 v161, v160
	s_nop 0
	v_fma_f32 v162, -v160, v161, 1.0
	v_fmac_f32_e32 v161, v162, v161
	v_div_scale_f32 v162, vcc, v152, v159, v152
	v_mul_f32_e32 v163, v162, v161
	v_fma_f32 v181, -v160, v163, v162
	v_fmac_f32_e32 v163, v181, v161
	v_fma_f32 v160, -v160, v163, v162
	v_div_fmas_f32 v160, v160, v161, v163
	v_div_fixup_f32 v159, v160, v159, v152
	v_mul_f32_e32 v152, 0xbfb8aa3b, v155
	v_exp_f32_e32 v152, v152
	s_nop 0
	v_add_f32_e32 v152, 1.0, v152
	v_div_scale_f32 v160, s[6:7], v152, v152, v155
	v_rcp_f32_e32 v161, v160
	s_nop 0
	v_fma_f32 v162, -v160, v161, 1.0
	v_fmac_f32_e32 v161, v162, v161
	v_div_scale_f32 v162, vcc, v155, v152, v155
	v_mul_f32_e32 v163, v162, v161
	v_fma_f32 v181, -v160, v163, v162
	v_fmac_f32_e32 v163, v181, v161
	v_fma_f32 v160, -v160, v163, v162
	v_div_fmas_f32 v160, v160, v161, v163
	v_div_fixup_f32 v155, v160, v152, v155
	v_mul_f32_e32 v152, 0xbfb8aa3b, v153
	v_exp_f32_e32 v152, v152
	s_nop 0
	v_add_f32_e32 v152, 1.0, v152
	v_div_scale_f32 v160, s[6:7], v152, v152, v153
	v_rcp_f32_e32 v161, v160
	s_nop 0
	v_fma_f32 v162, -v160, v161, 1.0
	v_fmac_f32_e32 v161, v162, v161
	v_div_scale_f32 v162, vcc, v153, v152, v153
	v_mul_f32_e32 v163, v162, v161
	v_fma_f32 v181, -v160, v163, v162
	v_fmac_f32_e32 v163, v181, v161
	v_fma_f32 v160, -v160, v163, v162
	v_div_fmas_f32 v160, v160, v161, v163
	v_div_fixup_f32 v160, v160, v152, v153
	v_cvt_pk_bf16_f32 v152, v149, v157
	v_cvt_pk_bf16_f32 v153, v154, v155
	v_cvt_pk_bf16_f32 v154, v156, v158
	v_pk_mul_f32 v[156:157], v[26:27], v[148:149] op_sel_hi:[1,0]
	v_cvt_pk_bf16_f32 v155, v159, v160
	global_store_dwordx4 v[150:151], v[152:155], off
	v_mul_f32_e32 v158, 0xbfb8aa3b, v156
	v_exp_f32_e32 v158, v158
	v_pk_mul_f32 v[154:155], v[28:29], v[148:149] op_sel_hi:[1,0]
	v_pk_mul_f32 v[152:153], v[20:21], v[148:149] op_sel_hi:[1,0]
	v_pk_mul_f32 v[148:149], v[18:19], v[148:149] op_sel_hi:[1,0]
	v_add_f32_e32 v158, 1.0, v158
	v_div_scale_f32 v159, s[6:7], v158, v158, v156
	v_rcp_f32_e32 v160, v159
	s_nop 0
	v_fma_f32 v161, -v159, v160, 1.0
	v_fmac_f32_e32 v160, v161, v160
	v_div_scale_f32 v161, vcc, v156, v158, v156
	v_mul_f32_e32 v162, v161, v160
	v_fma_f32 v163, -v159, v162, v161
	v_fmac_f32_e32 v162, v163, v160
	v_fma_f32 v159, -v159, v162, v161
	v_div_fmas_f32 v159, v159, v160, v162
	v_div_fixup_f32 v156, v159, v158, v156
	v_mul_f32_e32 v158, 0xbfb8aa3b, v148
	v_exp_f32_e32 v158, v158
	s_nop 0
	v_add_f32_e32 v158, 1.0, v158
	v_div_scale_f32 v159, s[6:7], v158, v158, v148
	v_rcp_f32_e32 v160, v159
	s_nop 0
	v_fma_f32 v161, -v159, v160, 1.0
	v_fmac_f32_e32 v160, v161, v160
	v_div_scale_f32 v161, vcc, v148, v158, v148
	v_mul_f32_e32 v162, v161, v160
	v_fma_f32 v163, -v159, v162, v161
	v_fmac_f32_e32 v162, v163, v160
	v_fma_f32 v159, -v159, v162, v161
	v_div_fmas_f32 v159, v159, v160, v162
	v_div_fixup_f32 v148, v159, v158, v148
	v_mul_f32_e32 v158, 0xbfb8aa3b, v157
	v_exp_f32_e32 v158, v158
	s_nop 0
	v_add_f32_e32 v158, 1.0, v158
	v_div_scale_f32 v159, s[6:7], v158, v158, v157
	v_rcp_f32_e32 v160, v159
	s_nop 0
	v_fma_f32 v161, -v159, v160, 1.0
	v_fmac_f32_e32 v160, v161, v160
	v_div_scale_f32 v161, vcc, v157, v158, v157
	v_mul_f32_e32 v162, v161, v160
	v_fma_f32 v163, -v159, v162, v161
	v_fmac_f32_e32 v162, v163, v160
	v_fma_f32 v159, -v159, v162, v161
	v_div_fmas_f32 v159, v159, v160, v162
	v_div_fixup_f32 v157, v159, v158, v157
	v_mul_f32_e32 v158, 0xbfb8aa3b, v149
	v_exp_f32_e32 v158, v158
	s_nop 0
	v_add_f32_e32 v158, 1.0, v158
	v_div_scale_f32 v159, s[6:7], v158, v158, v149
	v_rcp_f32_e32 v160, v159
	s_nop 0
	v_fma_f32 v161, -v159, v160, 1.0
	v_fmac_f32_e32 v160, v161, v160
	v_div_scale_f32 v161, vcc, v149, v158, v149
	v_mul_f32_e32 v162, v161, v160
	v_fma_f32 v163, -v159, v162, v161
	v_fmac_f32_e32 v162, v163, v160
	v_fma_f32 v159, -v159, v162, v161
	v_div_fmas_f32 v159, v159, v160, v162
	v_div_fixup_f32 v149, v159, v158, v149
	v_mul_f32_e32 v158, 0xbfb8aa3b, v154
	v_exp_f32_e32 v158, v158
	s_nop 0
	v_add_f32_e32 v158, 1.0, v158
	v_div_scale_f32 v159, s[6:7], v158, v158, v154
	v_rcp_f32_e32 v160, v159
	s_nop 0
	v_fma_f32 v161, -v159, v160, 1.0
	v_fmac_f32_e32 v160, v161, v160
	v_div_scale_f32 v161, vcc, v154, v158, v154
	v_mul_f32_e32 v162, v161, v160
	v_fma_f32 v163, -v159, v162, v161
	v_fmac_f32_e32 v162, v163, v160
	v_fma_f32 v159, -v159, v162, v161
	v_div_fmas_f32 v159, v159, v160, v162
	v_div_fixup_f32 v154, v159, v158, v154
	v_mul_f32_e32 v158, 0xbfb8aa3b, v152
	v_exp_f32_e32 v158, v158
	s_nop 0
	v_add_f32_e32 v158, 1.0, v158
	v_div_scale_f32 v159, s[6:7], v158, v158, v152
	v_rcp_f32_e32 v160, v159
	s_nop 0
	v_fma_f32 v161, -v159, v160, 1.0
	v_fmac_f32_e32 v160, v161, v160
	v_div_scale_f32 v161, vcc, v152, v158, v152
	v_mul_f32_e32 v162, v161, v160
	v_fma_f32 v163, -v159, v162, v161
	v_fmac_f32_e32 v162, v163, v160
	v_fma_f32 v159, -v159, v162, v161
	v_div_fmas_f32 v159, v159, v160, v162
	v_div_fixup_f32 v158, v159, v158, v152
	v_mul_f32_e32 v152, 0xbfb8aa3b, v155
	v_exp_f32_e32 v152, v152
	s_nop 0
	v_add_f32_e32 v152, 1.0, v152
	v_div_scale_f32 v159, s[6:7], v152, v152, v155
	v_rcp_f32_e32 v160, v159
	s_nop 0
	v_fma_f32 v161, -v159, v160, 1.0
	v_fmac_f32_e32 v160, v161, v160
	v_div_scale_f32 v161, vcc, v155, v152, v155
	v_mul_f32_e32 v162, v161, v160
	v_fma_f32 v163, -v159, v162, v161
	v_fmac_f32_e32 v162, v163, v160
	v_fma_f32 v159, -v159, v162, v161
	v_div_fmas_f32 v159, v159, v160, v162
	v_div_fixup_f32 v155, v159, v152, v155
	v_mul_f32_e32 v152, 0xbfb8aa3b, v153
	v_exp_f32_e32 v152, v152
	s_nop 0
	v_add_f32_e32 v152, 1.0, v152
	v_div_scale_f32 v159, s[6:7], v152, v152, v153
	v_rcp_f32_e32 v160, v159
	s_nop 0
	v_fma_f32 v161, -v159, v160, 1.0
	v_fmac_f32_e32 v160, v161, v160
	v_div_scale_f32 v161, vcc, v153, v152, v153
	v_mul_f32_e32 v162, v161, v160
	v_fma_f32 v163, -v159, v162, v161
	v_fmac_f32_e32 v162, v163, v160
	v_fma_f32 v159, -v159, v162, v161
	v_div_fmas_f32 v159, v159, v160, v162
	v_div_fixup_f32 v159, v159, v152, v153
	v_cvt_pk_bf16_f32 v152, v156, v157
	v_cvt_pk_bf16_f32 v153, v154, v155
	v_cvt_pk_bf16_f32 v154, v148, v149
	v_cvt_pk_bf16_f32 v155, v158, v159
	global_store_dwordx4 v[150:151], v[152:155], off offset:256
	v_add_u32_e32 v150, s13, v171
	v_ashrrev_i32_e32 v151, 31, v150
	v_lshl_add_u64 v[148:149], v[150:151], 2, s[10:11]
	global_load_dword v148, v[148:149], off
	v_lshlrev_b64 v[150:151], 13, v[150:151]
	v_lshl_add_u64 v[150:151], s[28:29], 0, v[150:151]
	v_lshl_add_u64 v[150:151], v[150:151], 0, s[0:1]
	v_lshl_add_u64 v[150:151], v[150:151], 0, v[0:1]
	s_waitcnt vmcnt(0) lgkmcnt(0)
	v_fmamk_f32 v148, v148, 0x3a000000, v207
	v_cmp_gt_f32_e32 vcc, s87, v148
	v_mul_f32_e32 v149, 0x4b800000, v148
	s_nop 0
	v_cndmask_b32_e32 v148, v148, v149, vcc
	v_rsq_f32_e32 v148, v148
	s_nop 0
	v_mul_f32_e32 v149, 0x45800000, v148
	v_cndmask_b32_e32 v148, v148, v149, vcc
	v_pk_mul_f32 v[156:157], v[14:15], v[148:149] op_sel_hi:[1,0]
	v_pk_mul_f32 v[154:155], v[16:17], v[148:149] op_sel_hi:[1,0]
	v_pk_mul_f32 v[152:153], v[8:9], v[148:149] op_sel_hi:[1,0]
	v_pk_mul_f32 v[158:159], v[6:7], v[148:149] op_sel_hi:[1,0]
	v_mul_f32_e32 v149, 0xbfb8aa3b, v156
	v_exp_f32_e32 v149, v149
	s_nop 0
	v_add_f32_e32 v149, 1.0, v149
	v_div_scale_f32 v160, s[6:7], v149, v149, v156
	v_rcp_f32_e32 v161, v160
	s_nop 0
	v_fma_f32 v162, -v160, v161, 1.0
	v_fmac_f32_e32 v161, v162, v161
	v_div_scale_f32 v162, vcc, v156, v149, v156
	v_mul_f32_e32 v163, v162, v161
	v_fma_f32 v181, -v160, v163, v162
	v_fmac_f32_e32 v163, v181, v161
	v_fma_f32 v160, -v160, v163, v162
	v_div_fmas_f32 v160, v160, v161, v163
	v_div_fixup_f32 v149, v160, v149, v156
	v_mul_f32_e32 v156, 0xbfb8aa3b, v158
	v_exp_f32_e32 v156, v156
	s_nop 0
	v_add_f32_e32 v156, 1.0, v156
	v_div_scale_f32 v160, s[6:7], v156, v156, v158
	v_rcp_f32_e32 v161, v160
	s_nop 0
	v_fma_f32 v162, -v160, v161, 1.0
	v_fmac_f32_e32 v161, v162, v161
	v_div_scale_f32 v162, vcc, v158, v156, v158
	v_mul_f32_e32 v163, v162, v161
	v_fma_f32 v181, -v160, v163, v162
	v_fmac_f32_e32 v163, v181, v161
	v_fma_f32 v160, -v160, v163, v162
	v_div_fmas_f32 v160, v160, v161, v163
	v_div_fixup_f32 v156, v160, v156, v158
	v_mul_f32_e32 v158, 0xbfb8aa3b, v157
	v_exp_f32_e32 v158, v158
	s_nop 0
	v_add_f32_e32 v158, 1.0, v158
	v_div_scale_f32 v160, s[6:7], v158, v158, v157
	v_rcp_f32_e32 v161, v160
	s_nop 0
	v_fma_f32 v162, -v160, v161, 1.0
	v_fmac_f32_e32 v161, v162, v161
	v_div_scale_f32 v162, vcc, v157, v158, v157
	v_mul_f32_e32 v163, v162, v161
	v_fma_f32 v181, -v160, v163, v162
	v_fmac_f32_e32 v163, v181, v161
	v_fma_f32 v160, -v160, v163, v162
	v_div_fmas_f32 v160, v160, v161, v163
	v_div_fixup_f32 v157, v160, v158, v157
	v_mul_f32_e32 v158, 0xbfb8aa3b, v159
	v_exp_f32_e32 v158, v158
	s_nop 0
	v_add_f32_e32 v158, 1.0, v158
	v_div_scale_f32 v160, s[6:7], v158, v158, v159
	v_rcp_f32_e32 v161, v160
	s_nop 0
	v_fma_f32 v162, -v160, v161, 1.0
	v_fmac_f32_e32 v161, v162, v161
	v_div_scale_f32 v162, vcc, v159, v158, v159
	v_mul_f32_e32 v163, v162, v161
	v_fma_f32 v181, -v160, v163, v162
	v_fmac_f32_e32 v163, v181, v161
	v_fma_f32 v160, -v160, v163, v162
	v_div_fmas_f32 v160, v160, v161, v163
	v_div_fixup_f32 v158, v160, v158, v159
	v_mul_f32_e32 v159, 0xbfb8aa3b, v154
	v_exp_f32_e32 v159, v159
	s_nop 0
	v_add_f32_e32 v159, 1.0, v159
	v_div_scale_f32 v160, s[6:7], v159, v159, v154
	v_rcp_f32_e32 v161, v160
	s_nop 0
	v_fma_f32 v162, -v160, v161, 1.0
	v_fmac_f32_e32 v161, v162, v161
	v_div_scale_f32 v162, vcc, v154, v159, v154
	v_mul_f32_e32 v163, v162, v161
	v_fma_f32 v181, -v160, v163, v162
	v_fmac_f32_e32 v163, v181, v161
	v_fma_f32 v160, -v160, v163, v162
	v_div_fmas_f32 v160, v160, v161, v163
	v_div_fixup_f32 v154, v160, v159, v154
	v_mul_f32_e32 v159, 0xbfb8aa3b, v152
	v_exp_f32_e32 v159, v159
	s_nop 0
	v_add_f32_e32 v159, 1.0, v159
	v_div_scale_f32 v160, s[6:7], v159, v159, v152
	v_rcp_f32_e32 v161, v160
	s_nop 0
	v_fma_f32 v162, -v160, v161, 1.0
	v_fmac_f32_e32 v161, v162, v161
	v_div_scale_f32 v162, vcc, v152, v159, v152
	v_mul_f32_e32 v163, v162, v161
	v_fma_f32 v181, -v160, v163, v162
	v_fmac_f32_e32 v163, v181, v161
	v_fma_f32 v160, -v160, v163, v162
	v_div_fmas_f32 v160, v160, v161, v163
	v_div_fixup_f32 v159, v160, v159, v152
	v_mul_f32_e32 v152, 0xbfb8aa3b, v155
	v_exp_f32_e32 v152, v152
	s_nop 0
	v_add_f32_e32 v152, 1.0, v152
	v_div_scale_f32 v160, s[6:7], v152, v152, v155
	v_rcp_f32_e32 v161, v160
	s_nop 0
	v_fma_f32 v162, -v160, v161, 1.0
	v_fmac_f32_e32 v161, v162, v161
	v_div_scale_f32 v162, vcc, v155, v152, v155
	v_mul_f32_e32 v163, v162, v161
	v_fma_f32 v181, -v160, v163, v162
	v_fmac_f32_e32 v163, v181, v161
	v_fma_f32 v160, -v160, v163, v162
	v_div_fmas_f32 v160, v160, v161, v163
	v_div_fixup_f32 v155, v160, v152, v155
	v_mul_f32_e32 v152, 0xbfb8aa3b, v153
	v_exp_f32_e32 v152, v152
	s_nop 0
	v_add_f32_e32 v152, 1.0, v152
	v_div_scale_f32 v160, s[6:7], v152, v152, v153
	v_rcp_f32_e32 v161, v160
	s_nop 0
	v_fma_f32 v162, -v160, v161, 1.0
	v_fmac_f32_e32 v161, v162, v161
	v_div_scale_f32 v162, vcc, v153, v152, v153
	v_mul_f32_e32 v163, v162, v161
	v_fma_f32 v181, -v160, v163, v162
	v_fmac_f32_e32 v163, v181, v161
	v_fma_f32 v160, -v160, v163, v162
	v_div_fmas_f32 v160, v160, v161, v163
	v_div_fixup_f32 v160, v160, v152, v153
	v_cvt_pk_bf16_f32 v152, v149, v157
	v_cvt_pk_bf16_f32 v153, v154, v155
	v_cvt_pk_bf16_f32 v154, v156, v158
	v_pk_mul_f32 v[156:157], v[10:11], v[148:149] op_sel_hi:[1,0]
	v_cvt_pk_bf16_f32 v155, v159, v160
	global_store_dwordx4 v[150:151], v[152:155], off
	v_mul_f32_e32 v0, 0xbfb8aa3b, v156
	v_exp_f32_e32 v0, v0
	v_pk_mul_f32 v[154:155], v[12:13], v[148:149] op_sel_hi:[1,0]
	v_pk_mul_f32 v[152:153], v[4:5], v[148:149] op_sel_hi:[1,0]
	v_pk_mul_f32 v[148:149], v[2:3], v[148:149] op_sel_hi:[1,0]
	v_add_f32_e32 v0, 1.0, v0
	v_div_scale_f32 v158, s[0:1], v0, v0, v156
	v_rcp_f32_e32 v159, v158
	s_nop 0
	v_fma_f32 v160, -v158, v159, 1.0
	v_fmac_f32_e32 v159, v160, v159
	v_div_scale_f32 v160, vcc, v156, v0, v156
	v_mul_f32_e32 v161, v160, v159
	v_fma_f32 v162, -v158, v161, v160
	v_fmac_f32_e32 v161, v162, v159
	v_fma_f32 v158, -v158, v161, v160
	v_div_fmas_f32 v158, v158, v159, v161
	v_div_fixup_f32 v0, v158, v0, v156
	v_mul_f32_e32 v156, 0xbfb8aa3b, v148
	v_exp_f32_e32 v156, v156
	s_nop 0
	v_add_f32_e32 v156, 1.0, v156
	v_div_scale_f32 v158, s[0:1], v156, v156, v148
	v_rcp_f32_e32 v159, v158
	s_nop 0
	v_fma_f32 v160, -v158, v159, 1.0
	v_fmac_f32_e32 v159, v160, v159
	v_div_scale_f32 v160, vcc, v148, v156, v148
	v_mul_f32_e32 v161, v160, v159
	v_fma_f32 v162, -v158, v161, v160
	v_fmac_f32_e32 v161, v162, v159
	v_fma_f32 v158, -v158, v161, v160
	v_div_fmas_f32 v158, v158, v159, v161
	v_div_fixup_f32 v148, v158, v156, v148
	v_mul_f32_e32 v156, 0xbfb8aa3b, v157
	v_exp_f32_e32 v156, v156
	s_nop 0
	v_add_f32_e32 v156, 1.0, v156
	v_div_scale_f32 v158, s[0:1], v156, v156, v157
	v_rcp_f32_e32 v159, v158
	s_nop 0
	v_fma_f32 v160, -v158, v159, 1.0
	v_fmac_f32_e32 v159, v160, v159
	v_div_scale_f32 v160, vcc, v157, v156, v157
	v_mul_f32_e32 v161, v160, v159
	v_fma_f32 v162, -v158, v161, v160
	v_fmac_f32_e32 v161, v162, v159
	v_fma_f32 v158, -v158, v161, v160
	v_div_fmas_f32 v158, v158, v159, v161
	v_div_fixup_f32 v156, v158, v156, v157
	v_mul_f32_e32 v157, 0xbfb8aa3b, v149
	v_exp_f32_e32 v157, v157
	s_nop 0
	v_add_f32_e32 v157, 1.0, v157
	v_div_scale_f32 v158, s[0:1], v157, v157, v149
	v_rcp_f32_e32 v159, v158
	s_nop 0
	v_fma_f32 v160, -v158, v159, 1.0
	v_fmac_f32_e32 v159, v160, v159
	v_div_scale_f32 v160, vcc, v149, v157, v149
	v_mul_f32_e32 v161, v160, v159
	v_fma_f32 v162, -v158, v161, v160
	v_fmac_f32_e32 v161, v162, v159
	v_fma_f32 v158, -v158, v161, v160
	v_div_fmas_f32 v158, v158, v159, v161
	v_div_fixup_f32 v149, v158, v157, v149
	v_mul_f32_e32 v157, 0xbfb8aa3b, v154
	v_exp_f32_e32 v157, v157
	s_nop 0
	v_add_f32_e32 v157, 1.0, v157
	v_div_scale_f32 v158, s[0:1], v157, v157, v154
	v_rcp_f32_e32 v159, v158
	s_nop 0
	v_fma_f32 v160, -v158, v159, 1.0
	v_fmac_f32_e32 v159, v160, v159
	v_div_scale_f32 v160, vcc, v154, v157, v154
	v_mul_f32_e32 v161, v160, v159
	v_fma_f32 v162, -v158, v161, v160
	v_fmac_f32_e32 v161, v162, v159
	v_fma_f32 v158, -v158, v161, v160
	v_div_fmas_f32 v158, v158, v159, v161
	v_div_fixup_f32 v154, v158, v157, v154
	v_mul_f32_e32 v157, 0xbfb8aa3b, v152
	v_exp_f32_e32 v157, v157
	s_nop 0
	v_add_f32_e32 v157, 1.0, v157
	v_div_scale_f32 v158, s[0:1], v157, v157, v152
	v_rcp_f32_e32 v159, v158
	s_nop 0
	v_fma_f32 v160, -v158, v159, 1.0
	v_fmac_f32_e32 v159, v160, v159
	v_div_scale_f32 v160, vcc, v152, v157, v152
	v_mul_f32_e32 v161, v160, v159
	v_fma_f32 v162, -v158, v161, v160
	v_fmac_f32_e32 v161, v162, v159
	v_fma_f32 v158, -v158, v161, v160
	v_div_fmas_f32 v158, v158, v159, v161
	v_div_fixup_f32 v157, v158, v157, v152
	v_mul_f32_e32 v152, 0xbfb8aa3b, v155
	v_exp_f32_e32 v152, v152
	s_nop 0
	v_add_f32_e32 v152, 1.0, v152
	v_div_scale_f32 v158, s[0:1], v152, v152, v155
	v_rcp_f32_e32 v159, v158
	s_nop 0
	v_fma_f32 v160, -v158, v159, 1.0
	v_fmac_f32_e32 v159, v160, v159
	v_div_scale_f32 v160, vcc, v155, v152, v155
	v_mul_f32_e32 v161, v160, v159
	v_fma_f32 v162, -v158, v161, v160
	v_fmac_f32_e32 v161, v162, v159
	v_fma_f32 v158, -v158, v161, v160
	v_div_fmas_f32 v158, v158, v159, v161
	v_div_fixup_f32 v155, v158, v152, v155
	v_mul_f32_e32 v152, 0xbfb8aa3b, v153
	v_exp_f32_e32 v152, v152
	s_nop 0
	v_add_f32_e32 v152, 1.0, v152
	v_div_scale_f32 v158, s[0:1], v152, v152, v153
	v_rcp_f32_e32 v159, v158
	s_mov_b64 s[0:1], 0
	v_fma_f32 v160, -v158, v159, 1.0
	v_fmac_f32_e32 v159, v160, v159
	v_div_scale_f32 v160, vcc, v153, v152, v153
	v_mul_f32_e32 v161, v160, v159
	v_fma_f32 v162, -v158, v161, v160
	v_fmac_f32_e32 v161, v162, v159
	v_fma_f32 v158, -v158, v161, v160
	v_div_fmas_f32 v158, v158, v159, v161
	v_div_fixup_f32 v158, v158, v152, v153
	v_cvt_pk_bf16_f32 v152, v0, v156
	v_cvt_pk_bf16_f32 v153, v154, v155
	v_cvt_pk_bf16_f32 v154, v148, v149
	v_cvt_pk_bf16_f32 v155, v157, v158
	global_store_dwordx4 v[150:151], v[152:155], off offset:256
.LBB0_475:
	s_andn2_b64 vcc, exec, s[0:1]
	s_cbranch_vccnz .LBB0_477
	v_lshl_add_u32 v154, s61, 8, v139
	v_ashrrev_i32_e32 v155, 31, v154
	v_lshl_add_u64 v[152:153], v[154:155], 2, s[10:11]
	global_load_dword v148, v[152:153], off
	v_lshl_add_u32 v0, s62, 8, v172
	v_lshl_add_u64 v[156:157], v[154:155], 1, s[16:17]
	s_mov_b32 s2, 0x8000
	s_mov_b32 s0, 0x10000
	s_mov_b32 s1, 0x20000
	s_mov_b32 s6, 0x28000
	s_mov_b32 s7, 0x38000
	s_waitcnt vmcnt(0) lgkmcnt(0)
	v_fmamk_f32 v148, v148, 0x3a000000, v207
	v_cmp_gt_f32_e32 vcc, s87, v148
	v_mul_f32_e32 v149, 0x4b800000, v148
	s_nop 0
	v_cndmask_b32_e32 v148, v148, v149, vcc
	v_rsq_f32_e32 v148, v148
	s_nop 0
	v_mul_f32_e32 v149, 0x45800000, v148
	v_cndmask_b32_e32 v160, v148, v149, vcc
	v_mul_f32_e32 v155, v126, v160
	v_lshlrev_b64 v[148:149], 15, v[0:1]
	v_bfe_u32 v158, v155, 16, 1
	v_lshl_add_u64 v[150:151], v[156:157], 0, v[148:149]
	v_add3_u32 v155, v155, v158, s63
	global_store_short_d16_hi v[150:151], v155, off
	v_mul_f32_e32 v155, v127, v160
	v_bfe_u32 v158, v155, 16, 1
	v_add3_u32 v155, v155, v158, s63
	v_add_co_u32_e32 v158, vcc, s2, v150
	v_or_b32_e32 v0, 0x80, v0
	s_nop 0
	v_addc_co_u32_e32 v159, vcc, 0, v151, vcc
	global_store_short_d16_hi v[158:159], v155, off
	v_mul_f32_e32 v155, v128, v160
	v_bfe_u32 v158, v155, 16, 1
	v_add3_u32 v155, v155, v158, s63
	v_add_co_u32_e32 v158, vcc, s0, v150
	s_nop 1
	v_addc_co_u32_e32 v159, vcc, 0, v151, vcc
	global_store_short_d16_hi v[158:159], v155, off
	v_mul_f32_e32 v155, v129, v160
	v_bfe_u32 v158, v155, 16, 1
	v_add3_u32 v155, v155, v158, s63
	v_add_co_u32_e32 v158, vcc, s93, v150
	s_nop 1
	v_addc_co_u32_e32 v159, vcc, 0, v151, vcc
	global_store_short_d16_hi v[158:159], v155, off
	v_mul_f32_e32 v155, v118, v160
	v_bfe_u32 v158, v155, 16, 1
	v_add3_u32 v155, v155, v158, s63
	v_add_co_u32_e32 v158, vcc, s1, v150
	s_nop 1
	v_addc_co_u32_e32 v159, vcc, 0, v151, vcc
	global_store_short_d16_hi v[158:159], v155, off
	v_mul_f32_e32 v155, v119, v160
	v_bfe_u32 v158, v155, 16, 1
	v_add3_u32 v155, v155, v158, s63
	v_add_co_u32_e32 v158, vcc, s6, v150
	s_nop 1
	v_addc_co_u32_e32 v159, vcc, 0, v151, vcc
	global_store_short_d16_hi v[158:159], v155, off
	v_mul_f32_e32 v155, v120, v160
	v_bfe_u32 v158, v155, 16, 1
	v_add3_u32 v155, v155, v158, s63
	v_add_co_u32_e32 v158, vcc, s83, v150
	s_nop 1
	v_addc_co_u32_e32 v159, vcc, 0, v151, vcc
	global_store_short_d16_hi v[158:159], v155, off
	v_mul_f32_e32 v155, v121, v160
	v_bfe_u32 v158, v155, 16, 1
	v_add_co_u32_e32 v150, vcc, s7, v150
	v_add3_u32 v155, v155, v158, s63
	s_nop 0
	v_addc_co_u32_e32 v151, vcc, 0, v151, vcc
	global_store_short_d16_hi v[150:151], v155, off
	v_lshlrev_b64 v[150:151], 15, v[0:1]
	v_mul_f32_e32 v0, v122, v160
	v_bfe_u32 v155, v0, 16, 1
	v_lshl_add_u64 v[156:157], v[156:157], 0, v[150:151]
	v_add3_u32 v0, v0, v155, s63
	global_store_short_d16_hi v[156:157], v0, off
	v_mul_f32_e32 v0, v123, v160
	v_bfe_u32 v155, v0, 16, 1
	v_add_co_u32_e32 v158, vcc, s2, v156
	v_add3_u32 v0, v0, v155, s63
	s_nop 0
	v_addc_co_u32_e32 v159, vcc, 0, v157, vcc
	global_store_short_d16_hi v[158:159], v0, off
	v_mul_f32_e32 v0, v124, v160
	v_bfe_u32 v155, v0, 16, 1
	v_add_co_u32_e32 v158, vcc, s0, v156
	v_add3_u32 v0, v0, v155, s63
	s_nop 0
	v_addc_co_u32_e32 v159, vcc, 0, v157, vcc
	global_store_short_d16_hi v[158:159], v0, off
	v_mul_f32_e32 v0, v125, v160
	v_bfe_u32 v155, v0, 16, 1
	v_add_co_u32_e32 v158, vcc, s93, v156
	v_add3_u32 v0, v0, v155, s63
	s_nop 0
	v_addc_co_u32_e32 v159, vcc, 0, v157, vcc
	global_store_short_d16_hi v[158:159], v0, off
	v_mul_f32_e32 v0, v114, v160
	v_bfe_u32 v155, v0, 16, 1
	v_add_co_u32_e32 v158, vcc, s1, v156
	v_add3_u32 v0, v0, v155, s63
	s_nop 0
	v_addc_co_u32_e32 v159, vcc, 0, v157, vcc
	global_store_short_d16_hi v[158:159], v0, off
	v_mul_f32_e32 v0, v115, v160
	v_bfe_u32 v155, v0, 16, 1
	v_add_co_u32_e32 v158, vcc, s6, v156
	v_add3_u32 v0, v0, v155, s63
	s_nop 0
	v_addc_co_u32_e32 v159, vcc, 0, v157, vcc
	global_store_short_d16_hi v[158:159], v0, off
	v_mul_f32_e32 v0, v116, v160
	v_bfe_u32 v155, v0, 16, 1
	v_add_co_u32_e32 v158, vcc, s83, v156
	v_add3_u32 v0, v0, v155, s63
	s_nop 0
	v_addc_co_u32_e32 v159, vcc, 0, v157, vcc
	global_store_short_d16_hi v[158:159], v0, off
	v_mul_f32_e32 v0, v117, v160
	v_bfe_u32 v155, v0, 16, 1
	v_add_co_u32_e32 v156, vcc, s7, v156
	v_add3_u32 v0, v0, v155, s63
	s_nop 0
	v_addc_co_u32_e32 v157, vcc, 0, v157, vcc
	global_store_short_d16_hi v[156:157], v0, off
	global_load_dword v0, v[152:153], off offset:64
	v_or_b32_e32 v158, 16, v154
	v_ashrrev_i32_e32 v159, 31, v158
	v_lshl_add_u64 v[156:157], s[16:17], 0, v[148:149]
	v_lshlrev_b64 v[160:161], 1, v[158:159]
	v_lshl_add_u64 v[158:159], v[156:157], 0, v[160:161]
	s_waitcnt vmcnt(0) lgkmcnt(0)
	v_fmamk_f32 v0, v0, 0x3a000000, v207
	v_cmp_gt_f32_e32 vcc, s87, v0
	v_mul_f32_e32 v155, 0x4b800000, v0
	s_nop 0
	v_cndmask_b32_e32 v0, v0, v155, vcc
	v_rsq_f32_e32 v0, v0
	s_nop 0
	v_mul_f32_e32 v155, 0x45800000, v0
	v_cndmask_b32_e32 v0, v0, v155, vcc
	v_mul_f32_e32 v155, v110, v0
	v_bfe_u32 v162, v155, 16, 1
	v_add3_u32 v155, v155, v162, s63
	global_store_short_d16_hi v[158:159], v155, off
	v_mul_f32_e32 v155, v111, v0
	v_bfe_u32 v162, v155, 16, 1
	v_add3_u32 v155, v155, v162, s63
	v_add_co_u32_e32 v162, vcc, s2, v158
	s_nop 1
	v_addc_co_u32_e32 v163, vcc, 0, v159, vcc
	global_store_short_d16_hi v[162:163], v155, off
	v_mul_f32_e32 v155, v112, v0
	v_bfe_u32 v162, v155, 16, 1
	v_add3_u32 v155, v155, v162, s63
	v_add_co_u32_e32 v162, vcc, s0, v158
	s_nop 1
	v_addc_co_u32_e32 v163, vcc, 0, v159, vcc
	global_store_short_d16_hi v[162:163], v155, off
	v_mul_f32_e32 v155, v113, v0
	v_bfe_u32 v162, v155, 16, 1
	v_add3_u32 v155, v155, v162, s63
	v_add_co_u32_e32 v162, vcc, s93, v158
	s_nop 1
	v_addc_co_u32_e32 v163, vcc, 0, v159, vcc
	global_store_short_d16_hi v[162:163], v155, off
	v_mul_f32_e32 v155, v102, v0
	v_bfe_u32 v162, v155, 16, 1
	v_add3_u32 v155, v155, v162, s63
	v_add_co_u32_e32 v162, vcc, s1, v158
	s_nop 1
	v_addc_co_u32_e32 v163, vcc, 0, v159, vcc
	global_store_short_d16_hi v[162:163], v155, off
	v_mul_f32_e32 v155, v103, v0
	v_bfe_u32 v162, v155, 16, 1
	v_add3_u32 v155, v155, v162, s63
	v_add_co_u32_e32 v162, vcc, s6, v158
	s_nop 1
	v_addc_co_u32_e32 v163, vcc, 0, v159, vcc
	global_store_short_d16_hi v[162:163], v155, off
	v_mul_f32_e32 v155, v104, v0
	v_bfe_u32 v162, v155, 16, 1
	v_add3_u32 v155, v155, v162, s63
	v_add_co_u32_e32 v162, vcc, s83, v158
	s_nop 1
	v_addc_co_u32_e32 v163, vcc, 0, v159, vcc
	global_store_short_d16_hi v[162:163], v155, off
	v_mul_f32_e32 v155, v105, v0
	v_bfe_u32 v162, v155, 16, 1
	v_add_co_u32_e32 v158, vcc, s7, v158
	v_add3_u32 v155, v155, v162, s63
	s_nop 0
	v_addc_co_u32_e32 v159, vcc, 0, v159, vcc
	global_store_short_d16_hi v[158:159], v155, off
	v_mul_f32_e32 v155, v106, v0
	v_lshl_add_u64 v[158:159], s[16:17], 0, v[150:151]
	v_bfe_u32 v162, v155, 16, 1
	v_lshl_add_u64 v[160:161], v[158:159], 0, v[160:161]
	v_add3_u32 v155, v155, v162, s63
	global_store_short_d16_hi v[160:161], v155, off
	v_mul_f32_e32 v155, v107, v0
	v_bfe_u32 v162, v155, 16, 1
	v_add3_u32 v155, v155, v162, s63
	v_add_co_u32_e32 v162, vcc, s2, v160
	s_nop 1
	v_addc_co_u32_e32 v163, vcc, 0, v161, vcc
	global_store_short_d16_hi v[162:163], v155, off
	v_mul_f32_e32 v155, v108, v0
	v_bfe_u32 v162, v155, 16, 1
	v_add3_u32 v155, v155, v162, s63
	v_add_co_u32_e32 v162, vcc, s0, v160
	s_nop 1
	v_addc_co_u32_e32 v163, vcc, 0, v161, vcc
	global_store_short_d16_hi v[162:163], v155, off
	v_mul_f32_e32 v155, v109, v0
	v_bfe_u32 v162, v155, 16, 1
	v_add3_u32 v155, v155, v162, s63
	v_add_co_u32_e32 v162, vcc, s93, v160
	s_nop 1
	v_addc_co_u32_e32 v163, vcc, 0, v161, vcc
	global_store_short_d16_hi v[162:163], v155, off
	v_mul_f32_e32 v155, v98, v0
	v_bfe_u32 v162, v155, 16, 1
	v_add3_u32 v155, v155, v162, s63
	v_add_co_u32_e32 v162, vcc, s1, v160
	s_nop 1
	v_addc_co_u32_e32 v163, vcc, 0, v161, vcc
	global_store_short_d16_hi v[162:163], v155, off
	v_mul_f32_e32 v155, v99, v0
	v_bfe_u32 v162, v155, 16, 1
	v_add3_u32 v155, v155, v162, s63
	v_add_co_u32_e32 v162, vcc, s6, v160
	s_nop 1
	v_addc_co_u32_e32 v163, vcc, 0, v161, vcc
	global_store_short_d16_hi v[162:163], v155, off
	v_mul_f32_e32 v155, v100, v0
	v_bfe_u32 v162, v155, 16, 1
	v_add3_u32 v155, v155, v162, s63
	v_add_co_u32_e32 v162, vcc, s83, v160
	v_mul_f32_e32 v0, v101, v0
	s_nop 0
	v_addc_co_u32_e32 v163, vcc, 0, v161, vcc
	global_store_short_d16_hi v[162:163], v155, off
	v_bfe_u32 v155, v0, 16, 1
	v_add_co_u32_e32 v160, vcc, s7, v160
	v_add3_u32 v0, v0, v155, s63
	s_nop 0
	v_addc_co_u32_e32 v161, vcc, 0, v161, vcc
	global_store_short_d16_hi v[160:161], v0, off
	global_load_dword v0, v[152:153], off offset:128
	v_or_b32_e32 v160, 32, v154
	v_ashrrev_i32_e32 v161, 31, v160
	v_lshlrev_b64 v[160:161], 1, v[160:161]
	v_lshl_add_u64 v[162:163], v[156:157], 0, v[160:161]
	v_lshl_add_u64 v[160:161], v[158:159], 0, v[160:161]
	s_waitcnt vmcnt(0) lgkmcnt(0)
	v_fmamk_f32 v0, v0, 0x3a000000, v207
	v_cmp_gt_f32_e32 vcc, s87, v0
	v_mul_f32_e32 v155, 0x4b800000, v0
	s_nop 0
	v_cndmask_b32_e32 v0, v0, v155, vcc
	v_rsq_f32_e32 v0, v0
	s_nop 0
	v_mul_f32_e32 v155, 0x45800000, v0
	v_cndmask_b32_e32 v0, v0, v155, vcc
	v_mul_f32_e32 v155, v94, v0
	v_bfe_u32 v181, v155, 16, 1
	v_add3_u32 v155, v155, v181, s63
	global_store_short_d16_hi v[162:163], v155, off
	v_mul_f32_e32 v155, v95, v0
	v_bfe_u32 v181, v155, 16, 1
	v_add_co_u32_e32 v182, vcc, s2, v162
	v_add3_u32 v155, v155, v181, s63
	s_nop 0
	v_addc_co_u32_e32 v183, vcc, 0, v163, vcc
	global_store_short_d16_hi v[182:183], v155, off
	v_mul_f32_e32 v155, v96, v0
	v_bfe_u32 v181, v155, 16, 1
	v_add_co_u32_e32 v182, vcc, s0, v162
	v_add3_u32 v155, v155, v181, s63
	s_nop 0
	v_addc_co_u32_e32 v183, vcc, 0, v163, vcc
	global_store_short_d16_hi v[182:183], v155, off
	v_mul_f32_e32 v155, v97, v0
	v_bfe_u32 v181, v155, 16, 1
	v_add_co_u32_e32 v182, vcc, s93, v162
	v_add3_u32 v155, v155, v181, s63
	s_nop 0
	v_addc_co_u32_e32 v183, vcc, 0, v163, vcc
	global_store_short_d16_hi v[182:183], v155, off
	v_mul_f32_e32 v155, v86, v0
	v_bfe_u32 v181, v155, 16, 1
	v_add_co_u32_e32 v182, vcc, s1, v162
	v_add3_u32 v155, v155, v181, s63
	s_nop 0
	v_addc_co_u32_e32 v183, vcc, 0, v163, vcc
	global_store_short_d16_hi v[182:183], v155, off
	v_mul_f32_e32 v155, v87, v0
	v_bfe_u32 v181, v155, 16, 1
	v_add_co_u32_e32 v182, vcc, s6, v162
	v_add3_u32 v155, v155, v181, s63
	s_nop 0
	v_addc_co_u32_e32 v183, vcc, 0, v163, vcc
	global_store_short_d16_hi v[182:183], v155, off
	v_mul_f32_e32 v155, v88, v0
	v_bfe_u32 v181, v155, 16, 1
	v_add_co_u32_e32 v182, vcc, s83, v162
	v_add3_u32 v155, v155, v181, s63
	s_nop 0
	v_addc_co_u32_e32 v183, vcc, 0, v163, vcc
	global_store_short_d16_hi v[182:183], v155, off
	v_mul_f32_e32 v155, v89, v0
	v_bfe_u32 v181, v155, 16, 1
	v_add_co_u32_e32 v162, vcc, s7, v162
	v_add3_u32 v155, v155, v181, s63
	s_nop 0
	v_addc_co_u32_e32 v163, vcc, 0, v163, vcc
	global_store_short_d16_hi v[162:163], v155, off
	v_mul_f32_e32 v155, v90, v0
	v_bfe_u32 v162, v155, 16, 1
	v_add3_u32 v155, v155, v162, s63
	global_store_short_d16_hi v[160:161], v155, off
	v_mul_f32_e32 v155, v91, v0
	v_bfe_u32 v162, v155, 16, 1
	v_add3_u32 v155, v155, v162, s63
	v_add_co_u32_e32 v162, vcc, s2, v160
	s_nop 1
	v_addc_co_u32_e32 v163, vcc, 0, v161, vcc
	global_store_short_d16_hi v[162:163], v155, off
	v_mul_f32_e32 v155, v92, v0
	v_bfe_u32 v162, v155, 16, 1
	v_add3_u32 v155, v155, v162, s63
	v_add_co_u32_e32 v162, vcc, s0, v160
	s_nop 1
	v_addc_co_u32_e32 v163, vcc, 0, v161, vcc
	global_store_short_d16_hi v[162:163], v155, off
	v_mul_f32_e32 v155, v93, v0
	v_bfe_u32 v162, v155, 16, 1
	v_add3_u32 v155, v155, v162, s63
	v_add_co_u32_e32 v162, vcc, s93, v160
	s_nop 1
	v_addc_co_u32_e32 v163, vcc, 0, v161, vcc
	global_store_short_d16_hi v[162:163], v155, off
	v_mul_f32_e32 v155, v82, v0
	v_bfe_u32 v162, v155, 16, 1
	v_add3_u32 v155, v155, v162, s63
	v_add_co_u32_e32 v162, vcc, s1, v160
	s_nop 1
	v_addc_co_u32_e32 v163, vcc, 0, v161, vcc
	global_store_short_d16_hi v[162:163], v155, off
	v_mul_f32_e32 v155, v83, v0
	v_bfe_u32 v162, v155, 16, 1
	v_add3_u32 v155, v155, v162, s63
	v_add_co_u32_e32 v162, vcc, s6, v160
	s_nop 1
	v_addc_co_u32_e32 v163, vcc, 0, v161, vcc
	global_store_short_d16_hi v[162:163], v155, off
	v_mul_f32_e32 v155, v84, v0
	v_bfe_u32 v162, v155, 16, 1
	v_add3_u32 v155, v155, v162, s63
	v_add_co_u32_e32 v162, vcc, s83, v160
	v_mul_f32_e32 v0, v85, v0
	s_nop 0
	v_addc_co_u32_e32 v163, vcc, 0, v161, vcc
	global_store_short_d16_hi v[162:163], v155, off
	v_bfe_u32 v155, v0, 16, 1
	v_add_co_u32_e32 v160, vcc, s7, v160
	v_add3_u32 v0, v0, v155, s63
	s_nop 0
	v_addc_co_u32_e32 v161, vcc, 0, v161, vcc
	global_store_short_d16_hi v[160:161], v0, off
	global_load_dword v0, v[152:153], off offset:192
	v_or_b32_e32 v160, 48, v154
	v_ashrrev_i32_e32 v161, 31, v160
	v_lshlrev_b64 v[160:161], 1, v[160:161]
	v_lshl_add_u64 v[156:157], v[156:157], 0, v[160:161]
	s_waitcnt vmcnt(0) lgkmcnt(0)
	v_fmamk_f32 v0, v0, 0x3a000000, v207
	v_cmp_gt_f32_e32 vcc, s87, v0
	v_mul_f32_e32 v155, 0x4b800000, v0
	s_nop 0
	v_cndmask_b32_e32 v0, v0, v155, vcc
	v_rsq_f32_e32 v0, v0
	s_nop 0
	v_mul_f32_e32 v155, 0x45800000, v0
	v_cndmask_b32_e32 v0, v0, v155, vcc
	v_mul_f32_e32 v155, v78, v0
	v_bfe_u32 v162, v155, 16, 1
	v_add3_u32 v155, v155, v162, s63
	global_store_short_d16_hi v[156:157], v155, off
	v_mul_f32_e32 v155, v79, v0
	v_bfe_u32 v162, v155, 16, 1
	v_add3_u32 v155, v155, v162, s63
	v_add_co_u32_e32 v162, vcc, s2, v156
	s_nop 1
	v_addc_co_u32_e32 v163, vcc, 0, v157, vcc
	global_store_short_d16_hi v[162:163], v155, off
	v_mul_f32_e32 v155, v80, v0
	v_bfe_u32 v162, v155, 16, 1
	v_add3_u32 v155, v155, v162, s63
	v_add_co_u32_e32 v162, vcc, s0, v156
	s_nop 1
	v_addc_co_u32_e32 v163, vcc, 0, v157, vcc
	global_store_short_d16_hi v[162:163], v155, off
	v_mul_f32_e32 v155, v81, v0
	v_bfe_u32 v162, v155, 16, 1
	v_add3_u32 v155, v155, v162, s63
	v_add_co_u32_e32 v162, vcc, s93, v156
	s_nop 1
	v_addc_co_u32_e32 v163, vcc, 0, v157, vcc
	global_store_short_d16_hi v[162:163], v155, off
	v_mul_f32_e32 v155, v70, v0
	v_bfe_u32 v162, v155, 16, 1
	v_add3_u32 v155, v155, v162, s63
	v_add_co_u32_e32 v162, vcc, s1, v156
	s_nop 1
	v_addc_co_u32_e32 v163, vcc, 0, v157, vcc
	global_store_short_d16_hi v[162:163], v155, off
	v_mul_f32_e32 v155, v71, v0
	v_bfe_u32 v162, v155, 16, 1
	v_add3_u32 v155, v155, v162, s63
	v_add_co_u32_e32 v162, vcc, s6, v156
	s_nop 1
	v_addc_co_u32_e32 v163, vcc, 0, v157, vcc
	global_store_short_d16_hi v[162:163], v155, off
	v_mul_f32_e32 v155, v72, v0
	v_bfe_u32 v162, v155, 16, 1
	v_add3_u32 v155, v155, v162, s63
	v_add_co_u32_e32 v162, vcc, s83, v156
	s_nop 1
	v_addc_co_u32_e32 v163, vcc, 0, v157, vcc
	global_store_short_d16_hi v[162:163], v155, off
	v_mul_f32_e32 v155, v73, v0
	v_bfe_u32 v162, v155, 16, 1
	v_add_co_u32_e32 v156, vcc, s7, v156
	v_add3_u32 v155, v155, v162, s63
	s_nop 0
	v_addc_co_u32_e32 v157, vcc, 0, v157, vcc
	global_store_short_d16_hi v[156:157], v155, off
	v_mul_f32_e32 v155, v74, v0
	v_lshl_add_u64 v[156:157], v[158:159], 0, v[160:161]
	v_bfe_u32 v158, v155, 16, 1
	v_add3_u32 v155, v155, v158, s63
	global_store_short_d16_hi v[156:157], v155, off
	v_mul_f32_e32 v155, v75, v0
	v_bfe_u32 v158, v155, 16, 1
	v_add3_u32 v155, v155, v158, s63
	v_add_co_u32_e32 v158, vcc, s2, v156
	s_nop 1
	v_addc_co_u32_e32 v159, vcc, 0, v157, vcc
	global_store_short_d16_hi v[158:159], v155, off
	v_mul_f32_e32 v155, v76, v0
	v_bfe_u32 v158, v155, 16, 1
	v_add3_u32 v155, v155, v158, s63
	v_add_co_u32_e32 v158, vcc, s0, v156
	s_nop 1
	v_addc_co_u32_e32 v159, vcc, 0, v157, vcc
	global_store_short_d16_hi v[158:159], v155, off
	v_mul_f32_e32 v155, v77, v0
	v_bfe_u32 v158, v155, 16, 1
	v_add3_u32 v155, v155, v158, s63
	v_add_co_u32_e32 v158, vcc, s93, v156
	s_nop 1
	v_addc_co_u32_e32 v159, vcc, 0, v157, vcc
	global_store_short_d16_hi v[158:159], v155, off
	v_mul_f32_e32 v155, v66, v0
	v_bfe_u32 v158, v155, 16, 1
	v_add3_u32 v155, v155, v158, s63
	v_add_co_u32_e32 v158, vcc, s1, v156
	s_nop 1
	v_addc_co_u32_e32 v159, vcc, 0, v157, vcc
	global_store_short_d16_hi v[158:159], v155, off
	v_mul_f32_e32 v155, v67, v0
	v_bfe_u32 v158, v155, 16, 1
	v_add3_u32 v155, v155, v158, s63
	v_add_co_u32_e32 v158, vcc, s6, v156
	s_nop 1
	v_addc_co_u32_e32 v159, vcc, 0, v157, vcc
	global_store_short_d16_hi v[158:159], v155, off
	v_mul_f32_e32 v155, v68, v0
	v_bfe_u32 v158, v155, 16, 1
	v_add3_u32 v155, v155, v158, s63
	v_add_co_u32_e32 v158, vcc, s83, v156
	v_mul_f32_e32 v0, v69, v0
	s_nop 0
	v_addc_co_u32_e32 v159, vcc, 0, v157, vcc
	global_store_short_d16_hi v[158:159], v155, off
	v_bfe_u32 v155, v0, 16, 1
	v_add_co_u32_e32 v156, vcc, s7, v156
	v_add3_u32 v0, v0, v155, s63
	s_nop 0
	v_addc_co_u32_e32 v157, vcc, 0, v157, vcc
	global_store_short_d16_hi v[156:157], v0, off
	global_load_dword v0, v[152:153], off offset:512
	v_add_u32_e32 v156, 0x80, v154
	v_ashrrev_i32_e32 v157, 31, v156
	v_lshl_add_u64 v[156:157], v[156:157], 1, s[16:17]
	v_lshl_add_u64 v[158:159], v[156:157], 0, v[148:149]
	v_lshl_add_u64 v[156:157], v[156:157], 0, v[150:151]
	s_waitcnt vmcnt(0) lgkmcnt(0)
	v_fmamk_f32 v0, v0, 0x3a000000, v207
	v_cmp_gt_f32_e32 vcc, s87, v0
	v_mul_f32_e32 v155, 0x4b800000, v0
	s_nop 0
	v_cndmask_b32_e32 v0, v0, v155, vcc
	v_rsq_f32_e32 v0, v0
	s_nop 0
	v_mul_f32_e32 v155, 0x45800000, v0
	v_cndmask_b32_e32 v0, v0, v155, vcc
	v_mul_f32_e32 v155, v62, v0
	v_bfe_u32 v160, v155, 16, 1
	v_add3_u32 v155, v155, v160, s63
	global_store_short_d16_hi v[158:159], v155, off
	v_mul_f32_e32 v155, v63, v0
	v_bfe_u32 v160, v155, 16, 1
	v_add3_u32 v155, v155, v160, s63
	v_add_co_u32_e32 v160, vcc, s2, v158
	s_nop 1
	v_addc_co_u32_e32 v161, vcc, 0, v159, vcc
	global_store_short_d16_hi v[160:161], v155, off
	v_mul_f32_e32 v155, v64, v0
	v_bfe_u32 v160, v155, 16, 1
	v_add3_u32 v155, v155, v160, s63
	v_add_co_u32_e32 v160, vcc, s0, v158
	s_nop 1
	v_addc_co_u32_e32 v161, vcc, 0, v159, vcc
	global_store_short_d16_hi v[160:161], v155, off
	v_mul_f32_e32 v155, v65, v0
	v_bfe_u32 v160, v155, 16, 1
	v_add3_u32 v155, v155, v160, s63
	v_add_co_u32_e32 v160, vcc, s93, v158
	s_nop 1
	v_addc_co_u32_e32 v161, vcc, 0, v159, vcc
	global_store_short_d16_hi v[160:161], v155, off
	v_mul_f32_e32 v155, v54, v0
	v_bfe_u32 v160, v155, 16, 1
	v_add3_u32 v155, v155, v160, s63
	v_add_co_u32_e32 v160, vcc, s1, v158
	s_nop 1
	v_addc_co_u32_e32 v161, vcc, 0, v159, vcc
	global_store_short_d16_hi v[160:161], v155, off
	v_mul_f32_e32 v155, v55, v0
	v_bfe_u32 v160, v155, 16, 1
	v_add3_u32 v155, v155, v160, s63
	v_add_co_u32_e32 v160, vcc, s6, v158
	s_nop 1
	v_addc_co_u32_e32 v161, vcc, 0, v159, vcc
	global_store_short_d16_hi v[160:161], v155, off
	v_mul_f32_e32 v155, v56, v0
	v_bfe_u32 v160, v155, 16, 1
	v_add3_u32 v155, v155, v160, s63
	v_add_co_u32_e32 v160, vcc, s83, v158
	s_nop 1
	v_addc_co_u32_e32 v161, vcc, 0, v159, vcc
	global_store_short_d16_hi v[160:161], v155, off
	v_mul_f32_e32 v155, v57, v0
	v_bfe_u32 v160, v155, 16, 1
	v_add_co_u32_e32 v158, vcc, s7, v158
	v_add3_u32 v155, v155, v160, s63
	s_nop 0
	v_addc_co_u32_e32 v159, vcc, 0, v159, vcc
	global_store_short_d16_hi v[158:159], v155, off
	v_mul_f32_e32 v155, v58, v0
	v_bfe_u32 v158, v155, 16, 1
	v_add3_u32 v155, v155, v158, s63
	global_store_short_d16_hi v[156:157], v155, off
	v_mul_f32_e32 v155, v59, v0
	v_bfe_u32 v158, v155, 16, 1
	v_add3_u32 v155, v155, v158, s63
	v_add_co_u32_e32 v158, vcc, s2, v156
	s_nop 1
	v_addc_co_u32_e32 v159, vcc, 0, v157, vcc
	global_store_short_d16_hi v[158:159], v155, off
	v_mul_f32_e32 v155, v60, v0
	v_bfe_u32 v158, v155, 16, 1
	v_add3_u32 v155, v155, v158, s63
	v_add_co_u32_e32 v158, vcc, s0, v156
	s_nop 1
	v_addc_co_u32_e32 v159, vcc, 0, v157, vcc
	global_store_short_d16_hi v[158:159], v155, off
	v_mul_f32_e32 v155, v61, v0
	v_bfe_u32 v158, v155, 16, 1
	v_add3_u32 v155, v155, v158, s63
	v_add_co_u32_e32 v158, vcc, s93, v156
	s_nop 1
	v_addc_co_u32_e32 v159, vcc, 0, v157, vcc
	global_store_short_d16_hi v[158:159], v155, off
	v_mul_f32_e32 v155, v50, v0
	v_bfe_u32 v158, v155, 16, 1
	v_add3_u32 v155, v155, v158, s63
	v_add_co_u32_e32 v158, vcc, s1, v156
	s_nop 1
	v_addc_co_u32_e32 v159, vcc, 0, v157, vcc
	global_store_short_d16_hi v[158:159], v155, off
	v_mul_f32_e32 v155, v51, v0
	v_bfe_u32 v158, v155, 16, 1
	v_add3_u32 v155, v155, v158, s63
	v_add_co_u32_e32 v158, vcc, s6, v156
	s_nop 1
	v_addc_co_u32_e32 v159, vcc, 0, v157, vcc
	global_store_short_d16_hi v[158:159], v155, off
	v_mul_f32_e32 v155, v52, v0
	v_bfe_u32 v158, v155, 16, 1
	v_add3_u32 v155, v155, v158, s63
	v_add_co_u32_e32 v158, vcc, s83, v156
	v_mul_f32_e32 v0, v53, v0
	s_nop 0
	v_addc_co_u32_e32 v159, vcc, 0, v157, vcc
	global_store_short_d16_hi v[158:159], v155, off
	v_bfe_u32 v155, v0, 16, 1
	v_add_co_u32_e32 v156, vcc, s7, v156
	v_add3_u32 v0, v0, v155, s63
	s_nop 0
	v_addc_co_u32_e32 v157, vcc, 0, v157, vcc
	global_store_short_d16_hi v[156:157], v0, off
	global_load_dword v0, v[152:153], off offset:576
	v_add_u32_e32 v156, 0x90, v154
	v_ashrrev_i32_e32 v157, 31, v156
	v_lshl_add_u64 v[156:157], v[156:157], 1, s[16:17]
	v_lshl_add_u64 v[158:159], v[156:157], 0, v[148:149]
	v_lshl_add_u64 v[156:157], v[156:157], 0, v[150:151]
	s_waitcnt vmcnt(0) lgkmcnt(0)
	v_fmamk_f32 v0, v0, 0x3a000000, v207
	v_cmp_gt_f32_e32 vcc, s87, v0
	v_mul_f32_e32 v155, 0x4b800000, v0
	s_nop 0
	v_cndmask_b32_e32 v0, v0, v155, vcc
	v_rsq_f32_e32 v0, v0
	s_nop 0
	v_mul_f32_e32 v155, 0x45800000, v0
	v_cndmask_b32_e32 v0, v0, v155, vcc
	v_mul_f32_e32 v155, v46, v0
	v_bfe_u32 v160, v155, 16, 1
	v_add3_u32 v155, v155, v160, s63
	global_store_short_d16_hi v[158:159], v155, off
	v_mul_f32_e32 v155, v47, v0
	v_bfe_u32 v160, v155, 16, 1
	v_add3_u32 v155, v155, v160, s63
	v_add_co_u32_e32 v160, vcc, s2, v158
	s_nop 1
	v_addc_co_u32_e32 v161, vcc, 0, v159, vcc
	global_store_short_d16_hi v[160:161], v155, off
	v_mul_f32_e32 v155, v48, v0
	v_bfe_u32 v160, v155, 16, 1
	v_add3_u32 v155, v155, v160, s63
	v_add_co_u32_e32 v160, vcc, s0, v158
	s_nop 1
	v_addc_co_u32_e32 v161, vcc, 0, v159, vcc
	global_store_short_d16_hi v[160:161], v155, off
	v_mul_f32_e32 v155, v49, v0
	v_bfe_u32 v160, v155, 16, 1
	v_add3_u32 v155, v155, v160, s63
	v_add_co_u32_e32 v160, vcc, s93, v158
	s_nop 1
	v_addc_co_u32_e32 v161, vcc, 0, v159, vcc
	global_store_short_d16_hi v[160:161], v155, off
	v_mul_f32_e32 v155, v38, v0
	v_bfe_u32 v160, v155, 16, 1
	v_add3_u32 v155, v155, v160, s63
	v_add_co_u32_e32 v160, vcc, s1, v158
	s_nop 1
	v_addc_co_u32_e32 v161, vcc, 0, v159, vcc
	global_store_short_d16_hi v[160:161], v155, off
	v_mul_f32_e32 v155, v39, v0
	v_bfe_u32 v160, v155, 16, 1
	v_add3_u32 v155, v155, v160, s63
	v_add_co_u32_e32 v160, vcc, s6, v158
	s_nop 1
	v_addc_co_u32_e32 v161, vcc, 0, v159, vcc
	global_store_short_d16_hi v[160:161], v155, off
	v_mul_f32_e32 v155, v40, v0
	v_bfe_u32 v160, v155, 16, 1
	v_add3_u32 v155, v155, v160, s63
	v_add_co_u32_e32 v160, vcc, s83, v158
	s_nop 1
	v_addc_co_u32_e32 v161, vcc, 0, v159, vcc
	global_store_short_d16_hi v[160:161], v155, off
	v_mul_f32_e32 v155, v41, v0
	v_bfe_u32 v160, v155, 16, 1
	v_add_co_u32_e32 v158, vcc, s7, v158
	v_add3_u32 v155, v155, v160, s63
	s_nop 0
	v_addc_co_u32_e32 v159, vcc, 0, v159, vcc
	global_store_short_d16_hi v[158:159], v155, off
	v_mul_f32_e32 v155, v42, v0
	v_bfe_u32 v158, v155, 16, 1
	v_add3_u32 v155, v155, v158, s63
	global_store_short_d16_hi v[156:157], v155, off
	v_mul_f32_e32 v155, v43, v0
	v_bfe_u32 v158, v155, 16, 1
	v_add3_u32 v155, v155, v158, s63
	v_add_co_u32_e32 v158, vcc, s2, v156
	s_nop 1
	v_addc_co_u32_e32 v159, vcc, 0, v157, vcc
	global_store_short_d16_hi v[158:159], v155, off
	v_mul_f32_e32 v155, v44, v0
	v_bfe_u32 v158, v155, 16, 1
	v_add3_u32 v155, v155, v158, s63
	v_add_co_u32_e32 v158, vcc, s0, v156
	s_nop 1
	v_addc_co_u32_e32 v159, vcc, 0, v157, vcc
	global_store_short_d16_hi v[158:159], v155, off
	v_mul_f32_e32 v155, v45, v0
	v_bfe_u32 v158, v155, 16, 1
	v_add3_u32 v155, v155, v158, s63
	v_add_co_u32_e32 v158, vcc, s93, v156
	s_nop 1
	v_addc_co_u32_e32 v159, vcc, 0, v157, vcc
	global_store_short_d16_hi v[158:159], v155, off
	v_mul_f32_e32 v155, v34, v0
	v_bfe_u32 v158, v155, 16, 1
	v_add3_u32 v155, v155, v158, s63
	v_add_co_u32_e32 v158, vcc, s1, v156
	s_nop 1
	v_addc_co_u32_e32 v159, vcc, 0, v157, vcc
	global_store_short_d16_hi v[158:159], v155, off
	v_mul_f32_e32 v155, v35, v0
	v_bfe_u32 v158, v155, 16, 1
	v_add3_u32 v155, v155, v158, s63
	v_add_co_u32_e32 v158, vcc, s6, v156
	s_nop 1
	v_addc_co_u32_e32 v159, vcc, 0, v157, vcc
	global_store_short_d16_hi v[158:159], v155, off
	v_mul_f32_e32 v155, v36, v0
	v_bfe_u32 v158, v155, 16, 1
	v_add3_u32 v155, v155, v158, s63
	v_add_co_u32_e32 v158, vcc, s83, v156
	v_mul_f32_e32 v0, v37, v0
	s_nop 0
	v_addc_co_u32_e32 v159, vcc, 0, v157, vcc
	global_store_short_d16_hi v[158:159], v155, off
	v_bfe_u32 v155, v0, 16, 1
	v_add_co_u32_e32 v156, vcc, s7, v156
	v_add3_u32 v0, v0, v155, s63
	s_nop 0
	v_addc_co_u32_e32 v157, vcc, 0, v157, vcc
	global_store_short_d16_hi v[156:157], v0, off
	global_load_dword v0, v[152:153], off offset:640
	v_add_u32_e32 v156, 0xa0, v154
	v_ashrrev_i32_e32 v157, 31, v156
	v_lshl_add_u64 v[156:157], v[156:157], 1, s[16:17]
	v_lshl_add_u64 v[158:159], v[156:157], 0, v[148:149]
	v_lshl_add_u64 v[156:157], v[156:157], 0, v[150:151]
	v_add_u32_e32 v154, 0xb0, v154
	s_waitcnt vmcnt(0) lgkmcnt(0)
	v_fmamk_f32 v0, v0, 0x3a000000, v207
	v_cmp_gt_f32_e32 vcc, s87, v0
	v_mul_f32_e32 v155, 0x4b800000, v0
	s_nop 0
	v_cndmask_b32_e32 v0, v0, v155, vcc
	v_rsq_f32_e32 v0, v0
	s_nop 0
	v_mul_f32_e32 v155, 0x45800000, v0
	v_cndmask_b32_e32 v0, v0, v155, vcc
	v_mul_f32_e32 v155, v30, v0
	v_bfe_u32 v160, v155, 16, 1
	v_add3_u32 v155, v155, v160, s63
	global_store_short_d16_hi v[158:159], v155, off
	v_mul_f32_e32 v155, v31, v0
	v_bfe_u32 v160, v155, 16, 1
	v_add3_u32 v155, v155, v160, s63
	v_add_co_u32_e32 v160, vcc, s2, v158
	s_nop 1
	v_addc_co_u32_e32 v161, vcc, 0, v159, vcc
	global_store_short_d16_hi v[160:161], v155, off
	v_mul_f32_e32 v155, v32, v0
	v_bfe_u32 v160, v155, 16, 1
	v_add3_u32 v155, v155, v160, s63
	v_add_co_u32_e32 v160, vcc, s0, v158
	s_nop 1
	v_addc_co_u32_e32 v161, vcc, 0, v159, vcc
	global_store_short_d16_hi v[160:161], v155, off
	v_mul_f32_e32 v155, v33, v0
	v_bfe_u32 v160, v155, 16, 1
	v_add3_u32 v155, v155, v160, s63
	v_add_co_u32_e32 v160, vcc, s93, v158
	s_nop 1
	v_addc_co_u32_e32 v161, vcc, 0, v159, vcc
	global_store_short_d16_hi v[160:161], v155, off
	v_mul_f32_e32 v155, v22, v0
	v_bfe_u32 v160, v155, 16, 1
	v_add3_u32 v155, v155, v160, s63
	v_add_co_u32_e32 v160, vcc, s1, v158
	s_nop 1
	v_addc_co_u32_e32 v161, vcc, 0, v159, vcc
	global_store_short_d16_hi v[160:161], v155, off
	v_mul_f32_e32 v155, v23, v0
	v_bfe_u32 v160, v155, 16, 1
	v_add3_u32 v155, v155, v160, s63
	v_add_co_u32_e32 v160, vcc, s6, v158
	s_nop 1
	v_addc_co_u32_e32 v161, vcc, 0, v159, vcc
	global_store_short_d16_hi v[160:161], v155, off
	v_mul_f32_e32 v155, v24, v0
	v_bfe_u32 v160, v155, 16, 1
	v_add3_u32 v155, v155, v160, s63
	v_add_co_u32_e32 v160, vcc, s83, v158
	s_nop 1
	v_addc_co_u32_e32 v161, vcc, 0, v159, vcc
	global_store_short_d16_hi v[160:161], v155, off
	v_mul_f32_e32 v155, v25, v0
	v_bfe_u32 v160, v155, 16, 1
	v_add_co_u32_e32 v158, vcc, s7, v158
	v_add3_u32 v155, v155, v160, s63
	s_nop 0
	v_addc_co_u32_e32 v159, vcc, 0, v159, vcc
	global_store_short_d16_hi v[158:159], v155, off
	v_mul_f32_e32 v155, v26, v0
	v_bfe_u32 v158, v155, 16, 1
	v_add3_u32 v155, v155, v158, s63
	global_store_short_d16_hi v[156:157], v155, off
	v_mul_f32_e32 v155, v27, v0
	v_bfe_u32 v158, v155, 16, 1
	v_add3_u32 v155, v155, v158, s63
	v_add_co_u32_e32 v158, vcc, s2, v156
	s_nop 1
	v_addc_co_u32_e32 v159, vcc, 0, v157, vcc
	global_store_short_d16_hi v[158:159], v155, off
	v_mul_f32_e32 v155, v28, v0
	v_bfe_u32 v158, v155, 16, 1
	v_add3_u32 v155, v155, v158, s63
	v_add_co_u32_e32 v158, vcc, s0, v156
	s_nop 1
	v_addc_co_u32_e32 v159, vcc, 0, v157, vcc
	global_store_short_d16_hi v[158:159], v155, off
	v_mul_f32_e32 v155, v29, v0
	v_bfe_u32 v158, v155, 16, 1
	v_add3_u32 v155, v155, v158, s63
	v_add_co_u32_e32 v158, vcc, s93, v156
	s_nop 1
	v_addc_co_u32_e32 v159, vcc, 0, v157, vcc
	global_store_short_d16_hi v[158:159], v155, off
	v_mul_f32_e32 v155, v18, v0
	v_bfe_u32 v158, v155, 16, 1
	v_add3_u32 v155, v155, v158, s63
	v_add_co_u32_e32 v158, vcc, s1, v156
	s_nop 1
	v_addc_co_u32_e32 v159, vcc, 0, v157, vcc
	global_store_short_d16_hi v[158:159], v155, off
	v_mul_f32_e32 v155, v19, v0
	v_bfe_u32 v158, v155, 16, 1
	v_add3_u32 v155, v155, v158, s63
	v_add_co_u32_e32 v158, vcc, s6, v156
	s_nop 1
	v_addc_co_u32_e32 v159, vcc, 0, v157, vcc
	global_store_short_d16_hi v[158:159], v155, off
	v_mul_f32_e32 v155, v20, v0
	v_bfe_u32 v158, v155, 16, 1
	v_add3_u32 v155, v155, v158, s63
	v_add_co_u32_e32 v158, vcc, s83, v156
	v_mul_f32_e32 v0, v21, v0
	s_nop 0
	v_addc_co_u32_e32 v159, vcc, 0, v157, vcc
	global_store_short_d16_hi v[158:159], v155, off
	v_bfe_u32 v155, v0, 16, 1
	v_add_co_u32_e32 v156, vcc, s7, v156
	v_add3_u32 v0, v0, v155, s63
	s_nop 0
	v_addc_co_u32_e32 v157, vcc, 0, v157, vcc
	global_store_short_d16_hi v[156:157], v0, off
	global_load_dword v0, v[152:153], off offset:704
	v_ashrrev_i32_e32 v155, 31, v154
	s_waitcnt vmcnt(0) lgkmcnt(0)
	v_fmamk_f32 v0, v0, 0x3a000000, v207
	v_cmp_gt_f32_e32 vcc, s87, v0
	v_mul_f32_e32 v152, 0x4b800000, v0
	s_nop 0
	v_cndmask_b32_e32 v0, v0, v152, vcc
	v_rsq_f32_e32 v0, v0
	s_nop 0
	v_mul_f32_e32 v152, 0x45800000, v0
	v_cndmask_b32_e32 v0, v0, v152, vcc
	v_lshl_add_u64 v[152:153], v[154:155], 1, s[16:17]
	v_mul_f32_e32 v154, v14, v0
	v_bfe_u32 v155, v154, 16, 1
	v_lshl_add_u64 v[148:149], v[152:153], 0, v[148:149]
	v_add3_u32 v154, v154, v155, s63
	global_store_short_d16_hi v[148:149], v154, off
	v_mul_f32_e32 v154, v15, v0
	v_bfe_u32 v155, v154, 16, 1
	v_add3_u32 v156, v154, v155, s63
	v_add_co_u32_e32 v154, vcc, s2, v148
	s_nop 1
	v_addc_co_u32_e32 v155, vcc, 0, v149, vcc
	global_store_short_d16_hi v[154:155], v156, off
	v_mul_f32_e32 v154, v16, v0
	v_bfe_u32 v155, v154, 16, 1
	v_add3_u32 v156, v154, v155, s63
	v_add_co_u32_e32 v154, vcc, s0, v148
	s_nop 1
	v_addc_co_u32_e32 v155, vcc, 0, v149, vcc
	global_store_short_d16_hi v[154:155], v156, off
	v_mul_f32_e32 v154, v17, v0
	v_bfe_u32 v155, v154, 16, 1
	v_add3_u32 v156, v154, v155, s63
	v_add_co_u32_e32 v154, vcc, s93, v148
	s_nop 1
	v_addc_co_u32_e32 v155, vcc, 0, v149, vcc
	global_store_short_d16_hi v[154:155], v156, off
	v_mul_f32_e32 v154, v6, v0
	v_bfe_u32 v155, v154, 16, 1
	v_add3_u32 v156, v154, v155, s63
	v_add_co_u32_e32 v154, vcc, s1, v148
	s_nop 1
	v_addc_co_u32_e32 v155, vcc, 0, v149, vcc
	global_store_short_d16_hi v[154:155], v156, off
	v_mul_f32_e32 v154, v7, v0
	v_bfe_u32 v155, v154, 16, 1
	v_add3_u32 v156, v154, v155, s63
	v_add_co_u32_e32 v154, vcc, s6, v148
	s_nop 1
	v_addc_co_u32_e32 v155, vcc, 0, v149, vcc
	global_store_short_d16_hi v[154:155], v156, off
	v_mul_f32_e32 v154, v8, v0
	v_bfe_u32 v155, v154, 16, 1
	v_add3_u32 v156, v154, v155, s63
	v_add_co_u32_e32 v154, vcc, s83, v148
	s_nop 1
	v_addc_co_u32_e32 v155, vcc, 0, v149, vcc
	global_store_short_d16_hi v[154:155], v156, off
	v_mul_f32_e32 v154, v9, v0
	v_bfe_u32 v155, v154, 16, 1
	v_add_co_u32_e32 v148, vcc, s7, v148
	v_add3_u32 v154, v154, v155, s63
	s_nop 0
	v_addc_co_u32_e32 v149, vcc, 0, v149, vcc
	global_store_short_d16_hi v[148:149], v154, off
	v_lshl_add_u64 v[148:149], v[152:153], 0, v[150:151]
	v_mul_f32_e32 v150, v10, v0
	v_bfe_u32 v151, v150, 16, 1
	v_add3_u32 v150, v150, v151, s63
	global_store_short_d16_hi v[148:149], v150, off
	v_mul_f32_e32 v150, v11, v0
	v_bfe_u32 v151, v150, 16, 1
	v_add3_u32 v152, v150, v151, s63
	v_add_co_u32_e32 v150, vcc, s2, v148
	s_nop 1
	v_addc_co_u32_e32 v151, vcc, 0, v149, vcc
	global_store_short_d16_hi v[150:151], v152, off
	v_mul_f32_e32 v150, v12, v0
	v_bfe_u32 v151, v150, 16, 1
	v_add3_u32 v152, v150, v151, s63
	v_add_co_u32_e32 v150, vcc, s0, v148
	s_nop 1
	v_addc_co_u32_e32 v151, vcc, 0, v149, vcc
	global_store_short_d16_hi v[150:151], v152, off
	v_mul_f32_e32 v150, v13, v0
	v_bfe_u32 v151, v150, 16, 1
	v_add3_u32 v152, v150, v151, s63
	v_add_co_u32_e32 v150, vcc, s93, v148
	s_nop 1
	v_addc_co_u32_e32 v151, vcc, 0, v149, vcc
	global_store_short_d16_hi v[150:151], v152, off
	v_mul_f32_e32 v150, v2, v0
	v_bfe_u32 v151, v150, 16, 1
	v_add3_u32 v152, v150, v151, s63
	v_add_co_u32_e32 v150, vcc, s1, v148
	s_nop 1
	v_addc_co_u32_e32 v151, vcc, 0, v149, vcc
	global_store_short_d16_hi v[150:151], v152, off
	v_mul_f32_e32 v150, v3, v0
	v_bfe_u32 v151, v150, 16, 1
	v_add3_u32 v152, v150, v151, s63
	v_add_co_u32_e32 v150, vcc, 0x28000, v148
	s_nop 1
	v_addc_co_u32_e32 v151, vcc, 0, v149, vcc
	global_store_short_d16_hi v[150:151], v152, off
	v_mul_f32_e32 v150, v4, v0
	v_bfe_u32 v151, v150, 16, 1
	v_add3_u32 v152, v150, v151, s63
	v_add_co_u32_e32 v150, vcc, 0x30000, v148
	v_mul_f32_e32 v0, v5, v0
	s_nop 0
	v_addc_co_u32_e32 v151, vcc, 0, v149, vcc
	global_store_short_d16_hi v[150:151], v152, off
	v_bfe_u32 v150, v0, 16, 1
	v_add_co_u32_e32 v148, vcc, 0x38000, v148
	v_add3_u32 v0, v0, v150, s63
	s_nop 0
	v_addc_co_u32_e32 v149, vcc, 0, v149, vcc
	global_store_short_d16_hi v[148:149], v0, off

.LBB0_478:
	s_andn2_b64 vcc, exec, s[0:1]
	s_cbranch_vccnz .LBB0_543
	s_cmp_gt_i32 s62, 7
	s_cselect_b64 s[40:41], -1, 0
	s_cmp_lt_i32 s62, 8
	s_cselect_b64 s[30:31], -1, 0
	s_and_b32 s2, s62, 7
	v_cvt_f32_ubyte0_e32 v0, s2
	v_sub_f32_e32 v0, 0xc0a00000, v0
	s_mov_b32 s7, 0xc2fc0000
	v_cmp_gt_f32_e32 vcc, s7, v0
	s_and_b64 s[0:1], vcc, exec
	s_cselect_b32 s0, 0xffffffc0, 0
	v_cndmask_b32_e32 v148, 0, v213, vcc
	v_add_f32_e32 v0, v0, v148
	v_exp_f32_e32 v0, v0
	s_lshl_b32 s13, s61, 8
	s_mov_b64 s[38:39], -1
	v_ldexp_f32 v0, v0, s0
	v_sub_f32_e32 v150, 1.0, v0
	v_add_f32_e32 v148, -1.0, v150
	v_sub_f32_e32 v149, v148, v150
	v_add_f32_e32 v149, 1.0, v149
	v_sub_f32_e64 v148, -v0, v148
	v_add_f32_e32 v151, v148, v149
	v_frexp_mant_f32_e32 v148, v150
	s_mov_b32 s0, 0x3f2aaaab
	v_cmp_gt_f32_e32 vcc, s0, v148
	v_cvt_f64_f32_e32 v[148:149], v150
	v_frexp_exp_i32_f64_e32 v148, v[148:149]
	v_subbrev_co_u32_e32 v148, vcc, 0, v148, vcc
	v_sub_u32_e32 v149, 0, v148
	v_ldexp_f32 v150, v150, v149
	v_ldexp_f32 v149, v151, v149
	v_add_f32_e32 v151, -1.0, v150
	v_add_f32_e32 v152, 1.0, v151
	v_sub_f32_e32 v152, v150, v152
	v_add_f32_e32 v152, v149, v152
	v_add_f32_e32 v153, v151, v152
	v_sub_f32_e32 v151, v153, v151
	v_sub_f32_e32 v151, v152, v151
	v_add_f32_e32 v152, 1.0, v150
	v_add_f32_e32 v154, -1.0, v152
	v_sub_f32_e32 v150, v150, v154
	v_add_f32_e32 v149, v149, v150
	v_add_f32_e32 v150, v152, v149
	v_sub_f32_e32 v152, v150, v152
	v_sub_f32_e32 v149, v149, v152
	v_rcp_f32_e32 v152, v150
	v_cvt_f32_i32_e32 v148, v148
	s_mov_b32 s0, 0x3f317218
	v_cmp_nlt_f32_e32 vcc, 1.0, v0
	v_mul_f32_e32 v154, v153, v152
	v_mul_f32_e32 v155, v150, v154
	v_fma_f32 v156, v154, v150, -v155
	v_fmac_f32_e32 v156, v154, v149
	v_add_f32_e32 v157, v155, v156
	v_sub_f32_e32 v158, v153, v157
	v_sub_f32_e32 v153, v153, v158
	v_sub_f32_e32 v155, v157, v155
	v_sub_f32_e32 v153, v153, v157
	v_add_f32_e32 v151, v151, v153
	v_sub_f32_e32 v153, v155, v156
	v_add_f32_e32 v151, v153, v151
	v_add_f32_e32 v153, v158, v151
	v_mul_f32_e32 v155, v152, v153
	v_mul_f32_e32 v156, v150, v155
	v_fma_f32 v150, v155, v150, -v156
	v_fmac_f32_e32 v150, v155, v149
	v_sub_f32_e32 v149, v158, v153
	v_add_f32_e32 v149, v151, v149
	v_add_f32_e32 v151, v156, v150
	v_sub_f32_e32 v157, v153, v151
	v_sub_f32_e32 v153, v153, v157
	v_sub_f32_e32 v156, v151, v156
	v_sub_f32_e32 v151, v153, v151
	v_add_f32_e32 v149, v149, v151
	v_sub_f32_e32 v150, v156, v150
	v_add_f32_e32 v149, v150, v149
	v_add_f32_e32 v150, v154, v155
	v_add_f32_e32 v149, v157, v149
	v_sub_f32_e32 v151, v150, v154
	v_mul_f32_e32 v149, v152, v149
	v_sub_f32_e32 v151, v155, v151
	v_add_f32_e32 v149, v151, v149
	v_mul_f32_e32 v154, 0x3f317218, v148
	v_add_f32_e32 v151, v150, v149
	v_fma_f32 v155, v148, s0, -v154
	v_mul_f32_e32 v152, v151, v151
	v_fmac_f32_e32 v155, 0xb102e308, v148
	v_sub_f32_e32 v148, v151, v150
	v_fmamk_f32 v153, v152, 0x3e9b6dac, v212
	v_sub_f32_e32 v148, v149, v148
	v_add_f32_e32 v149, v154, v155
	v_fmaak_f32 v153, v152, v153, 0x3f2aaada
	v_sub_f32_e32 v150, v149, v154
	v_ldexp_f32 v154, v151, 1
	v_mul_f32_e32 v151, v151, v152
	v_mul_f32_e32 v151, v151, v153
	v_add_f32_e32 v152, v154, v151
	v_sub_f32_e32 v153, v152, v154
	v_ldexp_f32 v148, v148, 1
	v_sub_f32_e32 v151, v151, v153
	v_add_f32_e32 v148, v148, v151
	v_add_f32_e32 v151, v152, v148
	v_sub_f32_e32 v152, v151, v152
	v_sub_f32_e32 v148, v148, v152
	v_add_f32_e32 v152, v149, v151
	v_sub_f32_e32 v153, v152, v149
	v_sub_f32_e32 v154, v152, v153
	v_sub_f32_e32 v150, v155, v150
	v_sub_f32_e32 v149, v149, v154
	v_sub_f32_e32 v151, v151, v153
	v_add_f32_e32 v149, v151, v149
	v_add_f32_e32 v151, v150, v148
	v_sub_f32_e32 v153, v151, v150
	v_sub_f32_e32 v154, v151, v153
	v_sub_f32_e32 v150, v150, v154
	v_sub_f32_e32 v148, v148, v153
	v_add_f32_e32 v149, v151, v149
	v_add_f32_e32 v148, v148, v150
	v_add_f32_e32 v150, v152, v149
	v_sub_f32_e32 v151, v150, v152
	v_sub_f32_e32 v149, v149, v151
	v_add_f32_e32 v148, v148, v149
	v_add_f32_e32 v148, v150, v148
	v_cndmask_b32_e32 v148, v248, v148, vcc
	v_cmp_neq_f32_e32 vcc, 1.0, v0
	s_mov_b32 s0, 0x33800000
	v_add_u32_e32 v152, s13, v139
	v_cndmask_b32_e32 v148, v229, v148, vcc
	v_cmp_gt_f32_e32 vcc, s0, v0
	v_ashrrev_i32_e32 v153, 31, v152
	s_nop 0
	v_cndmask_b32_e64 v0, v148, -v0, vcc
	v_lshl_add_u64 v[148:149], v[152:153], 2, s[10:11]
	global_load_dword v150, v[148:149], off
	v_mul_f32_e32 v181, 0x3fb8aa3b, v0
	v_mul_f32_e32 v182, v181, v173
	s_and_b64 vcc, exec, s[30:31]
	v_cmp_gt_f32_e64 s[0:1], s7, v182
	s_cbranch_vccz .LBB0_481
	s_nop 0
	v_cndmask_b32_e64 v0, 0, v213, s[0:1]
	v_fmac_f32_e32 v0, v181, v173
	v_exp_f32_e32 v0, v0
	v_cndmask_b32_e64 v148, 0, v250, s[0:1]
	s_mov_b64 s[38:39], 0
	v_ldexp_f32 v154, v0, v148

.LBB0_483:
	s_and_b64 s[0:1], s[40:41], exec
	v_readlane_b32 s0, v254, 30
	v_readlane_b32 s1, v254, 31
	s_cselect_b32 s1, s45, s1
	s_cselect_b32 s0, s44, s0
	s_lshl_b32 s6, s2, 9
	s_add_u32 s0, s0, s6
	s_addc_u32 s1, s1, 0
	v_lshlrev_b32_e32 v0, 1, v138
	v_lshl_add_u64 v[148:149], s[0:1], 0, v[0:1]
	s_waitcnt vmcnt(0) lgkmcnt(0)
	v_fmamk_f32 v0, v150, 0x3a000000, v207
	v_cmp_gt_f32_e32 vcc, s87, v0
	v_mul_f32_e32 v150, 0x4b800000, v0
	s_nop 0
	v_cndmask_b32_e32 v0, v0, v150, vcc
	v_rsq_f32_e32 v0, v0
	s_nop 0
	v_mul_f32_e32 v150, 0x45800000, v0
	v_cndmask_b32_e32 v156, v0, v150, vcc
	v_lshlrev_b64 v[150:151], 9, v[152:153]
	v_lshl_add_u64 v[162:163], v[140:141], 0, v[150:151]
	v_lshl_add_u64 v[160:161], v[142:143], 0, v[150:151]
	global_load_dwordx4 v[184:187], v[162:163], off
	global_load_dwordx4 v[188:191], v[160:161], off
	v_pk_mul_f32 v[122:123], v[122:123], v[156:157] op_sel_hi:[1,0]
	v_pk_mul_f32 v[124:125], v[124:125], v[156:157] op_sel_hi:[1,0]
	v_lshlrev_b32_e32 v0, 15, v138
	v_pk_mul_f32 v[128:129], v[128:129], v[156:157] op_sel_hi:[1,0]
	v_pk_mul_f32 v[126:127], v[126:127], v[156:157] op_sel_hi:[1,0]
	v_lshlrev_b64 v[150:151], 12, v[152:153]
	v_lshl_or_b32 v0, s2, 23, v0
	v_lshl_add_u64 v[158:159], v[148:149], 0, v[150:151]
	v_lshl_add_u64 v[150:151], s[14:15], 0, v[0:1]
	v_cndmask_b32_e64 v0, 0, 1, s[40:41]
	v_lshl_add_u64 v[152:153], v[152:153], 1, v[150:151]
	v_cmp_ne_u32_e64 s[38:39], 1, v0
	s_andn2_b64 vcc, exec, s[40:41]
	s_waitcnt vmcnt(0) lgkmcnt(0)
	v_pk_mul_f32 v[192:193], v[124:125], v[190:191]
	v_pk_mul_f32 v[194:195], v[122:123], v[188:189]
	v_pk_fma_f32 v[192:193], v[128:129], v[186:187], v[192:193] neg_lo:[0,0,1] neg_hi:[0,0,1]
	v_pk_fma_f32 v[194:195], v[126:127], v[184:185], v[194:195] neg_lo:[0,0,1] neg_hi:[0,0,1]
	v_pk_mul_f32 v[128:129], v[128:129], v[190:191]
	v_pk_mul_f32 v[126:127], v[126:127], v[188:189]
	v_pk_fma_f32 v[124:125], v[124:125], v[186:187], v[128:129]
	v_pk_fma_f32 v[122:123], v[122:123], v[184:185], v[126:127]
	v_pk_mul_f32 v[192:193], v[154:155], v[192:193] op_sel_hi:[0,1]
	v_pk_mul_f32 v[194:195], v[154:155], v[194:195] op_sel_hi:[0,1]
	v_pk_mul_f32 v[126:127], v[154:155], v[124:125] op_sel_hi:[0,1]
	v_pk_mul_f32 v[122:123], v[154:155], v[122:123] op_sel_hi:[0,1]
	v_cvt_pk_bf16_f32 v124, v194, v195
	v_cvt_pk_bf16_f32 v125, v192, v193
	v_cvt_pk_bf16_f32 v122, v122, v123
	v_cvt_pk_bf16_f32 v123, v126, v127
	global_store_dwordx2 v[158:159], v[124:125], off
	global_store_dwordx2 v[158:159], v[122:123], off offset:256
	s_cbranch_vccnz .LBB0_485
	v_add_co_u32_e32 v126, vcc, 0x8000, v152
	global_store_short v[152:153], v124, off
	s_nop 0
	v_addc_co_u32_e32 v127, vcc, 0, v153, vcc
	global_store_short_d16_hi v[126:127], v124, off
	v_add_co_u32_e32 v126, vcc, 0x10000, v152
	s_nop 1
	v_addc_co_u32_e32 v127, vcc, 0, v153, vcc
	global_store_short v[126:127], v125, off
	v_add_co_u32_e32 v126, vcc, 0x18000, v152
	s_nop 1
	v_addc_co_u32_e32 v127, vcc, 0, v153, vcc
	v_add_co_u32_e32 v124, vcc, 0x400000, v152
	global_store_short_d16_hi v[126:127], v125, off
	s_nop 0
	v_addc_co_u32_e32 v125, vcc, 0, v153, vcc
	global_store_short v[124:125], v122, off
	v_add_co_u32_e32 v124, vcc, 0x408000, v152
	s_nop 1
	v_addc_co_u32_e32 v125, vcc, 0, v153, vcc
	global_store_short_d16_hi v[124:125], v122, off
	v_add_co_u32_e32 v124, vcc, 0x410000, v152
	s_nop 1
	v_addc_co_u32_e32 v125, vcc, 0, v153, vcc
	global_store_short v[124:125], v123, off
	v_add_co_u32_e32 v124, vcc, 0x418000, v152
	s_nop 1
	v_addc_co_u32_e32 v125, vcc, 0, v153, vcc
	global_store_short_d16_hi v[124:125], v123, off
.LBB0_485:
	global_load_dwordx4 v[122:125], v[162:163], off offset:16
	s_nop 0
	global_load_dwordx4 v[126:129], v[160:161], off offset:16
	v_mov_b32_e32 v157, v156
	v_mov_b32_e32 v160, v156
	v_mov_b32_e32 v161, v156
	v_pk_mul_f32 v[116:117], v[116:117], v[160:161]
	v_pk_mul_f32 v[114:115], v[114:115], v[156:157]
	v_pk_mul_f32 v[120:121], v[120:121], v[160:161]
	v_pk_mul_f32 v[118:119], v[118:119], v[156:157]
	v_mov_b32_e32 v155, v154
	v_mov_b32_e32 v162, v154
	v_mov_b32_e32 v163, v154
	s_and_b64 vcc, exec, s[38:39]
	s_waitcnt vmcnt(0) lgkmcnt(0)
	v_pk_mul_f32 v[156:157], v[116:117], v[128:129]
	v_pk_mul_f32 v[160:161], v[114:115], v[126:127]
	v_pk_fma_f32 v[156:157], v[120:121], v[124:125], v[156:157] neg_lo:[0,0,1] neg_hi:[0,0,1]
	v_pk_fma_f32 v[160:161], v[118:119], v[122:123], v[160:161] neg_lo:[0,0,1] neg_hi:[0,0,1]
	v_pk_mul_f32 v[120:121], v[120:121], v[128:129]
	v_pk_mul_f32 v[118:119], v[118:119], v[126:127]
	v_pk_fma_f32 v[116:117], v[116:117], v[124:125], v[120:121]
	v_pk_fma_f32 v[114:115], v[114:115], v[122:123], v[118:119]
	v_pk_mul_f32 v[156:157], v[162:163], v[156:157]
	v_pk_mul_f32 v[160:161], v[154:155], v[160:161]
	v_pk_mul_f32 v[118:119], v[162:163], v[116:117]
	v_pk_mul_f32 v[114:115], v[154:155], v[114:115]
	v_cvt_pk_bf16_f32 v116, v160, v161
	v_cvt_pk_bf16_f32 v117, v156, v157
	s_nop 0
	v_cvt_pk_bf16_f32 v114, v114, v115
	v_cvt_pk_bf16_f32 v115, v118, v119
	global_store_dwordx2 v[158:159], v[116:117], off offset:8
	global_store_dwordx2 v[158:159], v[114:115], off offset:264
	s_cbranch_vccnz .LBB0_487
	v_add_co_u32_e32 v118, vcc, 0x20000, v152
	s_nop 1
	v_addc_co_u32_e32 v119, vcc, 0, v153, vcc
	global_store_short v[118:119], v116, off
	v_add_co_u32_e32 v118, vcc, 0x28000, v152
	s_nop 1
	v_addc_co_u32_e32 v119, vcc, 0, v153, vcc
	global_store_short_d16_hi v[118:119], v116, off
	v_add_co_u32_e32 v118, vcc, 0x30000, v152
	s_nop 1
	v_addc_co_u32_e32 v119, vcc, 0, v153, vcc
	global_store_short v[118:119], v117, off
	v_add_co_u32_e32 v118, vcc, 0x38000, v152
	s_nop 1
	v_addc_co_u32_e32 v119, vcc, 0, v153, vcc
	v_add_co_u32_e32 v116, vcc, 0x420000, v152
	global_store_short_d16_hi v[118:119], v117, off
	s_nop 0
	v_addc_co_u32_e32 v117, vcc, 0, v153, vcc
	global_store_short v[116:117], v114, off
	v_add_co_u32_e32 v116, vcc, 0x428000, v152
	s_nop 1
	v_addc_co_u32_e32 v117, vcc, 0, v153, vcc
	global_store_short_d16_hi v[116:117], v114, off
	v_add_co_u32_e32 v116, vcc, 0x430000, v152
	s_nop 1
	v_addc_co_u32_e32 v117, vcc, 0, v153, vcc
	global_store_short v[116:117], v115, off
	v_add_co_u32_e32 v116, vcc, 0x438000, v152
	s_nop 1
	v_addc_co_u32_e32 v117, vcc, 0, v153, vcc
	global_store_short_d16_hi v[116:117], v115, off
.LBB0_487:
	v_add_u32_e32 v114, s13, v165
	v_ashrrev_i32_e32 v115, 31, v114
	v_lshl_add_u64 v[116:117], v[114:115], 2, s[10:11]
	global_load_dword v0, v[116:117], off
	v_cndmask_b32_e64 v116, 0, 1, s[30:31]
	v_cmp_ne_u32_e64 s[40:41], 1, v116
	s_andn2_b64 vcc, exec, s[30:31]
	s_mov_b64 s[0:1], -1
	s_cbranch_vccnz .LBB0_489
	v_mul_f32_e32 v116, v181, v174
	v_cmp_gt_f32_e32 vcc, s7, v116
	s_mov_b64 s[0:1], 0
	s_nop 0
	v_cndmask_b32_e32 v117, 0, v213, vcc
	v_fmac_f32_e32 v117, v181, v174
	v_exp_f32_e32 v117, v117
	v_cndmask_b32_e32 v116, 0, v250, vcc
	v_ldexp_f32 v116, v117, v116

.LBB0_491:
	v_lshlrev_b64 v[118:119], 9, v[114:115]
	v_lshl_add_u64 v[124:125], v[140:141], 0, v[118:119]
	v_lshl_add_u64 v[122:123], v[142:143], 0, v[118:119]
	global_load_dwordx4 v[126:129], v[124:125], off
	global_load_dwordx4 v[152:155], v[122:123], off
	s_waitcnt vmcnt(0) lgkmcnt(0)
	v_fmamk_f32 v0, v0, 0x3a000000, v207
	v_cmp_gt_f32_e32 vcc, s87, v0
	v_mul_f32_e32 v117, 0x4b800000, v0
	v_lshlrev_b64 v[118:119], 12, v[114:115]
	v_cndmask_b32_e32 v0, v0, v117, vcc
	v_rsq_f32_e32 v0, v0
	v_lshl_add_u64 v[118:119], v[148:149], 0, v[118:119]
	v_lshl_add_u64 v[114:115], v[114:115], 1, v[150:151]
	v_mul_f32_e32 v117, 0x45800000, v0
	v_cndmask_b32_e32 v120, v0, v117, vcc
	v_pk_mul_f32 v[106:107], v[106:107], v[120:121] op_sel_hi:[1,0]
	v_pk_mul_f32 v[108:109], v[108:109], v[120:121] op_sel_hi:[1,0]
	v_pk_mul_f32 v[112:113], v[112:113], v[120:121] op_sel_hi:[1,0]
	v_pk_mul_f32 v[110:111], v[110:111], v[120:121] op_sel_hi:[1,0]
	s_and_b64 vcc, exec, s[38:39]
	v_pk_mul_f32 v[156:157], v[108:109], v[154:155]
	v_pk_mul_f32 v[158:159], v[106:107], v[152:153]
	v_pk_fma_f32 v[156:157], v[112:113], v[128:129], v[156:157] neg_lo:[0,0,1] neg_hi:[0,0,1]
	v_pk_fma_f32 v[158:159], v[110:111], v[126:127], v[158:159] neg_lo:[0,0,1] neg_hi:[0,0,1]
	v_pk_mul_f32 v[112:113], v[112:113], v[154:155]
	v_pk_mul_f32 v[110:111], v[110:111], v[152:153]
	v_pk_fma_f32 v[108:109], v[108:109], v[128:129], v[112:113]
	v_pk_fma_f32 v[106:107], v[106:107], v[126:127], v[110:111]
	v_pk_mul_f32 v[156:157], v[116:117], v[156:157] op_sel_hi:[0,1]
	v_pk_mul_f32 v[158:159], v[116:117], v[158:159] op_sel_hi:[0,1]
	v_pk_mul_f32 v[110:111], v[116:117], v[108:109] op_sel_hi:[0,1]
	v_pk_mul_f32 v[106:107], v[116:117], v[106:107] op_sel_hi:[0,1]
	v_cvt_pk_bf16_f32 v108, v158, v159
	v_cvt_pk_bf16_f32 v109, v156, v157
	v_cvt_pk_bf16_f32 v106, v106, v107
	v_cvt_pk_bf16_f32 v107, v110, v111
	global_store_dwordx2 v[118:119], v[108:109], off
	global_store_dwordx2 v[118:119], v[106:107], off offset:256
	s_cbranch_vccnz .LBB0_493
	v_add_co_u32_e32 v110, vcc, 0x8000, v114
	global_store_short v[114:115], v108, off
	s_nop 0
	v_addc_co_u32_e32 v111, vcc, 0, v115, vcc
	global_store_short_d16_hi v[110:111], v108, off
	v_add_co_u32_e32 v110, vcc, 0x10000, v114
	s_nop 1
	v_addc_co_u32_e32 v111, vcc, 0, v115, vcc
	global_store_short v[110:111], v109, off
	v_add_co_u32_e32 v110, vcc, 0x18000, v114
	s_nop 1
	v_addc_co_u32_e32 v111, vcc, 0, v115, vcc
	v_add_co_u32_e32 v108, vcc, 0x400000, v114
	global_store_short_d16_hi v[110:111], v109, off
	s_nop 0
	v_addc_co_u32_e32 v109, vcc, 0, v115, vcc
	global_store_short v[108:109], v106, off
	v_add_co_u32_e32 v108, vcc, 0x408000, v114
	s_nop 1
	v_addc_co_u32_e32 v109, vcc, 0, v115, vcc
	global_store_short_d16_hi v[108:109], v106, off
	v_add_co_u32_e32 v108, vcc, 0x410000, v114
	s_nop 1
	v_addc_co_u32_e32 v109, vcc, 0, v115, vcc
	global_store_short v[108:109], v107, off
	v_add_co_u32_e32 v108, vcc, 0x418000, v114
	s_nop 1
	v_addc_co_u32_e32 v109, vcc, 0, v115, vcc
	global_store_short_d16_hi v[108:109], v107, off
.LBB0_493:
	global_load_dwordx4 v[106:109], v[124:125], off offset:16
	s_nop 0
	global_load_dwordx4 v[110:113], v[122:123], off offset:16
	v_mov_b32_e32 v121, v120
	v_mov_b32_e32 v122, v120
	v_mov_b32_e32 v123, v120
	v_pk_mul_f32 v[100:101], v[100:101], v[122:123]
	v_pk_mul_f32 v[98:99], v[98:99], v[120:121]
	v_pk_mul_f32 v[104:105], v[104:105], v[122:123]
	v_pk_mul_f32 v[102:103], v[102:103], v[120:121]
	v_mov_b32_e32 v117, v116
	v_mov_b32_e32 v124, v116
	v_mov_b32_e32 v125, v116
	s_and_b64 vcc, exec, s[38:39]
	s_waitcnt vmcnt(0) lgkmcnt(0)
	v_pk_mul_f32 v[120:121], v[100:101], v[112:113]
	v_pk_mul_f32 v[122:123], v[98:99], v[110:111]
	v_pk_fma_f32 v[120:121], v[104:105], v[108:109], v[120:121] neg_lo:[0,0,1] neg_hi:[0,0,1]
	v_pk_fma_f32 v[122:123], v[102:103], v[106:107], v[122:123] neg_lo:[0,0,1] neg_hi:[0,0,1]
	v_pk_mul_f32 v[104:105], v[104:105], v[112:113]
	v_pk_mul_f32 v[102:103], v[102:103], v[110:111]
	v_pk_fma_f32 v[100:101], v[100:101], v[108:109], v[104:105]
	v_pk_fma_f32 v[98:99], v[98:99], v[106:107], v[102:103]
	v_pk_mul_f32 v[120:121], v[124:125], v[120:121]
	v_pk_mul_f32 v[122:123], v[116:117], v[122:123]
	v_pk_mul_f32 v[102:103], v[124:125], v[100:101]
	v_pk_mul_f32 v[98:99], v[116:117], v[98:99]
	v_cvt_pk_bf16_f32 v100, v122, v123
	v_cvt_pk_bf16_f32 v101, v120, v121
	s_nop 0
	v_cvt_pk_bf16_f32 v98, v98, v99
	v_cvt_pk_bf16_f32 v99, v102, v103
	global_store_dwordx2 v[118:119], v[100:101], off offset:8
	global_store_dwordx2 v[118:119], v[98:99], off offset:264
	s_cbranch_vccnz .LBB0_495
	v_add_co_u32_e32 v102, vcc, 0x20000, v114
	s_nop 1
	v_addc_co_u32_e32 v103, vcc, 0, v115, vcc
	global_store_short v[102:103], v100, off
	v_add_co_u32_e32 v102, vcc, 0x28000, v114
	s_nop 1
	v_addc_co_u32_e32 v103, vcc, 0, v115, vcc
	global_store_short_d16_hi v[102:103], v100, off
	v_add_co_u32_e32 v102, vcc, 0x30000, v114
	s_nop 1
	v_addc_co_u32_e32 v103, vcc, 0, v115, vcc
	global_store_short v[102:103], v101, off
	v_add_co_u32_e32 v102, vcc, 0x38000, v114
	s_nop 1
	v_addc_co_u32_e32 v103, vcc, 0, v115, vcc
	v_add_co_u32_e32 v100, vcc, 0x420000, v114
	global_store_short_d16_hi v[102:103], v101, off
	s_nop 0
	v_addc_co_u32_e32 v101, vcc, 0, v115, vcc
	global_store_short v[100:101], v98, off
	v_add_co_u32_e32 v100, vcc, 0x428000, v114
	s_nop 1
	v_addc_co_u32_e32 v101, vcc, 0, v115, vcc
	global_store_short_d16_hi v[100:101], v98, off
	v_add_co_u32_e32 v100, vcc, 0x430000, v114
	s_nop 1
	v_addc_co_u32_e32 v101, vcc, 0, v115, vcc
	global_store_short v[100:101], v99, off
	v_add_co_u32_e32 v100, vcc, 0x438000, v114
	s_nop 1
	v_addc_co_u32_e32 v101, vcc, 0, v115, vcc
	global_store_short_d16_hi v[100:101], v99, off
.LBB0_495:
	v_add_u32_e32 v98, s13, v166
	v_ashrrev_i32_e32 v99, 31, v98
	v_lshl_add_u64 v[100:101], v[98:99], 2, s[10:11]
	global_load_dword v0, v[100:101], off
	s_and_b64 vcc, exec, s[40:41]
	s_mov_b64 s[0:1], -1
	s_cbranch_vccnz .LBB0_497
	v_mul_f32_e32 v100, v181, v175
	v_cmp_gt_f32_e32 vcc, s7, v100
	s_mov_b64 s[0:1], 0
	s_nop 0
	v_cndmask_b32_e32 v101, 0, v213, vcc
	v_fmac_f32_e32 v101, v181, v175
	v_exp_f32_e32 v101, v101
	v_cndmask_b32_e32 v100, 0, v250, vcc
	v_ldexp_f32 v100, v101, v100

.LBB0_499:
	v_lshlrev_b64 v[102:103], 9, v[98:99]
	v_lshl_add_u64 v[108:109], v[140:141], 0, v[102:103]
	v_lshl_add_u64 v[106:107], v[142:143], 0, v[102:103]
	global_load_dwordx4 v[110:113], v[108:109], off
	global_load_dwordx4 v[114:117], v[106:107], off
	s_waitcnt vmcnt(0) lgkmcnt(0)
	v_fmamk_f32 v0, v0, 0x3a000000, v207
	v_cmp_gt_f32_e32 vcc, s87, v0
	v_mul_f32_e32 v101, 0x4b800000, v0
	v_lshlrev_b64 v[102:103], 12, v[98:99]
	v_cndmask_b32_e32 v0, v0, v101, vcc
	v_rsq_f32_e32 v0, v0
	v_lshl_add_u64 v[102:103], v[148:149], 0, v[102:103]
	v_lshl_add_u64 v[98:99], v[98:99], 1, v[150:151]
	v_mul_f32_e32 v101, 0x45800000, v0
	v_cndmask_b32_e32 v104, v0, v101, vcc
	v_pk_mul_f32 v[90:91], v[90:91], v[104:105] op_sel_hi:[1,0]
	v_pk_mul_f32 v[92:93], v[92:93], v[104:105] op_sel_hi:[1,0]
	v_pk_mul_f32 v[96:97], v[96:97], v[104:105] op_sel_hi:[1,0]
	v_pk_mul_f32 v[94:95], v[94:95], v[104:105] op_sel_hi:[1,0]
	s_and_b64 vcc, exec, s[38:39]
	v_pk_mul_f32 v[118:119], v[92:93], v[116:117]
	v_pk_mul_f32 v[120:121], v[90:91], v[114:115]
	v_pk_fma_f32 v[118:119], v[96:97], v[112:113], v[118:119] neg_lo:[0,0,1] neg_hi:[0,0,1]
	v_pk_fma_f32 v[120:121], v[94:95], v[110:111], v[120:121] neg_lo:[0,0,1] neg_hi:[0,0,1]
	v_pk_mul_f32 v[96:97], v[96:97], v[116:117]
	v_pk_mul_f32 v[94:95], v[94:95], v[114:115]
	v_pk_fma_f32 v[92:93], v[92:93], v[112:113], v[96:97]
	v_pk_fma_f32 v[90:91], v[90:91], v[110:111], v[94:95]
	v_pk_mul_f32 v[118:119], v[100:101], v[118:119] op_sel_hi:[0,1]
	v_pk_mul_f32 v[120:121], v[100:101], v[120:121] op_sel_hi:[0,1]
	v_pk_mul_f32 v[94:95], v[100:101], v[92:93] op_sel_hi:[0,1]
	v_pk_mul_f32 v[90:91], v[100:101], v[90:91] op_sel_hi:[0,1]
	v_cvt_pk_bf16_f32 v92, v120, v121
	v_cvt_pk_bf16_f32 v93, v118, v119
	v_cvt_pk_bf16_f32 v90, v90, v91
	v_cvt_pk_bf16_f32 v91, v94, v95
	global_store_dwordx2 v[102:103], v[92:93], off
	global_store_dwordx2 v[102:103], v[90:91], off offset:256
	s_cbranch_vccnz .LBB0_501
	v_add_co_u32_e32 v94, vcc, 0x8000, v98
	global_store_short v[98:99], v92, off
	s_nop 0
	v_addc_co_u32_e32 v95, vcc, 0, v99, vcc
	global_store_short_d16_hi v[94:95], v92, off
	v_add_co_u32_e32 v94, vcc, 0x10000, v98
	s_nop 1
	v_addc_co_u32_e32 v95, vcc, 0, v99, vcc
	global_store_short v[94:95], v93, off
	v_add_co_u32_e32 v94, vcc, 0x18000, v98
	s_nop 1
	v_addc_co_u32_e32 v95, vcc, 0, v99, vcc
	v_add_co_u32_e32 v92, vcc, 0x400000, v98
	global_store_short_d16_hi v[94:95], v93, off
	s_nop 0
	v_addc_co_u32_e32 v93, vcc, 0, v99, vcc
	global_store_short v[92:93], v90, off
	v_add_co_u32_e32 v92, vcc, 0x408000, v98
	s_nop 1
	v_addc_co_u32_e32 v93, vcc, 0, v99, vcc
	global_store_short_d16_hi v[92:93], v90, off
	v_add_co_u32_e32 v92, vcc, 0x410000, v98
	s_nop 1
	v_addc_co_u32_e32 v93, vcc, 0, v99, vcc
	global_store_short v[92:93], v91, off
	v_add_co_u32_e32 v92, vcc, 0x418000, v98
	s_nop 1
	v_addc_co_u32_e32 v93, vcc, 0, v99, vcc
	global_store_short_d16_hi v[92:93], v91, off
.LBB0_501:
	global_load_dwordx4 v[90:93], v[108:109], off offset:16
	s_nop 0
	global_load_dwordx4 v[94:97], v[106:107], off offset:16
	v_mov_b32_e32 v105, v104
	v_mov_b32_e32 v106, v104
	v_mov_b32_e32 v107, v104
	v_pk_mul_f32 v[84:85], v[84:85], v[106:107]
	v_pk_mul_f32 v[82:83], v[82:83], v[104:105]
	v_pk_mul_f32 v[88:89], v[88:89], v[106:107]
	v_pk_mul_f32 v[86:87], v[86:87], v[104:105]
	v_mov_b32_e32 v101, v100
	v_mov_b32_e32 v108, v100
	v_mov_b32_e32 v109, v100
	s_and_b64 vcc, exec, s[38:39]
	s_waitcnt vmcnt(0) lgkmcnt(0)
	v_pk_mul_f32 v[104:105], v[84:85], v[96:97]
	v_pk_mul_f32 v[106:107], v[82:83], v[94:95]
	v_pk_fma_f32 v[104:105], v[88:89], v[92:93], v[104:105] neg_lo:[0,0,1] neg_hi:[0,0,1]
	v_pk_fma_f32 v[106:107], v[86:87], v[90:91], v[106:107] neg_lo:[0,0,1] neg_hi:[0,0,1]
	v_pk_mul_f32 v[88:89], v[88:89], v[96:97]
	v_pk_mul_f32 v[86:87], v[86:87], v[94:95]
	v_pk_fma_f32 v[84:85], v[84:85], v[92:93], v[88:89]
	v_pk_fma_f32 v[82:83], v[82:83], v[90:91], v[86:87]
	v_pk_mul_f32 v[104:105], v[108:109], v[104:105]
	v_pk_mul_f32 v[106:107], v[100:101], v[106:107]
	v_pk_mul_f32 v[86:87], v[108:109], v[84:85]
	v_pk_mul_f32 v[82:83], v[100:101], v[82:83]
	v_cvt_pk_bf16_f32 v84, v106, v107
	v_cvt_pk_bf16_f32 v85, v104, v105
	s_nop 0
	v_cvt_pk_bf16_f32 v82, v82, v83
	v_cvt_pk_bf16_f32 v83, v86, v87
	global_store_dwordx2 v[102:103], v[84:85], off offset:8
	global_store_dwordx2 v[102:103], v[82:83], off offset:264
	s_cbranch_vccnz .LBB0_503
	v_add_co_u32_e32 v86, vcc, 0x20000, v98
	s_nop 1
	v_addc_co_u32_e32 v87, vcc, 0, v99, vcc
	global_store_short v[86:87], v84, off
	v_add_co_u32_e32 v86, vcc, 0x28000, v98
	s_nop 1
	v_addc_co_u32_e32 v87, vcc, 0, v99, vcc
	global_store_short_d16_hi v[86:87], v84, off
	v_add_co_u32_e32 v86, vcc, 0x30000, v98
	s_nop 1
	v_addc_co_u32_e32 v87, vcc, 0, v99, vcc
	global_store_short v[86:87], v85, off
	v_add_co_u32_e32 v86, vcc, 0x38000, v98
	s_nop 1
	v_addc_co_u32_e32 v87, vcc, 0, v99, vcc
	v_add_co_u32_e32 v84, vcc, 0x420000, v98
	global_store_short_d16_hi v[86:87], v85, off
	s_nop 0
	v_addc_co_u32_e32 v85, vcc, 0, v99, vcc
	global_store_short v[84:85], v82, off
	v_add_co_u32_e32 v84, vcc, 0x428000, v98
	s_nop 1
	v_addc_co_u32_e32 v85, vcc, 0, v99, vcc
	global_store_short_d16_hi v[84:85], v82, off
	v_add_co_u32_e32 v84, vcc, 0x430000, v98
	s_nop 1
	v_addc_co_u32_e32 v85, vcc, 0, v99, vcc
	global_store_short v[84:85], v83, off
	v_add_co_u32_e32 v84, vcc, 0x438000, v98
	s_nop 1
	v_addc_co_u32_e32 v85, vcc, 0, v99, vcc
	global_store_short_d16_hi v[84:85], v83, off
.LBB0_503:
	v_add_u32_e32 v82, s13, v167
	v_ashrrev_i32_e32 v83, 31, v82
	v_lshl_add_u64 v[84:85], v[82:83], 2, s[10:11]
	global_load_dword v0, v[84:85], off
	s_and_b64 vcc, exec, s[40:41]
	s_mov_b64 s[0:1], -1
	s_cbranch_vccnz .LBB0_505
	v_mul_f32_e32 v84, v181, v176
	v_cmp_gt_f32_e32 vcc, s7, v84
	s_mov_b64 s[0:1], 0
	s_nop 0
	v_cndmask_b32_e32 v85, 0, v213, vcc
	v_fmac_f32_e32 v85, v181, v176
	v_exp_f32_e32 v85, v85
	v_cndmask_b32_e32 v84, 0, v250, vcc
	v_ldexp_f32 v84, v85, v84

.LBB0_507:
	v_lshlrev_b64 v[86:87], 9, v[82:83]
	v_lshl_add_u64 v[92:93], v[140:141], 0, v[86:87]
	v_lshl_add_u64 v[90:91], v[142:143], 0, v[86:87]
	global_load_dwordx4 v[94:97], v[92:93], off
	global_load_dwordx4 v[98:101], v[90:91], off
	s_waitcnt vmcnt(0) lgkmcnt(0)
	v_fmamk_f32 v0, v0, 0x3a000000, v207
	v_cmp_gt_f32_e32 vcc, s87, v0
	v_mul_f32_e32 v85, 0x4b800000, v0
	v_lshlrev_b64 v[86:87], 12, v[82:83]
	v_cndmask_b32_e32 v0, v0, v85, vcc
	v_rsq_f32_e32 v0, v0
	v_lshl_add_u64 v[86:87], v[148:149], 0, v[86:87]
	v_lshl_add_u64 v[82:83], v[82:83], 1, v[150:151]
	v_mul_f32_e32 v85, 0x45800000, v0
	v_cndmask_b32_e32 v88, v0, v85, vcc
	v_pk_mul_f32 v[74:75], v[74:75], v[88:89] op_sel_hi:[1,0]
	v_pk_mul_f32 v[76:77], v[76:77], v[88:89] op_sel_hi:[1,0]
	v_pk_mul_f32 v[80:81], v[80:81], v[88:89] op_sel_hi:[1,0]
	v_pk_mul_f32 v[78:79], v[78:79], v[88:89] op_sel_hi:[1,0]
	s_and_b64 vcc, exec, s[38:39]
	v_pk_mul_f32 v[102:103], v[76:77], v[100:101]
	v_pk_mul_f32 v[104:105], v[74:75], v[98:99]
	v_pk_fma_f32 v[102:103], v[80:81], v[96:97], v[102:103] neg_lo:[0,0,1] neg_hi:[0,0,1]
	v_pk_fma_f32 v[104:105], v[78:79], v[94:95], v[104:105] neg_lo:[0,0,1] neg_hi:[0,0,1]
	v_pk_mul_f32 v[80:81], v[80:81], v[100:101]
	v_pk_mul_f32 v[78:79], v[78:79], v[98:99]
	v_pk_fma_f32 v[76:77], v[76:77], v[96:97], v[80:81]
	v_pk_fma_f32 v[74:75], v[74:75], v[94:95], v[78:79]
	v_pk_mul_f32 v[102:103], v[84:85], v[102:103] op_sel_hi:[0,1]
	v_pk_mul_f32 v[104:105], v[84:85], v[104:105] op_sel_hi:[0,1]
	v_pk_mul_f32 v[78:79], v[84:85], v[76:77] op_sel_hi:[0,1]
	v_pk_mul_f32 v[74:75], v[84:85], v[74:75] op_sel_hi:[0,1]
	v_cvt_pk_bf16_f32 v76, v104, v105
	v_cvt_pk_bf16_f32 v77, v102, v103
	v_cvt_pk_bf16_f32 v74, v74, v75
	v_cvt_pk_bf16_f32 v75, v78, v79
	global_store_dwordx2 v[86:87], v[76:77], off
	global_store_dwordx2 v[86:87], v[74:75], off offset:256
	s_cbranch_vccnz .LBB0_509
	v_add_co_u32_e32 v78, vcc, 0x8000, v82
	global_store_short v[82:83], v76, off
	s_nop 0
	v_addc_co_u32_e32 v79, vcc, 0, v83, vcc
	global_store_short_d16_hi v[78:79], v76, off
	v_add_co_u32_e32 v78, vcc, 0x10000, v82
	s_nop 1
	v_addc_co_u32_e32 v79, vcc, 0, v83, vcc
	global_store_short v[78:79], v77, off
	v_add_co_u32_e32 v78, vcc, 0x18000, v82
	s_nop 1
	v_addc_co_u32_e32 v79, vcc, 0, v83, vcc
	v_add_co_u32_e32 v76, vcc, 0x400000, v82
	global_store_short_d16_hi v[78:79], v77, off
	s_nop 0
	v_addc_co_u32_e32 v77, vcc, 0, v83, vcc
	global_store_short v[76:77], v74, off
	v_add_co_u32_e32 v76, vcc, 0x408000, v82
	s_nop 1
	v_addc_co_u32_e32 v77, vcc, 0, v83, vcc
	global_store_short_d16_hi v[76:77], v74, off
	v_add_co_u32_e32 v76, vcc, 0x410000, v82
	s_nop 1
	v_addc_co_u32_e32 v77, vcc, 0, v83, vcc
	global_store_short v[76:77], v75, off
	v_add_co_u32_e32 v76, vcc, 0x418000, v82
	s_nop 1
	v_addc_co_u32_e32 v77, vcc, 0, v83, vcc
	global_store_short_d16_hi v[76:77], v75, off
.LBB0_509:
	global_load_dwordx4 v[74:77], v[92:93], off offset:16
	s_nop 0
	global_load_dwordx4 v[78:81], v[90:91], off offset:16
	v_mov_b32_e32 v89, v88
	v_mov_b32_e32 v90, v88
	v_mov_b32_e32 v91, v88
	v_pk_mul_f32 v[68:69], v[68:69], v[90:91]
	v_pk_mul_f32 v[66:67], v[66:67], v[88:89]
	v_pk_mul_f32 v[72:73], v[72:73], v[90:91]
	v_pk_mul_f32 v[70:71], v[70:71], v[88:89]
	v_mov_b32_e32 v85, v84
	v_mov_b32_e32 v92, v84
	v_mov_b32_e32 v93, v84
	s_and_b64 vcc, exec, s[38:39]
	s_waitcnt vmcnt(0) lgkmcnt(0)
	v_pk_mul_f32 v[88:89], v[68:69], v[80:81]
	v_pk_mul_f32 v[90:91], v[66:67], v[78:79]
	v_pk_fma_f32 v[88:89], v[72:73], v[76:77], v[88:89] neg_lo:[0,0,1] neg_hi:[0,0,1]
	v_pk_fma_f32 v[90:91], v[70:71], v[74:75], v[90:91] neg_lo:[0,0,1] neg_hi:[0,0,1]
	v_pk_mul_f32 v[72:73], v[72:73], v[80:81]
	v_pk_mul_f32 v[70:71], v[70:71], v[78:79]
	v_pk_fma_f32 v[68:69], v[68:69], v[76:77], v[72:73]
	v_pk_fma_f32 v[66:67], v[66:67], v[74:75], v[70:71]
	v_pk_mul_f32 v[88:89], v[92:93], v[88:89]
	v_pk_mul_f32 v[90:91], v[84:85], v[90:91]
	v_pk_mul_f32 v[70:71], v[92:93], v[68:69]
	v_pk_mul_f32 v[66:67], v[84:85], v[66:67]
	v_cvt_pk_bf16_f32 v68, v90, v91
	v_cvt_pk_bf16_f32 v69, v88, v89
	s_nop 0
	v_cvt_pk_bf16_f32 v66, v66, v67
	v_cvt_pk_bf16_f32 v67, v70, v71
	global_store_dwordx2 v[86:87], v[68:69], off offset:8
	global_store_dwordx2 v[86:87], v[66:67], off offset:264
	s_cbranch_vccnz .LBB0_511
	v_add_co_u32_e32 v70, vcc, 0x20000, v82
	s_nop 1
	v_addc_co_u32_e32 v71, vcc, 0, v83, vcc
	global_store_short v[70:71], v68, off
	v_add_co_u32_e32 v70, vcc, 0x28000, v82
	s_nop 1
	v_addc_co_u32_e32 v71, vcc, 0, v83, vcc
	global_store_short_d16_hi v[70:71], v68, off
	v_add_co_u32_e32 v70, vcc, 0x30000, v82
	s_nop 1
	v_addc_co_u32_e32 v71, vcc, 0, v83, vcc
	global_store_short v[70:71], v69, off
	v_add_co_u32_e32 v70, vcc, 0x38000, v82
	s_nop 1
	v_addc_co_u32_e32 v71, vcc, 0, v83, vcc
	v_add_co_u32_e32 v68, vcc, 0x420000, v82
	global_store_short_d16_hi v[70:71], v69, off
	s_nop 0
	v_addc_co_u32_e32 v69, vcc, 0, v83, vcc
	global_store_short v[68:69], v66, off
	v_add_co_u32_e32 v68, vcc, 0x428000, v82
	s_nop 1
	v_addc_co_u32_e32 v69, vcc, 0, v83, vcc
	global_store_short_d16_hi v[68:69], v66, off
	v_add_co_u32_e32 v68, vcc, 0x430000, v82
	s_nop 1
	v_addc_co_u32_e32 v69, vcc, 0, v83, vcc
	global_store_short v[68:69], v67, off
	v_add_co_u32_e32 v68, vcc, 0x438000, v82
	s_nop 1
	v_addc_co_u32_e32 v69, vcc, 0, v83, vcc
	global_store_short_d16_hi v[68:69], v67, off
.LBB0_511:
	v_add_u32_e32 v66, s13, v168
	v_ashrrev_i32_e32 v67, 31, v66
	v_lshl_add_u64 v[68:69], v[66:67], 2, s[10:11]
	global_load_dword v0, v[68:69], off
	s_and_b64 vcc, exec, s[40:41]
	s_mov_b64 s[0:1], -1
	s_cbranch_vccnz .LBB0_513
	v_cmp_gt_f32_e32 vcc, s7, v182
	s_mov_b64 s[0:1], 0
	s_nop 0
	v_cndmask_b32_e32 v69, 0, v213, vcc
	v_fmac_f32_e32 v69, v181, v173
	v_exp_f32_e32 v69, v69
	v_cndmask_b32_e32 v68, 0, v250, vcc
	v_ldexp_f32 v68, v69, v68

.LBB0_515:
	v_lshlrev_b64 v[70:71], 9, v[66:67]
	v_lshl_add_u64 v[76:77], v[140:141], 0, v[70:71]
	v_lshl_add_u64 v[74:75], v[142:143], 0, v[70:71]
	global_load_dwordx4 v[78:81], v[76:77], off
	global_load_dwordx4 v[82:85], v[74:75], off
	s_waitcnt vmcnt(0) lgkmcnt(0)
	v_fmamk_f32 v0, v0, 0x3a000000, v207
	v_cmp_gt_f32_e32 vcc, s87, v0
	v_mul_f32_e32 v69, 0x4b800000, v0
	v_lshlrev_b64 v[70:71], 12, v[66:67]
	v_cndmask_b32_e32 v0, v0, v69, vcc
	v_rsq_f32_e32 v0, v0
	v_lshl_add_u64 v[70:71], v[148:149], 0, v[70:71]
	v_lshl_add_u64 v[66:67], v[66:67], 1, v[150:151]
	v_mul_f32_e32 v69, 0x45800000, v0
	v_cndmask_b32_e32 v72, v0, v69, vcc
	v_pk_mul_f32 v[58:59], v[58:59], v[72:73] op_sel_hi:[1,0]
	v_pk_mul_f32 v[60:61], v[60:61], v[72:73] op_sel_hi:[1,0]
	v_pk_mul_f32 v[64:65], v[64:65], v[72:73] op_sel_hi:[1,0]
	v_pk_mul_f32 v[62:63], v[62:63], v[72:73] op_sel_hi:[1,0]
	s_and_b64 vcc, exec, s[38:39]
	v_pk_mul_f32 v[86:87], v[60:61], v[84:85]
	v_pk_mul_f32 v[88:89], v[58:59], v[82:83]
	v_pk_fma_f32 v[86:87], v[64:65], v[80:81], v[86:87] neg_lo:[0,0,1] neg_hi:[0,0,1]
	v_pk_fma_f32 v[88:89], v[62:63], v[78:79], v[88:89] neg_lo:[0,0,1] neg_hi:[0,0,1]
	v_pk_mul_f32 v[64:65], v[64:65], v[84:85]
	v_pk_mul_f32 v[62:63], v[62:63], v[82:83]
	v_pk_fma_f32 v[60:61], v[60:61], v[80:81], v[64:65]
	v_pk_fma_f32 v[58:59], v[58:59], v[78:79], v[62:63]
	v_pk_mul_f32 v[86:87], v[68:69], v[86:87] op_sel_hi:[0,1]
	v_pk_mul_f32 v[88:89], v[68:69], v[88:89] op_sel_hi:[0,1]
	v_pk_mul_f32 v[62:63], v[68:69], v[60:61] op_sel_hi:[0,1]
	v_pk_mul_f32 v[58:59], v[68:69], v[58:59] op_sel_hi:[0,1]
	v_cvt_pk_bf16_f32 v60, v88, v89
	v_cvt_pk_bf16_f32 v61, v86, v87
	v_cvt_pk_bf16_f32 v58, v58, v59
	v_cvt_pk_bf16_f32 v59, v62, v63
	global_store_dwordx2 v[70:71], v[60:61], off
	global_store_dwordx2 v[70:71], v[58:59], off offset:256
	s_cbranch_vccnz .LBB0_517
	v_add_co_u32_e32 v62, vcc, 0x8000, v66
	global_store_short v[66:67], v60, off
	s_nop 0
	v_addc_co_u32_e32 v63, vcc, 0, v67, vcc
	global_store_short_d16_hi v[62:63], v60, off
	v_add_co_u32_e32 v62, vcc, 0x10000, v66
	s_nop 1
	v_addc_co_u32_e32 v63, vcc, 0, v67, vcc
	global_store_short v[62:63], v61, off
	v_add_co_u32_e32 v62, vcc, 0x18000, v66
	s_nop 1
	v_addc_co_u32_e32 v63, vcc, 0, v67, vcc
	v_add_co_u32_e32 v60, vcc, 0x400000, v66
	global_store_short_d16_hi v[62:63], v61, off
	s_nop 0
	v_addc_co_u32_e32 v61, vcc, 0, v67, vcc
	global_store_short v[60:61], v58, off
	v_add_co_u32_e32 v60, vcc, 0x408000, v66
	s_nop 1
	v_addc_co_u32_e32 v61, vcc, 0, v67, vcc
	global_store_short_d16_hi v[60:61], v58, off
	v_add_co_u32_e32 v60, vcc, 0x410000, v66
	s_nop 1
	v_addc_co_u32_e32 v61, vcc, 0, v67, vcc
	global_store_short v[60:61], v59, off
	v_add_co_u32_e32 v60, vcc, 0x418000, v66
	s_nop 1
	v_addc_co_u32_e32 v61, vcc, 0, v67, vcc
	global_store_short_d16_hi v[60:61], v59, off
.LBB0_517:
	global_load_dwordx4 v[58:61], v[76:77], off offset:16
	s_nop 0
	global_load_dwordx4 v[62:65], v[74:75], off offset:16
	v_mov_b32_e32 v73, v72
	v_mov_b32_e32 v74, v72
	v_mov_b32_e32 v75, v72
	v_pk_mul_f32 v[52:53], v[52:53], v[74:75]
	v_pk_mul_f32 v[50:51], v[50:51], v[72:73]
	v_pk_mul_f32 v[56:57], v[56:57], v[74:75]
	v_pk_mul_f32 v[54:55], v[54:55], v[72:73]
	v_mov_b32_e32 v69, v68
	v_mov_b32_e32 v76, v68
	v_mov_b32_e32 v77, v68
	s_and_b64 vcc, exec, s[38:39]
	s_waitcnt vmcnt(0) lgkmcnt(0)
	v_pk_mul_f32 v[72:73], v[52:53], v[64:65]
	v_pk_mul_f32 v[74:75], v[50:51], v[62:63]
	v_pk_fma_f32 v[72:73], v[56:57], v[60:61], v[72:73] neg_lo:[0,0,1] neg_hi:[0,0,1]
	v_pk_fma_f32 v[74:75], v[54:55], v[58:59], v[74:75] neg_lo:[0,0,1] neg_hi:[0,0,1]
	v_pk_mul_f32 v[56:57], v[56:57], v[64:65]
	v_pk_mul_f32 v[54:55], v[54:55], v[62:63]
	v_pk_fma_f32 v[52:53], v[52:53], v[60:61], v[56:57]
	v_pk_fma_f32 v[50:51], v[50:51], v[58:59], v[54:55]
	v_pk_mul_f32 v[72:73], v[76:77], v[72:73]
	v_pk_mul_f32 v[74:75], v[68:69], v[74:75]
	v_pk_mul_f32 v[54:55], v[76:77], v[52:53]
	v_pk_mul_f32 v[50:51], v[68:69], v[50:51]
	v_cvt_pk_bf16_f32 v52, v74, v75
	v_cvt_pk_bf16_f32 v53, v72, v73
	s_nop 0
	v_cvt_pk_bf16_f32 v50, v50, v51
	v_cvt_pk_bf16_f32 v51, v54, v55
	global_store_dwordx2 v[70:71], v[52:53], off offset:8
	global_store_dwordx2 v[70:71], v[50:51], off offset:264
	s_cbranch_vccnz .LBB0_519
	v_add_co_u32_e32 v54, vcc, 0x20000, v66
	s_nop 1
	v_addc_co_u32_e32 v55, vcc, 0, v67, vcc
	global_store_short v[54:55], v52, off
	v_add_co_u32_e32 v54, vcc, 0x28000, v66
	s_nop 1
	v_addc_co_u32_e32 v55, vcc, 0, v67, vcc
	global_store_short_d16_hi v[54:55], v52, off
	v_add_co_u32_e32 v54, vcc, 0x30000, v66
	s_nop 1
	v_addc_co_u32_e32 v55, vcc, 0, v67, vcc
	global_store_short v[54:55], v53, off
	v_add_co_u32_e32 v54, vcc, 0x38000, v66
	s_nop 1
	v_addc_co_u32_e32 v55, vcc, 0, v67, vcc
	v_add_co_u32_e32 v52, vcc, 0x420000, v66
	global_store_short_d16_hi v[54:55], v53, off
	s_nop 0
	v_addc_co_u32_e32 v53, vcc, 0, v67, vcc
	global_store_short v[52:53], v50, off
	v_add_co_u32_e32 v52, vcc, 0x428000, v66
	s_nop 1
	v_addc_co_u32_e32 v53, vcc, 0, v67, vcc
	global_store_short_d16_hi v[52:53], v50, off
	v_add_co_u32_e32 v52, vcc, 0x430000, v66
	s_nop 1
	v_addc_co_u32_e32 v53, vcc, 0, v67, vcc
	global_store_short v[52:53], v51, off
	v_add_co_u32_e32 v52, vcc, 0x438000, v66
	s_nop 1
	v_addc_co_u32_e32 v53, vcc, 0, v67, vcc
	global_store_short_d16_hi v[52:53], v51, off
.LBB0_519:
	v_add_u32_e32 v50, s13, v169
	v_ashrrev_i32_e32 v51, 31, v50
	v_lshl_add_u64 v[52:53], v[50:51], 2, s[10:11]
	global_load_dword v0, v[52:53], off
	s_and_b64 vcc, exec, s[40:41]
	s_mov_b64 s[0:1], -1
	s_cbranch_vccnz .LBB0_521
	v_mul_f32_e32 v52, v181, v177
	v_cmp_gt_f32_e32 vcc, s7, v52
	s_mov_b64 s[0:1], 0
	s_nop 0
	v_cndmask_b32_e32 v53, 0, v213, vcc
	v_fmac_f32_e32 v53, v181, v177
	v_exp_f32_e32 v53, v53
	v_cndmask_b32_e32 v52, 0, v250, vcc
	v_ldexp_f32 v52, v53, v52

.LBB0_523:
	v_lshlrev_b64 v[54:55], 9, v[50:51]
	v_lshl_add_u64 v[60:61], v[140:141], 0, v[54:55]
	v_lshl_add_u64 v[58:59], v[142:143], 0, v[54:55]
	global_load_dwordx4 v[62:65], v[60:61], off
	global_load_dwordx4 v[66:69], v[58:59], off
	s_waitcnt vmcnt(0) lgkmcnt(0)
	v_fmamk_f32 v0, v0, 0x3a000000, v207
	v_cmp_gt_f32_e32 vcc, s87, v0
	v_mul_f32_e32 v53, 0x4b800000, v0
	v_lshlrev_b64 v[54:55], 12, v[50:51]
	v_cndmask_b32_e32 v0, v0, v53, vcc
	v_rsq_f32_e32 v0, v0
	v_lshl_add_u64 v[54:55], v[148:149], 0, v[54:55]
	v_lshl_add_u64 v[50:51], v[50:51], 1, v[150:151]
	v_mul_f32_e32 v53, 0x45800000, v0
	v_cndmask_b32_e32 v56, v0, v53, vcc
	v_pk_mul_f32 v[42:43], v[42:43], v[56:57] op_sel_hi:[1,0]
	v_pk_mul_f32 v[44:45], v[44:45], v[56:57] op_sel_hi:[1,0]
	v_pk_mul_f32 v[48:49], v[48:49], v[56:57] op_sel_hi:[1,0]
	v_pk_mul_f32 v[46:47], v[46:47], v[56:57] op_sel_hi:[1,0]
	s_and_b64 vcc, exec, s[38:39]
	v_pk_mul_f32 v[70:71], v[44:45], v[68:69]
	v_pk_mul_f32 v[72:73], v[42:43], v[66:67]
	v_pk_fma_f32 v[70:71], v[48:49], v[64:65], v[70:71] neg_lo:[0,0,1] neg_hi:[0,0,1]
	v_pk_fma_f32 v[72:73], v[46:47], v[62:63], v[72:73] neg_lo:[0,0,1] neg_hi:[0,0,1]
	v_pk_mul_f32 v[48:49], v[48:49], v[68:69]
	v_pk_mul_f32 v[46:47], v[46:47], v[66:67]
	v_pk_fma_f32 v[44:45], v[44:45], v[64:65], v[48:49]
	v_pk_fma_f32 v[42:43], v[42:43], v[62:63], v[46:47]
	v_pk_mul_f32 v[70:71], v[52:53], v[70:71] op_sel_hi:[0,1]
	v_pk_mul_f32 v[72:73], v[52:53], v[72:73] op_sel_hi:[0,1]
	v_pk_mul_f32 v[46:47], v[52:53], v[44:45] op_sel_hi:[0,1]
	v_pk_mul_f32 v[42:43], v[52:53], v[42:43] op_sel_hi:[0,1]
	v_cvt_pk_bf16_f32 v44, v72, v73
	v_cvt_pk_bf16_f32 v45, v70, v71
	v_cvt_pk_bf16_f32 v42, v42, v43
	v_cvt_pk_bf16_f32 v43, v46, v47
	global_store_dwordx2 v[54:55], v[44:45], off
	global_store_dwordx2 v[54:55], v[42:43], off offset:256
	s_cbranch_vccnz .LBB0_525
	v_add_co_u32_e32 v46, vcc, 0x8000, v50
	global_store_short v[50:51], v44, off
	s_nop 0
	v_addc_co_u32_e32 v47, vcc, 0, v51, vcc
	global_store_short_d16_hi v[46:47], v44, off
	v_add_co_u32_e32 v46, vcc, 0x10000, v50
	s_nop 1
	v_addc_co_u32_e32 v47, vcc, 0, v51, vcc
	global_store_short v[46:47], v45, off
	v_add_co_u32_e32 v46, vcc, 0x18000, v50
	s_nop 1
	v_addc_co_u32_e32 v47, vcc, 0, v51, vcc
	v_add_co_u32_e32 v44, vcc, 0x400000, v50
	global_store_short_d16_hi v[46:47], v45, off
	s_nop 0
	v_addc_co_u32_e32 v45, vcc, 0, v51, vcc
	global_store_short v[44:45], v42, off
	v_add_co_u32_e32 v44, vcc, 0x408000, v50
	s_nop 1
	v_addc_co_u32_e32 v45, vcc, 0, v51, vcc
	global_store_short_d16_hi v[44:45], v42, off
	v_add_co_u32_e32 v44, vcc, 0x410000, v50
	s_nop 1
	v_addc_co_u32_e32 v45, vcc, 0, v51, vcc
	global_store_short v[44:45], v43, off
	v_add_co_u32_e32 v44, vcc, 0x418000, v50
	s_nop 1
	v_addc_co_u32_e32 v45, vcc, 0, v51, vcc
	global_store_short_d16_hi v[44:45], v43, off
.LBB0_525:
	global_load_dwordx4 v[42:45], v[60:61], off offset:16
	s_nop 0
	global_load_dwordx4 v[46:49], v[58:59], off offset:16
	v_mov_b32_e32 v57, v56
	v_mov_b32_e32 v58, v56
	v_mov_b32_e32 v59, v56
	v_pk_mul_f32 v[36:37], v[36:37], v[58:59]
	v_pk_mul_f32 v[34:35], v[34:35], v[56:57]
	v_pk_mul_f32 v[40:41], v[40:41], v[58:59]
	v_pk_mul_f32 v[38:39], v[38:39], v[56:57]
	v_mov_b32_e32 v53, v52
	v_mov_b32_e32 v60, v52
	v_mov_b32_e32 v61, v52
	s_and_b64 vcc, exec, s[38:39]
	s_waitcnt vmcnt(0) lgkmcnt(0)
	v_pk_mul_f32 v[56:57], v[36:37], v[48:49]
	v_pk_mul_f32 v[58:59], v[34:35], v[46:47]
	v_pk_fma_f32 v[56:57], v[40:41], v[44:45], v[56:57] neg_lo:[0,0,1] neg_hi:[0,0,1]
	v_pk_fma_f32 v[58:59], v[38:39], v[42:43], v[58:59] neg_lo:[0,0,1] neg_hi:[0,0,1]
	v_pk_mul_f32 v[40:41], v[40:41], v[48:49]
	v_pk_mul_f32 v[38:39], v[38:39], v[46:47]
	v_pk_fma_f32 v[36:37], v[36:37], v[44:45], v[40:41]
	v_pk_fma_f32 v[34:35], v[34:35], v[42:43], v[38:39]
	v_pk_mul_f32 v[56:57], v[60:61], v[56:57]
	v_pk_mul_f32 v[58:59], v[52:53], v[58:59]
	v_pk_mul_f32 v[38:39], v[60:61], v[36:37]
	v_pk_mul_f32 v[34:35], v[52:53], v[34:35]
	v_cvt_pk_bf16_f32 v36, v58, v59
	v_cvt_pk_bf16_f32 v37, v56, v57
	s_nop 0
	v_cvt_pk_bf16_f32 v34, v34, v35
	v_cvt_pk_bf16_f32 v35, v38, v39
	global_store_dwordx2 v[54:55], v[36:37], off offset:8
	global_store_dwordx2 v[54:55], v[34:35], off offset:264
	s_cbranch_vccnz .LBB0_527
	v_add_co_u32_e32 v38, vcc, 0x20000, v50
	s_nop 1
	v_addc_co_u32_e32 v39, vcc, 0, v51, vcc
	global_store_short v[38:39], v36, off
	v_add_co_u32_e32 v38, vcc, 0x28000, v50
	s_nop 1
	v_addc_co_u32_e32 v39, vcc, 0, v51, vcc
	global_store_short_d16_hi v[38:39], v36, off
	v_add_co_u32_e32 v38, vcc, 0x30000, v50
	s_nop 1
	v_addc_co_u32_e32 v39, vcc, 0, v51, vcc
	global_store_short v[38:39], v37, off
	v_add_co_u32_e32 v38, vcc, 0x38000, v50
	s_nop 1
	v_addc_co_u32_e32 v39, vcc, 0, v51, vcc
	v_add_co_u32_e32 v36, vcc, 0x420000, v50
	global_store_short_d16_hi v[38:39], v37, off
	s_nop 0
	v_addc_co_u32_e32 v37, vcc, 0, v51, vcc
	global_store_short v[36:37], v34, off
	v_add_co_u32_e32 v36, vcc, 0x428000, v50
	s_nop 1
	v_addc_co_u32_e32 v37, vcc, 0, v51, vcc
	global_store_short_d16_hi v[36:37], v34, off
	v_add_co_u32_e32 v36, vcc, 0x430000, v50
	s_nop 1
	v_addc_co_u32_e32 v37, vcc, 0, v51, vcc
	global_store_short v[36:37], v35, off
	v_add_co_u32_e32 v36, vcc, 0x438000, v50
	s_nop 1
	v_addc_co_u32_e32 v37, vcc, 0, v51, vcc
	global_store_short_d16_hi v[36:37], v35, off
.LBB0_527:
	v_add_u32_e32 v34, s13, v170
	v_ashrrev_i32_e32 v35, 31, v34
	v_lshl_add_u64 v[36:37], v[34:35], 2, s[10:11]
	global_load_dword v0, v[36:37], off
	s_and_b64 vcc, exec, s[40:41]
	s_mov_b64 s[0:1], -1
	s_cbranch_vccnz .LBB0_529
	v_mul_f32_e32 v36, v181, v178
	v_cmp_gt_f32_e32 vcc, s7, v36
	s_mov_b64 s[0:1], 0
	s_nop 0
	v_cndmask_b32_e32 v37, 0, v213, vcc
	v_fmac_f32_e32 v37, v181, v178
	v_exp_f32_e32 v37, v37
	v_cndmask_b32_e32 v36, 0, v250, vcc
	v_ldexp_f32 v36, v37, v36

.LBB0_531:
	v_lshlrev_b64 v[38:39], 9, v[34:35]
	v_lshl_add_u64 v[44:45], v[140:141], 0, v[38:39]
	v_lshl_add_u64 v[42:43], v[142:143], 0, v[38:39]
	global_load_dwordx4 v[46:49], v[44:45], off
	global_load_dwordx4 v[50:53], v[42:43], off
	s_waitcnt vmcnt(0) lgkmcnt(0)
	v_fmamk_f32 v0, v0, 0x3a000000, v207
	v_cmp_gt_f32_e32 vcc, s87, v0
	v_mul_f32_e32 v37, 0x4b800000, v0
	v_lshlrev_b64 v[38:39], 12, v[34:35]
	v_cndmask_b32_e32 v0, v0, v37, vcc
	v_rsq_f32_e32 v0, v0
	v_lshl_add_u64 v[38:39], v[148:149], 0, v[38:39]
	v_lshl_add_u64 v[34:35], v[34:35], 1, v[150:151]
	v_mul_f32_e32 v37, 0x45800000, v0
	v_cndmask_b32_e32 v40, v0, v37, vcc
	v_pk_mul_f32 v[26:27], v[26:27], v[40:41] op_sel_hi:[1,0]
	v_pk_mul_f32 v[28:29], v[28:29], v[40:41] op_sel_hi:[1,0]
	v_pk_mul_f32 v[32:33], v[32:33], v[40:41] op_sel_hi:[1,0]
	v_pk_mul_f32 v[30:31], v[30:31], v[40:41] op_sel_hi:[1,0]
	s_and_b64 vcc, exec, s[38:39]
	v_pk_mul_f32 v[54:55], v[28:29], v[52:53]
	v_pk_mul_f32 v[56:57], v[26:27], v[50:51]
	v_pk_fma_f32 v[54:55], v[32:33], v[48:49], v[54:55] neg_lo:[0,0,1] neg_hi:[0,0,1]
	v_pk_fma_f32 v[56:57], v[30:31], v[46:47], v[56:57] neg_lo:[0,0,1] neg_hi:[0,0,1]
	v_pk_mul_f32 v[32:33], v[32:33], v[52:53]
	v_pk_mul_f32 v[30:31], v[30:31], v[50:51]
	v_pk_fma_f32 v[28:29], v[28:29], v[48:49], v[32:33]
	v_pk_fma_f32 v[26:27], v[26:27], v[46:47], v[30:31]
	v_pk_mul_f32 v[54:55], v[36:37], v[54:55] op_sel_hi:[0,1]
	v_pk_mul_f32 v[56:57], v[36:37], v[56:57] op_sel_hi:[0,1]
	v_pk_mul_f32 v[30:31], v[36:37], v[28:29] op_sel_hi:[0,1]
	v_pk_mul_f32 v[26:27], v[36:37], v[26:27] op_sel_hi:[0,1]
	v_cvt_pk_bf16_f32 v28, v56, v57
	v_cvt_pk_bf16_f32 v29, v54, v55
	v_cvt_pk_bf16_f32 v26, v26, v27
	v_cvt_pk_bf16_f32 v27, v30, v31
	global_store_dwordx2 v[38:39], v[28:29], off
	global_store_dwordx2 v[38:39], v[26:27], off offset:256
	s_cbranch_vccnz .LBB0_533
	v_add_co_u32_e32 v30, vcc, 0x8000, v34
	global_store_short v[34:35], v28, off
	s_nop 0
	v_addc_co_u32_e32 v31, vcc, 0, v35, vcc
	global_store_short_d16_hi v[30:31], v28, off
	v_add_co_u32_e32 v30, vcc, 0x10000, v34
	s_nop 1
	v_addc_co_u32_e32 v31, vcc, 0, v35, vcc
	global_store_short v[30:31], v29, off
	v_add_co_u32_e32 v30, vcc, 0x18000, v34
	s_nop 1
	v_addc_co_u32_e32 v31, vcc, 0, v35, vcc
	v_add_co_u32_e32 v28, vcc, 0x400000, v34
	global_store_short_d16_hi v[30:31], v29, off
	s_nop 0
	v_addc_co_u32_e32 v29, vcc, 0, v35, vcc
	global_store_short v[28:29], v26, off
	v_add_co_u32_e32 v28, vcc, 0x408000, v34
	s_nop 1
	v_addc_co_u32_e32 v29, vcc, 0, v35, vcc
	global_store_short_d16_hi v[28:29], v26, off
	v_add_co_u32_e32 v28, vcc, 0x410000, v34
	s_nop 1
	v_addc_co_u32_e32 v29, vcc, 0, v35, vcc
	global_store_short v[28:29], v27, off
	v_add_co_u32_e32 v28, vcc, 0x418000, v34
	s_nop 1
	v_addc_co_u32_e32 v29, vcc, 0, v35, vcc
	global_store_short_d16_hi v[28:29], v27, off
.LBB0_533:
	global_load_dwordx4 v[26:29], v[44:45], off offset:16
	s_nop 0
	global_load_dwordx4 v[30:33], v[42:43], off offset:16
	v_mov_b32_e32 v41, v40
	v_mov_b32_e32 v42, v40
	v_mov_b32_e32 v43, v40
	v_pk_mul_f32 v[20:21], v[20:21], v[42:43]
	v_pk_mul_f32 v[18:19], v[18:19], v[40:41]
	v_pk_mul_f32 v[24:25], v[24:25], v[42:43]
	v_pk_mul_f32 v[22:23], v[22:23], v[40:41]
	v_mov_b32_e32 v37, v36
	v_mov_b32_e32 v44, v36
	v_mov_b32_e32 v45, v36
	s_and_b64 vcc, exec, s[38:39]
	s_waitcnt vmcnt(0) lgkmcnt(0)
	v_pk_mul_f32 v[40:41], v[20:21], v[32:33]
	v_pk_mul_f32 v[42:43], v[18:19], v[30:31]
	v_pk_fma_f32 v[40:41], v[24:25], v[28:29], v[40:41] neg_lo:[0,0,1] neg_hi:[0,0,1]
	v_pk_fma_f32 v[42:43], v[22:23], v[26:27], v[42:43] neg_lo:[0,0,1] neg_hi:[0,0,1]
	v_pk_mul_f32 v[24:25], v[24:25], v[32:33]
	v_pk_mul_f32 v[22:23], v[22:23], v[30:31]
	v_pk_fma_f32 v[20:21], v[20:21], v[28:29], v[24:25]
	v_pk_fma_f32 v[18:19], v[18:19], v[26:27], v[22:23]
	v_pk_mul_f32 v[40:41], v[44:45], v[40:41]
	v_pk_mul_f32 v[42:43], v[36:37], v[42:43]
	v_pk_mul_f32 v[22:23], v[44:45], v[20:21]
	v_pk_mul_f32 v[18:19], v[36:37], v[18:19]
	v_cvt_pk_bf16_f32 v20, v42, v43
	v_cvt_pk_bf16_f32 v21, v40, v41
	s_nop 0
	v_cvt_pk_bf16_f32 v18, v18, v19
	v_cvt_pk_bf16_f32 v19, v22, v23
	global_store_dwordx2 v[38:39], v[20:21], off offset:8
	global_store_dwordx2 v[38:39], v[18:19], off offset:264
	s_cbranch_vccnz .LBB0_535
	v_add_co_u32_e32 v22, vcc, 0x20000, v34
	s_nop 1
	v_addc_co_u32_e32 v23, vcc, 0, v35, vcc
	global_store_short v[22:23], v20, off
	v_add_co_u32_e32 v22, vcc, 0x28000, v34
	s_nop 1
	v_addc_co_u32_e32 v23, vcc, 0, v35, vcc
	global_store_short_d16_hi v[22:23], v20, off
	v_add_co_u32_e32 v22, vcc, 0x30000, v34
	s_nop 1
	v_addc_co_u32_e32 v23, vcc, 0, v35, vcc
	global_store_short v[22:23], v21, off
	v_add_co_u32_e32 v22, vcc, 0x38000, v34
	s_nop 1
	v_addc_co_u32_e32 v23, vcc, 0, v35, vcc
	v_add_co_u32_e32 v20, vcc, 0x420000, v34
	global_store_short_d16_hi v[22:23], v21, off
	s_nop 0
	v_addc_co_u32_e32 v21, vcc, 0, v35, vcc
	global_store_short v[20:21], v18, off
	v_add_co_u32_e32 v20, vcc, 0x428000, v34
	s_nop 1
	v_addc_co_u32_e32 v21, vcc, 0, v35, vcc
	global_store_short_d16_hi v[20:21], v18, off
	v_add_co_u32_e32 v20, vcc, 0x430000, v34
	s_nop 1
	v_addc_co_u32_e32 v21, vcc, 0, v35, vcc
	global_store_short v[20:21], v19, off
	v_add_co_u32_e32 v20, vcc, 0x438000, v34
	s_nop 1
	v_addc_co_u32_e32 v21, vcc, 0, v35, vcc
	global_store_short_d16_hi v[20:21], v19, off
.LBB0_535:
	v_add_u32_e32 v18, s13, v171
	v_ashrrev_i32_e32 v19, 31, v18
	v_lshl_add_u64 v[20:21], v[18:19], 2, s[10:11]
	global_load_dword v0, v[20:21], off
	s_and_b64 vcc, exec, s[40:41]
	s_mov_b64 s[0:1], -1
	s_cbranch_vccnz .LBB0_537
	v_mul_f32_e32 v20, v181, v179
	v_cmp_gt_f32_e32 vcc, s7, v20
	s_mov_b64 s[0:1], 0
	s_nop 0
	v_cndmask_b32_e32 v21, 0, v213, vcc
	v_fmac_f32_e32 v21, v181, v179
	v_exp_f32_e32 v21, v21
	v_cndmask_b32_e32 v20, 0, v250, vcc
	v_ldexp_f32 v20, v21, v20

.LBB0_539:
	v_lshlrev_b64 v[22:23], 9, v[18:19]
	v_lshl_add_u64 v[28:29], v[140:141], 0, v[22:23]
	v_lshl_add_u64 v[26:27], v[142:143], 0, v[22:23]
	global_load_dwordx4 v[30:33], v[28:29], off
	global_load_dwordx4 v[34:37], v[26:27], off
	s_waitcnt vmcnt(0) lgkmcnt(0)
	v_fmamk_f32 v0, v0, 0x3a000000, v207
	v_cmp_gt_f32_e32 vcc, s87, v0
	v_mul_f32_e32 v21, 0x4b800000, v0
	v_lshlrev_b64 v[22:23], 12, v[18:19]
	v_cndmask_b32_e32 v0, v0, v21, vcc
	v_rsq_f32_e32 v0, v0
	v_lshl_add_u64 v[22:23], v[148:149], 0, v[22:23]
	v_lshl_add_u64 v[18:19], v[18:19], 1, v[150:151]
	v_mul_f32_e32 v21, 0x45800000, v0
	v_cndmask_b32_e32 v24, v0, v21, vcc
	v_pk_mul_f32 v[10:11], v[10:11], v[24:25] op_sel_hi:[1,0]
	v_pk_mul_f32 v[12:13], v[12:13], v[24:25] op_sel_hi:[1,0]
	v_pk_mul_f32 v[16:17], v[16:17], v[24:25] op_sel_hi:[1,0]
	v_pk_mul_f32 v[14:15], v[14:15], v[24:25] op_sel_hi:[1,0]
	s_and_b64 vcc, exec, s[38:39]
	v_pk_mul_f32 v[38:39], v[12:13], v[36:37]
	v_pk_mul_f32 v[40:41], v[10:11], v[34:35]
	v_pk_fma_f32 v[38:39], v[16:17], v[32:33], v[38:39] neg_lo:[0,0,1] neg_hi:[0,0,1]
	v_pk_fma_f32 v[40:41], v[14:15], v[30:31], v[40:41] neg_lo:[0,0,1] neg_hi:[0,0,1]
	v_pk_mul_f32 v[16:17], v[16:17], v[36:37]
	v_pk_mul_f32 v[14:15], v[14:15], v[34:35]
	v_pk_fma_f32 v[12:13], v[12:13], v[32:33], v[16:17]
	v_pk_fma_f32 v[10:11], v[10:11], v[30:31], v[14:15]
	v_pk_mul_f32 v[38:39], v[20:21], v[38:39] op_sel_hi:[0,1]
	v_pk_mul_f32 v[40:41], v[20:21], v[40:41] op_sel_hi:[0,1]
	v_pk_mul_f32 v[14:15], v[20:21], v[12:13] op_sel_hi:[0,1]
	v_pk_mul_f32 v[10:11], v[20:21], v[10:11] op_sel_hi:[0,1]
	v_cvt_pk_bf16_f32 v12, v40, v41
	v_cvt_pk_bf16_f32 v13, v38, v39
	v_cvt_pk_bf16_f32 v10, v10, v11
	v_cvt_pk_bf16_f32 v11, v14, v15
	global_store_dwordx2 v[22:23], v[12:13], off
	global_store_dwordx2 v[22:23], v[10:11], off offset:256
	s_cbranch_vccnz .LBB0_541
	v_add_co_u32_e32 v14, vcc, 0x8000, v18
	global_store_short v[18:19], v12, off
	s_nop 0
	v_addc_co_u32_e32 v15, vcc, 0, v19, vcc
	global_store_short_d16_hi v[14:15], v12, off
	v_add_co_u32_e32 v14, vcc, 0x10000, v18
	s_nop 1
	v_addc_co_u32_e32 v15, vcc, 0, v19, vcc
	global_store_short v[14:15], v13, off
	v_add_co_u32_e32 v14, vcc, 0x18000, v18
	s_nop 1
	v_addc_co_u32_e32 v15, vcc, 0, v19, vcc
	v_add_co_u32_e32 v12, vcc, 0x400000, v18
	global_store_short_d16_hi v[14:15], v13, off
	s_nop 0
	v_addc_co_u32_e32 v13, vcc, 0, v19, vcc
	global_store_short v[12:13], v10, off
	v_add_co_u32_e32 v12, vcc, 0x408000, v18
	s_nop 1
	v_addc_co_u32_e32 v13, vcc, 0, v19, vcc
	global_store_short_d16_hi v[12:13], v10, off
	v_add_co_u32_e32 v12, vcc, 0x410000, v18
	s_nop 1
	v_addc_co_u32_e32 v13, vcc, 0, v19, vcc
	global_store_short v[12:13], v11, off
	v_add_co_u32_e32 v12, vcc, 0x418000, v18
	s_nop 1
	v_addc_co_u32_e32 v13, vcc, 0, v19, vcc
	global_store_short_d16_hi v[12:13], v11, off
.LBB0_541:
	global_load_dwordx4 v[10:13], v[28:29], off offset:16
	s_nop 0
	global_load_dwordx4 v[14:17], v[26:27], off offset:16
	v_mov_b32_e32 v25, v24
	v_mov_b32_e32 v26, v24
	v_mov_b32_e32 v27, v24
	v_pk_mul_f32 v[4:5], v[4:5], v[26:27]
	v_pk_mul_f32 v[2:3], v[2:3], v[24:25]
	v_pk_mul_f32 v[8:9], v[8:9], v[26:27]
	v_pk_mul_f32 v[6:7], v[6:7], v[24:25]
	v_mov_b32_e32 v21, v20
	v_mov_b32_e32 v28, v20
	v_mov_b32_e32 v29, v20
	s_and_b64 vcc, exec, s[38:39]
	s_waitcnt vmcnt(0) lgkmcnt(0)
	v_pk_mul_f32 v[24:25], v[4:5], v[16:17]
	v_pk_mul_f32 v[26:27], v[2:3], v[14:15]
	v_pk_fma_f32 v[24:25], v[8:9], v[12:13], v[24:25] neg_lo:[0,0,1] neg_hi:[0,0,1]
	v_pk_fma_f32 v[26:27], v[6:7], v[10:11], v[26:27] neg_lo:[0,0,1] neg_hi:[0,0,1]
	v_pk_mul_f32 v[8:9], v[8:9], v[16:17]
	v_pk_mul_f32 v[6:7], v[6:7], v[14:15]
	v_pk_fma_f32 v[4:5], v[4:5], v[12:13], v[8:9]
	v_pk_fma_f32 v[2:3], v[2:3], v[10:11], v[6:7]
	v_pk_mul_f32 v[24:25], v[28:29], v[24:25]
	v_pk_mul_f32 v[26:27], v[20:21], v[26:27]
	v_pk_mul_f32 v[6:7], v[28:29], v[4:5]
	v_pk_mul_f32 v[2:3], v[20:21], v[2:3]
	v_cvt_pk_bf16_f32 v4, v26, v27
	v_cvt_pk_bf16_f32 v5, v24, v25
	s_nop 0
	v_cvt_pk_bf16_f32 v2, v2, v3
	v_cvt_pk_bf16_f32 v3, v6, v7
	global_store_dwordx2 v[22:23], v[4:5], off offset:8
	global_store_dwordx2 v[22:23], v[2:3], off offset:264
	s_cbranch_vccnz .LBB0_543
	v_add_co_u32_e32 v6, vcc, 0x20000, v18
	s_nop 1
	v_addc_co_u32_e32 v7, vcc, 0, v19, vcc
	global_store_short v[6:7], v4, off
	v_add_co_u32_e32 v6, vcc, 0x28000, v18
	s_nop 1
	v_addc_co_u32_e32 v7, vcc, 0, v19, vcc
	global_store_short_d16_hi v[6:7], v4, off
	v_add_co_u32_e32 v6, vcc, 0x30000, v18
	s_nop 1
	v_addc_co_u32_e32 v7, vcc, 0, v19, vcc
	global_store_short v[6:7], v5, off
	v_add_co_u32_e32 v6, vcc, 0x38000, v18
	s_nop 1
	v_addc_co_u32_e32 v7, vcc, 0, v19, vcc
	v_add_co_u32_e32 v4, vcc, 0x420000, v18
	global_store_short_d16_hi v[6:7], v5, off
	s_nop 0
	v_addc_co_u32_e32 v5, vcc, 0, v19, vcc
	global_store_short v[4:5], v2, off
	v_add_co_u32_e32 v4, vcc, 0x428000, v18
	s_nop 1
	v_addc_co_u32_e32 v5, vcc, 0, v19, vcc
	global_store_short_d16_hi v[4:5], v2, off
	v_add_co_u32_e32 v4, vcc, 0x430000, v18
	s_nop 1
	v_addc_co_u32_e32 v5, vcc, 0, v19, vcc
	global_store_short v[4:5], v3, off
	v_add_co_u32_e32 v4, vcc, 0x438000, v18
	s_nop 1
	v_addc_co_u32_e32 v5, vcc, 0, v19, vcc
	global_store_short_d16_hi v[4:5], v3, off

.LBB0_600:
	s_or_b64 exec, exec, s[0:1]
	v_readlane_b32 s0, v255, 8
	v_readlane_b32 s1, v255, 9
	s_and_b64 vcc, exec, s[0:1]
	s_waitcnt lgkmcnt(0)
	s_barrier
	s_cbranch_vccz .LBB0_607
	v_readlane_b32 s0, v255, 17
	v_readlane_b32 s1, v255, 18
	s_add_u32 s0, s14, s0
	s_addc_u32 s1, s15, s1
	v_readlane_b32 s2, v255, 34
	v_mov_b32_e32 v100, v206
	s_add_u32 s0, s0, s2
	s_addc_u32 s1, s1, 0
	v_lshlrev_b32_e32 v0, 4, v100
	v_and_b32_e32 v0, 0xf0, v0
	v_lshl_add_u64 v[26:27], s[0:1], 0, v[0:1]
	v_ashrrev_i32_e32 v0, 4, v100
	v_readlane_b32 s0, v255, 16
	s_mov_b32 s4, s85
	s_nop 0
	v_add_u32_e32 v2, s0, v0
	v_add_u32_e32 v0, 0x200, v100
	v_ashrrev_i32_e32 v0, 4, v0
	v_add_u32_e32 v4, s0, v0
	v_add_u32_e32 v0, 0x400, v100
	v_ashrrev_i32_e32 v0, 4, v0
	v_add_u32_e32 v10, s0, v0
	v_add_u32_e32 v0, 0x600, v100
	v_ashrrev_i32_e32 v0, 4, v0
	v_add_u32_e32 v12, s0, v0
	v_add_u32_e32 v0, 0x800, v100
	v_ashrrev_i32_e32 v0, 4, v0
	v_add_u32_e32 v18, s0, v0
	v_add_u32_e32 v0, 0xa00, v100
	v_ashrrev_i32_e32 v0, 4, v0
	v_add_u32_e32 v20, s0, v0
	v_add_u32_e32 v0, 0xc00, v100
	v_ashrrev_i32_e32 v0, 4, v0
	v_add_u32_e32 v28, s0, v0
	v_add_u32_e32 v0, 0xe00, v100
	v_ashrrev_i32_e32 v0, 4, v0
	v_ashrrev_i32_e32 v3, 31, v2
	v_ashrrev_i32_e32 v5, 31, v4
	v_ashrrev_i32_e32 v11, 31, v10
	v_ashrrev_i32_e32 v13, 31, v12
	v_ashrrev_i32_e32 v19, 31, v18
	v_ashrrev_i32_e32 v21, 31, v20
	v_ashrrev_i32_e32 v29, 31, v28
	v_add_u32_e32 v30, s0, v0
	v_lshlrev_b64 v[2:3], 15, v[2:3]
	v_lshlrev_b64 v[4:5], 15, v[4:5]
	v_lshlrev_b64 v[10:11], 15, v[10:11]
	v_lshlrev_b64 v[12:13], 15, v[12:13]
	v_lshlrev_b64 v[18:19], 15, v[18:19]
	v_lshlrev_b64 v[20:21], 15, v[20:21]
	v_lshlrev_b64 v[28:29], 15, v[28:29]
	v_ashrrev_i32_e32 v31, 31, v30
	v_lshl_add_u64 v[2:3], v[26:27], 0, v[2:3]
	v_lshl_add_u64 v[6:7], v[26:27], 0, v[4:5]
	v_lshl_add_u64 v[10:11], v[26:27], 0, v[10:11]
	v_lshl_add_u64 v[14:15], v[26:27], 0, v[12:13]
	v_lshl_add_u64 v[18:19], v[26:27], 0, v[18:19]
	v_lshl_add_u64 v[22:23], v[26:27], 0, v[20:21]
	v_lshl_add_u64 v[28:29], v[26:27], 0, v[28:29]
	v_lshlrev_b64 v[30:31], 15, v[30:31]
	global_load_dwordx4 v[2:5], v[2:3], off
	s_nop 0
	global_load_dwordx4 v[6:9], v[6:7], off
	s_nop 0
	global_load_dwordx4 v[10:13], v[10:11], off
	s_nop 0
	global_load_dwordx4 v[14:17], v[14:15], off
	s_nop 0
	global_load_dwordx4 v[18:21], v[18:19], off
	s_nop 0
	global_load_dwordx4 v[22:25], v[22:23], off
	v_lshl_add_u64 v[26:27], v[26:27], 0, v[30:31]
	global_load_dwordx4 v[42:45], v[28:29], off
	global_load_dwordx4 v[46:49], v[26:27], off
.LBB0_602:
	s_ashr_i32 s0, s4, 9
	s_ashr_i32 s1, s0, 31
	s_lshl_b32 s2, s4, 3
	s_and_b32 s2, s2, 0xe00
	v_and_b32_e32 v26, 0xffffffc0, v100
	s_lshl_b64 s[0:1], s[0:1], 14
	v_and_b32_e32 v98, 15, v100
	v_add_u32_e32 v26, s2, v26
	s_add_u32 s0, s16, s0
	v_or_b32_e32 v82, v26, v98
	s_addc_u32 s1, s17, s1
	s_lshl_b32 s2, s4, 8
	s_and_b32 s2, s2, 0x3f00
	v_ashrrev_i32_e32 v83, 31, v82
	v_bfe_u32 v0, v100, 4, 2
	s_add_u32 s0, s0, s2
	v_lshlrev_b64 v[26:27], 15, v[82:83]
	v_or_b32_e32 v50, 16, v82
	v_or_b32_e32 v66, 32, v82
	v_or_b32_e32 v82, 48, v82
	s_addc_u32 s1, s1, 0
	v_lshlrev_b32_e32 v0, 4, v0
	v_ashrrev_i32_e32 v51, 31, v50
	v_ashrrev_i32_e32 v67, 31, v66
	v_ashrrev_i32_e32 v83, 31, v82
	v_lshl_add_u64 v[84:85], s[0:1], 0, v[0:1]
	v_lshlrev_b64 v[50:51], 15, v[50:51]
	v_lshlrev_b64 v[66:67], 15, v[66:67]
	v_lshlrev_b64 v[82:83], 15, v[82:83]
	v_lshl_add_u64 v[38:39], v[84:85], 0, v[26:27]
	v_lshl_add_u64 v[62:63], v[84:85], 0, v[50:51]
	v_lshl_add_u64 v[78:79], v[84:85], 0, v[66:67]
	v_lshl_add_u64 v[94:95], v[84:85], 0, v[82:83]
	global_load_dwordx4 v[26:29], v[38:39], off
	global_load_dwordx4 v[30:33], v[38:39], off offset:64
	global_load_dwordx4 v[34:37], v[38:39], off offset:128
	s_nop 0
	global_load_dwordx4 v[38:41], v[38:39], off offset:192
	s_nop 0
	global_load_dwordx4 v[50:53], v[62:63], off
	global_load_dwordx4 v[54:57], v[62:63], off offset:64
	global_load_dwordx4 v[58:61], v[62:63], off offset:128
	s_nop 0
	global_load_dwordx4 v[62:65], v[62:63], off offset:192
	s_nop 0
	global_load_dwordx4 v[66:69], v[78:79], off
	global_load_dwordx4 v[70:73], v[78:79], off offset:64
	global_load_dwordx4 v[74:77], v[78:79], off offset:128
	s_nop 0
	global_load_dwordx4 v[78:81], v[78:79], off offset:192
	s_nop 0
	global_load_dwordx4 v[82:85], v[94:95], off
	global_load_dwordx4 v[86:89], v[94:95], off offset:64
	global_load_dwordx4 v[90:93], v[94:95], off offset:128
	s_nop 0
	global_load_dwordx4 v[94:97], v[94:95], off offset:192
	v_lshlrev_b32_e32 v99, 3, v100
	v_and_b32_e32 v108, 0x78, v99
	v_lshl_add_u32 v110, v108, 1, 0
	v_ashrrev_i32_e32 v107, 4, v100
	s_movk_i32 s2, 0x110
	v_add_u32_e32 v99, 0x200, v100
	v_mad_u64_u32 v[102:103], s[0:1], v107, s2, v[110:111]
	v_ashrrev_i32_e32 v106, 4, v99
	v_add_u32_e32 v99, 0x400, v100
	s_waitcnt vmcnt(0) lgkmcnt(0)
	ds_write_b128 v102, v[2:5]
	v_mad_u64_u32 v[102:103], s[0:1], v106, s2, v[110:111]
	v_ashrrev_i32_e32 v105, 4, v99
	v_add_u32_e32 v99, 0x600, v100
	ds_write_b128 v102, v[6:9]
	v_mad_u64_u32 v[102:103], s[0:1], v105, s2, v[110:111]
	v_ashrrev_i32_e32 v104, 4, v99
	ds_write_b128 v102, v[10:13]
	v_mad_u64_u32 v[102:103], s[0:1], v104, s2, v[110:111]
	v_add_u32_e32 v99, 0x800, v100
	v_ashrrev_i32_e32 v103, 4, v99
	v_add_u32_e32 v99, 0xa00, v100
	ds_write_b128 v102, v[14:17]
	v_ashrrev_i32_e32 v102, 4, v99
	v_add_u32_e32 v99, 0xc00, v100
	v_mad_u64_u32 v[112:113], s[0:1], v103, s2, v[110:111]
	v_ashrrev_i32_e32 v101, 4, v99
	v_add_u32_e32 v99, 0xe00, v100
	ds_write_b128 v112, v[18:21]
	v_mad_u64_u32 v[112:113], s[0:1], v102, s2, v[110:111]
	v_ashrrev_i32_e32 v99, 4, v99
	ds_write_b128 v112, v[22:25]
	v_mad_u64_u32 v[112:113], s[0:1], v101, s2, v[110:111]
	v_mad_u64_u32 v[110:111], s[0:1], v99, s2, v[110:111]
	s_add_i32 s2, s4, s70
	s_cmpk_gt_i32 s2, 0x3ff
	s_cselect_b64 s[0:1], -1, 0
	s_and_b64 vcc, exec, s[0:1]
	ds_write_b128 v112, v[42:45]
	ds_write_b128 v110, v[46:49]
	s_waitcnt lgkmcnt(0)
	s_barrier
	s_cbranch_vccnz .LBB0_604
	s_ashr_i32 s6, s2, 9
	s_ashr_i32 s7, s6, 31
	s_lshl_b32 s5, s2, 2
	s_and_b32 s5, s5, 0x700
	s_lshl_b64 s[6:7], s[6:7], 14
	s_add_u32 s6, s14, s6
	s_addc_u32 s7, s15, s7
	s_lshl_b32 s10, s2, 8
	s_and_b32 s10, s10, 0x3f00
	s_add_u32 s6, s6, s10
	s_addc_u32 s7, s7, 0
	v_lshlrev_b32_e32 v2, 1, v108
	v_mov_b32_e32 v3, v1
	v_lshl_add_u64 v[42:43], s[6:7], 0, v[2:3]
	v_add_u32_e32 v2, s5, v107
	v_add_u32_e32 v4, s5, v106
	v_add_u32_e32 v10, s5, v105
	v_add_u32_e32 v12, s5, v104
	v_add_u32_e32 v18, s5, v103
	v_add_u32_e32 v20, s5, v102
	v_add_u32_e32 v44, s5, v101
	v_add_u32_e32 v46, s5, v99
	v_ashrrev_i32_e32 v3, 31, v2
	v_ashrrev_i32_e32 v5, 31, v4
	v_ashrrev_i32_e32 v11, 31, v10
	v_ashrrev_i32_e32 v13, 31, v12
	v_ashrrev_i32_e32 v19, 31, v18
	v_ashrrev_i32_e32 v21, 31, v20
	v_ashrrev_i32_e32 v45, 31, v44
	v_ashrrev_i32_e32 v47, 31, v46
	v_lshlrev_b64 v[2:3], 15, v[2:3]
	v_lshlrev_b64 v[4:5], 15, v[4:5]
	v_lshlrev_b64 v[10:11], 15, v[10:11]
	v_lshlrev_b64 v[12:13], 15, v[12:13]
	v_lshlrev_b64 v[18:19], 15, v[18:19]
	v_lshlrev_b64 v[20:21], 15, v[20:21]
	v_lshlrev_b64 v[44:45], 15, v[44:45]
	v_lshlrev_b64 v[46:47], 15, v[46:47]
	v_lshl_add_u64 v[2:3], v[42:43], 0, v[2:3]
	v_lshl_add_u64 v[6:7], v[42:43], 0, v[4:5]
	v_lshl_add_u64 v[10:11], v[42:43], 0, v[10:11]
	v_lshl_add_u64 v[14:15], v[42:43], 0, v[12:13]
	v_lshl_add_u64 v[18:19], v[42:43], 0, v[18:19]
	v_lshl_add_u64 v[22:23], v[42:43], 0, v[20:21]
	v_lshl_add_u64 v[44:45], v[42:43], 0, v[44:45]
	v_lshl_add_u64 v[46:47], v[42:43], 0, v[46:47]
	global_load_dwordx4 v[2:5], v[2:3], off
	s_nop 0
	global_load_dwordx4 v[6:9], v[6:7], off
	s_nop 0
	global_load_dwordx4 v[10:13], v[10:11], off
	s_nop 0
	global_load_dwordx4 v[14:17], v[14:15], off
	s_nop 0
	global_load_dwordx4 v[18:21], v[18:19], off
	s_nop 0
	global_load_dwordx4 v[22:25], v[22:23], off
	s_nop 0
	global_load_dwordx4 v[42:45], v[44:45], off
	s_nop 0
	global_load_dwordx4 v[46:49], v[46:47], off

.LBB0_605:
	ds_read_b128 v[102:105], v0
	ds_read_b128 v[106:109], v0 offset:64
	v_lshl_add_u64 v[126:127], v[98:99], 0, s[4:5]
	v_add_co_u32_e32 v128, vcc, s48, v126
	s_waitcnt lgkmcnt(0)
	v_mfma_f32_16x16x32_bf16 v[110:113], v[102:105], v[26:29], 0
	v_addc_co_u32_e32 v129, vcc, 0, v127, vcc
	v_add_co_u32_e32 v130, vcc, s49, v126
	v_mfma_f32_16x16x32_bf16 v[114:117], v[102:105], v[50:53], 0
	s_nop 0
	v_addc_co_u32_e32 v131, vcc, 0, v127, vcc
	v_add_co_u32_e32 v132, vcc, s53, v126
	v_mfma_f32_16x16x32_bf16 v[118:121], v[102:105], v[66:69], 0
	s_nop 0
	v_addc_co_u32_e32 v133, vcc, 0, v127, vcc
	v_add_co_u32_e32 v126, vcc, s96, v126
	v_mfma_f32_16x16x32_bf16 v[102:105], v[102:105], v[82:85], 0
	s_nop 0
	v_addc_co_u32_e32 v127, vcc, 0, v127, vcc
	s_add_u32 s4, s4, 64
	v_mfma_f32_16x16x32_bf16 v[110:113], v[106:109], v[30:33], v[110:113]
	s_addc_u32 s5, s5, 0
	s_cmpk_lg_i32 s4, 0x200
	v_mfma_f32_16x16x32_bf16 v[114:117], v[106:109], v[54:57], v[114:117]
	v_mfma_f32_16x16x32_bf16 v[118:121], v[106:109], v[70:73], v[118:121]
	v_mfma_f32_16x16x32_bf16 v[102:105], v[106:109], v[86:89], v[102:105]
	ds_read_b128 v[106:109], v0 offset:128
	ds_read_b128 v[122:125], v0 offset:192
	s_waitcnt lgkmcnt(0)
	v_mfma_f32_16x16x32_bf16 v[110:113], v[106:109], v[34:37], v[110:113]
	v_mfma_f32_16x16x32_bf16 v[114:117], v[106:109], v[58:61], v[114:117]
	v_mfma_f32_16x16x32_bf16 v[118:121], v[106:109], v[74:77], v[118:121]
	v_mfma_f32_16x16x32_bf16 v[102:105], v[106:109], v[90:93], v[102:105]
	v_mfma_f32_16x16x32_bf16 v[106:109], v[122:125], v[38:41], v[110:113]
	v_mfma_f32_16x16x32_bf16 v[110:113], v[122:125], v[62:65], v[114:117]
	v_mfma_f32_16x16x32_bf16 v[114:117], v[122:125], v[78:81], v[118:121]
	s_nop 5
	v_cvt_pk_bf16_f32 v106, v106, v107
	v_cvt_pk_bf16_f32 v107, v108, v109
	v_cvt_pk_bf16_f32 v108, v110, v111
	v_mfma_f32_16x16x32_bf16 v[102:105], v[122:125], v[94:97], v[102:105]
	v_cvt_pk_bf16_f32 v109, v112, v113
	v_cvt_pk_bf16_f32 v110, v114, v115
	v_cvt_pk_bf16_f32 v111, v116, v117
	s_nop 4
	v_cvt_pk_bf16_f32 v102, v102, v103
	v_cvt_pk_bf16_f32 v103, v104, v105
	global_store_dwordx2 v[128:129], v[106:107], off
	global_store_dwordx2 v[130:131], v[108:109], off
	global_store_dwordx2 v[132:133], v[110:111], off
	global_store_dwordx2 v[126:127], v[102:103], off
	ds_read_b128 v[102:105], v0 offset:4352
	ds_read_b128 v[106:109], v0 offset:4416
	s_waitcnt lgkmcnt(0)
	v_mfma_f32_16x16x32_bf16 v[110:113], v[102:105], v[26:29], 0
	v_mfma_f32_16x16x32_bf16 v[114:117], v[102:105], v[50:53], 0
	v_mfma_f32_16x16x32_bf16 v[118:121], v[102:105], v[66:69], 0
	v_mfma_f32_16x16x32_bf16 v[102:105], v[102:105], v[82:85], 0
	v_mfma_f32_16x16x32_bf16 v[110:113], v[106:109], v[30:33], v[110:113]
	v_mfma_f32_16x16x32_bf16 v[114:117], v[106:109], v[54:57], v[114:117]
	v_mfma_f32_16x16x32_bf16 v[118:121], v[106:109], v[70:73], v[118:121]
	v_mfma_f32_16x16x32_bf16 v[102:105], v[106:109], v[86:89], v[102:105]
	ds_read_b128 v[106:109], v0 offset:4480
	ds_read_b128 v[122:125], v0 offset:4544
	v_add_u32_e32 v0, 0x2200, v0
	s_waitcnt lgkmcnt(0)
	v_mfma_f32_16x16x32_bf16 v[110:113], v[106:109], v[34:37], v[110:113]
	v_mfma_f32_16x16x32_bf16 v[114:117], v[106:109], v[58:61], v[114:117]
	v_mfma_f32_16x16x32_bf16 v[118:121], v[106:109], v[74:77], v[118:121]
	v_mfma_f32_16x16x32_bf16 v[102:105], v[106:109], v[90:93], v[102:105]
	v_mfma_f32_16x16x32_bf16 v[106:109], v[122:125], v[38:41], v[110:113]
	v_mfma_f32_16x16x32_bf16 v[110:113], v[122:125], v[62:65], v[114:117]
	v_mfma_f32_16x16x32_bf16 v[114:117], v[122:125], v[78:81], v[118:121]
	s_nop 5
	v_cvt_pk_bf16_f32 v106, v106, v107
	v_cvt_pk_bf16_f32 v107, v108, v109
	v_cvt_pk_bf16_f32 v108, v110, v111
	v_mfma_f32_16x16x32_bf16 v[102:105], v[122:125], v[94:97], v[102:105]
	v_cvt_pk_bf16_f32 v109, v112, v113
	v_cvt_pk_bf16_f32 v110, v114, v115
	v_cvt_pk_bf16_f32 v111, v116, v117
	s_nop 4
	v_cvt_pk_bf16_f32 v102, v102, v103
	v_cvt_pk_bf16_f32 v103, v104, v105
	global_store_dwordx2 v[128:129], v[106:107], off offset:32
	global_store_dwordx2 v[130:131], v[108:109], off offset:32
	global_store_dwordx2 v[132:133], v[110:111], off offset:32
	global_store_dwordx2 v[126:127], v[102:103], off offset:32
	s_cbranch_scc1 .LBB0_605
	s_andn2_b64 vcc, exec, s[0:1]
	s_mov_b32 s4, s2
	s_waitcnt lgkmcnt(0)
	s_barrier
	s_cbranch_vccnz .LBB0_602

.LBB0_738:
	s_ashr_i32 s0, s12, 9
	s_ashr_i32 s1, s0, 31
	s_lshl_b64 s[14:15], s[0:1], 13
	s_lshl_b32 s0, s12, 7
	s_ashr_i32 s13, s12, 31
	s_and_b32 s0, s0, 0x1f80
	s_lshl_b64 s[18:19], s[12:13], 18
	s_bfe_u32 s2, s12, 0x30006
	s_or_b32 s14, s14, s0
	s_add_u32 s0, s4, s18
	s_addc_u32 s1, s5, s19
	s_lshl_b32 s13, s2, 9
	v_readlane_b32 s6, v254, 30
	s_waitcnt vmcnt(0)
	v_ashrrev_i32_e32 v4, 5, v251
	v_readlane_b32 s7, v254, 31
	s_add_u32 s6, s6, s13
	v_lshlrev_b32_e32 v0, 4, v251
	v_ashrrev_i32_e32 v5, 31, v4
	s_addc_u32 s7, s7, 0
	v_and_b32_e32 v2, 0x1f0, v0
	v_mov_b32_e32 v3, v1
	v_lshl_add_u64 v[6:7], s[14:15], 0, v[4:5]
	v_lshl_add_u64 v[38:39], s[6:7], 0, v[2:3]
	v_lshlrev_b64 v[6:7], 12, v[6:7]
	v_lshl_add_u64 v[6:7], v[38:39], 0, v[6:7]
	global_load_dwordx4 v[34:37], v[6:7], off
	v_add_u32_e32 v3, 0x200, v251
	v_and_b32_e32 v6, 0xffffffcf, v251
	v_ashrrev_i32_e32 v40, 5, v3
	v_ashrrev_i32_e32 v7, 31, v6
	v_ashrrev_i32_e32 v41, 31, v40
	v_bfe_u32 v252, v251, 4, 2
	v_lshlrev_b64 v[66:67], 9, v[6:7]
	v_add_u32_e32 v42, 0, v2
	v_lshl_add_u64 v[2:3], s[14:15], 0, v[40:41]
	v_lshlrev_b32_e32 v0, 4, v252
	v_lshlrev_b64 v[46:47], 12, v[2:3]
	v_lshl_add_u64 v[2:3], s[0:1], 0, v[66:67]
	s_movk_i32 s10, 0x210
	v_lshl_add_u64 v[2:3], v[2:3], 0, v[0:1]
	s_movk_i32 s0, 0x2000
	v_mad_u64_u32 v[44:45], s[6:7], v4, s10, v[42:43]
	v_add_co_u32_e32 v4, vcc, s0, v2
	s_movk_i32 s0, 0x4000
	s_nop 0
	v_addc_co_u32_e32 v5, vcc, 0, v3, vcc
	v_add_co_u32_e32 v6, vcc, s0, v2
	v_lshl_add_u64 v[46:47], v[38:39], 0, v[46:47]
	s_nop 0
	v_addc_co_u32_e32 v7, vcc, 0, v3, vcc
	v_add_co_u32_e32 v48, vcc, s75, v2
	v_add_u32_e32 v41, 0x400, v251
	s_nop 0
	v_addc_co_u32_e32 v49, vcc, 0, v3, vcc
	global_load_dwordx4 v[18:21], v[2:3], off
	global_load_dwordx4 v[14:17], v[2:3], off offset:64
	global_load_dwordx4 v[22:25], v[4:5], off
	global_load_dwordx4 v[10:13], v[4:5], off offset:64
	global_load_dwordx4 v[26:29], v[6:7], off
	s_nop 0
	global_load_dwordx4 v[6:9], v[6:7], off offset:64
	s_nop 0
	global_load_dwordx4 v[30:33], v[48:49], off
	global_load_dwordx4 v[2:5], v[48:49], off offset:64
	v_ashrrev_i32_e32 v226, 6, v251
	v_and_b32_e32 v217, 15, v251
	s_movk_i32 s30, 0x210
	s_waitcnt vmcnt(0) lgkmcnt(0)
	ds_write_b128 v44, v[34:37]
	global_load_dwordx4 v[34:37], v[46:47], off
	v_ashrrev_i32_e32 v44, 5, v41
	v_ashrrev_i32_e32 v45, 31, v44
	v_lshl_add_u64 v[46:47], s[14:15], 0, v[44:45]
	v_mad_u64_u32 v[40:41], s[0:1], v40, s10, v[42:43]
	v_lshlrev_b64 v[46:47], 12, v[46:47]
	v_lshl_add_u64 v[46:47], v[38:39], 0, v[46:47]
	v_mad_u64_u32 v[44:45], s[0:1], v44, s10, v[42:43]
	s_waitcnt vmcnt(0) lgkmcnt(0)
	ds_write_b128 v40, v[34:37]
	global_load_dwordx4 v[34:37], v[46:47], off
	v_add_u32_e32 v40, 0x600, v251
	v_ashrrev_i32_e32 v40, 5, v40
	v_ashrrev_i32_e32 v41, 31, v40
	v_lshl_add_u64 v[46:47], s[14:15], 0, v[40:41]
	v_lshlrev_b64 v[46:47], 12, v[46:47]
	v_lshl_add_u64 v[46:47], v[38:39], 0, v[46:47]
	v_add_u32_e32 v41, 0x800, v251
	s_waitcnt vmcnt(0) lgkmcnt(0)
	ds_write_b128 v44, v[34:37]
	global_load_dwordx4 v[34:37], v[46:47], off
	v_ashrrev_i32_e32 v44, 5, v41
	v_ashrrev_i32_e32 v45, 31, v44
	v_lshl_add_u64 v[46:47], s[14:15], 0, v[44:45]
	v_mad_u64_u32 v[40:41], s[0:1], v40, s10, v[42:43]
	v_lshlrev_b64 v[46:47], 12, v[46:47]
	v_lshl_add_u64 v[46:47], v[38:39], 0, v[46:47]
	v_mad_u64_u32 v[44:45], s[0:1], v44, s10, v[42:43]
	s_waitcnt vmcnt(0) lgkmcnt(0)
	ds_write_b128 v40, v[34:37]
	global_load_dwordx4 v[34:37], v[46:47], off
	v_add_u32_e32 v40, 0xa00, v251
	v_ashrrev_i32_e32 v40, 5, v40
	v_ashrrev_i32_e32 v41, 31, v40
	v_lshl_add_u64 v[46:47], s[14:15], 0, v[40:41]
	v_lshlrev_b64 v[46:47], 12, v[46:47]
	v_lshl_add_u64 v[46:47], v[38:39], 0, v[46:47]
	v_add_u32_e32 v41, 0xc00, v251
	s_waitcnt vmcnt(0) lgkmcnt(0)
	ds_write_b128 v44, v[34:37]
	global_load_dwordx4 v[34:37], v[46:47], off
	v_ashrrev_i32_e32 v44, 5, v41
	v_ashrrev_i32_e32 v45, 31, v44
	v_lshl_add_u64 v[46:47], s[14:15], 0, v[44:45]
	v_mad_u64_u32 v[40:41], s[0:1], v40, s10, v[42:43]
	v_lshlrev_b64 v[46:47], 12, v[46:47]
	v_lshl_add_u64 v[46:47], v[38:39], 0, v[46:47]
	s_waitcnt vmcnt(0) lgkmcnt(0)
	ds_write_b128 v40, v[34:37]
	global_load_dwordx4 v[34:37], v[46:47], off
	v_add_u32_e32 v40, 0xe00, v251
	v_ashrrev_i32_e32 v46, 5, v40
	v_ashrrev_i32_e32 v47, 31, v46
	v_mad_u64_u32 v[40:41], s[0:1], v44, s10, v[42:43]
	v_lshl_add_u64 v[44:45], s[14:15], 0, v[46:47]
	v_lshlrev_b64 v[44:45], 12, v[44:45]
	v_lshl_add_u64 v[38:39], v[38:39], 0, v[44:45]
	v_mad_u64_u32 v[42:43], s[6:7], v46, s10, v[42:43]
	s_waitcnt vmcnt(0) lgkmcnt(0)
	ds_write_b128 v40, v[34:37]
	global_load_dwordx4 v[38:41], v[38:39], off
	v_ashrrev_i32_e32 v36, 7, v251
	v_and_b32_e32 v34, 1, v226
	v_lshlrev_b32_e32 v35, 3, v252
	v_cmp_lt_i32_e32 vcc, 1, v36
	v_cmp_eq_u32_e64 s[0:1], 0, v34
	v_lshlrev_b32_e32 v214, 1, v35
	s_or_b64 s[0:1], vcc, s[0:1]
	v_lshl_or_b32 v68, v36, 5, v217
	s_waitcnt vmcnt(0) lgkmcnt(0)
	ds_write_b128 v42, v[38:41]
	s_waitcnt lgkmcnt(0)
	s_barrier
	s_and_saveexec_b64 s[6:7], s[0:1]
	s_xor_b64 s[0:1], exec, s[6:7]
	s_cbranch_execz .LBB0_740
	v_lshlrev_b32_e32 v69, 6, v34
	v_or3_b32 v34, v69, v217, s14
	v_mov_b32_e32 v35, s15
	s_lshl_b32 s2, s2, 8
	v_lshlrev_b64 v[34:35], 12, v[34:35]
	v_lshl_add_u64 v[34:35], s[44:45], 0, v[34:35]
	s_lshl_b32 s54, s2, 1
	v_lshl_add_u64 v[34:35], v[34:35], 0, s[54:55]
	v_mov_b32_e32 v215, v1
	v_lshl_add_u64 v[34:35], v[34:35], 0, v[214:215]
	v_add_co_u32_e32 v166, vcc, s56, v34
	s_nop 1
	v_addc_co_u32_e32 v167, vcc, 0, v35, vcc
	v_add_co_u32_e32 v168, vcc, s57, v34
	s_nop 1
	v_addc_co_u32_e32 v169, vcc, 0, v35, vcc
	v_add_co_u32_e32 v170, vcc, s83, v34
	s_nop 1
	v_addc_co_u32_e32 v171, vcc, 0, v35, vcc
	global_load_dwordx4 v[102:105], v[34:35], off
	global_load_dwordx4 v[106:109], v[34:35], off offset:64
	global_load_dwordx4 v[110:113], v[34:35], off offset:128
	global_load_dwordx4 v[114:117], v[166:167], off
	global_load_dwordx4 v[118:121], v[168:169], off
	global_load_dwordx4 v[122:125], v[170:171], off
	global_load_dwordx4 v[126:129], v[166:167], off offset:64
	global_load_dwordx4 v[130:133], v[168:169], off offset:64
	global_load_dwordx4 v[134:137], v[170:171], off offset:64
	global_load_dwordx4 v[138:141], v[166:167], off offset:128
	global_load_dwordx4 v[142:145], v[34:35], off offset:192
	global_load_dwordx4 v[146:149], v[168:169], off offset:128
	global_load_dwordx4 v[150:153], v[170:171], off offset:128
	global_load_dwordx4 v[154:157], v[166:167], off offset:192
	global_load_dwordx4 v[158:161], v[168:169], off offset:192
	global_load_dwordx4 v[162:165], v[170:171], off offset:192
	global_load_dwordx4 v[174:177], v[34:35], off offset:256
	global_load_dwordx4 v[178:181], v[166:167], off offset:256
	global_load_dwordx4 v[182:185], v[168:169], off offset:256
	global_load_dwordx4 v[186:189], v[170:171], off offset:256
	global_load_dwordx4 v[190:193], v[34:35], off offset:320
	global_load_dwordx4 v[194:197], v[166:167], off offset:320
	global_load_dwordx4 v[198:201], v[168:169], off offset:320
	global_load_dwordx4 v[202:205], v[170:171], off offset:320
	global_load_dwordx4 v[208:211], v[34:35], off offset:384
	global_load_dwordx4 v[230:233], v[166:167], off offset:384
	global_load_dwordx4 v[234:237], v[168:169], off offset:384
	global_load_dwordx4 v[238:241], v[170:171], off offset:384
	global_load_dwordx4 v[242:245], v[34:35], off offset:448
	global_load_dwordx4 v[246:249], v[166:167], off offset:448
	v_lshl_or_b32 v68, v36, 5, v217
	v_mul_lo_u32 v36, v68, s30
	v_add3_u32 v40, 0, v214, v36
	ds_read_b128 v[46:49], v40
	ds_read_b128 v[50:53], v40 offset:8448
	v_add_co_u32_e32 v36, vcc, s56, v34
	v_addc_co_u32_e32 v37, vcc, 0, v35, vcc
	v_add_co_u32_e32 v38, vcc, s57, v34
	ds_read_b128 v[82:85], v40 offset:64
	ds_read_b128 v[90:93], v40 offset:8512
	v_addc_co_u32_e32 v39, vcc, 0, v35, vcc
	s_mov_b32 s54, 0x34000
	s_waitcnt vmcnt(0) lgkmcnt(0)
	v_mov_b32_e32 v42, v102
	v_mov_b32_e32 v43, v103
	v_mov_b32_e32 v44, v104
	v_mov_b32_e32 v45, v105
	v_mov_b32_e32 v78, v106
	v_mov_b32_e32 v79, v107
	v_mov_b32_e32 v80, v108
	v_mov_b32_e32 v81, v109
	v_mov_b32_e32 v94, v110
	v_mov_b32_e32 v95, v111
	v_mov_b32_e32 v96, v112
	v_mov_b32_e32 v97, v113
	s_nop 1
	v_mfma_f32_16x16x32_bf16 v[54:57], v[42:45], v[46:49], 0
	ds_read_b128 v[98:101], v40 offset:8576
	v_mfma_f32_16x16x32_bf16 v[58:61], v[42:45], v[50:53], 0
	s_waitcnt lgkmcnt(0)
	v_mov_b32_e32 v42, v114
	v_mov_b32_e32 v43, v115
	v_mov_b32_e32 v44, v116
	v_mov_b32_e32 v45, v117
	s_nop 1
	v_mfma_f32_16x16x32_bf16 v[62:65], v[42:45], v[46:49], 0
	v_mfma_f32_16x16x32_bf16 v[70:73], v[42:45], v[50:53], 0
	s_waitcnt lgkmcnt(0)
	v_mov_b32_e32 v42, v118
	v_mov_b32_e32 v43, v119
	v_mov_b32_e32 v44, v120
	v_mov_b32_e32 v45, v121
	s_nop 1
	v_mfma_f32_16x16x32_bf16 v[74:77], v[42:45], v[46:49], 0
	v_mfma_f32_16x16x32_bf16 v[86:89], v[42:45], v[50:53], 0
	v_add_co_u32_e32 v42, vcc, s83, v34
	s_nop 1
	v_addc_co_u32_e32 v43, vcc, 0, v35, vcc
	v_mfma_f32_16x16x32_bf16 v[54:57], v[78:81], v[82:85], v[54:57]
	v_mfma_f32_16x16x32_bf16 v[58:61], v[78:81], v[90:93], v[58:61]
	s_waitcnt lgkmcnt(0)
	v_mov_b32_e32 v78, v122
	v_mov_b32_e32 v79, v123
	v_mov_b32_e32 v80, v124
	v_mov_b32_e32 v81, v125
	s_nop 1
	v_mfma_f32_16x16x32_bf16 v[44:47], v[78:81], v[46:49], 0
	v_mfma_f32_16x16x32_bf16 v[48:51], v[78:81], v[50:53], 0
	s_waitcnt lgkmcnt(0)
	v_mov_b32_e32 v78, v126
	v_mov_b32_e32 v79, v127
	v_mov_b32_e32 v80, v128
	v_mov_b32_e32 v81, v129
	s_nop 1
	v_mfma_f32_16x16x32_bf16 v[62:65], v[78:81], v[82:85], v[62:65]
	v_mfma_f32_16x16x32_bf16 v[70:73], v[78:81], v[90:93], v[70:73]
	s_waitcnt lgkmcnt(0)
	v_mov_b32_e32 v78, v130
	v_mov_b32_e32 v79, v131
	v_mov_b32_e32 v80, v132
	v_mov_b32_e32 v81, v133
	s_nop 1
	v_mfma_f32_16x16x32_bf16 v[74:77], v[78:81], v[82:85], v[74:77]
	v_mfma_f32_16x16x32_bf16 v[78:81], v[78:81], v[90:93], v[86:89]
	s_nop 2
	ds_read_b128 v[86:89], v40 offset:128
	s_waitcnt lgkmcnt(0)
	v_mfma_f32_16x16x32_bf16 v[52:55], v[94:97], v[86:89], v[54:57]
	v_mfma_f32_16x16x32_bf16 v[56:59], v[94:97], v[98:101], v[58:61]
	s_waitcnt lgkmcnt(0)
	v_mov_b32_e32 v94, v134
	v_mov_b32_e32 v95, v135
	v_mov_b32_e32 v96, v136
	v_mov_b32_e32 v97, v137
	s_nop 1
	v_mfma_f32_16x16x32_bf16 v[44:47], v[94:97], v[82:85], v[44:47]
	v_mfma_f32_16x16x32_bf16 v[48:51], v[94:97], v[90:93], v[48:51]
	ds_read_b128 v[94:97], v40 offset:8640
	s_waitcnt lgkmcnt(0)
	v_mov_b32_e32 v82, v138
	v_mov_b32_e32 v83, v139
	v_mov_b32_e32 v84, v140
	v_mov_b32_e32 v85, v141
	v_mov_b32_e32 v90, v142
	v_mov_b32_e32 v91, v143
	v_mov_b32_e32 v92, v144
	v_mov_b32_e32 v93, v145
	s_nop 1
	v_mfma_f32_16x16x32_bf16 v[60:63], v[82:85], v[86:89], v[62:65]
	v_mfma_f32_16x16x32_bf16 v[70:73], v[82:85], v[98:101], v[70:73]
	s_waitcnt lgkmcnt(0)
	v_mov_b32_e32 v82, v146
	v_mov_b32_e32 v83, v147
	v_mov_b32_e32 v84, v148
	v_mov_b32_e32 v85, v149
	s_nop 1
	v_mfma_f32_16x16x32_bf16 v[74:77], v[82:85], v[86:89], v[74:77]
	v_mfma_f32_16x16x32_bf16 v[78:81], v[82:85], v[98:101], v[78:81]
	ds_read_b128 v[82:85], v40 offset:192
	s_waitcnt lgkmcnt(0)
	v_mfma_f32_16x16x32_bf16 v[52:55], v[90:93], v[82:85], v[52:55]
	v_mfma_f32_16x16x32_bf16 v[56:59], v[90:93], v[94:97], v[56:59]
	s_waitcnt lgkmcnt(0)
	v_mov_b32_e32 v90, v150
	v_mov_b32_e32 v91, v151
	v_mov_b32_e32 v92, v152
	v_mov_b32_e32 v93, v153
	s_nop 1
	v_mfma_f32_16x16x32_bf16 v[44:47], v[90:93], v[86:89], v[44:47]
	v_mfma_f32_16x16x32_bf16 v[48:51], v[90:93], v[98:101], v[48:51]
	ds_read_b128 v[90:93], v40 offset:8704
	ds_read_b128 v[98:101], v40 offset:8896
	s_waitcnt lgkmcnt(0)
	v_mov_b32_e32 v86, v154
	v_mov_b32_e32 v87, v155
	v_mov_b32_e32 v88, v156
	v_mov_b32_e32 v89, v157
	s_nop 1
	v_mfma_f32_16x16x32_bf16 v[60:63], v[86:89], v[82:85], v[60:63]
	v_mfma_f32_16x16x32_bf16 v[70:73], v[86:89], v[94:97], v[70:73]
	s_waitcnt lgkmcnt(0)
	v_mov_b32_e32 v86, v158
	v_mov_b32_e32 v87, v159
	v_mov_b32_e32 v88, v160
	v_mov_b32_e32 v89, v161
	s_nop 1
	v_mfma_f32_16x16x32_bf16 v[74:77], v[86:89], v[82:85], v[74:77]
	v_mfma_f32_16x16x32_bf16 v[78:81], v[86:89], v[94:97], v[78:81]
	s_waitcnt lgkmcnt(0)
	v_mov_b32_e32 v86, v162
	v_mov_b32_e32 v87, v163
	v_mov_b32_e32 v88, v164
	v_mov_b32_e32 v89, v165
	s_nop 1
	v_mfma_f32_16x16x32_bf16 v[44:47], v[86:89], v[82:85], v[44:47]
	v_mfma_f32_16x16x32_bf16 v[48:51], v[86:89], v[94:97], v[48:51]
	ds_read_b128 v[86:89], v40 offset:256
	s_waitcnt lgkmcnt(0)
	v_mov_b32_e32 v82, v174
	v_mov_b32_e32 v83, v175
	v_mov_b32_e32 v84, v176
	v_mov_b32_e32 v85, v177
	s_nop 1
	v_mfma_f32_16x16x32_bf16 v[52:55], v[82:85], v[86:89], v[52:55]
	v_mfma_f32_16x16x32_bf16 v[56:59], v[82:85], v[90:93], v[56:59]
	s_waitcnt lgkmcnt(0)
	v_mov_b32_e32 v82, v178
	v_mov_b32_e32 v83, v179
	v_mov_b32_e32 v84, v180
	v_mov_b32_e32 v85, v181
	s_nop 1
	v_mfma_f32_16x16x32_bf16 v[60:63], v[82:85], v[86:89], v[60:63]
	v_mfma_f32_16x16x32_bf16 v[70:73], v[82:85], v[90:93], v[70:73]
	s_waitcnt lgkmcnt(0)
	v_mov_b32_e32 v82, v182
	v_mov_b32_e32 v83, v183
	v_mov_b32_e32 v84, v184
	v_mov_b32_e32 v85, v185
	s_nop 1
	v_mfma_f32_16x16x32_bf16 v[74:77], v[82:85], v[86:89], v[74:77]
	v_mfma_f32_16x16x32_bf16 v[78:81], v[82:85], v[90:93], v[78:81]
	s_waitcnt lgkmcnt(0)
	v_mov_b32_e32 v82, v186
	v_mov_b32_e32 v83, v187
	v_mov_b32_e32 v84, v188
	v_mov_b32_e32 v85, v189
	s_nop 1
	v_mfma_f32_16x16x32_bf16 v[44:47], v[82:85], v[86:89], v[44:47]
	v_mfma_f32_16x16x32_bf16 v[48:51], v[82:85], v[90:93], v[48:51]
	ds_read_b128 v[82:85], v40 offset:320
	ds_read_b128 v[90:93], v40 offset:8768
	s_waitcnt lgkmcnt(0)
	v_mov_b32_e32 v86, v190
	v_mov_b32_e32 v87, v191
	v_mov_b32_e32 v88, v192
	v_mov_b32_e32 v89, v193
	s_nop 1
	v_mfma_f32_16x16x32_bf16 v[52:55], v[86:89], v[82:85], v[52:55]
	v_mfma_f32_16x16x32_bf16 v[56:59], v[86:89], v[90:93], v[56:59]
	s_waitcnt lgkmcnt(0)
	v_mov_b32_e32 v86, v194
	v_mov_b32_e32 v87, v195
	v_mov_b32_e32 v88, v196
	v_mov_b32_e32 v89, v197
	s_nop 1
	v_mfma_f32_16x16x32_bf16 v[60:63], v[86:89], v[82:85], v[60:63]
	v_mfma_f32_16x16x32_bf16 v[70:73], v[86:89], v[90:93], v[70:73]
	s_waitcnt lgkmcnt(0)
	v_mov_b32_e32 v86, v198
	v_mov_b32_e32 v87, v199
	v_mov_b32_e32 v88, v200
	v_mov_b32_e32 v89, v201
	s_nop 1
	v_mfma_f32_16x16x32_bf16 v[74:77], v[86:89], v[82:85], v[74:77]
	v_mfma_f32_16x16x32_bf16 v[78:81], v[86:89], v[90:93], v[78:81]
	s_waitcnt lgkmcnt(0)
	v_mov_b32_e32 v86, v202
	v_mov_b32_e32 v87, v203
	v_mov_b32_e32 v88, v204
	v_mov_b32_e32 v89, v205
	s_nop 1
	v_mfma_f32_16x16x32_bf16 v[44:47], v[86:89], v[82:85], v[44:47]
	v_mfma_f32_16x16x32_bf16 v[48:51], v[86:89], v[90:93], v[48:51]
	ds_read_b128 v[86:89], v40 offset:384
	ds_read_b128 v[90:93], v40 offset:8832
	s_waitcnt lgkmcnt(0)
	v_mov_b32_e32 v82, v208
	v_mov_b32_e32 v83, v209
	v_mov_b32_e32 v84, v210
	v_mov_b32_e32 v85, v211
	s_nop 1
	v_mfma_f32_16x16x32_bf16 v[52:55], v[82:85], v[86:89], v[52:55]
	v_mfma_f32_16x16x32_bf16 v[56:59], v[82:85], v[90:93], v[56:59]
	s_waitcnt lgkmcnt(0)
	v_mov_b32_e32 v82, v230
	v_mov_b32_e32 v83, v231
	v_mov_b32_e32 v84, v232
	v_mov_b32_e32 v85, v233
	s_nop 1
	v_mfma_f32_16x16x32_bf16 v[94:97], v[82:85], v[86:89], v[60:63]
	s_nop 2
	s_waitcnt lgkmcnt(0)
	v_mov_b32_e32 v60, v234
	v_mov_b32_e32 v61, v235
	v_mov_b32_e32 v62, v236
	v_mov_b32_e32 v63, v237
	s_nop 1
	v_mfma_f32_16x16x32_bf16 v[74:77], v[60:63], v[86:89], v[74:77]
	v_mfma_f32_16x16x32_bf16 v[78:81], v[60:63], v[90:93], v[78:81]
	v_mfma_f32_16x16x32_bf16 v[70:73], v[82:85], v[90:93], v[70:73]
	s_waitcnt lgkmcnt(0)
	v_mov_b32_e32 v60, v238
	v_mov_b32_e32 v61, v239
	v_mov_b32_e32 v62, v240
	v_mov_b32_e32 v63, v241
	s_nop 1
	v_mfma_f32_16x16x32_bf16 v[82:85], v[60:63], v[86:89], v[44:47]
	s_nop 2
	s_nop 0
	v_mfma_f32_16x16x32_bf16 v[86:89], v[60:63], v[90:93], v[48:51]
	ds_read_b128 v[90:93], v40 offset:448
	s_waitcnt lgkmcnt(0)
	v_mov_b32_e32 v44, v242
	v_mov_b32_e32 v45, v243
	v_mov_b32_e32 v46, v244
	v_mov_b32_e32 v47, v245
	v_mov_b32_e32 v34, v246
	v_mov_b32_e32 v35, v247
	v_mov_b32_e32 v36, v248
	v_mov_b32_e32 v37, v249
	s_nop 1
	v_mfma_f32_16x16x32_bf16 v[62:65], v[44:47], v[90:93], v[52:55]
	v_mfma_f32_16x16x32_bf16 v[58:61], v[44:47], v[98:101], v[56:59]
	v_mfma_f32_16x16x32_bf16 v[54:57], v[34:37], v[90:93], v[94:97]
	v_mfma_f32_16x16x32_bf16 v[50:53], v[34:37], v[98:101], v[70:73]
	global_load_dwordx4 v[102:105], v[168:169], off offset:448
	global_load_dwordx4 v[106:109], v[170:171], off offset:448
	s_waitcnt vmcnt(0) lgkmcnt(0)
	v_mov_b32_e32 v34, v102
	v_mov_b32_e32 v35, v103
	v_mov_b32_e32 v36, v104
	v_mov_b32_e32 v37, v105
	s_nop 1
	v_mfma_f32_16x16x32_bf16 v[46:49], v[34:37], v[90:93], v[74:77]
	v_or_b32_e32 v70, 16, v68
	v_mfma_f32_16x16x32_bf16 v[38:41], v[34:37], v[98:101], v[78:81]
	s_waitcnt lgkmcnt(0)
	v_mov_b32_e32 v34, v106
	v_mov_b32_e32 v35, v107
	v_mov_b32_e32 v36, v108
	v_mov_b32_e32 v37, v109
	s_nop 1
	v_mfma_f32_16x16x32_bf16 v[42:45], v[34:37], v[90:93], v[82:85]
	v_mfma_f32_16x16x32_bf16 v[34:37], v[34:37], v[98:101], v[86:89]

.LBB0_743:
	ds_read_b128 v[164:167], v0
	ds_read_b128 v[174:177], v0 offset:64
	s_waitcnt vmcnt(0) lgkmcnt(0)
	v_mfma_f32_16x16x32_bf16 v[58:61], v[18:21], v[164:167], v[58:61]
	v_mfma_f32_16x16x32_bf16 v[46:49], v[22:25], v[164:167], v[46:49]
	v_mfma_f32_16x16x32_bf16 v[38:41], v[26:29], v[164:167], v[38:41]
	v_mfma_f32_16x16x32_bf16 v[34:37], v[30:33], v[164:167], v[34:37]
	ds_read_b128 v[164:167], v0 offset:8448
	s_waitcnt lgkmcnt(1)
	v_mfma_f32_16x16x32_bf16 v[58:61], v[14:17], v[174:177], v[58:61]
	v_mfma_f32_16x16x32_bf16 v[46:49], v[10:13], v[174:177], v[46:49]
	v_mfma_f32_16x16x32_bf16 v[38:41], v[6:9], v[174:177], v[38:41]
	v_mfma_f32_16x16x32_bf16 v[34:37], v[2:5], v[174:177], v[34:37]
	ds_read_b128 v[174:177], v0 offset:8512
	s_waitcnt lgkmcnt(1)
	v_mfma_f32_16x16x32_bf16 v[74:77], v[18:21], v[164:167], v[74:77]
	v_mfma_f32_16x16x32_bf16 v[62:65], v[22:25], v[164:167], v[62:65]
	v_mfma_f32_16x16x32_bf16 v[50:53], v[26:29], v[164:167], v[50:53]
	v_mfma_f32_16x16x32_bf16 v[42:45], v[30:33], v[164:167], v[42:45]
	ds_read_b128 v[164:167], v0 offset:16896
	s_waitcnt lgkmcnt(1)
	v_mfma_f32_16x16x32_bf16 v[74:77], v[14:17], v[174:177], v[74:77]
	v_mfma_f32_16x16x32_bf16 v[62:65], v[10:13], v[174:177], v[62:65]
	v_mfma_f32_16x16x32_bf16 v[50:53], v[6:9], v[174:177], v[50:53]
	v_mfma_f32_16x16x32_bf16 v[42:45], v[2:5], v[174:177], v[42:45]
	ds_read_b128 v[174:177], v0 offset:16960
	s_waitcnt lgkmcnt(1)
	v_mfma_f32_16x16x32_bf16 v[90:93], v[18:21], v[164:167], v[90:93]
	v_mfma_f32_16x16x32_bf16 v[78:81], v[22:25], v[164:167], v[78:81]
	v_mfma_f32_16x16x32_bf16 v[66:69], v[26:29], v[164:167], v[66:69]
	v_mfma_f32_16x16x32_bf16 v[54:57], v[30:33], v[164:167], v[54:57]
	ds_read_b128 v[164:167], v0 offset:25344
	s_waitcnt lgkmcnt(1)
	v_mfma_f32_16x16x32_bf16 v[90:93], v[14:17], v[174:177], v[90:93]
	v_mfma_f32_16x16x32_bf16 v[78:81], v[10:13], v[174:177], v[78:81]
	v_mfma_f32_16x16x32_bf16 v[66:69], v[6:9], v[174:177], v[66:69]
	v_mfma_f32_16x16x32_bf16 v[54:57], v[2:5], v[174:177], v[54:57]
	ds_read_b128 v[174:177], v0 offset:25408
	s_waitcnt lgkmcnt(1)
	v_mfma_f32_16x16x32_bf16 v[106:109], v[18:21], v[164:167], v[106:109]
	v_mfma_f32_16x16x32_bf16 v[94:97], v[22:25], v[164:167], v[94:97]
	v_mfma_f32_16x16x32_bf16 v[82:85], v[26:29], v[164:167], v[82:85]
	v_mfma_f32_16x16x32_bf16 v[70:73], v[30:33], v[164:167], v[70:73]
	ds_read_b128 v[164:167], v0 offset:33792
	s_waitcnt lgkmcnt(1)
	v_mfma_f32_16x16x32_bf16 v[106:109], v[14:17], v[174:177], v[106:109]
	v_mfma_f32_16x16x32_bf16 v[94:97], v[10:13], v[174:177], v[94:97]
	v_mfma_f32_16x16x32_bf16 v[82:85], v[6:9], v[174:177], v[82:85]
	v_mfma_f32_16x16x32_bf16 v[70:73], v[2:5], v[174:177], v[70:73]
	ds_read_b128 v[174:177], v0 offset:33856
	s_waitcnt lgkmcnt(1)
	v_mfma_f32_16x16x32_bf16 v[122:125], v[18:21], v[164:167], v[122:125]
	v_mfma_f32_16x16x32_bf16 v[110:113], v[22:25], v[164:167], v[110:113]
	v_mfma_f32_16x16x32_bf16 v[98:101], v[26:29], v[164:167], v[98:101]
	v_mfma_f32_16x16x32_bf16 v[86:89], v[30:33], v[164:167], v[86:89]
	ds_read_b128 v[164:167], v0 offset:42240
	s_waitcnt lgkmcnt(1)
	v_mfma_f32_16x16x32_bf16 v[122:125], v[14:17], v[174:177], v[122:125]
	v_mfma_f32_16x16x32_bf16 v[110:113], v[10:13], v[174:177], v[110:113]
	v_mfma_f32_16x16x32_bf16 v[98:101], v[6:9], v[174:177], v[98:101]
	v_mfma_f32_16x16x32_bf16 v[86:89], v[2:5], v[174:177], v[86:89]
	ds_read_b128 v[174:177], v0 offset:42304
	s_waitcnt lgkmcnt(1)
	v_mfma_f32_16x16x32_bf16 v[134:137], v[18:21], v[164:167], v[134:137]
	v_mfma_f32_16x16x32_bf16 v[126:129], v[22:25], v[164:167], v[126:129]
	v_mfma_f32_16x16x32_bf16 v[114:117], v[26:29], v[164:167], v[114:117]
	v_mfma_f32_16x16x32_bf16 v[102:105], v[30:33], v[164:167], v[102:105]
	ds_read_b128 v[164:167], v0 offset:50688
	s_waitcnt lgkmcnt(1)
	v_mfma_f32_16x16x32_bf16 v[134:137], v[14:17], v[174:177], v[134:137]
	v_mfma_f32_16x16x32_bf16 v[126:129], v[10:13], v[174:177], v[126:129]
	v_mfma_f32_16x16x32_bf16 v[114:117], v[6:9], v[174:177], v[114:117]
	v_mfma_f32_16x16x32_bf16 v[102:105], v[2:5], v[174:177], v[102:105]
	ds_read_b128 v[174:177], v0 offset:50752
	s_waitcnt lgkmcnt(1)
	v_mfma_f32_16x16x32_bf16 v[142:145], v[18:21], v[164:167], v[142:145]
	v_mfma_f32_16x16x32_bf16 v[138:141], v[22:25], v[164:167], v[138:141]
	v_mfma_f32_16x16x32_bf16 v[130:133], v[26:29], v[164:167], v[130:133]
	v_mfma_f32_16x16x32_bf16 v[118:121], v[30:33], v[164:167], v[118:121]
	ds_read_b128 v[164:167], v0 offset:59136
	s_waitcnt lgkmcnt(1)
	v_mfma_f32_16x16x32_bf16 v[142:145], v[14:17], v[174:177], v[142:145]
	v_mfma_f32_16x16x32_bf16 v[138:141], v[10:13], v[174:177], v[138:141]
	v_mfma_f32_16x16x32_bf16 v[130:133], v[6:9], v[174:177], v[130:133]
	v_mfma_f32_16x16x32_bf16 v[118:121], v[2:5], v[174:177], v[118:121]
	ds_read_b128 v[174:177], v0 offset:59200
	v_add_u32_e32 v0, 0x80, v0
	s_waitcnt lgkmcnt(1)
	v_mfma_f32_16x16x32_bf16 v[146:149], v[30:33], v[164:167], v[146:149]
	v_lshl_add_u64 v[30:31], v[162:163], 0, s[0:1]
	s_add_u32 s0, s0, 0x80
	s_addc_u32 s1, s1, 0
	v_mfma_f32_16x16x32_bf16 v[150:153], v[18:21], v[164:167], v[150:153]
	s_cmpk_lg_i32 s0, 0x180
	v_mfma_f32_16x16x32_bf16 v[154:157], v[22:25], v[164:167], v[154:157]
	v_mfma_f32_16x16x32_bf16 v[158:161], v[26:29], v[164:167], v[158:161]
	v_add_co_u32_e32 v164, vcc, s48, v30
	s_nop 1
	v_addc_co_u32_e32 v165, vcc, 0, v31, vcc
	v_add_co_u32_e32 v166, vcc, s49, v30
	global_load_dwordx4 v[18:21], v[164:165], off offset:128
	s_nop 0
	v_addc_co_u32_e32 v167, vcc, 0, v31, vcc
	v_add_co_u32_e32 v170, vcc, s53, v30
	global_load_dwordx4 v[22:25], v[166:167], off offset:128
	s_nop 0
	v_addc_co_u32_e32 v171, vcc, 0, v31, vcc
	v_add_co_u32_e32 v168, vcc, s96, v30
	global_load_dwordx4 v[26:29], v[170:171], off offset:128
	s_nop 0
	v_addc_co_u32_e32 v169, vcc, 0, v31, vcc
	global_load_dwordx4 v[30:33], v[168:169], off offset:128
	s_waitcnt lgkmcnt(0)
	v_mfma_f32_16x16x32_bf16 v[150:153], v[14:17], v[174:177], v[150:153]
	v_mfma_f32_16x16x32_bf16 v[154:157], v[10:13], v[174:177], v[154:157]
	v_mfma_f32_16x16x32_bf16 v[158:161], v[6:9], v[174:177], v[158:161]
	v_mfma_f32_16x16x32_bf16 v[146:149], v[2:5], v[174:177], v[146:149]
	global_load_dwordx4 v[14:17], v[164:165], off offset:192
	global_load_dwordx4 v[10:13], v[166:167], off offset:192
	global_load_dwordx4 v[6:9], v[170:171], off offset:192
	global_load_dwordx4 v[2:5], v[168:169], off offset:192
	s_cbranch_scc1 .LBB0_743
	v_and_b32_e32 v216, 0xffffffc0, v251
	v_add_u32_e32 v0, s13, v216
	v_or_b32_e32 v162, v0, v217
	v_ashrrev_i32_e32 v163, 31, v162
	v_lshlrev_b64 v[162:163], 15, v[162:163]
	v_lshl_add_u64 v[162:163], s[16:17], 0, v[162:163]
	v_lshl_add_u64 v[162:163], s[14:15], 1, v[162:163]
	v_mov_b32_e32 v215, v1
	v_add3_u32 v0, 0, v172, v214
	v_lshl_add_u64 v[218:219], v[162:163], 0, v[214:215]
	ds_read_b128 v[162:165], v0 offset:384
	s_mov_b32 s0, 0x80000
	s_waitcnt vmcnt(0) lgkmcnt(0)
	v_mfma_f32_16x16x32_bf16 v[246:249], v[30:33], v[162:165], v[34:37]
	s_nop 2
	ds_read_b128 v[34:37], v0 offset:8832
	v_add_co_u32_e32 v220, vcc, s0, v218
	s_waitcnt lgkmcnt(0)
	v_mfma_f32_16x16x32_bf16 v[208:211], v[18:21], v[34:37], v[74:77]
	v_addc_co_u32_e32 v221, vcc, 0, v219, vcc
	s_mov_b32 s0, 0x100000
	v_mfma_f32_16x16x32_bf16 v[62:65], v[22:25], v[34:37], v[62:65]
	v_add_co_u32_e32 v222, vcc, s0, v218
	s_mov_b32 s0, 0x180000
	v_mfma_f32_16x16x32_bf16 v[234:237], v[26:29], v[34:37], v[50:53]
	v_addc_co_u32_e32 v223, vcc, 0, v219, vcc
	v_add_co_u32_e32 v224, vcc, s0, v218
	v_mfma_f32_16x16x32_bf16 v[230:233], v[30:33], v[34:37], v[42:45]
	ds_read_b128 v[34:37], v0 offset:17280
	ds_read_b128 v[50:53], v0 offset:448
	v_addc_co_u32_e32 v225, vcc, 0, v219, vcc
	s_waitcnt lgkmcnt(1)
	v_mfma_f32_16x16x32_bf16 v[90:93], v[18:21], v[34:37], v[90:93]
	v_readlane_b32 s1, v255, 38
	s_movk_i32 s0, 0x110
	v_mfma_f32_16x16x32_bf16 v[194:197], v[22:25], v[34:37], v[78:81]
	v_mfma_f32_16x16x32_bf16 v[198:201], v[26:29], v[34:37], v[66:69]
	v_mfma_f32_16x16x32_bf16 v[202:205], v[30:33], v[34:37], v[54:57]
	ds_read_b128 v[34:37], v0 offset:25728
	s_waitcnt lgkmcnt(0)
	v_mfma_f32_16x16x32_bf16 v[66:69], v[18:21], v[34:37], v[106:109]
	v_mfma_f32_16x16x32_bf16 v[74:77], v[22:25], v[34:37], v[94:97]
	v_mfma_f32_16x16x32_bf16 v[78:81], v[26:29], v[34:37], v[82:85]
	v_mfma_f32_16x16x32_bf16 v[190:193], v[30:33], v[34:37], v[70:73]
	ds_read_b128 v[34:37], v0 offset:34176
	s_waitcnt lgkmcnt(0)
	v_mfma_f32_16x16x32_bf16 v[174:177], v[18:21], v[34:37], v[122:125]
	ds_read_b128 v[70:73], v0 offset:8896
	v_mfma_f32_16x16x32_bf16 v[178:181], v[22:25], v[34:37], v[110:113]
	v_mfma_f32_16x16x32_bf16 v[182:185], v[26:29], v[34:37], v[98:101]
	v_mfma_f32_16x16x32_bf16 v[186:189], v[30:33], v[34:37], v[86:89]
	ds_read_b128 v[34:37], v0 offset:42624
	v_mfma_f32_16x16x32_bf16 v[58:61], v[18:21], v[162:165], v[58:61]
	v_mfma_f32_16x16x32_bf16 v[238:241], v[22:25], v[162:165], v[46:49]
	v_mfma_f32_16x16x32_bf16 v[242:245], v[26:29], v[162:165], v[38:41]
	s_waitcnt lgkmcnt(0)
	v_mfma_f32_16x16x32_bf16 v[134:137], v[18:21], v[34:37], v[134:137]
	v_mfma_f32_16x16x32_bf16 v[162:165], v[22:25], v[34:37], v[126:129]
	v_mfma_f32_16x16x32_bf16 v[166:169], v[26:29], v[34:37], v[114:117]
	v_mfma_f32_16x16x32_bf16 v[170:173], v[30:33], v[34:37], v[102:105]
	ds_read_b128 v[34:37], v0 offset:51072
	v_mfma_f32_16x16x32_bf16 v[98:101], v[14:17], v[50:53], v[58:61]
	v_mfma_f32_16x16x32_bf16 v[102:105], v[10:13], v[50:53], v[238:241]
	v_mfma_f32_16x16x32_bf16 v[106:109], v[6:9], v[50:53], v[242:245]
	v_mfma_f32_16x16x32_bf16 v[110:113], v[2:5], v[50:53], v[246:249]
	v_mfma_f32_16x16x32_bf16 v[50:53], v[14:17], v[70:73], v[208:211]
	v_mfma_f32_16x16x32_bf16 v[54:57], v[10:13], v[70:73], v[62:65]
	v_mfma_f32_16x16x32_bf16 v[58:61], v[6:9], v[70:73], v[234:237]
	v_mfma_f32_16x16x32_bf16 v[62:65], v[2:5], v[70:73], v[230:233]
	ds_read_b128 v[70:73], v0 offset:17344
	s_waitcnt lgkmcnt(1)
	v_mfma_f32_16x16x32_bf16 v[114:117], v[18:21], v[34:37], v[142:145]
	v_mfma_f32_16x16x32_bf16 v[122:125], v[22:25], v[34:37], v[138:141]
	s_nop 1
	ds_read_b128 v[142:145], v0 offset:42688
	v_mfma_f32_16x16x32_bf16 v[126:129], v[26:29], v[34:37], v[130:133]
	v_mfma_f32_16x16x32_bf16 v[118:121], v[30:33], v[34:37], v[118:121]
	ds_read_b128 v[34:37], v0 offset:59520
	s_nop 0
	ds_read_b128 v[130:133], v0 offset:25792
	s_waitcnt lgkmcnt(1)
	v_mfma_f32_16x16x32_bf16 v[46:49], v[18:21], v[34:37], v[150:153]
	global_load_dwordx4 v[18:21], v[218:219], off
	v_mfma_f32_16x16x32_bf16 v[42:45], v[22:25], v[34:37], v[154:157]
	global_load_dwordx4 v[22:25], v[220:221], off
	v_mfma_f32_16x16x32_bf16 v[38:41], v[26:29], v[34:37], v[158:161]
	global_load_dwordx4 v[26:29], v[222:223], off
	v_mfma_f32_16x16x32_bf16 v[34:37], v[30:33], v[34:37], v[146:149]
	global_load_dwordx4 v[30:33], v[224:225], off
	v_mfma_f32_16x16x32_bf16 v[82:85], v[14:17], v[70:73], v[90:93]
	v_mfma_f32_16x16x32_bf16 v[86:89], v[10:13], v[70:73], v[194:197]
	v_mfma_f32_16x16x32_bf16 v[90:93], v[6:9], v[70:73], v[198:201]
	v_mfma_f32_16x16x32_bf16 v[94:97], v[2:5], v[70:73], v[202:205]
	s_waitcnt lgkmcnt(0)
	v_mfma_f32_16x16x32_bf16 v[66:69], v[14:17], v[130:133], v[66:69]
	v_mfma_f32_16x16x32_bf16 v[70:73], v[10:13], v[130:133], v[74:77]
	v_mfma_f32_16x16x32_bf16 v[74:77], v[6:9], v[130:133], v[78:81]
	v_mfma_f32_16x16x32_bf16 v[78:81], v[2:5], v[130:133], v[190:193]
	ds_read_b128 v[130:133], v0 offset:34240
	s_waitcnt lgkmcnt(0)
	v_mfma_f32_16x16x32_bf16 v[146:149], v[14:17], v[130:133], v[174:177]
	s_nop 2
	ds_read_b128 v[174:177], v0 offset:51136
	v_mfma_f32_16x16x32_bf16 v[150:153], v[10:13], v[130:133], v[178:181]
	v_mfma_f32_16x16x32_bf16 v[154:157], v[6:9], v[130:133], v[182:185]
	v_mfma_f32_16x16x32_bf16 v[158:161], v[2:5], v[130:133], v[186:189]
	v_mfma_f32_16x16x32_bf16 v[130:133], v[14:17], v[142:145], v[134:137]
	v_mfma_f32_16x16x32_bf16 v[134:137], v[10:13], v[142:145], v[162:165]
	s_waitcnt lgkmcnt(0)
	v_mfma_f32_16x16x32_bf16 v[162:165], v[14:17], v[174:177], v[114:117]
	s_nop 2
	ds_read_b128 v[114:117], v0 offset:59584
	v_mfma_f32_16x16x32_bf16 v[138:141], v[6:9], v[142:145], v[166:169]
	v_add_u32_e32 v0, s1, v214
	v_mad_u32_u24 v178, v217, s0, v0
	v_mfma_f32_16x16x32_bf16 v[142:145], v[2:5], v[142:145], v[170:173]
	v_mfma_f32_16x16x32_bf16 v[166:169], v[10:13], v[174:177], v[122:125]
	v_mfma_f32_16x16x32_bf16 v[170:173], v[6:9], v[174:177], v[126:129]
	v_mfma_f32_16x16x32_bf16 v[174:177], v[2:5], v[174:177], v[118:121]
	s_waitcnt lgkmcnt(0)
	v_mfma_f32_16x16x32_bf16 v[46:49], v[14:17], v[114:117], v[46:49]
	v_mfma_f32_16x16x32_bf16 v[42:45], v[10:13], v[114:117], v[42:45]
	v_mfma_f32_16x16x32_bf16 v[38:41], v[6:9], v[114:117], v[38:41]
	v_mfma_f32_16x16x32_bf16 v[34:37], v[2:5], v[114:117], v[34:37]
	global_load_dwordx4 v[2:5], v[218:219], off offset:64
	global_load_dwordx4 v[6:9], v[220:221], off offset:64
	global_load_dwordx4 v[10:13], v[222:223], off offset:64
	global_load_dwordx4 v[14:17], v[224:225], off offset:64
	ds_read_b128 v[114:117], v178
	s_waitcnt vmcnt(0) lgkmcnt(0)
	v_mfma_f32_16x16x32_bf16 v[126:129], v[18:21], v[114:117], v[98:101]
	s_nop 2
	ds_read_b128 v[98:101], v178 offset:4352
	v_mfma_f32_16x16x32_bf16 v[122:125], v[22:25], v[114:117], v[102:105]
	v_mfma_f32_16x16x32_bf16 v[118:121], v[26:29], v[114:117], v[106:109]
	v_mfma_f32_16x16x32_bf16 v[114:117], v[30:33], v[114:117], v[110:113]
	s_waitcnt lgkmcnt(0)
	v_mfma_f32_16x16x32_bf16 v[110:113], v[18:21], v[98:101], v[50:53]
	s_nop 2
	v_mov_b32_e32 v50, 0x2200
	v_mad_u32_u24 v186, v217, s0, v50
	v_add_u32_e32 v50, v0, v186
	ds_read_b128 v[50:53], v50
	v_mfma_f32_16x16x32_bf16 v[106:109], v[22:25], v[98:101], v[54:57]
	s_waitcnt lgkmcnt(0)
	v_mfma_f32_16x16x32_bf16 v[54:57], v[18:21], v[50:53], v[82:85]
	s_nop 2
	v_mov_b32_e32 v82, 0x3300
	v_mad_u32_u24 v187, v217, s0, v82
	v_add_u32_e32 v82, v0, v187
	ds_read_b128 v[82:85], v82
	v_mfma_f32_16x16x32_bf16 v[102:105], v[26:29], v[98:101], v[58:61]
	s_waitcnt lgkmcnt(0)
	v_mfma_f32_16x16x32_bf16 v[178:181], v[26:29], v[82:85], v[74:77]
	s_nop 2
	v_mov_b32_e32 v74, 0x4400
	v_mad_u32_u24 v188, v217, s0, v74
	v_add_u32_e32 v74, v0, v188
	ds_read_b128 v[74:77], v74
	v_mfma_f32_16x16x32_bf16 v[98:101], v[30:33], v[98:101], v[62:65]
	s_waitcnt lgkmcnt(0)
	v_mfma_f32_16x16x32_bf16 v[146:149], v[18:21], v[74:77], v[146:149]
	v_mfma_f32_16x16x32_bf16 v[150:153], v[22:25], v[74:77], v[150:153]
	v_mfma_f32_16x16x32_bf16 v[154:157], v[26:29], v[74:77], v[154:157]
	v_mfma_f32_16x16x32_bf16 v[158:161], v[30:33], v[74:77], v[158:161]
	v_mov_b32_e32 v74, 0x5500
	v_mad_u32_u24 v189, v217, s0, v74
	v_add_u32_e32 v74, v0, v189
	ds_read_b128 v[74:77], v74
	v_mfma_f32_16x16x32_bf16 v[58:61], v[22:25], v[50:53], v[86:89]
	s_waitcnt lgkmcnt(0)
	v_mfma_f32_16x16x32_bf16 v[130:133], v[18:21], v[74:77], v[130:133]
	v_mfma_f32_16x16x32_bf16 v[134:137], v[22:25], v[74:77], v[134:137]
	v_mfma_f32_16x16x32_bf16 v[138:141], v[26:29], v[74:77], v[138:141]
	v_mfma_f32_16x16x32_bf16 v[142:145], v[30:33], v[74:77], v[142:145]
	v_mov_b32_e32 v74, 0x6600
	v_mad_u32_u24 v190, v217, s0, v74
	v_add_u32_e32 v74, v0, v190
	ds_read_b128 v[74:77], v74
	v_mfma_f32_16x16x32_bf16 v[62:65], v[26:29], v[50:53], v[90:93]
	s_waitcnt lgkmcnt(0)
	v_mfma_f32_16x16x32_bf16 v[162:165], v[18:21], v[74:77], v[162:165]
	v_mfma_f32_16x16x32_bf16 v[166:169], v[22:25], v[74:77], v[166:169]
	v_mfma_f32_16x16x32_bf16 v[170:173], v[26:29], v[74:77], v[170:173]
	v_mfma_f32_16x16x32_bf16 v[174:177], v[30:33], v[74:77], v[174:177]
	v_mov_b32_e32 v74, 0x7700
	v_mad_u32_u24 v191, v217, s0, v74
	v_add_u32_e32 v0, v0, v191
	ds_read_b128 v[74:77], v0
	v_add3_u32 v0, s1, v186, v214
	v_mfma_f32_16x16x32_bf16 v[50:53], v[30:33], v[50:53], v[94:97]
	v_readlane_b32 s0, v255, 39
	v_mfma_f32_16x16x32_bf16 v[66:69], v[18:21], v[82:85], v[66:69]
	v_mfma_f32_16x16x32_bf16 v[70:73], v[22:25], v[82:85], v[70:73]
	v_mfma_f32_16x16x32_bf16 v[182:185], v[30:33], v[82:85], v[78:81]
	s_waitcnt lgkmcnt(0)
	v_mfma_f32_16x16x32_bf16 v[46:49], v[18:21], v[74:77], v[46:49]
	v_mfma_f32_16x16x32_bf16 v[42:45], v[22:25], v[74:77], v[42:45]
	v_mfma_f32_16x16x32_bf16 v[38:41], v[26:29], v[74:77], v[38:41]
	v_mfma_f32_16x16x32_bf16 v[34:37], v[30:33], v[74:77], v[34:37]
	global_load_dwordx4 v[18:21], v[218:219], off offset:128
	global_load_dwordx4 v[22:25], v[220:221], off offset:128
	global_load_dwordx4 v[26:29], v[222:223], off offset:128
	global_load_dwordx4 v[30:33], v[224:225], off offset:128
	ds_read_b128 v[74:77], v0 offset:64
	v_add3_u32 v0, s1, v187, v214
	s_waitcnt lgkmcnt(0)
	v_mfma_f32_16x16x32_bf16 v[82:85], v[14:17], v[74:77], v[50:53]
	s_nop 2
	ds_read_b128 v[50:53], v0 offset:64
	v_add3_u32 v0, s1, v188, v214
	s_waitcnt lgkmcnt(0)
	v_mfma_f32_16x16x32_bf16 v[78:81], v[2:5], v[50:53], v[66:69]
	v_mfma_f32_16x16x32_bf16 v[66:69], v[14:17], v[50:53], v[182:185]
	s_nop 2
	v_add3_u32 v182, s1, v189, v214
	v_mfma_f32_16x16x32_bf16 v[94:97], v[2:5], v[74:77], v[54:57]
	v_add3_u32 v183, s1, v190, v214
	v_add3_u32 v184, s1, v191, v214
	v_mfma_f32_16x16x32_bf16 v[90:93], v[6:9], v[74:77], v[58:61]
	v_mfma_f32_16x16x32_bf16 v[86:89], v[10:13], v[74:77], v[62:65]
	v_mfma_f32_16x16x32_bf16 v[74:77], v[6:9], v[50:53], v[70:73]
	s_nop 1
	ds_read_b128 v[62:65], v182 offset:64
	v_mfma_f32_16x16x32_bf16 v[70:73], v[10:13], v[50:53], v[178:181]
	ds_read_b128 v[50:53], v0 offset:64
	s_waitcnt lgkmcnt(0)
	v_mfma_f32_16x16x32_bf16 v[54:57], v[2:5], v[50:53], v[146:149]
	v_mfma_f32_16x16x32_bf16 v[58:61], v[6:9], v[50:53], v[150:153]
	v_mfma_f32_16x16x32_bf16 v[146:149], v[10:13], v[50:53], v[154:157]
	v_mfma_f32_16x16x32_bf16 v[150:153], v[2:5], v[62:65], v[130:133]
	v_mfma_f32_16x16x32_bf16 v[154:157], v[6:9], v[62:65], v[134:137]
	v_mfma_f32_16x16x32_bf16 v[138:141], v[10:13], v[62:65], v[138:141]
	v_mfma_f32_16x16x32_bf16 v[142:145], v[14:17], v[62:65], v[142:145]
	ds_read_b128 v[62:65], v183 offset:64
	v_mfma_f32_16x16x32_bf16 v[50:53], v[14:17], v[50:53], v[158:161]
	s_waitcnt lgkmcnt(0)
	v_mfma_f32_16x16x32_bf16 v[158:161], v[2:5], v[62:65], v[162:165]
	v_mfma_f32_16x16x32_bf16 v[162:165], v[6:9], v[62:65], v[166:169]
	v_mfma_f32_16x16x32_bf16 v[166:169], v[10:13], v[62:65], v[170:173]
	v_mfma_f32_16x16x32_bf16 v[170:173], v[14:17], v[62:65], v[174:177]
	ds_read_b128 v[62:65], v184 offset:64
	s_waitcnt lgkmcnt(0)
	v_mfma_f32_16x16x32_bf16 v[174:177], v[2:5], v[62:65], v[46:49]
	v_mfma_f32_16x16x32_bf16 v[178:181], v[6:9], v[62:65], v[42:45]
	global_load_dwordx4 v[2:5], v[218:219], off offset:192
	global_load_dwordx4 v[6:9], v[220:221], off offset:192
	global_load_dwordx4 v[130:133], v[222:223], off offset:192
	global_load_dwordx4 v[134:137], v[224:225], off offset:192
	v_mfma_f32_16x16x32_bf16 v[14:17], v[14:17], v[62:65], v[34:37]
	s_nop 2
	ds_read_b128 v[34:37], v0 offset:128
	v_mfma_f32_16x16x32_bf16 v[10:13], v[10:13], v[62:65], v[38:41]
	v_xor_b32_e32 v0, 16, v228
	s_waitcnt vmcnt(0) lgkmcnt(0)
	v_mfma_f32_16x16x32_bf16 v[62:65], v[18:21], v[34:37], v[54:57]
	v_mfma_f32_16x16x32_bf16 v[58:61], v[22:25], v[34:37], v[58:61]
	v_mfma_f32_16x16x32_bf16 v[54:57], v[26:29], v[34:37], v[146:149]
	v_mfma_f32_16x16x32_bf16 v[50:53], v[30:33], v[34:37], v[50:53]
	ds_read_b128 v[34:37], v182 offset:128
	s_waitcnt lgkmcnt(0)
	v_mfma_f32_16x16x32_bf16 v[42:45], v[22:25], v[34:37], v[154:157]
	s_nop 2
	ds_read_b128 v[154:157], v184 offset:128
	v_mfma_f32_16x16x32_bf16 v[38:41], v[26:29], v[34:37], v[138:141]
	s_nop 2
	ds_read_b128 v[138:141], v183 offset:128
	v_mfma_f32_16x16x32_bf16 v[46:49], v[18:21], v[34:37], v[150:153]
	s_waitcnt lgkmcnt(0)
	v_mfma_f32_16x16x32_bf16 v[150:153], v[26:29], v[138:141], v[166:169]
	v_mfma_f32_16x16x32_bf16 v[166:169], v[26:29], v[154:157], v[10:13]
	s_nop 2
	ds_read_b128 v[10:13], v183 offset:192
	v_mfma_f32_16x16x32_bf16 v[34:37], v[30:33], v[34:37], v[142:145]
	v_mfma_f32_16x16x32_bf16 v[142:145], v[18:21], v[138:141], v[158:161]
	v_mfma_f32_16x16x32_bf16 v[146:149], v[22:25], v[138:141], v[162:165]
	v_mfma_f32_16x16x32_bf16 v[138:141], v[30:33], v[138:141], v[170:173]
	v_mfma_f32_16x16x32_bf16 v[158:161], v[18:21], v[154:157], v[174:177]
	s_waitcnt lgkmcnt(0)
	v_mfma_f32_16x16x32_bf16 v[18:21], v[134:137], v[10:13], v[138:141]
	s_nop 4
	ds_read_b128 v[138:141], v184 offset:192
	v_mfma_f32_16x16x32_bf16 v[162:165], v[22:25], v[154:157], v[178:181]
	v_mfma_f32_16x16x32_bf16 v[154:157], v[30:33], v[154:157], v[14:17]
	v_mfma_f32_16x16x32_bf16 v[30:33], v[2:5], v[10:13], v[142:145]
	v_mfma_f32_16x16x32_bf16 v[26:29], v[6:9], v[10:13], v[146:149]
	v_mfma_f32_16x16x32_bf16 v[22:25], v[130:133], v[10:13], v[150:153]
	s_waitcnt lgkmcnt(0)
	v_mfma_f32_16x16x32_bf16 v[10:13], v[6:9], v[138:141], v[162:165]
	v_mfma_f32_16x16x32_bf16 v[6:9], v[130:133], v[138:141], v[166:169]
	v_and_b32_e32 v130, 64, v228
	v_add_u32_e32 v130, 64, v130
	v_cmp_lt_i32_e32 vcc, v0, v130
	v_xor_b32_e32 v131, 32, v228
	v_lshlrev_b32_e32 v132, 2, v217
	v_cndmask_b32_e32 v0, v228, v0, vcc
	v_cmp_lt_i32_e32 vcc, v131, v130
	v_mul_f32_e32 v133, v129, v129
	v_fmac_f32_e32 v133, v128, v128
	v_cndmask_b32_e32 v130, v228, v131, vcc
	v_lshlrev_b32_e32 v131, 2, v130
	v_lshlrev_b32_e32 v130, 9, v226
	v_add3_u32 v130, s0, v130, v132
	v_mul_f32_e32 v132, v127, v127
	v_fmac_f32_e32 v132, v126, v126
	v_mfma_f32_16x16x32_bf16 v[14:17], v[2:5], v[138:141], v[158:161]
	v_add_f32_e32 v132, v132, v133
	v_mul_f32_e32 v133, v123, v123
	v_fmac_f32_e32 v133, v122, v122
	v_mfma_f32_16x16x32_bf16 v[2:5], v[134:137], v[138:141], v[154:157]
	v_mul_f32_e32 v134, v125, v125
	v_fmac_f32_e32 v134, v124, v124
	v_add_f32_e32 v133, v133, v134
	v_add_f32_e32 v132, v132, v133
	v_mul_f32_e32 v133, v119, v119
	v_mul_f32_e32 v134, v121, v121
	v_fmac_f32_e32 v133, v118, v118
	v_fmac_f32_e32 v134, v120, v120
	v_add_f32_e32 v133, v133, v134
	v_add_f32_e32 v132, v132, v133
	v_mul_f32_e32 v133, v115, v115
	v_mul_f32_e32 v134, v117, v117
	v_fmac_f32_e32 v133, v114, v114
	v_fmac_f32_e32 v134, v116, v116
	v_add_f32_e32 v133, v133, v134
	v_lshlrev_b32_e32 v0, 2, v0
	v_add_f32_e32 v132, v132, v133
	ds_bpermute_b32 v133, v0, v132
	v_cmp_eq_u32_e32 vcc, 0, v252
	s_waitcnt lgkmcnt(0)
	v_add_f32_e32 v132, v132, v133
	ds_bpermute_b32 v133, v131, v132
	s_and_saveexec_b64 s[0:1], vcc
	s_cbranch_execz .LBB0_746
	s_waitcnt lgkmcnt(0)
	v_add_f32_e32 v132, v132, v133
	ds_write_b32 v130, v132

.LBB0_810:
	v_readlane_b32 s0, v254, 28
	v_readlane_b32 s1, v254, 29
	v_readlane_b32 s14, v254, 22
	s_andn2_b64 vcc, exec, s[0:1]
	v_readlane_b32 s15, v254, 23
	s_cbranch_vccnz .LBB0_812
	v_mov_b32_e32 v0, s8
	s_waitcnt vmcnt(0)
	v_add_co_u32_e32 v2, vcc, 0xd0000, v0
	v_mov_b32_e32 v0, s9
	s_waitcnt lgkmcnt(0)
	v_addc_co_u32_e32 v3, vcc, 0, v0, vcc
	global_load_dwordx2 v[2:3], v[2:3], off sc1
	s_waitcnt vmcnt(0) lgkmcnt(0)
	v_readfirstlane_b32 s15, v3
	v_readfirstlane_b32 s14, v2

.LBB0_832:
	v_lshl_or_b32 v188, s2, 8, v202
	v_lshl_add_u32 v192, s6, 8, v200
	v_ashrrev_i32_e32 v189, 31, v188
	v_ashrrev_i32_e32 v193, 31, v192
	v_lshl_add_u64 v[190:191], v[188:189], 2, s[14:15]
	v_lshlrev_b64 v[114:115], 13, v[192:193]
	v_lshl_add_u64 v[114:115], v[190:191], 0, v[114:115]
	global_load_dwordx4 v[208:211], v[114:115], off
	global_load_dwordx4 v[214:217], v[114:115], off offset:16
	global_load_dwordx4 v[218:221], v[114:115], off offset:512
	global_load_dwordx4 v[222:225], v[114:115], off offset:528
	v_or_b32_e32 v198, 16, v192
	v_ashrrev_i32_e32 v199, 31, v198
	v_lshlrev_b64 v[114:115], 13, v[198:199]
	v_or_b32_e32 v196, 32, v192
	v_lshl_add_u64 v[114:115], v[190:191], 0, v[114:115]
	v_ashrrev_i32_e32 v197, 31, v196
	global_load_dwordx4 v[174:177], v[114:115], off
	global_load_dwordx4 v[170:173], v[114:115], off offset:16
	global_load_dwordx4 v[166:169], v[114:115], off offset:512
	global_load_dwordx4 v[162:165], v[114:115], off offset:528
	v_lshlrev_b64 v[114:115], 13, v[196:197]
	v_or_b32_e32 v194, 48, v192
	v_lshl_add_u64 v[114:115], v[190:191], 0, v[114:115]
	v_ashrrev_i32_e32 v195, 31, v194
	global_load_dwordx4 v[154:157], v[114:115], off
	global_load_dwordx4 v[150:153], v[114:115], off offset:16
	global_load_dwordx4 v[134:137], v[114:115], off offset:512
	global_load_dwordx4 v[126:129], v[114:115], off offset:528
	v_lshlrev_b64 v[114:115], 13, v[194:195]
	v_lshl_add_u64 v[114:115], v[190:191], 0, v[114:115]
	global_load_dwordx4 v[142:145], v[114:115], off
	global_load_dwordx4 v[138:141], v[114:115], off offset:16
	global_load_dwordx4 v[118:121], v[114:115], off offset:512
	s_nop 0
	global_load_dwordx4 v[114:117], v[114:115], off offset:528
	v_lshlrev_b64 v[204:205], 11, v[192:193]
	v_readlane_b32 s10, v254, 22
	v_lshl_add_u64 v[204:205], v[204:205], 0, v[188:189]
	v_readlane_b32 s11, v254, 23
	s_waitcnt vmcnt(0) lgkmcnt(0)
	v_pk_add_f32 v[160:161], v[160:161], v[210:211]
	v_pk_add_f32 v[158:159], v[158:159], v[208:209]
	v_mul_f32_e32 v211, v161, v161
	v_mul_f32_e32 v210, v159, v159
	v_pk_add_f32 v[146:147], v[146:147], v[214:215]
	v_fmac_f32_e32 v210, v158, v158
	v_fmac_f32_e32 v211, v160, v160
	v_add_f32_e32 v210, v210, v211
	v_mul_f32_e32 v211, v147, v147
	v_pk_add_f32 v[148:149], v[148:149], v[216:217]
	v_lshl_add_u64 v[208:209], v[204:205], 2, s[10:11]
	v_fmac_f32_e32 v211, v146, v146
	global_store_dwordx4 v[208:209], v[158:161], off
	global_store_dwordx4 v[208:209], v[146:149], off offset:16
	v_add_f32_e32 v210, v210, v211
	v_mul_f32_e32 v211, v149, v149
	v_cvt_pk_bf16_f32 v158, v158, v159
	v_cvt_pk_bf16_f32 v159, v160, v161
	v_cvt_pk_bf16_f32 v160, v146, v147
	v_lshlrev_b64 v[146:147], 1, v[204:205]
	v_fmac_f32_e32 v211, v148, v148
	v_cvt_pk_bf16_f32 v161, v148, v149
	v_lshl_add_u64 v[148:149], s[34:35], 0, v[146:147]
	v_pk_add_f32 v[132:133], v[132:133], v[220:221]
	v_pk_add_f32 v[130:131], v[130:131], v[218:219]
	global_store_dwordx4 v[148:149], v[158:161], off
	v_mul_f32_e32 v148, v131, v131
	v_mul_f32_e32 v149, v133, v133
	v_pk_add_f32 v[122:123], v[122:123], v[222:223]
	v_fmac_f32_e32 v148, v130, v130
	v_fmac_f32_e32 v149, v132, v132
	v_add_f32_e32 v148, v148, v149
	v_mul_f32_e32 v149, v123, v123
	v_or_b32_e32 v146, 0x100, v146
	v_pk_add_f32 v[124:125], v[124:125], v[224:225]
	global_store_dwordx4 v[208:209], v[130:133], off offset:512
	global_store_dwordx4 v[208:209], v[122:125], off offset:528
	v_fmac_f32_e32 v149, v122, v122
	v_cvt_pk_bf16_f32 v130, v130, v131
	v_cvt_pk_bf16_f32 v131, v132, v133
	v_cvt_pk_bf16_f32 v132, v122, v123
	v_cvt_pk_bf16_f32 v133, v124, v125
	s_nop 0
	v_lshl_add_u64 v[122:123], s[34:35], 0, v[146:147]
	global_store_dwordx4 v[122:123], v[130:133], off
	v_and_b32_e32 v123, 64, v228
	v_add_f32_e32 v148, v148, v149
	v_mul_f32_e32 v149, v125, v125
	v_xor_b32_e32 v122, 16, v228
	v_add_u32_e32 v123, 64, v123
	v_fmac_f32_e32 v149, v124, v124
	v_cmp_lt_i32_e32 vcc, v122, v123
	v_add_f32_e32 v210, v211, v210
	v_add_f32_e32 v148, v149, v148
	v_cndmask_b32_e32 v122, v228, v122, vcc
	v_add_f32_e32 v148, v210, v148
	v_lshlrev_b32_e32 v130, 2, v122
	ds_bpermute_b32 v122, v130, v148
	v_xor_b32_e32 v124, 32, v228
	v_cmp_lt_i32_e32 vcc, v124, v123
	s_waitcnt lgkmcnt(0)
	v_add_f32_e32 v122, v148, v122
	v_cndmask_b32_e32 v123, v228, v124, vcc
	v_lshlrev_b32_e32 v131, 2, v123
	ds_bpermute_b32 v123, v131, v122
	s_and_saveexec_b64 s[30:31], s[38:39]
	s_cbranch_execz .LBB0_834
	v_lshl_add_u64 v[124:125], v[192:193], 2, s[4:5]
	s_waitcnt lgkmcnt(0)
	v_add_f32_e32 v122, v122, v123
	global_atomic_add_f32 v[124:125], v122, off
.LBB0_834:
	s_or_b64 exec, exec, s[30:31]
	v_pk_add_f32 v[112:113], v[112:113], v[176:177]
	v_pk_add_f32 v[110:111], v[110:111], v[174:175]
	v_mul_f32_e32 v133, v113, v113
	v_mul_f32_e32 v132, v111, v111
	s_waitcnt lgkmcnt(0)
	v_lshlrev_b64 v[122:123], 11, v[198:199]
	v_pk_add_f32 v[106:107], v[106:107], v[170:171]
	v_fmac_f32_e32 v132, v110, v110
	v_fmac_f32_e32 v133, v112, v112
	v_lshl_add_u64 v[122:123], v[122:123], 0, v[188:189]
	v_add_f32_e32 v132, v132, v133
	v_mul_f32_e32 v133, v107, v107
	v_pk_add_f32 v[108:109], v[108:109], v[172:173]
	v_lshl_add_u64 v[124:125], v[122:123], 2, s[10:11]
	v_fmac_f32_e32 v133, v106, v106
	global_store_dwordx4 v[124:125], v[110:113], off
	global_store_dwordx4 v[124:125], v[106:109], off offset:16
	v_add_f32_e32 v132, v132, v133
	v_mul_f32_e32 v133, v109, v109
	v_cvt_pk_bf16_f32 v110, v110, v111
	v_cvt_pk_bf16_f32 v111, v112, v113
	v_cvt_pk_bf16_f32 v112, v106, v107
	v_lshlrev_b64 v[106:107], 1, v[122:123]
	v_fmac_f32_e32 v133, v108, v108
	v_cvt_pk_bf16_f32 v113, v108, v109
	v_lshl_add_u64 v[108:109], s[34:35], 0, v[106:107]
	v_pk_add_f32 v[104:105], v[104:105], v[168:169]
	v_pk_add_f32 v[102:103], v[102:103], v[166:167]
	global_store_dwordx4 v[108:109], v[110:113], off
	v_mul_f32_e32 v108, v103, v103
	v_mul_f32_e32 v109, v105, v105
	v_pk_add_f32 v[98:99], v[98:99], v[162:163]
	v_fmac_f32_e32 v108, v102, v102
	v_fmac_f32_e32 v109, v104, v104
	v_add_f32_e32 v108, v108, v109
	v_mul_f32_e32 v109, v99, v99
	v_pk_add_f32 v[100:101], v[100:101], v[164:165]
	v_fmac_f32_e32 v109, v98, v98
	v_add_f32_e32 v108, v108, v109
	v_mul_f32_e32 v109, v101, v101
	v_fmac_f32_e32 v109, v100, v100
	v_add_f32_e32 v132, v133, v132
	v_add_f32_e32 v108, v109, v108
	v_add_f32_e32 v108, v132, v108
	ds_bpermute_b32 v109, v130, v108
	global_store_dwordx4 v[124:125], v[102:105], off offset:512
	global_store_dwordx4 v[124:125], v[98:101], off offset:528
	v_or_b32_e32 v106, 0x100, v106
	v_cvt_pk_bf16_f32 v102, v102, v103
	v_cvt_pk_bf16_f32 v103, v104, v105
	v_cvt_pk_bf16_f32 v104, v98, v99
	v_cvt_pk_bf16_f32 v105, v100, v101
	s_waitcnt lgkmcnt(0)
	v_add_f32_e32 v98, v108, v109
	ds_bpermute_b32 v99, v131, v98
	v_lshl_add_u64 v[100:101], s[34:35], 0, v[106:107]
	global_store_dwordx4 v[100:101], v[102:105], off
	s_and_saveexec_b64 s[30:31], s[38:39]
	s_cbranch_execz .LBB0_836
	v_lshl_add_u64 v[100:101], v[198:199], 2, s[4:5]
	s_waitcnt lgkmcnt(0)
	v_add_f32_e32 v98, v98, v99
	global_atomic_add_f32 v[100:101], v98, off
.LBB0_836:
	s_or_b64 exec, exec, s[30:31]
	v_pk_add_f32 v[96:97], v[96:97], v[156:157]
	v_pk_add_f32 v[94:95], v[94:95], v[154:155]
	v_mul_f32_e32 v103, v97, v97
	v_mul_f32_e32 v102, v95, v95
	s_waitcnt lgkmcnt(0)
	v_lshlrev_b64 v[98:99], 11, v[196:197]
	v_pk_add_f32 v[90:91], v[90:91], v[150:151]
	v_fmac_f32_e32 v102, v94, v94
	v_fmac_f32_e32 v103, v96, v96
	v_lshl_add_u64 v[98:99], v[98:99], 0, v[188:189]
	v_add_f32_e32 v102, v102, v103
	v_mul_f32_e32 v103, v91, v91
	v_pk_add_f32 v[92:93], v[92:93], v[152:153]
	v_lshl_add_u64 v[100:101], v[98:99], 2, s[10:11]
	v_fmac_f32_e32 v103, v90, v90
	global_store_dwordx4 v[100:101], v[94:97], off
	global_store_dwordx4 v[100:101], v[90:93], off offset:16
	v_add_f32_e32 v102, v102, v103
	v_mul_f32_e32 v103, v93, v93
	v_cvt_pk_bf16_f32 v94, v94, v95
	v_cvt_pk_bf16_f32 v95, v96, v97
	v_cvt_pk_bf16_f32 v96, v90, v91
	v_lshlrev_b64 v[90:91], 1, v[98:99]
	v_fmac_f32_e32 v103, v92, v92
	v_cvt_pk_bf16_f32 v97, v92, v93
	v_lshl_add_u64 v[92:93], s[34:35], 0, v[90:91]
	v_pk_add_f32 v[88:89], v[88:89], v[136:137]
	v_pk_add_f32 v[86:87], v[86:87], v[134:135]
	global_store_dwordx4 v[92:93], v[94:97], off
	v_mul_f32_e32 v92, v87, v87
	v_mul_f32_e32 v93, v89, v89
	v_pk_add_f32 v[82:83], v[82:83], v[126:127]
	v_fmac_f32_e32 v92, v86, v86
	v_fmac_f32_e32 v93, v88, v88
	v_add_f32_e32 v92, v92, v93
	v_mul_f32_e32 v93, v83, v83
	v_pk_add_f32 v[84:85], v[84:85], v[128:129]
	v_fmac_f32_e32 v93, v82, v82
	v_add_f32_e32 v92, v92, v93
	v_mul_f32_e32 v93, v85, v85
	v_fmac_f32_e32 v93, v84, v84
	v_add_f32_e32 v102, v103, v102
	v_add_f32_e32 v92, v93, v92
	v_add_f32_e32 v92, v102, v92
	ds_bpermute_b32 v93, v130, v92
	global_store_dwordx4 v[100:101], v[86:89], off offset:512
	global_store_dwordx4 v[100:101], v[82:85], off offset:528
	v_or_b32_e32 v90, 0x100, v90
	v_cvt_pk_bf16_f32 v86, v86, v87
	v_cvt_pk_bf16_f32 v87, v88, v89
	v_cvt_pk_bf16_f32 v88, v82, v83
	v_cvt_pk_bf16_f32 v89, v84, v85
	s_waitcnt lgkmcnt(0)
	v_add_f32_e32 v82, v92, v93
	ds_bpermute_b32 v83, v131, v82
	v_lshl_add_u64 v[84:85], s[34:35], 0, v[90:91]
	global_store_dwordx4 v[84:85], v[86:89], off
	s_and_saveexec_b64 s[30:31], s[38:39]
	s_cbranch_execz .LBB0_838
	v_lshl_add_u64 v[84:85], v[196:197], 2, s[4:5]
	s_waitcnt lgkmcnt(0)
	v_add_f32_e32 v82, v82, v83
	global_atomic_add_f32 v[84:85], v82, off
.LBB0_838:
	s_or_b64 exec, exec, s[30:31]
	v_pk_add_f32 v[80:81], v[80:81], v[144:145]
	v_pk_add_f32 v[78:79], v[78:79], v[142:143]
	v_mul_f32_e32 v87, v81, v81
	v_mul_f32_e32 v86, v79, v79
	s_waitcnt lgkmcnt(0)
	v_lshlrev_b64 v[82:83], 11, v[194:195]
	v_pk_add_f32 v[74:75], v[74:75], v[138:139]
	v_fmac_f32_e32 v86, v78, v78
	v_fmac_f32_e32 v87, v80, v80
	v_lshl_add_u64 v[82:83], v[82:83], 0, v[188:189]
	v_add_f32_e32 v86, v86, v87
	v_mul_f32_e32 v87, v75, v75
	v_pk_add_f32 v[76:77], v[76:77], v[140:141]
	v_lshl_add_u64 v[84:85], v[82:83], 2, s[10:11]
	v_fmac_f32_e32 v87, v74, v74
	global_store_dwordx4 v[84:85], v[78:81], off
	global_store_dwordx4 v[84:85], v[74:77], off offset:16
	v_add_f32_e32 v86, v86, v87
	v_mul_f32_e32 v87, v77, v77
	v_cvt_pk_bf16_f32 v78, v78, v79
	v_cvt_pk_bf16_f32 v79, v80, v81
	v_cvt_pk_bf16_f32 v80, v74, v75
	v_lshlrev_b64 v[74:75], 1, v[82:83]
	v_fmac_f32_e32 v87, v76, v76
	v_cvt_pk_bf16_f32 v81, v76, v77
	v_lshl_add_u64 v[76:77], s[34:35], 0, v[74:75]
	v_pk_add_f32 v[72:73], v[72:73], v[120:121]
	v_pk_add_f32 v[70:71], v[70:71], v[118:119]
	global_store_dwordx4 v[76:77], v[78:81], off
	v_mul_f32_e32 v76, v71, v71
	v_mul_f32_e32 v77, v73, v73
	v_pk_add_f32 v[66:67], v[66:67], v[114:115]
	v_fmac_f32_e32 v76, v70, v70
	v_fmac_f32_e32 v77, v72, v72
	v_add_f32_e32 v76, v76, v77
	v_mul_f32_e32 v77, v67, v67
	v_pk_add_f32 v[68:69], v[68:69], v[116:117]
	v_fmac_f32_e32 v77, v66, v66
	v_add_f32_e32 v76, v76, v77
	v_mul_f32_e32 v77, v69, v69
	v_fmac_f32_e32 v77, v68, v68
	v_add_f32_e32 v86, v87, v86
	v_add_f32_e32 v76, v77, v76
	v_add_f32_e32 v76, v86, v76
	ds_bpermute_b32 v77, v130, v76
	global_store_dwordx4 v[84:85], v[70:73], off offset:512
	global_store_dwordx4 v[84:85], v[66:69], off offset:528
	v_or_b32_e32 v74, 0x100, v74
	v_cvt_pk_bf16_f32 v70, v70, v71
	v_cvt_pk_bf16_f32 v71, v72, v73
	v_cvt_pk_bf16_f32 v72, v66, v67
	v_cvt_pk_bf16_f32 v73, v68, v69
	s_waitcnt lgkmcnt(0)
	v_add_f32_e32 v66, v76, v77
	ds_bpermute_b32 v67, v131, v66
	v_lshl_add_u64 v[68:69], s[34:35], 0, v[74:75]
	global_store_dwordx4 v[68:69], v[70:73], off
	s_and_saveexec_b64 s[30:31], s[38:39]
	s_cbranch_execz .LBB0_840
	v_lshl_add_u64 v[68:69], v[194:195], 2, s[4:5]
	s_waitcnt lgkmcnt(0)
	v_add_f32_e32 v66, v66, v67
	global_atomic_add_f32 v[68:69], v66, off
.LBB0_840:
	s_or_b64 exec, exec, s[30:31]
	v_add_u32_e32 v128, 0x80, v192
	v_ashrrev_i32_e32 v129, 31, v128
	s_waitcnt lgkmcnt(0)
	v_lshlrev_b64 v[66:67], 13, v[128:129]
	v_lshl_add_u64 v[66:67], v[190:191], 0, v[66:67]
	global_load_dwordx4 v[132:135], v[66:67], off
	global_load_dwordx4 v[136:139], v[66:67], off offset:16
	global_load_dwordx4 v[118:121], v[66:67], off offset:512
	global_load_dwordx4 v[114:117], v[66:67], off offset:528
	v_add_u32_e32 v126, 0x90, v192
	v_ashrrev_i32_e32 v127, 31, v126
	v_lshlrev_b64 v[66:67], 13, v[126:127]
	v_add_u32_e32 v124, 0xa0, v192
	v_lshl_add_u64 v[66:67], v[190:191], 0, v[66:67]
	v_ashrrev_i32_e32 v125, 31, v124
	global_load_dwordx4 v[110:113], v[66:67], off
	global_load_dwordx4 v[106:109], v[66:67], off offset:16
	global_load_dwordx4 v[102:105], v[66:67], off offset:512
	global_load_dwordx4 v[98:101], v[66:67], off offset:528
	v_lshlrev_b64 v[66:67], 13, v[124:125]
	v_add_u32_e32 v122, 0xb0, v192
	v_lshl_add_u64 v[66:67], v[190:191], 0, v[66:67]
	v_ashrrev_i32_e32 v123, 31, v122
	global_load_dwordx4 v[94:97], v[66:67], off
	global_load_dwordx4 v[90:93], v[66:67], off offset:16
	global_load_dwordx4 v[78:81], v[66:67], off offset:512
	global_load_dwordx4 v[74:77], v[66:67], off offset:528
	v_lshlrev_b64 v[66:67], 13, v[122:123]
	v_lshl_add_u64 v[66:67], v[190:191], 0, v[66:67]
	global_load_dwordx4 v[86:89], v[66:67], off
	global_load_dwordx4 v[82:85], v[66:67], off offset:16
	global_load_dwordx4 v[70:73], v[66:67], off offset:512
	s_nop 0
	global_load_dwordx4 v[66:69], v[66:67], off offset:528
	v_lshlrev_b64 v[140:141], 11, v[128:129]
	v_lshl_add_u64 v[140:141], v[140:141], 0, v[188:189]
	s_waitcnt vmcnt(0) lgkmcnt(0)
	v_pk_add_f32 v[64:65], v[64:65], v[134:135]
	v_pk_add_f32 v[62:63], v[62:63], v[132:133]
	v_mul_f32_e32 v135, v65, v65
	v_mul_f32_e32 v134, v63, v63
	v_pk_add_f32 v[58:59], v[58:59], v[136:137]
	v_fmac_f32_e32 v134, v62, v62
	v_fmac_f32_e32 v135, v64, v64
	v_add_f32_e32 v134, v134, v135
	v_mul_f32_e32 v135, v59, v59
	v_pk_add_f32 v[60:61], v[60:61], v[138:139]
	v_lshl_add_u64 v[132:133], v[140:141], 2, s[10:11]
	v_fmac_f32_e32 v135, v58, v58
	global_store_dwordx4 v[132:133], v[62:65], off
	global_store_dwordx4 v[132:133], v[58:61], off offset:16
	v_add_f32_e32 v134, v134, v135
	v_mul_f32_e32 v135, v61, v61
	v_cvt_pk_bf16_f32 v62, v62, v63
	v_cvt_pk_bf16_f32 v63, v64, v65
	v_cvt_pk_bf16_f32 v64, v58, v59
	v_lshlrev_b64 v[58:59], 1, v[140:141]
	v_fmac_f32_e32 v135, v60, v60
	v_cvt_pk_bf16_f32 v65, v60, v61
	v_lshl_add_u64 v[60:61], s[34:35], 0, v[58:59]
	v_pk_add_f32 v[56:57], v[56:57], v[120:121]
	v_pk_add_f32 v[54:55], v[54:55], v[118:119]
	global_store_dwordx4 v[60:61], v[62:65], off
	v_mul_f32_e32 v60, v55, v55
	v_mul_f32_e32 v61, v57, v57
	v_pk_add_f32 v[50:51], v[50:51], v[114:115]
	v_fmac_f32_e32 v60, v54, v54
	v_fmac_f32_e32 v61, v56, v56
	v_add_f32_e32 v60, v60, v61
	v_mul_f32_e32 v61, v51, v51
	v_pk_add_f32 v[52:53], v[52:53], v[116:117]
	v_fmac_f32_e32 v61, v50, v50
	v_add_f32_e32 v60, v60, v61
	v_mul_f32_e32 v61, v53, v53
	v_fmac_f32_e32 v61, v52, v52
	v_add_f32_e32 v134, v135, v134
	v_add_f32_e32 v60, v61, v60
	v_or_b32_e32 v58, 0x100, v58
	global_store_dwordx4 v[132:133], v[54:57], off offset:512
	global_store_dwordx4 v[132:133], v[50:53], off offset:528
	v_add_f32_e32 v60, v134, v60
	v_cvt_pk_bf16_f32 v54, v54, v55
	v_cvt_pk_bf16_f32 v55, v56, v57
	v_cvt_pk_bf16_f32 v56, v50, v51
	v_cvt_pk_bf16_f32 v57, v52, v53
	s_nop 0
	v_lshl_add_u64 v[50:51], s[34:35], 0, v[58:59]
	global_store_dwordx4 v[50:51], v[54:57], off
	ds_bpermute_b32 v50, v130, v60
	s_waitcnt lgkmcnt(0)
	v_add_f32_e32 v50, v60, v50
	ds_bpermute_b32 v51, v131, v50
	s_and_saveexec_b64 s[30:31], s[38:39]
	s_cbranch_execz .LBB0_842
	v_lshl_add_u64 v[52:53], v[128:129], 2, s[4:5]
	s_waitcnt lgkmcnt(0)
	v_add_f32_e32 v50, v50, v51
	global_atomic_add_f32 v[52:53], v50, off
.LBB0_842:
	s_or_b64 exec, exec, s[30:31]
	v_pk_add_f32 v[48:49], v[48:49], v[112:113]
	v_pk_add_f32 v[46:47], v[46:47], v[110:111]
	v_mul_f32_e32 v55, v49, v49
	v_mul_f32_e32 v54, v47, v47
	s_waitcnt lgkmcnt(0)
	v_lshlrev_b64 v[50:51], 11, v[126:127]
	v_pk_add_f32 v[42:43], v[42:43], v[106:107]
	v_fmac_f32_e32 v54, v46, v46
	v_fmac_f32_e32 v55, v48, v48
	v_lshl_add_u64 v[50:51], v[50:51], 0, v[188:189]
	v_add_f32_e32 v54, v54, v55
	v_mul_f32_e32 v55, v43, v43
	v_pk_add_f32 v[44:45], v[44:45], v[108:109]
	v_lshl_add_u64 v[52:53], v[50:51], 2, s[10:11]
	v_fmac_f32_e32 v55, v42, v42
	global_store_dwordx4 v[52:53], v[46:49], off
	global_store_dwordx4 v[52:53], v[42:45], off offset:16
	v_add_f32_e32 v54, v54, v55
	v_mul_f32_e32 v55, v45, v45
	v_cvt_pk_bf16_f32 v46, v46, v47
	v_cvt_pk_bf16_f32 v47, v48, v49
	v_cvt_pk_bf16_f32 v48, v42, v43
	v_lshlrev_b64 v[42:43], 1, v[50:51]
	v_fmac_f32_e32 v55, v44, v44
	v_cvt_pk_bf16_f32 v49, v44, v45
	v_lshl_add_u64 v[44:45], s[34:35], 0, v[42:43]
	v_pk_add_f32 v[40:41], v[40:41], v[104:105]
	v_pk_add_f32 v[38:39], v[38:39], v[102:103]
	global_store_dwordx4 v[44:45], v[46:49], off
	v_mul_f32_e32 v44, v39, v39
	v_mul_f32_e32 v45, v41, v41
	v_pk_add_f32 v[34:35], v[34:35], v[98:99]
	v_fmac_f32_e32 v44, v38, v38
	v_fmac_f32_e32 v45, v40, v40
	v_add_f32_e32 v44, v44, v45
	v_mul_f32_e32 v45, v35, v35
	v_pk_add_f32 v[36:37], v[36:37], v[100:101]
	v_fmac_f32_e32 v45, v34, v34
	v_add_f32_e32 v44, v44, v45
	v_mul_f32_e32 v45, v37, v37
	v_fmac_f32_e32 v45, v36, v36
	v_add_f32_e32 v54, v55, v54
	v_add_f32_e32 v44, v45, v44
	v_add_f32_e32 v44, v54, v44
	ds_bpermute_b32 v45, v130, v44
	global_store_dwordx4 v[52:53], v[38:41], off offset:512
	global_store_dwordx4 v[52:53], v[34:37], off offset:528
	v_or_b32_e32 v42, 0x100, v42
	v_cvt_pk_bf16_f32 v38, v38, v39
	v_cvt_pk_bf16_f32 v39, v40, v41
	v_cvt_pk_bf16_f32 v40, v34, v35
	v_cvt_pk_bf16_f32 v41, v36, v37
	s_waitcnt lgkmcnt(0)
	v_add_f32_e32 v34, v44, v45
	ds_bpermute_b32 v35, v131, v34
	v_lshl_add_u64 v[36:37], s[34:35], 0, v[42:43]
	global_store_dwordx4 v[36:37], v[38:41], off
	s_and_saveexec_b64 s[30:31], s[38:39]
	s_cbranch_execz .LBB0_844
	v_lshl_add_u64 v[36:37], v[126:127], 2, s[4:5]
	s_waitcnt lgkmcnt(0)
	v_add_f32_e32 v34, v34, v35
	global_atomic_add_f32 v[36:37], v34, off
.LBB0_844:
	s_or_b64 exec, exec, s[30:31]
	v_pk_add_f32 v[32:33], v[32:33], v[96:97]
	v_pk_add_f32 v[30:31], v[30:31], v[94:95]
	v_mul_f32_e32 v39, v33, v33
	v_mul_f32_e32 v38, v31, v31
	s_waitcnt lgkmcnt(0)
	v_lshlrev_b64 v[34:35], 11, v[124:125]
	v_pk_add_f32 v[26:27], v[26:27], v[90:91]
	v_fmac_f32_e32 v38, v30, v30
	v_fmac_f32_e32 v39, v32, v32
	v_lshl_add_u64 v[34:35], v[34:35], 0, v[188:189]
	v_add_f32_e32 v38, v38, v39
	v_mul_f32_e32 v39, v27, v27
	v_pk_add_f32 v[28:29], v[28:29], v[92:93]
	v_lshl_add_u64 v[36:37], v[34:35], 2, s[10:11]
	v_fmac_f32_e32 v39, v26, v26
	global_store_dwordx4 v[36:37], v[30:33], off
	global_store_dwordx4 v[36:37], v[26:29], off offset:16
	v_add_f32_e32 v38, v38, v39
	v_mul_f32_e32 v39, v29, v29
	v_cvt_pk_bf16_f32 v30, v30, v31
	v_cvt_pk_bf16_f32 v31, v32, v33
	v_cvt_pk_bf16_f32 v32, v26, v27
	v_lshlrev_b64 v[26:27], 1, v[34:35]
	v_fmac_f32_e32 v39, v28, v28
	v_cvt_pk_bf16_f32 v33, v28, v29
	v_lshl_add_u64 v[28:29], s[34:35], 0, v[26:27]
	v_pk_add_f32 v[24:25], v[24:25], v[80:81]
	v_pk_add_f32 v[22:23], v[22:23], v[78:79]
	global_store_dwordx4 v[28:29], v[30:33], off
	v_mul_f32_e32 v28, v23, v23
	v_mul_f32_e32 v29, v25, v25
	v_pk_add_f32 v[18:19], v[18:19], v[74:75]
	v_fmac_f32_e32 v28, v22, v22
	v_fmac_f32_e32 v29, v24, v24
	v_add_f32_e32 v28, v28, v29
	v_mul_f32_e32 v29, v19, v19
	v_pk_add_f32 v[20:21], v[20:21], v[76:77]
	v_fmac_f32_e32 v29, v18, v18
	v_add_f32_e32 v28, v28, v29
	v_mul_f32_e32 v29, v21, v21
	v_fmac_f32_e32 v29, v20, v20
	v_add_f32_e32 v38, v39, v38
	v_add_f32_e32 v28, v29, v28
	v_add_f32_e32 v28, v38, v28
	ds_bpermute_b32 v29, v130, v28
	global_store_dwordx4 v[36:37], v[22:25], off offset:512
	global_store_dwordx4 v[36:37], v[18:21], off offset:528
	v_or_b32_e32 v26, 0x100, v26
	v_cvt_pk_bf16_f32 v22, v22, v23
	v_cvt_pk_bf16_f32 v23, v24, v25
	v_cvt_pk_bf16_f32 v24, v18, v19
	v_cvt_pk_bf16_f32 v25, v20, v21
	s_waitcnt lgkmcnt(0)
	v_add_f32_e32 v18, v28, v29
	ds_bpermute_b32 v19, v131, v18
	v_lshl_add_u64 v[20:21], s[34:35], 0, v[26:27]
	global_store_dwordx4 v[20:21], v[22:25], off
	s_and_saveexec_b64 s[30:31], s[38:39]
	s_cbranch_execz .LBB0_846
	v_lshl_add_u64 v[20:21], v[124:125], 2, s[4:5]
	s_waitcnt lgkmcnt(0)
	v_add_f32_e32 v18, v18, v19
	global_atomic_add_f32 v[20:21], v18, off
.LBB0_846:
	s_or_b64 exec, exec, s[30:31]
	v_pk_add_f32 v[16:17], v[16:17], v[88:89]
	v_pk_add_f32 v[14:15], v[14:15], v[86:87]
	v_mul_f32_e32 v23, v17, v17
	v_mul_f32_e32 v22, v15, v15
	s_waitcnt lgkmcnt(0)
	v_lshlrev_b64 v[18:19], 11, v[122:123]
	v_pk_add_f32 v[10:11], v[10:11], v[82:83]
	v_fmac_f32_e32 v22, v14, v14
	v_fmac_f32_e32 v23, v16, v16
	v_lshl_add_u64 v[18:19], v[18:19], 0, v[188:189]
	v_add_f32_e32 v22, v22, v23
	v_mul_f32_e32 v23, v11, v11
	v_pk_add_f32 v[12:13], v[12:13], v[84:85]
	v_lshl_add_u64 v[20:21], v[18:19], 2, s[10:11]
	v_fmac_f32_e32 v23, v10, v10
	global_store_dwordx4 v[20:21], v[14:17], off
	global_store_dwordx4 v[20:21], v[10:13], off offset:16
	v_add_f32_e32 v22, v22, v23
	v_mul_f32_e32 v23, v13, v13
	v_cvt_pk_bf16_f32 v14, v14, v15
	v_cvt_pk_bf16_f32 v15, v16, v17
	v_cvt_pk_bf16_f32 v16, v10, v11
	v_lshlrev_b64 v[10:11], 1, v[18:19]
	v_fmac_f32_e32 v23, v12, v12
	v_cvt_pk_bf16_f32 v17, v12, v13
	v_lshl_add_u64 v[12:13], s[34:35], 0, v[10:11]
	v_pk_add_f32 v[8:9], v[8:9], v[72:73]
	v_pk_add_f32 v[6:7], v[6:7], v[70:71]
	global_store_dwordx4 v[12:13], v[14:17], off
	v_mul_f32_e32 v12, v7, v7
	v_mul_f32_e32 v13, v9, v9
	v_pk_add_f32 v[2:3], v[2:3], v[66:67]
	v_fmac_f32_e32 v12, v6, v6
	v_fmac_f32_e32 v13, v8, v8
	v_add_f32_e32 v12, v12, v13
	v_mul_f32_e32 v13, v3, v3
	v_pk_add_f32 v[4:5], v[4:5], v[68:69]
	v_fmac_f32_e32 v13, v2, v2
	v_add_f32_e32 v12, v12, v13
	v_mul_f32_e32 v13, v5, v5
	v_fmac_f32_e32 v13, v4, v4
	v_add_f32_e32 v22, v23, v22
	v_add_f32_e32 v12, v13, v12
	v_add_f32_e32 v12, v22, v12
	ds_bpermute_b32 v13, v130, v12
	global_store_dwordx4 v[20:21], v[6:9], off offset:512
	global_store_dwordx4 v[20:21], v[2:5], off offset:528
	v_or_b32_e32 v10, 0x100, v10
	v_cvt_pk_bf16_f32 v6, v6, v7
	v_cvt_pk_bf16_f32 v7, v8, v9
	v_cvt_pk_bf16_f32 v8, v2, v3
	v_cvt_pk_bf16_f32 v9, v4, v5
	s_waitcnt lgkmcnt(0)
	v_add_f32_e32 v2, v12, v13
	ds_bpermute_b32 v3, v131, v2
	v_lshl_add_u64 v[4:5], s[34:35], 0, v[10:11]
	global_store_dwordx4 v[4:5], v[6:9], off
	s_and_saveexec_b64 s[30:31], s[38:39]
	s_cbranch_execz .LBB0_848
	v_lshl_add_u64 v[4:5], v[122:123], 2, s[4:5]
	s_waitcnt lgkmcnt(0)
	v_add_f32_e32 v2, v2, v3
	global_atomic_add_f32 v[4:5], v2, off

.LBB0_904:
	s_or_b64 exec, exec, s[0:1]
	s_cmp_lg_u32 s73, 1
	s_waitcnt lgkmcnt(0)
	s_barrier
	s_cbranch_scc1 .LBB0_942
	v_mov_b32_e32 v0, s8
	v_add_co_u32_e32 v2, vcc, 0xd0000, v0
	v_mov_b32_e32 v0, s9
	v_mov_b32_e32 v7, v206
	v_addc_co_u32_e32 v3, vcc, 0, v0, vcc
	global_load_dwordx2 v[4:5], v[2:3], off offset:56 sc1
	s_nop 0
	global_load_dwordx2 v[2:3], v[2:3], off offset:48 sc1
	v_and_b32_e32 v9, 63, v7
	v_ashrrev_i32_e32 v0, 6, v7
	v_readlane_b32 s6, v254, 19
	s_add_u32 s0, s8, 0x21500000
	s_movk_i32 s2, 0x240
	v_lshl_add_u32 v46, v0, 14, 0
	v_add_u32_e32 v50, s6, v0
	v_lshlrev_b32_e32 v0, 3, v9
	s_addc_u32 s1, s9, 0
	v_and_b32_e32 v6, 31, v7
	v_lshrrev_b32_e32 v51, 5, v9
	v_lshrrev_b32_e32 v52, 3, v9
	v_cmp_gt_i32_e32 vcc, s2, v50
	v_and_b32_e32 v8, 56, v0
	v_lshlrev_b32_e32 v53, 5, v50
	s_waitcnt vmcnt(0) lgkmcnt(0)
	v_readfirstlane_b32 s13, v5
	v_readfirstlane_b32 s12, v4
	v_readfirstlane_b32 s15, v3
	v_readfirstlane_b32 s14, v2
	s_and_saveexec_b64 s[16:17], vcc
	s_mov_b32 s40, 0x38000
	s_movk_i32 s41, 0x3ff
	s_movk_i32 s42, 0x900
	s_movk_i32 s43, 0x3000
	s_mov_b32 s44, 0x9000
	s_mov_b32 s45, 0xf000
	s_mov_b32 s46, 0x15000
	s_mov_b32 s47, 0x1b000
	s_mov_b32 s48, 0x21000
	s_movk_i32 s49, 0xfa00
	s_mov_b32 s53, 0x27000
	s_mov_b32 s54, 0x2a000
	s_mov_b32 s61, 0x2d000
	s_mov_b32 s66, 0x33000
	s_mov_b32 s67, 0x36000
	s_mov_b32 s71, 0x39000
	s_mov_b32 s78, 0x3f000
	s_mov_b32 s79, 0x42000
	s_mov_b32 s82, 0x45000
	s_mov_b32 s90, 0x4b000
	s_cbranch_execz .LBB0_910
	v_lshrrev_b32_e32 v47, 5, v9
	v_and_b32_e32 v4, 31, v7
	v_lshrrev_b32_e32 v48, 3, v9
	v_lshlrev_b32_e32 v0, 1, v8
	s_cmp_lg_u64 s[14:15], 0
	v_lshl_add_u32 v5, v4, 2, v46
	v_mul_u32_u24_e32 v10, 0x84, v47
	v_mul_u32_u24_e32 v11, 0x84, v8
	v_lshl_add_u64 v[2:3], s[0:1], 0, v[0:1]
	v_lshlrev_b32_e32 v0, 2, v48
	s_mov_b64 s[18:19], 0
	s_cselect_b64 s[30:31], -1, 0
	v_add3_u32 v49, v46, v11, v0
	v_lshlrev_b32_e32 v54, 5, v50
	v_lshlrev_b32_e32 v0, 2, v4
	v_add_u32_e32 v55, v5, v10
	v_mov_b32_e32 v56, v50
	s_branch .LBB0_908
.LBB0_907:
	v_add_u32_e32 v5, 0x400, v55
	s_waitcnt vmcnt(0) lgkmcnt(0)
	ds_write2_b32 v55, v10, v11 offset1:66
	ds_write2_b32 v55, v12, v13 offset0:132 offset1:198
	ds_write2_b32 v5, v14, v15 offset0:8 offset1:74
	ds_write2_b32 v5, v16, v17 offset0:140 offset1:206
	v_add_u32_e32 v5, 0x800, v55
	ds_write2_b32 v5, v18, v19 offset0:16 offset1:82
	ds_write2_b32 v5, v20, v21 offset0:148 offset1:214
	v_add_u32_e32 v5, 0xc00, v55
	ds_write2_b32 v5, v22, v23 offset0:24 offset1:90
	ds_write2_b32 v5, v24, v25 offset0:156 offset1:222
	v_add_u32_e32 v5, 0x1000, v55
	ds_write2_b32 v5, v26, v27 offset0:32 offset1:98
	ds_write2_b32 v5, v28, v29 offset0:164 offset1:230
	v_add_u32_e32 v5, 0x1400, v55
	ds_write2_b32 v5, v30, v31 offset0:40 offset1:106
	ds_write2_b32 v5, v32, v33 offset0:172 offset1:238
	v_add_u32_e32 v5, 0x1800, v55
	ds_write2_b32 v5, v36, v37 offset0:48 offset1:114
	ds_write2_b32 v5, v38, v39 offset0:180 offset1:246
	v_add_u32_e32 v5, 0x1c00, v55
	ds_write2_b32 v5, v42, v43 offset0:56 offset1:122
	ds_write2_b32 v5, v44, v45 offset0:188 offset1:254
	s_waitcnt lgkmcnt(0)
	ds_read2_b32 v[10:11], v49 offset1:33
	s_waitcnt lgkmcnt(0)
	v_cvt_pk_bf16_f32 v10, v10, v11
	ds_read2_b32 v[12:13], v49 offset0:66 offset1:99
	s_waitcnt lgkmcnt(0)
	v_cvt_pk_bf16_f32 v11, v12, v13
	ds_read2_b32 v[12:13], v49 offset0:132 offset1:165
	s_waitcnt lgkmcnt(0)
	v_cvt_pk_bf16_f32 v12, v12, v13
	ds_read2_b32 v[14:15], v49 offset0:198 offset1:231
	s_waitcnt lgkmcnt(0)
	v_cvt_pk_bf16_f32 v13, v14, v15
	v_add3_u32 v14, v48, v54, v57
	v_ashrrev_i32_e32 v5, 31, v4
	v_ashrrev_i32_e32 v15, 31, v14
	v_lshl_add_u64 v[4:5], v[4:5], 1, v[2:3]
	v_lshlrev_b64 v[16:17], 12, v[14:15]
	v_lshl_add_u64 v[16:17], v[4:5], 0, v[16:17]
	global_store_dwordx4 v[16:17], v[10:13], off
	ds_read2_b32 v[10:11], v49 offset0:8 offset1:41
	v_add_u32_e32 v18, 16, v14
	s_waitcnt lgkmcnt(0)
	v_cvt_pk_bf16_f32 v10, v10, v11
	ds_read2_b32 v[12:13], v49 offset0:74 offset1:107
	s_waitcnt lgkmcnt(0)
	v_cvt_pk_bf16_f32 v11, v12, v13
	ds_read2_b32 v[12:13], v49 offset0:140 offset1:173
	s_waitcnt lgkmcnt(0)
	v_cvt_pk_bf16_f32 v12, v12, v13
	ds_read2_b32 v[16:17], v49 offset0:206 offset1:239
	s_waitcnt lgkmcnt(0)
	v_cvt_pk_bf16_f32 v13, v16, v17
	v_add_u32_e32 v16, 8, v14
	v_ashrrev_i32_e32 v17, 31, v16
	v_lshlrev_b64 v[16:17], 12, v[16:17]
	v_lshl_add_u64 v[16:17], v[4:5], 0, v[16:17]
	global_store_dwordx4 v[16:17], v[10:13], off
	ds_read2_b32 v[10:11], v49 offset0:16 offset1:49
	v_ashrrev_i32_e32 v19, 31, v18
	s_waitcnt lgkmcnt(0)
	v_cvt_pk_bf16_f32 v10, v10, v11
	ds_read2_b32 v[12:13], v49 offset0:82 offset1:115
	v_lshlrev_b64 v[18:19], 12, v[18:19]
	s_waitcnt lgkmcnt(0)
	v_cvt_pk_bf16_f32 v11, v12, v13
	ds_read2_b32 v[12:13], v49 offset0:148 offset1:181
	v_lshl_add_u64 v[18:19], v[4:5], 0, v[18:19]
	s_waitcnt lgkmcnt(0)
	v_cvt_pk_bf16_f32 v12, v12, v13
	ds_read2_b32 v[16:17], v49 offset0:214 offset1:247
	s_waitcnt lgkmcnt(0)
	v_cvt_pk_bf16_f32 v13, v16, v17
	global_store_dwordx4 v[18:19], v[10:13], off
	v_add_u32_e32 v14, 24, v14
	ds_read2_b32 v[10:11], v49 offset0:24 offset1:57
	v_ashrrev_i32_e32 v15, 31, v14
	s_waitcnt lgkmcnt(0)
	v_cvt_pk_bf16_f32 v10, v10, v11
	ds_read2_b32 v[12:13], v49 offset0:90 offset1:123
	v_lshlrev_b64 v[14:15], 12, v[14:15]
	s_waitcnt lgkmcnt(0)
	v_cvt_pk_bf16_f32 v11, v12, v13
	ds_read2_b32 v[12:13], v49 offset0:156 offset1:189
	v_lshl_add_u64 v[4:5], v[4:5], 0, v[14:15]
	s_waitcnt lgkmcnt(0)
	v_cvt_pk_bf16_f32 v12, v12, v13
	ds_read2_b32 v[16:17], v49 offset0:222 offset1:255
	s_waitcnt lgkmcnt(0)
	v_cvt_pk_bf16_f32 v13, v16, v17
	global_store_dwordx4 v[4:5], v[10:13], off
	s_waitcnt lgkmcnt(0)
	v_add_u32_e32 v56, s52, v56
	s_movk_i32 s2, 0x23f
	v_cmp_lt_i32_e32 vcc, s2, v56
	s_or_b64 s[18:19], vcc, s[18:19]
	v_add_u32_e32 v54, s3, v54
	s_andn2_b64 exec, exec, s[18:19]
	s_cbranch_execz .LBB0_910
.LBB0_908:
	s_mov_b32 s2, 0x38e38e39
	v_mul_hi_i32 v4, v56, s2
	v_lshrrev_b32_e32 v5, 31, v4
	v_ashrrev_i32_e32 v4, 2, v4
	v_add_u32_e32 v5, v4, v5
	s_movk_i32 s2, 0xfdc0
	v_lshlrev_b32_e32 v4, 6, v5
	v_mul_lo_u32 v57, v5, s2
	v_add_u32_e32 v10, v54, v57
	v_or_b32_e32 v34, v4, v47
	v_mov_b64_e32 v[12:13], s[12:13]
	v_mad_i64_i32 v[12:13], s[6:7], v34, s42, v[12:13]
	v_ashrrev_i32_e32 v11, 31, v10
	v_lshl_add_u64 v[10:11], v[10:11], 2, v[12:13]
	v_lshl_add_u64 v[40:41], v[10:11], 0, v[0:1]
	s_movk_i32 s2, 0x1000
	v_add_co_u32_e32 v12, vcc, s2, v40
	s_movk_i32 s2, 0x2000
	s_nop 0
	v_addc_co_u32_e32 v13, vcc, 0, v41, vcc
	global_load_dword v10, v[40:41], off nt
	global_load_dword v11, v[12:13], off offset:512 nt
	v_add_co_u32_e32 v12, vcc, s2, v40
	s_movk_i32 s2, 0x4000
	s_nop 0
	v_addc_co_u32_e32 v13, vcc, 0, v41, vcc
	v_add_co_u32_e32 v14, vcc, s43, v40
	global_load_dword v12, v[12:13], off offset:1024 nt
	s_nop 0
	v_addc_co_u32_e32 v15, vcc, 0, v41, vcc
	global_load_dword v13, v[14:15], off offset:1536 nt
	v_add_co_u32_e32 v14, vcc, s2, v40
	s_movk_i32 s2, 0x5000
	s_nop 0
	v_addc_co_u32_e32 v15, vcc, 0, v41, vcc
	v_add_co_u32_e32 v16, vcc, s2, v40
	global_load_dword v14, v[14:15], off offset:2048 nt
	s_nop 0
	v_addc_co_u32_e32 v17, vcc, 0, v41, vcc
	global_load_dword v15, v[16:17], off offset:2560 nt
	v_add_co_u32_e32 v16, vcc, s75, v40
	s_movk_i32 s2, 0x7000
	s_nop 0
	v_addc_co_u32_e32 v17, vcc, 0, v41, vcc
	v_add_co_u32_e32 v18, vcc, s2, v40
	global_load_dword v16, v[16:17], off offset:3072 nt
	s_nop 0
	v_addc_co_u32_e32 v19, vcc, 0, v41, vcc
	global_load_dword v17, v[18:19], off offset:3584 nt
	v_add_co_u32_e32 v18, vcc, s44, v40
	s_mov_b32 s2, 0xa000
	s_nop 0
	v_addc_co_u32_e32 v19, vcc, 0, v41, vcc
	v_add_co_u32_e32 v20, vcc, s2, v40
	s_mov_b32 s2, 0xb000
	s_nop 0
	v_addc_co_u32_e32 v21, vcc, 0, v41, vcc
	global_load_dword v18, v[18:19], off nt
	s_nop 0
	global_load_dword v19, v[20:21], off offset:512 nt
	v_add_co_u32_e32 v20, vcc, s2, v40
	s_mov_b32 s2, 0xd000
	s_nop 0
	v_addc_co_u32_e32 v21, vcc, 0, v41, vcc
	v_add_co_u32_e32 v22, vcc, s91, v40
	global_load_dword v20, v[20:21], off offset:1024 nt
	s_nop 0
	v_addc_co_u32_e32 v23, vcc, 0, v41, vcc
	global_load_dword v21, v[22:23], off offset:1536 nt
	v_add_co_u32_e32 v22, vcc, s2, v40
	s_mov_b32 s2, 0xe000
	s_nop 0
	v_addc_co_u32_e32 v23, vcc, 0, v41, vcc
	v_add_co_u32_e32 v24, vcc, s2, v40
	global_load_dword v22, v[22:23], off offset:2048 nt
	s_nop 0
	v_addc_co_u32_e32 v25, vcc, 0, v41, vcc
	global_load_dword v23, v[24:25], off offset:2560 nt
	v_add_co_u32_e32 v24, vcc, s45, v40
	s_mov_b32 s2, 0x13000
	s_nop 0
	v_addc_co_u32_e32 v25, vcc, 0, v41, vcc
	v_add_co_u32_e32 v26, vcc, s56, v40
	global_load_dword v24, v[24:25], off offset:3072 nt
	s_nop 0
	v_addc_co_u32_e32 v27, vcc, 0, v41, vcc
	global_load_dword v25, v[26:27], off offset:3584 nt
	v_add_co_u32_e32 v26, vcc, s74, v40
	s_nop 1
	v_addc_co_u32_e32 v27, vcc, 0, v41, vcc
	v_add_co_u32_e32 v28, vcc, s2, v40
	s_mov_b32 s2, 0x14000
	s_nop 0
	v_addc_co_u32_e32 v29, vcc, 0, v41, vcc
	global_load_dword v26, v[26:27], off nt
	s_nop 0
	global_load_dword v27, v[28:29], off offset:512 nt
	v_add_co_u32_e32 v28, vcc, s2, v40
	s_mov_b32 s2, 0x16000
	s_nop 0
	v_addc_co_u32_e32 v29, vcc, 0, v41, vcc
	v_add_co_u32_e32 v30, vcc, s46, v40
	global_load_dword v28, v[28:29], off offset:1024 nt
	s_nop 0
	v_addc_co_u32_e32 v31, vcc, 0, v41, vcc
	global_load_dword v29, v[30:31], off offset:1536 nt
	v_add_co_u32_e32 v30, vcc, s2, v40
	s_mov_b32 s2, 0x17000
	s_nop 0
	v_addc_co_u32_e32 v31, vcc, 0, v41, vcc
	v_add_co_u32_e32 v32, vcc, s2, v40
	global_load_dword v30, v[30:31], off offset:2048 nt
	s_nop 0
	v_addc_co_u32_e32 v33, vcc, 0, v41, vcc
	global_load_dword v31, v[32:33], off offset:2560 nt
	v_add_co_u32_e32 v32, vcc, s93, v40
	s_mov_b32 s2, 0x19000
	s_nop 0
	v_addc_co_u32_e32 v33, vcc, 0, v41, vcc
	v_add_co_u32_e32 v36, vcc, s2, v40
	global_load_dword v32, v[32:33], off offset:3072 nt
	s_nop 0
	v_addc_co_u32_e32 v37, vcc, 0, v41, vcc
	global_load_dword v33, v[36:37], off offset:3584 nt
	v_add_co_u32_e32 v36, vcc, 0x1b000, v40
	s_mov_b32 s2, 0x1c000
	s_nop 0
	v_addc_co_u32_e32 v37, vcc, 0, v41, vcc
	v_add_co_u32_e32 v38, vcc, s2, v40
	global_load_dword v36, v[36:37], off nt
	s_nop 0
	v_addc_co_u32_e32 v39, vcc, 0, v41, vcc
	global_load_dword v37, v[38:39], off offset:512 nt
	v_add_co_u32_e32 v38, vcc, 0x1d000, v40
	s_nop 1
	v_addc_co_u32_e32 v39, vcc, 0, v41, vcc
	v_add_co_u32_e32 v42, vcc, 0x1e000, v40
	global_load_dword v38, v[38:39], off offset:1024 nt
	s_nop 0
	v_addc_co_u32_e32 v43, vcc, 0, v41, vcc
	global_load_dword v39, v[42:43], off offset:1536 nt
	v_add_co_u32_e32 v42, vcc, 0x1f000, v40
	s_nop 1
	v_addc_co_u32_e32 v43, vcc, 0, v41, vcc
	v_add_co_u32_e32 v44, vcc, 0x20000, v40
	global_load_dword v42, v[42:43], off offset:2048 nt
	s_nop 0
	v_addc_co_u32_e32 v45, vcc, 0, v41, vcc
	global_load_dword v43, v[44:45], off offset:2560 nt
	v_add_co_u32_e32 v44, vcc, 0x21000, v40
	s_nop 1
	v_addc_co_u32_e32 v45, vcc, 0, v41, vcc
	v_add_co_u32_e32 v40, vcc, 0x22000, v40
	global_load_dword v44, v[44:45], off offset:3072 nt
	s_nop 0
	v_addc_co_u32_e32 v41, vcc, 0, v41, vcc
	global_load_dword v45, v[40:41], off offset:3584 nt
	s_andn2_b64 vcc, exec, s[30:31]
	s_cbranch_vccnz .LBB0_907
	v_ashrrev_i32_e32 v35, 31, v34
	v_lshl_add_u64 v[34:35], v[34:35], 2, s[14:15]
	global_load_dword v40, v[34:35], off
	global_load_dword v41, v[34:35], off offset:8
	global_load_dword v58, v[34:35], off offset:16
	global_load_dword v59, v[34:35], off offset:24
	global_load_dword v60, v[34:35], off offset:32
	global_load_dword v61, v[34:35], off offset:40
	global_load_dword v62, v[34:35], off offset:48
	global_load_dword v63, v[34:35], off offset:56
	global_load_dword v64, v[34:35], off offset:64
	global_load_dword v65, v[34:35], off offset:72
	global_load_dword v66, v[34:35], off offset:80
	global_load_dword v67, v[34:35], off offset:88
	global_load_dword v68, v[34:35], off offset:96
	global_load_dword v69, v[34:35], off offset:104
	global_load_dword v70, v[34:35], off offset:112
	global_load_dword v71, v[34:35], off offset:120
	global_load_dword v72, v[34:35], off offset:128
	global_load_dword v73, v[34:35], off offset:136
	global_load_dword v74, v[34:35], off offset:144
	global_load_dword v75, v[34:35], off offset:152
	global_load_dword v76, v[34:35], off offset:160
	global_load_dword v77, v[34:35], off offset:168
	global_load_dword v78, v[34:35], off offset:176
	global_load_dword v79, v[34:35], off offset:184
	global_load_dword v80, v[34:35], off offset:192
	global_load_dword v81, v[34:35], off offset:200
	global_load_dword v82, v[34:35], off offset:208
	global_load_dword v83, v[34:35], off offset:216
	global_load_dword v84, v[34:35], off offset:224
	global_load_dword v85, v[34:35], off offset:232
	global_load_dword v86, v[34:35], off offset:240
	global_load_dword v87, v[34:35], off offset:248
	s_waitcnt vmcnt(0) lgkmcnt(0)
	v_pk_mul_f32 v[10:11], v[10:11], v[40:41]
	v_pk_mul_f32 v[12:13], v[12:13], v[58:59]
	v_pk_mul_f32 v[14:15], v[14:15], v[60:61]
	v_pk_mul_f32 v[16:17], v[16:17], v[62:63]
	v_pk_mul_f32 v[18:19], v[18:19], v[64:65]
	v_pk_mul_f32 v[20:21], v[20:21], v[66:67]
	v_pk_mul_f32 v[22:23], v[22:23], v[68:69]
	v_pk_mul_f32 v[24:25], v[24:25], v[70:71]
	v_pk_mul_f32 v[26:27], v[26:27], v[72:73]
	v_pk_mul_f32 v[28:29], v[28:29], v[74:75]
	v_pk_mul_f32 v[30:31], v[30:31], v[76:77]
	v_pk_mul_f32 v[32:33], v[32:33], v[78:79]
	v_pk_mul_f32 v[36:37], v[36:37], v[80:81]
	v_pk_mul_f32 v[38:39], v[38:39], v[82:83]
	v_pk_mul_f32 v[42:43], v[42:43], v[84:85]
	v_pk_mul_f32 v[44:45], v[44:45], v[86:87]
	s_branch .LBB0_907

.LBB0_912:
	v_add_u32_e32 v10, s60, v10
	s_mov_b32 s2, 0xbfff
	v_cmp_lt_i32_e32 vcc, s2, v10
	global_store_dwordx4 v[12:13], v[2:5], off
	s_or_b64 s[14:15], vcc, s[14:15]
	v_lshl_add_u64 v[12:13], v[12:13], 0, s[10:11]
	s_andn2_b64 exec, exec, s[14:15]
	s_cbranch_execnz .LBB0_912
.LBB0_913:
	s_or_b64 exec, exec, s[12:13]
	v_mov_b32_e32 v0, s8
	v_add_co_u32_e32 v2, vcc, 0xd0000, v0
	v_mov_b32_e32 v0, s9
	s_nop 0
	v_addc_co_u32_e32 v3, vcc, 0, v0, vcc
	global_load_dwordx2 v[4:5], v[2:3], off offset:96 sc1
	s_add_u32 s12, s8, 0xd0060
	global_load_dwordx2 v[2:3], v[2:3], off offset:16 sc1
	s_addc_u32 s13, s9, 0
	s_add_u32 s14, s8, 0xd0010
	s_movk_i32 s7, 0x600
	s_mov_b32 s37, s73
	s_addc_u32 s15, s9, 0
	v_cmp_gt_i32_e32 vcc, s7, v50
	s_waitcnt vmcnt(0) lgkmcnt(0)
	v_readfirstlane_b32 s17, v5
	v_readfirstlane_b32 s16, v4
	v_readfirstlane_b32 s2, v3
	v_readfirstlane_b32 s6, v2
	s_and_saveexec_b64 s[18:19], vcc
	s_mov_b32 s7, 0x4e000
	s_mov_b32 s92, 0x51000
	s_mov_b32 s73, 0x57000
	s_mov_b32 s76, 0x5a000
	s_movk_i32 s36, 0x5ff
	s_cbranch_execz .LBB0_916
	v_lshrrev_b32_e32 v13, 5, v9
	v_and_b32_e32 v2, 31, v7
	v_lshrrev_b32_e32 v18, 3, v9
	v_lshlrev_b32_e32 v0, 1, v8
	s_add_u32 s30, s6, 0x4000
	v_lshl_add_u32 v3, v2, 2, v46
	v_mul_u32_u24_e32 v4, 0x84, v13
	v_mul_u32_u24_e32 v5, 0x84, v8
	v_lshl_add_u64 v[10:11], s[0:1], 0, v[0:1]
	v_lshlrev_b32_e32 v0, 2, v18
	s_addc_u32 s31, s2, 0
	v_add3_u32 v19, v46, v5, v0
	v_lshlrev_b32_e32 v12, 5, v50
	s_mov_b64 s[38:39], 0
	v_lshlrev_b32_e32 v0, 2, v2
	v_add_u32_e32 v20, v3, v4
	v_mov_b32_e32 v21, v50
.LBB0_915:
	v_mul_hi_i32 v2, v21, s81
	v_lshrrev_b32_e32 v3, 31, v2
	v_ashrrev_i32_e32 v2, 3, v2
	v_add_u32_e32 v2, v2, v3
	v_lshlrev_b32_e32 v4, 6, v2
	v_mad_u64_u32 v[2:3], s[0:1], v2, s49, v[12:13]
	v_or_b32_e32 v14, v4, v13
	v_mov_b64_e32 v[16:17], s[16:17]
	v_mad_i64_i32 v[16:17], s[0:1], v14, s89, v[16:17]
	v_ashrrev_i32_e32 v3, 31, v2
	v_lshl_add_u64 v[16:17], v[2:3], 2, v[16:17]
	v_lshl_add_u64 v[56:57], v[16:17], 0, v[0:1]
	v_add_co_u32_e64 v16, s[0:1], s43, v56
	global_load_dword v54, v[56:57], off nt
	s_nop 0
	v_addc_co_u32_e64 v17, s[0:1], 0, v57, s[0:1]
	global_load_dword v49, v[16:17], off nt
	v_add_co_u32_e64 v16, s[0:1], s75, v56
	v_ashrrev_i32_e32 v15, 31, v14
	s_nop 0
	v_addc_co_u32_e64 v17, s[0:1], 0, v57, s[0:1]
	global_load_dword v48, v[16:17], off nt
	v_add_co_u32_e64 v16, s[0:1], s44, v56
	v_add_u32_e32 v21, s52, v21
	s_nop 0
	v_addc_co_u32_e64 v17, s[0:1], 0, v57, s[0:1]
	global_load_dword v47, v[16:17], off nt
	v_add_co_u32_e64 v16, s[0:1], s91, v56
	v_add_u32_e32 v12, s3, v12
	s_nop 0
	v_addc_co_u32_e64 v17, s[0:1], 0, v57, s[0:1]
	global_load_dword v45, v[16:17], off nt
	v_add_co_u32_e64 v16, s[0:1], s45, v56
	s_nop 1
	v_addc_co_u32_e64 v17, s[0:1], 0, v57, s[0:1]
	global_load_dword v44, v[16:17], off nt
	v_add_co_u32_e64 v16, s[0:1], s74, v56
	s_nop 1
	v_addc_co_u32_e64 v17, s[0:1], 0, v57, s[0:1]
	global_load_dword v43, v[16:17], off nt
	v_add_co_u32_e64 v16, s[0:1], s46, v56
	s_nop 1
	v_addc_co_u32_e64 v17, s[0:1], 0, v57, s[0:1]
	global_load_dword v42, v[16:17], off nt
	v_add_co_u32_e64 v16, s[0:1], s93, v56
	s_nop 1
	v_addc_co_u32_e64 v17, s[0:1], 0, v57, s[0:1]
	global_load_dword v41, v[16:17], off nt
	v_add_co_u32_e64 v16, s[0:1], s47, v56
	s_nop 1
	v_addc_co_u32_e64 v17, s[0:1], 0, v57, s[0:1]
	global_load_dword v40, v[16:17], off nt
	v_add_co_u32_e64 v16, s[0:1], s72, v56
	s_nop 1
	v_addc_co_u32_e64 v17, s[0:1], 0, v57, s[0:1]
	global_load_dword v39, v[16:17], off nt
	v_add_co_u32_e64 v16, s[0:1], s48, v56
	s_nop 1
	v_addc_co_u32_e64 v17, s[0:1], 0, v57, s[0:1]
	global_load_dword v38, v[16:17], off nt
	v_add_co_u32_e64 v16, s[0:1], s95, v56
	s_nop 1
	v_addc_co_u32_e64 v17, s[0:1], 0, v57, s[0:1]
	global_load_dword v37, v[16:17], off nt
	v_add_co_u32_e64 v16, s[0:1], s53, v56
	s_nop 1
	v_addc_co_u32_e64 v17, s[0:1], 0, v57, s[0:1]
	global_load_dword v36, v[16:17], off nt
	v_add_co_u32_e64 v16, s[0:1], s54, v56
	s_nop 1
	v_addc_co_u32_e64 v17, s[0:1], 0, v57, s[0:1]
	global_load_dword v35, v[16:17], off nt
	v_add_co_u32_e64 v16, s[0:1], s61, v56
	s_nop 1
	v_addc_co_u32_e64 v17, s[0:1], 0, v57, s[0:1]
	global_load_dword v34, v[16:17], off nt
	v_add_co_u32_e64 v16, s[0:1], s83, v56
	s_nop 1
	v_addc_co_u32_e64 v17, s[0:1], 0, v57, s[0:1]
	global_load_dword v33, v[16:17], off nt
	v_add_co_u32_e64 v16, s[0:1], s66, v56
	s_nop 1
	v_addc_co_u32_e64 v17, s[0:1], 0, v57, s[0:1]
	global_load_dword v32, v[16:17], off nt
	v_add_co_u32_e64 v16, s[0:1], s67, v56
	s_nop 1
	v_addc_co_u32_e64 v17, s[0:1], 0, v57, s[0:1]
	global_load_dword v31, v[16:17], off nt
	v_add_co_u32_e64 v16, s[0:1], s71, v56
	s_nop 1
	v_addc_co_u32_e64 v17, s[0:1], 0, v57, s[0:1]
	global_load_dword v30, v[16:17], off nt
	v_add_co_u32_e64 v16, s[0:1], s33, v56
	s_nop 1
	v_addc_co_u32_e64 v17, s[0:1], 0, v57, s[0:1]
	global_load_dword v29, v[16:17], off nt
	v_add_co_u32_e64 v16, s[0:1], s78, v56
	s_nop 1
	v_addc_co_u32_e64 v17, s[0:1], 0, v57, s[0:1]
	global_load_dword v28, v[16:17], off nt
	v_add_co_u32_e64 v16, s[0:1], s79, v56
	s_nop 1
	v_addc_co_u32_e64 v17, s[0:1], 0, v57, s[0:1]
	global_load_dword v27, v[16:17], off nt
	v_add_co_u32_e64 v16, s[0:1], s82, v56
	s_nop 1
	v_addc_co_u32_e64 v17, s[0:1], 0, v57, s[0:1]
	global_load_dword v26, v[16:17], off nt
	v_add_co_u32_e64 v16, s[0:1], s80, v56
	s_nop 1
	v_addc_co_u32_e64 v17, s[0:1], 0, v57, s[0:1]
	global_load_dword v25, v[16:17], off nt
	v_add_co_u32_e64 v16, s[0:1], s90, v56
	s_nop 1
	v_addc_co_u32_e64 v17, s[0:1], 0, v57, s[0:1]
	global_load_dword v24, v[16:17], off nt
	v_add_co_u32_e64 v16, s[0:1], s7, v56
	s_nop 1
	v_addc_co_u32_e64 v17, s[0:1], 0, v57, s[0:1]
	global_load_dword v23, v[16:17], off nt
	v_add_co_u32_e64 v16, s[0:1], s92, v56
	s_nop 1
	v_addc_co_u32_e64 v17, s[0:1], 0, v57, s[0:1]
	global_load_dword v22, v[16:17], off nt
	v_add_co_u32_e64 v16, s[0:1], s97, v56
	s_nop 1
	v_addc_co_u32_e64 v17, s[0:1], 0, v57, s[0:1]
	v_add_co_u32_e64 v58, s[0:1], s73, v56
	global_load_dword v17, v[16:17], off nt
	s_nop 0
	v_addc_co_u32_e64 v59, s[0:1], 0, v57, s[0:1]
	global_load_dword v16, v[58:59], off nt
	v_add_co_u32_e64 v58, s[0:1], s76, v56
	s_nop 1
	v_addc_co_u32_e64 v59, s[0:1], 0, v57, s[0:1]
	v_add_co_u32_e64 v56, s[0:1], s77, v56
	global_load_dword v5, v[58:59], off nt
	s_nop 0
	v_addc_co_u32_e64 v57, s[0:1], 0, v57, s[0:1]
	global_load_dword v3, v[56:57], off nt
	v_lshl_add_u64 v[56:57], v[14:15], 2, s[30:31]
	global_load_dword v14, v[56:57], off
	global_load_dword v15, v[56:57], off offset:40
	v_cmp_lt_i32_e64 s[0:1], s36, v21
	s_or_b64 s[38:39], s[0:1], s[38:39]
	s_waitcnt vmcnt(0) lgkmcnt(0)
	v_mul_f32_e32 v54, v54, v14
	global_load_dword v14, v[56:57], off offset:8
	v_mul_f32_e32 v15, v44, v15
	global_load_dword v44, v[56:57], off offset:48
	s_waitcnt vmcnt(0) lgkmcnt(0)
	v_mul_f32_e32 v49, v49, v14
	global_load_dword v14, v[56:57], off offset:16
	v_mul_f32_e32 v43, v43, v44
	global_load_dword v44, v[56:57], off offset:56
	s_waitcnt vmcnt(0) lgkmcnt(0)
	v_mul_f32_e32 v48, v48, v14
	global_load_dword v14, v[56:57], off offset:24
	v_mul_f32_e32 v42, v42, v44
	global_load_dword v44, v[56:57], off offset:64
	s_waitcnt vmcnt(0) lgkmcnt(0)
	v_mul_f32_e32 v47, v47, v14
	global_load_dword v14, v[56:57], off offset:32
	v_mul_f32_e32 v41, v41, v44
	global_load_dword v44, v[56:57], off offset:72
	s_waitcnt vmcnt(0) lgkmcnt(0)
	v_mul_f32_e32 v14, v45, v14
	v_mul_f32_e32 v40, v40, v44
	global_load_dword v44, v[56:57], off offset:80
	s_waitcnt vmcnt(0) lgkmcnt(0)
	v_mul_f32_e32 v39, v39, v44
	global_load_dword v44, v[56:57], off offset:88
	s_waitcnt vmcnt(0) lgkmcnt(0)
	v_mul_f32_e32 v38, v38, v44
	global_load_dword v44, v[56:57], off offset:96
	s_waitcnt vmcnt(0) lgkmcnt(0)
	v_mul_f32_e32 v37, v37, v44
	global_load_dword v44, v[56:57], off offset:104
	s_waitcnt vmcnt(0) lgkmcnt(0)
	v_mul_f32_e32 v36, v36, v44
	global_load_dword v44, v[56:57], off offset:112
	s_waitcnt vmcnt(0) lgkmcnt(0)
	v_mul_f32_e32 v35, v35, v44
	global_load_dword v44, v[56:57], off offset:120
	s_waitcnt vmcnt(0) lgkmcnt(0)
	v_mul_f32_e32 v34, v34, v44
	global_load_dword v44, v[56:57], off offset:128
	s_waitcnt vmcnt(0) lgkmcnt(0)
	v_mul_f32_e32 v33, v33, v44
	global_load_dword v44, v[56:57], off offset:136
	s_waitcnt vmcnt(0) lgkmcnt(0)
	v_mul_f32_e32 v32, v32, v44
	global_load_dword v44, v[56:57], off offset:144
	s_waitcnt vmcnt(0) lgkmcnt(0)
	v_mul_f32_e32 v31, v31, v44
	global_load_dword v44, v[56:57], off offset:152
	s_waitcnt vmcnt(0) lgkmcnt(0)
	v_mul_f32_e32 v30, v30, v44
	global_load_dword v44, v[56:57], off offset:160
	s_waitcnt vmcnt(0) lgkmcnt(0)
	v_mul_f32_e32 v29, v29, v44
	global_load_dword v44, v[56:57], off offset:168
	s_waitcnt vmcnt(0) lgkmcnt(0)
	v_mul_f32_e32 v28, v28, v44
	global_load_dword v44, v[56:57], off offset:176
	s_waitcnt vmcnt(0) lgkmcnt(0)
	v_mul_f32_e32 v27, v27, v44
	global_load_dword v44, v[56:57], off offset:184
	s_waitcnt vmcnt(0) lgkmcnt(0)
	v_mul_f32_e32 v26, v26, v44
	global_load_dword v44, v[56:57], off offset:192
	s_waitcnt vmcnt(0) lgkmcnt(0)
	v_mul_f32_e32 v25, v25, v44
	global_load_dword v44, v[56:57], off offset:200
	s_waitcnt vmcnt(0) lgkmcnt(0)
	v_mul_f32_e32 v24, v24, v44
	global_load_dword v44, v[56:57], off offset:208
	s_waitcnt vmcnt(0) lgkmcnt(0)
	v_mul_f32_e32 v23, v23, v44
	global_load_dword v44, v[56:57], off offset:216
	s_waitcnt vmcnt(0) lgkmcnt(0)
	v_mul_f32_e32 v22, v22, v44
	global_load_dword v44, v[56:57], off offset:224
	s_waitcnt vmcnt(0) lgkmcnt(0)
	v_mul_f32_e32 v17, v17, v44
	global_load_dword v44, v[56:57], off offset:232
	s_waitcnt vmcnt(0) lgkmcnt(0)
	v_mul_f32_e32 v16, v16, v44
	global_load_dword v44, v[56:57], off offset:240
	s_waitcnt vmcnt(0) lgkmcnt(0)
	v_mul_f32_e32 v5, v5, v44
	global_load_dword v44, v[56:57], off offset:248
	ds_write2_b32 v20, v54, v49 offset1:66
	ds_write2_b32 v20, v48, v47 offset0:132 offset1:198
	s_waitcnt vmcnt(0) lgkmcnt(0)
	v_mul_f32_e32 v3, v3, v44
	v_add_u32_e32 v44, 0x400, v20
	ds_write2_b32 v44, v14, v15 offset0:8 offset1:74
	ds_write2_b32 v44, v43, v42 offset0:140 offset1:206
	v_add_u32_e32 v14, 0x800, v20
	ds_write2_b32 v14, v41, v40 offset0:16 offset1:82
	ds_write2_b32 v14, v39, v38 offset0:148 offset1:214
	v_add_u32_e32 v14, 0xc00, v20
	ds_write2_b32 v14, v37, v36 offset0:24 offset1:90
	ds_write2_b32 v14, v35, v34 offset0:156 offset1:222
	v_add_u32_e32 v14, 0x1000, v20
	ds_write2_b32 v14, v33, v32 offset0:32 offset1:98
	ds_write2_b32 v14, v31, v30 offset0:164 offset1:230
	v_add_u32_e32 v14, 0x1400, v20
	ds_write2_b32 v14, v29, v28 offset0:40 offset1:106
	ds_write2_b32 v14, v27, v26 offset0:172 offset1:238
	v_add_u32_e32 v14, 0x1800, v20
	ds_write2_b32 v14, v25, v24 offset0:48 offset1:114
	ds_write2_b32 v14, v23, v22 offset0:180 offset1:246
	v_add_u32_e32 v14, 0x1c00, v20
	ds_write2_b32 v14, v17, v16 offset0:56 offset1:122
	ds_write2_b32 v14, v5, v3 offset0:188 offset1:254
	v_add_u32_e32 v26, v2, v18
	s_waitcnt lgkmcnt(0)
	v_ashrrev_i32_e32 v5, 31, v4
	v_add_u32_e32 v2, 0x300, v26
	v_lshl_add_u64 v[14:15], v[4:5], 1, v[10:11]
	ds_read2_b32 v[4:5], v19 offset1:33
	v_ashrrev_i32_e32 v3, 31, v2
	s_waitcnt lgkmcnt(0)
	v_cvt_pk_bf16_f32 v22, v4, v5
	ds_read2_b32 v[4:5], v19 offset0:66 offset1:99
	v_lshlrev_b64 v[2:3], 12, v[2:3]
	s_waitcnt lgkmcnt(0)
	v_cvt_pk_bf16_f32 v23, v4, v5
	ds_read2_b32 v[4:5], v19 offset0:132 offset1:165
	v_lshl_add_u64 v[2:3], v[14:15], 0, v[2:3]
	s_waitcnt lgkmcnt(0)
	v_cvt_pk_bf16_f32 v24, v4, v5
	ds_read2_b32 v[4:5], v19 offset0:198 offset1:231
	s_waitcnt lgkmcnt(0)
	v_cvt_pk_bf16_f32 v25, v4, v5
	global_store_dwordx4 v[2:3], v[22:25], off
	ds_read2_b32 v[2:3], v19 offset0:8 offset1:41
	s_waitcnt lgkmcnt(0)
	v_cvt_pk_bf16_f32 v2, v2, v3
	ds_read2_b32 v[4:5], v19 offset0:74 offset1:107
	s_waitcnt lgkmcnt(0)
	v_cvt_pk_bf16_f32 v3, v4, v5
	ds_read2_b32 v[4:5], v19 offset0:140 offset1:173
	s_waitcnt lgkmcnt(0)
	v_cvt_pk_bf16_f32 v4, v4, v5
	ds_read2_b32 v[16:17], v19 offset0:206 offset1:239
	s_waitcnt lgkmcnt(0)
	v_cvt_pk_bf16_f32 v5, v16, v17
	v_add_u32_e32 v16, 0x308, v26
	v_ashrrev_i32_e32 v17, 31, v16
	v_lshlrev_b64 v[16:17], 12, v[16:17]
	v_lshl_add_u64 v[16:17], v[14:15], 0, v[16:17]
	global_store_dwordx4 v[16:17], v[2:5], off
	ds_read2_b32 v[2:3], v19 offset0:16 offset1:49
	s_waitcnt lgkmcnt(0)
	v_cvt_pk_bf16_f32 v2, v2, v3
	ds_read2_b32 v[4:5], v19 offset0:82 offset1:115
	s_waitcnt lgkmcnt(0)
	v_cvt_pk_bf16_f32 v3, v4, v5
	ds_read2_b32 v[4:5], v19 offset0:148 offset1:181
	s_waitcnt lgkmcnt(0)
	v_cvt_pk_bf16_f32 v4, v4, v5
	ds_read2_b32 v[16:17], v19 offset0:214 offset1:247
	s_waitcnt lgkmcnt(0)
	v_cvt_pk_bf16_f32 v5, v16, v17
	v_add_u32_e32 v16, 0x310, v26
	v_ashrrev_i32_e32 v17, 31, v16
	v_lshlrev_b64 v[16:17], 12, v[16:17]
	v_lshl_add_u64 v[16:17], v[14:15], 0, v[16:17]
	global_store_dwordx4 v[16:17], v[2:5], off
	ds_read2_b32 v[2:3], v19 offset0:24 offset1:57
	s_waitcnt lgkmcnt(0)
	v_cvt_pk_bf16_f32 v2, v2, v3
	ds_read2_b32 v[4:5], v19 offset0:90 offset1:123
	s_waitcnt lgkmcnt(0)
	v_cvt_pk_bf16_f32 v3, v4, v5
	ds_read2_b32 v[4:5], v19 offset0:156 offset1:189
	s_waitcnt lgkmcnt(0)
	v_cvt_pk_bf16_f32 v4, v4, v5
	ds_read2_b32 v[16:17], v19 offset0:222 offset1:255
	s_waitcnt lgkmcnt(0)
	v_cvt_pk_bf16_f32 v5, v16, v17
	v_add_u32_e32 v16, 0x318, v26
	v_ashrrev_i32_e32 v17, 31, v16
	v_lshlrev_b64 v[16:17], 12, v[16:17]
	v_lshl_add_u64 v[14:15], v[14:15], 0, v[16:17]
	global_store_dwordx4 v[14:15], v[2:5], off
	s_waitcnt lgkmcnt(0)
	s_andn2_b64 exec, exec, s[38:39]
	s_cbranch_execnz .LBB0_915
.LBB0_916:
	s_or_b64 exec, exec, s[18:19]
	v_mov_b64_e32 v[2:3], s[12:13]
	global_load_dwordx2 v[2:3], v[2:3], off sc1
	s_waitcnt vmcnt(0) lgkmcnt(0)
	v_readfirstlane_b32 s2, v3
	v_readfirstlane_b32 s6, v2
	v_mov_b64_e32 v[2:3], s[14:15]
	global_load_dwordx2 v[2:3], v[2:3], off sc1
	s_waitcnt vmcnt(0) lgkmcnt(0)
	v_readfirstlane_b32 s7, v3
	v_readfirstlane_b32 s10, v2
	s_and_saveexec_b64 s[0:1], vcc
	s_mov_b32 s11, 0x4e000
	s_mov_b32 s18, 0x51000
	s_mov_b32 s19, 0x57000
	s_mov_b32 s73, 0x5a000
	s_movk_i32 s30, 0x5ff
	s_mov_b32 s36, 0xa8000
	s_mov_b32 s76, 0xfffe0
	s_cbranch_execz .LBB0_919
	s_add_u32 s12, s6, 0xc00000
	s_addc_u32 s13, s2, 0
	s_add_u32 s14, s10, 0x6000
	v_lshrrev_b32_e32 v13, 5, v9
	v_and_b32_e32 v2, 31, v7
	v_lshrrev_b32_e32 v20, 3, v9
	v_lshlrev_b32_e32 v0, 1, v8
	s_addc_u32 s15, s7, 0
	v_lshl_add_u32 v3, v2, 2, v46
	v_mul_u32_u24_e32 v14, 0x84, v13
	v_mul_u32_u24_e32 v12, 0x84, v8
	v_lshl_add_u64 v[4:5], s[8:9], 0, v[0:1]
	s_mov_b64 s[6:7], 0x22200000
	v_lshlrev_b32_e32 v0, 2, v20
	v_lshl_add_u64 v[10:11], v[4:5], 0, s[6:7]
	v_add3_u32 v21, v46, v12, v0
	v_lshlrev_b32_e32 v12, 5, v50
	s_mov_b64 s[16:17], 0
	v_lshlrev_b32_e32 v0, 2, v2
	v_add_u32_e32 v22, v3, v14
	v_mov_b32_e32 v23, v50
.LBB0_918:
	v_mul_hi_i32 v2, v23, s81
	v_lshrrev_b32_e32 v3, 31, v2
	v_ashrrev_i32_e32 v2, 3, v2
	v_add_u32_e32 v2, v2, v3
	v_lshlrev_b32_e32 v4, 6, v2
	v_mad_u64_u32 v[2:3], s[6:7], v2, s49, v[12:13]
	v_or_b32_e32 v14, v4, v13
	v_mov_b64_e32 v[16:17], s[12:13]
	v_mad_i64_i32 v[16:17], s[6:7], v14, s89, v[16:17]
	v_ashrrev_i32_e32 v3, 31, v2
	v_lshl_add_u64 v[16:17], v[2:3], 2, v[16:17]
	v_lshl_add_u64 v[56:57], v[16:17], 0, v[0:1]
	v_add_co_u32_e32 v16, vcc, s43, v56
	global_load_dword v54, v[56:57], off nt
	s_nop 0
	v_addc_co_u32_e32 v17, vcc, 0, v57, vcc
	global_load_dword v49, v[16:17], off nt
	v_add_co_u32_e32 v16, vcc, s75, v56
	v_ashrrev_i32_e32 v15, 31, v14
	s_nop 0
	v_addc_co_u32_e32 v17, vcc, 0, v57, vcc
	global_load_dword v48, v[16:17], off nt
	v_add_co_u32_e32 v16, vcc, s44, v56
	v_add_u32_e32 v23, s52, v23
	s_nop 0
	v_addc_co_u32_e32 v17, vcc, 0, v57, vcc
	global_load_dword v47, v[16:17], off nt
	v_add_co_u32_e32 v16, vcc, s91, v56
	v_add_u32_e32 v12, s3, v12
	s_nop 0
	v_addc_co_u32_e32 v17, vcc, 0, v57, vcc
	global_load_dword v45, v[16:17], off nt
	v_add_co_u32_e32 v16, vcc, s45, v56
	s_nop 1
	v_addc_co_u32_e32 v17, vcc, 0, v57, vcc
	global_load_dword v44, v[16:17], off nt
	v_add_co_u32_e32 v16, vcc, s74, v56
	s_nop 1
	v_addc_co_u32_e32 v17, vcc, 0, v57, vcc
	global_load_dword v43, v[16:17], off nt
	v_add_co_u32_e32 v16, vcc, s46, v56
	s_nop 1
	v_addc_co_u32_e32 v17, vcc, 0, v57, vcc
	global_load_dword v42, v[16:17], off nt
	v_add_co_u32_e32 v16, vcc, s93, v56
	s_nop 1
	v_addc_co_u32_e32 v17, vcc, 0, v57, vcc
	global_load_dword v41, v[16:17], off nt
	v_add_co_u32_e32 v16, vcc, s47, v56
	s_nop 1
	v_addc_co_u32_e32 v17, vcc, 0, v57, vcc
	global_load_dword v40, v[16:17], off nt
	v_add_co_u32_e32 v16, vcc, s72, v56
	s_nop 1
	v_addc_co_u32_e32 v17, vcc, 0, v57, vcc
	global_load_dword v39, v[16:17], off nt
	v_add_co_u32_e32 v16, vcc, s48, v56
	s_nop 1
	v_addc_co_u32_e32 v17, vcc, 0, v57, vcc
	global_load_dword v38, v[16:17], off nt
	v_add_co_u32_e32 v16, vcc, s95, v56
	s_nop 1
	v_addc_co_u32_e32 v17, vcc, 0, v57, vcc
	global_load_dword v37, v[16:17], off nt
	v_add_co_u32_e32 v16, vcc, s53, v56
	s_nop 1
	v_addc_co_u32_e32 v17, vcc, 0, v57, vcc
	global_load_dword v36, v[16:17], off nt
	v_add_co_u32_e32 v16, vcc, s54, v56
	s_nop 1
	v_addc_co_u32_e32 v17, vcc, 0, v57, vcc
	global_load_dword v35, v[16:17], off nt
	v_add_co_u32_e32 v16, vcc, s61, v56
	s_nop 1
	v_addc_co_u32_e32 v17, vcc, 0, v57, vcc
	global_load_dword v34, v[16:17], off nt
	v_add_co_u32_e32 v16, vcc, s83, v56
	s_nop 1
	v_addc_co_u32_e32 v17, vcc, 0, v57, vcc
	global_load_dword v33, v[16:17], off nt
	v_add_co_u32_e32 v16, vcc, s66, v56
	s_nop 1
	v_addc_co_u32_e32 v17, vcc, 0, v57, vcc
	global_load_dword v32, v[16:17], off nt
	v_add_co_u32_e32 v16, vcc, s67, v56
	s_nop 1
	v_addc_co_u32_e32 v17, vcc, 0, v57, vcc
	global_load_dword v31, v[16:17], off nt
	v_add_co_u32_e32 v16, vcc, s71, v56
	s_nop 1
	v_addc_co_u32_e32 v17, vcc, 0, v57, vcc
	global_load_dword v30, v[16:17], off nt
	v_add_co_u32_e32 v16, vcc, s33, v56
	s_nop 1
	v_addc_co_u32_e32 v17, vcc, 0, v57, vcc
	global_load_dword v29, v[16:17], off nt
	v_add_co_u32_e32 v16, vcc, s78, v56
	s_nop 1
	v_addc_co_u32_e32 v17, vcc, 0, v57, vcc
	global_load_dword v28, v[16:17], off nt
	v_add_co_u32_e32 v16, vcc, s79, v56
	s_nop 1
	v_addc_co_u32_e32 v17, vcc, 0, v57, vcc
	global_load_dword v27, v[16:17], off nt
	v_add_co_u32_e32 v16, vcc, s82, v56
	s_nop 1
	v_addc_co_u32_e32 v17, vcc, 0, v57, vcc
	global_load_dword v26, v[16:17], off nt
	v_add_co_u32_e32 v16, vcc, s80, v56
	s_nop 1
	v_addc_co_u32_e32 v17, vcc, 0, v57, vcc
	global_load_dword v25, v[16:17], off nt
	v_add_co_u32_e32 v16, vcc, s90, v56
	s_nop 1
	v_addc_co_u32_e32 v17, vcc, 0, v57, vcc
	global_load_dword v24, v[16:17], off nt
	v_add_co_u32_e32 v16, vcc, s11, v56
	s_nop 1
	v_addc_co_u32_e32 v17, vcc, 0, v57, vcc
	global_load_dword v19, v[16:17], off nt
	v_add_co_u32_e32 v16, vcc, s18, v56
	s_nop 1
	v_addc_co_u32_e32 v17, vcc, 0, v57, vcc
	global_load_dword v18, v[16:17], off nt
	v_add_co_u32_e32 v16, vcc, s97, v56
	s_nop 1
	v_addc_co_u32_e32 v17, vcc, 0, v57, vcc
	v_add_co_u32_e32 v58, vcc, s19, v56
	global_load_dword v17, v[16:17], off nt
	s_nop 0
	v_addc_co_u32_e32 v59, vcc, 0, v57, vcc
	global_load_dword v16, v[58:59], off nt
	v_add_co_u32_e32 v58, vcc, s73, v56
	s_nop 1
	v_addc_co_u32_e32 v59, vcc, 0, v57, vcc
	v_add_co_u32_e32 v56, vcc, s77, v56
	global_load_dword v5, v[58:59], off nt
	s_nop 0
	v_addc_co_u32_e32 v57, vcc, 0, v57, vcc
	global_load_dword v3, v[56:57], off nt
	v_lshl_add_u64 v[56:57], v[14:15], 2, s[14:15]
	global_load_dword v14, v[56:57], off
	global_load_dword v15, v[56:57], off offset:40
	v_cmp_lt_i32_e32 vcc, s30, v23
	s_or_b64 s[16:17], vcc, s[16:17]
	s_waitcnt vmcnt(0) lgkmcnt(0)
	v_mul_f32_e32 v54, v54, v14
	global_load_dword v14, v[56:57], off offset:8
	v_mul_f32_e32 v15, v44, v15
	global_load_dword v44, v[56:57], off offset:48
	s_waitcnt vmcnt(0) lgkmcnt(0)
	v_mul_f32_e32 v49, v49, v14
	global_load_dword v14, v[56:57], off offset:16
	v_mul_f32_e32 v43, v43, v44
	global_load_dword v44, v[56:57], off offset:56
	s_waitcnt vmcnt(0) lgkmcnt(0)
	v_mul_f32_e32 v48, v48, v14
	global_load_dword v14, v[56:57], off offset:24
	v_mul_f32_e32 v42, v42, v44
	global_load_dword v44, v[56:57], off offset:64
	s_waitcnt vmcnt(0) lgkmcnt(0)
	v_mul_f32_e32 v47, v47, v14
	global_load_dword v14, v[56:57], off offset:32
	v_mul_f32_e32 v41, v41, v44
	global_load_dword v44, v[56:57], off offset:72
	s_waitcnt vmcnt(0) lgkmcnt(0)
	v_mul_f32_e32 v14, v45, v14
	v_mul_f32_e32 v40, v40, v44
	global_load_dword v44, v[56:57], off offset:80
	s_waitcnt vmcnt(0) lgkmcnt(0)
	v_mul_f32_e32 v39, v39, v44
	global_load_dword v44, v[56:57], off offset:88
	s_waitcnt vmcnt(0) lgkmcnt(0)
	v_mul_f32_e32 v38, v38, v44
	global_load_dword v44, v[56:57], off offset:96
	s_waitcnt vmcnt(0) lgkmcnt(0)
	v_mul_f32_e32 v37, v37, v44
	global_load_dword v44, v[56:57], off offset:104
	s_waitcnt vmcnt(0) lgkmcnt(0)
	v_mul_f32_e32 v36, v36, v44
	global_load_dword v44, v[56:57], off offset:112
	s_waitcnt vmcnt(0) lgkmcnt(0)
	v_mul_f32_e32 v35, v35, v44
	global_load_dword v44, v[56:57], off offset:120
	s_waitcnt vmcnt(0) lgkmcnt(0)
	v_mul_f32_e32 v34, v34, v44
	global_load_dword v44, v[56:57], off offset:128
	s_waitcnt vmcnt(0) lgkmcnt(0)
	v_mul_f32_e32 v33, v33, v44
	global_load_dword v44, v[56:57], off offset:136
	s_waitcnt vmcnt(0) lgkmcnt(0)
	v_mul_f32_e32 v32, v32, v44
	global_load_dword v44, v[56:57], off offset:144
	s_waitcnt vmcnt(0) lgkmcnt(0)
	v_mul_f32_e32 v31, v31, v44
	global_load_dword v44, v[56:57], off offset:152
	s_waitcnt vmcnt(0) lgkmcnt(0)
	v_mul_f32_e32 v30, v30, v44
	global_load_dword v44, v[56:57], off offset:160
	s_waitcnt vmcnt(0) lgkmcnt(0)
	v_mul_f32_e32 v29, v29, v44
	global_load_dword v44, v[56:57], off offset:168
	s_waitcnt vmcnt(0) lgkmcnt(0)
	v_mul_f32_e32 v28, v28, v44
	global_load_dword v44, v[56:57], off offset:176
	s_waitcnt vmcnt(0) lgkmcnt(0)
	v_mul_f32_e32 v27, v27, v44
	global_load_dword v44, v[56:57], off offset:184
	s_waitcnt vmcnt(0) lgkmcnt(0)
	v_mul_f32_e32 v26, v26, v44
	global_load_dword v44, v[56:57], off offset:192
	s_waitcnt vmcnt(0) lgkmcnt(0)
	v_mul_f32_e32 v25, v25, v44
	global_load_dword v44, v[56:57], off offset:200
	s_waitcnt vmcnt(0) lgkmcnt(0)
	v_mul_f32_e32 v24, v24, v44
	global_load_dword v44, v[56:57], off offset:208
	s_waitcnt vmcnt(0) lgkmcnt(0)
	v_mul_f32_e32 v19, v19, v44
	global_load_dword v44, v[56:57], off offset:216
	s_waitcnt vmcnt(0) lgkmcnt(0)
	v_mul_f32_e32 v18, v18, v44
	global_load_dword v44, v[56:57], off offset:224
	s_waitcnt vmcnt(0) lgkmcnt(0)
	v_mul_f32_e32 v17, v17, v44
	global_load_dword v44, v[56:57], off offset:232
	s_waitcnt vmcnt(0) lgkmcnt(0)
	v_mul_f32_e32 v16, v16, v44
	global_load_dword v44, v[56:57], off offset:240
	s_waitcnt vmcnt(0) lgkmcnt(0)
	v_mul_f32_e32 v5, v5, v44
	global_load_dword v44, v[56:57], off offset:248
	ds_write2_b32 v22, v54, v49 offset1:66
	ds_write2_b32 v22, v48, v47 offset0:132 offset1:198
	s_waitcnt vmcnt(0) lgkmcnt(0)
	v_mul_f32_e32 v3, v3, v44
	v_add_u32_e32 v44, 0x400, v22
	ds_write2_b32 v44, v14, v15 offset0:8 offset1:74
	ds_write2_b32 v44, v43, v42 offset0:140 offset1:206
	v_add_u32_e32 v14, 0x800, v22
	ds_write2_b32 v14, v41, v40 offset0:16 offset1:82
	ds_write2_b32 v14, v39, v38 offset0:148 offset1:214
	v_add_u32_e32 v14, 0xc00, v22
	ds_write2_b32 v14, v37, v36 offset0:24 offset1:90
	ds_write2_b32 v14, v35, v34 offset0:156 offset1:222
	v_add_u32_e32 v14, 0x1000, v22
	ds_write2_b32 v14, v33, v32 offset0:32 offset1:98
	ds_write2_b32 v14, v31, v30 offset0:164 offset1:230
	v_add_u32_e32 v14, 0x1400, v22
	ds_write2_b32 v14, v29, v28 offset0:40 offset1:106
	ds_write2_b32 v14, v27, v26 offset0:172 offset1:238
	v_add_u32_e32 v14, 0x1800, v22
	ds_write2_b32 v14, v25, v24 offset0:48 offset1:114
	ds_write2_b32 v14, v19, v18 offset0:180 offset1:246
	v_add_u32_e32 v14, 0x1c00, v22
	ds_write2_b32 v14, v17, v16 offset0:56 offset1:122
	ds_write2_b32 v14, v5, v3 offset0:188 offset1:254
	s_waitcnt lgkmcnt(0)
	v_ashrrev_i32_e32 v5, 31, v4
	v_add_u32_e32 v16, v2, v20
	v_lshl_add_u64 v[14:15], v[4:5], 1, v[10:11]
	ds_read2_b32 v[4:5], v21 offset1:33
	v_ashrrev_i32_e32 v17, 31, v16
	s_waitcnt lgkmcnt(0)
	v_cvt_pk_bf16_f32 v24, v4, v5
	ds_read2_b32 v[4:5], v21 offset0:66 offset1:99
	v_lshlrev_b64 v[2:3], 12, v[16:17]
	s_waitcnt lgkmcnt(0)
	v_cvt_pk_bf16_f32 v25, v4, v5
	ds_read2_b32 v[4:5], v21 offset0:132 offset1:165
	v_lshl_add_u64 v[2:3], v[14:15], 0, v[2:3]
	s_waitcnt lgkmcnt(0)
	v_cvt_pk_bf16_f32 v26, v4, v5
	ds_read2_b32 v[4:5], v21 offset0:198 offset1:231
	s_waitcnt lgkmcnt(0)
	v_cvt_pk_bf16_f32 v27, v4, v5
	global_store_dwordx4 v[2:3], v[24:27], off
	ds_read2_b32 v[2:3], v21 offset0:8 offset1:41
	s_waitcnt lgkmcnt(0)
	v_cvt_pk_bf16_f32 v2, v2, v3
	ds_read2_b32 v[4:5], v21 offset0:74 offset1:107
	s_waitcnt lgkmcnt(0)
	v_cvt_pk_bf16_f32 v3, v4, v5
	ds_read2_b32 v[4:5], v21 offset0:140 offset1:173
	s_waitcnt lgkmcnt(0)
	v_cvt_pk_bf16_f32 v4, v4, v5
	ds_read2_b32 v[18:19], v21 offset0:206 offset1:239
	s_waitcnt lgkmcnt(0)
	v_cvt_pk_bf16_f32 v5, v18, v19
	v_add_u32_e32 v18, 8, v16
	v_ashrrev_i32_e32 v19, 31, v18
	v_lshlrev_b64 v[18:19], 12, v[18:19]
	v_lshl_add_u64 v[18:19], v[14:15], 0, v[18:19]
	global_store_dwordx4 v[18:19], v[2:5], off
	ds_read2_b32 v[2:3], v21 offset0:16 offset1:49
	s_waitcnt lgkmcnt(0)
	v_cvt_pk_bf16_f32 v2, v2, v3
	ds_read2_b32 v[4:5], v21 offset0:82 offset1:115
	s_waitcnt lgkmcnt(0)
	v_cvt_pk_bf16_f32 v3, v4, v5
	ds_read2_b32 v[4:5], v21 offset0:148 offset1:181
	s_waitcnt lgkmcnt(0)
	v_cvt_pk_bf16_f32 v4, v4, v5
	ds_read2_b32 v[18:19], v21 offset0:214 offset1:247
	s_waitcnt lgkmcnt(0)
	v_cvt_pk_bf16_f32 v5, v18, v19
	v_add_u32_e32 v18, 16, v16
	v_ashrrev_i32_e32 v19, 31, v18
	v_lshlrev_b64 v[18:19], 12, v[18:19]
	v_lshl_add_u64 v[18:19], v[14:15], 0, v[18:19]
	global_store_dwordx4 v[18:19], v[2:5], off
	v_add_u32_e32 v16, 24, v16
	ds_read2_b32 v[2:3], v21 offset0:24 offset1:57
	v_ashrrev_i32_e32 v17, 31, v16
	s_waitcnt lgkmcnt(0)
	v_cvt_pk_bf16_f32 v2, v2, v3
	ds_read2_b32 v[4:5], v21 offset0:90 offset1:123
	v_lshlrev_b64 v[16:17], 12, v[16:17]
	s_waitcnt lgkmcnt(0)
	v_cvt_pk_bf16_f32 v3, v4, v5
	ds_read2_b32 v[4:5], v21 offset0:156 offset1:189
	v_lshl_add_u64 v[14:15], v[14:15], 0, v[16:17]
	s_waitcnt lgkmcnt(0)
	v_cvt_pk_bf16_f32 v4, v4, v5
	ds_read2_b32 v[18:19], v21 offset0:222 offset1:255
	s_waitcnt lgkmcnt(0)
	v_cvt_pk_bf16_f32 v5, v18, v19
	global_store_dwordx4 v[14:15], v[2:5], off
	s_waitcnt lgkmcnt(0)
	s_andn2_b64 exec, exec, s[16:17]
	s_cbranch_execnz .LBB0_918
.LBB0_919:
	s_or_b64 exec, exec, s[0:1]
	v_mov_b32_e32 v0, s8
	v_add_co_u32_e32 v2, vcc, 0xd0000, v0
	v_mov_b32_e32 v0, s9
	s_nop 0
	v_addc_co_u32_e32 v3, vcc, 0, v0, vcc
	global_load_dwordx2 v[4:5], v[2:3], off offset:72 sc1
	v_cmp_lt_i32_e32 vcc, s41, v50
	global_load_dwordx2 v[2:3], v[2:3], off offset:64 sc1
	s_waitcnt vmcnt(0) lgkmcnt(0)
	v_readfirstlane_b32 s1, v5
	v_readfirstlane_b32 s0, v4
	v_readfirstlane_b32 s13, v3
	v_readfirstlane_b32 s12, v2
	s_and_saveexec_b64 s[6:7], vcc
	s_xor_b64 s[14:15], exec, s[6:7]
	s_cbranch_execz .LBB0_921
	v_lshrrev_b32_e32 v51, 5, v9
	v_and_b32_e32 v0, 31, v7
	v_lshrrev_b32_e32 v52, 3, v9
	v_mul_u32_u24_e32 v54, 0x84, v51
	v_mul_u32_u24_e32 v47, 0x84, v8
	v_mov_b32_e32 v9, v1
	v_or_b32_e32 v55, 8, v52
	v_or_b32_e32 v56, 16, v52
	v_or_b32_e32 v57, 24, v52
	v_mov_b64_e32 v[6:7], v[0:1]

.LBB0_923:
	s_waitcnt vmcnt(0) lgkmcnt(0)
	ds_write2_b32 v58, v10, v11 offset1:66
	ds_write2_b32 v58, v12, v13 offset0:132 offset1:198
	v_add_u32_e32 v10, 0x400, v58
	ds_write2_b32 v10, v14, v15 offset0:8 offset1:74
	ds_write2_b32 v10, v16, v17 offset0:140 offset1:206
	v_add_u32_e32 v10, 0x800, v58
	ds_write2_b32 v10, v18, v19 offset0:16 offset1:82
	ds_write2_b32 v10, v20, v21 offset0:148 offset1:214
	v_add_u32_e32 v10, 0xc00, v58
	ds_write2_b32 v10, v22, v23 offset0:24 offset1:90
	ds_write2_b32 v10, v24, v25 offset0:156 offset1:222
	v_add_u32_e32 v10, 0x1000, v58
	ds_write2_b32 v10, v26, v27 offset0:32 offset1:98
	ds_write2_b32 v10, v28, v29 offset0:164 offset1:230
	v_add_u32_e32 v10, 0x1400, v58
	ds_write2_b32 v10, v30, v31 offset0:40 offset1:106
	ds_write2_b32 v10, v32, v33 offset0:172 offset1:238
	v_add_u32_e32 v10, 0x1800, v58
	ds_write2_b32 v10, v36, v37 offset0:48 offset1:114
	ds_write2_b32 v10, v38, v39 offset0:180 offset1:246
	v_add_u32_e32 v10, 0x1c00, v58
	ds_write2_b32 v10, v42, v43 offset0:56 offset1:122
	ds_write2_b32 v10, v44, v45 offset0:188 offset1:254
	s_waitcnt lgkmcnt(0)
	ds_read2_b32 v[10:11], v48 offset1:33
	s_waitcnt lgkmcnt(0)
	v_cvt_pk_bf16_f32 v10, v10, v11
	ds_read2_b32 v[12:13], v48 offset0:66 offset1:99
	s_waitcnt lgkmcnt(0)
	v_cvt_pk_bf16_f32 v11, v12, v13
	ds_read2_b32 v[12:13], v48 offset0:132 offset1:165
	s_waitcnt lgkmcnt(0)
	v_cvt_pk_bf16_f32 v12, v12, v13
	ds_read2_b32 v[14:15], v48 offset0:198 offset1:231
	v_sub_u32_e32 v16, 0, v5
	s_waitcnt lgkmcnt(0)
	v_cvt_pk_bf16_f32 v13, v14, v15
	v_add3_u32 v14, v52, v49, v16
	v_ashrrev_i32_e32 v5, 31, v4
	v_ashrrev_i32_e32 v15, 31, v14
	v_lshl_add_u64 v[4:5], v[4:5], 1, v[2:3]
	v_lshlrev_b64 v[16:17], 10, v[14:15]
	v_lshl_add_u64 v[16:17], v[4:5], 0, v[16:17]
	global_store_dwordx4 v[16:17], v[10:13], off
	ds_read2_b32 v[10:11], v48 offset0:8 offset1:41
	v_add_u32_e32 v18, 16, v14
	s_waitcnt lgkmcnt(0)
	v_cvt_pk_bf16_f32 v10, v10, v11
	ds_read2_b32 v[12:13], v48 offset0:74 offset1:107
	s_waitcnt lgkmcnt(0)
	v_cvt_pk_bf16_f32 v11, v12, v13
	ds_read2_b32 v[12:13], v48 offset0:140 offset1:173
	s_waitcnt lgkmcnt(0)
	v_cvt_pk_bf16_f32 v12, v12, v13
	ds_read2_b32 v[16:17], v48 offset0:206 offset1:239
	s_waitcnt lgkmcnt(0)
	v_cvt_pk_bf16_f32 v13, v16, v17
	v_add_u32_e32 v16, 8, v14
	v_ashrrev_i32_e32 v17, 31, v16
	v_lshlrev_b64 v[16:17], 10, v[16:17]
	v_lshl_add_u64 v[16:17], v[4:5], 0, v[16:17]
	global_store_dwordx4 v[16:17], v[10:13], off
	ds_read2_b32 v[10:11], v48 offset0:16 offset1:49
	v_ashrrev_i32_e32 v19, 31, v18
	s_waitcnt lgkmcnt(0)
	v_cvt_pk_bf16_f32 v10, v10, v11
	ds_read2_b32 v[12:13], v48 offset0:82 offset1:115
	v_lshlrev_b64 v[18:19], 10, v[18:19]
	s_waitcnt lgkmcnt(0)
	v_cvt_pk_bf16_f32 v11, v12, v13
	ds_read2_b32 v[12:13], v48 offset0:148 offset1:181
	v_lshl_add_u64 v[18:19], v[4:5], 0, v[18:19]
	s_waitcnt lgkmcnt(0)
	v_cvt_pk_bf16_f32 v12, v12, v13
	ds_read2_b32 v[16:17], v48 offset0:214 offset1:247
	s_waitcnt lgkmcnt(0)
	v_cvt_pk_bf16_f32 v13, v16, v17
	global_store_dwordx4 v[18:19], v[10:13], off
	v_add_u32_e32 v14, 24, v14
	ds_read2_b32 v[10:11], v48 offset0:24 offset1:57
	v_ashrrev_i32_e32 v15, 31, v14
	s_waitcnt lgkmcnt(0)
	v_cvt_pk_bf16_f32 v10, v10, v11
	ds_read2_b32 v[12:13], v48 offset0:90 offset1:123
	v_lshlrev_b64 v[14:15], 10, v[14:15]
	s_waitcnt lgkmcnt(0)
	v_cvt_pk_bf16_f32 v11, v12, v13
	ds_read2_b32 v[12:13], v48 offset0:156 offset1:189
	v_lshl_add_u64 v[4:5], v[4:5], 0, v[14:15]
	s_waitcnt lgkmcnt(0)
	v_cvt_pk_bf16_f32 v12, v12, v13
	ds_read2_b32 v[16:17], v48 offset0:222 offset1:255
	s_waitcnt lgkmcnt(0)
	v_cvt_pk_bf16_f32 v13, v16, v17
	global_store_dwordx4 v[4:5], v[10:13], off
	s_waitcnt lgkmcnt(0)
	v_add_u32_e32 v59, s52, v59
	v_cmp_lt_i32_e32 vcc, s41, v59
	s_or_b64 s[16:17], vcc, s[16:17]
	v_add_u32_e32 v49, s3, v49
	s_andn2_b64 exec, exec, s[16:17]
	s_cbranch_execz .LBB0_926
.LBB0_924:
	v_ashrrev_i32_e32 v4, 31, v59
	v_lshrrev_b32_e32 v4, 25, v4
	v_add_u32_e32 v4, v59, v4
	v_ashrrev_i32_e32 v5, 7, v4
	v_lshlrev_b32_e32 v4, 6, v5
	v_or_b32_e32 v34, v4, v51
	v_lshlrev_b32_e32 v5, 12, v5
	v_ashrrev_i32_e32 v35, 31, v34
	v_sub_u32_e32 v10, v49, v5
	v_lshlrev_b64 v[12:13], 14, v[34:35]
	v_lshl_add_u64 v[12:13], s[0:1], 0, v[12:13]
	v_ashrrev_i32_e32 v11, 31, v10
	v_lshl_add_u64 v[10:11], v[10:11], 2, v[12:13]
	v_lshl_add_u64 v[40:41], v[10:11], 0, v[0:1]
	s_mov_b32 s2, 0x8000
	v_add_co_u32_e32 v12, vcc, s2, v40
	global_load_dword v10, v[40:41], off nt
	s_nop 0
	v_addc_co_u32_e32 v13, vcc, 0, v41, vcc
	global_load_dword v11, v[12:13], off nt
	v_add_co_u32_e32 v12, vcc, s56, v40
	s_mov_b32 s2, 0x28000
	s_nop 0
	v_addc_co_u32_e32 v13, vcc, 0, v41, vcc
	v_add_co_u32_e32 v14, vcc, s93, v40
	global_load_dword v12, v[12:13], off nt
	s_nop 0
	v_addc_co_u32_e32 v15, vcc, 0, v41, vcc
	global_load_dword v13, v[14:15], off nt
	v_add_co_u32_e32 v14, vcc, s57, v40
	s_nop 1
	v_addc_co_u32_e32 v15, vcc, 0, v41, vcc
	v_add_co_u32_e32 v16, vcc, s2, v40
	global_load_dword v14, v[14:15], off nt
	s_nop 0
	v_addc_co_u32_e32 v17, vcc, 0, v41, vcc
	global_load_dword v15, v[16:17], off nt
	v_add_co_u32_e32 v16, vcc, s83, v40
	s_mov_b32 s2, 0x40000
	s_nop 0
	v_addc_co_u32_e32 v17, vcc, 0, v41, vcc
	v_add_co_u32_e32 v18, vcc, s40, v40
	global_load_dword v16, v[16:17], off nt
	s_nop 0
	v_addc_co_u32_e32 v19, vcc, 0, v41, vcc
	global_load_dword v17, v[18:19], off nt
	v_add_co_u32_e32 v18, vcc, s2, v40
	s_mov_b32 s2, 0x80000
	s_nop 0
	v_addc_co_u32_e32 v19, vcc, 0, v41, vcc
	v_add_co_u32_e32 v20, vcc, s80, v40
	global_load_dword v18, v[18:19], off nt
	s_nop 0
	v_addc_co_u32_e32 v21, vcc, 0, v41, vcc
	global_load_dword v19, v[20:21], off nt
	v_add_co_u32_e32 v20, vcc, s6, v40
	s_nop 1
	v_addc_co_u32_e32 v21, vcc, 0, v41, vcc
	v_add_co_u32_e32 v22, vcc, s10, v40
	global_load_dword v20, v[20:21], off nt
	s_nop 0
	v_addc_co_u32_e32 v23, vcc, 0, v41, vcc
	global_load_dword v21, v[22:23], off nt
	v_add_co_u32_e32 v22, vcc, s86, v40
	s_nop 1
	v_addc_co_u32_e32 v23, vcc, 0, v41, vcc
	v_add_co_u32_e32 v24, vcc, s11, v40
	global_load_dword v22, v[22:23], off nt
	s_nop 0
	v_addc_co_u32_e32 v25, vcc, 0, v41, vcc
	global_load_dword v23, v[24:25], off nt
	v_add_co_u32_e32 v24, vcc, s7, v40
	s_nop 1
	v_addc_co_u32_e32 v25, vcc, 0, v41, vcc
	v_add_co_u32_e32 v26, vcc, s88, v40
	global_load_dword v24, v[24:25], off nt
	s_nop 0
	v_addc_co_u32_e32 v27, vcc, 0, v41, vcc
	global_load_dword v25, v[26:27], off nt
	v_add_co_u32_e32 v26, vcc, s2, v40
	s_mov_b32 s2, 0x88000
	s_nop 0
	v_addc_co_u32_e32 v27, vcc, 0, v41, vcc
	v_add_co_u32_e32 v28, vcc, s2, v40
	s_mov_b32 s2, 0x90000
	s_nop 0
	v_addc_co_u32_e32 v29, vcc, 0, v41, vcc
	global_load_dword v26, v[26:27], off nt
	s_nop 0
	global_load_dword v27, v[28:29], off nt
	v_add_co_u32_e32 v28, vcc, s2, v40
	s_mov_b32 s2, 0x98000
	s_nop 0
	v_addc_co_u32_e32 v29, vcc, 0, v41, vcc
	v_add_co_u32_e32 v30, vcc, s2, v40
	s_mov_b32 s2, 0xa0000
	s_nop 0
	v_addc_co_u32_e32 v31, vcc, 0, v41, vcc
	global_load_dword v28, v[28:29], off nt
	s_nop 0
	global_load_dword v29, v[30:31], off nt
	v_add_co_u32_e32 v30, vcc, s2, v40
	s_mov_b32 s2, 0xb0000
	s_nop 0
	v_addc_co_u32_e32 v31, vcc, 0, v41, vcc
	v_add_co_u32_e32 v32, vcc, s36, v40
	global_load_dword v30, v[30:31], off nt
	s_nop 0
	v_addc_co_u32_e32 v33, vcc, 0, v41, vcc
	global_load_dword v31, v[32:33], off nt
	v_add_co_u32_e32 v32, vcc, s2, v40
	s_mov_b32 s2, 0xb8000
	s_nop 0
	v_addc_co_u32_e32 v33, vcc, 0, v41, vcc
	v_add_co_u32_e32 v36, vcc, s2, v40
	s_mov_b32 s2, 0xc0000
	s_nop 0
	v_addc_co_u32_e32 v37, vcc, 0, v41, vcc
	global_load_dword v32, v[32:33], off nt
	s_nop 0
	global_load_dword v33, v[36:37], off nt
	v_add_co_u32_e32 v36, vcc, s2, v40
	s_mov_b32 s2, 0xc8000
	s_nop 0
	v_addc_co_u32_e32 v37, vcc, 0, v41, vcc
	v_add_co_u32_e32 v38, vcc, s2, v40
	s_mov_b32 s2, 0xd0000
	s_nop 0
	v_addc_co_u32_e32 v39, vcc, 0, v41, vcc
	global_load_dword v36, v[36:37], off nt
	s_nop 0
	global_load_dword v37, v[38:39], off nt
	v_add_co_u32_e32 v38, vcc, s2, v40
	s_mov_b32 s2, 0xe0000
	s_nop 0
	v_addc_co_u32_e32 v39, vcc, 0, v41, vcc
	v_add_co_u32_e32 v42, vcc, 0xd8000, v40
	global_load_dword v38, v[38:39], off nt
	s_nop 0
	v_addc_co_u32_e32 v43, vcc, 0, v41, vcc
	global_load_dword v39, v[42:43], off nt
	v_add_co_u32_e32 v42, vcc, s2, v40
	s_nop 1
	v_addc_co_u32_e32 v43, vcc, 0, v41, vcc
	v_add_co_u32_e32 v44, vcc, 0xe8000, v40
	global_load_dword v42, v[42:43], off nt
	s_nop 0
	v_addc_co_u32_e32 v45, vcc, 0, v41, vcc
	global_load_dword v43, v[44:45], off nt
	v_add_co_u32_e32 v44, vcc, 0xf0000, v40
	s_nop 1
	v_addc_co_u32_e32 v45, vcc, 0, v41, vcc
	v_add_co_u32_e32 v40, vcc, 0xf8000, v40
	global_load_dword v44, v[44:45], off nt
	s_nop 0
	v_addc_co_u32_e32 v41, vcc, 0, v41, vcc
	global_load_dword v45, v[40:41], off nt
	s_andn2_b64 vcc, exec, s[18:19]
	s_cbranch_vccnz .LBB0_923
	v_lshl_add_u64 v[34:35], v[34:35], 2, s[12:13]
	global_load_dword v40, v[34:35], off
	global_load_dword v41, v[34:35], off offset:8
	global_load_dword v60, v[34:35], off offset:16
	global_load_dword v61, v[34:35], off offset:24
	global_load_dword v62, v[34:35], off offset:32
	global_load_dword v63, v[34:35], off offset:40
	global_load_dword v64, v[34:35], off offset:48
	global_load_dword v65, v[34:35], off offset:56
	global_load_dword v66, v[34:35], off offset:64
	global_load_dword v67, v[34:35], off offset:72
	global_load_dword v68, v[34:35], off offset:80
	global_load_dword v69, v[34:35], off offset:88
	global_load_dword v70, v[34:35], off offset:96
	global_load_dword v71, v[34:35], off offset:104
	global_load_dword v72, v[34:35], off offset:112
	global_load_dword v73, v[34:35], off offset:120
	global_load_dword v74, v[34:35], off offset:128
	global_load_dword v75, v[34:35], off offset:136
	global_load_dword v76, v[34:35], off offset:144
	global_load_dword v77, v[34:35], off offset:152
	global_load_dword v78, v[34:35], off offset:160
	global_load_dword v79, v[34:35], off offset:168
	global_load_dword v80, v[34:35], off offset:176
	global_load_dword v81, v[34:35], off offset:184
	global_load_dword v82, v[34:35], off offset:192
	global_load_dword v83, v[34:35], off offset:200
	global_load_dword v84, v[34:35], off offset:208
	global_load_dword v85, v[34:35], off offset:216
	global_load_dword v86, v[34:35], off offset:224
	global_load_dword v87, v[34:35], off offset:232
	global_load_dword v88, v[34:35], off offset:240
	global_load_dword v89, v[34:35], off offset:248
	s_waitcnt vmcnt(0) lgkmcnt(0)
	v_pk_mul_f32 v[10:11], v[10:11], v[40:41]
	v_pk_mul_f32 v[12:13], v[12:13], v[60:61]
	v_pk_mul_f32 v[14:15], v[14:15], v[62:63]
	v_pk_mul_f32 v[16:17], v[16:17], v[64:65]
	v_pk_mul_f32 v[18:19], v[18:19], v[66:67]
	v_pk_mul_f32 v[20:21], v[20:21], v[68:69]
	v_pk_mul_f32 v[22:23], v[22:23], v[70:71]
	v_pk_mul_f32 v[24:25], v[24:25], v[72:73]
	v_pk_mul_f32 v[26:27], v[26:27], v[74:75]
	v_pk_mul_f32 v[28:29], v[28:29], v[76:77]
	v_pk_mul_f32 v[30:31], v[30:31], v[78:79]
	v_pk_mul_f32 v[32:33], v[32:33], v[80:81]
	v_pk_mul_f32 v[36:37], v[36:37], v[82:83]
	v_pk_mul_f32 v[38:39], v[38:39], v[84:85]
	v_pk_mul_f32 v[42:43], v[42:43], v[86:87]
	v_pk_mul_f32 v[44:45], v[44:45], v[88:89]
	s_branch .LBB0_923

.LBB0_929:
	v_mov_b64_e32 v[2:3], s[0:1]
	global_load_dwordx2 v[2:3], v[2:3], off sc1
	s_waitcnt vmcnt(0) lgkmcnt(0)
	v_readfirstlane_b32 s2, v3
	v_readfirstlane_b32 s6, v2
	v_mov_b64_e32 v[2:3], s[12:13]
	global_load_dwordx2 v[2:3], v[2:3], off sc1
	s_waitcnt vmcnt(0) lgkmcnt(0)
	v_readfirstlane_b32 s45, v3
	v_readfirstlane_b32 s44, v2
	s_and_saveexec_b64 s[16:17], s[38:39]
	s_movk_i32 s48, 0x3000
	s_mov_b32 s49, 0x2a000
	s_mov_b32 s53, 0x36000
	s_mov_b32 s61, 0x42000
	s_mov_b32 s66, 0x4e000
	s_cbranch_execz .LBB0_938
	s_mul_i32 s7, s54, 0x1200000
	s_add_u32 s18, s6, s7
	s_mul_i32 s6, s54, 0x600
	s_mov_b32 s7, s55
	s_addc_u32 s19, s2, 0
	s_lshl_b64 s[6:7], s[6:7], 2
	s_add_u32 s30, s44, s6
	s_addc_u32 s31, s45, s7
	s_mul_i32 s6, s54, 0x900000
	s_mov_b32 s7, s55
	s_cmp_lg_u64 s[44:45], 0
	s_mov_b64 s[42:43], 0
	s_cselect_b64 s[44:45], -1, 0
	v_lshl_add_u64 v[2:3], v[8:9], 0, s[6:7]
	v_lshlrev_b32_e32 v0, 5, v50
	v_mov_b32_e32 v4, v50
	s_branch .LBB0_932
.LBB0_931:
	s_or_b64 exec, exec, s[46:47]
	v_ashrrev_i32_e32 v13, 31, v12
	v_lshl_add_u64 v[16:17], v[12:13], 1, v[2:3]
	ds_read2_b32 v[12:13], v59 offset1:33
	s_waitcnt lgkmcnt(0)
	v_cvt_pk_bf16_f32 v12, v12, v13
	ds_read2_b32 v[14:15], v59 offset0:66 offset1:99
	s_waitcnt lgkmcnt(0)
	v_cvt_pk_bf16_f32 v13, v14, v15
	ds_read2_b32 v[14:15], v59 offset0:132 offset1:165
	s_waitcnt lgkmcnt(0)
	v_cvt_pk_bf16_f32 v14, v14, v15
	ds_read2_b32 v[18:19], v59 offset0:198 offset1:231
	s_waitcnt lgkmcnt(0)
	v_cvt_pk_bf16_f32 v15, v18, v19
	v_add_u32_e32 v18, v5, v52
	v_mul_i32_i24_e32 v18, 0x600, v18
	v_ashrrev_i32_e32 v19, 31, v18
	v_lshl_add_u64 v[18:19], v[18:19], 1, v[16:17]
	global_store_dwordx4 v[18:19], v[12:15], off
	ds_read2_b32 v[12:13], v60 offset1:33
	v_add_u32_e32 v4, s52, v4
	s_waitcnt lgkmcnt(0)
	v_cvt_pk_bf16_f32 v12, v12, v13
	ds_read2_b32 v[14:15], v60 offset0:66 offset1:99
	s_waitcnt lgkmcnt(0)
	v_cvt_pk_bf16_f32 v13, v14, v15
	ds_read2_b32 v[14:15], v60 offset0:132 offset1:165
	s_waitcnt lgkmcnt(0)
	v_cvt_pk_bf16_f32 v14, v14, v15
	ds_read2_b32 v[18:19], v60 offset0:198 offset1:231
	s_waitcnt lgkmcnt(0)
	v_cvt_pk_bf16_f32 v15, v18, v19
	v_add_u32_e32 v18, v5, v55
	v_mul_i32_i24_e32 v18, 0x600, v18
	v_ashrrev_i32_e32 v19, 31, v18
	v_lshl_add_u64 v[18:19], v[18:19], 1, v[16:17]
	global_store_dwordx4 v[18:19], v[12:15], off
	ds_read2_b32 v[12:13], v61 offset1:33
	s_movk_i32 s2, 0x8ff
	s_waitcnt lgkmcnt(0)
	v_cvt_pk_bf16_f32 v12, v12, v13
	ds_read2_b32 v[14:15], v61 offset0:66 offset1:99
	s_waitcnt lgkmcnt(0)
	v_cvt_pk_bf16_f32 v13, v14, v15
	ds_read2_b32 v[14:15], v61 offset0:132 offset1:165
	s_waitcnt lgkmcnt(0)
	v_cvt_pk_bf16_f32 v14, v14, v15
	ds_read2_b32 v[18:19], v61 offset0:198 offset1:231
	s_waitcnt lgkmcnt(0)
	v_cvt_pk_bf16_f32 v15, v18, v19
	v_add_u32_e32 v18, v5, v56
	v_mul_i32_i24_e32 v18, 0x600, v18
	v_ashrrev_i32_e32 v19, 31, v18
	v_lshl_add_u64 v[18:19], v[18:19], 1, v[16:17]
	global_store_dwordx4 v[18:19], v[12:15], off
	ds_read2_b32 v[12:13], v62 offset1:33
	v_add_u32_e32 v5, v5, v57
	s_waitcnt lgkmcnt(0)
	v_cvt_pk_bf16_f32 v12, v12, v13
	ds_read2_b32 v[14:15], v62 offset0:66 offset1:99
	s_waitcnt lgkmcnt(0)
	v_cvt_pk_bf16_f32 v13, v14, v15
	ds_read2_b32 v[14:15], v62 offset0:132 offset1:165
	s_waitcnt lgkmcnt(0)
	v_cvt_pk_bf16_f32 v14, v14, v15
	ds_read2_b32 v[18:19], v62 offset0:198 offset1:231
	s_waitcnt lgkmcnt(0)
	v_cvt_pk_bf16_f32 v15, v18, v19
	v_mul_i32_i24_e32 v18, 0x600, v5
	v_ashrrev_i32_e32 v19, 31, v18
	v_lshl_add_u64 v[16:17], v[18:19], 1, v[16:17]
	global_store_dwordx4 v[16:17], v[12:15], off
	s_waitcnt lgkmcnt(0)
	v_cmp_lt_i32_e32 vcc, s2, v4
	v_add_u32_e32 v0, s3, v0
	s_or_b64 s[42:43], vcc, s[42:43]
	s_andn2_b64 exec, exec, s[42:43]
	s_cbranch_execz .LBB0_938
.LBB0_932:
	v_mul_hi_i32 v5, v4, s81
	v_lshrrev_b32_e32 v12, 31, v5
	v_ashrrev_i32_e32 v5, 4, v5
	v_add_u32_e32 v5, v5, v12
	v_lshlrev_b32_e32 v12, 6, v5
	s_movk_i32 s2, 0xf400
	v_mad_u64_u32 v[14:15], s[6:7], v5, s2, v[0:1]
	v_or_b32_e32 v40, v12, v51
	v_mov_b64_e32 v[16:17], s[18:19]
	v_mad_i64_i32 v[16:17], s[6:7], v40, s48, v[16:17]
	v_ashrrev_i32_e32 v15, 31, v14
	v_lshl_add_u64 v[14:15], v[14:15], 2, v[16:17]
	v_lshl_add_u64 v[46:47], v[6:7], 2, v[14:15]
	v_add_co_u32_e32 v16, vcc, s75, v46
	global_load_dword v14, v[46:47], off nt
	s_nop 0
	v_addc_co_u32_e32 v17, vcc, 0, v47, vcc
	global_load_dword v15, v[16:17], off nt
	v_add_co_u32_e32 v16, vcc, s91, v46
	s_mov_b32 s2, 0x66000
	s_nop 0
	v_addc_co_u32_e32 v17, vcc, 0, v47, vcc
	v_add_co_u32_e32 v18, vcc, s74, v46
	global_load_dword v16, v[16:17], off nt
	s_nop 0
	v_addc_co_u32_e32 v19, vcc, 0, v47, vcc
	global_load_dword v17, v[18:19], off nt
	v_add_co_u32_e32 v18, vcc, s93, v46
	s_nop 1
	v_addc_co_u32_e32 v19, vcc, 0, v47, vcc
	v_add_co_u32_e32 v20, vcc, s72, v46
	global_load_dword v18, v[18:19], off nt
	s_nop 0
	v_addc_co_u32_e32 v21, vcc, 0, v47, vcc
	global_load_dword v19, v[20:21], off nt
	v_add_co_u32_e32 v20, vcc, s95, v46
	s_nop 1
	v_addc_co_u32_e32 v21, vcc, 0, v47, vcc
	v_add_co_u32_e32 v22, vcc, s49, v46
	global_load_dword v20, v[20:21], off nt
	s_nop 0
	v_addc_co_u32_e32 v23, vcc, 0, v47, vcc
	global_load_dword v21, v[22:23], off nt
	v_add_co_u32_e32 v22, vcc, s83, v46
	s_nop 1
	v_addc_co_u32_e32 v23, vcc, 0, v47, vcc
	v_add_co_u32_e32 v24, vcc, s53, v46
	global_load_dword v22, v[22:23], off nt
	s_nop 0
	v_addc_co_u32_e32 v25, vcc, 0, v47, vcc
	global_load_dword v23, v[24:25], off nt
	v_add_co_u32_e32 v24, vcc, s33, v46
	s_nop 1
	v_addc_co_u32_e32 v25, vcc, 0, v47, vcc
	v_add_co_u32_e32 v26, vcc, s61, v46
	global_load_dword v24, v[24:25], off nt
	s_nop 0
	v_addc_co_u32_e32 v27, vcc, 0, v47, vcc
	global_load_dword v25, v[26:27], off nt
	v_add_co_u32_e32 v26, vcc, s80, v46
	s_nop 1
	v_addc_co_u32_e32 v27, vcc, 0, v47, vcc
	v_add_co_u32_e32 v28, vcc, s66, v46
	global_load_dword v26, v[26:27], off nt
	s_nop 0
	v_addc_co_u32_e32 v29, vcc, 0, v47, vcc
	global_load_dword v27, v[28:29], off nt
	v_add_co_u32_e32 v28, vcc, s97, v46
	s_nop 1
	v_addc_co_u32_e32 v29, vcc, 0, v47, vcc
	v_add_co_u32_e32 v30, vcc, s73, v46
	global_load_dword v28, v[28:29], off nt
	s_nop 0
	v_addc_co_u32_e32 v31, vcc, 0, v47, vcc
	global_load_dword v29, v[30:31], off nt
	v_add_co_u32_e32 v30, vcc, s86, v46
	s_nop 1
	v_addc_co_u32_e32 v31, vcc, 0, v47, vcc
	v_add_co_u32_e32 v32, vcc, s2, v46
	global_load_dword v30, v[30:31], off nt
	s_nop 0
	v_addc_co_u32_e32 v33, vcc, 0, v47, vcc
	global_load_dword v31, v[32:33], off nt
	v_add_co_u32_e32 v32, vcc, s94, v46
	s_mov_b32 s2, 0x72000
	s_nop 0
	v_addc_co_u32_e32 v33, vcc, 0, v47, vcc
	v_add_co_u32_e32 v34, vcc, s2, v46
	global_load_dword v32, v[32:33], off nt
	s_nop 0
	v_addc_co_u32_e32 v35, vcc, 0, v47, vcc
	global_load_dword v33, v[34:35], off nt
	v_add_co_u32_e32 v34, vcc, s88, v46
	s_mov_b32 s2, 0x7e000
	s_nop 0
	v_addc_co_u32_e32 v35, vcc, 0, v47, vcc
	v_add_co_u32_e32 v36, vcc, s2, v46
	s_mov_b32 s2, 0x84000
	s_nop 0
	v_addc_co_u32_e32 v37, vcc, 0, v47, vcc
	global_load_dword v34, v[34:35], off nt
	s_nop 0
	global_load_dword v35, v[36:37], off nt
	v_add_co_u32_e32 v36, vcc, s2, v46
	s_mov_b32 s2, 0x8a000
	s_nop 0
	v_addc_co_u32_e32 v37, vcc, 0, v47, vcc
	v_add_co_u32_e32 v38, vcc, s2, v46
	s_mov_b32 s2, 0x90000
	s_nop 0
	v_addc_co_u32_e32 v39, vcc, 0, v47, vcc
	global_load_dword v36, v[36:37], off nt
	s_nop 0
	global_load_dword v37, v[38:39], off nt
	v_add_co_u32_e32 v38, vcc, s2, v46
	s_mov_b32 s2, 0x96000
	s_nop 0
	v_addc_co_u32_e32 v39, vcc, 0, v47, vcc
	v_add_co_u32_e32 v42, vcc, s2, v46
	s_mov_b32 s2, 0x9c000
	s_nop 0
	v_addc_co_u32_e32 v43, vcc, 0, v47, vcc
	global_load_dword v38, v[38:39], off nt
	s_nop 0
	global_load_dword v39, v[42:43], off nt
	v_add_co_u32_e32 v42, vcc, s2, v46
	s_mov_b32 s2, 0xa2000
	s_nop 0
	v_addc_co_u32_e32 v43, vcc, 0, v47, vcc
	v_add_co_u32_e32 v44, vcc, s2, v46
	global_load_dword v42, v[42:43], off nt
	s_nop 0
	v_addc_co_u32_e32 v45, vcc, 0, v47, vcc
	global_load_dword v43, v[44:45], off nt
	v_add_co_u32_e32 v44, vcc, s36, v46
	s_nop 1
	v_addc_co_u32_e32 v45, vcc, 0, v47, vcc
	v_add_co_u32_e32 v48, vcc, 0xae000, v46
	global_load_dword v44, v[44:45], off nt
	s_nop 0
	v_addc_co_u32_e32 v49, vcc, 0, v47, vcc
	global_load_dword v45, v[48:49], off nt
	v_add_co_u32_e32 v48, vcc, 0xb4000, v46
	s_nop 1
	v_addc_co_u32_e32 v49, vcc, 0, v47, vcc
	v_add_co_u32_e32 v46, vcc, 0xba000, v46
	global_load_dword v48, v[48:49], off nt
	s_nop 0
	v_addc_co_u32_e32 v47, vcc, 0, v47, vcc
	global_load_dword v49, v[46:47], off nt
	s_andn2_b64 vcc, exec, s[44:45]
	s_cbranch_vccnz .LBB0_934
	v_ashrrev_i32_e32 v41, 31, v40
	v_lshl_add_u64 v[40:41], v[40:41], 2, s[30:31]
	global_load_dword v46, v[40:41], off
	global_load_dword v47, v[40:41], off offset:8
	global_load_dword v64, v[40:41], off offset:16
	global_load_dword v65, v[40:41], off offset:24
	global_load_dword v66, v[40:41], off offset:32
	global_load_dword v67, v[40:41], off offset:40
	global_load_dword v68, v[40:41], off offset:48
	global_load_dword v69, v[40:41], off offset:56
	global_load_dword v70, v[40:41], off offset:64
	global_load_dword v71, v[40:41], off offset:72
	global_load_dword v72, v[40:41], off offset:80
	global_load_dword v73, v[40:41], off offset:88
	global_load_dword v74, v[40:41], off offset:96
	global_load_dword v75, v[40:41], off offset:104
	global_load_dword v76, v[40:41], off offset:112
	global_load_dword v77, v[40:41], off offset:120
	global_load_dword v78, v[40:41], off offset:128
	global_load_dword v79, v[40:41], off offset:136
	global_load_dword v80, v[40:41], off offset:144
	global_load_dword v81, v[40:41], off offset:152
	global_load_dword v82, v[40:41], off offset:160
	global_load_dword v83, v[40:41], off offset:168
	global_load_dword v84, v[40:41], off offset:176
	global_load_dword v85, v[40:41], off offset:184
	global_load_dword v86, v[40:41], off offset:192
	global_load_dword v87, v[40:41], off offset:200
	global_load_dword v88, v[40:41], off offset:208
	global_load_dword v89, v[40:41], off offset:216
	global_load_dword v90, v[40:41], off offset:224
	global_load_dword v91, v[40:41], off offset:232
	global_load_dword v92, v[40:41], off offset:240
	global_load_dword v93, v[40:41], off offset:248
	s_waitcnt vmcnt(0) lgkmcnt(0)
	v_pk_mul_f32 v[14:15], v[14:15], v[46:47]
	v_pk_mul_f32 v[16:17], v[16:17], v[64:65]
	v_pk_mul_f32 v[18:19], v[18:19], v[66:67]
	v_pk_mul_f32 v[20:21], v[20:21], v[68:69]
	v_pk_mul_f32 v[22:23], v[22:23], v[70:71]
	v_pk_mul_f32 v[24:25], v[24:25], v[72:73]
	v_pk_mul_f32 v[26:27], v[26:27], v[74:75]
	v_pk_mul_f32 v[28:29], v[28:29], v[76:77]
	v_pk_mul_f32 v[30:31], v[30:31], v[78:79]
	v_pk_mul_f32 v[32:33], v[32:33], v[80:81]
	v_pk_mul_f32 v[34:35], v[34:35], v[82:83]
	v_pk_mul_f32 v[36:37], v[36:37], v[84:85]
	v_pk_mul_f32 v[38:39], v[38:39], v[86:87]
	v_pk_mul_f32 v[42:43], v[42:43], v[88:89]
	v_pk_mul_f32 v[44:45], v[44:45], v[90:91]
	v_pk_mul_f32 v[48:49], v[48:49], v[92:93]

.LBB0_938:
	s_or_b64 exec, exec, s[16:17]
	v_mov_b64_e32 v[2:3], s[8:9]
	global_load_dwordx2 v[2:3], v[2:3], off sc1
	s_xor_b64 s[14:15], s[14:15], -1
	s_waitcnt vmcnt(0) lgkmcnt(0)
	v_readfirstlane_b32 s2, v3
	v_readfirstlane_b32 s6, v2
	s_and_saveexec_b64 s[16:17], s[40:41]
	s_mov_b32 s42, 0x40000
	s_mov_b32 s43, 0x50000
	s_mov_b32 s44, 0x70000
	s_movk_i32 s45, 0x4000
	s_mov_b32 s46, 0x8000
	s_mov_b32 s47, 0x14000
	s_mov_b32 s48, 0x1c000
	s_mov_b32 s49, 0x28000
	s_mov_b32 s53, 0x2c000
	s_mov_b32 s61, 0x34000
	s_mov_b32 s66, 0x38000
	s_mov_b32 s67, 0x44000
	s_mov_b32 s71, 0x4c000
	s_mov_b32 s78, 0x58000
	s_mov_b32 s79, 0x5c000
	s_mov_b32 s92, 0x64000
	s_mov_b32 s90, 0x68000
	s_mov_b32 s82, 0x74000
	s_mov_b32 s72, 0x7c000
	s_cbranch_execz .LBB0_928
	s_lshl_b64 s[10:11], s[54:55], 24
	s_add_u32 s18, s6, s10
	s_addc_u32 s19, s2, s11
	s_lshl_b64 s[6:7], s[54:55], 23
	v_lshl_add_u64 v[12:13], v[10:11], 0, s[6:7]
	s_mov_b64 s[30:31], 0
	v_mov_b32_e32 v0, v53
	v_mov_b32_e32 v18, v50
.LBB0_940:
	v_ashrrev_i32_e32 v2, 31, v18
	v_lshrrev_b32_e32 v2, 26, v2
	v_add_u32_e32 v3, v18, v2
	v_and_b32_e32 v2, 0xffffffc0, v3
	v_lshlrev_b32_e32 v3, 5, v3
	v_or_b32_e32 v4, v2, v51
	v_and_b32_e32 v3, 0xfffff800, v3
	v_ashrrev_i32_e32 v5, 31, v4
	v_sub_u32_e32 v14, v0, v3
	v_lshlrev_b64 v[4:5], 13, v[4:5]
	v_lshl_add_u64 v[4:5], s[18:19], 0, v[4:5]
	v_ashrrev_i32_e32 v15, 31, v14
	v_lshl_add_u64 v[4:5], v[14:15], 2, v[4:5]
	v_lshl_add_u64 v[4:5], v[6:7], 2, v[4:5]
	v_add_co_u32_e32 v16, vcc, s45, v4
	global_load_dword v3, v[4:5], off nt
	s_nop 0
	v_addc_co_u32_e32 v17, vcc, 0, v5, vcc
	global_load_dword v15, v[16:17], off nt
	v_add_co_u32_e32 v16, vcc, s46, v4
	v_add_u32_e32 v18, s52, v18
	s_nop 0
	v_addc_co_u32_e32 v17, vcc, 0, v5, vcc
	global_load_dword v19, v[16:17], off nt
	v_add_co_u32_e32 v16, vcc, s91, v4
	s_movk_i32 s2, 0x7ff
	s_nop 0
	v_addc_co_u32_e32 v17, vcc, 0, v5, vcc
	global_load_dword v20, v[16:17], off nt
	v_add_co_u32_e32 v16, vcc, s56, v4
	v_add_u32_e32 v0, s3, v0
	s_nop 0
	v_addc_co_u32_e32 v17, vcc, 0, v5, vcc
	global_load_dword v21, v[16:17], off nt
	v_add_co_u32_e32 v16, vcc, s47, v4
	s_nop 1
	v_addc_co_u32_e32 v17, vcc, 0, v5, vcc
	global_load_dword v22, v[16:17], off nt
	v_add_co_u32_e32 v16, vcc, s93, v4
	s_nop 1
	v_addc_co_u32_e32 v17, vcc, 0, v5, vcc
	global_load_dword v23, v[16:17], off nt
	v_add_co_u32_e32 v16, vcc, s48, v4
	s_nop 1
	v_addc_co_u32_e32 v17, vcc, 0, v5, vcc
	global_load_dword v24, v[16:17], off nt
	v_add_co_u32_e32 v16, vcc, s57, v4
	s_nop 1
	v_addc_co_u32_e32 v17, vcc, 0, v5, vcc
	global_load_dword v25, v[16:17], off nt
	v_add_co_u32_e32 v16, vcc, s95, v4
	s_nop 1
	v_addc_co_u32_e32 v17, vcc, 0, v5, vcc
	global_load_dword v26, v[16:17], off nt
	v_add_co_u32_e32 v16, vcc, s49, v4
	s_nop 1
	v_addc_co_u32_e32 v17, vcc, 0, v5, vcc
	global_load_dword v27, v[16:17], off nt
	v_add_co_u32_e32 v16, vcc, s53, v4
	s_nop 1
	v_addc_co_u32_e32 v17, vcc, 0, v5, vcc
	global_load_dword v28, v[16:17], off nt
	v_add_co_u32_e32 v16, vcc, s83, v4
	s_nop 1
	v_addc_co_u32_e32 v17, vcc, 0, v5, vcc
	global_load_dword v29, v[16:17], off nt
	v_add_co_u32_e32 v16, vcc, s61, v4
	s_nop 1
	v_addc_co_u32_e32 v17, vcc, 0, v5, vcc
	global_load_dword v30, v[16:17], off nt
	v_add_co_u32_e32 v16, vcc, s66, v4
	s_nop 1
	v_addc_co_u32_e32 v17, vcc, 0, v5, vcc
	global_load_dword v31, v[16:17], off nt
	v_add_co_u32_e32 v16, vcc, s33, v4
	s_nop 1
	v_addc_co_u32_e32 v17, vcc, 0, v5, vcc
	global_load_dword v32, v[16:17], off nt
	v_add_co_u32_e32 v16, vcc, s42, v4
	s_nop 1
	v_addc_co_u32_e32 v17, vcc, 0, v5, vcc
	global_load_dword v33, v[16:17], off nt
	v_add_co_u32_e32 v16, vcc, s67, v4
	s_nop 1
	v_addc_co_u32_e32 v17, vcc, 0, v5, vcc
	global_load_dword v34, v[16:17], off nt
	v_add_co_u32_e32 v16, vcc, s80, v4
	s_nop 1
	v_addc_co_u32_e32 v17, vcc, 0, v5, vcc
	global_load_dword v35, v[16:17], off nt
	v_add_co_u32_e32 v16, vcc, s71, v4
	s_nop 1
	v_addc_co_u32_e32 v17, vcc, 0, v5, vcc
	global_load_dword v36, v[16:17], off nt
	v_add_co_u32_e32 v16, vcc, s43, v4
	s_nop 1
	v_addc_co_u32_e32 v17, vcc, 0, v5, vcc
	global_load_dword v37, v[16:17], off nt
	v_add_co_u32_e32 v16, vcc, s97, v4
	s_nop 1
	v_addc_co_u32_e32 v17, vcc, 0, v5, vcc
	global_load_dword v38, v[16:17], off nt
	v_add_co_u32_e32 v16, vcc, s78, v4
	s_nop 1
	v_addc_co_u32_e32 v17, vcc, 0, v5, vcc
	global_load_dword v39, v[16:17], off nt
	v_add_co_u32_e32 v16, vcc, s79, v4
	s_nop 1
	v_addc_co_u32_e32 v17, vcc, 0, v5, vcc
	global_load_dword v40, v[16:17], off nt
	v_add_co_u32_e32 v16, vcc, s86, v4
	s_nop 1
	v_addc_co_u32_e32 v17, vcc, 0, v5, vcc
	global_load_dword v41, v[16:17], off nt
	v_add_co_u32_e32 v16, vcc, s92, v4
	s_nop 1
	v_addc_co_u32_e32 v17, vcc, 0, v5, vcc
	global_load_dword v42, v[16:17], off nt
	v_add_co_u32_e32 v16, vcc, s90, v4
	s_nop 1
	v_addc_co_u32_e32 v17, vcc, 0, v5, vcc
	global_load_dword v43, v[16:17], off nt
	v_add_co_u32_e32 v16, vcc, s94, v4
	s_nop 1
	v_addc_co_u32_e32 v17, vcc, 0, v5, vcc
	global_load_dword v44, v[16:17], off nt
	v_add_co_u32_e32 v16, vcc, s44, v4
	s_nop 1
	v_addc_co_u32_e32 v17, vcc, 0, v5, vcc
	global_load_dword v45, v[16:17], off nt
	v_add_co_u32_e32 v16, vcc, s82, v4
	s_nop 1
	v_addc_co_u32_e32 v17, vcc, 0, v5, vcc
	global_load_dword v46, v[16:17], off nt
	v_add_co_u32_e32 v16, vcc, s88, v4
	s_nop 1
	v_addc_co_u32_e32 v17, vcc, 0, v5, vcc
	v_add_co_u32_e32 v4, vcc, s72, v4
	global_load_dword v16, v[16:17], off nt
	s_nop 0
	v_addc_co_u32_e32 v5, vcc, 0, v5, vcc
	global_load_dword v4, v[4:5], off nt
	v_add_u32_e32 v5, v58, v54
	s_waitcnt vmcnt(0) lgkmcnt(0)
	ds_write2_b32 v5, v3, v15 offset1:66
	ds_write2_b32 v5, v19, v20 offset0:132 offset1:198
	v_add_u32_e32 v3, 0x400, v5
	ds_write2_b32 v3, v21, v22 offset0:8 offset1:74
	ds_write2_b32 v3, v23, v24 offset0:140 offset1:206
	v_add_u32_e32 v3, 0x800, v5
	ds_write2_b32 v3, v25, v26 offset0:16 offset1:82
	ds_write2_b32 v3, v27, v28 offset0:148 offset1:214
	v_add_u32_e32 v3, 0xc00, v5
	ds_write2_b32 v3, v29, v30 offset0:24 offset1:90
	ds_write2_b32 v3, v31, v32 offset0:156 offset1:222
	v_add_u32_e32 v3, 0x1000, v5
	ds_write2_b32 v3, v33, v34 offset0:32 offset1:98
	ds_write2_b32 v3, v35, v36 offset0:164 offset1:230
	v_add_u32_e32 v3, 0x1400, v5
	ds_write2_b32 v3, v37, v38 offset0:40 offset1:106
	ds_write2_b32 v3, v39, v40 offset0:172 offset1:238
	v_add_u32_e32 v3, 0x1800, v5
	ds_write2_b32 v3, v41, v42 offset0:48 offset1:114
	ds_write2_b32 v3, v43, v44 offset0:180 offset1:246
	v_add_u32_e32 v3, 0x1c00, v5
	ds_write2_b32 v3, v45, v46 offset0:56 offset1:122
	ds_write2_b32 v3, v16, v4 offset0:188 offset1:254
	s_waitcnt lgkmcnt(0)
	v_ashrrev_i32_e32 v3, 31, v2
	v_lshl_add_u64 v[16:17], v[2:3], 1, v[12:13]
	ds_read2_b32 v[2:3], v59 offset1:33
	s_waitcnt lgkmcnt(0)
	v_cvt_pk_bf16_f32 v2, v2, v3
	ds_read2_b32 v[4:5], v59 offset0:66 offset1:99
	s_waitcnt lgkmcnt(0)
	v_cvt_pk_bf16_f32 v3, v4, v5
	ds_read2_b32 v[4:5], v59 offset0:132 offset1:165
	s_waitcnt lgkmcnt(0)
	v_cvt_pk_bf16_f32 v4, v4, v5
	ds_read2_b32 v[20:21], v59 offset0:198 offset1:231
	s_waitcnt lgkmcnt(0)
	v_cvt_pk_bf16_f32 v5, v20, v21
	v_add_u32_e32 v20, v14, v52
	v_ashrrev_i32_e32 v21, 31, v20
	v_lshlrev_b64 v[20:21], 12, v[20:21]
	v_lshl_add_u64 v[20:21], v[16:17], 0, v[20:21]
	global_store_dwordx4 v[20:21], v[2:5], off
	ds_read2_b32 v[2:3], v60 offset1:33
	v_cmp_lt_i32_e32 vcc, s2, v18
	s_waitcnt lgkmcnt(0)
	v_cvt_pk_bf16_f32 v2, v2, v3
	ds_read2_b32 v[4:5], v60 offset0:66 offset1:99
	s_waitcnt lgkmcnt(0)
	v_cvt_pk_bf16_f32 v3, v4, v5
	ds_read2_b32 v[4:5], v60 offset0:132 offset1:165
	s_waitcnt lgkmcnt(0)
	v_cvt_pk_bf16_f32 v4, v4, v5
	ds_read2_b32 v[20:21], v60 offset0:198 offset1:231
	s_waitcnt lgkmcnt(0)
	v_cvt_pk_bf16_f32 v5, v20, v21
	v_add_u32_e32 v20, v14, v55
	v_ashrrev_i32_e32 v21, 31, v20
	v_lshlrev_b64 v[20:21], 12, v[20:21]
	v_lshl_add_u64 v[20:21], v[16:17], 0, v[20:21]
	global_store_dwordx4 v[20:21], v[2:5], off
	ds_read2_b32 v[2:3], v61 offset1:33
	s_or_b64 s[30:31], vcc, s[30:31]
	s_waitcnt lgkmcnt(0)
	v_cvt_pk_bf16_f32 v2, v2, v3
	ds_read2_b32 v[4:5], v61 offset0:66 offset1:99
	s_waitcnt lgkmcnt(0)
	v_cvt_pk_bf16_f32 v3, v4, v5
	ds_read2_b32 v[4:5], v61 offset0:132 offset1:165
	s_waitcnt lgkmcnt(0)
	v_cvt_pk_bf16_f32 v4, v4, v5
	ds_read2_b32 v[20:21], v61 offset0:198 offset1:231
	s_waitcnt lgkmcnt(0)
	v_cvt_pk_bf16_f32 v5, v20, v21
	v_add_u32_e32 v20, v14, v56
	v_ashrrev_i32_e32 v21, 31, v20
	v_lshlrev_b64 v[20:21], 12, v[20:21]
	v_lshl_add_u64 v[20:21], v[16:17], 0, v[20:21]
	global_store_dwordx4 v[20:21], v[2:5], off
	v_add_u32_e32 v14, v14, v57
	ds_read2_b32 v[2:3], v62 offset1:33
	v_ashrrev_i32_e32 v15, 31, v14
	s_waitcnt lgkmcnt(0)
	v_cvt_pk_bf16_f32 v2, v2, v3
	ds_read2_b32 v[4:5], v62 offset0:66 offset1:99
	v_lshlrev_b64 v[14:15], 12, v[14:15]
	s_waitcnt lgkmcnt(0)
	v_cvt_pk_bf16_f32 v3, v4, v5
	ds_read2_b32 v[4:5], v62 offset0:132 offset1:165
	v_lshl_add_u64 v[14:15], v[16:17], 0, v[14:15]
	s_waitcnt lgkmcnt(0)
	v_cvt_pk_bf16_f32 v4, v4, v5
	ds_read2_b32 v[20:21], v62 offset0:198 offset1:231
	s_waitcnt lgkmcnt(0)
	v_cvt_pk_bf16_f32 v5, v20, v21
	global_store_dwordx4 v[14:15], v[2:5], off
	s_waitcnt lgkmcnt(0)
	s_andn2_b64 exec, exec, s[30:31]
	s_cbranch_execnz .LBB0_940
	s_branch .LBB0_928

.LBB0_1031:
	v_lshl_or_b32 v188, s2, 8, v216
	v_lshl_add_u32 v192, s6, 8, v214
	v_readlane_b32 s6, v254, 22
	v_ashrrev_i32_e32 v189, 31, v188
	v_readlane_b32 s7, v254, 23
	v_ashrrev_i32_e32 v193, 31, v192
	v_lshlrev_b64 v[114:115], 13, v[192:193]
	v_lshl_add_u64 v[190:191], v[188:189], 2, s[6:7]
	v_lshl_add_u64 v[226:227], v[190:191], 0, v[114:115]
	global_load_dwordx4 v[208:211], v[226:227], off
	global_load_dwordx4 v[218:221], v[226:227], off offset:16
	global_load_dwordx4 v[222:225], v[226:227], off offset:512
	global_load_dwordx4 v[230:233], v[226:227], off offset:528
	v_or_b32_e32 v202, 16, v192
	v_ashrrev_i32_e32 v203, 31, v202
	v_or_b32_e32 v198, 32, v192
	v_lshlrev_b64 v[114:115], 13, v[202:203]
	v_ashrrev_i32_e32 v199, 31, v198
	v_or_b32_e32 v194, 48, v192
	v_lshl_add_u64 v[204:205], v[190:191], 0, v[114:115]
	v_lshlrev_b64 v[114:115], 13, v[198:199]
	v_ashrrev_i32_e32 v195, 31, v194
	v_lshl_add_u64 v[200:201], v[190:191], 0, v[114:115]
	v_lshlrev_b64 v[114:115], 13, v[194:195]
	v_lshl_add_u64 v[196:197], v[190:191], 0, v[114:115]
	global_load_dwordx4 v[174:177], v[204:205], off
	global_load_dwordx4 v[170:173], v[204:205], off offset:16
	global_load_dwordx4 v[166:169], v[204:205], off offset:512
	global_load_dwordx4 v[162:165], v[204:205], off offset:528
	global_load_dwordx4 v[158:161], v[200:201], off
	global_load_dwordx4 v[154:157], v[200:201], off offset:16
	global_load_dwordx4 v[134:137], v[200:201], off offset:512
	global_load_dwordx4 v[130:133], v[200:201], off offset:528
	global_load_dwordx4 v[142:145], v[196:197], off
	global_load_dwordx4 v[138:141], v[196:197], off offset:16
	global_load_dwordx4 v[118:121], v[196:197], off offset:512
	global_load_dwordx4 v[114:117], v[196:197], off offset:528
	v_lshlrev_b64 v[234:235], 11, v[192:193]
	v_lshl_add_u64 v[234:235], v[234:235], 0, v[188:189]
	s_waitcnt vmcnt(0) lgkmcnt(0)
	v_pk_add_f32 v[152:153], v[152:153], v[210:211]
	v_pk_add_f32 v[150:151], v[150:151], v[208:209]
	v_mul_f32_e32 v209, v153, v153
	v_mul_f32_e32 v208, v151, v151
	v_pk_add_f32 v[146:147], v[146:147], v[218:219]
	v_fmac_f32_e32 v208, v150, v150
	v_fmac_f32_e32 v209, v152, v152
	v_add_f32_e32 v208, v208, v209
	v_mul_f32_e32 v209, v147, v147
	v_pk_add_f32 v[148:149], v[148:149], v[220:221]
	v_fmac_f32_e32 v209, v146, v146
	global_store_dwordx4 v[226:227], v[150:153], off
	global_store_dwordx4 v[226:227], v[146:149], off offset:16
	v_add_f32_e32 v208, v208, v209
	v_mul_f32_e32 v209, v149, v149
	v_cvt_pk_bf16_f32 v150, v150, v151
	v_cvt_pk_bf16_f32 v151, v152, v153
	v_cvt_pk_bf16_f32 v152, v146, v147
	v_lshlrev_b64 v[146:147], 1, v[234:235]
	v_fmac_f32_e32 v209, v148, v148
	v_cvt_pk_bf16_f32 v153, v148, v149
	v_lshl_add_u64 v[148:149], s[34:35], 0, v[146:147]
	v_pk_add_f32 v[128:129], v[128:129], v[224:225]
	v_pk_add_f32 v[126:127], v[126:127], v[222:223]
	global_store_dwordx4 v[148:149], v[150:153], off
	v_mul_f32_e32 v148, v127, v127
	v_mul_f32_e32 v149, v129, v129
	v_pk_add_f32 v[122:123], v[122:123], v[230:231]
	v_fmac_f32_e32 v148, v126, v126
	v_fmac_f32_e32 v149, v128, v128
	v_add_f32_e32 v148, v148, v149
	v_mul_f32_e32 v149, v123, v123
	v_or_b32_e32 v146, 0x100, v146
	v_pk_add_f32 v[124:125], v[124:125], v[232:233]
	global_store_dwordx4 v[226:227], v[126:129], off offset:512
	global_store_dwordx4 v[226:227], v[122:125], off offset:528
	v_fmac_f32_e32 v149, v122, v122
	v_cvt_pk_bf16_f32 v126, v126, v127
	v_cvt_pk_bf16_f32 v127, v128, v129
	v_cvt_pk_bf16_f32 v128, v122, v123
	v_cvt_pk_bf16_f32 v129, v124, v125
	s_nop 0
	v_lshl_add_u64 v[122:123], s[34:35], 0, v[146:147]
	global_store_dwordx4 v[122:123], v[126:129], off
	v_and_b32_e32 v123, 64, v228
	v_add_f32_e32 v148, v148, v149
	v_mul_f32_e32 v149, v125, v125
	v_xor_b32_e32 v122, 16, v228
	v_add_u32_e32 v123, 64, v123
	v_fmac_f32_e32 v149, v124, v124
	v_cmp_lt_i32_e32 vcc, v122, v123
	v_add_f32_e32 v208, v209, v208
	v_add_f32_e32 v148, v149, v148
	v_cndmask_b32_e32 v122, v228, v122, vcc
	v_add_f32_e32 v148, v208, v148
	v_lshlrev_b32_e32 v146, 2, v122
	ds_bpermute_b32 v122, v146, v148
	v_xor_b32_e32 v124, 32, v228
	v_cmp_lt_i32_e32 vcc, v124, v123
	s_waitcnt lgkmcnt(0)
	v_add_f32_e32 v122, v148, v122
	v_cndmask_b32_e32 v123, v228, v124, vcc
	v_lshlrev_b32_e32 v147, 2, v123
	ds_bpermute_b32 v123, v147, v122
	s_and_saveexec_b64 s[18:19], s[36:37]
	v_readlane_b32 s28, v254, 14
	v_readlane_b32 s50, v254, 16
	v_readlane_b32 s29, v254, 15
	v_readlane_b32 s51, v254, 17
	s_mov_b32 s54, 0x34000
	s_mov_b32 s53, 0x2d504000
	s_cbranch_execz .LBB0_1033
	v_lshl_add_u64 v[124:125], v[192:193], 2, s[4:5]
	s_waitcnt lgkmcnt(0)
	v_add_f32_e32 v122, v122, v123
	global_atomic_add_f32 v[124:125], v122, off
.LBB0_1033:
	s_or_b64 exec, exec, s[18:19]
	v_pk_add_f32 v[112:113], v[112:113], v[176:177]
	v_pk_add_f32 v[110:111], v[110:111], v[174:175]
	v_mul_f32_e32 v125, v113, v113
	v_mul_f32_e32 v124, v111, v111
	v_pk_add_f32 v[106:107], v[106:107], v[170:171]
	v_fmac_f32_e32 v124, v110, v110
	v_fmac_f32_e32 v125, v112, v112
	s_waitcnt lgkmcnt(0)
	v_lshlrev_b64 v[122:123], 11, v[202:203]
	v_add_f32_e32 v124, v124, v125
	v_mul_f32_e32 v125, v107, v107
	v_lshl_add_u64 v[122:123], v[122:123], 0, v[188:189]
	v_pk_add_f32 v[108:109], v[108:109], v[172:173]
	v_fmac_f32_e32 v125, v106, v106
	global_store_dwordx4 v[204:205], v[110:113], off
	global_store_dwordx4 v[204:205], v[106:109], off offset:16
	v_add_f32_e32 v124, v124, v125
	v_mul_f32_e32 v125, v109, v109
	v_cvt_pk_bf16_f32 v110, v110, v111
	v_cvt_pk_bf16_f32 v111, v112, v113
	v_cvt_pk_bf16_f32 v112, v106, v107
	v_lshlrev_b64 v[106:107], 1, v[122:123]
	v_fmac_f32_e32 v125, v108, v108
	v_cvt_pk_bf16_f32 v113, v108, v109
	v_lshl_add_u64 v[108:109], s[34:35], 0, v[106:107]
	v_pk_add_f32 v[104:105], v[104:105], v[168:169]
	v_pk_add_f32 v[102:103], v[102:103], v[166:167]
	global_store_dwordx4 v[108:109], v[110:113], off
	v_mul_f32_e32 v108, v103, v103
	v_mul_f32_e32 v109, v105, v105
	v_pk_add_f32 v[98:99], v[98:99], v[162:163]
	v_fmac_f32_e32 v108, v102, v102
	v_fmac_f32_e32 v109, v104, v104
	v_add_f32_e32 v108, v108, v109
	v_mul_f32_e32 v109, v99, v99
	v_pk_add_f32 v[100:101], v[100:101], v[164:165]
	v_fmac_f32_e32 v109, v98, v98
	v_add_f32_e32 v108, v108, v109
	v_mul_f32_e32 v109, v101, v101
	v_fmac_f32_e32 v109, v100, v100
	v_add_f32_e32 v124, v125, v124
	v_add_f32_e32 v108, v109, v108
	v_add_f32_e32 v108, v124, v108
	ds_bpermute_b32 v109, v146, v108
	global_store_dwordx4 v[204:205], v[102:105], off offset:512
	global_store_dwordx4 v[204:205], v[98:101], off offset:528
	v_or_b32_e32 v106, 0x100, v106
	v_cvt_pk_bf16_f32 v102, v102, v103
	v_cvt_pk_bf16_f32 v103, v104, v105
	v_cvt_pk_bf16_f32 v104, v98, v99
	v_cvt_pk_bf16_f32 v105, v100, v101
	s_waitcnt lgkmcnt(0)
	v_add_f32_e32 v98, v108, v109
	ds_bpermute_b32 v99, v147, v98
	v_lshl_add_u64 v[100:101], s[34:35], 0, v[106:107]
	global_store_dwordx4 v[100:101], v[102:105], off
	s_and_saveexec_b64 s[18:19], s[36:37]
	s_cbranch_execz .LBB0_1035
	v_lshl_add_u64 v[100:101], v[202:203], 2, s[4:5]
	s_waitcnt lgkmcnt(0)
	v_add_f32_e32 v98, v98, v99
	global_atomic_add_f32 v[100:101], v98, off
.LBB0_1035:
	s_or_b64 exec, exec, s[18:19]
	v_pk_add_f32 v[96:97], v[96:97], v[160:161]
	v_pk_add_f32 v[94:95], v[94:95], v[158:159]
	v_mul_f32_e32 v101, v97, v97
	v_mul_f32_e32 v100, v95, v95
	v_pk_add_f32 v[90:91], v[90:91], v[154:155]
	v_fmac_f32_e32 v100, v94, v94
	v_fmac_f32_e32 v101, v96, v96
	s_waitcnt lgkmcnt(0)
	v_lshlrev_b64 v[98:99], 11, v[198:199]
	v_add_f32_e32 v100, v100, v101
	v_mul_f32_e32 v101, v91, v91
	v_lshl_add_u64 v[98:99], v[98:99], 0, v[188:189]
	v_pk_add_f32 v[92:93], v[92:93], v[156:157]
	v_fmac_f32_e32 v101, v90, v90
	global_store_dwordx4 v[200:201], v[94:97], off
	global_store_dwordx4 v[200:201], v[90:93], off offset:16
	v_add_f32_e32 v100, v100, v101
	v_mul_f32_e32 v101, v93, v93
	v_cvt_pk_bf16_f32 v94, v94, v95
	v_cvt_pk_bf16_f32 v95, v96, v97
	v_cvt_pk_bf16_f32 v96, v90, v91
	v_lshlrev_b64 v[90:91], 1, v[98:99]
	v_fmac_f32_e32 v101, v92, v92
	v_cvt_pk_bf16_f32 v97, v92, v93
	v_lshl_add_u64 v[92:93], s[34:35], 0, v[90:91]
	v_pk_add_f32 v[88:89], v[88:89], v[136:137]
	v_pk_add_f32 v[86:87], v[86:87], v[134:135]
	global_store_dwordx4 v[92:93], v[94:97], off
	v_mul_f32_e32 v92, v87, v87
	v_mul_f32_e32 v93, v89, v89
	v_pk_add_f32 v[82:83], v[82:83], v[130:131]
	v_fmac_f32_e32 v92, v86, v86
	v_fmac_f32_e32 v93, v88, v88
	v_add_f32_e32 v92, v92, v93
	v_mul_f32_e32 v93, v83, v83
	v_pk_add_f32 v[84:85], v[84:85], v[132:133]
	v_fmac_f32_e32 v93, v82, v82
	v_add_f32_e32 v92, v92, v93
	v_mul_f32_e32 v93, v85, v85
	v_fmac_f32_e32 v93, v84, v84
	v_add_f32_e32 v100, v101, v100
	v_add_f32_e32 v92, v93, v92
	v_add_f32_e32 v92, v100, v92
	ds_bpermute_b32 v93, v146, v92
	global_store_dwordx4 v[200:201], v[86:89], off offset:512
	global_store_dwordx4 v[200:201], v[82:85], off offset:528
	v_or_b32_e32 v90, 0x100, v90
	v_cvt_pk_bf16_f32 v86, v86, v87
	v_cvt_pk_bf16_f32 v87, v88, v89
	v_cvt_pk_bf16_f32 v88, v82, v83
	v_cvt_pk_bf16_f32 v89, v84, v85
	s_waitcnt lgkmcnt(0)
	v_add_f32_e32 v82, v92, v93
	ds_bpermute_b32 v83, v147, v82
	v_lshl_add_u64 v[84:85], s[34:35], 0, v[90:91]
	global_store_dwordx4 v[84:85], v[86:89], off
	s_and_saveexec_b64 s[18:19], s[36:37]
	s_mov_b32 s56, 0x10000
	s_mov_b32 s57, 0x20000
	s_cbranch_execz .LBB0_1037
	v_lshl_add_u64 v[84:85], v[198:199], 2, s[4:5]
	s_waitcnt lgkmcnt(0)
	v_add_f32_e32 v82, v82, v83
	global_atomic_add_f32 v[84:85], v82, off
.LBB0_1037:
	s_or_b64 exec, exec, s[18:19]
	v_pk_add_f32 v[80:81], v[80:81], v[144:145]
	v_pk_add_f32 v[78:79], v[78:79], v[142:143]
	v_mul_f32_e32 v85, v81, v81
	v_mul_f32_e32 v84, v79, v79
	v_pk_add_f32 v[74:75], v[74:75], v[138:139]
	v_fmac_f32_e32 v84, v78, v78
	v_fmac_f32_e32 v85, v80, v80
	s_waitcnt lgkmcnt(0)
	v_lshlrev_b64 v[82:83], 11, v[194:195]
	v_add_f32_e32 v84, v84, v85
	v_mul_f32_e32 v85, v75, v75
	v_lshl_add_u64 v[82:83], v[82:83], 0, v[188:189]
	v_pk_add_f32 v[76:77], v[76:77], v[140:141]
	v_fmac_f32_e32 v85, v74, v74
	global_store_dwordx4 v[196:197], v[78:81], off
	global_store_dwordx4 v[196:197], v[74:77], off offset:16
	v_add_f32_e32 v84, v84, v85
	v_mul_f32_e32 v85, v77, v77
	v_cvt_pk_bf16_f32 v78, v78, v79
	v_cvt_pk_bf16_f32 v79, v80, v81
	v_cvt_pk_bf16_f32 v80, v74, v75
	v_lshlrev_b64 v[74:75], 1, v[82:83]
	v_fmac_f32_e32 v85, v76, v76
	v_cvt_pk_bf16_f32 v81, v76, v77
	v_lshl_add_u64 v[76:77], s[34:35], 0, v[74:75]
	v_pk_add_f32 v[72:73], v[72:73], v[120:121]
	v_pk_add_f32 v[70:71], v[70:71], v[118:119]
	global_store_dwordx4 v[76:77], v[78:81], off
	v_mul_f32_e32 v76, v71, v71
	v_mul_f32_e32 v77, v73, v73
	v_pk_add_f32 v[66:67], v[66:67], v[114:115]
	v_fmac_f32_e32 v76, v70, v70
	v_fmac_f32_e32 v77, v72, v72
	v_add_f32_e32 v76, v76, v77
	v_mul_f32_e32 v77, v67, v67
	v_pk_add_f32 v[68:69], v[68:69], v[116:117]
	v_fmac_f32_e32 v77, v66, v66
	v_add_f32_e32 v76, v76, v77
	v_mul_f32_e32 v77, v69, v69
	v_fmac_f32_e32 v77, v68, v68
	v_add_f32_e32 v84, v85, v84
	v_add_f32_e32 v76, v77, v76
	v_add_f32_e32 v76, v84, v76
	ds_bpermute_b32 v77, v146, v76
	global_store_dwordx4 v[196:197], v[70:73], off offset:512
	global_store_dwordx4 v[196:197], v[66:69], off offset:528
	v_or_b32_e32 v74, 0x100, v74
	v_cvt_pk_bf16_f32 v70, v70, v71
	v_cvt_pk_bf16_f32 v71, v72, v73
	v_cvt_pk_bf16_f32 v72, v66, v67
	v_cvt_pk_bf16_f32 v73, v68, v69
	s_waitcnt lgkmcnt(0)
	v_add_f32_e32 v66, v76, v77
	ds_bpermute_b32 v67, v147, v66
	v_lshl_add_u64 v[68:69], s[34:35], 0, v[74:75]
	global_store_dwordx4 v[68:69], v[70:73], off
	s_and_saveexec_b64 s[18:19], s[36:37]
	s_cbranch_execz .LBB0_1039
	v_lshl_add_u64 v[68:69], v[194:195], 2, s[4:5]
	s_waitcnt lgkmcnt(0)
	v_add_f32_e32 v66, v66, v67
	global_atomic_add_f32 v[68:69], v66, off
.LBB0_1039:
	s_or_b64 exec, exec, s[18:19]
	v_add_u32_e32 v134, 0x80, v192
	v_ashrrev_i32_e32 v135, 31, v134
	s_waitcnt lgkmcnt(0)
	v_lshlrev_b64 v[66:67], 13, v[134:135]
	v_lshl_add_u64 v[136:137], v[190:191], 0, v[66:67]
	global_load_dwordx4 v[138:141], v[136:137], off
	global_load_dwordx4 v[142:145], v[136:137], off offset:16
	global_load_dwordx4 v[118:121], v[136:137], off offset:512
	global_load_dwordx4 v[114:117], v[136:137], off offset:528
	v_add_u32_e32 v130, 0x90, v192
	v_ashrrev_i32_e32 v131, 31, v130
	v_add_u32_e32 v126, 0xa0, v192
	v_lshlrev_b64 v[66:67], 13, v[130:131]
	v_ashrrev_i32_e32 v127, 31, v126
	v_add_u32_e32 v122, 0xb0, v192
	v_lshl_add_u64 v[132:133], v[190:191], 0, v[66:67]
	v_lshlrev_b64 v[66:67], 13, v[126:127]
	v_ashrrev_i32_e32 v123, 31, v122
	v_lshl_add_u64 v[128:129], v[190:191], 0, v[66:67]
	v_lshlrev_b64 v[66:67], 13, v[122:123]
	v_lshl_add_u64 v[124:125], v[190:191], 0, v[66:67]
	global_load_dwordx4 v[110:113], v[132:133], off
	global_load_dwordx4 v[106:109], v[132:133], off offset:16
	global_load_dwordx4 v[102:105], v[132:133], off offset:512
	global_load_dwordx4 v[98:101], v[132:133], off offset:528
	global_load_dwordx4 v[94:97], v[128:129], off
	global_load_dwordx4 v[90:93], v[128:129], off offset:16
	global_load_dwordx4 v[78:81], v[128:129], off offset:512
	global_load_dwordx4 v[74:77], v[128:129], off offset:528
	global_load_dwordx4 v[86:89], v[124:125], off
	global_load_dwordx4 v[82:85], v[124:125], off offset:16
	global_load_dwordx4 v[70:73], v[124:125], off offset:512
	global_load_dwordx4 v[66:69], v[124:125], off offset:528
	v_lshlrev_b64 v[148:149], 11, v[134:135]
	v_lshl_add_u64 v[148:149], v[148:149], 0, v[188:189]
	s_waitcnt vmcnt(0) lgkmcnt(0)
	v_pk_add_f32 v[64:65], v[64:65], v[140:141]
	v_pk_add_f32 v[62:63], v[62:63], v[138:139]
	v_mul_f32_e32 v139, v65, v65
	v_mul_f32_e32 v138, v63, v63
	v_pk_add_f32 v[58:59], v[58:59], v[142:143]
	v_fmac_f32_e32 v138, v62, v62
	v_fmac_f32_e32 v139, v64, v64
	v_add_f32_e32 v138, v138, v139
	v_mul_f32_e32 v139, v59, v59
	v_pk_add_f32 v[60:61], v[60:61], v[144:145]
	v_fmac_f32_e32 v139, v58, v58
	global_store_dwordx4 v[136:137], v[62:65], off
	global_store_dwordx4 v[136:137], v[58:61], off offset:16
	v_add_f32_e32 v138, v138, v139
	v_mul_f32_e32 v139, v61, v61
	v_cvt_pk_bf16_f32 v62, v62, v63
	v_cvt_pk_bf16_f32 v63, v64, v65
	v_cvt_pk_bf16_f32 v64, v58, v59
	v_lshlrev_b64 v[58:59], 1, v[148:149]
	v_fmac_f32_e32 v139, v60, v60
	v_cvt_pk_bf16_f32 v65, v60, v61
	v_lshl_add_u64 v[60:61], s[34:35], 0, v[58:59]
	v_pk_add_f32 v[56:57], v[56:57], v[120:121]
	v_pk_add_f32 v[54:55], v[54:55], v[118:119]
	global_store_dwordx4 v[60:61], v[62:65], off
	v_mul_f32_e32 v60, v55, v55
	v_mul_f32_e32 v61, v57, v57
	v_pk_add_f32 v[50:51], v[50:51], v[114:115]
	v_fmac_f32_e32 v60, v54, v54
	v_fmac_f32_e32 v61, v56, v56
	v_add_f32_e32 v60, v60, v61
	v_mul_f32_e32 v61, v51, v51
	v_pk_add_f32 v[52:53], v[52:53], v[116:117]
	v_fmac_f32_e32 v61, v50, v50
	v_add_f32_e32 v60, v60, v61
	v_mul_f32_e32 v61, v53, v53
	v_fmac_f32_e32 v61, v52, v52
	v_add_f32_e32 v138, v139, v138
	v_add_f32_e32 v60, v61, v60
	v_or_b32_e32 v58, 0x100, v58
	global_store_dwordx4 v[136:137], v[54:57], off offset:512
	global_store_dwordx4 v[136:137], v[50:53], off offset:528
	v_add_f32_e32 v60, v138, v60
	v_cvt_pk_bf16_f32 v54, v54, v55
	v_cvt_pk_bf16_f32 v55, v56, v57
	v_cvt_pk_bf16_f32 v56, v50, v51
	v_cvt_pk_bf16_f32 v57, v52, v53
	s_nop 0
	v_lshl_add_u64 v[50:51], s[34:35], 0, v[58:59]
	global_store_dwordx4 v[50:51], v[54:57], off
	ds_bpermute_b32 v50, v146, v60
	s_waitcnt lgkmcnt(0)
	v_add_f32_e32 v50, v60, v50
	ds_bpermute_b32 v51, v147, v50
	s_and_saveexec_b64 s[18:19], s[36:37]
	s_cbranch_execz .LBB0_1041
	v_lshl_add_u64 v[52:53], v[134:135], 2, s[4:5]
	s_waitcnt lgkmcnt(0)
	v_add_f32_e32 v50, v50, v51
	global_atomic_add_f32 v[52:53], v50, off
.LBB0_1041:
	s_or_b64 exec, exec, s[18:19]
	v_pk_add_f32 v[48:49], v[48:49], v[112:113]
	v_pk_add_f32 v[46:47], v[46:47], v[110:111]
	v_mul_f32_e32 v53, v49, v49
	v_mul_f32_e32 v52, v47, v47
	v_pk_add_f32 v[42:43], v[42:43], v[106:107]
	v_fmac_f32_e32 v52, v46, v46
	v_fmac_f32_e32 v53, v48, v48
	s_waitcnt lgkmcnt(0)
	v_lshlrev_b64 v[50:51], 11, v[130:131]
	v_add_f32_e32 v52, v52, v53
	v_mul_f32_e32 v53, v43, v43
	v_lshl_add_u64 v[50:51], v[50:51], 0, v[188:189]
	v_pk_add_f32 v[44:45], v[44:45], v[108:109]
	v_fmac_f32_e32 v53, v42, v42
	global_store_dwordx4 v[132:133], v[46:49], off
	global_store_dwordx4 v[132:133], v[42:45], off offset:16
	v_add_f32_e32 v52, v52, v53
	v_mul_f32_e32 v53, v45, v45
	v_cvt_pk_bf16_f32 v46, v46, v47
	v_cvt_pk_bf16_f32 v47, v48, v49
	v_cvt_pk_bf16_f32 v48, v42, v43
	v_lshlrev_b64 v[42:43], 1, v[50:51]
	v_fmac_f32_e32 v53, v44, v44
	v_cvt_pk_bf16_f32 v49, v44, v45
	v_lshl_add_u64 v[44:45], s[34:35], 0, v[42:43]
	v_pk_add_f32 v[40:41], v[40:41], v[104:105]
	v_pk_add_f32 v[38:39], v[38:39], v[102:103]
	global_store_dwordx4 v[44:45], v[46:49], off
	v_mul_f32_e32 v44, v39, v39
	v_mul_f32_e32 v45, v41, v41
	v_pk_add_f32 v[34:35], v[34:35], v[98:99]
	v_fmac_f32_e32 v44, v38, v38
	v_fmac_f32_e32 v45, v40, v40
	v_add_f32_e32 v44, v44, v45
	v_mul_f32_e32 v45, v35, v35
	v_pk_add_f32 v[36:37], v[36:37], v[100:101]
	v_fmac_f32_e32 v45, v34, v34
	v_add_f32_e32 v44, v44, v45
	v_mul_f32_e32 v45, v37, v37
	v_fmac_f32_e32 v45, v36, v36
	v_add_f32_e32 v52, v53, v52
	v_add_f32_e32 v44, v45, v44
	v_add_f32_e32 v44, v52, v44
	ds_bpermute_b32 v45, v146, v44
	global_store_dwordx4 v[132:133], v[38:41], off offset:512
	global_store_dwordx4 v[132:133], v[34:37], off offset:528
	v_or_b32_e32 v42, 0x100, v42
	v_cvt_pk_bf16_f32 v38, v38, v39
	v_cvt_pk_bf16_f32 v39, v40, v41
	v_cvt_pk_bf16_f32 v40, v34, v35
	v_cvt_pk_bf16_f32 v41, v36, v37
	s_waitcnt lgkmcnt(0)
	v_add_f32_e32 v34, v44, v45
	ds_bpermute_b32 v35, v147, v34
	v_lshl_add_u64 v[36:37], s[34:35], 0, v[42:43]
	global_store_dwordx4 v[36:37], v[38:41], off
	s_and_saveexec_b64 s[18:19], s[36:37]
	s_cbranch_execz .LBB0_1043
	v_lshl_add_u64 v[36:37], v[130:131], 2, s[4:5]
	s_waitcnt lgkmcnt(0)
	v_add_f32_e32 v34, v34, v35
	global_atomic_add_f32 v[36:37], v34, off
.LBB0_1043:
	s_or_b64 exec, exec, s[18:19]
	v_pk_add_f32 v[32:33], v[32:33], v[96:97]
	v_pk_add_f32 v[30:31], v[30:31], v[94:95]
	v_mul_f32_e32 v37, v33, v33
	v_mul_f32_e32 v36, v31, v31
	v_pk_add_f32 v[26:27], v[26:27], v[90:91]
	v_fmac_f32_e32 v36, v30, v30
	v_fmac_f32_e32 v37, v32, v32
	s_waitcnt lgkmcnt(0)
	v_lshlrev_b64 v[34:35], 11, v[126:127]
	v_add_f32_e32 v36, v36, v37
	v_mul_f32_e32 v37, v27, v27
	v_lshl_add_u64 v[34:35], v[34:35], 0, v[188:189]
	v_pk_add_f32 v[28:29], v[28:29], v[92:93]
	v_fmac_f32_e32 v37, v26, v26
	global_store_dwordx4 v[128:129], v[30:33], off
	global_store_dwordx4 v[128:129], v[26:29], off offset:16
	v_add_f32_e32 v36, v36, v37
	v_mul_f32_e32 v37, v29, v29
	v_cvt_pk_bf16_f32 v30, v30, v31
	v_cvt_pk_bf16_f32 v31, v32, v33
	v_cvt_pk_bf16_f32 v32, v26, v27
	v_lshlrev_b64 v[26:27], 1, v[34:35]
	v_fmac_f32_e32 v37, v28, v28
	v_cvt_pk_bf16_f32 v33, v28, v29
	v_lshl_add_u64 v[28:29], s[34:35], 0, v[26:27]
	v_pk_add_f32 v[24:25], v[24:25], v[80:81]
	v_pk_add_f32 v[22:23], v[22:23], v[78:79]
	global_store_dwordx4 v[28:29], v[30:33], off
	v_mul_f32_e32 v28, v23, v23
	v_mul_f32_e32 v29, v25, v25
	v_pk_add_f32 v[18:19], v[18:19], v[74:75]
	v_fmac_f32_e32 v28, v22, v22
	v_fmac_f32_e32 v29, v24, v24
	v_add_f32_e32 v28, v28, v29
	v_mul_f32_e32 v29, v19, v19
	v_pk_add_f32 v[20:21], v[20:21], v[76:77]
	v_fmac_f32_e32 v29, v18, v18
	v_add_f32_e32 v28, v28, v29
	v_mul_f32_e32 v29, v21, v21
	v_fmac_f32_e32 v29, v20, v20
	v_add_f32_e32 v36, v37, v36
	v_add_f32_e32 v28, v29, v28
	v_add_f32_e32 v28, v36, v28
	ds_bpermute_b32 v29, v146, v28
	global_store_dwordx4 v[128:129], v[22:25], off offset:512
	global_store_dwordx4 v[128:129], v[18:21], off offset:528
	v_or_b32_e32 v26, 0x100, v26
	v_cvt_pk_bf16_f32 v22, v22, v23
	v_cvt_pk_bf16_f32 v23, v24, v25
	v_cvt_pk_bf16_f32 v24, v18, v19
	v_cvt_pk_bf16_f32 v25, v20, v21
	s_waitcnt lgkmcnt(0)
	v_add_f32_e32 v18, v28, v29
	ds_bpermute_b32 v19, v147, v18
	v_lshl_add_u64 v[20:21], s[34:35], 0, v[26:27]
	global_store_dwordx4 v[20:21], v[22:25], off
	s_and_saveexec_b64 s[18:19], s[36:37]
	s_cbranch_execz .LBB0_1045
	v_lshl_add_u64 v[20:21], v[126:127], 2, s[4:5]
	s_waitcnt lgkmcnt(0)
	v_add_f32_e32 v18, v18, v19
	global_atomic_add_f32 v[20:21], v18, off
.LBB0_1045:
	s_or_b64 exec, exec, s[18:19]
	v_pk_add_f32 v[16:17], v[16:17], v[88:89]
	v_pk_add_f32 v[14:15], v[14:15], v[86:87]
	v_mul_f32_e32 v21, v17, v17
	v_mul_f32_e32 v20, v15, v15
	v_pk_add_f32 v[10:11], v[10:11], v[82:83]
	v_fmac_f32_e32 v20, v14, v14
	v_fmac_f32_e32 v21, v16, v16
	s_waitcnt lgkmcnt(0)
	v_lshlrev_b64 v[18:19], 11, v[122:123]
	v_add_f32_e32 v20, v20, v21
	v_mul_f32_e32 v21, v11, v11
	v_lshl_add_u64 v[18:19], v[18:19], 0, v[188:189]
	v_pk_add_f32 v[12:13], v[12:13], v[84:85]
	v_fmac_f32_e32 v21, v10, v10
	global_store_dwordx4 v[124:125], v[14:17], off
	global_store_dwordx4 v[124:125], v[10:13], off offset:16
	v_add_f32_e32 v20, v20, v21
	v_mul_f32_e32 v21, v13, v13
	v_cvt_pk_bf16_f32 v14, v14, v15
	v_cvt_pk_bf16_f32 v15, v16, v17
	v_cvt_pk_bf16_f32 v16, v10, v11
	v_lshlrev_b64 v[10:11], 1, v[18:19]
	v_fmac_f32_e32 v21, v12, v12
	v_cvt_pk_bf16_f32 v17, v12, v13
	v_lshl_add_u64 v[12:13], s[34:35], 0, v[10:11]
	v_pk_add_f32 v[8:9], v[8:9], v[72:73]
	v_pk_add_f32 v[6:7], v[6:7], v[70:71]
	global_store_dwordx4 v[12:13], v[14:17], off
	v_mul_f32_e32 v12, v7, v7
	v_mul_f32_e32 v13, v9, v9
	v_pk_add_f32 v[2:3], v[2:3], v[66:67]
	v_fmac_f32_e32 v12, v6, v6
	v_fmac_f32_e32 v13, v8, v8
	v_add_f32_e32 v12, v12, v13
	v_mul_f32_e32 v13, v3, v3
	v_pk_add_f32 v[4:5], v[4:5], v[68:69]
	v_fmac_f32_e32 v13, v2, v2
	v_add_f32_e32 v12, v12, v13
	v_mul_f32_e32 v13, v5, v5
	v_fmac_f32_e32 v13, v4, v4
	v_add_f32_e32 v20, v21, v20
	v_add_f32_e32 v12, v13, v12
	v_add_f32_e32 v12, v20, v12
	ds_bpermute_b32 v13, v146, v12
	global_store_dwordx4 v[124:125], v[6:9], off offset:512
	global_store_dwordx4 v[124:125], v[2:5], off offset:528
	v_or_b32_e32 v10, 0x100, v10
	v_cvt_pk_bf16_f32 v6, v6, v7
	v_cvt_pk_bf16_f32 v7, v8, v9
	v_cvt_pk_bf16_f32 v8, v2, v3
	v_cvt_pk_bf16_f32 v9, v4, v5
	s_waitcnt lgkmcnt(0)
	v_add_f32_e32 v2, v12, v13
	ds_bpermute_b32 v3, v147, v2
	v_lshl_add_u64 v[4:5], s[34:35], 0, v[10:11]
	global_store_dwordx4 v[4:5], v[6:9], off
	s_and_saveexec_b64 s[18:19], s[36:37]
	s_cbranch_execz .LBB0_1047
	v_lshl_add_u64 v[4:5], v[122:123], 2, s[4:5]
	s_waitcnt lgkmcnt(0)
	v_add_f32_e32 v2, v2, v3
	global_atomic_add_f32 v[4:5], v2, off
